# y-path of scan steps: masked final reduction stage + masked LDS store replaced by all-lane DPP add + uniform store (bitwise identical value)
# speedup vs baseline: 1.0859x; 1.0023x over previous
.LBB0_341:
	ds_read_b128 v[96:99], v134
	ds_read_b128 v[92:95], v134 offset:256
	ds_read_b128 v[100:103], v134 offset:4096
	ds_read_b128 v[116:119], v134 offset:4352
	ds_read_b128 v[108:111], v134 offset:8192
	ds_read_b128 v[104:107], v134 offset:8448
	ds_read_b128 v[120:123], v134 offset:12288
	ds_read_b128 v[112:115], v134 offset:12544
	ds_read_b128 v[190:193], v134 offset:16384
	ds_read_b128 v[88:91], v134 offset:16640
	s_waitcnt lgkmcnt(7)
	v_mul_f32 v124, v84, v100
	v_mul_f32 v100, v80, v100
	v_mul_f32 v125, v85, v101
	v_mul_f32 v101, v81, v101
	v_add_u32_e32 v189, 0x5000, v182
	v_fma_f32 v124, v86, v102, v124
	v_fma_f32 v100, v82, v102, v100
	v_fma_f32 v102, v87, v103, v125
	v_fma_f32 v101, v83, v103, v101
	ds_read2_b32 v[126:127], v189 offset0:32 offset1:48
	v_add_f32_e32 v102, v124, v102
	v_add_f32_e32 v103, v100, v101
	ds_read2_b32 v[100:101], v189 offset1:16
	v_add_f32_dpp v102, v102, v102 row_ror:8 row_mask:0xf bank_mask:0xf bound_ctrl:1
	v_add_f32_dpp v103, v103, v103 row_ror:8 row_mask:0xf bank_mask:0xf bound_ctrl:1
	s_waitcnt lgkmcnt(0)
	v_mul_f32 v124, v100, v120
	v_add_u32_e32 v185, 0xb000, v182
	v_add_f32_dpp v102, v102, v102 row_ror:4 row_mask:0xf bank_mask:0xf bound_ctrl:1
	v_add_f32_dpp v103, v103, v103 row_ror:4 row_mask:0xf bank_mask:0xf bound_ctrl:1
	s_nop 0
	v_add_f32_dpp v102, v102, v102 row_ror:2 row_mask:0xf bank_mask:0xf bound_ctrl:1
	v_add_f32_dpp v103, v103, v103 row_ror:2 row_mask:0xf bank_mask:0xf bound_ctrl:1
	s_nop 0
	v_add_f32_dpp v102, v102, v102 row_ror:1 row_mask:0xf bank_mask:0xf bound_ctrl:1
	v_fma_f32 v124, v102, v108, v124
	v_add_f32_dpp v103, v103, v103 row_ror:1 row_mask:0xf bank_mask:0xf bound_ctrl:1
	v_fma_f32 v141, v84, v96, v124
	v_mul_f32 v84, v101, v120
	v_fma_f32 v84, v103, v108, v84
	v_fma_f32 v148, v80, v96, v84
	v_mul_f32 v80, v100, v121
	v_fma_f32 v80, v102, v109, v80
	v_fma_f32 v150, v85, v97, v80
	v_mul_f32 v80, v101, v121
	v_fma_f32 v80, v103, v109, v80
	v_fma_f32 v151, v81, v97, v80
	v_mul_f32 v80, v100, v122
	v_mul_f32 v81, v148, v190
	v_fma_f32 v80, v102, v110, v80
	v_fma_f32 v149, v86, v98, v80
	v_mul_f32 v80, v101, v122
	v_fma_f32 v80, v103, v110, v80
	v_fma_f32 v86, v82, v98, v80
	v_mul_f32 v80, v100, v123
	v_mul_f32 v82, v150, v191
	v_fma_f32 v80, v102, v111, v80
	v_fma_f32 v81, v86, v192, v81
	v_fma_f32 v85, v87, v99, v80
	v_mul_f32 v80, v101, v123
	v_fma_f32 v80, v103, v111, v80
	v_fma_f32 v82, v85, v193, v82
	v_fma_f32 v84, v83, v99, v80
	v_mul_f32 v80, v141, v190
	v_mul_f32 v83, v151, v191
	v_fma_f32 v80, v149, v192, v80
	v_fma_f32 v83, v84, v193, v83
	v_add_f32_e32 v80, v80, v82
	v_add_f32_e32 v82, v81, v83
	s_nop 0
	v_add_f32_dpp v80, v80, v80 row_ror:8 row_mask:0xf bank_mask:0xf bound_ctrl:1
	v_add_f32_dpp v82, v82, v82 row_ror:8 row_mask:0xf bank_mask:0xf bound_ctrl:1
	s_nop 0
	v_add_f32_dpp v80, v80, v80 row_ror:4 row_mask:0xf bank_mask:0xf bound_ctrl:1
	v_add_f32_dpp v82, v82, v82 row_ror:4 row_mask:0xf bank_mask:0xf bound_ctrl:1
	s_nop 0
	v_add_f32_dpp v80, v80, v80 row_ror:2 row_mask:0xf bank_mask:0xf bound_ctrl:1
	v_add_f32_dpp v82, v82, v82 row_ror:2 row_mask:0xf bank_mask:0xf bound_ctrl:1
	s_nop 0
	v_add_f32_dpp v80, v80, v80 row_ror:1 row_mask:0xf bank_mask:0xf bound_ctrl:1
	v_add_f32_dpp v82, v82, v82 row_ror:1 row_mask:0xf bank_mask:0xf bound_ctrl:1
	ds_write2_b32 v185, v80, v82 offset1:16
	v_mul_f32 v87, v141, v116
	v_mul_f32 v116, v148, v116
	v_mul_f32 v152, v150, v117
	v_mul_f32 v117, v151, v117
	ds_read_b128 v[96:99], v134 offset:512
	ds_read_b128 v[120:123], v134 offset:4608
	ds_read_b128 v[100:103], v134 offset:8704
	ds_read_b128 v[108:111], v134 offset:12800
	ds_read_b128 v[80:83], v134 offset:16896
	ds_read2_b32 v[124:125], v189 offset0:64 offset1:80
	v_fma_f32 v87, v149, v118, v87
	v_fma_f32 v116, v86, v118, v116
	v_fma_f32 v118, v85, v119, v152
	v_fma_f32 v117, v84, v119, v117
	v_add_f32_e32 v87, v87, v118
	v_add_f32_e32 v116, v116, v117
	v_mul_f32 v117, v126, v112
	v_mul_f32 v112, v127, v112
	v_add_f32_dpp v87, v87, v87 row_ror:8 row_mask:0xf bank_mask:0xf bound_ctrl:1
	v_add_f32_dpp v116, v116, v116 row_ror:8 row_mask:0xf bank_mask:0xf bound_ctrl:1
	s_nop 0
	v_add_f32_dpp v87, v87, v87 row_ror:4 row_mask:0xf bank_mask:0xf bound_ctrl:1
	v_add_f32_dpp v116, v116, v116 row_ror:4 row_mask:0xf bank_mask:0xf bound_ctrl:1
	s_nop 0
	v_add_f32_dpp v87, v87, v87 row_ror:2 row_mask:0xf bank_mask:0xf bound_ctrl:1
	v_add_f32_dpp v116, v116, v116 row_ror:2 row_mask:0xf bank_mask:0xf bound_ctrl:1
	s_nop 0
	v_add_f32_dpp v87, v87, v87 row_ror:1 row_mask:0xf bank_mask:0xf bound_ctrl:1
	v_add_f32_dpp v116, v116, v116 row_ror:1 row_mask:0xf bank_mask:0xf bound_ctrl:1
	v_fma_f32 v117, v87, v104, v117
	v_fma_f32 v104, v116, v104, v112
	v_fma_f32 v141, v141, v92, v117
	v_fma_f32 v92, v148, v92, v104
	v_mul_f32 v104, v126, v113
	v_fma_f32 v104, v87, v105, v104
	v_fma_f32 v148, v150, v93, v104
	v_mul_f32 v104, v127, v113
	v_fma_f32 v104, v116, v105, v104
	v_fma_f32 v93, v151, v93, v104
	v_mul_f32 v104, v126, v114
	v_fma_f32 v104, v87, v106, v104
	v_fma_f32 v149, v149, v94, v104
	v_mul_f32 v104, v127, v114
	v_fma_f32 v104, v116, v106, v104
	v_fma_f32 v94, v86, v94, v104
	v_mul_f32 v86, v126, v115
	v_fma_f32 v86, v87, v107, v86
	v_mul_f32 v87, v93, v89
	v_fma_f32 v150, v85, v95, v86
	v_mul_f32 v85, v127, v115
	v_mul_f32 v86, v148, v89
	v_fma_f32 v85, v116, v107, v85
	v_fma_f32 v86, v150, v91, v86
	v_fma_f32 v95, v84, v95, v85
	v_mul_f32 v84, v141, v88
	v_mul_f32 v85, v92, v88
	v_fma_f32 v84, v149, v90, v84
	v_fma_f32 v85, v94, v90, v85
	v_fma_f32 v87, v95, v91, v87
	v_add_f32_e32 v84, v84, v86
	v_add_f32_e32 v86, v85, v87
	s_nop 0
	v_add_f32_dpp v84, v84, v84 row_ror:8 row_mask:0xf bank_mask:0xf bound_ctrl:1
	v_add_f32_dpp v86, v86, v86 row_ror:8 row_mask:0xf bank_mask:0xf bound_ctrl:1
	s_nop 0
	v_add_f32_dpp v84, v84, v84 row_ror:4 row_mask:0xf bank_mask:0xf bound_ctrl:1
	v_add_f32_dpp v86, v86, v86 row_ror:4 row_mask:0xf bank_mask:0xf bound_ctrl:1
	s_nop 0
	v_add_f32_dpp v84, v84, v84 row_ror:2 row_mask:0xf bank_mask:0xf bound_ctrl:1
	v_add_f32_dpp v86, v86, v86 row_ror:2 row_mask:0xf bank_mask:0xf bound_ctrl:1
	s_nop 0
	v_add_f32_dpp v84, v84, v84 row_ror:1 row_mask:0xf bank_mask:0xf bound_ctrl:1
	v_add_f32_dpp v86, v86, v86 row_ror:1 row_mask:0xf bank_mask:0xf bound_ctrl:1
	ds_write2_b32 v185, v84, v86 offset0:32 offset1:48
	s_waitcnt lgkmcnt(4)
	v_mul_f32 v151, v141, v120
	v_mul_f32 v120, v92, v120
	v_mul_f32 v152, v148, v121
	v_mul_f32 v121, v93, v121
	ds_read_b128 v[88:91], v134 offset:768
	ds_read_b128 v[116:119], v134 offset:4864
	ds_read_b128 v[104:107], v134 offset:8960
	ds_read_b128 v[112:115], v134 offset:13056
	ds_read_b128 v[84:87], v134 offset:17152
	ds_read2_b32 v[126:127], v189 offset0:96 offset1:112
	v_fma_f32 v151, v149, v122, v151
	v_fma_f32 v120, v94, v122, v120
	v_fma_f32 v122, v150, v123, v152
	v_fma_f32 v121, v95, v123, v121
	v_add_f32_e32 v122, v151, v122
	v_add_f32_e32 v120, v120, v121
	s_nop 0
	v_add_f32_dpp v121, v122, v122 row_ror:8 row_mask:0xf bank_mask:0xf bound_ctrl:1
	v_add_f32_dpp v120, v120, v120 row_ror:8 row_mask:0xf bank_mask:0xf bound_ctrl:1
	s_waitcnt lgkmcnt(6)
	v_mul_f32 v122, v124, v108
	v_mul_f32 v108, v125, v108
	v_add_f32_dpp v121, v121, v121 row_ror:4 row_mask:0xf bank_mask:0xf bound_ctrl:1
	v_add_f32_dpp v120, v120, v120 row_ror:4 row_mask:0xf bank_mask:0xf bound_ctrl:1
	s_nop 0
	v_add_f32_dpp v121, v121, v121 row_ror:2 row_mask:0xf bank_mask:0xf bound_ctrl:1
	v_add_f32_dpp v120, v120, v120 row_ror:2 row_mask:0xf bank_mask:0xf bound_ctrl:1
	s_nop 0
	v_add_f32_dpp v121, v121, v121 row_ror:1 row_mask:0xf bank_mask:0xf bound_ctrl:1
	v_add_f32_dpp v120, v120, v120 row_ror:1 row_mask:0xf bank_mask:0xf bound_ctrl:1
	v_fma_f32 v122, v121, v100, v122
	v_fma_f32 v100, v120, v100, v108
	v_fma_f32 v141, v141, v96, v122
	v_fma_f32 v96, v92, v96, v100
	v_mul_f32 v92, v124, v109
	v_fma_f32 v92, v121, v101, v92
	v_fma_f32 v151, v148, v97, v92
	v_mul_f32 v92, v125, v109
	v_fma_f32 v92, v120, v101, v92
	v_fma_f32 v97, v93, v97, v92
	v_mul_f32 v92, v124, v110
	v_mul_f32 v93, v151, v81
	v_fma_f32 v92, v121, v102, v92
	v_mul_f32 v81, v97, v81
	v_fma_f32 v152, v149, v98, v92
	v_mul_f32 v92, v125, v110
	v_fma_f32 v92, v120, v102, v92
	v_fma_f32 v98, v94, v98, v92
	v_mul_f32 v92, v124, v111
	v_fma_f32 v92, v121, v103, v92
	v_fma_f32 v124, v150, v99, v92
	v_mul_f32 v92, v125, v111
	v_fma_f32 v92, v120, v103, v92
	v_fma_f32 v99, v95, v99, v92
	v_mul_f32 v92, v141, v80
	v_mul_f32 v80, v96, v80
	v_fma_f32 v92, v152, v82, v92
	v_fma_f32 v80, v98, v82, v80
	v_fma_f32 v82, v124, v83, v93
	v_fma_f32 v81, v99, v83, v81
	v_add_f32_e32 v82, v92, v82
	v_add_f32_e32 v83, v80, v81
	s_nop 0
	v_add_f32_dpp v80, v82, v82 row_ror:8 row_mask:0xf bank_mask:0xf bound_ctrl:1
	v_add_f32_dpp v82, v83, v83 row_ror:8 row_mask:0xf bank_mask:0xf bound_ctrl:1
	s_nop 0
	v_add_f32_dpp v80, v80, v80 row_ror:4 row_mask:0xf bank_mask:0xf bound_ctrl:1
	v_add_f32_dpp v82, v82, v82 row_ror:4 row_mask:0xf bank_mask:0xf bound_ctrl:1
	s_nop 0
	v_add_f32_dpp v80, v80, v80 row_ror:2 row_mask:0xf bank_mask:0xf bound_ctrl:1
	v_add_f32_dpp v82, v82, v82 row_ror:2 row_mask:0xf bank_mask:0xf bound_ctrl:1
	s_nop 0
	v_add_f32_dpp v80, v80, v80 row_ror:1 row_mask:0xf bank_mask:0xf bound_ctrl:1
	v_add_f32_dpp v82, v82, v82 row_ror:1 row_mask:0xf bank_mask:0xf bound_ctrl:1
	ds_write2_b32 v185, v80, v82 offset0:64 offset1:80
	s_waitcnt lgkmcnt(4)
	v_mul_f32 v125, v141, v116
	v_mul_f32 v116, v96, v116
	v_mul_f32 v150, v151, v117
	v_mul_f32 v117, v97, v117
	ds_read_b128 v[92:95], v134 offset:1024
	ds_read_b128 v[120:123], v134 offset:5120
	ds_read_b128 v[100:103], v134 offset:9216
	ds_read_b128 v[108:111], v134 offset:13312
	ds_read_b128 v[80:83], v134 offset:17408
	ds_read2_b32 v[148:149], v189 offset0:128 offset1:144
	v_fma_f32 v116, v98, v118, v116
	v_fma_f32 v125, v152, v118, v125
	v_fma_f32 v118, v124, v119, v150
	v_fma_f32 v117, v99, v119, v117
	v_add_f32_e32 v118, v125, v118
	v_add_f32_e32 v116, v116, v117
	s_nop 1
	v_add_f32_dpp v116, v116, v116 row_ror:8 row_mask:0xf bank_mask:0xf bound_ctrl:1
	v_add_f32_dpp v117, v118, v118 row_ror:8 row_mask:0xf bank_mask:0xf bound_ctrl:1
	s_nop 0
	v_add_f32_dpp v116, v116, v116 row_ror:4 row_mask:0xf bank_mask:0xf bound_ctrl:1
	v_add_f32_dpp v117, v117, v117 row_ror:4 row_mask:0xf bank_mask:0xf bound_ctrl:1
	s_nop 0
	v_add_f32_dpp v116, v116, v116 row_ror:2 row_mask:0xf bank_mask:0xf bound_ctrl:1
	v_add_f32_dpp v117, v117, v117 row_ror:2 row_mask:0xf bank_mask:0xf bound_ctrl:1
	s_nop 0
	v_add_f32_dpp v125, v116, v116 row_ror:1 row_mask:0xf bank_mask:0xf bound_ctrl:1
	s_waitcnt lgkmcnt(6)
	v_mul_f32 v116, v126, v112
	v_add_f32_dpp v119, v117, v117 row_ror:1 row_mask:0xf bank_mask:0xf bound_ctrl:1
	v_fma_f32 v116, v119, v104, v116
	v_mul_f32 v112, v127, v112
	v_fma_f32 v116, v141, v88, v116
	v_fma_f32 v104, v125, v104, v112
	v_fma_f32 v88, v96, v88, v104
	v_mul_f32 v96, v126, v113
	v_fma_f32 v96, v119, v105, v96
	v_fma_f32 v117, v151, v89, v96
	v_mul_f32 v96, v127, v113
	v_fma_f32 v96, v125, v105, v96
	v_fma_f32 v89, v97, v89, v96
	v_mul_f32 v96, v126, v114
	v_mul_f32 v97, v117, v85
	v_fma_f32 v96, v119, v106, v96
	v_mul_f32 v85, v89, v85
	v_fma_f32 v118, v152, v90, v96
	v_mul_f32 v96, v127, v114
	v_fma_f32 v96, v125, v106, v96
	v_fma_f32 v90, v98, v90, v96
	v_mul_f32 v96, v126, v115
	v_fma_f32 v96, v119, v107, v96
	v_fma_f32 v119, v124, v91, v96
	v_mul_f32 v96, v127, v115
	v_fma_f32 v96, v125, v107, v96
	v_fma_f32 v91, v99, v91, v96
	v_mul_f32 v96, v116, v84
	v_mul_f32 v84, v88, v84
	v_fma_f32 v96, v118, v86, v96
	v_fma_f32 v84, v90, v86, v84
	v_fma_f32 v86, v119, v87, v97
	v_fma_f32 v85, v91, v87, v85
	v_add_f32_e32 v86, v96, v86
	v_add_f32_e32 v87, v84, v85
	s_nop 0
	v_add_f32_dpp v84, v86, v86 row_ror:8 row_mask:0xf bank_mask:0xf bound_ctrl:1
	v_add_f32_dpp v86, v87, v87 row_ror:8 row_mask:0xf bank_mask:0xf bound_ctrl:1
	s_nop 0
	v_add_f32_dpp v84, v84, v84 row_ror:4 row_mask:0xf bank_mask:0xf bound_ctrl:1
	v_add_f32_dpp v86, v86, v86 row_ror:4 row_mask:0xf bank_mask:0xf bound_ctrl:1
	s_nop 0
	v_add_f32_dpp v84, v84, v84 row_ror:2 row_mask:0xf bank_mask:0xf bound_ctrl:1
	v_add_f32_dpp v86, v86, v86 row_ror:2 row_mask:0xf bank_mask:0xf bound_ctrl:1
	s_nop 0
	v_add_f32_dpp v84, v84, v84 row_ror:1 row_mask:0xf bank_mask:0xf bound_ctrl:1
	v_add_f32_dpp v86, v86, v86 row_ror:1 row_mask:0xf bank_mask:0xf bound_ctrl:1
	ds_write2_b32 v185, v84, v86 offset0:96 offset1:112
	s_waitcnt lgkmcnt(4)
	v_mul_f32 v141, v116, v120
	v_mul_f32 v120, v88, v120
	v_mul_f32 v152, v117, v121
	v_mul_f32 v121, v89, v121
	ds_read_b128 v[96:99], v134 offset:1280
	ds_read_b128 v[124:127], v134 offset:5376
	ds_read_b128 v[104:107], v134 offset:9472
	ds_read_b128 v[112:115], v134 offset:13568
	ds_read_b128 v[84:87], v134 offset:17664
	ds_read2_b32 v[150:151], v189 offset0:160 offset1:176
	v_fma_f32 v141, v118, v122, v141
	v_fma_f32 v120, v90, v122, v120
	v_fma_f32 v122, v119, v123, v152
	v_fma_f32 v121, v91, v123, v121
	v_add_f32_e32 v122, v141, v122
	v_add_f32_e32 v120, v120, v121
	s_nop 0
	v_add_f32_dpp v121, v122, v122 row_ror:8 row_mask:0xf bank_mask:0xf bound_ctrl:1
	v_add_f32_dpp v120, v120, v120 row_ror:8 row_mask:0xf bank_mask:0xf bound_ctrl:1
	s_waitcnt lgkmcnt(6)
	v_mul_f32 v122, v148, v108
	v_mul_f32 v108, v149, v108
	v_add_f32_dpp v121, v121, v121 row_ror:4 row_mask:0xf bank_mask:0xf bound_ctrl:1
	v_add_f32_dpp v120, v120, v120 row_ror:4 row_mask:0xf bank_mask:0xf bound_ctrl:1
	s_nop 0
	v_add_f32_dpp v121, v121, v121 row_ror:2 row_mask:0xf bank_mask:0xf bound_ctrl:1
	v_add_f32_dpp v120, v120, v120 row_ror:2 row_mask:0xf bank_mask:0xf bound_ctrl:1
	s_nop 0
	v_add_f32_dpp v121, v121, v121 row_ror:1 row_mask:0xf bank_mask:0xf bound_ctrl:1
	v_add_f32_dpp v120, v120, v120 row_ror:1 row_mask:0xf bank_mask:0xf bound_ctrl:1
	v_fma_f32 v122, v121, v100, v122
	v_fma_f32 v100, v120, v100, v108
	v_fma_f32 v141, v116, v92, v122
	v_fma_f32 v92, v88, v92, v100
	v_mul_f32 v88, v148, v109
	v_fma_f32 v88, v121, v101, v88
	v_fma_f32 v152, v117, v93, v88
	v_mul_f32 v88, v149, v109
	v_fma_f32 v88, v120, v101, v88
	v_fma_f32 v93, v89, v93, v88
	v_mul_f32 v88, v148, v110
	v_mul_f32 v89, v152, v81
	v_fma_f32 v88, v121, v102, v88
	v_mul_f32 v81, v93, v81
	v_fma_f32 v153, v118, v94, v88
	v_mul_f32 v88, v149, v110
	v_fma_f32 v88, v120, v102, v88
	v_fma_f32 v94, v90, v94, v88
	v_mul_f32 v88, v148, v111
	v_fma_f32 v88, v121, v103, v88
	v_fma_f32 v186, v119, v95, v88
	v_mul_f32 v88, v149, v111
	v_fma_f32 v88, v120, v103, v88
	v_fma_f32 v95, v91, v95, v88
	v_mul_f32 v88, v141, v80
	v_mul_f32 v80, v92, v80
	v_fma_f32 v88, v153, v82, v88
	v_fma_f32 v80, v94, v82, v80
	v_fma_f32 v82, v186, v83, v89
	v_fma_f32 v81, v95, v83, v81
	v_add_f32_e32 v82, v88, v82
	v_add_f32_e32 v83, v80, v81
	s_nop 0
	v_add_f32_dpp v80, v82, v82 row_ror:8 row_mask:0xf bank_mask:0xf bound_ctrl:1
	v_add_f32_dpp v82, v83, v83 row_ror:8 row_mask:0xf bank_mask:0xf bound_ctrl:1
	s_nop 0
	v_add_f32_dpp v80, v80, v80 row_ror:4 row_mask:0xf bank_mask:0xf bound_ctrl:1
	v_add_f32_dpp v82, v82, v82 row_ror:4 row_mask:0xf bank_mask:0xf bound_ctrl:1
	s_nop 0
	v_add_f32_dpp v80, v80, v80 row_ror:2 row_mask:0xf bank_mask:0xf bound_ctrl:1
	v_add_f32_dpp v82, v82, v82 row_ror:2 row_mask:0xf bank_mask:0xf bound_ctrl:1
	s_nop 0
	v_add_f32_dpp v80, v80, v80 row_ror:1 row_mask:0xf bank_mask:0xf bound_ctrl:1
	v_add_f32_dpp v82, v82, v82 row_ror:1 row_mask:0xf bank_mask:0xf bound_ctrl:1
	ds_write2_b32 v185, v80, v82 offset0:128 offset1:144
	s_waitcnt lgkmcnt(4)
	v_mul_f32 v80, v141, v124
	v_mul_f32 v82, v152, v125
	v_mul_f32 v81, v92, v124
	v_mul_f32 v83, v93, v125
	ds_read_b128 v[100:103], v134 offset:1536
	ds_read_b128 v[120:123], v134 offset:5632
	ds_read_b128 v[108:111], v134 offset:9728
	ds_read_b128 v[116:119], v134 offset:13824
	ds_read_b128 v[88:91], v134 offset:17920
	ds_read2_b32 v[148:149], v189 offset0:192 offset1:208
	v_fma_f32 v80, v153, v126, v80
	v_fma_f32 v82, v186, v127, v82
	v_fma_f32 v81, v94, v126, v81
	v_fma_f32 v83, v95, v127, v83
	v_add_f32_e32 v80, v80, v82
	v_add_f32_e32 v81, v81, v83
	s_nop 0
	v_add_f32_dpp v80, v80, v80 row_ror:8 row_mask:0xf bank_mask:0xf bound_ctrl:1
	s_waitcnt lgkmcnt(6)
	v_mul_f32 v82, v150, v112
	v_add_f32_dpp v81, v81, v81 row_ror:8 row_mask:0xf bank_mask:0xf bound_ctrl:1
	v_add_f32_dpp v80, v80, v80 row_ror:4 row_mask:0xf bank_mask:0xf bound_ctrl:1
	s_nop 0
	v_add_f32_dpp v81, v81, v81 row_ror:4 row_mask:0xf bank_mask:0xf bound_ctrl:1
	v_add_f32_dpp v80, v80, v80 row_ror:2 row_mask:0xf bank_mask:0xf bound_ctrl:1
	s_nop 0
	v_add_f32_dpp v81, v81, v81 row_ror:2 row_mask:0xf bank_mask:0xf bound_ctrl:1
	v_add_f32_dpp v80, v80, v80 row_ror:1 row_mask:0xf bank_mask:0xf bound_ctrl:1
	v_fma_f32 v82, v80, v104, v82
	v_fma_f32 v126, v141, v96, v82
	v_mul_f32 v82, v151, v112
	v_add_f32_dpp v81, v81, v81 row_ror:1 row_mask:0xf bank_mask:0xf bound_ctrl:1
	v_fma_f32 v82, v81, v104, v82
	v_fma_f32 v127, v92, v96, v82
	v_mul_f32 v82, v150, v113
	v_fma_f32 v82, v80, v105, v82
	v_fma_f32 v141, v152, v97, v82
	v_mul_f32 v82, v151, v113
	v_fma_f32 v82, v81, v105, v82
	v_fma_f32 v152, v93, v97, v82
	v_mul_f32 v82, v150, v114
	v_fma_f32 v82, v80, v106, v82
	v_mul_f32 v83, v152, v85
	v_fma_f32 v153, v153, v98, v82
	v_mul_f32 v82, v151, v114
	v_fma_f32 v82, v81, v106, v82
	v_fma_f32 v187, v94, v98, v82
	v_mul_f32 v82, v150, v115
	v_fma_f32 v80, v80, v107, v82
	v_mul_f32 v82, v141, v85
	v_fma_f32 v186, v186, v99, v80
	v_mul_f32 v80, v151, v115
	v_fma_f32 v80, v81, v107, v80
	v_mul_f32 v81, v127, v84
	v_fma_f32 v82, v186, v87, v82
	v_fma_f32 v151, v95, v99, v80
	v_mul_f32 v80, v126, v84
	v_fma_f32 v81, v187, v86, v81
	v_fma_f32 v80, v153, v86, v80
	v_fma_f32 v83, v151, v87, v83
	v_add_f32_e32 v80, v80, v82
	v_add_f32_e32 v82, v81, v83
	s_nop 0
	v_add_f32_dpp v80, v80, v80 row_ror:8 row_mask:0xf bank_mask:0xf bound_ctrl:1
	v_add_f32_dpp v82, v82, v82 row_ror:8 row_mask:0xf bank_mask:0xf bound_ctrl:1
	s_nop 0
	v_add_f32_dpp v80, v80, v80 row_ror:4 row_mask:0xf bank_mask:0xf bound_ctrl:1
	v_add_f32_dpp v82, v82, v82 row_ror:4 row_mask:0xf bank_mask:0xf bound_ctrl:1
	s_nop 0
	v_add_f32_dpp v80, v80, v80 row_ror:2 row_mask:0xf bank_mask:0xf bound_ctrl:1
	v_add_f32_dpp v82, v82, v82 row_ror:2 row_mask:0xf bank_mask:0xf bound_ctrl:1
	s_nop 0
	v_add_f32_dpp v80, v80, v80 row_ror:1 row_mask:0xf bank_mask:0xf bound_ctrl:1
	v_add_f32_dpp v82, v82, v82 row_ror:1 row_mask:0xf bank_mask:0xf bound_ctrl:1
	ds_write2_b32 v185, v80, v82 offset0:160 offset1:176
	s_waitcnt lgkmcnt(4)
	v_mul_f32 v84, v126, v120
	v_mul_f32 v86, v141, v121
	v_mul_f32 v85, v127, v120
	v_mul_f32 v87, v152, v121
	ds_read_b128 v[92:95], v134 offset:1792
	ds_read_b128 v[112:115], v134 offset:5888
	ds_read_b128 v[96:99], v134 offset:9984
	ds_read_b128 v[104:107], v134 offset:14080
	ds_read_b128 v[80:83], v134 offset:18176
	ds_read2_b32 v[124:125], v189 offset0:224 offset1:240
	v_fma_f32 v84, v153, v122, v84
	v_fma_f32 v86, v186, v123, v86
	v_fma_f32 v85, v187, v122, v85
	v_fma_f32 v87, v151, v123, v87
	v_add_f32_e32 v84, v84, v86
	v_add_f32_e32 v85, v85, v87
	s_nop 0
	v_add_f32_dpp v84, v84, v84 row_ror:8 row_mask:0xf bank_mask:0xf bound_ctrl:1
	s_waitcnt lgkmcnt(6)
	v_mul_f32 v86, v148, v116
	v_add_f32_dpp v85, v85, v85 row_ror:8 row_mask:0xf bank_mask:0xf bound_ctrl:1
	v_add_f32_dpp v84, v84, v84 row_ror:4 row_mask:0xf bank_mask:0xf bound_ctrl:1
	s_nop 0
	v_add_f32_dpp v85, v85, v85 row_ror:4 row_mask:0xf bank_mask:0xf bound_ctrl:1
	v_add_f32_dpp v84, v84, v84 row_ror:2 row_mask:0xf bank_mask:0xf bound_ctrl:1
	s_nop 0
	v_add_f32_dpp v85, v85, v85 row_ror:2 row_mask:0xf bank_mask:0xf bound_ctrl:1
	v_add_f32_dpp v84, v84, v84 row_ror:1 row_mask:0xf bank_mask:0xf bound_ctrl:1
	v_fma_f32 v86, v84, v108, v86
	v_fma_f32 v120, v126, v100, v86
	v_mul_f32 v86, v149, v116
	v_add_f32_dpp v85, v85, v85 row_ror:1 row_mask:0xf bank_mask:0xf bound_ctrl:1
	v_fma_f32 v86, v85, v108, v86
	v_fma_f32 v121, v127, v100, v86
	v_mul_f32 v86, v148, v117
	v_fma_f32 v86, v84, v109, v86
	v_fma_f32 v126, v141, v101, v86
	v_mul_f32 v86, v149, v117
	v_fma_f32 v86, v85, v109, v86
	v_fma_f32 v127, v152, v101, v86
	v_mul_f32 v86, v148, v118
	v_fma_f32 v86, v84, v110, v86
	v_mul_f32 v87, v127, v89
	v_fma_f32 v141, v153, v102, v86
	v_mul_f32 v86, v149, v118
	v_fma_f32 v86, v85, v110, v86
	v_fma_f32 v150, v187, v102, v86
	v_mul_f32 v86, v148, v119
	v_fma_f32 v84, v84, v111, v86
	v_mul_f32 v86, v126, v89
	v_fma_f32 v148, v186, v103, v84
	v_mul_f32 v84, v149, v119
	v_fma_f32 v84, v85, v111, v84
	v_mul_f32 v85, v121, v88
	v_fma_f32 v86, v148, v91, v86
	v_fma_f32 v149, v151, v103, v84
	v_mul_f32 v84, v120, v88
	v_fma_f32 v85, v150, v90, v85
	v_fma_f32 v84, v141, v90, v84
	v_fma_f32 v87, v149, v91, v87
	v_add_f32_e32 v84, v84, v86
	v_add_f32_e32 v86, v85, v87
	s_nop 0
	v_add_f32_dpp v84, v84, v84 row_ror:8 row_mask:0xf bank_mask:0xf bound_ctrl:1
	v_add_f32_dpp v86, v86, v86 row_ror:8 row_mask:0xf bank_mask:0xf bound_ctrl:1
	s_nop 0
	v_add_f32_dpp v84, v84, v84 row_ror:4 row_mask:0xf bank_mask:0xf bound_ctrl:1
	v_add_f32_dpp v86, v86, v86 row_ror:4 row_mask:0xf bank_mask:0xf bound_ctrl:1
	s_nop 0
	v_add_f32_dpp v84, v84, v84 row_ror:2 row_mask:0xf bank_mask:0xf bound_ctrl:1
	v_add_f32_dpp v86, v86, v86 row_ror:2 row_mask:0xf bank_mask:0xf bound_ctrl:1
	s_nop 0
	v_add_f32_dpp v84, v84, v84 row_ror:1 row_mask:0xf bank_mask:0xf bound_ctrl:1
	v_add_f32_dpp v86, v86, v86 row_ror:1 row_mask:0xf bank_mask:0xf bound_ctrl:1
	ds_write2_b32 v185, v84, v86 offset0:192 offset1:208
	s_waitcnt lgkmcnt(4)
	v_mul_f32 v151, v120, v112
	v_mul_f32 v112, v121, v112
	v_mul_f32 v152, v126, v113
	v_mul_f32 v113, v127, v113
	ds_read_b128 v[88:91], v134 offset:2048
	ds_read_b128 v[116:119], v134 offset:6144
	ds_read_b128 v[100:103], v134 offset:10240
	ds_read_b128 v[108:111], v134 offset:14336
	ds_read_b128 v[84:87], v134 offset:18432
	v_fma_f32 v151, v141, v114, v151
	v_fma_f32 v112, v150, v114, v112
	v_fma_f32 v114, v148, v115, v152
	v_fma_f32 v113, v149, v115, v113
	v_add_u32_e32 v187, 0x5400, v182
	v_add_f32_e32 v114, v151, v114
	v_add_f32_e32 v112, v112, v113
	ds_read2_b32 v[122:123], v187 offset1:16
	v_add_f32_dpp v113, v114, v114 row_ror:8 row_mask:0xf bank_mask:0xf bound_ctrl:1
	v_add_f32_dpp v112, v112, v112 row_ror:8 row_mask:0xf bank_mask:0xf bound_ctrl:1
	s_waitcnt lgkmcnt(6)
	v_mul_f32 v114, v124, v104
	v_mul_f32 v104, v125, v104
	v_add_f32_dpp v113, v113, v113 row_ror:4 row_mask:0xf bank_mask:0xf bound_ctrl:1
	v_add_f32_dpp v112, v112, v112 row_ror:4 row_mask:0xf bank_mask:0xf bound_ctrl:1
	s_nop 0
	v_add_f32_dpp v113, v113, v113 row_ror:2 row_mask:0xf bank_mask:0xf bound_ctrl:1
	v_add_f32_dpp v112, v112, v112 row_ror:2 row_mask:0xf bank_mask:0xf bound_ctrl:1
	s_nop 0
	v_add_f32_dpp v113, v113, v113 row_ror:1 row_mask:0xf bank_mask:0xf bound_ctrl:1
	v_add_f32_dpp v112, v112, v112 row_ror:1 row_mask:0xf bank_mask:0xf bound_ctrl:1
	v_fma_f32 v114, v113, v96, v114
	v_fma_f32 v96, v112, v96, v104
	v_fma_f32 v151, v120, v92, v114
	v_fma_f32 v152, v121, v92, v96
	v_mul_f32 v92, v124, v105
	v_fma_f32 v92, v113, v97, v92
	v_fma_f32 v126, v126, v93, v92
	v_mul_f32 v92, v125, v105
	v_fma_f32 v92, v112, v97, v92
	v_fma_f32 v127, v127, v93, v92
	v_mul_f32 v92, v124, v106
	v_mul_f32 v93, v126, v81
	v_fma_f32 v92, v113, v98, v92
	v_mul_f32 v81, v127, v81
	v_fma_f32 v141, v141, v94, v92
	v_mul_f32 v92, v125, v106
	v_fma_f32 v92, v112, v98, v92
	v_fma_f32 v150, v150, v94, v92
	v_mul_f32 v92, v124, v107
	v_fma_f32 v92, v113, v99, v92
	v_fma_f32 v153, v148, v95, v92
	v_mul_f32 v92, v125, v107
	v_fma_f32 v92, v112, v99, v92
	v_fma_f32 v186, v149, v95, v92
	v_mul_f32 v92, v151, v80
	v_mul_f32 v80, v152, v80
	v_fma_f32 v92, v141, v82, v92
	v_fma_f32 v80, v150, v82, v80
	v_fma_f32 v82, v153, v83, v93
	v_fma_f32 v81, v186, v83, v81
	v_add_f32_e32 v82, v92, v82
	v_add_f32_e32 v83, v80, v81
	s_nop 0
	v_add_f32_dpp v80, v82, v82 row_ror:8 row_mask:0xf bank_mask:0xf bound_ctrl:1
	v_add_f32_dpp v82, v83, v83 row_ror:8 row_mask:0xf bank_mask:0xf bound_ctrl:1
	s_nop 0
	v_add_f32_dpp v80, v80, v80 row_ror:4 row_mask:0xf bank_mask:0xf bound_ctrl:1
	v_add_f32_dpp v82, v82, v82 row_ror:4 row_mask:0xf bank_mask:0xf bound_ctrl:1
	s_nop 0
	v_add_f32_dpp v80, v80, v80 row_ror:2 row_mask:0xf bank_mask:0xf bound_ctrl:1
	v_add_f32_dpp v82, v82, v82 row_ror:2 row_mask:0xf bank_mask:0xf bound_ctrl:1
	s_nop 0
	v_add_f32_dpp v80, v80, v80 row_ror:1 row_mask:0xf bank_mask:0xf bound_ctrl:1
	v_add_f32_dpp v82, v82, v82 row_ror:1 row_mask:0xf bank_mask:0xf bound_ctrl:1
	ds_write2_b32 v185, v80, v82 offset0:224 offset1:240
	s_waitcnt lgkmcnt(4)
	v_mul_f32 v124, v151, v116
	v_mul_f32 v116, v152, v116
	v_mul_f32 v125, v126, v117
	v_mul_f32 v117, v127, v117
	ds_read_b128 v[92:95], v134 offset:2304
	ds_read_b128 v[112:115], v134 offset:6400
	ds_read_b128 v[96:99], v134 offset:10496
	ds_read_b128 v[104:107], v134 offset:14592
	ds_read_b128 v[80:83], v134 offset:18688
	ds_read2_b32 v[120:121], v187 offset0:32 offset1:48
	v_fma_f32 v124, v141, v118, v124
	v_fma_f32 v116, v150, v118, v116
	v_fma_f32 v118, v153, v119, v125
	v_fma_f32 v117, v186, v119, v117
	v_add_f32_e32 v118, v124, v118
	v_add_f32_e32 v116, v116, v117
	s_nop 0
	v_add_f32_dpp v117, v118, v118 row_ror:8 row_mask:0xf bank_mask:0xf bound_ctrl:1
	v_add_f32_dpp v116, v116, v116 row_ror:8 row_mask:0xf bank_mask:0xf bound_ctrl:1
	s_waitcnt lgkmcnt(6)
	v_mul_f32 v118, v122, v108
	v_mul_f32 v108, v123, v108
	v_add_f32_dpp v117, v117, v117 row_ror:4 row_mask:0xf bank_mask:0xf bound_ctrl:1
	v_add_f32_dpp v116, v116, v116 row_ror:4 row_mask:0xf bank_mask:0xf bound_ctrl:1
	s_nop 0
	v_add_f32_dpp v117, v117, v117 row_ror:2 row_mask:0xf bank_mask:0xf bound_ctrl:1
	v_add_f32_dpp v116, v116, v116 row_ror:2 row_mask:0xf bank_mask:0xf bound_ctrl:1
	s_nop 0
	v_add_f32_dpp v117, v117, v117 row_ror:1 row_mask:0xf bank_mask:0xf bound_ctrl:1
	v_add_f32_dpp v116, v116, v116 row_ror:1 row_mask:0xf bank_mask:0xf bound_ctrl:1
	v_fma_f32 v118, v117, v100, v118
	v_fma_f32 v100, v116, v100, v108
	v_fma_f32 v124, v151, v88, v118
	v_fma_f32 v125, v152, v88, v100
	v_mul_f32 v88, v122, v109
	v_fma_f32 v88, v117, v101, v88
	v_fma_f32 v126, v126, v89, v88
	v_mul_f32 v88, v123, v109
	v_fma_f32 v88, v116, v101, v88
	v_fma_f32 v127, v127, v89, v88
	v_mul_f32 v88, v122, v110
	v_mul_f32 v89, v126, v85
	v_fma_f32 v88, v117, v102, v88
	v_mul_f32 v85, v127, v85
	v_fma_f32 v141, v141, v90, v88
	v_mul_f32 v88, v123, v110
	v_fma_f32 v88, v116, v102, v88
	v_fma_f32 v148, v150, v90, v88
	v_mul_f32 v88, v122, v111
	v_fma_f32 v88, v117, v103, v88
	v_fma_f32 v149, v153, v91, v88
	v_mul_f32 v88, v123, v111
	v_fma_f32 v88, v116, v103, v88
	v_fma_f32 v150, v186, v91, v88
	v_mul_f32 v88, v124, v84
	v_mul_f32 v84, v125, v84
	v_add_u32_e32 v186, 0xb400, v182
	v_fma_f32 v88, v141, v86, v88
	v_fma_f32 v84, v148, v86, v84
	v_fma_f32 v86, v149, v87, v89
	v_fma_f32 v85, v150, v87, v85
	v_add_f32_e32 v86, v88, v86
	v_add_f32_e32 v87, v84, v85
	s_nop 0
	v_add_f32_dpp v84, v86, v86 row_ror:8 row_mask:0xf bank_mask:0xf bound_ctrl:1
	v_add_f32_dpp v86, v87, v87 row_ror:8 row_mask:0xf bank_mask:0xf bound_ctrl:1
	s_nop 0
	v_add_f32_dpp v84, v84, v84 row_ror:4 row_mask:0xf bank_mask:0xf bound_ctrl:1
	v_add_f32_dpp v86, v86, v86 row_ror:4 row_mask:0xf bank_mask:0xf bound_ctrl:1
	s_nop 0
	v_add_f32_dpp v84, v84, v84 row_ror:2 row_mask:0xf bank_mask:0xf bound_ctrl:1
	v_add_f32_dpp v86, v86, v86 row_ror:2 row_mask:0xf bank_mask:0xf bound_ctrl:1
	s_nop 0
	v_add_f32_dpp v84, v84, v84 row_ror:1 row_mask:0xf bank_mask:0xf bound_ctrl:1
	v_add_f32_dpp v86, v86, v86 row_ror:1 row_mask:0xf bank_mask:0xf bound_ctrl:1
	ds_write2_b32 v186, v84, v86 offset1:16
	s_waitcnt lgkmcnt(4)
	v_mul_f32 v151, v124, v112
	v_mul_f32 v112, v125, v112
	v_mul_f32 v152, v126, v113
	v_mul_f32 v113, v127, v113
	ds_read_b128 v[88:91], v134 offset:2560
	ds_read_b128 v[116:119], v134 offset:6656
	ds_read_b128 v[100:103], v134 offset:10752
	ds_read_b128 v[108:111], v134 offset:14848
	ds_read_b128 v[84:87], v134 offset:18944
	ds_read2_b32 v[122:123], v187 offset0:64 offset1:80
	v_fma_f32 v151, v141, v114, v151
	v_fma_f32 v112, v148, v114, v112
	v_fma_f32 v114, v149, v115, v152
	v_fma_f32 v113, v150, v115, v113
	v_add_f32_e32 v114, v151, v114
	v_add_f32_e32 v112, v112, v113
	s_nop 0
	v_add_f32_dpp v113, v114, v114 row_ror:8 row_mask:0xf bank_mask:0xf bound_ctrl:1
	v_add_f32_dpp v112, v112, v112 row_ror:8 row_mask:0xf bank_mask:0xf bound_ctrl:1
	s_waitcnt lgkmcnt(6)
	v_mul_f32 v114, v120, v104
	v_mul_f32 v104, v121, v104
	v_add_f32_dpp v113, v113, v113 row_ror:4 row_mask:0xf bank_mask:0xf bound_ctrl:1
	v_add_f32_dpp v112, v112, v112 row_ror:4 row_mask:0xf bank_mask:0xf bound_ctrl:1
	s_nop 0
	v_add_f32_dpp v113, v113, v113 row_ror:2 row_mask:0xf bank_mask:0xf bound_ctrl:1
	v_add_f32_dpp v112, v112, v112 row_ror:2 row_mask:0xf bank_mask:0xf bound_ctrl:1
	s_nop 0
	v_add_f32_dpp v113, v113, v113 row_ror:1 row_mask:0xf bank_mask:0xf bound_ctrl:1
	v_add_f32_dpp v112, v112, v112 row_ror:1 row_mask:0xf bank_mask:0xf bound_ctrl:1
	v_fma_f32 v114, v113, v96, v114
	v_fma_f32 v96, v112, v96, v104
	v_fma_f32 v124, v124, v92, v114
	v_fma_f32 v125, v125, v92, v96
	v_mul_f32 v92, v120, v105
	v_fma_f32 v92, v113, v97, v92
	v_fma_f32 v126, v126, v93, v92
	v_mul_f32 v92, v121, v105
	v_fma_f32 v92, v112, v97, v92
	v_fma_f32 v127, v127, v93, v92
	v_mul_f32 v92, v120, v106
	v_mul_f32 v93, v126, v81
	v_fma_f32 v92, v113, v98, v92
	v_mul_f32 v81, v127, v81
	v_fma_f32 v141, v141, v94, v92
	v_mul_f32 v92, v121, v106
	v_fma_f32 v92, v112, v98, v92
	v_fma_f32 v148, v148, v94, v92
	v_mul_f32 v92, v120, v107
	v_fma_f32 v92, v113, v99, v92
	v_fma_f32 v149, v149, v95, v92
	v_mul_f32 v92, v121, v107
	v_fma_f32 v92, v112, v99, v92
	v_fma_f32 v150, v150, v95, v92
	v_mul_f32 v92, v124, v80
	v_mul_f32 v80, v125, v80
	v_fma_f32 v92, v141, v82, v92
	v_fma_f32 v80, v148, v82, v80
	v_fma_f32 v82, v149, v83, v93
	v_fma_f32 v81, v150, v83, v81
	v_add_f32_e32 v82, v92, v82
	v_add_f32_e32 v83, v80, v81
	s_nop 0
	v_add_f32_dpp v80, v82, v82 row_ror:8 row_mask:0xf bank_mask:0xf bound_ctrl:1
	v_add_f32_dpp v82, v83, v83 row_ror:8 row_mask:0xf bank_mask:0xf bound_ctrl:1
	s_nop 0
	v_add_f32_dpp v80, v80, v80 row_ror:4 row_mask:0xf bank_mask:0xf bound_ctrl:1
	v_add_f32_dpp v82, v82, v82 row_ror:4 row_mask:0xf bank_mask:0xf bound_ctrl:1
	s_nop 0
	v_add_f32_dpp v80, v80, v80 row_ror:2 row_mask:0xf bank_mask:0xf bound_ctrl:1
	v_add_f32_dpp v82, v82, v82 row_ror:2 row_mask:0xf bank_mask:0xf bound_ctrl:1
	s_nop 0
	v_add_f32_dpp v80, v80, v80 row_ror:1 row_mask:0xf bank_mask:0xf bound_ctrl:1
	v_add_f32_dpp v82, v82, v82 row_ror:1 row_mask:0xf bank_mask:0xf bound_ctrl:1
	ds_write2_b32 v186, v80, v82 offset0:32 offset1:48
	s_waitcnt lgkmcnt(4)
	v_mul_f32 v151, v124, v116
	v_mul_f32 v116, v125, v116
	v_mul_f32 v152, v126, v117
	v_mul_f32 v117, v127, v117
	ds_read_b128 v[92:95], v134 offset:2816
	ds_read_b128 v[112:115], v134 offset:6912
	ds_read_b128 v[96:99], v134 offset:11008
	ds_read_b128 v[104:107], v134 offset:15104
	ds_read_b128 v[80:83], v134 offset:19200
	ds_read2_b32 v[120:121], v187 offset0:96 offset1:112
	v_fma_f32 v151, v141, v118, v151
	v_fma_f32 v116, v148, v118, v116
	v_fma_f32 v118, v149, v119, v152
	v_fma_f32 v117, v150, v119, v117
	v_add_f32_e32 v118, v151, v118
	v_add_f32_e32 v116, v116, v117
	s_nop 0
	v_add_f32_dpp v117, v118, v118 row_ror:8 row_mask:0xf bank_mask:0xf bound_ctrl:1
	v_add_f32_dpp v116, v116, v116 row_ror:8 row_mask:0xf bank_mask:0xf bound_ctrl:1
	s_waitcnt lgkmcnt(6)
	v_mul_f32 v118, v122, v108
	v_mul_f32 v108, v123, v108
	v_add_f32_dpp v117, v117, v117 row_ror:4 row_mask:0xf bank_mask:0xf bound_ctrl:1
	v_add_f32_dpp v116, v116, v116 row_ror:4 row_mask:0xf bank_mask:0xf bound_ctrl:1
	s_nop 0
	v_add_f32_dpp v117, v117, v117 row_ror:2 row_mask:0xf bank_mask:0xf bound_ctrl:1
	v_add_f32_dpp v116, v116, v116 row_ror:2 row_mask:0xf bank_mask:0xf bound_ctrl:1
	s_nop 0
	v_add_f32_dpp v117, v117, v117 row_ror:1 row_mask:0xf bank_mask:0xf bound_ctrl:1
	v_add_f32_dpp v116, v116, v116 row_ror:1 row_mask:0xf bank_mask:0xf bound_ctrl:1
	v_fma_f32 v118, v117, v100, v118
	v_fma_f32 v100, v116, v100, v108
	v_fma_f32 v124, v124, v88, v118
	v_fma_f32 v125, v125, v88, v100
	v_mul_f32 v88, v122, v109
	v_fma_f32 v88, v117, v101, v88
	v_fma_f32 v126, v126, v89, v88
	v_mul_f32 v88, v123, v109
	v_fma_f32 v88, v116, v101, v88
	v_fma_f32 v127, v127, v89, v88
	v_mul_f32 v88, v122, v110
	v_mul_f32 v89, v126, v85
	v_fma_f32 v88, v117, v102, v88
	v_mul_f32 v85, v127, v85
	v_fma_f32 v141, v141, v90, v88
	v_mul_f32 v88, v123, v110
	v_fma_f32 v88, v116, v102, v88
	v_fma_f32 v148, v148, v90, v88
	v_mul_f32 v88, v122, v111
	v_fma_f32 v88, v117, v103, v88
	v_fma_f32 v149, v149, v91, v88
	v_mul_f32 v88, v123, v111
	v_fma_f32 v88, v116, v103, v88
	v_fma_f32 v150, v150, v91, v88
	v_mul_f32 v88, v124, v84
	v_mul_f32 v84, v125, v84
	v_fma_f32 v88, v141, v86, v88
	v_fma_f32 v84, v148, v86, v84
	v_fma_f32 v86, v149, v87, v89
	v_fma_f32 v85, v150, v87, v85
	v_add_f32_e32 v86, v88, v86
	v_add_f32_e32 v87, v84, v85
	s_nop 0
	v_add_f32_dpp v84, v86, v86 row_ror:8 row_mask:0xf bank_mask:0xf bound_ctrl:1
	v_add_f32_dpp v86, v87, v87 row_ror:8 row_mask:0xf bank_mask:0xf bound_ctrl:1
	s_nop 0
	v_add_f32_dpp v84, v84, v84 row_ror:4 row_mask:0xf bank_mask:0xf bound_ctrl:1
	v_add_f32_dpp v86, v86, v86 row_ror:4 row_mask:0xf bank_mask:0xf bound_ctrl:1
	s_nop 0
	v_add_f32_dpp v84, v84, v84 row_ror:2 row_mask:0xf bank_mask:0xf bound_ctrl:1
	v_add_f32_dpp v86, v86, v86 row_ror:2 row_mask:0xf bank_mask:0xf bound_ctrl:1
	s_nop 0
	v_add_f32_dpp v84, v84, v84 row_ror:1 row_mask:0xf bank_mask:0xf bound_ctrl:1
	v_add_f32_dpp v86, v86, v86 row_ror:1 row_mask:0xf bank_mask:0xf bound_ctrl:1
	ds_write2_b32 v186, v84, v86 offset0:64 offset1:80
	s_waitcnt lgkmcnt(4)
	v_mul_f32 v151, v124, v112
	v_mul_f32 v112, v125, v112
	v_mul_f32 v152, v126, v113
	v_mul_f32 v113, v127, v113
	ds_read_b128 v[88:91], v134 offset:3072
	ds_read_b128 v[116:119], v134 offset:7168
	ds_read_b128 v[100:103], v134 offset:11264
	ds_read_b128 v[108:111], v134 offset:15360
	ds_read_b128 v[84:87], v134 offset:19456
	ds_read2_b32 v[122:123], v187 offset0:128 offset1:144
	v_fma_f32 v151, v141, v114, v151
	v_fma_f32 v112, v148, v114, v112
	v_fma_f32 v114, v149, v115, v152
	v_fma_f32 v113, v150, v115, v113
	v_add_f32_e32 v114, v151, v114
	v_add_f32_e32 v112, v112, v113
	s_nop 0
	v_add_f32_dpp v113, v114, v114 row_ror:8 row_mask:0xf bank_mask:0xf bound_ctrl:1
	v_add_f32_dpp v112, v112, v112 row_ror:8 row_mask:0xf bank_mask:0xf bound_ctrl:1
	s_waitcnt lgkmcnt(6)
	v_mul_f32 v114, v120, v104
	v_mul_f32 v104, v121, v104
	v_add_f32_dpp v113, v113, v113 row_ror:4 row_mask:0xf bank_mask:0xf bound_ctrl:1
	v_add_f32_dpp v112, v112, v112 row_ror:4 row_mask:0xf bank_mask:0xf bound_ctrl:1
	s_nop 0
	v_add_f32_dpp v113, v113, v113 row_ror:2 row_mask:0xf bank_mask:0xf bound_ctrl:1
	v_add_f32_dpp v112, v112, v112 row_ror:2 row_mask:0xf bank_mask:0xf bound_ctrl:1
	s_nop 0
	v_add_f32_dpp v113, v113, v113 row_ror:1 row_mask:0xf bank_mask:0xf bound_ctrl:1
	v_add_f32_dpp v112, v112, v112 row_ror:1 row_mask:0xf bank_mask:0xf bound_ctrl:1
	v_fma_f32 v114, v113, v96, v114
	v_fma_f32 v96, v112, v96, v104
	v_fma_f32 v124, v124, v92, v114
	v_fma_f32 v125, v125, v92, v96
	v_mul_f32 v92, v120, v105
	v_fma_f32 v92, v113, v97, v92
	v_fma_f32 v126, v126, v93, v92
	v_mul_f32 v92, v121, v105
	v_fma_f32 v92, v112, v97, v92
	v_fma_f32 v127, v127, v93, v92
	v_mul_f32 v92, v120, v106
	v_mul_f32 v93, v126, v81
	v_fma_f32 v92, v113, v98, v92
	v_mul_f32 v81, v127, v81
	v_fma_f32 v141, v141, v94, v92
	v_mul_f32 v92, v121, v106
	v_fma_f32 v92, v112, v98, v92
	v_fma_f32 v148, v148, v94, v92
	v_mul_f32 v92, v120, v107
	v_fma_f32 v92, v113, v99, v92
	v_fma_f32 v149, v149, v95, v92
	v_mul_f32 v92, v121, v107
	v_fma_f32 v92, v112, v99, v92
	v_fma_f32 v150, v150, v95, v92
	v_mul_f32 v92, v124, v80
	v_mul_f32 v80, v125, v80
	v_fma_f32 v92, v141, v82, v92
	v_fma_f32 v80, v148, v82, v80
	v_fma_f32 v82, v149, v83, v93
	v_fma_f32 v81, v150, v83, v81
	v_add_f32_e32 v82, v92, v82
	v_add_f32_e32 v83, v80, v81
	s_nop 0
	v_add_f32_dpp v80, v82, v82 row_ror:8 row_mask:0xf bank_mask:0xf bound_ctrl:1
	v_add_f32_dpp v82, v83, v83 row_ror:8 row_mask:0xf bank_mask:0xf bound_ctrl:1
	s_nop 0
	v_add_f32_dpp v80, v80, v80 row_ror:4 row_mask:0xf bank_mask:0xf bound_ctrl:1
	v_add_f32_dpp v82, v82, v82 row_ror:4 row_mask:0xf bank_mask:0xf bound_ctrl:1
	s_nop 0
	v_add_f32_dpp v80, v80, v80 row_ror:2 row_mask:0xf bank_mask:0xf bound_ctrl:1
	v_add_f32_dpp v82, v82, v82 row_ror:2 row_mask:0xf bank_mask:0xf bound_ctrl:1
	s_nop 0
	v_add_f32_dpp v80, v80, v80 row_ror:1 row_mask:0xf bank_mask:0xf bound_ctrl:1
	v_add_f32_dpp v82, v82, v82 row_ror:1 row_mask:0xf bank_mask:0xf bound_ctrl:1
	ds_write2_b32 v186, v80, v82 offset0:96 offset1:112
	s_waitcnt lgkmcnt(4)
	v_mul_f32 v151, v124, v116
	v_mul_f32 v116, v125, v116
	v_mul_f32 v152, v126, v117
	v_mul_f32 v117, v127, v117
	ds_read_b128 v[92:95], v134 offset:3328
	ds_read_b128 v[112:115], v134 offset:7424
	ds_read_b128 v[96:99], v134 offset:11520
	ds_read_b128 v[104:107], v134 offset:15616
	ds_read_b128 v[80:83], v134 offset:19712
	ds_read2_b32 v[120:121], v187 offset0:160 offset1:176
	v_fma_f32 v151, v141, v118, v151
	v_fma_f32 v116, v148, v118, v116
	v_fma_f32 v118, v149, v119, v152
	v_fma_f32 v117, v150, v119, v117
	v_add_f32_e32 v118, v151, v118
	v_add_f32_e32 v116, v116, v117
	s_nop 0
	v_add_f32_dpp v117, v118, v118 row_ror:8 row_mask:0xf bank_mask:0xf bound_ctrl:1
	v_add_f32_dpp v116, v116, v116 row_ror:8 row_mask:0xf bank_mask:0xf bound_ctrl:1
	s_waitcnt lgkmcnt(6)
	v_mul_f32 v118, v122, v108
	v_mul_f32 v108, v123, v108
	v_add_f32_dpp v117, v117, v117 row_ror:4 row_mask:0xf bank_mask:0xf bound_ctrl:1
	v_add_f32_dpp v116, v116, v116 row_ror:4 row_mask:0xf bank_mask:0xf bound_ctrl:1
	s_nop 0
	v_add_f32_dpp v117, v117, v117 row_ror:2 row_mask:0xf bank_mask:0xf bound_ctrl:1
	v_add_f32_dpp v116, v116, v116 row_ror:2 row_mask:0xf bank_mask:0xf bound_ctrl:1
	s_nop 0
	v_add_f32_dpp v117, v117, v117 row_ror:1 row_mask:0xf bank_mask:0xf bound_ctrl:1
	v_add_f32_dpp v116, v116, v116 row_ror:1 row_mask:0xf bank_mask:0xf bound_ctrl:1
	v_fma_f32 v118, v117, v100, v118
	v_fma_f32 v100, v116, v100, v108
	v_fma_f32 v124, v124, v88, v118
	v_fma_f32 v125, v125, v88, v100
	v_mul_f32 v88, v122, v109
	v_fma_f32 v88, v117, v101, v88
	v_fma_f32 v126, v126, v89, v88
	v_mul_f32 v88, v123, v109
	v_fma_f32 v88, v116, v101, v88
	v_fma_f32 v127, v127, v89, v88
	v_mul_f32 v88, v122, v110
	v_mul_f32 v89, v126, v85
	v_fma_f32 v88, v117, v102, v88
	v_mul_f32 v85, v127, v85
	v_fma_f32 v141, v141, v90, v88
	v_mul_f32 v88, v123, v110
	v_fma_f32 v88, v116, v102, v88
	v_fma_f32 v148, v148, v90, v88
	v_mul_f32 v88, v122, v111
	v_fma_f32 v88, v117, v103, v88
	v_fma_f32 v149, v149, v91, v88
	v_mul_f32 v88, v123, v111
	v_fma_f32 v88, v116, v103, v88
	v_fma_f32 v150, v150, v91, v88
	v_mul_f32 v88, v124, v84
	v_mul_f32 v84, v125, v84
	v_fma_f32 v88, v141, v86, v88
	v_fma_f32 v84, v148, v86, v84
	v_fma_f32 v86, v149, v87, v89
	v_fma_f32 v85, v150, v87, v85
	v_add_f32_e32 v86, v88, v86
	v_add_f32_e32 v87, v84, v85
	s_nop 0
	v_add_f32_dpp v84, v86, v86 row_ror:8 row_mask:0xf bank_mask:0xf bound_ctrl:1
	v_add_f32_dpp v86, v87, v87 row_ror:8 row_mask:0xf bank_mask:0xf bound_ctrl:1
	s_nop 0
	v_add_f32_dpp v84, v84, v84 row_ror:4 row_mask:0xf bank_mask:0xf bound_ctrl:1
	v_add_f32_dpp v86, v86, v86 row_ror:4 row_mask:0xf bank_mask:0xf bound_ctrl:1
	s_nop 0
	v_add_f32_dpp v84, v84, v84 row_ror:2 row_mask:0xf bank_mask:0xf bound_ctrl:1
	v_add_f32_dpp v86, v86, v86 row_ror:2 row_mask:0xf bank_mask:0xf bound_ctrl:1
	s_nop 0
	v_add_f32_dpp v84, v84, v84 row_ror:1 row_mask:0xf bank_mask:0xf bound_ctrl:1
	v_add_f32_dpp v86, v86, v86 row_ror:1 row_mask:0xf bank_mask:0xf bound_ctrl:1
	ds_write2_b32 v186, v84, v86 offset0:128 offset1:144
	s_waitcnt lgkmcnt(4)
	v_mul_f32 v151, v124, v112
	v_mul_f32 v112, v125, v112
	v_mul_f32 v152, v126, v113
	v_mul_f32 v113, v127, v113
	ds_read_b128 v[88:91], v134 offset:3584
	ds_read_b128 v[116:119], v134 offset:7680
	ds_read_b128 v[100:103], v134 offset:11776
	ds_read_b128 v[108:111], v134 offset:15872
	ds_read_b128 v[84:87], v134 offset:19968
	ds_read2_b32 v[122:123], v187 offset0:192 offset1:208
	v_fma_f32 v151, v141, v114, v151
	v_fma_f32 v112, v148, v114, v112
	v_fma_f32 v114, v149, v115, v152
	v_fma_f32 v113, v150, v115, v113
	v_add_f32_e32 v114, v151, v114
	v_add_f32_e32 v112, v112, v113
	s_nop 0
	v_add_f32_dpp v113, v114, v114 row_ror:8 row_mask:0xf bank_mask:0xf bound_ctrl:1
	v_add_f32_dpp v112, v112, v112 row_ror:8 row_mask:0xf bank_mask:0xf bound_ctrl:1
	s_waitcnt lgkmcnt(6)
	v_mul_f32 v114, v120, v104
	v_mul_f32 v104, v121, v104
	v_add_f32_dpp v113, v113, v113 row_ror:4 row_mask:0xf bank_mask:0xf bound_ctrl:1
	v_add_f32_dpp v112, v112, v112 row_ror:4 row_mask:0xf bank_mask:0xf bound_ctrl:1
	s_nop 0
	v_add_f32_dpp v113, v113, v113 row_ror:2 row_mask:0xf bank_mask:0xf bound_ctrl:1
	v_add_f32_dpp v112, v112, v112 row_ror:2 row_mask:0xf bank_mask:0xf bound_ctrl:1
	s_nop 0
	v_add_f32_dpp v113, v113, v113 row_ror:1 row_mask:0xf bank_mask:0xf bound_ctrl:1
	v_add_f32_dpp v112, v112, v112 row_ror:1 row_mask:0xf bank_mask:0xf bound_ctrl:1
	v_fma_f32 v114, v113, v96, v114
	v_fma_f32 v96, v112, v96, v104
	v_fma_f32 v124, v124, v92, v114
	v_fma_f32 v125, v125, v92, v96
	v_mul_f32 v92, v120, v105
	v_fma_f32 v92, v113, v97, v92
	v_fma_f32 v126, v126, v93, v92
	v_mul_f32 v92, v121, v105
	v_fma_f32 v92, v112, v97, v92
	v_fma_f32 v127, v127, v93, v92
	v_mul_f32 v92, v120, v106
	v_mul_f32 v93, v126, v81
	v_fma_f32 v92, v113, v98, v92
	v_mul_f32 v81, v127, v81
	v_fma_f32 v141, v141, v94, v92
	v_mul_f32 v92, v121, v106
	v_fma_f32 v92, v112, v98, v92
	v_fma_f32 v148, v148, v94, v92
	v_mul_f32 v92, v120, v107
	v_fma_f32 v92, v113, v99, v92
	v_fma_f32 v149, v149, v95, v92
	v_mul_f32 v92, v121, v107
	v_fma_f32 v92, v112, v99, v92
	v_fma_f32 v150, v150, v95, v92
	v_mul_f32 v92, v124, v80
	v_mul_f32 v80, v125, v80
	v_fma_f32 v92, v141, v82, v92
	v_fma_f32 v80, v148, v82, v80
	v_fma_f32 v82, v149, v83, v93
	v_fma_f32 v81, v150, v83, v81
	v_add_f32_e32 v82, v92, v82
	v_add_f32_e32 v83, v80, v81
	s_nop 0
	v_add_f32_dpp v80, v82, v82 row_ror:8 row_mask:0xf bank_mask:0xf bound_ctrl:1
	v_add_f32_dpp v82, v83, v83 row_ror:8 row_mask:0xf bank_mask:0xf bound_ctrl:1
	s_nop 0
	v_add_f32_dpp v80, v80, v80 row_ror:4 row_mask:0xf bank_mask:0xf bound_ctrl:1
	v_add_f32_dpp v82, v82, v82 row_ror:4 row_mask:0xf bank_mask:0xf bound_ctrl:1
	s_nop 0
	v_add_f32_dpp v80, v80, v80 row_ror:2 row_mask:0xf bank_mask:0xf bound_ctrl:1
	v_add_f32_dpp v82, v82, v82 row_ror:2 row_mask:0xf bank_mask:0xf bound_ctrl:1
	s_nop 0
	v_add_f32_dpp v80, v80, v80 row_ror:1 row_mask:0xf bank_mask:0xf bound_ctrl:1
	v_add_f32_dpp v82, v82, v82 row_ror:1 row_mask:0xf bank_mask:0xf bound_ctrl:1
	ds_write2_b32 v186, v80, v82 offset0:160 offset1:176
	s_waitcnt lgkmcnt(4)
	v_mul_f32 v151, v124, v116
	v_mul_f32 v116, v125, v116
	v_mul_f32 v152, v126, v117
	v_mul_f32 v117, v127, v117
	ds_read_b128 v[92:95], v134 offset:3840
	ds_read_b128 v[112:115], v134 offset:7936
	ds_read_b128 v[96:99], v134 offset:12032
	ds_read_b128 v[104:107], v134 offset:16128
	ds_read_b128 v[80:83], v134 offset:20224
	ds_read2_b32 v[120:121], v187 offset0:224 offset1:240
	v_fma_f32 v116, v148, v118, v116
	v_fma_f32 v151, v141, v118, v151
	v_fma_f32 v118, v149, v119, v152
	v_fma_f32 v117, v150, v119, v117
	v_add_f32_e32 v118, v151, v118
	v_add_f32_e32 v116, v116, v117
	s_nop 1
	v_add_f32_dpp v116, v116, v116 row_ror:8 row_mask:0xf bank_mask:0xf bound_ctrl:1
	v_add_f32_dpp v117, v118, v118 row_ror:8 row_mask:0xf bank_mask:0xf bound_ctrl:1
	s_nop 0
	v_add_f32_dpp v116, v116, v116 row_ror:4 row_mask:0xf bank_mask:0xf bound_ctrl:1
	v_add_f32_dpp v117, v117, v117 row_ror:4 row_mask:0xf bank_mask:0xf bound_ctrl:1
	s_nop 0
	v_add_f32_dpp v116, v116, v116 row_ror:2 row_mask:0xf bank_mask:0xf bound_ctrl:1
	v_add_f32_dpp v117, v117, v117 row_ror:2 row_mask:0xf bank_mask:0xf bound_ctrl:1
	s_nop 0
	v_add_f32_dpp v118, v116, v116 row_ror:1 row_mask:0xf bank_mask:0xf bound_ctrl:1
	s_waitcnt lgkmcnt(6)
	v_mul_f32 v116, v122, v108
	v_add_f32_dpp v117, v117, v117 row_ror:1 row_mask:0xf bank_mask:0xf bound_ctrl:1
	v_fma_f32 v116, v117, v100, v116
	v_mul_f32 v108, v123, v108
	v_fma_f32 v100, v118, v100, v108
	v_fma_f32 v116, v124, v88, v116
	v_mul_f32 v108, v123, v109
	v_fma_f32 v88, v125, v88, v100
	v_mul_f32 v100, v122, v109
	v_fma_f32 v100, v117, v101, v100
	v_fma_f32 v101, v118, v101, v108
	v_mul_f32 v108, v123, v110
	v_fma_f32 v100, v126, v89, v100
	v_fma_f32 v89, v127, v89, v101
	v_mul_f32 v101, v122, v110
	v_fma_f32 v101, v117, v102, v101
	v_fma_f32 v102, v118, v102, v108
	v_mul_f32 v108, v123, v111
	v_fma_f32 v101, v141, v90, v101
	v_fma_f32 v90, v148, v90, v102
	v_mul_f32 v102, v122, v111
	v_fma_f32 v102, v117, v103, v102
	v_fma_f32 v103, v118, v103, v108
	v_mul_f32 v108, v100, v85
	v_mul_f32 v85, v89, v85
	v_fma_f32 v102, v149, v91, v102
	v_fma_f32 v91, v150, v91, v103
	v_mul_f32 v103, v116, v84
	v_mul_f32 v84, v88, v84
	v_fma_f32 v103, v101, v86, v103
	v_fma_f32 v84, v90, v86, v84
	v_fma_f32 v86, v102, v87, v108
	v_fma_f32 v85, v91, v87, v85
	v_add_f32_e32 v86, v103, v86
	v_add_f32_e32 v87, v84, v85
	s_nop 0
	v_add_f32_dpp v84, v86, v86 row_ror:8 row_mask:0xf bank_mask:0xf bound_ctrl:1
	v_add_f32_dpp v86, v87, v87 row_ror:8 row_mask:0xf bank_mask:0xf bound_ctrl:1
	s_nop 0
	v_add_f32_dpp v84, v84, v84 row_ror:4 row_mask:0xf bank_mask:0xf bound_ctrl:1
	v_add_f32_dpp v86, v86, v86 row_ror:4 row_mask:0xf bank_mask:0xf bound_ctrl:1
	s_nop 0
	v_add_f32_dpp v84, v84, v84 row_ror:2 row_mask:0xf bank_mask:0xf bound_ctrl:1
	v_add_f32_dpp v86, v86, v86 row_ror:2 row_mask:0xf bank_mask:0xf bound_ctrl:1
	s_nop 0
	v_add_f32_dpp v84, v84, v84 row_ror:1 row_mask:0xf bank_mask:0xf bound_ctrl:1
	v_add_f32_dpp v86, v86, v86 row_ror:1 row_mask:0xf bank_mask:0xf bound_ctrl:1
	ds_write2_b32 v186, v84, v86 offset0:192 offset1:208
	s_waitcnt lgkmcnt(4)
	v_mul_f32 v84, v116, v112
	v_mul_f32 v86, v100, v113
	v_mul_f32 v85, v88, v112
	v_mul_f32 v87, v89, v113
	v_fma_f32 v84, v101, v114, v84
	v_fma_f32 v86, v102, v115, v86
	v_fma_f32 v85, v90, v114, v85
	v_fma_f32 v87, v91, v115, v87
	v_add_f32_e32 v84, v84, v86
	v_add_f32_e32 v85, v85, v87
	s_nop 0
	v_add_f32_dpp v84, v84, v84 row_ror:8 row_mask:0xf bank_mask:0xf bound_ctrl:1
	s_waitcnt lgkmcnt(0)
	v_mul_f32 v86, v120, v105
	v_mul_f32 v87, v121, v105
	v_add_f32_dpp v84, v84, v84 row_ror:4 row_mask:0xf bank_mask:0xf bound_ctrl:1
	s_nop 1
	v_add_f32_dpp v84, v84, v84 row_ror:2 row_mask:0xf bank_mask:0xf bound_ctrl:1
	s_nop 1
	v_add_f32_dpp v103, v84, v84 row_ror:1 row_mask:0xf bank_mask:0xf bound_ctrl:1
	v_add_f32_dpp v84, v85, v85 row_ror:8 row_mask:0xf bank_mask:0xf bound_ctrl:1
	v_mul_f32 v85, v121, v104
	v_fma_f32 v86, v103, v97, v86
	v_fma_f32 v86, v100, v93, v86
	v_add_f32_dpp v84, v84, v84 row_ror:4 row_mask:0xf bank_mask:0xf bound_ctrl:1
	s_nop 1
	v_add_f32_dpp v84, v84, v84 row_ror:2 row_mask:0xf bank_mask:0xf bound_ctrl:1
	s_nop 1
	v_add_f32_dpp v108, v84, v84 row_ror:1 row_mask:0xf bank_mask:0xf bound_ctrl:1
	v_fma_f32 v85, v108, v96, v85
	v_mul_f32 v84, v120, v104
	v_fma_f32 v87, v108, v97, v87
	v_fma_f32 v85, v88, v92, v85
	v_mul_f32 v88, v120, v106
	v_fma_f32 v84, v103, v96, v84
	v_fma_f32 v87, v89, v93, v87
	v_mul_f32 v89, v86, v81
	v_fma_f32 v88, v103, v98, v88
	v_fma_f32 v84, v116, v92, v84
	v_mul_f32 v81, v87, v81
	v_fma_f32 v96, v101, v94, v88
	v_mul_f32 v88, v121, v106
	v_fma_f32 v88, v108, v98, v88
	v_fma_f32 v97, v90, v94, v88
	v_mul_f32 v88, v120, v107
	v_fma_f32 v88, v103, v99, v88
	v_fma_f32 v98, v102, v95, v88
	v_mul_f32 v88, v121, v107
	v_fma_f32 v88, v108, v99, v88
	v_fma_f32 v99, v91, v95, v88
	v_mul_f32 v88, v84, v80
	v_mul_f32 v80, v85, v80
	v_fma_f32 v88, v96, v82, v88
	v_fma_f32 v80, v97, v82, v80
	v_fma_f32 v82, v98, v83, v89
	v_fma_f32 v81, v99, v83, v81
	v_add_f32_e32 v82, v88, v82
	v_add_f32_e32 v83, v80, v81
	s_nop 0
	v_add_f32_dpp v80, v82, v82 row_ror:8 row_mask:0xf bank_mask:0xf bound_ctrl:1
	v_add_f32_dpp v82, v83, v83 row_ror:8 row_mask:0xf bank_mask:0xf bound_ctrl:1
	s_nop 0
	v_add_f32_dpp v80, v80, v80 row_ror:4 row_mask:0xf bank_mask:0xf bound_ctrl:1
	v_add_f32_dpp v82, v82, v82 row_ror:4 row_mask:0xf bank_mask:0xf bound_ctrl:1
	s_nop 0
	v_add_f32_dpp v80, v80, v80 row_ror:2 row_mask:0xf bank_mask:0xf bound_ctrl:1
	v_add_f32_dpp v82, v82, v82 row_ror:2 row_mask:0xf bank_mask:0xf bound_ctrl:1
	s_nop 0
	v_add_f32_dpp v80, v80, v80 row_ror:1 row_mask:0xf bank_mask:0xf bound_ctrl:1
	v_add_f32_dpp v82, v82, v82 row_ror:1 row_mask:0xf bank_mask:0xf bound_ctrl:1
	ds_write2_b32 v186, v80, v82 offset0:224 offset1:240
	s_and_saveexec_b64 s[8:9], s[38:39]
	s_cbranch_execz .LBB0_375
	v_add_f32_e32 v88, v0, v44
	v_min_f32_e32 v92, 0, v88
	v_mul_f32_e64 v88, |v88|, s62
	v_exp_f32_e32 v88, v88
	v_add_f32_e32 v89, v1, v45
	v_add_f32_e32 v90, v2, v46
	v_add_f32_e32 v91, v3, v47
	v_add_f32_e32 v88, 1.0, v88
	v_cmp_gt_f32_e32 vcc, s5, v88
	s_mov_b32 s4, 0xf800000
	v_add_f32_e32 v80, v4, v28
	v_cndmask_b32_e64 v93, 0, 32, vcc
	v_ldexp_f32 v88, v88, v93
	v_log_f32_e32 v88, v88
	v_mul_f32_e32 v80, 0xbfb8aa3b, v80
	v_exp_f32_e32 v82, v80
	v_add_f32_e32 v80, v5, v29
	v_mul_f32_e32 v93, 0x3f317217, v88
	v_fma_f32 v93, v88, s76, -v93
	v_fmac_f32_e32 v93, 0x3377d1cf, v88
	v_fmac_f32_e32 v93, 0x3f317217, v88
	v_cmp_lt_f32_e64 s[42:43], |v88|, s77
	v_mul_f32_e32 v80, 0xbfb8aa3b, v80
	v_exp_f32_e32 v83, v80
	v_cndmask_b32_e64 v88, v88, v93, s[42:43]
	v_cndmask_b32_e32 v93, 0, v171, vcc
	v_sub_f32_e32 v88, v88, v93
	v_sub_f32_e32 v88, v92, v88
	v_min_f32_e32 v92, 0, v89
	v_mul_f32_e64 v89, |v89|, s62
	v_exp_f32_e32 v89, v89
	v_add_f32_e32 v88, -0.5, v88
	v_mul_f32_e32 v88, 0x3fb8aa3b, v88
	v_exp_f32_e32 v88, v88
	v_add_f32_e32 v89, 1.0, v89
	v_cmp_gt_f32_e32 vcc, s5, v89
	v_pk_add_f32 v[82:83], v[82:83], 1.0 op_sel_hi:[1,0]
	v_mul_f32_e32 v88, 0xbfb8aa3b, v88
	v_cndmask_b32_e64 v93, 0, 32, vcc
	v_ldexp_f32 v89, v89, v93
	v_log_f32_e32 v89, v89
	v_exp_f32_e32 v88, v88
	v_add_f32_e32 v80, v6, v30
	v_add_f32_e32 v81, v7, v31
	v_mul_f32_e32 v93, 0x3f317217, v89
	v_fma_f32 v93, v89, s76, -v93
	v_fmac_f32_e32 v93, 0x3377d1cf, v89
	v_fmac_f32_e32 v93, 0x3f317217, v89
	v_cmp_lt_f32_e64 s[42:43], |v89|, s77
	v_mul_f32_e32 v80, 0xbfb8aa3b, v80
	v_mul_f32_e32 v81, 0xbfb8aa3b, v81
	v_cndmask_b32_e64 v89, v89, v93, s[42:43]
	v_cndmask_b32_e32 v93, 0, v171, vcc
	v_sub_f32_e32 v89, v89, v93
	v_sub_f32_e32 v89, v92, v89
	v_min_f32_e32 v92, 0, v90
	v_mul_f32_e64 v90, |v90|, s62
	v_exp_f32_e32 v90, v90
	v_add_f32_e32 v89, -0.5, v89
	v_mul_f32_e32 v89, 0x3fb8aa3b, v89
	v_exp_f32_e32 v89, v89
	v_add_f32_e32 v90, 1.0, v90
	v_cmp_gt_f32_e32 vcc, s5, v90
	v_exp_f32_e32 v80, v80
	v_mul_f32_e32 v89, 0xbfb8aa3b, v89
	v_cndmask_b32_e64 v93, 0, 32, vcc
	v_ldexp_f32 v90, v90, v93
	v_log_f32_e32 v90, v90
	v_exp_f32_e32 v89, v89
	v_exp_f32_e32 v81, v81
	v_mul_f32_e32 v93, 0x3f317217, v90
	v_fma_f32 v93, v90, s76, -v93
	v_fmac_f32_e32 v93, 0x3377d1cf, v90
	v_fmac_f32_e32 v93, 0x3f317217, v90
	v_cmp_lt_f32_e64 s[42:43], |v90|, s77
	v_pk_add_f32 v[80:81], v[80:81], 1.0 op_sel_hi:[1,0]
	s_nop 0
	v_cndmask_b32_e64 v90, v90, v93, s[42:43]
	v_cndmask_b32_e32 v93, 0, v171, vcc
	v_sub_f32_e32 v90, v90, v93
	v_sub_f32_e32 v90, v92, v90
	v_min_f32_e32 v92, 0, v91
	v_mul_f32_e64 v91, |v91|, s62
	v_exp_f32_e32 v91, v91
	v_add_f32_e32 v90, -0.5, v90
	v_mul_f32_e32 v90, 0x3fb8aa3b, v90
	v_exp_f32_e32 v90, v90
	v_add_f32_e32 v91, 1.0, v91
	v_cmp_gt_f32_e32 vcc, s5, v91
	v_mul_f32_e32 v90, 0xbfb8aa3b, v90
	s_nop 0
	v_cndmask_b32_e64 v93, 0, 32, vcc
	v_ldexp_f32 v91, v91, v93
	v_log_f32_e32 v91, v91
	v_exp_f32_e32 v90, v90
	v_mul_f32_e32 v93, 0x3f317217, v91
	v_fma_f32 v93, v91, s76, -v93
	v_fmac_f32_e32 v93, 0x3377d1cf, v91
	v_fmac_f32_e32 v93, 0x3f317217, v91
	v_cmp_lt_f32_e64 s[42:43], |v91|, s77
	s_nop 1
	v_cndmask_b32_e64 v91, v91, v93, s[42:43]
	v_cndmask_b32_e32 v93, 0, v171, vcc
	v_sub_f32_e32 v91, v91, v93
	v_sub_f32_e32 v91, v92, v91
	v_add_f32_e32 v91, -0.5, v91
	v_mul_f32_e32 v91, 0x3fb8aa3b, v91
	v_exp_f32_e32 v91, v91
	v_pk_mul_f32 v[92:93], v[10:11], v[42:43]
	v_mul_f32_e32 v91, 0xbfb8aa3b, v91
	v_exp_f32_e32 v91, v91
	v_pk_mul_f32 v[94:95], v[92:93], v[92:93]
	ds_write_b128 v181, v[88:91] offset:22528
	v_pk_mul_f32 v[88:89], v[8:9], v[40:41]
	v_pk_mul_f32 v[90:91], v[88:89], v[88:89]
	v_add_f32_e32 v90, v91, v90
	v_add_f32_e32 v90, v94, v90
	v_add_f32_e32 v90, v95, v90
	s_nop 1
	v_add_f32_dpp v90, v90, v90 row_ror:8 row_mask:0xf bank_mask:0xf bound_ctrl:1
	s_nop 1
	v_add_f32_dpp v90, v90, v90 row_ror:4 row_mask:0xf bank_mask:0xf bound_ctrl:1
	s_nop 1
	v_add_f32_dpp v90, v90, v90 row_ror:2 row_mask:0xf bank_mask:0xf bound_ctrl:1
	s_nop 1
	v_add_f32_dpp v90, v90, v90 row_ror:1 row_mask:0xf bank_mask:0xf bound_ctrl:1
	v_cmp_gt_f32_e32 vcc, s4, v90
	v_mul_f32_e32 v91, 0x4f800000, v90
	s_nop 0
	v_cndmask_b32_e32 v90, v90, v91, vcc
	v_sqrt_f32_e32 v91, v90
	s_nop 0
	v_add_u32_e32 v94, -1, v91
	v_fma_f32 v95, -v94, v91, v90
	v_cmp_ge_f32_e64 s[42:43], 0, v95
	v_add_u32_e32 v95, 1, v91
	s_nop 0
	v_cndmask_b32_e64 v94, v91, v94, s[42:43]
	v_fma_f32 v91, -v95, v91, v90
	v_cmp_lt_f32_e64 s[42:43], 0, v91
	s_nop 1
	v_cndmask_b32_e64 v91, v94, v95, s[42:43]
	v_mul_f32_e32 v94, 0x37800000, v91
	v_cndmask_b32_e32 v91, v91, v94, vcc
	v_cmp_class_f32_e32 vcc, v90, v160
	s_nop 1
	v_cndmask_b32_e32 v90, v91, v90, vcc
	v_max_f32_e32 v90, 0x2b8cbccc, v90
	v_div_scale_f32 v91, s[22:23], v90, v90, 1.0
	v_rcp_f32_e32 v94, v91
	s_nop 0
	v_fma_f32 v95, -v91, v94, 1.0
	v_fmac_f32_e32 v94, v95, v94
	v_div_scale_f32 v95, vcc, 1.0, v90, 1.0
	v_mul_f32_e32 v100, v95, v94
	v_fma_f32 v101, -v91, v100, v95
	v_fmac_f32_e32 v100, v101, v94
	v_fma_f32 v91, -v91, v100, v95
	v_div_fmas_f32 v91, v91, v94, v100
	v_div_fixup_f32 v90, v91, v90, 1.0
	v_pk_mul_f32 v[94:95], v[88:89], v[90:91] op_sel_hi:[1,0]
	v_pk_mul_f32 v[92:93], v[92:93], v[90:91] op_sel_hi:[1,0]
	v_xor_b32_e32 v89, 0x80000000, v95
	v_xor_b32_e32 v88, 0x80000000, v94
	v_xor_b32_e32 v91, 0x80000000, v93
	v_xor_b32_e32 v90, 0x80000000, v92
	ds_write_b128 v181, v[88:91] offset:26624
	v_div_scale_f32 v88, s[22:23], v83, v83, 1.0
	v_rcp_f32_e32 v89, v88
	s_nop 0
	v_fma_f32 v90, -v88, v89, 1.0
	v_fmac_f32_e32 v89, v90, v89
	v_div_scale_f32 v90, vcc, 1.0, v83, 1.0
	v_mul_f32_e32 v91, v90, v89
	v_fma_f32 v100, -v88, v91, v90
	v_fmac_f32_e32 v91, v100, v89
	v_fma_f32 v88, -v88, v91, v90
	v_div_fmas_f32 v88, v88, v89, v91
	v_div_fixup_f32 v83, v88, v83, 1.0
	v_div_scale_f32 v88, s[22:23], v82, v82, 1.0
	v_rcp_f32_e32 v89, v88
	s_nop 0
	v_fma_f32 v90, -v88, v89, 1.0
	v_fmac_f32_e32 v89, v90, v89
	v_div_scale_f32 v90, vcc, 1.0, v82, 1.0
	v_mul_f32_e32 v91, v90, v89
	v_fma_f32 v100, -v88, v91, v90
	v_fmac_f32_e32 v91, v100, v89
	v_fma_f32 v88, -v88, v91, v90
	v_div_scale_f32 v90, s[22:23], v81, v81, 1.0
	v_div_fmas_f32 v88, v88, v89, v91
	v_rcp_f32_e32 v91, v90
	v_div_fixup_f32 v82, v88, v82, 1.0
	v_pk_mul_f32 v[88:89], v[82:83], v[94:95]
	v_fma_f32 v94, -v90, v91, 1.0
	v_fmac_f32_e32 v91, v94, v91
	v_div_scale_f32 v94, vcc, 1.0, v81, 1.0
	v_mul_f32_e32 v95, v94, v91
	v_fma_f32 v100, -v90, v95, v94
	v_fmac_f32_e32 v95, v100, v91
	v_fma_f32 v90, -v90, v95, v94
	v_div_fmas_f32 v90, v90, v91, v95
	v_div_fixup_f32 v95, v90, v81, 1.0
	v_div_scale_f32 v81, s[22:23], v80, v80, 1.0
	v_rcp_f32_e32 v90, v81
	s_nop 0
	v_fma_f32 v91, -v81, v90, 1.0
	v_fmac_f32_e32 v90, v91, v90
	v_div_scale_f32 v91, vcc, 1.0, v80, 1.0
	v_mul_f32_e32 v94, v91, v90
	v_fma_f32 v100, -v81, v94, v91
	v_fmac_f32_e32 v94, v100, v90
	v_fma_f32 v81, -v81, v94, v91
	v_div_fmas_f32 v81, v81, v90, v94
	v_div_fixup_f32 v94, v81, v80, 1.0
	v_pk_add_f32 v[80:81], v[82:83], -1.0 op_sel_hi:[1,0]
	v_pk_add_f32 v[82:83], v[94:95], -1.0 op_sel_hi:[1,0]
	v_pk_fma_f32 v[80:81], v[12:13], v[80:81], 1.0 op_sel_hi:[1,1,0]
	v_pk_fma_f32 v[82:83], v[14:15], v[82:83], 1.0 op_sel_hi:[1,1,0]
	v_pk_mul_f32 v[90:91], v[94:95], v[92:93]
	v_pk_mul_f32 v[80:81], v[40:41], v[80:81]
	v_pk_mul_f32 v[82:83], v[42:43], v[82:83]
	ds_write_b128 v181, v[88:91] offset:30720
	ds_write_b128 v181, v[80:83] offset:34816
	ds_write_b128 v181, v[16:19] offset:38912

.LBB0_381:
	ds_read2st64_b32 v[80:81], v179 offset0:176 offset1:180
	v_ashrrev_i32_e32 v127, 31, v126
	v_lshlrev_b64 v[82:83], 13, v[126:127]
	v_ashrrev_i32_e32 v125, 31, v124
	v_lshl_add_u64 v[82:83], v[144:145], 0, v[82:83]
	s_waitcnt lgkmcnt(0)
	global_store_dword v[82:83], v80, off
	v_lshlrev_b64 v[82:83], 13, v[124:125]
	v_lshl_add_u64 v[82:83], v[144:145], 0, v[82:83]
	global_store_dword v[82:83], v81, off
	ds_read_b128 v[104:107], v134 offset:22528
	ds_read_b128 v[88:91], v134 offset:22784
	ds_read_b128 v[108:111], v134 offset:26624
	ds_read_b128 v[112:115], v134 offset:26880
	ds_read_b128 v[116:119], v134 offset:30720
	ds_read_b128 v[92:95], v134 offset:30976
	ds_read_b128 v[150:153], v134 offset:34816
	ds_read_b128 v[100:103], v134 offset:35072
	ds_read_b128 v[192:195], v134 offset:38912
	ds_read_b128 v[80:83], v134 offset:39168
	s_waitcnt lgkmcnt(7)
	v_mul_f32 v122, v84, v108
	v_mul_f32 v108, v85, v108
	v_mul_f32 v123, v86, v109
	v_mul_f32 v109, v87, v109
	v_add_u32_e32 v190, 0xa800, v182
	v_fma_f32 v122, v96, v110, v122
	v_fma_f32 v108, v97, v110, v108
	v_fma_f32 v110, v98, v111, v123
	v_fma_f32 v109, v99, v111, v109
	ds_read2_b32 v[120:121], v190 offset0:32 offset1:48
	v_add_f32_e32 v110, v122, v110
	v_add_f32_e32 v111, v108, v109
	s_nop 0
	v_add_f32_dpp v110, v110, v110 row_ror:8 row_mask:0xf bank_mask:0xf bound_ctrl:1
	ds_read2_b32 v[108:109], v190 offset1:16
	v_add_f32_dpp v111, v111, v111 row_ror:8 row_mask:0xf bank_mask:0xf bound_ctrl:1
	v_add_f32_dpp v110, v110, v110 row_ror:4 row_mask:0xf bank_mask:0xf bound_ctrl:1
	s_waitcnt lgkmcnt(0)
	v_mul_f32 v122, v108, v150
	v_add_u32_e32 v188, 0xb800, v182
	v_add_f32_dpp v111, v111, v111 row_ror:4 row_mask:0xf bank_mask:0xf bound_ctrl:1
	v_add_f32_dpp v110, v110, v110 row_ror:2 row_mask:0xf bank_mask:0xf bound_ctrl:1
	s_nop 0
	v_add_f32_dpp v111, v111, v111 row_ror:2 row_mask:0xf bank_mask:0xf bound_ctrl:1
	v_add_f32_dpp v110, v110, v110 row_ror:1 row_mask:0xf bank_mask:0xf bound_ctrl:1
	v_fma_f32 v122, v110, v116, v122
	v_fma_f32 v122, v84, v104, v122
	v_mul_f32 v84, v109, v150
	v_add_f32_dpp v111, v111, v111 row_ror:1 row_mask:0xf bank_mask:0xf bound_ctrl:1
	v_fma_f32 v84, v111, v116, v84
	v_fma_f32 v123, v85, v104, v84
	v_mul_f32 v84, v108, v151
	v_fma_f32 v84, v110, v117, v84
	v_mul_f32 v85, v123, v192
	v_fma_f32 v125, v86, v105, v84
	v_mul_f32 v84, v109, v151
	v_fma_f32 v84, v111, v117, v84
	v_mul_f32 v86, v125, v193
	v_fma_f32 v127, v87, v105, v84
	v_mul_f32 v84, v108, v152
	v_fma_f32 v84, v110, v118, v84
	v_mul_f32 v87, v127, v193
	v_fma_f32 v141, v96, v106, v84
	v_mul_f32 v84, v109, v152
	v_fma_f32 v84, v111, v118, v84
	v_fma_f32 v150, v97, v106, v84
	v_mul_f32 v84, v108, v153
	v_fma_f32 v84, v110, v119, v84
	v_fma_f32 v85, v150, v194, v85
	v_fma_f32 v151, v98, v107, v84
	v_mul_f32 v84, v109, v153
	v_fma_f32 v84, v111, v119, v84
	v_fma_f32 v86, v151, v195, v86
	v_fma_f32 v152, v99, v107, v84
	v_mul_f32 v84, v122, v192
	v_fma_f32 v84, v141, v194, v84
	v_fma_f32 v87, v152, v195, v87
	v_add_f32_e32 v84, v84, v86
	v_add_f32_e32 v86, v85, v87
	s_nop 0
	v_add_f32_dpp v84, v84, v84 row_ror:8 row_mask:0xf bank_mask:0xf bound_ctrl:1
	v_add_f32_dpp v86, v86, v86 row_ror:8 row_mask:0xf bank_mask:0xf bound_ctrl:1
	s_nop 0
	v_add_f32_dpp v84, v84, v84 row_ror:4 row_mask:0xf bank_mask:0xf bound_ctrl:1
	v_add_f32_dpp v86, v86, v86 row_ror:4 row_mask:0xf bank_mask:0xf bound_ctrl:1
	s_nop 0
	v_add_f32_dpp v84, v84, v84 row_ror:2 row_mask:0xf bank_mask:0xf bound_ctrl:1
	v_add_f32_dpp v86, v86, v86 row_ror:2 row_mask:0xf bank_mask:0xf bound_ctrl:1
	s_nop 0
	v_add_f32_dpp v84, v84, v84 row_ror:1 row_mask:0xf bank_mask:0xf bound_ctrl:1
	v_add_f32_dpp v86, v86, v86 row_ror:1 row_mask:0xf bank_mask:0xf bound_ctrl:1
	ds_write2_b32 v188, v84, v86 offset1:16
	v_mul_f32 v153, v122, v112
	v_mul_f32 v112, v123, v112
	v_mul_f32 v191, v125, v113
	v_mul_f32 v113, v127, v113
	ds_read_b128 v[96:99], v134 offset:23040
	ds_read_b128 v[116:119], v134 offset:27136
	ds_read_b128 v[104:107], v134 offset:31232
	ds_read_b128 v[108:111], v134 offset:35328
	ds_read_b128 v[84:87], v134 offset:39424
	ds_read2_b32 v[148:149], v190 offset0:64 offset1:80
	v_fma_f32 v153, v141, v114, v153
	v_fma_f32 v112, v150, v114, v112
	v_fma_f32 v114, v151, v115, v191
	v_fma_f32 v113, v152, v115, v113
	v_add_f32_e32 v114, v153, v114
	v_add_f32_e32 v112, v112, v113
	s_nop 0
	v_add_f32_dpp v113, v114, v114 row_ror:8 row_mask:0xf bank_mask:0xf bound_ctrl:1
	v_add_f32_dpp v112, v112, v112 row_ror:8 row_mask:0xf bank_mask:0xf bound_ctrl:1
	v_mul_f32 v114, v120, v100
	v_mul_f32 v100, v121, v100
	v_add_f32_dpp v113, v113, v113 row_ror:4 row_mask:0xf bank_mask:0xf bound_ctrl:1
	v_add_f32_dpp v112, v112, v112 row_ror:4 row_mask:0xf bank_mask:0xf bound_ctrl:1
	s_nop 0
	v_add_f32_dpp v113, v113, v113 row_ror:2 row_mask:0xf bank_mask:0xf bound_ctrl:1
	v_add_f32_dpp v112, v112, v112 row_ror:2 row_mask:0xf bank_mask:0xf bound_ctrl:1
	s_nop 0
	v_add_f32_dpp v113, v113, v113 row_ror:1 row_mask:0xf bank_mask:0xf bound_ctrl:1
	v_add_f32_dpp v112, v112, v112 row_ror:1 row_mask:0xf bank_mask:0xf bound_ctrl:1
	v_fma_f32 v114, v113, v92, v114
	v_fma_f32 v92, v112, v92, v100
	v_fma_f32 v153, v122, v88, v114
	v_fma_f32 v92, v123, v88, v92
	v_mul_f32 v88, v120, v101
	v_fma_f32 v88, v113, v93, v88
	v_fma_f32 v125, v125, v89, v88
	v_mul_f32 v88, v121, v101
	v_fma_f32 v88, v112, v93, v88
	v_fma_f32 v93, v127, v89, v88
	v_mul_f32 v88, v120, v102
	v_mul_f32 v89, v125, v81
	v_fma_f32 v88, v113, v94, v88
	v_mul_f32 v81, v93, v81
	v_fma_f32 v127, v141, v90, v88
	v_mul_f32 v88, v121, v102
	v_fma_f32 v88, v112, v94, v88
	v_fma_f32 v94, v150, v90, v88
	v_mul_f32 v88, v120, v103
	v_fma_f32 v88, v113, v95, v88
	v_fma_f32 v141, v151, v91, v88
	v_mul_f32 v88, v121, v103
	v_fma_f32 v88, v112, v95, v88
	v_fma_f32 v95, v152, v91, v88
	v_mul_f32 v88, v153, v80
	v_mul_f32 v80, v92, v80
	v_fma_f32 v88, v127, v82, v88
	v_fma_f32 v80, v94, v82, v80
	v_fma_f32 v82, v141, v83, v89
	v_fma_f32 v81, v95, v83, v81
	v_add_f32_e32 v82, v88, v82
	v_add_f32_e32 v83, v80, v81
	s_nop 0
	v_add_f32_dpp v80, v82, v82 row_ror:8 row_mask:0xf bank_mask:0xf bound_ctrl:1
	v_add_f32_dpp v82, v83, v83 row_ror:8 row_mask:0xf bank_mask:0xf bound_ctrl:1
	s_nop 0
	v_add_f32_dpp v80, v80, v80 row_ror:4 row_mask:0xf bank_mask:0xf bound_ctrl:1
	v_add_f32_dpp v82, v82, v82 row_ror:4 row_mask:0xf bank_mask:0xf bound_ctrl:1
	s_nop 0
	v_add_f32_dpp v80, v80, v80 row_ror:2 row_mask:0xf bank_mask:0xf bound_ctrl:1
	v_add_f32_dpp v82, v82, v82 row_ror:2 row_mask:0xf bank_mask:0xf bound_ctrl:1
	s_nop 0
	v_add_f32_dpp v80, v80, v80 row_ror:1 row_mask:0xf bank_mask:0xf bound_ctrl:1
	v_add_f32_dpp v82, v82, v82 row_ror:1 row_mask:0xf bank_mask:0xf bound_ctrl:1
	ds_write2_b32 v188, v80, v82 offset0:32 offset1:48
	s_waitcnt lgkmcnt(4)
	v_mul_f32 v152, v153, v116
	v_mul_f32 v116, v92, v116
	v_mul_f32 v191, v125, v117
	v_mul_f32 v117, v93, v117
	ds_read_b128 v[88:91], v134 offset:23296
	ds_read_b128 v[120:123], v134 offset:27392
	ds_read_b128 v[100:103], v134 offset:31488
	ds_read_b128 v[112:115], v134 offset:35584
	ds_read_b128 v[80:83], v134 offset:39680
	ds_read2_b32 v[150:151], v190 offset0:96 offset1:112
	v_fma_f32 v152, v127, v118, v152
	v_fma_f32 v116, v94, v118, v116
	v_fma_f32 v118, v141, v119, v191
	v_fma_f32 v117, v95, v119, v117
	v_add_f32_e32 v118, v152, v118
	v_add_f32_e32 v116, v116, v117
	s_nop 0
	v_add_f32_dpp v117, v118, v118 row_ror:8 row_mask:0xf bank_mask:0xf bound_ctrl:1
	v_add_f32_dpp v116, v116, v116 row_ror:8 row_mask:0xf bank_mask:0xf bound_ctrl:1
	s_waitcnt lgkmcnt(6)
	v_mul_f32 v118, v148, v108
	v_mul_f32 v108, v149, v108
	v_add_f32_dpp v117, v117, v117 row_ror:4 row_mask:0xf bank_mask:0xf bound_ctrl:1
	v_add_f32_dpp v116, v116, v116 row_ror:4 row_mask:0xf bank_mask:0xf bound_ctrl:1
	s_nop 0
	v_add_f32_dpp v117, v117, v117 row_ror:2 row_mask:0xf bank_mask:0xf bound_ctrl:1
	v_add_f32_dpp v116, v116, v116 row_ror:2 row_mask:0xf bank_mask:0xf bound_ctrl:1
	s_nop 0
	v_add_f32_dpp v117, v117, v117 row_ror:1 row_mask:0xf bank_mask:0xf bound_ctrl:1
	v_add_f32_dpp v116, v116, v116 row_ror:1 row_mask:0xf bank_mask:0xf bound_ctrl:1
	v_fma_f32 v118, v117, v104, v118
	v_fma_f32 v104, v116, v104, v108
	v_fma_f32 v108, v92, v96, v104
	v_mul_f32 v92, v148, v109
	v_fma_f32 v152, v153, v96, v118
	v_fma_f32 v92, v117, v105, v92
	v_fma_f32 v125, v125, v97, v92
	v_mul_f32 v92, v149, v109
	v_fma_f32 v92, v116, v105, v92
	v_fma_f32 v109, v93, v97, v92
	v_mul_f32 v92, v148, v110
	v_mul_f32 v93, v125, v85
	v_fma_f32 v92, v117, v106, v92
	v_mul_f32 v85, v109, v85
	v_fma_f32 v127, v127, v98, v92
	v_mul_f32 v92, v149, v110
	v_fma_f32 v92, v116, v106, v92
	v_fma_f32 v110, v94, v98, v92
	v_mul_f32 v92, v148, v111
	v_fma_f32 v92, v117, v107, v92
	v_fma_f32 v141, v141, v99, v92
	v_mul_f32 v92, v149, v111
	v_fma_f32 v92, v116, v107, v92
	v_fma_f32 v111, v95, v99, v92
	v_mul_f32 v92, v152, v84
	v_mul_f32 v84, v108, v84
	v_fma_f32 v92, v127, v86, v92
	v_fma_f32 v84, v110, v86, v84
	v_fma_f32 v86, v141, v87, v93
	v_fma_f32 v85, v111, v87, v85
	v_add_f32_e32 v86, v92, v86
	v_add_f32_e32 v87, v84, v85
	s_nop 0
	v_add_f32_dpp v84, v86, v86 row_ror:8 row_mask:0xf bank_mask:0xf bound_ctrl:1
	v_add_f32_dpp v86, v87, v87 row_ror:8 row_mask:0xf bank_mask:0xf bound_ctrl:1
	s_nop 0
	v_add_f32_dpp v84, v84, v84 row_ror:4 row_mask:0xf bank_mask:0xf bound_ctrl:1
	v_add_f32_dpp v86, v86, v86 row_ror:4 row_mask:0xf bank_mask:0xf bound_ctrl:1
	s_nop 0
	v_add_f32_dpp v84, v84, v84 row_ror:2 row_mask:0xf bank_mask:0xf bound_ctrl:1
	v_add_f32_dpp v86, v86, v86 row_ror:2 row_mask:0xf bank_mask:0xf bound_ctrl:1
	s_nop 0
	v_add_f32_dpp v84, v84, v84 row_ror:1 row_mask:0xf bank_mask:0xf bound_ctrl:1
	v_add_f32_dpp v86, v86, v86 row_ror:1 row_mask:0xf bank_mask:0xf bound_ctrl:1
	ds_write2_b32 v188, v84, v86 offset0:64 offset1:80
	s_waitcnt lgkmcnt(4)
	v_mul_f32 v153, v152, v120
	v_mul_f32 v120, v108, v120
	v_mul_f32 v191, v125, v121
	v_mul_f32 v121, v109, v121
	ds_read_b128 v[92:95], v134 offset:23552
	ds_read_b128 v[116:119], v134 offset:27648
	ds_read_b128 v[96:99], v134 offset:31744
	ds_read_b128 v[104:107], v134 offset:35840
	ds_read_b128 v[84:87], v134 offset:39936
	ds_read2_b32 v[148:149], v190 offset0:128 offset1:144
	v_fma_f32 v120, v110, v122, v120
	v_fma_f32 v153, v127, v122, v153
	v_fma_f32 v122, v141, v123, v191
	v_fma_f32 v121, v111, v123, v121
	v_add_f32_e32 v122, v153, v122
	v_add_f32_e32 v120, v120, v121
	s_nop 1
	v_add_f32_dpp v120, v120, v120 row_ror:8 row_mask:0xf bank_mask:0xf bound_ctrl:1
	v_add_f32_dpp v121, v122, v122 row_ror:8 row_mask:0xf bank_mask:0xf bound_ctrl:1
	s_nop 0
	v_add_f32_dpp v120, v120, v120 row_ror:4 row_mask:0xf bank_mask:0xf bound_ctrl:1
	v_add_f32_dpp v121, v121, v121 row_ror:4 row_mask:0xf bank_mask:0xf bound_ctrl:1
	s_nop 0
	v_add_f32_dpp v120, v120, v120 row_ror:2 row_mask:0xf bank_mask:0xf bound_ctrl:1
	v_add_f32_dpp v121, v121, v121 row_ror:2 row_mask:0xf bank_mask:0xf bound_ctrl:1
	s_nop 0
	v_add_f32_dpp v191, v120, v120 row_ror:1 row_mask:0xf bank_mask:0xf bound_ctrl:1
	s_waitcnt lgkmcnt(6)
	v_mul_f32 v120, v150, v112
	v_add_f32_dpp v153, v121, v121 row_ror:1 row_mask:0xf bank_mask:0xf bound_ctrl:1
	v_fma_f32 v120, v153, v100, v120
	v_mul_f32 v112, v151, v112
	v_fma_f32 v120, v152, v88, v120
	v_fma_f32 v100, v191, v100, v112
	v_fma_f32 v121, v108, v88, v100
	v_mul_f32 v88, v150, v113
	v_fma_f32 v88, v153, v101, v88
	v_fma_f32 v122, v125, v89, v88
	v_mul_f32 v88, v151, v113
	v_fma_f32 v88, v191, v101, v88
	v_fma_f32 v123, v109, v89, v88
	v_mul_f32 v88, v150, v114
	v_mul_f32 v89, v122, v81
	v_fma_f32 v88, v153, v102, v88
	v_mul_f32 v81, v123, v81
	v_fma_f32 v125, v127, v90, v88
	v_mul_f32 v88, v151, v114
	v_fma_f32 v88, v191, v102, v88
	v_fma_f32 v127, v110, v90, v88
	v_mul_f32 v88, v150, v115
	v_fma_f32 v88, v153, v103, v88
	v_fma_f32 v141, v141, v91, v88
	v_mul_f32 v88, v151, v115
	v_fma_f32 v88, v191, v103, v88
	v_fma_f32 v152, v111, v91, v88
	v_mul_f32 v88, v120, v80
	v_mul_f32 v80, v121, v80
	v_fma_f32 v88, v125, v82, v88
	v_fma_f32 v80, v127, v82, v80
	v_fma_f32 v82, v141, v83, v89
	v_fma_f32 v81, v152, v83, v81
	v_add_f32_e32 v82, v88, v82
	v_add_f32_e32 v83, v80, v81
	s_nop 0
	v_add_f32_dpp v80, v82, v82 row_ror:8 row_mask:0xf bank_mask:0xf bound_ctrl:1
	v_add_f32_dpp v82, v83, v83 row_ror:8 row_mask:0xf bank_mask:0xf bound_ctrl:1
	s_nop 0
	v_add_f32_dpp v80, v80, v80 row_ror:4 row_mask:0xf bank_mask:0xf bound_ctrl:1
	v_add_f32_dpp v82, v82, v82 row_ror:4 row_mask:0xf bank_mask:0xf bound_ctrl:1
	s_nop 0
	v_add_f32_dpp v80, v80, v80 row_ror:2 row_mask:0xf bank_mask:0xf bound_ctrl:1
	v_add_f32_dpp v82, v82, v82 row_ror:2 row_mask:0xf bank_mask:0xf bound_ctrl:1
	s_nop 0
	v_add_f32_dpp v80, v80, v80 row_ror:1 row_mask:0xf bank_mask:0xf bound_ctrl:1
	v_add_f32_dpp v82, v82, v82 row_ror:1 row_mask:0xf bank_mask:0xf bound_ctrl:1
	ds_write2_b32 v188, v80, v82 offset0:96 offset1:112
	s_waitcnt lgkmcnt(4)
	v_mul_f32 v153, v120, v116
	v_mul_f32 v116, v121, v116
	v_mul_f32 v191, v122, v117
	v_mul_f32 v117, v123, v117
	ds_read_b128 v[88:91], v134 offset:23808
	ds_read_b128 v[112:115], v134 offset:27904
	ds_read_b128 v[100:103], v134 offset:32000
	ds_read_b128 v[108:111], v134 offset:36096
	ds_read_b128 v[80:83], v134 offset:40192
	ds_read2_b32 v[150:151], v190 offset0:160 offset1:176
	v_fma_f32 v116, v127, v118, v116
	v_fma_f32 v153, v125, v118, v153
	v_fma_f32 v118, v141, v119, v191
	v_fma_f32 v117, v152, v119, v117
	v_add_f32_e32 v118, v153, v118
	v_add_f32_e32 v116, v116, v117
	s_nop 1
	v_add_f32_dpp v116, v116, v116 row_ror:8 row_mask:0xf bank_mask:0xf bound_ctrl:1
	v_add_f32_dpp v117, v118, v118 row_ror:8 row_mask:0xf bank_mask:0xf bound_ctrl:1
	s_nop 0
	v_add_f32_dpp v116, v116, v116 row_ror:4 row_mask:0xf bank_mask:0xf bound_ctrl:1
	v_add_f32_dpp v117, v117, v117 row_ror:4 row_mask:0xf bank_mask:0xf bound_ctrl:1
	s_nop 0
	v_add_f32_dpp v116, v116, v116 row_ror:2 row_mask:0xf bank_mask:0xf bound_ctrl:1
	v_add_f32_dpp v117, v117, v117 row_ror:2 row_mask:0xf bank_mask:0xf bound_ctrl:1
	s_nop 0
	v_add_f32_dpp v191, v116, v116 row_ror:1 row_mask:0xf bank_mask:0xf bound_ctrl:1
	s_waitcnt lgkmcnt(6)
	v_mul_f32 v116, v148, v104
	v_add_f32_dpp v153, v117, v117 row_ror:1 row_mask:0xf bank_mask:0xf bound_ctrl:1
	v_fma_f32 v116, v153, v96, v116
	v_mul_f32 v104, v149, v104
	v_fma_f32 v116, v120, v92, v116
	v_fma_f32 v96, v191, v96, v104
	v_fma_f32 v117, v121, v92, v96
	v_mul_f32 v92, v148, v105
	v_fma_f32 v92, v153, v97, v92
	v_fma_f32 v118, v122, v93, v92
	v_mul_f32 v92, v149, v105
	v_fma_f32 v92, v191, v97, v92
	v_fma_f32 v119, v123, v93, v92
	v_mul_f32 v92, v148, v106
	v_mul_f32 v93, v118, v85
	v_fma_f32 v92, v153, v98, v92
	v_mul_f32 v85, v119, v85
	v_fma_f32 v125, v125, v94, v92
	v_mul_f32 v92, v149, v106
	v_fma_f32 v92, v191, v98, v92
	v_fma_f32 v127, v127, v94, v92
	v_mul_f32 v92, v148, v107
	v_fma_f32 v92, v153, v99, v92
	v_fma_f32 v141, v141, v95, v92
	v_mul_f32 v92, v149, v107
	v_fma_f32 v92, v191, v99, v92
	v_fma_f32 v148, v152, v95, v92
	v_mul_f32 v92, v116, v84
	v_mul_f32 v84, v117, v84
	v_fma_f32 v92, v125, v86, v92
	v_fma_f32 v84, v127, v86, v84
	v_fma_f32 v86, v141, v87, v93
	v_fma_f32 v85, v148, v87, v85
	v_add_f32_e32 v86, v92, v86
	v_add_f32_e32 v87, v84, v85
	s_nop 0
	v_add_f32_dpp v84, v86, v86 row_ror:8 row_mask:0xf bank_mask:0xf bound_ctrl:1
	v_add_f32_dpp v86, v87, v87 row_ror:8 row_mask:0xf bank_mask:0xf bound_ctrl:1
	s_nop 0
	v_add_f32_dpp v84, v84, v84 row_ror:4 row_mask:0xf bank_mask:0xf bound_ctrl:1
	v_add_f32_dpp v86, v86, v86 row_ror:4 row_mask:0xf bank_mask:0xf bound_ctrl:1
	s_nop 0
	v_add_f32_dpp v84, v84, v84 row_ror:2 row_mask:0xf bank_mask:0xf bound_ctrl:1
	v_add_f32_dpp v86, v86, v86 row_ror:2 row_mask:0xf bank_mask:0xf bound_ctrl:1
	s_nop 0
	v_add_f32_dpp v84, v84, v84 row_ror:1 row_mask:0xf bank_mask:0xf bound_ctrl:1
	v_add_f32_dpp v86, v86, v86 row_ror:1 row_mask:0xf bank_mask:0xf bound_ctrl:1
	ds_write2_b32 v188, v84, v86 offset0:128 offset1:144
	s_waitcnt lgkmcnt(4)
	v_mul_f32 v149, v116, v112
	v_mul_f32 v112, v117, v112
	v_mul_f32 v191, v118, v113
	v_mul_f32 v113, v119, v113
	ds_read_b128 v[92:95], v134 offset:24064
	ds_read_b128 v[120:123], v134 offset:28160
	ds_read_b128 v[96:99], v134 offset:32256
	ds_read_b128 v[104:107], v134 offset:36352
	ds_read_b128 v[84:87], v134 offset:40448
	ds_read2_b32 v[152:153], v190 offset0:192 offset1:208
	v_fma_f32 v112, v127, v114, v112
	v_fma_f32 v149, v125, v114, v149
	v_fma_f32 v114, v141, v115, v191
	v_fma_f32 v113, v148, v115, v113
	v_add_f32_e32 v114, v149, v114
	v_add_f32_e32 v112, v112, v113
	s_nop 1
	v_add_f32_dpp v112, v112, v112 row_ror:8 row_mask:0xf bank_mask:0xf bound_ctrl:1
	v_add_f32_dpp v113, v114, v114 row_ror:8 row_mask:0xf bank_mask:0xf bound_ctrl:1
	s_nop 0
	v_add_f32_dpp v112, v112, v112 row_ror:4 row_mask:0xf bank_mask:0xf bound_ctrl:1
	v_add_f32_dpp v113, v113, v113 row_ror:4 row_mask:0xf bank_mask:0xf bound_ctrl:1
	s_nop 0
	v_add_f32_dpp v112, v112, v112 row_ror:2 row_mask:0xf bank_mask:0xf bound_ctrl:1
	v_add_f32_dpp v113, v113, v113 row_ror:2 row_mask:0xf bank_mask:0xf bound_ctrl:1
	s_nop 0
	v_add_f32_dpp v194, v112, v112 row_ror:1 row_mask:0xf bank_mask:0xf bound_ctrl:1
	s_waitcnt lgkmcnt(6)
	v_mul_f32 v112, v150, v108
	v_add_f32_dpp v149, v113, v113 row_ror:1 row_mask:0xf bank_mask:0xf bound_ctrl:1
	v_fma_f32 v112, v149, v100, v112
	v_mul_f32 v108, v151, v108
	v_fma_f32 v112, v116, v88, v112
	v_fma_f32 v100, v194, v100, v108
	v_fma_f32 v113, v117, v88, v100
	v_mul_f32 v88, v150, v109
	v_fma_f32 v88, v149, v101, v88
	v_fma_f32 v114, v118, v89, v88
	v_mul_f32 v88, v151, v109
	v_fma_f32 v88, v194, v101, v88
	v_fma_f32 v115, v119, v89, v88
	v_mul_f32 v88, v150, v110
	v_mul_f32 v89, v114, v81
	v_fma_f32 v88, v149, v102, v88
	v_mul_f32 v81, v115, v81
	v_fma_f32 v191, v125, v90, v88
	v_mul_f32 v88, v151, v110
	v_fma_f32 v88, v194, v102, v88
	v_fma_f32 v192, v127, v90, v88
	v_mul_f32 v88, v150, v111
	v_fma_f32 v88, v149, v103, v88
	v_fma_f32 v193, v141, v91, v88
	v_mul_f32 v88, v151, v111
	v_fma_f32 v88, v194, v103, v88
	v_fma_f32 v194, v148, v91, v88
	v_mul_f32 v88, v112, v80
	v_mul_f32 v80, v113, v80
	v_fma_f32 v88, v191, v82, v88
	v_fma_f32 v80, v192, v82, v80
	v_fma_f32 v82, v193, v83, v89
	v_fma_f32 v81, v194, v83, v81
	v_add_f32_e32 v82, v88, v82
	v_add_f32_e32 v83, v80, v81
	s_nop 0
	v_add_f32_dpp v80, v82, v82 row_ror:8 row_mask:0xf bank_mask:0xf bound_ctrl:1
	v_add_f32_dpp v82, v83, v83 row_ror:8 row_mask:0xf bank_mask:0xf bound_ctrl:1
	s_nop 0
	v_add_f32_dpp v80, v80, v80 row_ror:4 row_mask:0xf bank_mask:0xf bound_ctrl:1
	v_add_f32_dpp v82, v82, v82 row_ror:4 row_mask:0xf bank_mask:0xf bound_ctrl:1
	s_nop 0
	v_add_f32_dpp v80, v80, v80 row_ror:2 row_mask:0xf bank_mask:0xf bound_ctrl:1
	v_add_f32_dpp v82, v82, v82 row_ror:2 row_mask:0xf bank_mask:0xf bound_ctrl:1
	s_nop 0
	v_add_f32_dpp v80, v80, v80 row_ror:1 row_mask:0xf bank_mask:0xf bound_ctrl:1
	v_add_f32_dpp v82, v82, v82 row_ror:1 row_mask:0xf bank_mask:0xf bound_ctrl:1
	ds_write2_b32 v188, v80, v82 offset0:160 offset1:176
	s_waitcnt lgkmcnt(4)
	v_mul_f32 v125, v112, v120
	v_mul_f32 v120, v113, v120
	v_mul_f32 v127, v114, v121
	v_mul_f32 v121, v115, v121
	ds_read_b128 v[88:91], v134 offset:24320
	ds_read_b128 v[116:119], v134 offset:28416
	ds_read_b128 v[100:103], v134 offset:32512
	ds_read_b128 v[108:111], v134 offset:36608
	ds_read_b128 v[80:83], v134 offset:40704
	ds_read2_b32 v[148:149], v190 offset0:224 offset1:240
	v_fma_f32 v120, v192, v122, v120
	v_fma_f32 v125, v191, v122, v125
	v_fma_f32 v122, v193, v123, v127
	v_fma_f32 v121, v194, v123, v121
	v_add_f32_e32 v122, v125, v122
	v_add_f32_e32 v120, v120, v121
	s_nop 1
	v_add_f32_dpp v120, v120, v120 row_ror:8 row_mask:0xf bank_mask:0xf bound_ctrl:1
	v_add_f32_dpp v121, v122, v122 row_ror:8 row_mask:0xf bank_mask:0xf bound_ctrl:1
	s_nop 0
	v_add_f32_dpp v120, v120, v120 row_ror:4 row_mask:0xf bank_mask:0xf bound_ctrl:1
	v_add_f32_dpp v121, v121, v121 row_ror:4 row_mask:0xf bank_mask:0xf bound_ctrl:1
	s_nop 0
	v_add_f32_dpp v120, v120, v120 row_ror:2 row_mask:0xf bank_mask:0xf bound_ctrl:1
	v_add_f32_dpp v121, v121, v121 row_ror:2 row_mask:0xf bank_mask:0xf bound_ctrl:1
	s_nop 0
	v_add_f32_dpp v123, v120, v120 row_ror:1 row_mask:0xf bank_mask:0xf bound_ctrl:1
	s_waitcnt lgkmcnt(6)
	v_mul_f32 v120, v152, v104
	v_add_f32_dpp v122, v121, v121 row_ror:1 row_mask:0xf bank_mask:0xf bound_ctrl:1
	v_fma_f32 v120, v122, v96, v120
	v_mul_f32 v104, v153, v104
	v_fma_f32 v120, v112, v92, v120
	v_fma_f32 v96, v123, v96, v104
	v_fma_f32 v121, v113, v92, v96
	v_mul_f32 v92, v152, v105
	v_fma_f32 v92, v122, v97, v92
	v_fma_f32 v125, v114, v93, v92
	v_mul_f32 v92, v153, v105
	v_fma_f32 v92, v123, v97, v92
	v_fma_f32 v127, v115, v93, v92
	v_mul_f32 v92, v152, v106
	v_mul_f32 v93, v125, v85
	v_fma_f32 v92, v122, v98, v92
	v_mul_f32 v85, v127, v85
	v_fma_f32 v141, v191, v94, v92
	v_mul_f32 v92, v153, v106
	v_fma_f32 v92, v123, v98, v92
	v_fma_f32 v150, v192, v94, v92
	v_mul_f32 v92, v152, v107
	v_fma_f32 v92, v122, v99, v92
	v_fma_f32 v151, v193, v95, v92
	v_mul_f32 v92, v153, v107
	v_fma_f32 v92, v123, v99, v92
	v_fma_f32 v153, v194, v95, v92
	v_mul_f32 v92, v120, v84
	v_mul_f32 v84, v121, v84
	v_fma_f32 v92, v141, v86, v92
	v_fma_f32 v84, v150, v86, v84
	v_fma_f32 v86, v151, v87, v93
	v_fma_f32 v85, v153, v87, v85
	v_add_f32_e32 v86, v92, v86
	v_add_f32_e32 v87, v84, v85
	s_nop 0
	v_add_f32_dpp v84, v86, v86 row_ror:8 row_mask:0xf bank_mask:0xf bound_ctrl:1
	v_add_f32_dpp v86, v87, v87 row_ror:8 row_mask:0xf bank_mask:0xf bound_ctrl:1
	s_nop 0
	v_add_f32_dpp v84, v84, v84 row_ror:4 row_mask:0xf bank_mask:0xf bound_ctrl:1
	v_add_f32_dpp v86, v86, v86 row_ror:4 row_mask:0xf bank_mask:0xf bound_ctrl:1
	s_nop 0
	v_add_f32_dpp v84, v84, v84 row_ror:2 row_mask:0xf bank_mask:0xf bound_ctrl:1
	v_add_f32_dpp v86, v86, v86 row_ror:2 row_mask:0xf bank_mask:0xf bound_ctrl:1
	s_nop 0
	v_add_f32_dpp v84, v84, v84 row_ror:1 row_mask:0xf bank_mask:0xf bound_ctrl:1
	v_add_f32_dpp v86, v86, v86 row_ror:1 row_mask:0xf bank_mask:0xf bound_ctrl:1
	ds_write2_b32 v188, v84, v86 offset0:192 offset1:208
	s_waitcnt lgkmcnt(4)
	v_mul_f32 v191, v120, v116
	v_mul_f32 v116, v121, v116
	v_mul_f32 v192, v125, v117
	v_mul_f32 v117, v127, v117
	ds_read_b128 v[112:115], v134 offset:28672
	ds_read_b128 v[96:99], v134 offset:32768
	ds_read_b128 v[104:107], v134 offset:36864
	ds_read_b128 v[92:95], v134 offset:24576
	ds_read_b128 v[84:87], v134 offset:40960
	v_fma_f32 v191, v141, v118, v191
	v_fma_f32 v116, v150, v118, v116
	v_fma_f32 v118, v151, v119, v192
	v_fma_f32 v117, v153, v119, v117
	v_add_u32_e32 v152, 0xac00, v182
	v_add_f32_e32 v118, v191, v118
	v_add_f32_e32 v116, v116, v117
	ds_read2_b32 v[122:123], v152 offset1:16
	v_add_f32_dpp v117, v118, v118 row_ror:8 row_mask:0xf bank_mask:0xf bound_ctrl:1
	v_add_f32_dpp v116, v116, v116 row_ror:8 row_mask:0xf bank_mask:0xf bound_ctrl:1
	s_waitcnt lgkmcnt(6)
	v_mul_f32 v118, v148, v108
	v_mul_f32 v108, v149, v108
	v_add_f32_dpp v117, v117, v117 row_ror:4 row_mask:0xf bank_mask:0xf bound_ctrl:1
	v_add_f32_dpp v116, v116, v116 row_ror:4 row_mask:0xf bank_mask:0xf bound_ctrl:1
	s_nop 0
	v_add_f32_dpp v117, v117, v117 row_ror:2 row_mask:0xf bank_mask:0xf bound_ctrl:1
	v_add_f32_dpp v116, v116, v116 row_ror:2 row_mask:0xf bank_mask:0xf bound_ctrl:1
	s_nop 0
	v_add_f32_dpp v117, v117, v117 row_ror:1 row_mask:0xf bank_mask:0xf bound_ctrl:1
	v_add_f32_dpp v116, v116, v116 row_ror:1 row_mask:0xf bank_mask:0xf bound_ctrl:1
	v_fma_f32 v118, v117, v100, v118
	v_fma_f32 v100, v116, v100, v108
	v_fma_f32 v191, v120, v88, v118
	v_fma_f32 v192, v121, v88, v100
	v_mul_f32 v88, v148, v109
	v_fma_f32 v88, v117, v101, v88
	v_fma_f32 v193, v125, v89, v88
	v_mul_f32 v88, v149, v109
	v_fma_f32 v88, v116, v101, v88
	v_fma_f32 v194, v127, v89, v88
	v_mul_f32 v88, v148, v110
	v_mul_f32 v89, v193, v81
	v_fma_f32 v88, v117, v102, v88
	v_mul_f32 v81, v194, v81
	v_fma_f32 v195, v141, v90, v88
	v_mul_f32 v88, v149, v110
	v_fma_f32 v88, v116, v102, v88
	v_fma_f32 v150, v150, v90, v88
	v_mul_f32 v88, v148, v111
	v_fma_f32 v88, v117, v103, v88
	v_fma_f32 v151, v151, v91, v88
	v_mul_f32 v88, v149, v111
	v_fma_f32 v88, v116, v103, v88
	v_fma_f32 v153, v153, v91, v88
	v_mul_f32 v88, v191, v80
	v_mul_f32 v80, v192, v80
	v_fma_f32 v88, v195, v82, v88
	v_fma_f32 v80, v150, v82, v80
	v_fma_f32 v82, v151, v83, v89
	v_fma_f32 v81, v153, v83, v81
	v_add_f32_e32 v82, v88, v82
	v_add_f32_e32 v83, v80, v81
	s_nop 0
	v_add_f32_dpp v80, v82, v82 row_ror:8 row_mask:0xf bank_mask:0xf bound_ctrl:1
	v_add_f32_dpp v82, v83, v83 row_ror:8 row_mask:0xf bank_mask:0xf bound_ctrl:1
	s_nop 0
	v_add_f32_dpp v80, v80, v80 row_ror:4 row_mask:0xf bank_mask:0xf bound_ctrl:1
	v_add_f32_dpp v82, v82, v82 row_ror:4 row_mask:0xf bank_mask:0xf bound_ctrl:1
	s_nop 0
	v_add_f32_dpp v80, v80, v80 row_ror:2 row_mask:0xf bank_mask:0xf bound_ctrl:1
	v_add_f32_dpp v82, v82, v82 row_ror:2 row_mask:0xf bank_mask:0xf bound_ctrl:1
	s_nop 0
	v_add_f32_dpp v80, v80, v80 row_ror:1 row_mask:0xf bank_mask:0xf bound_ctrl:1
	v_add_f32_dpp v82, v82, v82 row_ror:1 row_mask:0xf bank_mask:0xf bound_ctrl:1
	ds_write2_b32 v188, v80, v82 offset0:224 offset1:240
	s_waitcnt lgkmcnt(5)
	v_mul_f32 v125, v191, v112
	v_mul_f32 v112, v192, v112
	v_mul_f32 v127, v193, v113
	v_mul_f32 v113, v194, v113
	ds_read_b128 v[116:119], v134 offset:28928
	ds_read_b128 v[100:103], v134 offset:33024
	ds_read_b128 v[108:111], v134 offset:37120
	ds_read_b128 v[88:91], v134 offset:24832
	ds_read_b128 v[80:83], v134 offset:41216
	ds_read2_b32 v[120:121], v152 offset0:32 offset1:48
	v_fma_f32 v125, v195, v114, v125
	v_fma_f32 v112, v150, v114, v112
	v_fma_f32 v114, v151, v115, v127
	v_fma_f32 v113, v153, v115, v113
	v_add_f32_e32 v114, v125, v114
	v_add_f32_e32 v112, v112, v113
	s_nop 0
	v_add_f32_dpp v113, v114, v114 row_ror:8 row_mask:0xf bank_mask:0xf bound_ctrl:1
	v_add_f32_dpp v112, v112, v112 row_ror:8 row_mask:0xf bank_mask:0xf bound_ctrl:1
	s_waitcnt lgkmcnt(6)
	v_mul_f32 v114, v122, v104
	v_mul_f32 v104, v123, v104
	v_add_f32_dpp v113, v113, v113 row_ror:4 row_mask:0xf bank_mask:0xf bound_ctrl:1
	v_add_f32_dpp v112, v112, v112 row_ror:4 row_mask:0xf bank_mask:0xf bound_ctrl:1
	s_nop 0
	v_add_f32_dpp v113, v113, v113 row_ror:2 row_mask:0xf bank_mask:0xf bound_ctrl:1
	v_add_f32_dpp v112, v112, v112 row_ror:2 row_mask:0xf bank_mask:0xf bound_ctrl:1
	s_nop 0
	v_add_f32_dpp v113, v113, v113 row_ror:1 row_mask:0xf bank_mask:0xf bound_ctrl:1
	v_add_f32_dpp v112, v112, v112 row_ror:1 row_mask:0xf bank_mask:0xf bound_ctrl:1
	v_fma_f32 v114, v113, v96, v114
	v_fma_f32 v96, v112, v96, v104
	v_fma_f32 v125, v191, v92, v114
	v_fma_f32 v127, v192, v92, v96
	v_mul_f32 v92, v122, v105
	v_fma_f32 v92, v113, v97, v92
	v_fma_f32 v141, v193, v93, v92
	v_mul_f32 v92, v123, v105
	v_fma_f32 v92, v112, v97, v92
	v_fma_f32 v148, v194, v93, v92
	v_mul_f32 v92, v122, v106
	v_mul_f32 v93, v141, v85
	v_fma_f32 v92, v113, v98, v92
	v_mul_f32 v85, v148, v85
	v_fma_f32 v149, v195, v94, v92
	v_mul_f32 v92, v123, v106
	v_fma_f32 v92, v112, v98, v92
	v_fma_f32 v150, v150, v94, v92
	v_mul_f32 v92, v122, v107
	v_fma_f32 v92, v113, v99, v92
	v_fma_f32 v151, v151, v95, v92
	v_mul_f32 v92, v123, v107
	v_fma_f32 v92, v112, v99, v92
	v_fma_f32 v191, v153, v95, v92
	v_mul_f32 v92, v125, v84
	v_mul_f32 v84, v127, v84
	v_add_u32_e32 v153, 0xbc00, v182
	v_fma_f32 v92, v149, v86, v92
	v_fma_f32 v84, v150, v86, v84
	v_fma_f32 v86, v151, v87, v93
	v_fma_f32 v85, v191, v87, v85
	v_add_f32_e32 v86, v92, v86
	v_add_f32_e32 v87, v84, v85
	s_nop 0
	v_add_f32_dpp v84, v86, v86 row_ror:8 row_mask:0xf bank_mask:0xf bound_ctrl:1
	v_add_f32_dpp v86, v87, v87 row_ror:8 row_mask:0xf bank_mask:0xf bound_ctrl:1
	s_nop 0
	v_add_f32_dpp v84, v84, v84 row_ror:4 row_mask:0xf bank_mask:0xf bound_ctrl:1
	v_add_f32_dpp v86, v86, v86 row_ror:4 row_mask:0xf bank_mask:0xf bound_ctrl:1
	s_nop 0
	v_add_f32_dpp v84, v84, v84 row_ror:2 row_mask:0xf bank_mask:0xf bound_ctrl:1
	v_add_f32_dpp v86, v86, v86 row_ror:2 row_mask:0xf bank_mask:0xf bound_ctrl:1
	s_nop 0
	v_add_f32_dpp v84, v84, v84 row_ror:1 row_mask:0xf bank_mask:0xf bound_ctrl:1
	v_add_f32_dpp v86, v86, v86 row_ror:1 row_mask:0xf bank_mask:0xf bound_ctrl:1
	ds_write2_b32 v153, v84, v86 offset1:16
	s_waitcnt lgkmcnt(5)
	v_mul_f32 v192, v125, v116
	v_mul_f32 v116, v127, v116
	v_mul_f32 v193, v141, v117
	v_mul_f32 v117, v148, v117
	ds_read_b128 v[112:115], v134 offset:29184
	ds_read_b128 v[96:99], v134 offset:33280
	ds_read_b128 v[104:107], v134 offset:37376
	ds_read_b128 v[92:95], v134 offset:25088
	ds_read_b128 v[84:87], v134 offset:41472
	ds_read2_b32 v[122:123], v152 offset0:64 offset1:80
	v_fma_f32 v192, v149, v118, v192
	v_fma_f32 v116, v150, v118, v116
	v_fma_f32 v118, v151, v119, v193
	v_fma_f32 v117, v191, v119, v117
	v_add_f32_e32 v118, v192, v118
	v_add_f32_e32 v116, v116, v117
	s_nop 0
	v_add_f32_dpp v117, v118, v118 row_ror:8 row_mask:0xf bank_mask:0xf bound_ctrl:1
	v_add_f32_dpp v116, v116, v116 row_ror:8 row_mask:0xf bank_mask:0xf bound_ctrl:1
	s_waitcnt lgkmcnt(6)
	v_mul_f32 v118, v120, v108
	v_mul_f32 v108, v121, v108
	v_add_f32_dpp v117, v117, v117 row_ror:4 row_mask:0xf bank_mask:0xf bound_ctrl:1
	v_add_f32_dpp v116, v116, v116 row_ror:4 row_mask:0xf bank_mask:0xf bound_ctrl:1
	s_nop 0
	v_add_f32_dpp v117, v117, v117 row_ror:2 row_mask:0xf bank_mask:0xf bound_ctrl:1
	v_add_f32_dpp v116, v116, v116 row_ror:2 row_mask:0xf bank_mask:0xf bound_ctrl:1
	s_nop 0
	v_add_f32_dpp v117, v117, v117 row_ror:1 row_mask:0xf bank_mask:0xf bound_ctrl:1
	v_add_f32_dpp v116, v116, v116 row_ror:1 row_mask:0xf bank_mask:0xf bound_ctrl:1
	v_fma_f32 v118, v117, v100, v118
	v_fma_f32 v100, v116, v100, v108
	v_fma_f32 v125, v125, v88, v118
	v_fma_f32 v127, v127, v88, v100
	v_mul_f32 v88, v120, v109
	v_fma_f32 v88, v117, v101, v88
	v_fma_f32 v141, v141, v89, v88
	v_mul_f32 v88, v121, v109
	v_fma_f32 v88, v116, v101, v88
	v_fma_f32 v148, v148, v89, v88
	v_mul_f32 v88, v120, v110
	v_mul_f32 v89, v141, v81
	v_fma_f32 v88, v117, v102, v88
	v_mul_f32 v81, v148, v81
	v_fma_f32 v149, v149, v90, v88
	v_mul_f32 v88, v121, v110
	v_fma_f32 v88, v116, v102, v88
	v_fma_f32 v150, v150, v90, v88
	v_mul_f32 v88, v120, v111
	v_fma_f32 v88, v117, v103, v88
	v_fma_f32 v151, v151, v91, v88
	v_mul_f32 v88, v121, v111
	v_fma_f32 v88, v116, v103, v88
	v_fma_f32 v191, v191, v91, v88
	v_mul_f32 v88, v125, v80
	v_mul_f32 v80, v127, v80
	v_fma_f32 v88, v149, v82, v88
	v_fma_f32 v80, v150, v82, v80
	v_fma_f32 v82, v151, v83, v89
	v_fma_f32 v81, v191, v83, v81
	v_add_f32_e32 v82, v88, v82
	v_add_f32_e32 v83, v80, v81
	s_nop 0
	v_add_f32_dpp v80, v82, v82 row_ror:8 row_mask:0xf bank_mask:0xf bound_ctrl:1
	v_add_f32_dpp v82, v83, v83 row_ror:8 row_mask:0xf bank_mask:0xf bound_ctrl:1
	s_nop 0
	v_add_f32_dpp v80, v80, v80 row_ror:4 row_mask:0xf bank_mask:0xf bound_ctrl:1
	v_add_f32_dpp v82, v82, v82 row_ror:4 row_mask:0xf bank_mask:0xf bound_ctrl:1
	s_nop 0
	v_add_f32_dpp v80, v80, v80 row_ror:2 row_mask:0xf bank_mask:0xf bound_ctrl:1
	v_add_f32_dpp v82, v82, v82 row_ror:2 row_mask:0xf bank_mask:0xf bound_ctrl:1
	s_nop 0
	v_add_f32_dpp v80, v80, v80 row_ror:1 row_mask:0xf bank_mask:0xf bound_ctrl:1
	v_add_f32_dpp v82, v82, v82 row_ror:1 row_mask:0xf bank_mask:0xf bound_ctrl:1
	ds_write2_b32 v153, v80, v82 offset0:32 offset1:48
	s_waitcnt lgkmcnt(5)
	v_mul_f32 v192, v125, v112
	v_mul_f32 v112, v127, v112
	v_mul_f32 v193, v141, v113
	v_mul_f32 v113, v148, v113
	ds_read_b128 v[116:119], v134 offset:29440
	ds_read_b128 v[100:103], v134 offset:33536
	ds_read_b128 v[108:111], v134 offset:37632
	ds_read_b128 v[88:91], v134 offset:25344
	ds_read_b128 v[80:83], v134 offset:41728
	ds_read2_b32 v[120:121], v152 offset0:96 offset1:112
	v_fma_f32 v192, v149, v114, v192
	v_fma_f32 v112, v150, v114, v112
	v_fma_f32 v114, v151, v115, v193
	v_fma_f32 v113, v191, v115, v113
	v_add_f32_e32 v114, v192, v114
	v_add_f32_e32 v112, v112, v113
	s_nop 0
	v_add_f32_dpp v113, v114, v114 row_ror:8 row_mask:0xf bank_mask:0xf bound_ctrl:1
	v_add_f32_dpp v112, v112, v112 row_ror:8 row_mask:0xf bank_mask:0xf bound_ctrl:1
	s_waitcnt lgkmcnt(6)
	v_mul_f32 v114, v122, v104
	v_mul_f32 v104, v123, v104
	v_add_f32_dpp v113, v113, v113 row_ror:4 row_mask:0xf bank_mask:0xf bound_ctrl:1
	v_add_f32_dpp v112, v112, v112 row_ror:4 row_mask:0xf bank_mask:0xf bound_ctrl:1
	s_nop 0
	v_add_f32_dpp v113, v113, v113 row_ror:2 row_mask:0xf bank_mask:0xf bound_ctrl:1
	v_add_f32_dpp v112, v112, v112 row_ror:2 row_mask:0xf bank_mask:0xf bound_ctrl:1
	s_nop 0
	v_add_f32_dpp v113, v113, v113 row_ror:1 row_mask:0xf bank_mask:0xf bound_ctrl:1
	v_add_f32_dpp v112, v112, v112 row_ror:1 row_mask:0xf bank_mask:0xf bound_ctrl:1
	v_fma_f32 v114, v113, v96, v114
	v_fma_f32 v96, v112, v96, v104
	v_fma_f32 v125, v125, v92, v114
	v_fma_f32 v127, v127, v92, v96
	v_mul_f32 v92, v122, v105
	v_fma_f32 v92, v113, v97, v92
	v_fma_f32 v141, v141, v93, v92
	v_mul_f32 v92, v123, v105
	v_fma_f32 v92, v112, v97, v92
	v_fma_f32 v148, v148, v93, v92
	v_mul_f32 v92, v122, v106
	v_mul_f32 v93, v141, v85
	v_fma_f32 v92, v113, v98, v92
	v_mul_f32 v85, v148, v85
	v_fma_f32 v149, v149, v94, v92
	v_mul_f32 v92, v123, v106
	v_fma_f32 v92, v112, v98, v92
	v_fma_f32 v150, v150, v94, v92
	v_mul_f32 v92, v122, v107
	v_fma_f32 v92, v113, v99, v92
	v_fma_f32 v151, v151, v95, v92
	v_mul_f32 v92, v123, v107
	v_fma_f32 v92, v112, v99, v92
	v_fma_f32 v191, v191, v95, v92
	v_mul_f32 v92, v125, v84
	v_mul_f32 v84, v127, v84
	v_fma_f32 v92, v149, v86, v92
	v_fma_f32 v84, v150, v86, v84
	v_fma_f32 v86, v151, v87, v93
	v_fma_f32 v85, v191, v87, v85
	v_add_f32_e32 v86, v92, v86
	v_add_f32_e32 v87, v84, v85
	s_nop 0
	v_add_f32_dpp v84, v86, v86 row_ror:8 row_mask:0xf bank_mask:0xf bound_ctrl:1
	v_add_f32_dpp v86, v87, v87 row_ror:8 row_mask:0xf bank_mask:0xf bound_ctrl:1
	s_nop 0
	v_add_f32_dpp v84, v84, v84 row_ror:4 row_mask:0xf bank_mask:0xf bound_ctrl:1
	v_add_f32_dpp v86, v86, v86 row_ror:4 row_mask:0xf bank_mask:0xf bound_ctrl:1
	s_nop 0
	v_add_f32_dpp v84, v84, v84 row_ror:2 row_mask:0xf bank_mask:0xf bound_ctrl:1
	v_add_f32_dpp v86, v86, v86 row_ror:2 row_mask:0xf bank_mask:0xf bound_ctrl:1
	s_nop 0
	v_add_f32_dpp v84, v84, v84 row_ror:1 row_mask:0xf bank_mask:0xf bound_ctrl:1
	v_add_f32_dpp v86, v86, v86 row_ror:1 row_mask:0xf bank_mask:0xf bound_ctrl:1
	ds_write2_b32 v153, v84, v86 offset0:64 offset1:80
	s_waitcnt lgkmcnt(5)
	v_mul_f32 v192, v125, v116
	v_mul_f32 v116, v127, v116
	v_mul_f32 v193, v141, v117
	v_mul_f32 v117, v148, v117
	ds_read_b128 v[112:115], v134 offset:29696
	ds_read_b128 v[96:99], v134 offset:33792
	ds_read_b128 v[104:107], v134 offset:37888
	ds_read_b128 v[92:95], v134 offset:25600
	ds_read_b128 v[84:87], v134 offset:41984
	ds_read2_b32 v[122:123], v152 offset0:128 offset1:144
	v_fma_f32 v192, v149, v118, v192
	v_fma_f32 v116, v150, v118, v116
	v_fma_f32 v118, v151, v119, v193
	v_fma_f32 v117, v191, v119, v117
	v_add_f32_e32 v118, v192, v118
	v_add_f32_e32 v116, v116, v117
	s_nop 0
	v_add_f32_dpp v117, v118, v118 row_ror:8 row_mask:0xf bank_mask:0xf bound_ctrl:1
	v_add_f32_dpp v116, v116, v116 row_ror:8 row_mask:0xf bank_mask:0xf bound_ctrl:1
	s_waitcnt lgkmcnt(6)
	v_mul_f32 v118, v120, v108
	v_mul_f32 v108, v121, v108
	v_add_f32_dpp v117, v117, v117 row_ror:4 row_mask:0xf bank_mask:0xf bound_ctrl:1
	v_add_f32_dpp v116, v116, v116 row_ror:4 row_mask:0xf bank_mask:0xf bound_ctrl:1
	s_nop 0
	v_add_f32_dpp v117, v117, v117 row_ror:2 row_mask:0xf bank_mask:0xf bound_ctrl:1
	v_add_f32_dpp v116, v116, v116 row_ror:2 row_mask:0xf bank_mask:0xf bound_ctrl:1
	s_nop 0
	v_add_f32_dpp v117, v117, v117 row_ror:1 row_mask:0xf bank_mask:0xf bound_ctrl:1
	v_add_f32_dpp v116, v116, v116 row_ror:1 row_mask:0xf bank_mask:0xf bound_ctrl:1
	v_fma_f32 v118, v117, v100, v118
	v_fma_f32 v100, v116, v100, v108
	v_fma_f32 v125, v125, v88, v118
	v_fma_f32 v127, v127, v88, v100
	v_mul_f32 v88, v120, v109
	v_fma_f32 v88, v117, v101, v88
	v_fma_f32 v141, v141, v89, v88
	v_mul_f32 v88, v121, v109
	v_fma_f32 v88, v116, v101, v88
	v_fma_f32 v148, v148, v89, v88
	v_mul_f32 v88, v120, v110
	v_mul_f32 v89, v141, v81
	v_fma_f32 v88, v117, v102, v88
	v_mul_f32 v81, v148, v81
	v_fma_f32 v149, v149, v90, v88
	v_mul_f32 v88, v121, v110
	v_fma_f32 v88, v116, v102, v88
	v_fma_f32 v150, v150, v90, v88
	v_mul_f32 v88, v120, v111
	v_fma_f32 v88, v117, v103, v88
	v_fma_f32 v151, v151, v91, v88
	v_mul_f32 v88, v121, v111
	v_fma_f32 v88, v116, v103, v88
	v_fma_f32 v191, v191, v91, v88
	v_mul_f32 v88, v125, v80
	v_mul_f32 v80, v127, v80
	v_fma_f32 v88, v149, v82, v88
	v_fma_f32 v80, v150, v82, v80
	v_fma_f32 v82, v151, v83, v89
	v_fma_f32 v81, v191, v83, v81
	v_add_f32_e32 v82, v88, v82
	v_add_f32_e32 v83, v80, v81
	s_nop 0
	v_add_f32_dpp v80, v82, v82 row_ror:8 row_mask:0xf bank_mask:0xf bound_ctrl:1
	v_add_f32_dpp v82, v83, v83 row_ror:8 row_mask:0xf bank_mask:0xf bound_ctrl:1
	s_nop 0
	v_add_f32_dpp v80, v80, v80 row_ror:4 row_mask:0xf bank_mask:0xf bound_ctrl:1
	v_add_f32_dpp v82, v82, v82 row_ror:4 row_mask:0xf bank_mask:0xf bound_ctrl:1
	s_nop 0
	v_add_f32_dpp v80, v80, v80 row_ror:2 row_mask:0xf bank_mask:0xf bound_ctrl:1
	v_add_f32_dpp v82, v82, v82 row_ror:2 row_mask:0xf bank_mask:0xf bound_ctrl:1
	s_nop 0
	v_add_f32_dpp v80, v80, v80 row_ror:1 row_mask:0xf bank_mask:0xf bound_ctrl:1
	v_add_f32_dpp v82, v82, v82 row_ror:1 row_mask:0xf bank_mask:0xf bound_ctrl:1
	ds_write2_b32 v153, v80, v82 offset0:96 offset1:112
	s_waitcnt lgkmcnt(5)
	v_mul_f32 v192, v125, v112
	v_mul_f32 v112, v127, v112
	v_mul_f32 v193, v141, v113
	v_mul_f32 v113, v148, v113
	ds_read_b128 v[116:119], v134 offset:29952
	ds_read_b128 v[100:103], v134 offset:34048
	ds_read_b128 v[108:111], v134 offset:38144
	ds_read_b128 v[88:91], v134 offset:25856
	ds_read_b128 v[80:83], v134 offset:42240
	ds_read2_b32 v[120:121], v152 offset0:160 offset1:176
	v_fma_f32 v192, v149, v114, v192
	v_fma_f32 v112, v150, v114, v112
	v_fma_f32 v114, v151, v115, v193
	v_fma_f32 v113, v191, v115, v113
	v_add_f32_e32 v114, v192, v114
	v_add_f32_e32 v112, v112, v113
	s_nop 0
	v_add_f32_dpp v113, v114, v114 row_ror:8 row_mask:0xf bank_mask:0xf bound_ctrl:1
	v_add_f32_dpp v112, v112, v112 row_ror:8 row_mask:0xf bank_mask:0xf bound_ctrl:1
	s_waitcnt lgkmcnt(6)
	v_mul_f32 v114, v122, v104
	v_mul_f32 v104, v123, v104
	v_add_f32_dpp v113, v113, v113 row_ror:4 row_mask:0xf bank_mask:0xf bound_ctrl:1
	v_add_f32_dpp v112, v112, v112 row_ror:4 row_mask:0xf bank_mask:0xf bound_ctrl:1
	s_nop 0
	v_add_f32_dpp v113, v113, v113 row_ror:2 row_mask:0xf bank_mask:0xf bound_ctrl:1
	v_add_f32_dpp v112, v112, v112 row_ror:2 row_mask:0xf bank_mask:0xf bound_ctrl:1
	s_nop 0
	v_add_f32_dpp v113, v113, v113 row_ror:1 row_mask:0xf bank_mask:0xf bound_ctrl:1
	v_add_f32_dpp v112, v112, v112 row_ror:1 row_mask:0xf bank_mask:0xf bound_ctrl:1
	v_fma_f32 v114, v113, v96, v114
	v_fma_f32 v96, v112, v96, v104
	v_fma_f32 v125, v125, v92, v114
	v_fma_f32 v127, v127, v92, v96
	v_mul_f32 v92, v122, v105
	v_fma_f32 v92, v113, v97, v92
	v_fma_f32 v141, v141, v93, v92
	v_mul_f32 v92, v123, v105
	v_fma_f32 v92, v112, v97, v92
	v_fma_f32 v148, v148, v93, v92
	v_mul_f32 v92, v122, v106
	v_mul_f32 v93, v141, v85
	v_fma_f32 v92, v113, v98, v92
	v_mul_f32 v85, v148, v85
	v_fma_f32 v149, v149, v94, v92
	v_mul_f32 v92, v123, v106
	v_fma_f32 v92, v112, v98, v92
	v_fma_f32 v150, v150, v94, v92
	v_mul_f32 v92, v122, v107
	v_fma_f32 v92, v113, v99, v92
	v_fma_f32 v151, v151, v95, v92
	v_mul_f32 v92, v123, v107
	v_fma_f32 v92, v112, v99, v92
	v_fma_f32 v191, v191, v95, v92
	v_mul_f32 v92, v125, v84
	v_mul_f32 v84, v127, v84
	v_fma_f32 v92, v149, v86, v92
	v_fma_f32 v84, v150, v86, v84
	v_fma_f32 v86, v151, v87, v93
	v_fma_f32 v85, v191, v87, v85
	v_add_f32_e32 v86, v92, v86
	v_add_f32_e32 v87, v84, v85
	s_nop 0
	v_add_f32_dpp v84, v86, v86 row_ror:8 row_mask:0xf bank_mask:0xf bound_ctrl:1
	v_add_f32_dpp v86, v87, v87 row_ror:8 row_mask:0xf bank_mask:0xf bound_ctrl:1
	s_nop 0
	v_add_f32_dpp v84, v84, v84 row_ror:4 row_mask:0xf bank_mask:0xf bound_ctrl:1
	v_add_f32_dpp v86, v86, v86 row_ror:4 row_mask:0xf bank_mask:0xf bound_ctrl:1
	s_nop 0
	v_add_f32_dpp v84, v84, v84 row_ror:2 row_mask:0xf bank_mask:0xf bound_ctrl:1
	v_add_f32_dpp v86, v86, v86 row_ror:2 row_mask:0xf bank_mask:0xf bound_ctrl:1
	s_nop 0
	v_add_f32_dpp v84, v84, v84 row_ror:1 row_mask:0xf bank_mask:0xf bound_ctrl:1
	v_add_f32_dpp v86, v86, v86 row_ror:1 row_mask:0xf bank_mask:0xf bound_ctrl:1
	ds_write2_b32 v153, v84, v86 offset0:128 offset1:144
	s_waitcnt lgkmcnt(5)
	v_mul_f32 v192, v125, v116
	v_mul_f32 v116, v127, v116
	v_mul_f32 v193, v141, v117
	v_mul_f32 v117, v148, v117
	ds_read_b128 v[112:115], v134 offset:30208
	ds_read_b128 v[96:99], v134 offset:34304
	ds_read_b128 v[104:107], v134 offset:38400
	ds_read_b128 v[92:95], v134 offset:26112
	ds_read_b128 v[84:87], v134 offset:42496
	ds_read2_b32 v[122:123], v152 offset0:192 offset1:208
	v_fma_f32 v192, v149, v118, v192
	v_fma_f32 v116, v150, v118, v116
	v_fma_f32 v118, v151, v119, v193
	v_fma_f32 v117, v191, v119, v117
	v_add_f32_e32 v118, v192, v118
	v_add_f32_e32 v116, v116, v117
	s_nop 0
	v_add_f32_dpp v117, v118, v118 row_ror:8 row_mask:0xf bank_mask:0xf bound_ctrl:1
	v_add_f32_dpp v116, v116, v116 row_ror:8 row_mask:0xf bank_mask:0xf bound_ctrl:1
	s_waitcnt lgkmcnt(6)
	v_mul_f32 v118, v120, v108
	v_mul_f32 v108, v121, v108
	v_add_f32_dpp v117, v117, v117 row_ror:4 row_mask:0xf bank_mask:0xf bound_ctrl:1
	v_add_f32_dpp v116, v116, v116 row_ror:4 row_mask:0xf bank_mask:0xf bound_ctrl:1
	s_nop 0
	v_add_f32_dpp v117, v117, v117 row_ror:2 row_mask:0xf bank_mask:0xf bound_ctrl:1
	v_add_f32_dpp v116, v116, v116 row_ror:2 row_mask:0xf bank_mask:0xf bound_ctrl:1
	s_nop 0
	v_add_f32_dpp v117, v117, v117 row_ror:1 row_mask:0xf bank_mask:0xf bound_ctrl:1
	v_add_f32_dpp v116, v116, v116 row_ror:1 row_mask:0xf bank_mask:0xf bound_ctrl:1
	v_fma_f32 v118, v117, v100, v118
	v_fma_f32 v100, v116, v100, v108
	v_fma_f32 v125, v125, v88, v118
	v_fma_f32 v127, v127, v88, v100
	v_mul_f32 v88, v120, v109
	v_fma_f32 v88, v117, v101, v88
	v_fma_f32 v141, v141, v89, v88
	v_mul_f32 v88, v121, v109
	v_fma_f32 v88, v116, v101, v88
	v_fma_f32 v148, v148, v89, v88
	v_mul_f32 v88, v120, v110
	v_mul_f32 v89, v141, v81
	v_fma_f32 v88, v117, v102, v88
	v_mul_f32 v81, v148, v81
	v_fma_f32 v149, v149, v90, v88
	v_mul_f32 v88, v121, v110
	v_fma_f32 v88, v116, v102, v88
	v_fma_f32 v150, v150, v90, v88
	v_mul_f32 v88, v120, v111
	v_fma_f32 v88, v117, v103, v88
	v_fma_f32 v151, v151, v91, v88
	v_mul_f32 v88, v121, v111
	v_fma_f32 v88, v116, v103, v88
	v_fma_f32 v191, v191, v91, v88
	v_mul_f32 v88, v125, v80
	v_mul_f32 v80, v127, v80
	v_fma_f32 v88, v149, v82, v88
	v_fma_f32 v80, v150, v82, v80
	v_fma_f32 v82, v151, v83, v89
	v_fma_f32 v81, v191, v83, v81
	v_add_f32_e32 v82, v88, v82
	v_add_f32_e32 v83, v80, v81
	s_nop 0
	v_add_f32_dpp v80, v82, v82 row_ror:8 row_mask:0xf bank_mask:0xf bound_ctrl:1
	v_add_f32_dpp v82, v83, v83 row_ror:8 row_mask:0xf bank_mask:0xf bound_ctrl:1
	s_nop 0
	v_add_f32_dpp v80, v80, v80 row_ror:4 row_mask:0xf bank_mask:0xf bound_ctrl:1
	v_add_f32_dpp v82, v82, v82 row_ror:4 row_mask:0xf bank_mask:0xf bound_ctrl:1
	s_nop 0
	v_add_f32_dpp v80, v80, v80 row_ror:2 row_mask:0xf bank_mask:0xf bound_ctrl:1
	v_add_f32_dpp v82, v82, v82 row_ror:2 row_mask:0xf bank_mask:0xf bound_ctrl:1
	s_nop 0
	v_add_f32_dpp v80, v80, v80 row_ror:1 row_mask:0xf bank_mask:0xf bound_ctrl:1
	v_add_f32_dpp v82, v82, v82 row_ror:1 row_mask:0xf bank_mask:0xf bound_ctrl:1
	ds_write2_b32 v153, v80, v82 offset0:160 offset1:176
	s_waitcnt lgkmcnt(5)
	v_mul_f32 v192, v125, v112
	v_mul_f32 v112, v127, v112
	v_mul_f32 v193, v141, v113
	v_mul_f32 v113, v148, v113
	ds_read_b128 v[116:119], v134 offset:30464
	ds_read_b128 v[100:103], v134 offset:34560
	ds_read_b128 v[108:111], v134 offset:38656
	ds_read_b128 v[88:91], v134 offset:26368
	ds_read_b128 v[80:83], v134 offset:42752
	ds_read2_b32 v[120:121], v152 offset0:224 offset1:240
	v_fma_f32 v112, v150, v114, v112
	v_fma_f32 v192, v149, v114, v192
	v_fma_f32 v114, v151, v115, v193
	v_fma_f32 v113, v191, v115, v113
	v_add_f32_e32 v114, v192, v114
	v_add_f32_e32 v112, v112, v113
	s_nop 1
	v_add_f32_dpp v112, v112, v112 row_ror:8 row_mask:0xf bank_mask:0xf bound_ctrl:1
	v_add_f32_dpp v113, v114, v114 row_ror:8 row_mask:0xf bank_mask:0xf bound_ctrl:1
	s_nop 0
	v_add_f32_dpp v112, v112, v112 row_ror:4 row_mask:0xf bank_mask:0xf bound_ctrl:1
	v_add_f32_dpp v113, v113, v113 row_ror:4 row_mask:0xf bank_mask:0xf bound_ctrl:1
	s_nop 0
	v_add_f32_dpp v112, v112, v112 row_ror:2 row_mask:0xf bank_mask:0xf bound_ctrl:1
	v_add_f32_dpp v113, v113, v113 row_ror:2 row_mask:0xf bank_mask:0xf bound_ctrl:1
	s_nop 0
	v_add_f32_dpp v114, v112, v112 row_ror:1 row_mask:0xf bank_mask:0xf bound_ctrl:1
	s_waitcnt lgkmcnt(6)
	v_mul_f32 v112, v122, v104
	v_add_f32_dpp v113, v113, v113 row_ror:1 row_mask:0xf bank_mask:0xf bound_ctrl:1
	v_fma_f32 v112, v113, v96, v112
	v_mul_f32 v104, v123, v104
	v_fma_f32 v96, v114, v96, v104
	v_fma_f32 v112, v125, v92, v112
	v_mul_f32 v104, v123, v105
	v_fma_f32 v92, v127, v92, v96
	v_mul_f32 v96, v122, v105
	v_fma_f32 v96, v113, v97, v96
	v_fma_f32 v97, v114, v97, v104
	v_mul_f32 v104, v123, v106
	v_fma_f32 v96, v141, v93, v96
	v_fma_f32 v93, v148, v93, v97
	v_mul_f32 v97, v122, v106
	v_fma_f32 v97, v113, v98, v97
	v_fma_f32 v98, v114, v98, v104
	v_mul_f32 v104, v123, v107
	v_fma_f32 v97, v149, v94, v97
	v_fma_f32 v94, v150, v94, v98
	v_mul_f32 v98, v122, v107
	v_fma_f32 v98, v113, v99, v98
	v_fma_f32 v99, v114, v99, v104
	v_mul_f32 v104, v96, v85
	v_mul_f32 v85, v93, v85
	v_fma_f32 v98, v151, v95, v98
	v_fma_f32 v95, v191, v95, v99
	v_mul_f32 v99, v112, v84
	v_mul_f32 v84, v92, v84
	v_fma_f32 v99, v97, v86, v99
	v_fma_f32 v84, v94, v86, v84
	v_fma_f32 v86, v98, v87, v104
	v_fma_f32 v85, v95, v87, v85
	v_add_f32_e32 v86, v99, v86
	v_add_f32_e32 v87, v84, v85
	s_nop 0
	v_add_f32_dpp v84, v86, v86 row_ror:8 row_mask:0xf bank_mask:0xf bound_ctrl:1
	v_add_f32_dpp v86, v87, v87 row_ror:8 row_mask:0xf bank_mask:0xf bound_ctrl:1
	s_nop 0
	v_add_f32_dpp v84, v84, v84 row_ror:4 row_mask:0xf bank_mask:0xf bound_ctrl:1
	v_add_f32_dpp v86, v86, v86 row_ror:4 row_mask:0xf bank_mask:0xf bound_ctrl:1
	s_nop 0
	v_add_f32_dpp v84, v84, v84 row_ror:2 row_mask:0xf bank_mask:0xf bound_ctrl:1
	v_add_f32_dpp v86, v86, v86 row_ror:2 row_mask:0xf bank_mask:0xf bound_ctrl:1
	s_nop 0
	v_add_f32_dpp v84, v84, v84 row_ror:1 row_mask:0xf bank_mask:0xf bound_ctrl:1
	v_add_f32_dpp v86, v86, v86 row_ror:1 row_mask:0xf bank_mask:0xf bound_ctrl:1
	ds_write2_b32 v153, v84, v86 offset0:192 offset1:208
	s_waitcnt lgkmcnt(5)
	v_mul_f32 v84, v112, v116
	v_mul_f32 v86, v96, v117
	v_mul_f32 v85, v92, v116
	v_mul_f32 v87, v93, v117
	v_fma_f32 v84, v97, v118, v84
	v_fma_f32 v86, v98, v119, v86
	v_fma_f32 v85, v94, v118, v85
	v_fma_f32 v87, v95, v119, v87
	v_add_f32_e32 v84, v84, v86
	v_add_f32_e32 v85, v85, v87
	s_nop 0
	v_add_f32_dpp v84, v84, v84 row_ror:8 row_mask:0xf bank_mask:0xf bound_ctrl:1
	s_waitcnt lgkmcnt(0)
	v_mul_f32 v86, v120, v109
	v_mul_f32 v87, v121, v109
	v_add_f32_dpp v84, v84, v84 row_ror:4 row_mask:0xf bank_mask:0xf bound_ctrl:1
	s_nop 1
	v_add_f32_dpp v84, v84, v84 row_ror:2 row_mask:0xf bank_mask:0xf bound_ctrl:1
	s_nop 1
	v_add_f32_dpp v99, v84, v84 row_ror:1 row_mask:0xf bank_mask:0xf bound_ctrl:1
	v_add_f32_dpp v84, v85, v85 row_ror:8 row_mask:0xf bank_mask:0xf bound_ctrl:1
	v_mul_f32 v85, v121, v108
	v_fma_f32 v86, v99, v101, v86
	v_fma_f32 v86, v96, v89, v86
	v_add_f32_dpp v84, v84, v84 row_ror:4 row_mask:0xf bank_mask:0xf bound_ctrl:1
	s_nop 1
	v_add_f32_dpp v84, v84, v84 row_ror:2 row_mask:0xf bank_mask:0xf bound_ctrl:1
	s_nop 1
	v_add_f32_dpp v104, v84, v84 row_ror:1 row_mask:0xf bank_mask:0xf bound_ctrl:1
	v_mul_f32 v84, v120, v108
	v_fma_f32 v85, v104, v100, v85
	v_fma_f32 v87, v104, v101, v87
	v_fma_f32 v84, v99, v100, v84
	v_fma_f32 v85, v92, v88, v85
	v_fma_f32 v87, v93, v89, v87
	v_mul_f32 v89, v86, v81
	v_fma_f32 v84, v112, v88, v84
	v_mul_f32 v88, v120, v110
	v_mul_f32 v81, v87, v81
	v_fma_f32 v88, v99, v102, v88
	v_fma_f32 v96, v97, v90, v88
	v_mul_f32 v88, v121, v110
	v_fma_f32 v88, v104, v102, v88
	v_fma_f32 v97, v94, v90, v88
	v_mul_f32 v88, v120, v111
	v_fma_f32 v88, v99, v103, v88
	v_fma_f32 v98, v98, v91, v88
	v_mul_f32 v88, v121, v111
	v_fma_f32 v88, v104, v103, v88
	v_fma_f32 v99, v95, v91, v88
	v_mul_f32 v88, v84, v80
	v_mul_f32 v80, v85, v80
	v_fma_f32 v88, v96, v82, v88
	v_fma_f32 v80, v97, v82, v80
	v_fma_f32 v82, v98, v83, v89
	v_fma_f32 v81, v99, v83, v81
	v_add_f32_e32 v82, v88, v82
	v_add_f32_e32 v83, v80, v81
	s_nop 0
	v_add_f32_dpp v80, v82, v82 row_ror:8 row_mask:0xf bank_mask:0xf bound_ctrl:1
	v_add_f32_dpp v82, v83, v83 row_ror:8 row_mask:0xf bank_mask:0xf bound_ctrl:1
	s_nop 0
	v_add_f32_dpp v80, v80, v80 row_ror:4 row_mask:0xf bank_mask:0xf bound_ctrl:1
	v_add_f32_dpp v82, v82, v82 row_ror:4 row_mask:0xf bank_mask:0xf bound_ctrl:1
	s_nop 0
	v_add_f32_dpp v80, v80, v80 row_ror:2 row_mask:0xf bank_mask:0xf bound_ctrl:1
	v_add_f32_dpp v82, v82, v82 row_ror:2 row_mask:0xf bank_mask:0xf bound_ctrl:1
	s_nop 0
	v_add_f32_dpp v80, v80, v80 row_ror:1 row_mask:0xf bank_mask:0xf bound_ctrl:1
	v_add_f32_dpp v82, v82, v82 row_ror:1 row_mask:0xf bank_mask:0xf bound_ctrl:1
	ds_write2_b32 v153, v80, v82 offset0:224 offset1:240
	s_and_saveexec_b64 s[8:9], s[38:39]
	s_cbranch_execz .LBB0_415
	v_add_f32_e32 v88, v0, v64
	v_min_f32_e32 v92, 0, v88
	v_mul_f32_e64 v88, |v88|, s62
	v_exp_f32_e32 v88, v88
	v_add_f32_e32 v89, v1, v65
	v_add_f32_e32 v90, v2, v66
	v_add_f32_e32 v91, v3, v67
	v_add_f32_e32 v88, 1.0, v88
	v_cmp_gt_f32_e32 vcc, s5, v88
	s_mov_b32 s4, 0xf800000
	v_add_f32_e32 v80, v4, v60
	v_cndmask_b32_e64 v93, 0, 32, vcc
	v_ldexp_f32 v88, v88, v93
	v_log_f32_e32 v88, v88
	v_mul_f32_e32 v80, 0xbfb8aa3b, v80
	v_exp_f32_e32 v82, v80
	v_add_f32_e32 v80, v5, v61
	v_mul_f32_e32 v93, 0x3f317217, v88
	v_fma_f32 v93, v88, s76, -v93
	v_fmac_f32_e32 v93, 0x3377d1cf, v88
	v_fmac_f32_e32 v93, 0x3f317217, v88
	v_cmp_lt_f32_e64 s[42:43], |v88|, s77
	v_mul_f32_e32 v80, 0xbfb8aa3b, v80
	v_exp_f32_e32 v83, v80
	v_cndmask_b32_e64 v88, v88, v93, s[42:43]
	v_cndmask_b32_e32 v93, 0, v171, vcc
	v_sub_f32_e32 v88, v88, v93
	v_sub_f32_e32 v88, v92, v88
	v_min_f32_e32 v92, 0, v89
	v_mul_f32_e64 v89, |v89|, s62
	v_exp_f32_e32 v89, v89
	v_add_f32_e32 v88, -0.5, v88
	v_mul_f32_e32 v88, 0x3fb8aa3b, v88
	v_exp_f32_e32 v88, v88
	v_add_f32_e32 v89, 1.0, v89
	v_cmp_gt_f32_e32 vcc, s5, v89
	v_pk_add_f32 v[82:83], v[82:83], 1.0 op_sel_hi:[1,0]
	v_mul_f32_e32 v88, 0xbfb8aa3b, v88
	v_cndmask_b32_e64 v93, 0, 32, vcc
	v_ldexp_f32 v89, v89, v93
	v_log_f32_e32 v89, v89
	v_exp_f32_e32 v88, v88
	v_add_f32_e32 v80, v6, v62
	v_add_f32_e32 v81, v7, v63
	v_mul_f32_e32 v93, 0x3f317217, v89
	v_fma_f32 v93, v89, s76, -v93
	v_fmac_f32_e32 v93, 0x3377d1cf, v89
	v_fmac_f32_e32 v93, 0x3f317217, v89
	v_cmp_lt_f32_e64 s[42:43], |v89|, s77
	v_mul_f32_e32 v80, 0xbfb8aa3b, v80
	v_mul_f32_e32 v81, 0xbfb8aa3b, v81
	v_cndmask_b32_e64 v89, v89, v93, s[42:43]
	v_cndmask_b32_e32 v93, 0, v171, vcc
	v_sub_f32_e32 v89, v89, v93
	v_sub_f32_e32 v89, v92, v89
	v_min_f32_e32 v92, 0, v90
	v_mul_f32_e64 v90, |v90|, s62
	v_exp_f32_e32 v90, v90
	v_add_f32_e32 v89, -0.5, v89
	v_mul_f32_e32 v89, 0x3fb8aa3b, v89
	v_exp_f32_e32 v89, v89
	v_add_f32_e32 v90, 1.0, v90
	v_cmp_gt_f32_e32 vcc, s5, v90
	v_exp_f32_e32 v80, v80
	v_mul_f32_e32 v89, 0xbfb8aa3b, v89
	v_cndmask_b32_e64 v93, 0, 32, vcc
	v_ldexp_f32 v90, v90, v93
	v_log_f32_e32 v90, v90
	v_exp_f32_e32 v89, v89
	v_exp_f32_e32 v81, v81
	v_mul_f32_e32 v93, 0x3f317217, v90
	v_fma_f32 v93, v90, s76, -v93
	v_fmac_f32_e32 v93, 0x3377d1cf, v90
	v_fmac_f32_e32 v93, 0x3f317217, v90
	v_cmp_lt_f32_e64 s[42:43], |v90|, s77
	v_pk_add_f32 v[80:81], v[80:81], 1.0 op_sel_hi:[1,0]
	s_nop 0
	v_cndmask_b32_e64 v90, v90, v93, s[42:43]
	v_cndmask_b32_e32 v93, 0, v171, vcc
	v_sub_f32_e32 v90, v90, v93
	v_sub_f32_e32 v90, v92, v90
	v_min_f32_e32 v92, 0, v91
	v_mul_f32_e64 v91, |v91|, s62
	v_exp_f32_e32 v91, v91
	v_add_f32_e32 v90, -0.5, v90
	v_mul_f32_e32 v90, 0x3fb8aa3b, v90
	v_exp_f32_e32 v90, v90
	v_add_f32_e32 v91, 1.0, v91
	v_cmp_gt_f32_e32 vcc, s5, v91
	v_mul_f32_e32 v90, 0xbfb8aa3b, v90
	s_nop 0
	v_cndmask_b32_e64 v93, 0, 32, vcc
	v_ldexp_f32 v91, v91, v93
	v_log_f32_e32 v91, v91
	v_exp_f32_e32 v90, v90
	v_mul_f32_e32 v93, 0x3f317217, v91
	v_fma_f32 v93, v91, s76, -v93
	v_fmac_f32_e32 v93, 0x3377d1cf, v91
	v_fmac_f32_e32 v93, 0x3f317217, v91
	v_cmp_lt_f32_e64 s[42:43], |v91|, s77
	s_nop 1
	v_cndmask_b32_e64 v91, v91, v93, s[42:43]
	v_cndmask_b32_e32 v93, 0, v171, vcc
	v_sub_f32_e32 v91, v91, v93
	v_sub_f32_e32 v91, v92, v91
	v_add_f32_e32 v91, -0.5, v91
	v_mul_f32_e32 v91, 0x3fb8aa3b, v91
	v_exp_f32_e32 v91, v91
	v_pk_mul_f32 v[92:93], v[10:11], v[58:59]
	v_mul_f32_e32 v91, 0xbfb8aa3b, v91
	v_exp_f32_e32 v91, v91
	v_pk_mul_f32 v[94:95], v[92:93], v[92:93]
	ds_write_b128 v181, v[88:91]
	v_pk_mul_f32 v[88:89], v[8:9], v[56:57]
	v_pk_mul_f32 v[90:91], v[88:89], v[88:89]
	v_add_f32_e32 v90, v91, v90
	v_add_f32_e32 v90, v94, v90
	v_add_f32_e32 v90, v95, v90
	s_nop 1
	v_add_f32_dpp v90, v90, v90 row_ror:8 row_mask:0xf bank_mask:0xf bound_ctrl:1
	s_nop 1
	v_add_f32_dpp v90, v90, v90 row_ror:4 row_mask:0xf bank_mask:0xf bound_ctrl:1
	s_nop 1
	v_add_f32_dpp v90, v90, v90 row_ror:2 row_mask:0xf bank_mask:0xf bound_ctrl:1
	s_nop 1
	v_add_f32_dpp v90, v90, v90 row_ror:1 row_mask:0xf bank_mask:0xf bound_ctrl:1
	v_cmp_gt_f32_e32 vcc, s4, v90
	v_mul_f32_e32 v91, 0x4f800000, v90
	s_nop 0
	v_cndmask_b32_e32 v90, v90, v91, vcc
	v_sqrt_f32_e32 v91, v90
	s_nop 0
	v_add_u32_e32 v94, -1, v91
	v_fma_f32 v95, -v94, v91, v90
	v_cmp_ge_f32_e64 s[42:43], 0, v95
	v_add_u32_e32 v95, 1, v91
	s_nop 0
	v_cndmask_b32_e64 v94, v91, v94, s[42:43]
	v_fma_f32 v91, -v95, v91, v90
	v_cmp_lt_f32_e64 s[42:43], 0, v91
	s_nop 1
	v_cndmask_b32_e64 v91, v94, v95, s[42:43]
	v_mul_f32_e32 v94, 0x37800000, v91
	v_cndmask_b32_e32 v91, v91, v94, vcc
	v_cmp_class_f32_e32 vcc, v90, v160
	s_nop 1
	v_cndmask_b32_e32 v90, v91, v90, vcc
	v_max_f32_e32 v90, 0x2b8cbccc, v90
	v_div_scale_f32 v91, s[22:23], v90, v90, 1.0
	v_rcp_f32_e32 v94, v91
	s_nop 0
	v_fma_f32 v95, -v91, v94, 1.0
	v_fmac_f32_e32 v94, v95, v94
	v_div_scale_f32 v95, vcc, 1.0, v90, 1.0
	v_mul_f32_e32 v100, v95, v94
	v_fma_f32 v101, -v91, v100, v95
	v_fmac_f32_e32 v100, v101, v94
	v_fma_f32 v91, -v91, v100, v95
	v_div_fmas_f32 v91, v91, v94, v100
	v_div_fixup_f32 v90, v91, v90, 1.0
	v_pk_mul_f32 v[94:95], v[88:89], v[90:91] op_sel_hi:[1,0]
	v_pk_mul_f32 v[92:93], v[92:93], v[90:91] op_sel_hi:[1,0]
	v_xor_b32_e32 v89, 0x80000000, v95
	v_xor_b32_e32 v88, 0x80000000, v94
	v_xor_b32_e32 v91, 0x80000000, v93
	v_xor_b32_e32 v90, 0x80000000, v92
	ds_write_b128 v181, v[88:91] offset:4096
	v_div_scale_f32 v88, s[22:23], v83, v83, 1.0
	v_rcp_f32_e32 v89, v88
	s_nop 0
	v_fma_f32 v90, -v88, v89, 1.0
	v_fmac_f32_e32 v89, v90, v89
	v_div_scale_f32 v90, vcc, 1.0, v83, 1.0
	v_mul_f32_e32 v91, v90, v89
	v_fma_f32 v100, -v88, v91, v90
	v_fmac_f32_e32 v91, v100, v89
	v_fma_f32 v88, -v88, v91, v90
	v_div_fmas_f32 v88, v88, v89, v91
	v_div_fixup_f32 v83, v88, v83, 1.0
	v_div_scale_f32 v88, s[22:23], v82, v82, 1.0
	v_rcp_f32_e32 v89, v88
	s_nop 0
	v_fma_f32 v90, -v88, v89, 1.0
	v_fmac_f32_e32 v89, v90, v89
	v_div_scale_f32 v90, vcc, 1.0, v82, 1.0
	v_mul_f32_e32 v91, v90, v89
	v_fma_f32 v100, -v88, v91, v90
	v_fmac_f32_e32 v91, v100, v89
	v_fma_f32 v88, -v88, v91, v90
	v_div_scale_f32 v90, s[22:23], v81, v81, 1.0
	v_div_fmas_f32 v88, v88, v89, v91
	v_rcp_f32_e32 v91, v90
	v_div_fixup_f32 v82, v88, v82, 1.0
	v_pk_mul_f32 v[88:89], v[82:83], v[94:95]
	v_fma_f32 v94, -v90, v91, 1.0
	v_fmac_f32_e32 v91, v94, v91
	v_div_scale_f32 v94, vcc, 1.0, v81, 1.0
	v_mul_f32_e32 v95, v94, v91
	v_fma_f32 v100, -v90, v95, v94
	v_fmac_f32_e32 v95, v100, v91
	v_fma_f32 v90, -v90, v95, v94
	v_div_fmas_f32 v90, v90, v91, v95
	v_div_fixup_f32 v95, v90, v81, 1.0
	v_div_scale_f32 v81, s[22:23], v80, v80, 1.0
	v_rcp_f32_e32 v90, v81
	s_nop 0
	v_fma_f32 v91, -v81, v90, 1.0
	v_fmac_f32_e32 v90, v91, v90
	v_div_scale_f32 v91, vcc, 1.0, v80, 1.0
	v_mul_f32_e32 v94, v91, v90
	v_fma_f32 v100, -v81, v94, v91
	v_fmac_f32_e32 v94, v100, v90
	v_fma_f32 v81, -v81, v94, v91
	v_div_fmas_f32 v81, v81, v90, v94
	v_div_fixup_f32 v94, v81, v80, 1.0
	v_pk_add_f32 v[80:81], v[82:83], -1.0 op_sel_hi:[1,0]
	v_pk_add_f32 v[82:83], v[94:95], -1.0 op_sel_hi:[1,0]
	v_pk_fma_f32 v[80:81], v[12:13], v[80:81], 1.0 op_sel_hi:[1,1,0]
	v_pk_fma_f32 v[82:83], v[14:15], v[82:83], 1.0 op_sel_hi:[1,1,0]
	v_pk_mul_f32 v[90:91], v[94:95], v[92:93]
	v_pk_mul_f32 v[80:81], v[56:57], v[80:81]
	v_pk_mul_f32 v[82:83], v[58:59], v[82:83]
	ds_write_b128 v181, v[88:91] offset:8192
	ds_write_b128 v181, v[80:83] offset:12288
	ds_write_b128 v181, v[52:55] offset:16384

.LBB0_419:
	ds_read2st64_b32 v[80:81], v179 offset0:184 offset1:188
	v_add_u32_e32 v82, 16, v126
	v_ashrrev_i32_e32 v83, 31, v82
	v_lshlrev_b64 v[82:83], 13, v[82:83]
	v_lshl_add_u64 v[82:83], v[144:145], 0, v[82:83]
	s_waitcnt lgkmcnt(0)
	global_store_dword v[82:83], v80, off
	v_add_u32_e32 v82, 16, v124
	v_ashrrev_i32_e32 v83, 31, v82
	v_lshlrev_b64 v[82:83], 13, v[82:83]
	v_lshl_add_u64 v[82:83], v[144:145], 0, v[82:83]
	global_store_dword v[82:83], v81, off
	ds_read_b128 v[104:107], v134
	ds_read_b128 v[88:91], v134 offset:256
	ds_read_b128 v[108:111], v134 offset:4096
	ds_read_b128 v[112:115], v134 offset:4352
	ds_read_b128 v[116:119], v134 offset:8192
	ds_read_b128 v[92:95], v134 offset:8448
	ds_read_b128 v[192:195], v134 offset:12288
	ds_read_b128 v[100:103], v134 offset:12544
	ds_read_b128 v[196:199], v134 offset:16384
	ds_read_b128 v[80:83], v134 offset:16640
	ds_read2_b32 v[120:121], v189 offset0:32 offset1:48
	s_waitcnt lgkmcnt(8)
	v_mul_f32 v122, v84, v108
	v_mul_f32 v108, v85, v108
	v_mul_f32 v123, v86, v109
	v_mul_f32 v109, v87, v109
	v_fma_f32 v122, v96, v110, v122
	v_fma_f32 v108, v97, v110, v108
	v_fma_f32 v110, v98, v111, v123
	v_fma_f32 v109, v99, v111, v109
	v_add_f32_e32 v110, v122, v110
	v_add_f32_e32 v111, v108, v109
	s_nop 0
	v_add_f32_dpp v110, v110, v110 row_ror:8 row_mask:0xf bank_mask:0xf bound_ctrl:1
	ds_read2_b32 v[108:109], v189 offset1:16
	v_add_f32_dpp v111, v111, v111 row_ror:8 row_mask:0xf bank_mask:0xf bound_ctrl:1
	v_add_f32_dpp v110, v110, v110 row_ror:4 row_mask:0xf bank_mask:0xf bound_ctrl:1
	s_waitcnt lgkmcnt(0)
	v_mul_f32 v122, v108, v192
	v_add_f32_dpp v111, v111, v111 row_ror:4 row_mask:0xf bank_mask:0xf bound_ctrl:1
	v_add_f32_dpp v110, v110, v110 row_ror:2 row_mask:0xf bank_mask:0xf bound_ctrl:1
	s_nop 0
	v_add_f32_dpp v111, v111, v111 row_ror:2 row_mask:0xf bank_mask:0xf bound_ctrl:1
	v_add_f32_dpp v110, v110, v110 row_ror:1 row_mask:0xf bank_mask:0xf bound_ctrl:1
	v_fma_f32 v122, v110, v116, v122
	v_fma_f32 v122, v84, v104, v122
	v_mul_f32 v84, v109, v192
	v_add_f32_dpp v111, v111, v111 row_ror:1 row_mask:0xf bank_mask:0xf bound_ctrl:1
	v_fma_f32 v84, v111, v116, v84
	v_fma_f32 v123, v85, v104, v84
	v_mul_f32 v84, v108, v193
	v_fma_f32 v84, v110, v117, v84
	v_mul_f32 v85, v123, v196
	v_fma_f32 v125, v86, v105, v84
	v_mul_f32 v84, v109, v193
	v_fma_f32 v84, v111, v117, v84
	v_mul_f32 v86, v125, v197
	v_fma_f32 v127, v87, v105, v84
	v_mul_f32 v84, v108, v194
	v_fma_f32 v84, v110, v118, v84
	v_mul_f32 v87, v127, v197
	v_fma_f32 v141, v96, v106, v84
	v_mul_f32 v84, v109, v194
	v_fma_f32 v84, v111, v118, v84
	v_fma_f32 v150, v97, v106, v84
	v_mul_f32 v84, v108, v195
	v_fma_f32 v84, v110, v119, v84
	v_fma_f32 v85, v150, v198, v85
	v_fma_f32 v151, v98, v107, v84
	v_mul_f32 v84, v109, v195
	v_fma_f32 v84, v111, v119, v84
	v_fma_f32 v86, v151, v199, v86
	v_fma_f32 v191, v99, v107, v84
	v_mul_f32 v84, v122, v196
	v_fma_f32 v84, v141, v198, v84
	v_fma_f32 v87, v191, v199, v87
	v_add_f32_e32 v84, v84, v86
	v_add_f32_e32 v86, v85, v87
	s_nop 0
	v_add_f32_dpp v84, v84, v84 row_ror:8 row_mask:0xf bank_mask:0xf bound_ctrl:1
	v_add_f32_dpp v86, v86, v86 row_ror:8 row_mask:0xf bank_mask:0xf bound_ctrl:1
	s_nop 0
	v_add_f32_dpp v84, v84, v84 row_ror:4 row_mask:0xf bank_mask:0xf bound_ctrl:1
	v_add_f32_dpp v86, v86, v86 row_ror:4 row_mask:0xf bank_mask:0xf bound_ctrl:1
	s_nop 0
	v_add_f32_dpp v84, v84, v84 row_ror:2 row_mask:0xf bank_mask:0xf bound_ctrl:1
	v_add_f32_dpp v86, v86, v86 row_ror:2 row_mask:0xf bank_mask:0xf bound_ctrl:1
	s_nop 0
	v_add_f32_dpp v84, v84, v84 row_ror:1 row_mask:0xf bank_mask:0xf bound_ctrl:1
	v_add_f32_dpp v86, v86, v86 row_ror:1 row_mask:0xf bank_mask:0xf bound_ctrl:1
	ds_write2_b32 v185, v84, v86 offset1:16
	v_mul_f32 v192, v122, v112
	v_mul_f32 v112, v123, v112
	v_mul_f32 v193, v125, v113
	v_mul_f32 v113, v127, v113
	ds_read_b128 v[96:99], v134 offset:512
	ds_read_b128 v[116:119], v134 offset:4608
	ds_read_b128 v[104:107], v134 offset:8704
	ds_read_b128 v[108:111], v134 offset:12800
	ds_read_b128 v[84:87], v134 offset:16896
	ds_read2_b32 v[148:149], v189 offset0:64 offset1:80
	v_fma_f32 v192, v141, v114, v192
	v_fma_f32 v112, v150, v114, v112
	v_fma_f32 v114, v151, v115, v193
	v_fma_f32 v113, v191, v115, v113
	v_add_f32_e32 v114, v192, v114
	v_add_f32_e32 v112, v112, v113
	s_nop 0
	v_add_f32_dpp v113, v114, v114 row_ror:8 row_mask:0xf bank_mask:0xf bound_ctrl:1
	v_add_f32_dpp v112, v112, v112 row_ror:8 row_mask:0xf bank_mask:0xf bound_ctrl:1
	v_mul_f32 v114, v120, v100
	v_mul_f32 v100, v121, v100
	v_add_f32_dpp v113, v113, v113 row_ror:4 row_mask:0xf bank_mask:0xf bound_ctrl:1
	v_add_f32_dpp v112, v112, v112 row_ror:4 row_mask:0xf bank_mask:0xf bound_ctrl:1
	s_nop 0
	v_add_f32_dpp v113, v113, v113 row_ror:2 row_mask:0xf bank_mask:0xf bound_ctrl:1
	v_add_f32_dpp v112, v112, v112 row_ror:2 row_mask:0xf bank_mask:0xf bound_ctrl:1
	s_nop 0
	v_add_f32_dpp v113, v113, v113 row_ror:1 row_mask:0xf bank_mask:0xf bound_ctrl:1
	v_add_f32_dpp v112, v112, v112 row_ror:1 row_mask:0xf bank_mask:0xf bound_ctrl:1
	v_fma_f32 v114, v113, v92, v114
	v_fma_f32 v92, v112, v92, v100
	v_fma_f32 v192, v122, v88, v114
	v_fma_f32 v92, v123, v88, v92
	v_mul_f32 v88, v120, v101
	v_fma_f32 v88, v113, v93, v88
	v_fma_f32 v125, v125, v89, v88
	v_mul_f32 v88, v121, v101
	v_fma_f32 v88, v112, v93, v88
	v_fma_f32 v93, v127, v89, v88
	v_mul_f32 v88, v120, v102
	v_mul_f32 v89, v125, v81
	v_fma_f32 v88, v113, v94, v88
	v_mul_f32 v81, v93, v81
	v_fma_f32 v127, v141, v90, v88
	v_mul_f32 v88, v121, v102
	v_fma_f32 v88, v112, v94, v88
	v_fma_f32 v94, v150, v90, v88
	v_mul_f32 v88, v120, v103
	v_fma_f32 v88, v113, v95, v88
	v_fma_f32 v141, v151, v91, v88
	v_mul_f32 v88, v121, v103
	v_fma_f32 v88, v112, v95, v88
	v_fma_f32 v95, v191, v91, v88
	v_mul_f32 v88, v192, v80
	v_mul_f32 v80, v92, v80
	v_fma_f32 v88, v127, v82, v88
	v_fma_f32 v80, v94, v82, v80
	v_fma_f32 v82, v141, v83, v89
	v_fma_f32 v81, v95, v83, v81
	v_add_f32_e32 v82, v88, v82
	v_add_f32_e32 v83, v80, v81
	s_nop 0
	v_add_f32_dpp v80, v82, v82 row_ror:8 row_mask:0xf bank_mask:0xf bound_ctrl:1
	v_add_f32_dpp v82, v83, v83 row_ror:8 row_mask:0xf bank_mask:0xf bound_ctrl:1
	s_nop 0
	v_add_f32_dpp v80, v80, v80 row_ror:4 row_mask:0xf bank_mask:0xf bound_ctrl:1
	v_add_f32_dpp v82, v82, v82 row_ror:4 row_mask:0xf bank_mask:0xf bound_ctrl:1
	s_nop 0
	v_add_f32_dpp v80, v80, v80 row_ror:2 row_mask:0xf bank_mask:0xf bound_ctrl:1
	v_add_f32_dpp v82, v82, v82 row_ror:2 row_mask:0xf bank_mask:0xf bound_ctrl:1
	s_nop 0
	v_add_f32_dpp v80, v80, v80 row_ror:1 row_mask:0xf bank_mask:0xf bound_ctrl:1
	v_add_f32_dpp v82, v82, v82 row_ror:1 row_mask:0xf bank_mask:0xf bound_ctrl:1
	ds_write2_b32 v185, v80, v82 offset0:32 offset1:48
	s_waitcnt lgkmcnt(4)
	v_mul_f32 v191, v192, v116
	v_mul_f32 v116, v92, v116
	v_mul_f32 v193, v125, v117
	v_mul_f32 v117, v93, v117
	ds_read_b128 v[88:91], v134 offset:768
	ds_read_b128 v[120:123], v134 offset:4864
	ds_read_b128 v[100:103], v134 offset:8960
	ds_read_b128 v[112:115], v134 offset:13056
	ds_read_b128 v[80:83], v134 offset:17152
	ds_read2_b32 v[150:151], v189 offset0:96 offset1:112
	v_fma_f32 v191, v127, v118, v191
	v_fma_f32 v116, v94, v118, v116
	v_fma_f32 v118, v141, v119, v193
	v_fma_f32 v117, v95, v119, v117
	v_add_f32_e32 v118, v191, v118
	v_add_f32_e32 v116, v116, v117
	s_nop 0
	v_add_f32_dpp v117, v118, v118 row_ror:8 row_mask:0xf bank_mask:0xf bound_ctrl:1
	v_add_f32_dpp v116, v116, v116 row_ror:8 row_mask:0xf bank_mask:0xf bound_ctrl:1
	s_waitcnt lgkmcnt(6)
	v_mul_f32 v118, v148, v108
	v_mul_f32 v108, v149, v108
	v_add_f32_dpp v117, v117, v117 row_ror:4 row_mask:0xf bank_mask:0xf bound_ctrl:1
	v_add_f32_dpp v116, v116, v116 row_ror:4 row_mask:0xf bank_mask:0xf bound_ctrl:1
	s_nop 0
	v_add_f32_dpp v117, v117, v117 row_ror:2 row_mask:0xf bank_mask:0xf bound_ctrl:1
	v_add_f32_dpp v116, v116, v116 row_ror:2 row_mask:0xf bank_mask:0xf bound_ctrl:1
	s_nop 0
	v_add_f32_dpp v117, v117, v117 row_ror:1 row_mask:0xf bank_mask:0xf bound_ctrl:1
	v_add_f32_dpp v116, v116, v116 row_ror:1 row_mask:0xf bank_mask:0xf bound_ctrl:1
	v_fma_f32 v118, v117, v104, v118
	v_fma_f32 v104, v116, v104, v108
	v_fma_f32 v108, v92, v96, v104
	v_mul_f32 v92, v148, v109
	v_fma_f32 v191, v192, v96, v118
	v_fma_f32 v92, v117, v105, v92
	v_fma_f32 v125, v125, v97, v92
	v_mul_f32 v92, v149, v109
	v_fma_f32 v92, v116, v105, v92
	v_fma_f32 v109, v93, v97, v92
	v_mul_f32 v92, v148, v110
	v_mul_f32 v93, v125, v85
	v_fma_f32 v92, v117, v106, v92
	v_mul_f32 v85, v109, v85
	v_fma_f32 v127, v127, v98, v92
	v_mul_f32 v92, v149, v110
	v_fma_f32 v92, v116, v106, v92
	v_fma_f32 v110, v94, v98, v92
	v_mul_f32 v92, v148, v111
	v_fma_f32 v92, v117, v107, v92
	v_fma_f32 v141, v141, v99, v92
	v_mul_f32 v92, v149, v111
	v_fma_f32 v92, v116, v107, v92
	v_fma_f32 v111, v95, v99, v92
	v_mul_f32 v92, v191, v84
	v_mul_f32 v84, v108, v84
	v_fma_f32 v92, v127, v86, v92
	v_fma_f32 v84, v110, v86, v84
	v_fma_f32 v86, v141, v87, v93
	v_fma_f32 v85, v111, v87, v85
	v_add_f32_e32 v86, v92, v86
	v_add_f32_e32 v87, v84, v85
	s_nop 0
	v_add_f32_dpp v84, v86, v86 row_ror:8 row_mask:0xf bank_mask:0xf bound_ctrl:1
	v_add_f32_dpp v86, v87, v87 row_ror:8 row_mask:0xf bank_mask:0xf bound_ctrl:1
	s_nop 0
	v_add_f32_dpp v84, v84, v84 row_ror:4 row_mask:0xf bank_mask:0xf bound_ctrl:1
	v_add_f32_dpp v86, v86, v86 row_ror:4 row_mask:0xf bank_mask:0xf bound_ctrl:1
	s_nop 0
	v_add_f32_dpp v84, v84, v84 row_ror:2 row_mask:0xf bank_mask:0xf bound_ctrl:1
	v_add_f32_dpp v86, v86, v86 row_ror:2 row_mask:0xf bank_mask:0xf bound_ctrl:1
	s_nop 0
	v_add_f32_dpp v84, v84, v84 row_ror:1 row_mask:0xf bank_mask:0xf bound_ctrl:1
	v_add_f32_dpp v86, v86, v86 row_ror:1 row_mask:0xf bank_mask:0xf bound_ctrl:1
	ds_write2_b32 v185, v84, v86 offset0:64 offset1:80
	s_waitcnt lgkmcnt(4)
	v_mul_f32 v192, v191, v120
	v_mul_f32 v120, v108, v120
	v_mul_f32 v193, v125, v121
	v_mul_f32 v121, v109, v121
	ds_read_b128 v[92:95], v134 offset:1024
	ds_read_b128 v[116:119], v134 offset:5120
	ds_read_b128 v[96:99], v134 offset:9216
	ds_read_b128 v[104:107], v134 offset:13312
	ds_read_b128 v[84:87], v134 offset:17408
	ds_read2_b32 v[148:149], v189 offset0:128 offset1:144
	v_fma_f32 v192, v127, v122, v192
	v_fma_f32 v120, v110, v122, v120
	v_fma_f32 v122, v141, v123, v193
	v_fma_f32 v121, v111, v123, v121
	v_add_f32_e32 v122, v192, v122
	v_add_f32_e32 v120, v120, v121
	s_nop 0
	v_add_f32_dpp v121, v122, v122 row_ror:8 row_mask:0xf bank_mask:0xf bound_ctrl:1
	v_add_f32_dpp v120, v120, v120 row_ror:8 row_mask:0xf bank_mask:0xf bound_ctrl:1
	s_waitcnt lgkmcnt(6)
	v_mul_f32 v122, v150, v112
	v_mul_f32 v112, v151, v112
	v_add_f32_dpp v121, v121, v121 row_ror:4 row_mask:0xf bank_mask:0xf bound_ctrl:1
	v_add_f32_dpp v120, v120, v120 row_ror:4 row_mask:0xf bank_mask:0xf bound_ctrl:1
	s_nop 0
	v_add_f32_dpp v121, v121, v121 row_ror:2 row_mask:0xf bank_mask:0xf bound_ctrl:1
	v_add_f32_dpp v120, v120, v120 row_ror:2 row_mask:0xf bank_mask:0xf bound_ctrl:1
	s_nop 0
	v_add_f32_dpp v121, v121, v121 row_ror:1 row_mask:0xf bank_mask:0xf bound_ctrl:1
	v_fma_f32 v122, v121, v100, v122
	v_add_f32_dpp v120, v120, v120 row_ror:1 row_mask:0xf bank_mask:0xf bound_ctrl:1
	v_fma_f32 v122, v191, v88, v122
	v_fma_f32 v100, v120, v100, v112
	v_fma_f32 v123, v108, v88, v100
	v_mul_f32 v88, v150, v113
	v_fma_f32 v88, v121, v101, v88
	v_fma_f32 v125, v125, v89, v88
	v_mul_f32 v88, v151, v113
	v_fma_f32 v88, v120, v101, v88
	v_fma_f32 v191, v109, v89, v88
	v_mul_f32 v88, v150, v114
	v_mul_f32 v89, v125, v81
	v_fma_f32 v88, v121, v102, v88
	v_mul_f32 v81, v191, v81
	v_fma_f32 v127, v127, v90, v88
	v_mul_f32 v88, v151, v114
	v_fma_f32 v88, v120, v102, v88
	v_fma_f32 v192, v110, v90, v88
	v_mul_f32 v88, v150, v115
	v_fma_f32 v88, v121, v103, v88
	v_fma_f32 v141, v141, v91, v88
	v_mul_f32 v88, v151, v115
	v_fma_f32 v88, v120, v103, v88
	v_fma_f32 v150, v111, v91, v88
	v_mul_f32 v88, v122, v80
	v_mul_f32 v80, v123, v80
	v_fma_f32 v88, v127, v82, v88
	v_fma_f32 v80, v192, v82, v80
	v_fma_f32 v82, v141, v83, v89
	v_fma_f32 v81, v150, v83, v81
	v_add_f32_e32 v82, v88, v82
	v_add_f32_e32 v83, v80, v81
	s_nop 0
	v_add_f32_dpp v80, v82, v82 row_ror:8 row_mask:0xf bank_mask:0xf bound_ctrl:1
	v_add_f32_dpp v82, v83, v83 row_ror:8 row_mask:0xf bank_mask:0xf bound_ctrl:1
	s_nop 0
	v_add_f32_dpp v80, v80, v80 row_ror:4 row_mask:0xf bank_mask:0xf bound_ctrl:1
	v_add_f32_dpp v82, v82, v82 row_ror:4 row_mask:0xf bank_mask:0xf bound_ctrl:1
	s_nop 0
	v_add_f32_dpp v80, v80, v80 row_ror:2 row_mask:0xf bank_mask:0xf bound_ctrl:1
	v_add_f32_dpp v82, v82, v82 row_ror:2 row_mask:0xf bank_mask:0xf bound_ctrl:1
	s_nop 0
	v_add_f32_dpp v80, v80, v80 row_ror:1 row_mask:0xf bank_mask:0xf bound_ctrl:1
	v_add_f32_dpp v82, v82, v82 row_ror:1 row_mask:0xf bank_mask:0xf bound_ctrl:1
	ds_write2_b32 v185, v80, v82 offset0:96 offset1:112
	s_waitcnt lgkmcnt(4)
	v_mul_f32 v151, v122, v116
	v_mul_f32 v116, v123, v116
	v_mul_f32 v193, v125, v117
	v_mul_f32 v117, v191, v117
	ds_read_b128 v[88:91], v134 offset:1280
	ds_read_b128 v[112:115], v134 offset:5376
	ds_read_b128 v[100:103], v134 offset:9472
	ds_read_b128 v[108:111], v134 offset:13568
	ds_read_b128 v[80:83], v134 offset:17664
	ds_read2_b32 v[120:121], v189 offset0:160 offset1:176
	v_fma_f32 v151, v127, v118, v151
	v_fma_f32 v116, v192, v118, v116
	v_fma_f32 v118, v141, v119, v193
	v_fma_f32 v117, v150, v119, v117
	v_add_f32_e32 v118, v151, v118
	v_add_f32_e32 v116, v116, v117
	s_nop 0
	v_add_f32_dpp v117, v118, v118 row_ror:8 row_mask:0xf bank_mask:0xf bound_ctrl:1
	v_add_f32_dpp v116, v116, v116 row_ror:8 row_mask:0xf bank_mask:0xf bound_ctrl:1
	s_waitcnt lgkmcnt(6)
	v_mul_f32 v118, v148, v104
	v_mul_f32 v104, v149, v104
	v_add_f32_dpp v117, v117, v117 row_ror:4 row_mask:0xf bank_mask:0xf bound_ctrl:1
	v_add_f32_dpp v116, v116, v116 row_ror:4 row_mask:0xf bank_mask:0xf bound_ctrl:1
	s_nop 0
	v_add_f32_dpp v117, v117, v117 row_ror:2 row_mask:0xf bank_mask:0xf bound_ctrl:1
	v_add_f32_dpp v116, v116, v116 row_ror:2 row_mask:0xf bank_mask:0xf bound_ctrl:1
	s_nop 0
	v_add_f32_dpp v117, v117, v117 row_ror:1 row_mask:0xf bank_mask:0xf bound_ctrl:1
	v_add_f32_dpp v116, v116, v116 row_ror:1 row_mask:0xf bank_mask:0xf bound_ctrl:1
	v_fma_f32 v118, v117, v96, v118
	v_fma_f32 v96, v116, v96, v104
	v_fma_f32 v151, v122, v92, v118
	v_fma_f32 v193, v123, v92, v96
	v_mul_f32 v92, v148, v105
	v_fma_f32 v92, v117, v97, v92
	v_fma_f32 v125, v125, v93, v92
	v_mul_f32 v92, v149, v105
	v_fma_f32 v92, v116, v97, v92
	v_fma_f32 v191, v191, v93, v92
	v_mul_f32 v92, v148, v106
	v_mul_f32 v93, v125, v85
	v_fma_f32 v92, v117, v98, v92
	v_mul_f32 v85, v191, v85
	v_fma_f32 v127, v127, v94, v92
	v_mul_f32 v92, v149, v106
	v_fma_f32 v92, v116, v98, v92
	v_fma_f32 v192, v192, v94, v92
	v_mul_f32 v92, v148, v107
	v_fma_f32 v92, v117, v99, v92
	v_fma_f32 v141, v141, v95, v92
	v_mul_f32 v92, v149, v107
	v_fma_f32 v92, v116, v99, v92
	v_fma_f32 v148, v150, v95, v92
	v_mul_f32 v92, v151, v84
	v_mul_f32 v84, v193, v84
	v_fma_f32 v92, v127, v86, v92
	v_fma_f32 v84, v192, v86, v84
	v_fma_f32 v86, v141, v87, v93
	v_fma_f32 v85, v148, v87, v85
	v_add_f32_e32 v86, v92, v86
	v_add_f32_e32 v87, v84, v85
	s_nop 0
	v_add_f32_dpp v84, v86, v86 row_ror:8 row_mask:0xf bank_mask:0xf bound_ctrl:1
	v_add_f32_dpp v86, v87, v87 row_ror:8 row_mask:0xf bank_mask:0xf bound_ctrl:1
	s_nop 0
	v_add_f32_dpp v84, v84, v84 row_ror:4 row_mask:0xf bank_mask:0xf bound_ctrl:1
	v_add_f32_dpp v86, v86, v86 row_ror:4 row_mask:0xf bank_mask:0xf bound_ctrl:1
	s_nop 0
	v_add_f32_dpp v84, v84, v84 row_ror:2 row_mask:0xf bank_mask:0xf bound_ctrl:1
	v_add_f32_dpp v86, v86, v86 row_ror:2 row_mask:0xf bank_mask:0xf bound_ctrl:1
	s_nop 0
	v_add_f32_dpp v84, v84, v84 row_ror:1 row_mask:0xf bank_mask:0xf bound_ctrl:1
	v_add_f32_dpp v86, v86, v86 row_ror:1 row_mask:0xf bank_mask:0xf bound_ctrl:1
	ds_write2_b32 v185, v84, v86 offset0:128 offset1:144
	s_waitcnt lgkmcnt(4)
	v_mul_f32 v149, v151, v112
	v_mul_f32 v112, v193, v112
	v_mul_f32 v150, v125, v113
	v_mul_f32 v113, v191, v113
	ds_read_b128 v[92:95], v134 offset:1536
	ds_read_b128 v[116:119], v134 offset:5632
	ds_read_b128 v[96:99], v134 offset:9728
	ds_read_b128 v[104:107], v134 offset:13824
	ds_read_b128 v[84:87], v134 offset:17920
	ds_read2_b32 v[122:123], v189 offset0:192 offset1:208
	v_fma_f32 v149, v127, v114, v149
	v_fma_f32 v112, v192, v114, v112
	v_fma_f32 v114, v141, v115, v150
	v_fma_f32 v113, v148, v115, v113
	v_add_f32_e32 v114, v149, v114
	v_add_f32_e32 v112, v112, v113
	s_nop 0
	v_add_f32_dpp v113, v114, v114 row_ror:8 row_mask:0xf bank_mask:0xf bound_ctrl:1
	v_add_f32_dpp v112, v112, v112 row_ror:8 row_mask:0xf bank_mask:0xf bound_ctrl:1
	s_waitcnt lgkmcnt(6)
	v_mul_f32 v114, v120, v108
	v_mul_f32 v108, v121, v108
	v_add_f32_dpp v113, v113, v113 row_ror:4 row_mask:0xf bank_mask:0xf bound_ctrl:1
	v_add_f32_dpp v112, v112, v112 row_ror:4 row_mask:0xf bank_mask:0xf bound_ctrl:1
	s_nop 0
	v_add_f32_dpp v113, v113, v113 row_ror:2 row_mask:0xf bank_mask:0xf bound_ctrl:1
	v_add_f32_dpp v112, v112, v112 row_ror:2 row_mask:0xf bank_mask:0xf bound_ctrl:1
	s_nop 0
	v_add_f32_dpp v113, v113, v113 row_ror:1 row_mask:0xf bank_mask:0xf bound_ctrl:1
	v_add_f32_dpp v112, v112, v112 row_ror:1 row_mask:0xf bank_mask:0xf bound_ctrl:1
	v_fma_f32 v114, v113, v100, v114
	v_fma_f32 v100, v112, v100, v108
	v_fma_f32 v149, v151, v88, v114
	v_fma_f32 v150, v193, v88, v100
	v_mul_f32 v88, v120, v109
	v_fma_f32 v88, v113, v101, v88
	v_fma_f32 v125, v125, v89, v88
	v_mul_f32 v88, v121, v109
	v_fma_f32 v88, v112, v101, v88
	v_fma_f32 v151, v191, v89, v88
	v_mul_f32 v88, v120, v110
	v_mul_f32 v89, v125, v81
	v_fma_f32 v88, v113, v102, v88
	v_mul_f32 v81, v151, v81
	v_fma_f32 v127, v127, v90, v88
	v_mul_f32 v88, v121, v110
	v_fma_f32 v88, v112, v102, v88
	v_fma_f32 v191, v192, v90, v88
	v_mul_f32 v88, v120, v111
	v_fma_f32 v88, v113, v103, v88
	v_fma_f32 v141, v141, v91, v88
	v_mul_f32 v88, v121, v111
	v_fma_f32 v88, v112, v103, v88
	v_fma_f32 v148, v148, v91, v88
	v_mul_f32 v88, v149, v80
	v_mul_f32 v80, v150, v80
	v_fma_f32 v88, v127, v82, v88
	v_fma_f32 v80, v191, v82, v80
	v_fma_f32 v82, v141, v83, v89
	v_fma_f32 v81, v148, v83, v81
	v_add_f32_e32 v82, v88, v82
	v_add_f32_e32 v83, v80, v81
	s_nop 0
	v_add_f32_dpp v80, v82, v82 row_ror:8 row_mask:0xf bank_mask:0xf bound_ctrl:1
	v_add_f32_dpp v82, v83, v83 row_ror:8 row_mask:0xf bank_mask:0xf bound_ctrl:1
	s_nop 0
	v_add_f32_dpp v80, v80, v80 row_ror:4 row_mask:0xf bank_mask:0xf bound_ctrl:1
	v_add_f32_dpp v82, v82, v82 row_ror:4 row_mask:0xf bank_mask:0xf bound_ctrl:1
	s_nop 0
	v_add_f32_dpp v80, v80, v80 row_ror:2 row_mask:0xf bank_mask:0xf bound_ctrl:1
	v_add_f32_dpp v82, v82, v82 row_ror:2 row_mask:0xf bank_mask:0xf bound_ctrl:1
	s_nop 0
	v_add_f32_dpp v80, v80, v80 row_ror:1 row_mask:0xf bank_mask:0xf bound_ctrl:1
	v_add_f32_dpp v82, v82, v82 row_ror:1 row_mask:0xf bank_mask:0xf bound_ctrl:1
	ds_write2_b32 v185, v80, v82 offset0:160 offset1:176
	ds_read_b128 v[88:91], v134 offset:1792
	ds_read_b128 v[112:115], v134 offset:5888
	ds_read_b128 v[100:103], v134 offset:9984
	ds_read_b128 v[108:111], v134 offset:14080
	ds_read_b128 v[80:83], v134 offset:18176
	ds_read2_b32 v[120:121], v189 offset0:224 offset1:240
	s_waitcnt lgkmcnt(10)
	v_mul_f32 v189, v149, v116
	v_mul_f32 v116, v150, v116
	v_mul_f32 v192, v125, v117
	v_mul_f32 v117, v151, v117
	v_fma_f32 v189, v127, v118, v189
	v_fma_f32 v116, v191, v118, v116
	v_fma_f32 v118, v141, v119, v192
	v_fma_f32 v117, v148, v119, v117
	v_add_f32_e32 v118, v189, v118
	v_add_f32_e32 v116, v116, v117
	s_nop 0
	v_add_f32_dpp v117, v118, v118 row_ror:8 row_mask:0xf bank_mask:0xf bound_ctrl:1
	v_add_f32_dpp v116, v116, v116 row_ror:8 row_mask:0xf bank_mask:0xf bound_ctrl:1
	s_waitcnt lgkmcnt(6)
	v_mul_f32 v118, v122, v104
	v_mul_f32 v104, v123, v104
	v_add_f32_dpp v117, v117, v117 row_ror:4 row_mask:0xf bank_mask:0xf bound_ctrl:1
	v_add_f32_dpp v116, v116, v116 row_ror:4 row_mask:0xf bank_mask:0xf bound_ctrl:1
	s_nop 0
	v_add_f32_dpp v117, v117, v117 row_ror:2 row_mask:0xf bank_mask:0xf bound_ctrl:1
	v_add_f32_dpp v116, v116, v116 row_ror:2 row_mask:0xf bank_mask:0xf bound_ctrl:1
	s_nop 0
	v_add_f32_dpp v117, v117, v117 row_ror:1 row_mask:0xf bank_mask:0xf bound_ctrl:1
	v_add_f32_dpp v116, v116, v116 row_ror:1 row_mask:0xf bank_mask:0xf bound_ctrl:1
	v_fma_f32 v118, v117, v96, v118
	v_fma_f32 v96, v116, v96, v104
	v_fma_f32 v149, v149, v92, v118
	v_fma_f32 v150, v150, v92, v96
	v_mul_f32 v92, v122, v105
	v_fma_f32 v92, v117, v97, v92
	v_fma_f32 v125, v125, v93, v92
	v_mul_f32 v92, v123, v105
	v_fma_f32 v92, v116, v97, v92
	v_fma_f32 v151, v151, v93, v92
	v_mul_f32 v92, v122, v106
	v_mul_f32 v93, v125, v85
	v_fma_f32 v92, v117, v98, v92
	v_mul_f32 v85, v151, v85
	v_fma_f32 v127, v127, v94, v92
	v_mul_f32 v92, v123, v106
	v_fma_f32 v92, v116, v98, v92
	v_fma_f32 v189, v191, v94, v92
	v_mul_f32 v92, v122, v107
	v_fma_f32 v92, v117, v99, v92
	v_fma_f32 v141, v141, v95, v92
	v_mul_f32 v92, v123, v107
	v_fma_f32 v92, v116, v99, v92
	v_fma_f32 v148, v148, v95, v92
	v_mul_f32 v92, v149, v84
	v_mul_f32 v84, v150, v84
	v_fma_f32 v92, v127, v86, v92
	v_fma_f32 v84, v189, v86, v84
	v_fma_f32 v86, v141, v87, v93
	v_fma_f32 v85, v148, v87, v85
	v_add_f32_e32 v86, v92, v86
	v_add_f32_e32 v87, v84, v85
	s_nop 0
	v_add_f32_dpp v84, v86, v86 row_ror:8 row_mask:0xf bank_mask:0xf bound_ctrl:1
	v_add_f32_dpp v86, v87, v87 row_ror:8 row_mask:0xf bank_mask:0xf bound_ctrl:1
	s_nop 0
	v_add_f32_dpp v84, v84, v84 row_ror:4 row_mask:0xf bank_mask:0xf bound_ctrl:1
	v_add_f32_dpp v86, v86, v86 row_ror:4 row_mask:0xf bank_mask:0xf bound_ctrl:1
	s_nop 0
	v_add_f32_dpp v84, v84, v84 row_ror:2 row_mask:0xf bank_mask:0xf bound_ctrl:1
	v_add_f32_dpp v86, v86, v86 row_ror:2 row_mask:0xf bank_mask:0xf bound_ctrl:1
	s_nop 0
	v_add_f32_dpp v84, v84, v84 row_ror:1 row_mask:0xf bank_mask:0xf bound_ctrl:1
	v_add_f32_dpp v86, v86, v86 row_ror:1 row_mask:0xf bank_mask:0xf bound_ctrl:1
	ds_write2_b32 v185, v84, v86 offset0:192 offset1:208
	s_waitcnt lgkmcnt(4)
	v_mul_f32 v191, v149, v112
	v_mul_f32 v112, v150, v112
	v_mul_f32 v192, v125, v113
	v_mul_f32 v113, v151, v113
	ds_read_b128 v[92:95], v134 offset:2048
	ds_read_b128 v[116:119], v134 offset:6144
	ds_read_b128 v[96:99], v134 offset:10240
	ds_read_b128 v[104:107], v134 offset:14336
	ds_read_b128 v[84:87], v134 offset:18432
	ds_read2_b32 v[122:123], v187 offset1:16
	v_fma_f32 v191, v127, v114, v191
	v_fma_f32 v112, v189, v114, v112
	v_fma_f32 v114, v141, v115, v192
	v_fma_f32 v113, v148, v115, v113
	v_add_f32_e32 v114, v191, v114
	v_add_f32_e32 v112, v112, v113
	s_nop 0
	v_add_f32_dpp v113, v114, v114 row_ror:8 row_mask:0xf bank_mask:0xf bound_ctrl:1
	v_add_f32_dpp v112, v112, v112 row_ror:8 row_mask:0xf bank_mask:0xf bound_ctrl:1
	s_waitcnt lgkmcnt(6)
	v_mul_f32 v114, v120, v108
	v_mul_f32 v108, v121, v108
	v_add_f32_dpp v113, v113, v113 row_ror:4 row_mask:0xf bank_mask:0xf bound_ctrl:1
	v_add_f32_dpp v112, v112, v112 row_ror:4 row_mask:0xf bank_mask:0xf bound_ctrl:1
	s_nop 0
	v_add_f32_dpp v113, v113, v113 row_ror:2 row_mask:0xf bank_mask:0xf bound_ctrl:1
	v_add_f32_dpp v112, v112, v112 row_ror:2 row_mask:0xf bank_mask:0xf bound_ctrl:1
	s_nop 0
	v_add_f32_dpp v113, v113, v113 row_ror:1 row_mask:0xf bank_mask:0xf bound_ctrl:1
	v_add_f32_dpp v112, v112, v112 row_ror:1 row_mask:0xf bank_mask:0xf bound_ctrl:1
	v_fma_f32 v114, v113, v100, v114
	v_fma_f32 v100, v112, v100, v108
	v_fma_f32 v149, v149, v88, v114
	v_fma_f32 v150, v150, v88, v100
	v_mul_f32 v88, v120, v109
	v_fma_f32 v88, v113, v101, v88
	v_fma_f32 v125, v125, v89, v88
	v_mul_f32 v88, v121, v109
	v_fma_f32 v88, v112, v101, v88
	v_fma_f32 v151, v151, v89, v88
	v_mul_f32 v88, v120, v110
	v_mul_f32 v89, v125, v81
	v_fma_f32 v88, v113, v102, v88
	v_mul_f32 v81, v151, v81
	v_fma_f32 v127, v127, v90, v88
	v_mul_f32 v88, v121, v110
	v_fma_f32 v88, v112, v102, v88
	v_fma_f32 v189, v189, v90, v88
	v_mul_f32 v88, v120, v111
	v_fma_f32 v88, v113, v103, v88
	v_fma_f32 v141, v141, v91, v88
	v_mul_f32 v88, v121, v111
	v_fma_f32 v88, v112, v103, v88
	v_fma_f32 v148, v148, v91, v88
	v_mul_f32 v88, v149, v80
	v_mul_f32 v80, v150, v80
	v_fma_f32 v88, v127, v82, v88
	v_fma_f32 v80, v189, v82, v80
	v_fma_f32 v82, v141, v83, v89
	v_fma_f32 v81, v148, v83, v81
	v_add_f32_e32 v82, v88, v82
	v_add_f32_e32 v83, v80, v81
	s_nop 0
	v_add_f32_dpp v80, v82, v82 row_ror:8 row_mask:0xf bank_mask:0xf bound_ctrl:1
	v_add_f32_dpp v82, v83, v83 row_ror:8 row_mask:0xf bank_mask:0xf bound_ctrl:1
	s_nop 0
	v_add_f32_dpp v80, v80, v80 row_ror:4 row_mask:0xf bank_mask:0xf bound_ctrl:1
	v_add_f32_dpp v82, v82, v82 row_ror:4 row_mask:0xf bank_mask:0xf bound_ctrl:1
	s_nop 0
	v_add_f32_dpp v80, v80, v80 row_ror:2 row_mask:0xf bank_mask:0xf bound_ctrl:1
	v_add_f32_dpp v82, v82, v82 row_ror:2 row_mask:0xf bank_mask:0xf bound_ctrl:1
	s_nop 0
	v_add_f32_dpp v80, v80, v80 row_ror:1 row_mask:0xf bank_mask:0xf bound_ctrl:1
	v_add_f32_dpp v82, v82, v82 row_ror:1 row_mask:0xf bank_mask:0xf bound_ctrl:1
	ds_write2_b32 v185, v80, v82 offset0:224 offset1:240
	s_waitcnt lgkmcnt(4)
	v_mul_f32 v185, v149, v116
	v_mul_f32 v116, v150, v116
	v_mul_f32 v191, v125, v117
	v_mul_f32 v117, v151, v117
	ds_read_b128 v[88:91], v134 offset:2304
	ds_read_b128 v[112:115], v134 offset:6400
	ds_read_b128 v[100:103], v134 offset:10496
	ds_read_b128 v[108:111], v134 offset:14592
	ds_read_b128 v[80:83], v134 offset:18688
	ds_read2_b32 v[120:121], v187 offset0:32 offset1:48
	v_fma_f32 v185, v127, v118, v185
	v_fma_f32 v116, v189, v118, v116
	v_fma_f32 v118, v141, v119, v191
	v_fma_f32 v117, v148, v119, v117
	v_add_f32_e32 v118, v185, v118
	v_add_f32_e32 v116, v116, v117
	s_nop 0
	v_add_f32_dpp v117, v118, v118 row_ror:8 row_mask:0xf bank_mask:0xf bound_ctrl:1
	v_add_f32_dpp v116, v116, v116 row_ror:8 row_mask:0xf bank_mask:0xf bound_ctrl:1
	s_waitcnt lgkmcnt(6)
	v_mul_f32 v118, v122, v104
	v_mul_f32 v104, v123, v104
	v_add_f32_dpp v117, v117, v117 row_ror:4 row_mask:0xf bank_mask:0xf bound_ctrl:1
	v_add_f32_dpp v116, v116, v116 row_ror:4 row_mask:0xf bank_mask:0xf bound_ctrl:1
	s_nop 0
	v_add_f32_dpp v117, v117, v117 row_ror:2 row_mask:0xf bank_mask:0xf bound_ctrl:1
	v_add_f32_dpp v116, v116, v116 row_ror:2 row_mask:0xf bank_mask:0xf bound_ctrl:1
	s_nop 0
	v_add_f32_dpp v117, v117, v117 row_ror:1 row_mask:0xf bank_mask:0xf bound_ctrl:1
	v_add_f32_dpp v116, v116, v116 row_ror:1 row_mask:0xf bank_mask:0xf bound_ctrl:1
	v_fma_f32 v118, v117, v96, v118
	v_fma_f32 v96, v116, v96, v104
	v_fma_f32 v149, v149, v92, v118
	v_fma_f32 v150, v150, v92, v96
	v_mul_f32 v92, v122, v105
	v_fma_f32 v92, v117, v97, v92
	v_fma_f32 v125, v125, v93, v92
	v_mul_f32 v92, v123, v105
	v_fma_f32 v92, v116, v97, v92
	v_fma_f32 v151, v151, v93, v92
	v_mul_f32 v92, v122, v106
	v_mul_f32 v93, v125, v85
	v_fma_f32 v92, v117, v98, v92
	v_mul_f32 v85, v151, v85
	v_fma_f32 v127, v127, v94, v92
	v_mul_f32 v92, v123, v106
	v_fma_f32 v92, v116, v98, v92
	v_fma_f32 v185, v189, v94, v92
	v_mul_f32 v92, v122, v107
	v_fma_f32 v92, v117, v99, v92
	v_fma_f32 v141, v141, v95, v92
	v_mul_f32 v92, v123, v107
	v_fma_f32 v92, v116, v99, v92
	v_fma_f32 v148, v148, v95, v92
	v_mul_f32 v92, v149, v84
	v_mul_f32 v84, v150, v84
	v_fma_f32 v92, v127, v86, v92
	v_fma_f32 v84, v185, v86, v84
	v_fma_f32 v86, v141, v87, v93
	v_fma_f32 v85, v148, v87, v85
	v_add_f32_e32 v86, v92, v86
	v_add_f32_e32 v87, v84, v85
	s_nop 0
	v_add_f32_dpp v84, v86, v86 row_ror:8 row_mask:0xf bank_mask:0xf bound_ctrl:1
	v_add_f32_dpp v86, v87, v87 row_ror:8 row_mask:0xf bank_mask:0xf bound_ctrl:1
	s_nop 0
	v_add_f32_dpp v84, v84, v84 row_ror:4 row_mask:0xf bank_mask:0xf bound_ctrl:1
	v_add_f32_dpp v86, v86, v86 row_ror:4 row_mask:0xf bank_mask:0xf bound_ctrl:1
	s_nop 0
	v_add_f32_dpp v84, v84, v84 row_ror:2 row_mask:0xf bank_mask:0xf bound_ctrl:1
	v_add_f32_dpp v86, v86, v86 row_ror:2 row_mask:0xf bank_mask:0xf bound_ctrl:1
	s_nop 0
	v_add_f32_dpp v84, v84, v84 row_ror:1 row_mask:0xf bank_mask:0xf bound_ctrl:1
	v_add_f32_dpp v86, v86, v86 row_ror:1 row_mask:0xf bank_mask:0xf bound_ctrl:1
	ds_write2_b32 v186, v84, v86 offset1:16
	s_waitcnt lgkmcnt(4)
	v_mul_f32 v189, v149, v112
	v_mul_f32 v112, v150, v112
	v_mul_f32 v191, v125, v113
	v_mul_f32 v113, v151, v113
	ds_read_b128 v[92:95], v134 offset:2560
	ds_read_b128 v[116:119], v134 offset:6656
	ds_read_b128 v[96:99], v134 offset:10752
	ds_read_b128 v[104:107], v134 offset:14848
	ds_read_b128 v[84:87], v134 offset:18944
	ds_read2_b32 v[122:123], v187 offset0:64 offset1:80
	v_fma_f32 v189, v127, v114, v189
	v_fma_f32 v112, v185, v114, v112
	v_fma_f32 v114, v141, v115, v191
	v_fma_f32 v113, v148, v115, v113
	v_add_f32_e32 v114, v189, v114
	v_add_f32_e32 v112, v112, v113
	s_nop 0
	v_add_f32_dpp v113, v114, v114 row_ror:8 row_mask:0xf bank_mask:0xf bound_ctrl:1
	v_add_f32_dpp v112, v112, v112 row_ror:8 row_mask:0xf bank_mask:0xf bound_ctrl:1
	s_waitcnt lgkmcnt(6)
	v_mul_f32 v114, v120, v108
	v_mul_f32 v108, v121, v108
	v_add_f32_dpp v113, v113, v113 row_ror:4 row_mask:0xf bank_mask:0xf bound_ctrl:1
	v_add_f32_dpp v112, v112, v112 row_ror:4 row_mask:0xf bank_mask:0xf bound_ctrl:1
	s_nop 0
	v_add_f32_dpp v113, v113, v113 row_ror:2 row_mask:0xf bank_mask:0xf bound_ctrl:1
	v_add_f32_dpp v112, v112, v112 row_ror:2 row_mask:0xf bank_mask:0xf bound_ctrl:1
	s_nop 0
	v_add_f32_dpp v113, v113, v113 row_ror:1 row_mask:0xf bank_mask:0xf bound_ctrl:1
	v_add_f32_dpp v112, v112, v112 row_ror:1 row_mask:0xf bank_mask:0xf bound_ctrl:1
	v_fma_f32 v114, v113, v100, v114
	v_fma_f32 v100, v112, v100, v108
	v_fma_f32 v149, v149, v88, v114
	v_fma_f32 v150, v150, v88, v100
	v_mul_f32 v88, v120, v109
	v_fma_f32 v88, v113, v101, v88
	v_fma_f32 v125, v125, v89, v88
	v_mul_f32 v88, v121, v109
	v_fma_f32 v88, v112, v101, v88
	v_fma_f32 v151, v151, v89, v88
	v_mul_f32 v88, v120, v110
	v_mul_f32 v89, v125, v81
	v_fma_f32 v88, v113, v102, v88
	v_mul_f32 v81, v151, v81
	v_fma_f32 v127, v127, v90, v88
	v_mul_f32 v88, v121, v110
	v_fma_f32 v88, v112, v102, v88
	v_fma_f32 v185, v185, v90, v88
	v_mul_f32 v88, v120, v111
	v_fma_f32 v88, v113, v103, v88
	v_fma_f32 v141, v141, v91, v88
	v_mul_f32 v88, v121, v111
	v_fma_f32 v88, v112, v103, v88
	v_fma_f32 v148, v148, v91, v88
	v_mul_f32 v88, v149, v80
	v_mul_f32 v80, v150, v80
	v_fma_f32 v88, v127, v82, v88
	v_fma_f32 v80, v185, v82, v80
	v_fma_f32 v82, v141, v83, v89
	v_fma_f32 v81, v148, v83, v81
	v_add_f32_e32 v82, v88, v82
	v_add_f32_e32 v83, v80, v81
	s_nop 0
	v_add_f32_dpp v80, v82, v82 row_ror:8 row_mask:0xf bank_mask:0xf bound_ctrl:1
	v_add_f32_dpp v82, v83, v83 row_ror:8 row_mask:0xf bank_mask:0xf bound_ctrl:1
	s_nop 0
	v_add_f32_dpp v80, v80, v80 row_ror:4 row_mask:0xf bank_mask:0xf bound_ctrl:1
	v_add_f32_dpp v82, v82, v82 row_ror:4 row_mask:0xf bank_mask:0xf bound_ctrl:1
	s_nop 0
	v_add_f32_dpp v80, v80, v80 row_ror:2 row_mask:0xf bank_mask:0xf bound_ctrl:1
	v_add_f32_dpp v82, v82, v82 row_ror:2 row_mask:0xf bank_mask:0xf bound_ctrl:1
	s_nop 0
	v_add_f32_dpp v80, v80, v80 row_ror:1 row_mask:0xf bank_mask:0xf bound_ctrl:1
	v_add_f32_dpp v82, v82, v82 row_ror:1 row_mask:0xf bank_mask:0xf bound_ctrl:1
	ds_write2_b32 v186, v80, v82 offset0:32 offset1:48
	s_waitcnt lgkmcnt(4)
	v_mul_f32 v189, v149, v116
	v_mul_f32 v116, v150, v116
	v_mul_f32 v191, v125, v117
	v_mul_f32 v117, v151, v117
	ds_read_b128 v[88:91], v134 offset:2816
	ds_read_b128 v[112:115], v134 offset:6912
	ds_read_b128 v[100:103], v134 offset:11008
	ds_read_b128 v[108:111], v134 offset:15104
	ds_read_b128 v[80:83], v134 offset:19200
	ds_read2_b32 v[120:121], v187 offset0:96 offset1:112
	v_fma_f32 v189, v127, v118, v189
	v_fma_f32 v116, v185, v118, v116
	v_fma_f32 v118, v141, v119, v191
	v_fma_f32 v117, v148, v119, v117
	v_add_f32_e32 v118, v189, v118
	v_add_f32_e32 v116, v116, v117
	s_nop 0
	v_add_f32_dpp v117, v118, v118 row_ror:8 row_mask:0xf bank_mask:0xf bound_ctrl:1
	v_add_f32_dpp v116, v116, v116 row_ror:8 row_mask:0xf bank_mask:0xf bound_ctrl:1
	s_waitcnt lgkmcnt(6)
	v_mul_f32 v118, v122, v104
	v_mul_f32 v104, v123, v104
	v_add_f32_dpp v117, v117, v117 row_ror:4 row_mask:0xf bank_mask:0xf bound_ctrl:1
	v_add_f32_dpp v116, v116, v116 row_ror:4 row_mask:0xf bank_mask:0xf bound_ctrl:1
	s_nop 0
	v_add_f32_dpp v117, v117, v117 row_ror:2 row_mask:0xf bank_mask:0xf bound_ctrl:1
	v_add_f32_dpp v116, v116, v116 row_ror:2 row_mask:0xf bank_mask:0xf bound_ctrl:1
	s_nop 0
	v_add_f32_dpp v117, v117, v117 row_ror:1 row_mask:0xf bank_mask:0xf bound_ctrl:1
	v_add_f32_dpp v116, v116, v116 row_ror:1 row_mask:0xf bank_mask:0xf bound_ctrl:1
	v_fma_f32 v118, v117, v96, v118
	v_fma_f32 v96, v116, v96, v104
	v_fma_f32 v149, v149, v92, v118
	v_fma_f32 v150, v150, v92, v96
	v_mul_f32 v92, v122, v105
	v_fma_f32 v92, v117, v97, v92
	v_fma_f32 v125, v125, v93, v92
	v_mul_f32 v92, v123, v105
	v_fma_f32 v92, v116, v97, v92
	v_fma_f32 v151, v151, v93, v92
	v_mul_f32 v92, v122, v106
	v_mul_f32 v93, v125, v85
	v_fma_f32 v92, v117, v98, v92
	v_mul_f32 v85, v151, v85
	v_fma_f32 v127, v127, v94, v92
	v_mul_f32 v92, v123, v106
	v_fma_f32 v92, v116, v98, v92
	v_fma_f32 v185, v185, v94, v92
	v_mul_f32 v92, v122, v107
	v_fma_f32 v92, v117, v99, v92
	v_fma_f32 v141, v141, v95, v92
	v_mul_f32 v92, v123, v107
	v_fma_f32 v92, v116, v99, v92
	v_fma_f32 v148, v148, v95, v92
	v_mul_f32 v92, v149, v84
	v_mul_f32 v84, v150, v84
	v_fma_f32 v92, v127, v86, v92
	v_fma_f32 v84, v185, v86, v84
	v_fma_f32 v86, v141, v87, v93
	v_fma_f32 v85, v148, v87, v85
	v_add_f32_e32 v86, v92, v86
	v_add_f32_e32 v87, v84, v85
	s_nop 0
	v_add_f32_dpp v84, v86, v86 row_ror:8 row_mask:0xf bank_mask:0xf bound_ctrl:1
	v_add_f32_dpp v86, v87, v87 row_ror:8 row_mask:0xf bank_mask:0xf bound_ctrl:1
	s_nop 0
	v_add_f32_dpp v84, v84, v84 row_ror:4 row_mask:0xf bank_mask:0xf bound_ctrl:1
	v_add_f32_dpp v86, v86, v86 row_ror:4 row_mask:0xf bank_mask:0xf bound_ctrl:1
	s_nop 0
	v_add_f32_dpp v84, v84, v84 row_ror:2 row_mask:0xf bank_mask:0xf bound_ctrl:1
	v_add_f32_dpp v86, v86, v86 row_ror:2 row_mask:0xf bank_mask:0xf bound_ctrl:1
	s_nop 0
	v_add_f32_dpp v84, v84, v84 row_ror:1 row_mask:0xf bank_mask:0xf bound_ctrl:1
	v_add_f32_dpp v86, v86, v86 row_ror:1 row_mask:0xf bank_mask:0xf bound_ctrl:1
	ds_write2_b32 v186, v84, v86 offset0:64 offset1:80
	s_waitcnt lgkmcnt(4)
	v_mul_f32 v189, v149, v112
	v_mul_f32 v112, v150, v112
	v_mul_f32 v191, v125, v113
	v_mul_f32 v113, v151, v113
	ds_read_b128 v[92:95], v134 offset:3072
	ds_read_b128 v[116:119], v134 offset:7168
	ds_read_b128 v[96:99], v134 offset:11264
	ds_read_b128 v[104:107], v134 offset:15360
	ds_read_b128 v[84:87], v134 offset:19456
	ds_read2_b32 v[122:123], v187 offset0:128 offset1:144
	v_fma_f32 v189, v127, v114, v189
	v_fma_f32 v112, v185, v114, v112
	v_fma_f32 v114, v141, v115, v191
	v_fma_f32 v113, v148, v115, v113
	v_add_f32_e32 v114, v189, v114
	v_add_f32_e32 v112, v112, v113
	s_nop 0
	v_add_f32_dpp v113, v114, v114 row_ror:8 row_mask:0xf bank_mask:0xf bound_ctrl:1
	v_add_f32_dpp v112, v112, v112 row_ror:8 row_mask:0xf bank_mask:0xf bound_ctrl:1
	s_waitcnt lgkmcnt(6)
	v_mul_f32 v114, v120, v108
	v_mul_f32 v108, v121, v108
	v_add_f32_dpp v113, v113, v113 row_ror:4 row_mask:0xf bank_mask:0xf bound_ctrl:1
	v_add_f32_dpp v112, v112, v112 row_ror:4 row_mask:0xf bank_mask:0xf bound_ctrl:1
	s_nop 0
	v_add_f32_dpp v113, v113, v113 row_ror:2 row_mask:0xf bank_mask:0xf bound_ctrl:1
	v_add_f32_dpp v112, v112, v112 row_ror:2 row_mask:0xf bank_mask:0xf bound_ctrl:1
	s_nop 0
	v_add_f32_dpp v113, v113, v113 row_ror:1 row_mask:0xf bank_mask:0xf bound_ctrl:1
	v_add_f32_dpp v112, v112, v112 row_ror:1 row_mask:0xf bank_mask:0xf bound_ctrl:1
	v_fma_f32 v114, v113, v100, v114
	v_fma_f32 v100, v112, v100, v108
	v_fma_f32 v149, v149, v88, v114
	v_fma_f32 v150, v150, v88, v100
	v_mul_f32 v88, v120, v109
	v_fma_f32 v88, v113, v101, v88
	v_fma_f32 v125, v125, v89, v88
	v_mul_f32 v88, v121, v109
	v_fma_f32 v88, v112, v101, v88
	v_fma_f32 v151, v151, v89, v88
	v_mul_f32 v88, v120, v110
	v_mul_f32 v89, v125, v81
	v_fma_f32 v88, v113, v102, v88
	v_mul_f32 v81, v151, v81
	v_fma_f32 v127, v127, v90, v88
	v_mul_f32 v88, v121, v110
	v_fma_f32 v88, v112, v102, v88
	v_fma_f32 v185, v185, v90, v88
	v_mul_f32 v88, v120, v111
	v_fma_f32 v88, v113, v103, v88
	v_fma_f32 v141, v141, v91, v88
	v_mul_f32 v88, v121, v111
	v_fma_f32 v88, v112, v103, v88
	v_fma_f32 v148, v148, v91, v88
	v_mul_f32 v88, v149, v80
	v_mul_f32 v80, v150, v80
	v_fma_f32 v88, v127, v82, v88
	v_fma_f32 v80, v185, v82, v80
	v_fma_f32 v82, v141, v83, v89
	v_fma_f32 v81, v148, v83, v81
	v_add_f32_e32 v82, v88, v82
	v_add_f32_e32 v83, v80, v81
	s_nop 0
	v_add_f32_dpp v80, v82, v82 row_ror:8 row_mask:0xf bank_mask:0xf bound_ctrl:1
	v_add_f32_dpp v82, v83, v83 row_ror:8 row_mask:0xf bank_mask:0xf bound_ctrl:1
	s_nop 0
	v_add_f32_dpp v80, v80, v80 row_ror:4 row_mask:0xf bank_mask:0xf bound_ctrl:1
	v_add_f32_dpp v82, v82, v82 row_ror:4 row_mask:0xf bank_mask:0xf bound_ctrl:1
	s_nop 0
	v_add_f32_dpp v80, v80, v80 row_ror:2 row_mask:0xf bank_mask:0xf bound_ctrl:1
	v_add_f32_dpp v82, v82, v82 row_ror:2 row_mask:0xf bank_mask:0xf bound_ctrl:1
	s_nop 0
	v_add_f32_dpp v80, v80, v80 row_ror:1 row_mask:0xf bank_mask:0xf bound_ctrl:1
	v_add_f32_dpp v82, v82, v82 row_ror:1 row_mask:0xf bank_mask:0xf bound_ctrl:1
	ds_write2_b32 v186, v80, v82 offset0:96 offset1:112
	s_waitcnt lgkmcnt(4)
	v_mul_f32 v189, v149, v116
	v_mul_f32 v116, v150, v116
	v_mul_f32 v191, v125, v117
	v_mul_f32 v117, v151, v117
	ds_read_b128 v[88:91], v134 offset:3328
	ds_read_b128 v[112:115], v134 offset:7424
	ds_read_b128 v[100:103], v134 offset:11520
	ds_read_b128 v[108:111], v134 offset:15616
	ds_read_b128 v[80:83], v134 offset:19712
	ds_read2_b32 v[120:121], v187 offset0:160 offset1:176
	v_fma_f32 v189, v127, v118, v189
	v_fma_f32 v116, v185, v118, v116
	v_fma_f32 v118, v141, v119, v191
	v_fma_f32 v117, v148, v119, v117
	v_add_f32_e32 v118, v189, v118
	v_add_f32_e32 v116, v116, v117
	s_nop 0
	v_add_f32_dpp v117, v118, v118 row_ror:8 row_mask:0xf bank_mask:0xf bound_ctrl:1
	v_add_f32_dpp v116, v116, v116 row_ror:8 row_mask:0xf bank_mask:0xf bound_ctrl:1
	s_waitcnt lgkmcnt(6)
	v_mul_f32 v118, v122, v104
	v_mul_f32 v104, v123, v104
	v_add_f32_dpp v117, v117, v117 row_ror:4 row_mask:0xf bank_mask:0xf bound_ctrl:1
	v_add_f32_dpp v116, v116, v116 row_ror:4 row_mask:0xf bank_mask:0xf bound_ctrl:1
	s_nop 0
	v_add_f32_dpp v117, v117, v117 row_ror:2 row_mask:0xf bank_mask:0xf bound_ctrl:1
	v_add_f32_dpp v116, v116, v116 row_ror:2 row_mask:0xf bank_mask:0xf bound_ctrl:1
	s_nop 0
	v_add_f32_dpp v117, v117, v117 row_ror:1 row_mask:0xf bank_mask:0xf bound_ctrl:1
	v_add_f32_dpp v116, v116, v116 row_ror:1 row_mask:0xf bank_mask:0xf bound_ctrl:1
	v_fma_f32 v118, v117, v96, v118
	v_fma_f32 v96, v116, v96, v104
	v_fma_f32 v149, v149, v92, v118
	v_fma_f32 v150, v150, v92, v96
	v_mul_f32 v92, v122, v105
	v_fma_f32 v92, v117, v97, v92
	v_fma_f32 v125, v125, v93, v92
	v_mul_f32 v92, v123, v105
	v_fma_f32 v92, v116, v97, v92
	v_fma_f32 v151, v151, v93, v92
	v_mul_f32 v92, v122, v106
	v_mul_f32 v93, v125, v85
	v_fma_f32 v92, v117, v98, v92
	v_mul_f32 v85, v151, v85
	v_fma_f32 v127, v127, v94, v92
	v_mul_f32 v92, v123, v106
	v_fma_f32 v92, v116, v98, v92
	v_fma_f32 v185, v185, v94, v92
	v_mul_f32 v92, v122, v107
	v_fma_f32 v92, v117, v99, v92
	v_fma_f32 v141, v141, v95, v92
	v_mul_f32 v92, v123, v107
	v_fma_f32 v92, v116, v99, v92
	v_fma_f32 v148, v148, v95, v92
	v_mul_f32 v92, v149, v84
	v_mul_f32 v84, v150, v84
	v_fma_f32 v92, v127, v86, v92
	v_fma_f32 v84, v185, v86, v84
	v_fma_f32 v86, v141, v87, v93
	v_fma_f32 v85, v148, v87, v85
	v_add_f32_e32 v86, v92, v86
	v_add_f32_e32 v87, v84, v85
	s_nop 0
	v_add_f32_dpp v84, v86, v86 row_ror:8 row_mask:0xf bank_mask:0xf bound_ctrl:1
	v_add_f32_dpp v86, v87, v87 row_ror:8 row_mask:0xf bank_mask:0xf bound_ctrl:1
	s_nop 0
	v_add_f32_dpp v84, v84, v84 row_ror:4 row_mask:0xf bank_mask:0xf bound_ctrl:1
	v_add_f32_dpp v86, v86, v86 row_ror:4 row_mask:0xf bank_mask:0xf bound_ctrl:1
	s_nop 0
	v_add_f32_dpp v84, v84, v84 row_ror:2 row_mask:0xf bank_mask:0xf bound_ctrl:1
	v_add_f32_dpp v86, v86, v86 row_ror:2 row_mask:0xf bank_mask:0xf bound_ctrl:1
	s_nop 0
	v_add_f32_dpp v84, v84, v84 row_ror:1 row_mask:0xf bank_mask:0xf bound_ctrl:1
	v_add_f32_dpp v86, v86, v86 row_ror:1 row_mask:0xf bank_mask:0xf bound_ctrl:1
	ds_write2_b32 v186, v84, v86 offset0:128 offset1:144
	s_waitcnt lgkmcnt(4)
	v_mul_f32 v189, v149, v112
	v_mul_f32 v112, v150, v112
	v_mul_f32 v191, v125, v113
	v_mul_f32 v113, v151, v113
	ds_read_b128 v[92:95], v134 offset:3584
	ds_read_b128 v[116:119], v134 offset:7680
	ds_read_b128 v[96:99], v134 offset:11776
	ds_read_b128 v[104:107], v134 offset:15872
	ds_read_b128 v[84:87], v134 offset:19968
	ds_read2_b32 v[122:123], v187 offset0:192 offset1:208
	v_fma_f32 v189, v127, v114, v189
	v_fma_f32 v112, v185, v114, v112
	v_fma_f32 v114, v141, v115, v191
	v_fma_f32 v113, v148, v115, v113
	v_add_f32_e32 v114, v189, v114
	v_add_f32_e32 v112, v112, v113
	s_nop 0
	v_add_f32_dpp v113, v114, v114 row_ror:8 row_mask:0xf bank_mask:0xf bound_ctrl:1
	v_add_f32_dpp v112, v112, v112 row_ror:8 row_mask:0xf bank_mask:0xf bound_ctrl:1
	s_waitcnt lgkmcnt(6)
	v_mul_f32 v114, v120, v108
	v_mul_f32 v108, v121, v108
	v_add_f32_dpp v113, v113, v113 row_ror:4 row_mask:0xf bank_mask:0xf bound_ctrl:1
	v_add_f32_dpp v112, v112, v112 row_ror:4 row_mask:0xf bank_mask:0xf bound_ctrl:1
	s_nop 0
	v_add_f32_dpp v113, v113, v113 row_ror:2 row_mask:0xf bank_mask:0xf bound_ctrl:1
	v_add_f32_dpp v112, v112, v112 row_ror:2 row_mask:0xf bank_mask:0xf bound_ctrl:1
	s_nop 0
	v_add_f32_dpp v113, v113, v113 row_ror:1 row_mask:0xf bank_mask:0xf bound_ctrl:1
	v_add_f32_dpp v112, v112, v112 row_ror:1 row_mask:0xf bank_mask:0xf bound_ctrl:1
	v_fma_f32 v114, v113, v100, v114
	v_fma_f32 v100, v112, v100, v108
	v_fma_f32 v149, v149, v88, v114
	v_fma_f32 v150, v150, v88, v100
	v_mul_f32 v88, v120, v109
	v_fma_f32 v88, v113, v101, v88
	v_fma_f32 v125, v125, v89, v88
	v_mul_f32 v88, v121, v109
	v_fma_f32 v88, v112, v101, v88
	v_fma_f32 v151, v151, v89, v88
	v_mul_f32 v88, v120, v110
	v_mul_f32 v89, v125, v81
	v_fma_f32 v88, v113, v102, v88
	v_mul_f32 v81, v151, v81
	v_fma_f32 v127, v127, v90, v88
	v_mul_f32 v88, v121, v110
	v_fma_f32 v88, v112, v102, v88
	v_fma_f32 v185, v185, v90, v88
	v_mul_f32 v88, v120, v111
	v_fma_f32 v88, v113, v103, v88
	v_fma_f32 v141, v141, v91, v88
	v_mul_f32 v88, v121, v111
	v_fma_f32 v88, v112, v103, v88
	v_fma_f32 v148, v148, v91, v88
	v_mul_f32 v88, v149, v80
	v_mul_f32 v80, v150, v80
	v_fma_f32 v88, v127, v82, v88
	v_fma_f32 v80, v185, v82, v80
	v_fma_f32 v82, v141, v83, v89
	v_fma_f32 v81, v148, v83, v81
	v_add_f32_e32 v82, v88, v82
	v_add_f32_e32 v83, v80, v81
	s_nop 0
	v_add_f32_dpp v80, v82, v82 row_ror:8 row_mask:0xf bank_mask:0xf bound_ctrl:1
	v_add_f32_dpp v82, v83, v83 row_ror:8 row_mask:0xf bank_mask:0xf bound_ctrl:1
	s_nop 0
	v_add_f32_dpp v80, v80, v80 row_ror:4 row_mask:0xf bank_mask:0xf bound_ctrl:1
	v_add_f32_dpp v82, v82, v82 row_ror:4 row_mask:0xf bank_mask:0xf bound_ctrl:1
	s_nop 0
	v_add_f32_dpp v80, v80, v80 row_ror:2 row_mask:0xf bank_mask:0xf bound_ctrl:1
	v_add_f32_dpp v82, v82, v82 row_ror:2 row_mask:0xf bank_mask:0xf bound_ctrl:1
	s_nop 0
	v_add_f32_dpp v80, v80, v80 row_ror:1 row_mask:0xf bank_mask:0xf bound_ctrl:1
	v_add_f32_dpp v82, v82, v82 row_ror:1 row_mask:0xf bank_mask:0xf bound_ctrl:1
	ds_write2_b32 v186, v80, v82 offset0:160 offset1:176
	ds_read_b128 v[88:91], v134 offset:3840
	ds_read_b128 v[112:115], v134 offset:7936
	ds_read_b128 v[100:103], v134 offset:12032
	ds_read_b128 v[108:111], v134 offset:16128
	ds_read_b128 v[80:83], v134 offset:20224
	ds_read2_b32 v[120:121], v187 offset0:224 offset1:240
	s_waitcnt lgkmcnt(10)
	v_mul_f32 v187, v149, v116
	v_mul_f32 v116, v150, v116
	v_mul_f32 v189, v125, v117
	v_mul_f32 v117, v151, v117
	v_fma_f32 v187, v127, v118, v187
	v_fma_f32 v116, v185, v118, v116
	v_fma_f32 v118, v141, v119, v189
	v_fma_f32 v117, v148, v119, v117
	v_add_f32_e32 v116, v116, v117
	v_add_f32_e32 v118, v187, v118
	s_nop 0
	v_add_f32_dpp v116, v116, v116 row_ror:8 row_mask:0xf bank_mask:0xf bound_ctrl:1
	v_add_f32_dpp v117, v118, v118 row_ror:8 row_mask:0xf bank_mask:0xf bound_ctrl:1
	s_nop 0
	v_add_f32_dpp v116, v116, v116 row_ror:4 row_mask:0xf bank_mask:0xf bound_ctrl:1
	v_add_f32_dpp v117, v117, v117 row_ror:4 row_mask:0xf bank_mask:0xf bound_ctrl:1
	s_nop 0
	v_add_f32_dpp v116, v116, v116 row_ror:2 row_mask:0xf bank_mask:0xf bound_ctrl:1
	v_add_f32_dpp v117, v117, v117 row_ror:2 row_mask:0xf bank_mask:0xf bound_ctrl:1
	s_nop 0
	v_add_f32_dpp v118, v116, v116 row_ror:1 row_mask:0xf bank_mask:0xf bound_ctrl:1
	s_waitcnt lgkmcnt(6)
	v_mul_f32 v116, v122, v104
	v_add_f32_dpp v117, v117, v117 row_ror:1 row_mask:0xf bank_mask:0xf bound_ctrl:1
	v_fma_f32 v116, v117, v96, v116
	v_mul_f32 v104, v123, v104
	v_fma_f32 v96, v118, v96, v104
	v_fma_f32 v116, v149, v92, v116
	v_mul_f32 v104, v123, v105
	v_fma_f32 v92, v150, v92, v96
	v_mul_f32 v96, v122, v105
	v_fma_f32 v96, v117, v97, v96
	v_fma_f32 v97, v118, v97, v104
	v_mul_f32 v104, v123, v106
	v_fma_f32 v96, v125, v93, v96
	v_fma_f32 v93, v151, v93, v97
	v_mul_f32 v97, v122, v106
	v_fma_f32 v97, v117, v98, v97
	v_fma_f32 v98, v118, v98, v104
	v_mul_f32 v104, v123, v107
	v_fma_f32 v97, v127, v94, v97
	v_fma_f32 v94, v185, v94, v98
	v_mul_f32 v98, v122, v107
	v_fma_f32 v98, v117, v99, v98
	v_fma_f32 v99, v118, v99, v104
	v_mul_f32 v104, v96, v85
	v_mul_f32 v85, v93, v85
	v_fma_f32 v98, v141, v95, v98
	v_fma_f32 v95, v148, v95, v99
	v_mul_f32 v99, v116, v84
	v_mul_f32 v84, v92, v84
	v_fma_f32 v99, v97, v86, v99
	v_fma_f32 v84, v94, v86, v84
	v_fma_f32 v86, v98, v87, v104
	v_fma_f32 v85, v95, v87, v85
	v_add_f32_e32 v86, v99, v86
	v_add_f32_e32 v87, v84, v85
	s_nop 0
	v_add_f32_dpp v84, v86, v86 row_ror:8 row_mask:0xf bank_mask:0xf bound_ctrl:1
	v_add_f32_dpp v86, v87, v87 row_ror:8 row_mask:0xf bank_mask:0xf bound_ctrl:1
	s_nop 0
	v_add_f32_dpp v84, v84, v84 row_ror:4 row_mask:0xf bank_mask:0xf bound_ctrl:1
	v_add_f32_dpp v86, v86, v86 row_ror:4 row_mask:0xf bank_mask:0xf bound_ctrl:1
	s_nop 0
	v_add_f32_dpp v84, v84, v84 row_ror:2 row_mask:0xf bank_mask:0xf bound_ctrl:1
	v_add_f32_dpp v86, v86, v86 row_ror:2 row_mask:0xf bank_mask:0xf bound_ctrl:1
	s_nop 0
	v_add_f32_dpp v84, v84, v84 row_ror:1 row_mask:0xf bank_mask:0xf bound_ctrl:1
	v_add_f32_dpp v86, v86, v86 row_ror:1 row_mask:0xf bank_mask:0xf bound_ctrl:1
	ds_write2_b32 v186, v84, v86 offset0:192 offset1:208
	s_waitcnt lgkmcnt(4)
	v_mul_f32 v84, v116, v112
	v_mul_f32 v86, v96, v113
	v_mul_f32 v85, v92, v112
	v_mul_f32 v87, v93, v113
	v_fma_f32 v84, v97, v114, v84
	v_fma_f32 v86, v98, v115, v86
	v_fma_f32 v85, v94, v114, v85
	v_fma_f32 v87, v95, v115, v87
	v_add_f32_e32 v84, v84, v86
	v_add_f32_e32 v85, v85, v87
	s_nop 0
	v_add_f32_dpp v84, v84, v84 row_ror:8 row_mask:0xf bank_mask:0xf bound_ctrl:1
	s_waitcnt lgkmcnt(0)
	v_mul_f32 v86, v120, v109
	v_mul_f32 v87, v121, v109
	v_add_f32_dpp v84, v84, v84 row_ror:4 row_mask:0xf bank_mask:0xf bound_ctrl:1
	s_nop 1
	v_add_f32_dpp v84, v84, v84 row_ror:2 row_mask:0xf bank_mask:0xf bound_ctrl:1
	s_nop 1
	v_add_f32_dpp v99, v84, v84 row_ror:1 row_mask:0xf bank_mask:0xf bound_ctrl:1
	v_add_f32_dpp v84, v85, v85 row_ror:8 row_mask:0xf bank_mask:0xf bound_ctrl:1
	v_mul_f32 v85, v121, v108
	v_fma_f32 v86, v99, v101, v86
	v_fma_f32 v86, v96, v89, v86
	v_add_f32_dpp v84, v84, v84 row_ror:4 row_mask:0xf bank_mask:0xf bound_ctrl:1
	s_nop 1
	v_add_f32_dpp v84, v84, v84 row_ror:2 row_mask:0xf bank_mask:0xf bound_ctrl:1
	s_nop 1
	v_add_f32_dpp v104, v84, v84 row_ror:1 row_mask:0xf bank_mask:0xf bound_ctrl:1
	v_mul_f32 v84, v120, v108
	v_fma_f32 v85, v104, v100, v85
	v_fma_f32 v87, v104, v101, v87
	v_fma_f32 v84, v99, v100, v84
	v_fma_f32 v85, v92, v88, v85
	v_fma_f32 v87, v93, v89, v87
	v_mul_f32 v89, v86, v81
	v_fma_f32 v84, v116, v88, v84
	v_mul_f32 v88, v120, v110
	v_mul_f32 v81, v87, v81
	v_fma_f32 v88, v99, v102, v88
	v_fma_f32 v96, v97, v90, v88
	v_mul_f32 v88, v121, v110
	v_fma_f32 v88, v104, v102, v88
	v_fma_f32 v97, v94, v90, v88
	v_mul_f32 v88, v120, v111
	v_fma_f32 v88, v99, v103, v88
	v_fma_f32 v98, v98, v91, v88
	v_mul_f32 v88, v121, v111
	v_fma_f32 v88, v104, v103, v88
	v_fma_f32 v99, v95, v91, v88
	v_mul_f32 v88, v84, v80
	v_mul_f32 v80, v85, v80
	v_fma_f32 v88, v96, v82, v88
	v_fma_f32 v80, v97, v82, v80
	v_fma_f32 v82, v98, v83, v89
	v_fma_f32 v81, v99, v83, v81
	v_add_f32_e32 v82, v88, v82
	v_add_f32_e32 v83, v80, v81
	s_nop 0
	v_add_f32_dpp v80, v82, v82 row_ror:8 row_mask:0xf bank_mask:0xf bound_ctrl:1
	v_add_f32_dpp v82, v83, v83 row_ror:8 row_mask:0xf bank_mask:0xf bound_ctrl:1
	s_nop 0
	v_add_f32_dpp v80, v80, v80 row_ror:4 row_mask:0xf bank_mask:0xf bound_ctrl:1
	v_add_f32_dpp v82, v82, v82 row_ror:4 row_mask:0xf bank_mask:0xf bound_ctrl:1
	s_nop 0
	v_add_f32_dpp v80, v80, v80 row_ror:2 row_mask:0xf bank_mask:0xf bound_ctrl:1
	v_add_f32_dpp v82, v82, v82 row_ror:2 row_mask:0xf bank_mask:0xf bound_ctrl:1
	s_nop 0
	v_add_f32_dpp v80, v80, v80 row_ror:1 row_mask:0xf bank_mask:0xf bound_ctrl:1
	v_add_f32_dpp v82, v82, v82 row_ror:1 row_mask:0xf bank_mask:0xf bound_ctrl:1
	ds_write2_b32 v186, v80, v82 offset0:224 offset1:240
	s_and_saveexec_b64 s[8:9], s[38:39]
	s_cbranch_execz .LBB0_453
	v_add_f32_e32 v88, v0, v76
	v_min_f32_e32 v92, 0, v88
	v_mul_f32_e64 v88, |v88|, s62
	v_exp_f32_e32 v88, v88
	v_add_f32_e32 v89, v1, v77
	v_add_f32_e32 v90, v2, v78
	v_add_f32_e32 v91, v3, v79
	v_add_f32_e32 v88, 1.0, v88
	v_cmp_gt_f32_e32 vcc, s5, v88
	s_mov_b32 s4, 0xf800000
	v_add_f32_e32 v80, v4, v72
	v_cndmask_b32_e64 v93, 0, 32, vcc
	v_ldexp_f32 v88, v88, v93
	v_log_f32_e32 v88, v88
	v_mul_f32_e32 v80, 0xbfb8aa3b, v80
	v_exp_f32_e32 v82, v80
	v_add_f32_e32 v80, v5, v73
	v_mul_f32_e32 v93, 0x3f317217, v88
	v_fma_f32 v93, v88, s76, -v93
	v_fmac_f32_e32 v93, 0x3377d1cf, v88
	v_fmac_f32_e32 v93, 0x3f317217, v88
	v_cmp_lt_f32_e64 s[42:43], |v88|, s77
	v_mul_f32_e32 v80, 0xbfb8aa3b, v80
	v_exp_f32_e32 v83, v80
	v_cndmask_b32_e64 v88, v88, v93, s[42:43]
	v_cndmask_b32_e32 v93, 0, v171, vcc
	v_sub_f32_e32 v88, v88, v93
	v_sub_f32_e32 v88, v92, v88
	v_min_f32_e32 v92, 0, v89
	v_mul_f32_e64 v89, |v89|, s62
	v_exp_f32_e32 v89, v89
	v_add_f32_e32 v88, -0.5, v88
	v_mul_f32_e32 v88, 0x3fb8aa3b, v88
	v_exp_f32_e32 v88, v88
	v_add_f32_e32 v89, 1.0, v89
	v_cmp_gt_f32_e32 vcc, s5, v89
	v_pk_add_f32 v[82:83], v[82:83], 1.0 op_sel_hi:[1,0]
	v_mul_f32_e32 v88, 0xbfb8aa3b, v88
	v_cndmask_b32_e64 v93, 0, 32, vcc
	v_ldexp_f32 v89, v89, v93
	v_log_f32_e32 v89, v89
	v_exp_f32_e32 v88, v88
	v_add_f32_e32 v80, v6, v74
	v_add_f32_e32 v81, v7, v75
	v_mul_f32_e32 v93, 0x3f317217, v89
	v_fma_f32 v93, v89, s76, -v93
	v_fmac_f32_e32 v93, 0x3377d1cf, v89
	v_fmac_f32_e32 v93, 0x3f317217, v89
	v_cmp_lt_f32_e64 s[42:43], |v89|, s77
	v_mul_f32_e32 v80, 0xbfb8aa3b, v80
	v_mul_f32_e32 v81, 0xbfb8aa3b, v81
	v_cndmask_b32_e64 v89, v89, v93, s[42:43]
	v_cndmask_b32_e32 v93, 0, v171, vcc
	v_sub_f32_e32 v89, v89, v93
	v_sub_f32_e32 v89, v92, v89
	v_min_f32_e32 v92, 0, v90
	v_mul_f32_e64 v90, |v90|, s62
	v_exp_f32_e32 v90, v90
	v_add_f32_e32 v89, -0.5, v89
	v_mul_f32_e32 v89, 0x3fb8aa3b, v89
	v_exp_f32_e32 v89, v89
	v_add_f32_e32 v90, 1.0, v90
	v_cmp_gt_f32_e32 vcc, s5, v90
	v_exp_f32_e32 v80, v80
	v_mul_f32_e32 v89, 0xbfb8aa3b, v89
	v_cndmask_b32_e64 v93, 0, 32, vcc
	v_ldexp_f32 v90, v90, v93
	v_log_f32_e32 v90, v90
	v_exp_f32_e32 v89, v89
	v_exp_f32_e32 v81, v81
	v_mul_f32_e32 v93, 0x3f317217, v90
	v_fma_f32 v93, v90, s76, -v93
	v_fmac_f32_e32 v93, 0x3377d1cf, v90
	v_fmac_f32_e32 v93, 0x3f317217, v90
	v_cmp_lt_f32_e64 s[42:43], |v90|, s77
	v_pk_add_f32 v[80:81], v[80:81], 1.0 op_sel_hi:[1,0]
	s_nop 0
	v_cndmask_b32_e64 v90, v90, v93, s[42:43]
	v_cndmask_b32_e32 v93, 0, v171, vcc
	v_sub_f32_e32 v90, v90, v93
	v_sub_f32_e32 v90, v92, v90
	v_min_f32_e32 v92, 0, v91
	v_mul_f32_e64 v91, |v91|, s62
	v_exp_f32_e32 v91, v91
	v_add_f32_e32 v90, -0.5, v90
	v_mul_f32_e32 v90, 0x3fb8aa3b, v90
	v_exp_f32_e32 v90, v90
	v_add_f32_e32 v91, 1.0, v91
	v_cmp_gt_f32_e32 vcc, s5, v91
	v_mul_f32_e32 v90, 0xbfb8aa3b, v90
	s_nop 0
	v_cndmask_b32_e64 v93, 0, 32, vcc
	v_ldexp_f32 v91, v91, v93
	v_log_f32_e32 v91, v91
	v_exp_f32_e32 v90, v90
	v_mul_f32_e32 v93, 0x3f317217, v91
	v_fma_f32 v93, v91, s76, -v93
	v_fmac_f32_e32 v93, 0x3377d1cf, v91
	v_fmac_f32_e32 v93, 0x3f317217, v91
	v_cmp_lt_f32_e64 s[42:43], |v91|, s77
	s_nop 1
	v_cndmask_b32_e64 v91, v91, v93, s[42:43]
	v_cndmask_b32_e32 v93, 0, v171, vcc
	v_sub_f32_e32 v91, v91, v93
	v_sub_f32_e32 v91, v92, v91
	v_add_f32_e32 v91, -0.5, v91
	v_mul_f32_e32 v91, 0x3fb8aa3b, v91
	v_exp_f32_e32 v91, v91
	v_pk_mul_f32 v[92:93], v[10:11], v[70:71]
	v_mul_f32_e32 v91, 0xbfb8aa3b, v91
	v_exp_f32_e32 v91, v91
	v_pk_mul_f32 v[94:95], v[92:93], v[92:93]
	ds_write_b128 v181, v[88:91] offset:22528
	v_pk_mul_f32 v[88:89], v[8:9], v[68:69]
	v_pk_mul_f32 v[90:91], v[88:89], v[88:89]
	v_add_f32_e32 v90, v91, v90
	v_add_f32_e32 v90, v94, v90
	v_add_f32_e32 v90, v95, v90
	s_nop 1
	v_add_f32_dpp v90, v90, v90 row_ror:8 row_mask:0xf bank_mask:0xf bound_ctrl:1
	s_nop 1
	v_add_f32_dpp v90, v90, v90 row_ror:4 row_mask:0xf bank_mask:0xf bound_ctrl:1
	s_nop 1
	v_add_f32_dpp v90, v90, v90 row_ror:2 row_mask:0xf bank_mask:0xf bound_ctrl:1
	s_nop 1
	v_add_f32_dpp v90, v90, v90 row_ror:1 row_mask:0xf bank_mask:0xf bound_ctrl:1
	v_cmp_gt_f32_e32 vcc, s4, v90
	v_mul_f32_e32 v91, 0x4f800000, v90
	s_nop 0
	v_cndmask_b32_e32 v90, v90, v91, vcc
	v_sqrt_f32_e32 v91, v90
	s_nop 0
	v_add_u32_e32 v94, -1, v91
	v_fma_f32 v95, -v94, v91, v90
	v_cmp_ge_f32_e64 s[42:43], 0, v95
	v_add_u32_e32 v95, 1, v91
	s_nop 0
	v_cndmask_b32_e64 v94, v91, v94, s[42:43]
	v_fma_f32 v91, -v95, v91, v90
	v_cmp_lt_f32_e64 s[42:43], 0, v91
	s_nop 1
	v_cndmask_b32_e64 v91, v94, v95, s[42:43]
	v_mul_f32_e32 v94, 0x37800000, v91
	v_cndmask_b32_e32 v91, v91, v94, vcc
	v_cmp_class_f32_e32 vcc, v90, v160
	s_nop 1
	v_cndmask_b32_e32 v90, v91, v90, vcc
	v_max_f32_e32 v90, 0x2b8cbccc, v90
	v_div_scale_f32 v91, s[22:23], v90, v90, 1.0
	v_rcp_f32_e32 v94, v91
	s_nop 0
	v_fma_f32 v95, -v91, v94, 1.0
	v_fmac_f32_e32 v94, v95, v94
	v_div_scale_f32 v95, vcc, 1.0, v90, 1.0
	v_mul_f32_e32 v100, v95, v94
	v_fma_f32 v101, -v91, v100, v95
	v_fmac_f32_e32 v100, v101, v94
	v_fma_f32 v91, -v91, v100, v95
	v_div_fmas_f32 v91, v91, v94, v100
	v_div_fixup_f32 v90, v91, v90, 1.0
	v_pk_mul_f32 v[94:95], v[88:89], v[90:91] op_sel_hi:[1,0]
	v_pk_mul_f32 v[92:93], v[92:93], v[90:91] op_sel_hi:[1,0]
	v_xor_b32_e32 v89, 0x80000000, v95
	v_xor_b32_e32 v88, 0x80000000, v94
	v_xor_b32_e32 v91, 0x80000000, v93
	v_xor_b32_e32 v90, 0x80000000, v92
	ds_write_b128 v181, v[88:91] offset:26624
	v_div_scale_f32 v88, s[22:23], v83, v83, 1.0
	v_rcp_f32_e32 v89, v88
	s_nop 0
	v_fma_f32 v90, -v88, v89, 1.0
	v_fmac_f32_e32 v89, v90, v89
	v_div_scale_f32 v90, vcc, 1.0, v83, 1.0
	v_mul_f32_e32 v91, v90, v89
	v_fma_f32 v100, -v88, v91, v90
	v_fmac_f32_e32 v91, v100, v89
	v_fma_f32 v88, -v88, v91, v90
	v_div_fmas_f32 v88, v88, v89, v91
	v_div_fixup_f32 v83, v88, v83, 1.0
	v_div_scale_f32 v88, s[22:23], v82, v82, 1.0
	v_rcp_f32_e32 v89, v88
	s_nop 0
	v_fma_f32 v90, -v88, v89, 1.0
	v_fmac_f32_e32 v89, v90, v89
	v_div_scale_f32 v90, vcc, 1.0, v82, 1.0
	v_mul_f32_e32 v91, v90, v89
	v_fma_f32 v100, -v88, v91, v90
	v_fmac_f32_e32 v91, v100, v89
	v_fma_f32 v88, -v88, v91, v90
	v_div_scale_f32 v90, s[22:23], v81, v81, 1.0
	v_div_fmas_f32 v88, v88, v89, v91
	v_rcp_f32_e32 v91, v90
	v_div_fixup_f32 v82, v88, v82, 1.0
	v_pk_mul_f32 v[88:89], v[82:83], v[94:95]
	v_fma_f32 v94, -v90, v91, 1.0
	v_fmac_f32_e32 v91, v94, v91
	v_div_scale_f32 v94, vcc, 1.0, v81, 1.0
	v_mul_f32_e32 v95, v94, v91
	v_fma_f32 v100, -v90, v95, v94
	v_fmac_f32_e32 v95, v100, v91
	v_fma_f32 v90, -v90, v95, v94
	v_div_fmas_f32 v90, v90, v91, v95
	v_div_fixup_f32 v95, v90, v81, 1.0
	v_div_scale_f32 v81, s[22:23], v80, v80, 1.0
	v_rcp_f32_e32 v90, v81
	s_nop 0
	v_fma_f32 v91, -v81, v90, 1.0
	v_fmac_f32_e32 v90, v91, v90
	v_div_scale_f32 v91, vcc, 1.0, v80, 1.0
	v_mul_f32_e32 v94, v91, v90
	v_fma_f32 v100, -v81, v94, v91
	v_fmac_f32_e32 v94, v100, v90
	v_fma_f32 v81, -v81, v94, v91
	v_div_fmas_f32 v81, v81, v90, v94
	v_div_fixup_f32 v94, v81, v80, 1.0
	v_pk_add_f32 v[80:81], v[82:83], -1.0 op_sel_hi:[1,0]
	v_pk_add_f32 v[82:83], v[94:95], -1.0 op_sel_hi:[1,0]
	v_pk_fma_f32 v[80:81], v[12:13], v[80:81], 1.0 op_sel_hi:[1,1,0]
	v_pk_fma_f32 v[82:83], v[14:15], v[82:83], 1.0 op_sel_hi:[1,1,0]
	v_pk_mul_f32 v[90:91], v[94:95], v[92:93]
	v_pk_mul_f32 v[80:81], v[68:69], v[80:81]
	v_pk_mul_f32 v[82:83], v[70:71], v[82:83]
	ds_write_b128 v181, v[88:91] offset:30720
	ds_write_b128 v181, v[80:83] offset:34816
	ds_write_b128 v181, v[48:51] offset:38912

.LBB0_457:
	ds_read2st64_b32 v[80:81], v179 offset0:176 offset1:180
	v_add_u32_e32 v82, 32, v126
	v_ashrrev_i32_e32 v83, 31, v82
	v_lshlrev_b64 v[82:83], 13, v[82:83]
	v_lshl_add_u64 v[82:83], v[144:145], 0, v[82:83]
	s_waitcnt lgkmcnt(0)
	global_store_dword v[82:83], v80, off
	v_add_u32_e32 v82, 32, v124
	v_ashrrev_i32_e32 v83, 31, v82
	v_lshlrev_b64 v[82:83], 13, v[82:83]
	v_lshl_add_u64 v[82:83], v[144:145], 0, v[82:83]
	global_store_dword v[82:83], v81, off
	ds_read_b128 v[104:107], v134 offset:22528
	ds_read_b128 v[88:91], v134 offset:22784
	ds_read_b128 v[108:111], v134 offset:26624
	ds_read_b128 v[112:115], v134 offset:26880
	ds_read_b128 v[116:119], v134 offset:30720
	ds_read_b128 v[92:95], v134 offset:30976
	ds_read_b128 v[148:151], v134 offset:34816
	ds_read_b128 v[100:103], v134 offset:35072
	ds_read_b128 v[192:195], v134 offset:38912
	ds_read_b128 v[80:83], v134 offset:39168
	ds_read2_b32 v[120:121], v190 offset0:32 offset1:48
	s_waitcnt lgkmcnt(8)
	v_mul_f32 v122, v84, v108
	v_mul_f32 v108, v85, v108
	v_mul_f32 v123, v86, v109
	v_mul_f32 v109, v87, v109
	v_fma_f32 v122, v96, v110, v122
	v_fma_f32 v108, v97, v110, v108
	v_fma_f32 v110, v98, v111, v123
	v_fma_f32 v109, v99, v111, v109
	v_add_f32_e32 v110, v122, v110
	v_add_f32_e32 v111, v108, v109
	s_nop 0
	v_add_f32_dpp v110, v110, v110 row_ror:8 row_mask:0xf bank_mask:0xf bound_ctrl:1
	ds_read2_b32 v[108:109], v190 offset1:16
	v_add_f32_dpp v111, v111, v111 row_ror:8 row_mask:0xf bank_mask:0xf bound_ctrl:1
	v_add_f32_dpp v110, v110, v110 row_ror:4 row_mask:0xf bank_mask:0xf bound_ctrl:1
	s_waitcnt lgkmcnt(0)
	v_mul_f32 v122, v108, v148
	v_add_f32_dpp v111, v111, v111 row_ror:4 row_mask:0xf bank_mask:0xf bound_ctrl:1
	v_add_f32_dpp v110, v110, v110 row_ror:2 row_mask:0xf bank_mask:0xf bound_ctrl:1
	s_nop 0
	v_add_f32_dpp v111, v111, v111 row_ror:2 row_mask:0xf bank_mask:0xf bound_ctrl:1
	v_add_f32_dpp v110, v110, v110 row_ror:1 row_mask:0xf bank_mask:0xf bound_ctrl:1
	v_fma_f32 v122, v110, v116, v122
	v_fma_f32 v122, v84, v104, v122
	v_mul_f32 v84, v109, v148
	v_add_f32_dpp v111, v111, v111 row_ror:1 row_mask:0xf bank_mask:0xf bound_ctrl:1
	v_fma_f32 v84, v111, v116, v84
	v_fma_f32 v123, v85, v104, v84
	v_mul_f32 v84, v108, v149
	v_fma_f32 v84, v110, v117, v84
	v_mul_f32 v85, v123, v192
	v_fma_f32 v126, v86, v105, v84
	v_mul_f32 v84, v109, v149
	v_fma_f32 v84, v111, v117, v84
	v_mul_f32 v86, v126, v193
	v_fma_f32 v127, v87, v105, v84
	v_mul_f32 v84, v108, v150
	v_fma_f32 v84, v110, v118, v84
	v_mul_f32 v87, v127, v193
	v_fma_f32 v141, v96, v106, v84
	v_mul_f32 v84, v109, v150
	v_fma_f32 v84, v111, v118, v84
	v_fma_f32 v148, v97, v106, v84
	v_mul_f32 v84, v108, v151
	v_fma_f32 v84, v110, v119, v84
	v_fma_f32 v85, v148, v194, v85
	v_fma_f32 v149, v98, v107, v84
	v_mul_f32 v84, v109, v151
	v_fma_f32 v84, v111, v119, v84
	v_fma_f32 v86, v149, v195, v86
	v_fma_f32 v150, v99, v107, v84
	v_mul_f32 v84, v122, v192
	v_fma_f32 v84, v141, v194, v84
	v_fma_f32 v87, v150, v195, v87
	v_add_f32_e32 v84, v84, v86
	v_add_f32_e32 v86, v85, v87
	s_nop 0
	v_add_f32_dpp v84, v84, v84 row_ror:8 row_mask:0xf bank_mask:0xf bound_ctrl:1
	v_add_f32_dpp v86, v86, v86 row_ror:8 row_mask:0xf bank_mask:0xf bound_ctrl:1
	s_nop 0
	v_add_f32_dpp v84, v84, v84 row_ror:4 row_mask:0xf bank_mask:0xf bound_ctrl:1
	v_add_f32_dpp v86, v86, v86 row_ror:4 row_mask:0xf bank_mask:0xf bound_ctrl:1
	s_nop 0
	v_add_f32_dpp v84, v84, v84 row_ror:2 row_mask:0xf bank_mask:0xf bound_ctrl:1
	v_add_f32_dpp v86, v86, v86 row_ror:2 row_mask:0xf bank_mask:0xf bound_ctrl:1
	s_nop 0
	v_add_f32_dpp v84, v84, v84 row_ror:1 row_mask:0xf bank_mask:0xf bound_ctrl:1
	v_add_f32_dpp v86, v86, v86 row_ror:1 row_mask:0xf bank_mask:0xf bound_ctrl:1
	ds_write2_b32 v188, v84, v86 offset1:16
	v_mul_f32 v151, v122, v112
	v_mul_f32 v112, v123, v112
	v_mul_f32 v185, v126, v113
	v_mul_f32 v113, v127, v113
	ds_read_b128 v[96:99], v134 offset:23040
	ds_read_b128 v[116:119], v134 offset:27136
	ds_read_b128 v[104:107], v134 offset:31232
	ds_read_b128 v[108:111], v134 offset:35328
	ds_read_b128 v[84:87], v134 offset:39424
	ds_read2_b32 v[124:125], v190 offset0:64 offset1:80
	v_fma_f32 v151, v141, v114, v151
	v_fma_f32 v112, v148, v114, v112
	v_fma_f32 v114, v149, v115, v185
	v_fma_f32 v113, v150, v115, v113
	v_add_f32_e32 v114, v151, v114
	v_add_f32_e32 v112, v112, v113
	s_nop 0
	v_add_f32_dpp v113, v114, v114 row_ror:8 row_mask:0xf bank_mask:0xf bound_ctrl:1
	v_add_f32_dpp v112, v112, v112 row_ror:8 row_mask:0xf bank_mask:0xf bound_ctrl:1
	v_mul_f32 v114, v120, v100
	v_mul_f32 v100, v121, v100
	v_add_f32_dpp v113, v113, v113 row_ror:4 row_mask:0xf bank_mask:0xf bound_ctrl:1
	v_add_f32_dpp v112, v112, v112 row_ror:4 row_mask:0xf bank_mask:0xf bound_ctrl:1
	s_nop 0
	v_add_f32_dpp v113, v113, v113 row_ror:2 row_mask:0xf bank_mask:0xf bound_ctrl:1
	v_add_f32_dpp v112, v112, v112 row_ror:2 row_mask:0xf bank_mask:0xf bound_ctrl:1
	s_nop 0
	v_add_f32_dpp v113, v113, v113 row_ror:1 row_mask:0xf bank_mask:0xf bound_ctrl:1
	v_add_f32_dpp v112, v112, v112 row_ror:1 row_mask:0xf bank_mask:0xf bound_ctrl:1
	v_fma_f32 v114, v113, v92, v114
	v_fma_f32 v92, v112, v92, v100
	v_fma_f32 v151, v122, v88, v114
	v_fma_f32 v92, v123, v88, v92
	v_mul_f32 v88, v120, v101
	v_fma_f32 v88, v113, v93, v88
	v_fma_f32 v185, v126, v89, v88
	v_mul_f32 v88, v121, v101
	v_fma_f32 v88, v112, v93, v88
	v_fma_f32 v93, v127, v89, v88
	v_mul_f32 v88, v120, v102
	v_mul_f32 v89, v185, v81
	v_fma_f32 v88, v113, v94, v88
	v_mul_f32 v81, v93, v81
	v_fma_f32 v141, v141, v90, v88
	v_mul_f32 v88, v121, v102
	v_fma_f32 v88, v112, v94, v88
	v_fma_f32 v94, v148, v90, v88
	v_mul_f32 v88, v120, v103
	v_fma_f32 v88, v113, v95, v88
	v_fma_f32 v148, v149, v91, v88
	v_mul_f32 v88, v121, v103
	v_fma_f32 v88, v112, v95, v88
	v_fma_f32 v95, v150, v91, v88
	v_mul_f32 v88, v151, v80
	v_mul_f32 v80, v92, v80
	v_fma_f32 v88, v141, v82, v88
	v_fma_f32 v80, v94, v82, v80
	v_fma_f32 v82, v148, v83, v89
	v_fma_f32 v81, v95, v83, v81
	v_add_f32_e32 v82, v88, v82
	v_add_f32_e32 v83, v80, v81
	s_nop 0
	v_add_f32_dpp v80, v82, v82 row_ror:8 row_mask:0xf bank_mask:0xf bound_ctrl:1
	v_add_f32_dpp v82, v83, v83 row_ror:8 row_mask:0xf bank_mask:0xf bound_ctrl:1
	s_nop 0
	v_add_f32_dpp v80, v80, v80 row_ror:4 row_mask:0xf bank_mask:0xf bound_ctrl:1
	v_add_f32_dpp v82, v82, v82 row_ror:4 row_mask:0xf bank_mask:0xf bound_ctrl:1
	s_nop 0
	v_add_f32_dpp v80, v80, v80 row_ror:2 row_mask:0xf bank_mask:0xf bound_ctrl:1
	v_add_f32_dpp v82, v82, v82 row_ror:2 row_mask:0xf bank_mask:0xf bound_ctrl:1
	s_nop 0
	v_add_f32_dpp v80, v80, v80 row_ror:1 row_mask:0xf bank_mask:0xf bound_ctrl:1
	v_add_f32_dpp v82, v82, v82 row_ror:1 row_mask:0xf bank_mask:0xf bound_ctrl:1
	ds_write2_b32 v188, v80, v82 offset0:32 offset1:48
	s_waitcnt lgkmcnt(4)
	v_mul_f32 v149, v151, v116
	v_mul_f32 v116, v92, v116
	v_mul_f32 v150, v185, v117
	v_mul_f32 v117, v93, v117
	ds_read_b128 v[88:91], v134 offset:23296
	ds_read_b128 v[120:123], v134 offset:27392
	ds_read_b128 v[100:103], v134 offset:31488
	ds_read_b128 v[112:115], v134 offset:35584
	ds_read_b128 v[80:83], v134 offset:39680
	ds_read2_b32 v[126:127], v190 offset0:96 offset1:112
	v_fma_f32 v149, v141, v118, v149
	v_fma_f32 v116, v94, v118, v116
	v_fma_f32 v118, v148, v119, v150
	v_fma_f32 v117, v95, v119, v117
	v_add_f32_e32 v118, v149, v118
	v_add_f32_e32 v116, v116, v117
	s_nop 0
	v_add_f32_dpp v117, v118, v118 row_ror:8 row_mask:0xf bank_mask:0xf bound_ctrl:1
	v_add_f32_dpp v116, v116, v116 row_ror:8 row_mask:0xf bank_mask:0xf bound_ctrl:1
	s_waitcnt lgkmcnt(6)
	v_mul_f32 v118, v124, v108
	v_mul_f32 v108, v125, v108
	v_add_f32_dpp v117, v117, v117 row_ror:4 row_mask:0xf bank_mask:0xf bound_ctrl:1
	v_add_f32_dpp v116, v116, v116 row_ror:4 row_mask:0xf bank_mask:0xf bound_ctrl:1
	s_nop 0
	v_add_f32_dpp v117, v117, v117 row_ror:2 row_mask:0xf bank_mask:0xf bound_ctrl:1
	v_add_f32_dpp v116, v116, v116 row_ror:2 row_mask:0xf bank_mask:0xf bound_ctrl:1
	s_nop 0
	v_add_f32_dpp v117, v117, v117 row_ror:1 row_mask:0xf bank_mask:0xf bound_ctrl:1
	v_add_f32_dpp v116, v116, v116 row_ror:1 row_mask:0xf bank_mask:0xf bound_ctrl:1
	v_fma_f32 v118, v117, v104, v118
	v_fma_f32 v104, v116, v104, v108
	v_fma_f32 v108, v92, v96, v104
	v_mul_f32 v92, v124, v109
	v_fma_f32 v149, v151, v96, v118
	v_fma_f32 v92, v117, v105, v92
	v_fma_f32 v150, v185, v97, v92
	v_mul_f32 v92, v125, v109
	v_fma_f32 v92, v116, v105, v92
	v_fma_f32 v109, v93, v97, v92
	v_mul_f32 v92, v124, v110
	v_mul_f32 v93, v150, v85
	v_fma_f32 v92, v117, v106, v92
	v_mul_f32 v85, v109, v85
	v_fma_f32 v141, v141, v98, v92
	v_mul_f32 v92, v125, v110
	v_fma_f32 v92, v116, v106, v92
	v_fma_f32 v110, v94, v98, v92
	v_mul_f32 v92, v124, v111
	v_fma_f32 v92, v117, v107, v92
	v_fma_f32 v148, v148, v99, v92
	v_mul_f32 v92, v125, v111
	v_fma_f32 v92, v116, v107, v92
	v_fma_f32 v111, v95, v99, v92
	v_mul_f32 v92, v149, v84
	v_mul_f32 v84, v108, v84
	v_fma_f32 v92, v141, v86, v92
	v_fma_f32 v84, v110, v86, v84
	v_fma_f32 v86, v148, v87, v93
	v_fma_f32 v85, v111, v87, v85
	v_add_f32_e32 v86, v92, v86
	v_add_f32_e32 v87, v84, v85
	s_nop 0
	v_add_f32_dpp v84, v86, v86 row_ror:8 row_mask:0xf bank_mask:0xf bound_ctrl:1
	v_add_f32_dpp v86, v87, v87 row_ror:8 row_mask:0xf bank_mask:0xf bound_ctrl:1
	s_nop 0
	v_add_f32_dpp v84, v84, v84 row_ror:4 row_mask:0xf bank_mask:0xf bound_ctrl:1
	v_add_f32_dpp v86, v86, v86 row_ror:4 row_mask:0xf bank_mask:0xf bound_ctrl:1
	s_nop 0
	v_add_f32_dpp v84, v84, v84 row_ror:2 row_mask:0xf bank_mask:0xf bound_ctrl:1
	v_add_f32_dpp v86, v86, v86 row_ror:2 row_mask:0xf bank_mask:0xf bound_ctrl:1
	s_nop 0
	v_add_f32_dpp v84, v84, v84 row_ror:1 row_mask:0xf bank_mask:0xf bound_ctrl:1
	v_add_f32_dpp v86, v86, v86 row_ror:1 row_mask:0xf bank_mask:0xf bound_ctrl:1
	ds_write2_b32 v188, v84, v86 offset0:64 offset1:80
	s_waitcnt lgkmcnt(4)
	v_mul_f32 v151, v149, v120
	v_mul_f32 v120, v108, v120
	v_mul_f32 v185, v150, v121
	v_mul_f32 v121, v109, v121
	ds_read_b128 v[92:95], v134 offset:23552
	ds_read_b128 v[116:119], v134 offset:27648
	ds_read_b128 v[96:99], v134 offset:31744
	ds_read_b128 v[104:107], v134 offset:35840
	ds_read_b128 v[84:87], v134 offset:39936
	ds_read2_b32 v[124:125], v190 offset0:128 offset1:144
	v_fma_f32 v120, v110, v122, v120
	v_fma_f32 v151, v141, v122, v151
	v_fma_f32 v122, v148, v123, v185
	v_fma_f32 v121, v111, v123, v121
	v_add_f32_e32 v122, v151, v122
	v_add_f32_e32 v120, v120, v121
	s_nop 1
	v_add_f32_dpp v120, v120, v120 row_ror:8 row_mask:0xf bank_mask:0xf bound_ctrl:1
	v_add_f32_dpp v121, v122, v122 row_ror:8 row_mask:0xf bank_mask:0xf bound_ctrl:1
	s_nop 0
	v_add_f32_dpp v120, v120, v120 row_ror:4 row_mask:0xf bank_mask:0xf bound_ctrl:1
	v_add_f32_dpp v121, v121, v121 row_ror:4 row_mask:0xf bank_mask:0xf bound_ctrl:1
	s_nop 0
	v_add_f32_dpp v120, v120, v120 row_ror:2 row_mask:0xf bank_mask:0xf bound_ctrl:1
	v_add_f32_dpp v121, v121, v121 row_ror:2 row_mask:0xf bank_mask:0xf bound_ctrl:1
	s_nop 0
	v_add_f32_dpp v185, v120, v120 row_ror:1 row_mask:0xf bank_mask:0xf bound_ctrl:1
	s_waitcnt lgkmcnt(6)
	v_mul_f32 v120, v126, v112
	v_add_f32_dpp v151, v121, v121 row_ror:1 row_mask:0xf bank_mask:0xf bound_ctrl:1
	v_fma_f32 v120, v151, v100, v120
	v_mul_f32 v112, v127, v112
	v_fma_f32 v120, v149, v88, v120
	v_fma_f32 v100, v185, v100, v112
	v_fma_f32 v121, v108, v88, v100
	v_mul_f32 v88, v126, v113
	v_fma_f32 v88, v151, v101, v88
	v_fma_f32 v122, v150, v89, v88
	v_mul_f32 v88, v127, v113
	v_fma_f32 v88, v185, v101, v88
	v_fma_f32 v123, v109, v89, v88
	v_mul_f32 v88, v126, v114
	v_mul_f32 v89, v122, v81
	v_fma_f32 v88, v151, v102, v88
	v_mul_f32 v81, v123, v81
	v_fma_f32 v141, v141, v90, v88
	v_mul_f32 v88, v127, v114
	v_fma_f32 v88, v185, v102, v88
	v_fma_f32 v149, v110, v90, v88
	v_mul_f32 v88, v126, v115
	v_fma_f32 v88, v151, v103, v88
	v_fma_f32 v148, v148, v91, v88
	v_mul_f32 v88, v127, v115
	v_fma_f32 v88, v185, v103, v88
	v_fma_f32 v150, v111, v91, v88
	v_mul_f32 v88, v120, v80
	v_mul_f32 v80, v121, v80
	v_fma_f32 v88, v141, v82, v88
	v_fma_f32 v80, v149, v82, v80
	v_fma_f32 v82, v148, v83, v89
	v_fma_f32 v81, v150, v83, v81
	v_add_f32_e32 v82, v88, v82
	v_add_f32_e32 v83, v80, v81
	s_nop 0
	v_add_f32_dpp v80, v82, v82 row_ror:8 row_mask:0xf bank_mask:0xf bound_ctrl:1
	v_add_f32_dpp v82, v83, v83 row_ror:8 row_mask:0xf bank_mask:0xf bound_ctrl:1
	s_nop 0
	v_add_f32_dpp v80, v80, v80 row_ror:4 row_mask:0xf bank_mask:0xf bound_ctrl:1
	v_add_f32_dpp v82, v82, v82 row_ror:4 row_mask:0xf bank_mask:0xf bound_ctrl:1
	s_nop 0
	v_add_f32_dpp v80, v80, v80 row_ror:2 row_mask:0xf bank_mask:0xf bound_ctrl:1
	v_add_f32_dpp v82, v82, v82 row_ror:2 row_mask:0xf bank_mask:0xf bound_ctrl:1
	s_nop 0
	v_add_f32_dpp v80, v80, v80 row_ror:1 row_mask:0xf bank_mask:0xf bound_ctrl:1
	v_add_f32_dpp v82, v82, v82 row_ror:1 row_mask:0xf bank_mask:0xf bound_ctrl:1
	ds_write2_b32 v188, v80, v82 offset0:96 offset1:112
	s_waitcnt lgkmcnt(4)
	v_mul_f32 v151, v120, v116
	v_mul_f32 v116, v121, v116
	v_mul_f32 v185, v122, v117
	v_mul_f32 v117, v123, v117
	ds_read_b128 v[88:91], v134 offset:23808
	ds_read_b128 v[112:115], v134 offset:27904
	ds_read_b128 v[100:103], v134 offset:32000
	ds_read_b128 v[108:111], v134 offset:36096
	ds_read_b128 v[80:83], v134 offset:40192
	ds_read2_b32 v[126:127], v190 offset0:160 offset1:176
	v_fma_f32 v116, v149, v118, v116
	v_fma_f32 v151, v141, v118, v151
	v_fma_f32 v118, v148, v119, v185
	v_fma_f32 v117, v150, v119, v117
	v_add_f32_e32 v118, v151, v118
	v_add_f32_e32 v116, v116, v117
	s_nop 1
	v_add_f32_dpp v116, v116, v116 row_ror:8 row_mask:0xf bank_mask:0xf bound_ctrl:1
	v_add_f32_dpp v117, v118, v118 row_ror:8 row_mask:0xf bank_mask:0xf bound_ctrl:1
	s_nop 0
	v_add_f32_dpp v116, v116, v116 row_ror:4 row_mask:0xf bank_mask:0xf bound_ctrl:1
	v_add_f32_dpp v117, v117, v117 row_ror:4 row_mask:0xf bank_mask:0xf bound_ctrl:1
	s_nop 0
	v_add_f32_dpp v116, v116, v116 row_ror:2 row_mask:0xf bank_mask:0xf bound_ctrl:1
	v_add_f32_dpp v117, v117, v117 row_ror:2 row_mask:0xf bank_mask:0xf bound_ctrl:1
	s_nop 0
	v_add_f32_dpp v186, v116, v116 row_ror:1 row_mask:0xf bank_mask:0xf bound_ctrl:1
	s_waitcnt lgkmcnt(6)
	v_mul_f32 v116, v124, v104
	v_add_f32_dpp v185, v117, v117 row_ror:1 row_mask:0xf bank_mask:0xf bound_ctrl:1
	v_fma_f32 v116, v185, v96, v116
	v_mul_f32 v104, v125, v104
	v_fma_f32 v116, v120, v92, v116
	v_fma_f32 v96, v186, v96, v104
	v_fma_f32 v117, v121, v92, v96
	v_mul_f32 v92, v124, v105
	v_fma_f32 v92, v185, v97, v92
	v_fma_f32 v118, v122, v93, v92
	v_mul_f32 v92, v125, v105
	v_fma_f32 v92, v186, v97, v92
	v_fma_f32 v119, v123, v93, v92
	v_mul_f32 v92, v124, v106
	v_mul_f32 v93, v118, v85
	v_fma_f32 v92, v185, v98, v92
	v_mul_f32 v85, v119, v85
	v_fma_f32 v141, v141, v94, v92
	v_mul_f32 v92, v125, v106
	v_fma_f32 v92, v186, v98, v92
	v_fma_f32 v151, v149, v94, v92
	v_mul_f32 v92, v124, v107
	v_fma_f32 v92, v185, v99, v92
	v_fma_f32 v124, v148, v95, v92
	v_mul_f32 v92, v125, v107
	v_fma_f32 v92, v186, v99, v92
	v_fma_f32 v125, v150, v95, v92
	v_mul_f32 v92, v116, v84
	v_mul_f32 v84, v117, v84
	v_fma_f32 v92, v141, v86, v92
	v_fma_f32 v84, v151, v86, v84
	v_fma_f32 v86, v124, v87, v93
	v_fma_f32 v85, v125, v87, v85
	v_add_f32_e32 v86, v92, v86
	v_add_f32_e32 v87, v84, v85
	s_nop 0
	v_add_f32_dpp v84, v86, v86 row_ror:8 row_mask:0xf bank_mask:0xf bound_ctrl:1
	v_add_f32_dpp v86, v87, v87 row_ror:8 row_mask:0xf bank_mask:0xf bound_ctrl:1
	s_nop 0
	v_add_f32_dpp v84, v84, v84 row_ror:4 row_mask:0xf bank_mask:0xf bound_ctrl:1
	v_add_f32_dpp v86, v86, v86 row_ror:4 row_mask:0xf bank_mask:0xf bound_ctrl:1
	s_nop 0
	v_add_f32_dpp v84, v84, v84 row_ror:2 row_mask:0xf bank_mask:0xf bound_ctrl:1
	v_add_f32_dpp v86, v86, v86 row_ror:2 row_mask:0xf bank_mask:0xf bound_ctrl:1
	s_nop 0
	v_add_f32_dpp v84, v84, v84 row_ror:1 row_mask:0xf bank_mask:0xf bound_ctrl:1
	v_add_f32_dpp v86, v86, v86 row_ror:1 row_mask:0xf bank_mask:0xf bound_ctrl:1
	ds_write2_b32 v188, v84, v86 offset0:128 offset1:144
	s_waitcnt lgkmcnt(4)
	v_mul_f32 v150, v116, v112
	v_mul_f32 v112, v117, v112
	v_mul_f32 v185, v118, v113
	v_mul_f32 v113, v119, v113
	ds_read_b128 v[92:95], v134 offset:24064
	ds_read_b128 v[120:123], v134 offset:28160
	ds_read_b128 v[96:99], v134 offset:32256
	ds_read_b128 v[104:107], v134 offset:36352
	ds_read_b128 v[84:87], v134 offset:40448
	ds_read2_b32 v[148:149], v190 offset0:192 offset1:208
	v_fma_f32 v112, v151, v114, v112
	v_fma_f32 v150, v141, v114, v150
	v_fma_f32 v114, v124, v115, v185
	v_fma_f32 v113, v125, v115, v113
	v_add_f32_e32 v114, v150, v114
	v_add_f32_e32 v112, v112, v113
	s_nop 1
	v_add_f32_dpp v112, v112, v112 row_ror:8 row_mask:0xf bank_mask:0xf bound_ctrl:1
	v_add_f32_dpp v113, v114, v114 row_ror:8 row_mask:0xf bank_mask:0xf bound_ctrl:1
	s_nop 0
	v_add_f32_dpp v112, v112, v112 row_ror:4 row_mask:0xf bank_mask:0xf bound_ctrl:1
	v_add_f32_dpp v113, v113, v113 row_ror:4 row_mask:0xf bank_mask:0xf bound_ctrl:1
	s_nop 0
	v_add_f32_dpp v112, v112, v112 row_ror:2 row_mask:0xf bank_mask:0xf bound_ctrl:1
	v_add_f32_dpp v113, v113, v113 row_ror:2 row_mask:0xf bank_mask:0xf bound_ctrl:1
	s_nop 0
	v_add_f32_dpp v186, v112, v112 row_ror:1 row_mask:0xf bank_mask:0xf bound_ctrl:1
	s_waitcnt lgkmcnt(6)
	v_mul_f32 v112, v126, v108
	v_add_f32_dpp v185, v113, v113 row_ror:1 row_mask:0xf bank_mask:0xf bound_ctrl:1
	v_fma_f32 v112, v185, v100, v112
	v_mul_f32 v108, v127, v108
	v_fma_f32 v112, v116, v88, v112
	v_fma_f32 v100, v186, v100, v108
	v_fma_f32 v113, v117, v88, v100
	v_mul_f32 v88, v126, v109
	v_fma_f32 v88, v185, v101, v88
	v_fma_f32 v114, v118, v89, v88
	v_mul_f32 v88, v127, v109
	v_fma_f32 v88, v186, v101, v88
	v_fma_f32 v115, v119, v89, v88
	v_mul_f32 v88, v126, v110
	v_mul_f32 v89, v114, v81
	v_fma_f32 v88, v185, v102, v88
	v_mul_f32 v81, v115, v81
	v_fma_f32 v141, v141, v90, v88
	v_mul_f32 v88, v127, v110
	v_fma_f32 v88, v186, v102, v88
	v_fma_f32 v150, v151, v90, v88
	v_mul_f32 v88, v126, v111
	v_fma_f32 v88, v185, v103, v88
	v_fma_f32 v151, v124, v91, v88
	v_mul_f32 v88, v127, v111
	v_fma_f32 v88, v186, v103, v88
	v_fma_f32 v185, v125, v91, v88
	v_mul_f32 v88, v112, v80
	v_mul_f32 v80, v113, v80
	v_fma_f32 v88, v141, v82, v88
	v_fma_f32 v80, v150, v82, v80
	v_fma_f32 v82, v151, v83, v89
	v_fma_f32 v81, v185, v83, v81
	v_add_f32_e32 v82, v88, v82
	v_add_f32_e32 v83, v80, v81
	s_nop 0
	v_add_f32_dpp v80, v82, v82 row_ror:8 row_mask:0xf bank_mask:0xf bound_ctrl:1
	v_add_f32_dpp v82, v83, v83 row_ror:8 row_mask:0xf bank_mask:0xf bound_ctrl:1
	s_nop 0
	v_add_f32_dpp v80, v80, v80 row_ror:4 row_mask:0xf bank_mask:0xf bound_ctrl:1
	v_add_f32_dpp v82, v82, v82 row_ror:4 row_mask:0xf bank_mask:0xf bound_ctrl:1
	s_nop 0
	v_add_f32_dpp v80, v80, v80 row_ror:2 row_mask:0xf bank_mask:0xf bound_ctrl:1
	v_add_f32_dpp v82, v82, v82 row_ror:2 row_mask:0xf bank_mask:0xf bound_ctrl:1
	s_nop 0
	v_add_f32_dpp v80, v80, v80 row_ror:1 row_mask:0xf bank_mask:0xf bound_ctrl:1
	v_add_f32_dpp v82, v82, v82 row_ror:1 row_mask:0xf bank_mask:0xf bound_ctrl:1
	ds_write2_b32 v188, v80, v82 offset0:160 offset1:176
	s_waitcnt lgkmcnt(4)
	v_mul_f32 v126, v112, v120
	v_mul_f32 v120, v113, v120
	v_mul_f32 v127, v114, v121
	v_mul_f32 v121, v115, v121
	ds_read_b128 v[88:91], v134 offset:24320
	ds_read_b128 v[116:119], v134 offset:28416
	ds_read_b128 v[100:103], v134 offset:32512
	ds_read_b128 v[108:111], v134 offset:36608
	ds_read_b128 v[80:83], v134 offset:40704
	ds_read2_b32 v[124:125], v190 offset0:224 offset1:240
	v_fma_f32 v126, v141, v122, v126
	v_fma_f32 v120, v150, v122, v120
	v_fma_f32 v122, v151, v123, v127
	v_fma_f32 v121, v185, v123, v121
	v_add_f32_e32 v122, v126, v122
	v_add_f32_e32 v120, v120, v121
	s_nop 0
	v_add_f32_dpp v121, v122, v122 row_ror:8 row_mask:0xf bank_mask:0xf bound_ctrl:1
	v_add_f32_dpp v120, v120, v120 row_ror:8 row_mask:0xf bank_mask:0xf bound_ctrl:1
	s_waitcnt lgkmcnt(6)
	v_mul_f32 v122, v148, v104
	v_mul_f32 v104, v149, v104
	v_add_f32_dpp v121, v121, v121 row_ror:4 row_mask:0xf bank_mask:0xf bound_ctrl:1
	v_add_f32_dpp v120, v120, v120 row_ror:4 row_mask:0xf bank_mask:0xf bound_ctrl:1
	s_nop 0
	v_add_f32_dpp v121, v121, v121 row_ror:2 row_mask:0xf bank_mask:0xf bound_ctrl:1
	v_add_f32_dpp v120, v120, v120 row_ror:2 row_mask:0xf bank_mask:0xf bound_ctrl:1
	s_nop 0
	v_add_f32_dpp v121, v121, v121 row_ror:1 row_mask:0xf bank_mask:0xf bound_ctrl:1
	v_fma_f32 v122, v121, v96, v122
	v_add_f32_dpp v120, v120, v120 row_ror:1 row_mask:0xf bank_mask:0xf bound_ctrl:1
	v_fma_f32 v122, v112, v92, v122
	v_fma_f32 v96, v120, v96, v104
	v_fma_f32 v123, v113, v92, v96
	v_mul_f32 v92, v148, v105
	v_fma_f32 v92, v121, v97, v92
	v_fma_f32 v126, v114, v93, v92
	v_mul_f32 v92, v149, v105
	v_fma_f32 v92, v120, v97, v92
	v_fma_f32 v127, v115, v93, v92
	v_mul_f32 v92, v148, v106
	v_mul_f32 v93, v126, v85
	v_fma_f32 v92, v121, v98, v92
	v_mul_f32 v85, v127, v85
	v_fma_f32 v141, v141, v94, v92
	v_mul_f32 v92, v149, v106
	v_fma_f32 v92, v120, v98, v92
	v_fma_f32 v150, v150, v94, v92
	v_mul_f32 v92, v148, v107
	v_fma_f32 v92, v121, v99, v92
	v_fma_f32 v148, v151, v95, v92
	v_mul_f32 v92, v149, v107
	v_fma_f32 v92, v120, v99, v92
	v_fma_f32 v149, v185, v95, v92
	v_mul_f32 v92, v122, v84
	v_mul_f32 v84, v123, v84
	v_fma_f32 v92, v141, v86, v92
	v_fma_f32 v84, v150, v86, v84
	v_fma_f32 v86, v148, v87, v93
	v_fma_f32 v85, v149, v87, v85
	v_add_f32_e32 v86, v92, v86
	v_add_f32_e32 v87, v84, v85
	s_nop 0
	v_add_f32_dpp v84, v86, v86 row_ror:8 row_mask:0xf bank_mask:0xf bound_ctrl:1
	v_add_f32_dpp v86, v87, v87 row_ror:8 row_mask:0xf bank_mask:0xf bound_ctrl:1
	s_nop 0
	v_add_f32_dpp v84, v84, v84 row_ror:4 row_mask:0xf bank_mask:0xf bound_ctrl:1
	v_add_f32_dpp v86, v86, v86 row_ror:4 row_mask:0xf bank_mask:0xf bound_ctrl:1
	s_nop 0
	v_add_f32_dpp v84, v84, v84 row_ror:2 row_mask:0xf bank_mask:0xf bound_ctrl:1
	v_add_f32_dpp v86, v86, v86 row_ror:2 row_mask:0xf bank_mask:0xf bound_ctrl:1
	s_nop 0
	v_add_f32_dpp v84, v84, v84 row_ror:1 row_mask:0xf bank_mask:0xf bound_ctrl:1
	v_add_f32_dpp v86, v86, v86 row_ror:1 row_mask:0xf bank_mask:0xf bound_ctrl:1
	ds_write2_b32 v188, v84, v86 offset0:192 offset1:208
	s_waitcnt lgkmcnt(4)
	v_mul_f32 v151, v122, v116
	v_mul_f32 v116, v123, v116
	v_mul_f32 v185, v126, v117
	v_mul_f32 v117, v127, v117
	ds_read_b128 v[112:115], v134 offset:28672
	ds_read_b128 v[96:99], v134 offset:32768
	ds_read_b128 v[104:107], v134 offset:36864
	ds_read_b128 v[92:95], v134 offset:24576
	ds_read_b128 v[84:87], v134 offset:40960
	ds_read2_b32 v[120:121], v152 offset1:16
	v_fma_f32 v151, v141, v118, v151
	v_fma_f32 v116, v150, v118, v116
	v_fma_f32 v118, v148, v119, v185
	v_fma_f32 v117, v149, v119, v117
	v_add_f32_e32 v118, v151, v118
	v_add_f32_e32 v116, v116, v117
	s_nop 0
	v_add_f32_dpp v117, v118, v118 row_ror:8 row_mask:0xf bank_mask:0xf bound_ctrl:1
	v_add_f32_dpp v116, v116, v116 row_ror:8 row_mask:0xf bank_mask:0xf bound_ctrl:1
	s_waitcnt lgkmcnt(6)
	v_mul_f32 v118, v124, v108
	v_mul_f32 v108, v125, v108
	v_add_f32_dpp v117, v117, v117 row_ror:4 row_mask:0xf bank_mask:0xf bound_ctrl:1
	v_add_f32_dpp v116, v116, v116 row_ror:4 row_mask:0xf bank_mask:0xf bound_ctrl:1
	s_nop 0
	v_add_f32_dpp v117, v117, v117 row_ror:2 row_mask:0xf bank_mask:0xf bound_ctrl:1
	v_add_f32_dpp v116, v116, v116 row_ror:2 row_mask:0xf bank_mask:0xf bound_ctrl:1
	s_nop 0
	v_add_f32_dpp v117, v117, v117 row_ror:1 row_mask:0xf bank_mask:0xf bound_ctrl:1
	v_add_f32_dpp v116, v116, v116 row_ror:1 row_mask:0xf bank_mask:0xf bound_ctrl:1
	v_fma_f32 v118, v117, v100, v118
	v_fma_f32 v100, v116, v100, v108
	v_fma_f32 v151, v122, v88, v118
	v_fma_f32 v185, v123, v88, v100
	v_mul_f32 v88, v124, v109
	v_fma_f32 v88, v117, v101, v88
	v_fma_f32 v126, v126, v89, v88
	v_mul_f32 v88, v125, v109
	v_fma_f32 v88, v116, v101, v88
	v_fma_f32 v127, v127, v89, v88
	v_mul_f32 v88, v124, v110
	v_mul_f32 v89, v126, v81
	v_fma_f32 v88, v117, v102, v88
	v_mul_f32 v81, v127, v81
	v_fma_f32 v141, v141, v90, v88
	v_mul_f32 v88, v125, v110
	v_fma_f32 v88, v116, v102, v88
	v_fma_f32 v150, v150, v90, v88
	v_mul_f32 v88, v124, v111
	v_fma_f32 v88, v117, v103, v88
	v_fma_f32 v124, v148, v91, v88
	v_mul_f32 v88, v125, v111
	v_fma_f32 v88, v116, v103, v88
	v_fma_f32 v125, v149, v91, v88
	v_mul_f32 v88, v151, v80
	v_mul_f32 v80, v185, v80
	v_fma_f32 v88, v141, v82, v88
	v_fma_f32 v80, v150, v82, v80
	v_fma_f32 v82, v124, v83, v89
	v_fma_f32 v81, v125, v83, v81
	v_add_f32_e32 v82, v88, v82
	v_add_f32_e32 v83, v80, v81
	s_nop 0
	v_add_f32_dpp v80, v82, v82 row_ror:8 row_mask:0xf bank_mask:0xf bound_ctrl:1
	v_add_f32_dpp v82, v83, v83 row_ror:8 row_mask:0xf bank_mask:0xf bound_ctrl:1
	s_nop 0
	v_add_f32_dpp v80, v80, v80 row_ror:4 row_mask:0xf bank_mask:0xf bound_ctrl:1
	v_add_f32_dpp v82, v82, v82 row_ror:4 row_mask:0xf bank_mask:0xf bound_ctrl:1
	s_nop 0
	v_add_f32_dpp v80, v80, v80 row_ror:2 row_mask:0xf bank_mask:0xf bound_ctrl:1
	v_add_f32_dpp v82, v82, v82 row_ror:2 row_mask:0xf bank_mask:0xf bound_ctrl:1
	s_nop 0
	v_add_f32_dpp v80, v80, v80 row_ror:1 row_mask:0xf bank_mask:0xf bound_ctrl:1
	v_add_f32_dpp v82, v82, v82 row_ror:1 row_mask:0xf bank_mask:0xf bound_ctrl:1
	ds_write2_b32 v188, v80, v82 offset0:224 offset1:240
	s_waitcnt lgkmcnt(5)
	v_mul_f32 v148, v151, v112
	v_mul_f32 v112, v185, v112
	v_mul_f32 v149, v126, v113
	v_mul_f32 v113, v127, v113
	ds_read_b128 v[116:119], v134 offset:28928
	ds_read_b128 v[100:103], v134 offset:33024
	ds_read_b128 v[108:111], v134 offset:37120
	ds_read_b128 v[88:91], v134 offset:24832
	ds_read_b128 v[80:83], v134 offset:41216
	ds_read2_b32 v[122:123], v152 offset0:32 offset1:48
	v_fma_f32 v148, v141, v114, v148
	v_fma_f32 v112, v150, v114, v112
	v_fma_f32 v114, v124, v115, v149
	v_fma_f32 v113, v125, v115, v113
	v_add_f32_e32 v114, v148, v114
	v_add_f32_e32 v112, v112, v113
	s_nop 0
	v_add_f32_dpp v113, v114, v114 row_ror:8 row_mask:0xf bank_mask:0xf bound_ctrl:1
	v_add_f32_dpp v112, v112, v112 row_ror:8 row_mask:0xf bank_mask:0xf bound_ctrl:1
	s_waitcnt lgkmcnt(6)
	v_mul_f32 v114, v120, v104
	v_mul_f32 v104, v121, v104
	v_add_f32_dpp v113, v113, v113 row_ror:4 row_mask:0xf bank_mask:0xf bound_ctrl:1
	v_add_f32_dpp v112, v112, v112 row_ror:4 row_mask:0xf bank_mask:0xf bound_ctrl:1
	s_nop 0
	v_add_f32_dpp v113, v113, v113 row_ror:2 row_mask:0xf bank_mask:0xf bound_ctrl:1
	v_add_f32_dpp v112, v112, v112 row_ror:2 row_mask:0xf bank_mask:0xf bound_ctrl:1
	s_nop 0
	v_add_f32_dpp v113, v113, v113 row_ror:1 row_mask:0xf bank_mask:0xf bound_ctrl:1
	v_add_f32_dpp v112, v112, v112 row_ror:1 row_mask:0xf bank_mask:0xf bound_ctrl:1
	v_fma_f32 v114, v113, v96, v114
	v_fma_f32 v96, v112, v96, v104
	v_fma_f32 v148, v151, v92, v114
	v_fma_f32 v149, v185, v92, v96
	v_mul_f32 v92, v120, v105
	v_fma_f32 v92, v113, v97, v92
	v_fma_f32 v126, v126, v93, v92
	v_mul_f32 v92, v121, v105
	v_fma_f32 v92, v112, v97, v92
	v_fma_f32 v127, v127, v93, v92
	v_mul_f32 v92, v120, v106
	v_mul_f32 v93, v126, v85
	v_fma_f32 v92, v113, v98, v92
	v_mul_f32 v85, v127, v85
	v_fma_f32 v141, v141, v94, v92
	v_mul_f32 v92, v121, v106
	v_fma_f32 v92, v112, v98, v92
	v_fma_f32 v150, v150, v94, v92
	v_mul_f32 v92, v120, v107
	v_fma_f32 v92, v113, v99, v92
	v_fma_f32 v124, v124, v95, v92
	v_mul_f32 v92, v121, v107
	v_fma_f32 v92, v112, v99, v92
	v_fma_f32 v125, v125, v95, v92
	v_mul_f32 v92, v148, v84
	v_mul_f32 v84, v149, v84
	v_fma_f32 v92, v141, v86, v92
	v_fma_f32 v84, v150, v86, v84
	v_fma_f32 v86, v124, v87, v93
	v_fma_f32 v85, v125, v87, v85
	v_add_f32_e32 v86, v92, v86
	v_add_f32_e32 v87, v84, v85
	s_nop 0
	v_add_f32_dpp v84, v86, v86 row_ror:8 row_mask:0xf bank_mask:0xf bound_ctrl:1
	v_add_f32_dpp v86, v87, v87 row_ror:8 row_mask:0xf bank_mask:0xf bound_ctrl:1
	s_nop 0
	v_add_f32_dpp v84, v84, v84 row_ror:4 row_mask:0xf bank_mask:0xf bound_ctrl:1
	v_add_f32_dpp v86, v86, v86 row_ror:4 row_mask:0xf bank_mask:0xf bound_ctrl:1
	s_nop 0
	v_add_f32_dpp v84, v84, v84 row_ror:2 row_mask:0xf bank_mask:0xf bound_ctrl:1
	v_add_f32_dpp v86, v86, v86 row_ror:2 row_mask:0xf bank_mask:0xf bound_ctrl:1
	s_nop 0
	v_add_f32_dpp v84, v84, v84 row_ror:1 row_mask:0xf bank_mask:0xf bound_ctrl:1
	v_add_f32_dpp v86, v86, v86 row_ror:1 row_mask:0xf bank_mask:0xf bound_ctrl:1
	ds_write2_b32 v153, v84, v86 offset1:16
	s_waitcnt lgkmcnt(5)
	v_mul_f32 v151, v148, v116
	v_mul_f32 v116, v149, v116
	v_mul_f32 v185, v126, v117
	v_mul_f32 v117, v127, v117
	ds_read_b128 v[112:115], v134 offset:29184
	ds_read_b128 v[96:99], v134 offset:33280
	ds_read_b128 v[104:107], v134 offset:37376
	ds_read_b128 v[92:95], v134 offset:25088
	ds_read_b128 v[84:87], v134 offset:41472
	ds_read2_b32 v[120:121], v152 offset0:64 offset1:80
	v_fma_f32 v151, v141, v118, v151
	v_fma_f32 v116, v150, v118, v116
	v_fma_f32 v118, v124, v119, v185
	v_fma_f32 v117, v125, v119, v117
	v_add_f32_e32 v118, v151, v118
	v_add_f32_e32 v116, v116, v117
	s_nop 0
	v_add_f32_dpp v117, v118, v118 row_ror:8 row_mask:0xf bank_mask:0xf bound_ctrl:1
	v_add_f32_dpp v116, v116, v116 row_ror:8 row_mask:0xf bank_mask:0xf bound_ctrl:1
	s_waitcnt lgkmcnt(6)
	v_mul_f32 v118, v122, v108
	v_mul_f32 v108, v123, v108
	v_add_f32_dpp v117, v117, v117 row_ror:4 row_mask:0xf bank_mask:0xf bound_ctrl:1
	v_add_f32_dpp v116, v116, v116 row_ror:4 row_mask:0xf bank_mask:0xf bound_ctrl:1
	s_nop 0
	v_add_f32_dpp v117, v117, v117 row_ror:2 row_mask:0xf bank_mask:0xf bound_ctrl:1
	v_add_f32_dpp v116, v116, v116 row_ror:2 row_mask:0xf bank_mask:0xf bound_ctrl:1
	s_nop 0
	v_add_f32_dpp v117, v117, v117 row_ror:1 row_mask:0xf bank_mask:0xf bound_ctrl:1
	v_add_f32_dpp v116, v116, v116 row_ror:1 row_mask:0xf bank_mask:0xf bound_ctrl:1
	v_fma_f32 v118, v117, v100, v118
	v_fma_f32 v100, v116, v100, v108
	v_fma_f32 v148, v148, v88, v118
	v_fma_f32 v149, v149, v88, v100
	v_mul_f32 v88, v122, v109
	v_fma_f32 v88, v117, v101, v88
	v_fma_f32 v126, v126, v89, v88
	v_mul_f32 v88, v123, v109
	v_fma_f32 v88, v116, v101, v88
	v_fma_f32 v127, v127, v89, v88
	v_mul_f32 v88, v122, v110
	v_mul_f32 v89, v126, v81
	v_fma_f32 v88, v117, v102, v88
	v_mul_f32 v81, v127, v81
	v_fma_f32 v141, v141, v90, v88
	v_mul_f32 v88, v123, v110
	v_fma_f32 v88, v116, v102, v88
	v_fma_f32 v150, v150, v90, v88
	v_mul_f32 v88, v122, v111
	v_fma_f32 v88, v117, v103, v88
	v_fma_f32 v124, v124, v91, v88
	v_mul_f32 v88, v123, v111
	v_fma_f32 v88, v116, v103, v88
	v_fma_f32 v125, v125, v91, v88
	v_mul_f32 v88, v148, v80
	v_mul_f32 v80, v149, v80
	v_fma_f32 v88, v141, v82, v88
	v_fma_f32 v80, v150, v82, v80
	v_fma_f32 v82, v124, v83, v89
	v_fma_f32 v81, v125, v83, v81
	v_add_f32_e32 v82, v88, v82
	v_add_f32_e32 v83, v80, v81
	s_nop 0
	v_add_f32_dpp v80, v82, v82 row_ror:8 row_mask:0xf bank_mask:0xf bound_ctrl:1
	v_add_f32_dpp v82, v83, v83 row_ror:8 row_mask:0xf bank_mask:0xf bound_ctrl:1
	s_nop 0
	v_add_f32_dpp v80, v80, v80 row_ror:4 row_mask:0xf bank_mask:0xf bound_ctrl:1
	v_add_f32_dpp v82, v82, v82 row_ror:4 row_mask:0xf bank_mask:0xf bound_ctrl:1
	s_nop 0
	v_add_f32_dpp v80, v80, v80 row_ror:2 row_mask:0xf bank_mask:0xf bound_ctrl:1
	v_add_f32_dpp v82, v82, v82 row_ror:2 row_mask:0xf bank_mask:0xf bound_ctrl:1
	s_nop 0
	v_add_f32_dpp v80, v80, v80 row_ror:1 row_mask:0xf bank_mask:0xf bound_ctrl:1
	v_add_f32_dpp v82, v82, v82 row_ror:1 row_mask:0xf bank_mask:0xf bound_ctrl:1
	ds_write2_b32 v153, v80, v82 offset0:32 offset1:48
	s_waitcnt lgkmcnt(5)
	v_mul_f32 v151, v148, v112
	v_mul_f32 v112, v149, v112
	v_mul_f32 v185, v126, v113
	v_mul_f32 v113, v127, v113
	ds_read_b128 v[116:119], v134 offset:29440
	ds_read_b128 v[100:103], v134 offset:33536
	ds_read_b128 v[108:111], v134 offset:37632
	ds_read_b128 v[88:91], v134 offset:25344
	ds_read_b128 v[80:83], v134 offset:41728
	ds_read2_b32 v[122:123], v152 offset0:96 offset1:112
	v_fma_f32 v151, v141, v114, v151
	v_fma_f32 v112, v150, v114, v112
	v_fma_f32 v114, v124, v115, v185
	v_fma_f32 v113, v125, v115, v113
	v_add_f32_e32 v114, v151, v114
	v_add_f32_e32 v112, v112, v113
	s_nop 0
	v_add_f32_dpp v113, v114, v114 row_ror:8 row_mask:0xf bank_mask:0xf bound_ctrl:1
	v_add_f32_dpp v112, v112, v112 row_ror:8 row_mask:0xf bank_mask:0xf bound_ctrl:1
	s_waitcnt lgkmcnt(6)
	v_mul_f32 v114, v120, v104
	v_mul_f32 v104, v121, v104
	v_add_f32_dpp v113, v113, v113 row_ror:4 row_mask:0xf bank_mask:0xf bound_ctrl:1
	v_add_f32_dpp v112, v112, v112 row_ror:4 row_mask:0xf bank_mask:0xf bound_ctrl:1
	s_nop 0
	v_add_f32_dpp v113, v113, v113 row_ror:2 row_mask:0xf bank_mask:0xf bound_ctrl:1
	v_add_f32_dpp v112, v112, v112 row_ror:2 row_mask:0xf bank_mask:0xf bound_ctrl:1
	s_nop 0
	v_add_f32_dpp v113, v113, v113 row_ror:1 row_mask:0xf bank_mask:0xf bound_ctrl:1
	v_add_f32_dpp v112, v112, v112 row_ror:1 row_mask:0xf bank_mask:0xf bound_ctrl:1
	v_fma_f32 v114, v113, v96, v114
	v_fma_f32 v96, v112, v96, v104
	v_fma_f32 v148, v148, v92, v114
	v_fma_f32 v149, v149, v92, v96
	v_mul_f32 v92, v120, v105
	v_fma_f32 v92, v113, v97, v92
	v_fma_f32 v126, v126, v93, v92
	v_mul_f32 v92, v121, v105
	v_fma_f32 v92, v112, v97, v92
	v_fma_f32 v127, v127, v93, v92
	v_mul_f32 v92, v120, v106
	v_mul_f32 v93, v126, v85
	v_fma_f32 v92, v113, v98, v92
	v_mul_f32 v85, v127, v85
	v_fma_f32 v141, v141, v94, v92
	v_mul_f32 v92, v121, v106
	v_fma_f32 v92, v112, v98, v92
	v_fma_f32 v150, v150, v94, v92
	v_mul_f32 v92, v120, v107
	v_fma_f32 v92, v113, v99, v92
	v_fma_f32 v124, v124, v95, v92
	v_mul_f32 v92, v121, v107
	v_fma_f32 v92, v112, v99, v92
	v_fma_f32 v125, v125, v95, v92
	v_mul_f32 v92, v148, v84
	v_mul_f32 v84, v149, v84
	v_fma_f32 v92, v141, v86, v92
	v_fma_f32 v84, v150, v86, v84
	v_fma_f32 v86, v124, v87, v93
	v_fma_f32 v85, v125, v87, v85
	v_add_f32_e32 v86, v92, v86
	v_add_f32_e32 v87, v84, v85
	s_nop 0
	v_add_f32_dpp v84, v86, v86 row_ror:8 row_mask:0xf bank_mask:0xf bound_ctrl:1
	v_add_f32_dpp v86, v87, v87 row_ror:8 row_mask:0xf bank_mask:0xf bound_ctrl:1
	s_nop 0
	v_add_f32_dpp v84, v84, v84 row_ror:4 row_mask:0xf bank_mask:0xf bound_ctrl:1
	v_add_f32_dpp v86, v86, v86 row_ror:4 row_mask:0xf bank_mask:0xf bound_ctrl:1
	s_nop 0
	v_add_f32_dpp v84, v84, v84 row_ror:2 row_mask:0xf bank_mask:0xf bound_ctrl:1
	v_add_f32_dpp v86, v86, v86 row_ror:2 row_mask:0xf bank_mask:0xf bound_ctrl:1
	s_nop 0
	v_add_f32_dpp v84, v84, v84 row_ror:1 row_mask:0xf bank_mask:0xf bound_ctrl:1
	v_add_f32_dpp v86, v86, v86 row_ror:1 row_mask:0xf bank_mask:0xf bound_ctrl:1
	ds_write2_b32 v153, v84, v86 offset0:64 offset1:80
	s_waitcnt lgkmcnt(5)
	v_mul_f32 v151, v148, v116
	v_mul_f32 v116, v149, v116
	v_mul_f32 v185, v126, v117
	v_mul_f32 v117, v127, v117
	ds_read_b128 v[112:115], v134 offset:29696
	ds_read_b128 v[96:99], v134 offset:33792
	ds_read_b128 v[104:107], v134 offset:37888
	ds_read_b128 v[92:95], v134 offset:25600
	ds_read_b128 v[84:87], v134 offset:41984
	ds_read2_b32 v[120:121], v152 offset0:128 offset1:144
	v_fma_f32 v151, v141, v118, v151
	v_fma_f32 v116, v150, v118, v116
	v_fma_f32 v118, v124, v119, v185
	v_fma_f32 v117, v125, v119, v117
	v_add_f32_e32 v118, v151, v118
	v_add_f32_e32 v116, v116, v117
	s_nop 0
	v_add_f32_dpp v117, v118, v118 row_ror:8 row_mask:0xf bank_mask:0xf bound_ctrl:1
	v_add_f32_dpp v116, v116, v116 row_ror:8 row_mask:0xf bank_mask:0xf bound_ctrl:1
	s_waitcnt lgkmcnt(6)
	v_mul_f32 v118, v122, v108
	v_mul_f32 v108, v123, v108
	v_add_f32_dpp v117, v117, v117 row_ror:4 row_mask:0xf bank_mask:0xf bound_ctrl:1
	v_add_f32_dpp v116, v116, v116 row_ror:4 row_mask:0xf bank_mask:0xf bound_ctrl:1
	s_nop 0
	v_add_f32_dpp v117, v117, v117 row_ror:2 row_mask:0xf bank_mask:0xf bound_ctrl:1
	v_add_f32_dpp v116, v116, v116 row_ror:2 row_mask:0xf bank_mask:0xf bound_ctrl:1
	s_nop 0
	v_add_f32_dpp v117, v117, v117 row_ror:1 row_mask:0xf bank_mask:0xf bound_ctrl:1
	v_add_f32_dpp v116, v116, v116 row_ror:1 row_mask:0xf bank_mask:0xf bound_ctrl:1
	v_fma_f32 v118, v117, v100, v118
	v_fma_f32 v100, v116, v100, v108
	v_fma_f32 v148, v148, v88, v118
	v_fma_f32 v149, v149, v88, v100
	v_mul_f32 v88, v122, v109
	v_fma_f32 v88, v117, v101, v88
	v_fma_f32 v126, v126, v89, v88
	v_mul_f32 v88, v123, v109
	v_fma_f32 v88, v116, v101, v88
	v_fma_f32 v127, v127, v89, v88
	v_mul_f32 v88, v122, v110
	v_mul_f32 v89, v126, v81
	v_fma_f32 v88, v117, v102, v88
	v_mul_f32 v81, v127, v81
	v_fma_f32 v141, v141, v90, v88
	v_mul_f32 v88, v123, v110
	v_fma_f32 v88, v116, v102, v88
	v_fma_f32 v150, v150, v90, v88
	v_mul_f32 v88, v122, v111
	v_fma_f32 v88, v117, v103, v88
	v_fma_f32 v124, v124, v91, v88
	v_mul_f32 v88, v123, v111
	v_fma_f32 v88, v116, v103, v88
	v_fma_f32 v125, v125, v91, v88
	v_mul_f32 v88, v148, v80
	v_mul_f32 v80, v149, v80
	v_fma_f32 v88, v141, v82, v88
	v_fma_f32 v80, v150, v82, v80
	v_fma_f32 v82, v124, v83, v89
	v_fma_f32 v81, v125, v83, v81
	v_add_f32_e32 v82, v88, v82
	v_add_f32_e32 v83, v80, v81
	s_nop 0
	v_add_f32_dpp v80, v82, v82 row_ror:8 row_mask:0xf bank_mask:0xf bound_ctrl:1
	v_add_f32_dpp v82, v83, v83 row_ror:8 row_mask:0xf bank_mask:0xf bound_ctrl:1
	s_nop 0
	v_add_f32_dpp v80, v80, v80 row_ror:4 row_mask:0xf bank_mask:0xf bound_ctrl:1
	v_add_f32_dpp v82, v82, v82 row_ror:4 row_mask:0xf bank_mask:0xf bound_ctrl:1
	s_nop 0
	v_add_f32_dpp v80, v80, v80 row_ror:2 row_mask:0xf bank_mask:0xf bound_ctrl:1
	v_add_f32_dpp v82, v82, v82 row_ror:2 row_mask:0xf bank_mask:0xf bound_ctrl:1
	s_nop 0
	v_add_f32_dpp v80, v80, v80 row_ror:1 row_mask:0xf bank_mask:0xf bound_ctrl:1
	v_add_f32_dpp v82, v82, v82 row_ror:1 row_mask:0xf bank_mask:0xf bound_ctrl:1
	ds_write2_b32 v153, v80, v82 offset0:96 offset1:112
	s_waitcnt lgkmcnt(5)
	v_mul_f32 v151, v148, v112
	v_mul_f32 v112, v149, v112
	v_mul_f32 v185, v126, v113
	v_mul_f32 v113, v127, v113
	ds_read_b128 v[116:119], v134 offset:29952
	ds_read_b128 v[100:103], v134 offset:34048
	ds_read_b128 v[108:111], v134 offset:38144
	ds_read_b128 v[88:91], v134 offset:25856
	ds_read_b128 v[80:83], v134 offset:42240
	ds_read2_b32 v[122:123], v152 offset0:160 offset1:176
	v_fma_f32 v151, v141, v114, v151
	v_fma_f32 v112, v150, v114, v112
	v_fma_f32 v114, v124, v115, v185
	v_fma_f32 v113, v125, v115, v113
	v_add_f32_e32 v114, v151, v114
	v_add_f32_e32 v112, v112, v113
	s_nop 0
	v_add_f32_dpp v113, v114, v114 row_ror:8 row_mask:0xf bank_mask:0xf bound_ctrl:1
	v_add_f32_dpp v112, v112, v112 row_ror:8 row_mask:0xf bank_mask:0xf bound_ctrl:1
	s_waitcnt lgkmcnt(6)
	v_mul_f32 v114, v120, v104
	v_mul_f32 v104, v121, v104
	v_add_f32_dpp v113, v113, v113 row_ror:4 row_mask:0xf bank_mask:0xf bound_ctrl:1
	v_add_f32_dpp v112, v112, v112 row_ror:4 row_mask:0xf bank_mask:0xf bound_ctrl:1
	s_nop 0
	v_add_f32_dpp v113, v113, v113 row_ror:2 row_mask:0xf bank_mask:0xf bound_ctrl:1
	v_add_f32_dpp v112, v112, v112 row_ror:2 row_mask:0xf bank_mask:0xf bound_ctrl:1
	s_nop 0
	v_add_f32_dpp v113, v113, v113 row_ror:1 row_mask:0xf bank_mask:0xf bound_ctrl:1
	v_add_f32_dpp v112, v112, v112 row_ror:1 row_mask:0xf bank_mask:0xf bound_ctrl:1
	v_fma_f32 v114, v113, v96, v114
	v_fma_f32 v96, v112, v96, v104
	v_fma_f32 v148, v148, v92, v114
	v_fma_f32 v149, v149, v92, v96
	v_mul_f32 v92, v120, v105
	v_fma_f32 v92, v113, v97, v92
	v_fma_f32 v126, v126, v93, v92
	v_mul_f32 v92, v121, v105
	v_fma_f32 v92, v112, v97, v92
	v_fma_f32 v127, v127, v93, v92
	v_mul_f32 v92, v120, v106
	v_mul_f32 v93, v126, v85
	v_fma_f32 v92, v113, v98, v92
	v_mul_f32 v85, v127, v85
	v_fma_f32 v141, v141, v94, v92
	v_mul_f32 v92, v121, v106
	v_fma_f32 v92, v112, v98, v92
	v_fma_f32 v150, v150, v94, v92
	v_mul_f32 v92, v120, v107
	v_fma_f32 v92, v113, v99, v92
	v_fma_f32 v124, v124, v95, v92
	v_mul_f32 v92, v121, v107
	v_fma_f32 v92, v112, v99, v92
	v_fma_f32 v125, v125, v95, v92
	v_mul_f32 v92, v148, v84
	v_mul_f32 v84, v149, v84
	v_fma_f32 v92, v141, v86, v92
	v_fma_f32 v84, v150, v86, v84
	v_fma_f32 v86, v124, v87, v93
	v_fma_f32 v85, v125, v87, v85
	v_add_f32_e32 v86, v92, v86
	v_add_f32_e32 v87, v84, v85
	s_nop 0
	v_add_f32_dpp v84, v86, v86 row_ror:8 row_mask:0xf bank_mask:0xf bound_ctrl:1
	v_add_f32_dpp v86, v87, v87 row_ror:8 row_mask:0xf bank_mask:0xf bound_ctrl:1
	s_nop 0
	v_add_f32_dpp v84, v84, v84 row_ror:4 row_mask:0xf bank_mask:0xf bound_ctrl:1
	v_add_f32_dpp v86, v86, v86 row_ror:4 row_mask:0xf bank_mask:0xf bound_ctrl:1
	s_nop 0
	v_add_f32_dpp v84, v84, v84 row_ror:2 row_mask:0xf bank_mask:0xf bound_ctrl:1
	v_add_f32_dpp v86, v86, v86 row_ror:2 row_mask:0xf bank_mask:0xf bound_ctrl:1
	s_nop 0
	v_add_f32_dpp v84, v84, v84 row_ror:1 row_mask:0xf bank_mask:0xf bound_ctrl:1
	v_add_f32_dpp v86, v86, v86 row_ror:1 row_mask:0xf bank_mask:0xf bound_ctrl:1
	ds_write2_b32 v153, v84, v86 offset0:128 offset1:144
	s_waitcnt lgkmcnt(5)
	v_mul_f32 v151, v148, v116
	v_mul_f32 v116, v149, v116
	v_mul_f32 v185, v126, v117
	v_mul_f32 v117, v127, v117
	ds_read_b128 v[112:115], v134 offset:30208
	ds_read_b128 v[96:99], v134 offset:34304
	ds_read_b128 v[104:107], v134 offset:38400
	ds_read_b128 v[92:95], v134 offset:26112
	ds_read_b128 v[84:87], v134 offset:42496
	ds_read2_b32 v[120:121], v152 offset0:192 offset1:208
	v_fma_f32 v151, v141, v118, v151
	v_fma_f32 v116, v150, v118, v116
	v_fma_f32 v118, v124, v119, v185
	v_fma_f32 v117, v125, v119, v117
	v_add_f32_e32 v118, v151, v118
	v_add_f32_e32 v116, v116, v117
	s_nop 0
	v_add_f32_dpp v117, v118, v118 row_ror:8 row_mask:0xf bank_mask:0xf bound_ctrl:1
	v_add_f32_dpp v116, v116, v116 row_ror:8 row_mask:0xf bank_mask:0xf bound_ctrl:1
	s_waitcnt lgkmcnt(6)
	v_mul_f32 v118, v122, v108
	v_mul_f32 v108, v123, v108
	v_add_f32_dpp v117, v117, v117 row_ror:4 row_mask:0xf bank_mask:0xf bound_ctrl:1
	v_add_f32_dpp v116, v116, v116 row_ror:4 row_mask:0xf bank_mask:0xf bound_ctrl:1
	s_nop 0
	v_add_f32_dpp v117, v117, v117 row_ror:2 row_mask:0xf bank_mask:0xf bound_ctrl:1
	v_add_f32_dpp v116, v116, v116 row_ror:2 row_mask:0xf bank_mask:0xf bound_ctrl:1
	s_nop 0
	v_add_f32_dpp v117, v117, v117 row_ror:1 row_mask:0xf bank_mask:0xf bound_ctrl:1
	v_add_f32_dpp v116, v116, v116 row_ror:1 row_mask:0xf bank_mask:0xf bound_ctrl:1
	v_fma_f32 v118, v117, v100, v118
	v_fma_f32 v100, v116, v100, v108
	v_fma_f32 v148, v148, v88, v118
	v_fma_f32 v149, v149, v88, v100
	v_mul_f32 v88, v122, v109
	v_fma_f32 v88, v117, v101, v88
	v_fma_f32 v126, v126, v89, v88
	v_mul_f32 v88, v123, v109
	v_fma_f32 v88, v116, v101, v88
	v_fma_f32 v127, v127, v89, v88
	v_mul_f32 v88, v122, v110
	v_mul_f32 v89, v126, v81
	v_fma_f32 v88, v117, v102, v88
	v_mul_f32 v81, v127, v81
	v_fma_f32 v141, v141, v90, v88
	v_mul_f32 v88, v123, v110
	v_fma_f32 v88, v116, v102, v88
	v_fma_f32 v150, v150, v90, v88
	v_mul_f32 v88, v122, v111
	v_fma_f32 v88, v117, v103, v88
	v_fma_f32 v124, v124, v91, v88
	v_mul_f32 v88, v123, v111
	v_fma_f32 v88, v116, v103, v88
	v_fma_f32 v125, v125, v91, v88
	v_mul_f32 v88, v148, v80
	v_mul_f32 v80, v149, v80
	v_fma_f32 v88, v141, v82, v88
	v_fma_f32 v80, v150, v82, v80
	v_fma_f32 v82, v124, v83, v89
	v_fma_f32 v81, v125, v83, v81
	v_add_f32_e32 v82, v88, v82
	v_add_f32_e32 v83, v80, v81
	s_nop 0
	v_add_f32_dpp v80, v82, v82 row_ror:8 row_mask:0xf bank_mask:0xf bound_ctrl:1
	v_add_f32_dpp v82, v83, v83 row_ror:8 row_mask:0xf bank_mask:0xf bound_ctrl:1
	s_nop 0
	v_add_f32_dpp v80, v80, v80 row_ror:4 row_mask:0xf bank_mask:0xf bound_ctrl:1
	v_add_f32_dpp v82, v82, v82 row_ror:4 row_mask:0xf bank_mask:0xf bound_ctrl:1
	s_nop 0
	v_add_f32_dpp v80, v80, v80 row_ror:2 row_mask:0xf bank_mask:0xf bound_ctrl:1
	v_add_f32_dpp v82, v82, v82 row_ror:2 row_mask:0xf bank_mask:0xf bound_ctrl:1
	s_nop 0
	v_add_f32_dpp v80, v80, v80 row_ror:1 row_mask:0xf bank_mask:0xf bound_ctrl:1
	v_add_f32_dpp v82, v82, v82 row_ror:1 row_mask:0xf bank_mask:0xf bound_ctrl:1
	ds_write2_b32 v153, v80, v82 offset0:160 offset1:176
	s_waitcnt lgkmcnt(5)
	v_mul_f32 v151, v148, v112
	v_mul_f32 v112, v149, v112
	ds_read_b128 v[116:119], v134 offset:30464
	ds_read_b128 v[100:103], v134 offset:34560
	ds_read_b128 v[108:111], v134 offset:38656
	ds_read_b128 v[80:83], v134 offset:26368
	ds_read_b128 v[88:91], v134 offset:42752
	ds_read2_b32 v[122:123], v152 offset0:224 offset1:240
	v_mul_f32 v152, v126, v113
	v_mul_f32 v113, v127, v113
	v_fma_f32 v112, v150, v114, v112
	v_fma_f32 v151, v141, v114, v151
	v_fma_f32 v114, v124, v115, v152
	v_fma_f32 v113, v125, v115, v113
	v_add_f32_e32 v112, v112, v113
	v_add_f32_e32 v114, v151, v114
	s_nop 0
	v_add_f32_dpp v112, v112, v112 row_ror:8 row_mask:0xf bank_mask:0xf bound_ctrl:1
	v_add_f32_dpp v113, v114, v114 row_ror:8 row_mask:0xf bank_mask:0xf bound_ctrl:1
	s_nop 0
	v_add_f32_dpp v112, v112, v112 row_ror:4 row_mask:0xf bank_mask:0xf bound_ctrl:1
	v_add_f32_dpp v113, v113, v113 row_ror:4 row_mask:0xf bank_mask:0xf bound_ctrl:1
	s_nop 0
	v_add_f32_dpp v112, v112, v112 row_ror:2 row_mask:0xf bank_mask:0xf bound_ctrl:1
	v_add_f32_dpp v113, v113, v113 row_ror:2 row_mask:0xf bank_mask:0xf bound_ctrl:1
	s_nop 0
	v_add_f32_dpp v114, v112, v112 row_ror:1 row_mask:0xf bank_mask:0xf bound_ctrl:1
	s_waitcnt lgkmcnt(6)
	v_mul_f32 v112, v120, v104
	v_add_f32_dpp v113, v113, v113 row_ror:1 row_mask:0xf bank_mask:0xf bound_ctrl:1
	v_fma_f32 v112, v113, v96, v112
	v_mul_f32 v104, v121, v104
	v_fma_f32 v96, v114, v96, v104
	v_fma_f32 v112, v148, v92, v112
	v_mul_f32 v104, v121, v105
	v_fma_f32 v92, v149, v92, v96
	v_mul_f32 v96, v120, v105
	v_fma_f32 v96, v113, v97, v96
	v_fma_f32 v97, v114, v97, v104
	v_mul_f32 v104, v121, v106
	v_fma_f32 v96, v126, v93, v96
	v_fma_f32 v93, v127, v93, v97
	v_mul_f32 v97, v120, v106
	v_fma_f32 v97, v113, v98, v97
	v_fma_f32 v98, v114, v98, v104
	v_mul_f32 v104, v121, v107
	v_fma_f32 v97, v141, v94, v97
	v_fma_f32 v94, v150, v94, v98
	v_mul_f32 v98, v120, v107
	v_fma_f32 v98, v113, v99, v98
	v_fma_f32 v99, v114, v99, v104
	v_mul_f32 v104, v96, v85
	v_mul_f32 v85, v93, v85
	v_fma_f32 v98, v124, v95, v98
	v_fma_f32 v95, v125, v95, v99
	v_mul_f32 v99, v112, v84
	v_mul_f32 v84, v92, v84
	v_fma_f32 v99, v97, v86, v99
	v_fma_f32 v84, v94, v86, v84
	v_fma_f32 v86, v98, v87, v104
	v_fma_f32 v85, v95, v87, v85
	v_add_f32_e32 v86, v99, v86
	v_add_f32_e32 v87, v84, v85
	s_nop 0
	v_add_f32_dpp v84, v86, v86 row_ror:8 row_mask:0xf bank_mask:0xf bound_ctrl:1
	v_add_f32_dpp v86, v87, v87 row_ror:8 row_mask:0xf bank_mask:0xf bound_ctrl:1
	s_nop 0
	v_add_f32_dpp v84, v84, v84 row_ror:4 row_mask:0xf bank_mask:0xf bound_ctrl:1
	v_add_f32_dpp v86, v86, v86 row_ror:4 row_mask:0xf bank_mask:0xf bound_ctrl:1
	s_nop 0
	v_add_f32_dpp v84, v84, v84 row_ror:2 row_mask:0xf bank_mask:0xf bound_ctrl:1
	v_add_f32_dpp v86, v86, v86 row_ror:2 row_mask:0xf bank_mask:0xf bound_ctrl:1
	s_nop 0
	v_add_f32_dpp v84, v84, v84 row_ror:1 row_mask:0xf bank_mask:0xf bound_ctrl:1
	v_add_f32_dpp v86, v86, v86 row_ror:1 row_mask:0xf bank_mask:0xf bound_ctrl:1
	ds_write2_b32 v153, v84, v86 offset0:192 offset1:208
	s_waitcnt lgkmcnt(5)
	v_mul_f32 v84, v112, v116
	v_mul_f32 v86, v96, v117
	v_mul_f32 v85, v92, v116
	v_mul_f32 v87, v93, v117
	v_fma_f32 v84, v97, v118, v84
	v_fma_f32 v86, v98, v119, v86
	v_fma_f32 v85, v94, v118, v85
	v_fma_f32 v87, v95, v119, v87
	v_add_f32_e32 v84, v84, v86
	v_add_f32_e32 v85, v85, v87
	s_nop 0
	v_add_f32_dpp v84, v84, v84 row_ror:8 row_mask:0xf bank_mask:0xf bound_ctrl:1
	s_waitcnt lgkmcnt(0)
	v_mul_f32 v86, v123, v109
	v_add_f32_dpp v84, v84, v84 row_ror:4 row_mask:0xf bank_mask:0xf bound_ctrl:1
	s_nop 1
	v_add_f32_dpp v84, v84, v84 row_ror:2 row_mask:0xf bank_mask:0xf bound_ctrl:1
	s_nop 1
	v_add_f32_dpp v87, v84, v84 row_ror:1 row_mask:0xf bank_mask:0xf bound_ctrl:1
	v_add_f32_dpp v84, v85, v85 row_ror:8 row_mask:0xf bank_mask:0xf bound_ctrl:1
	v_mul_f32 v85, v123, v108
	s_nop 0
	v_add_f32_dpp v84, v84, v84 row_ror:4 row_mask:0xf bank_mask:0xf bound_ctrl:1
	s_nop 1
	v_add_f32_dpp v84, v84, v84 row_ror:2 row_mask:0xf bank_mask:0xf bound_ctrl:1
	s_nop 1
	v_add_f32_dpp v99, v84, v84 row_ror:1 row_mask:0xf bank_mask:0xf bound_ctrl:1
	v_mul_f32 v84, v122, v108
	v_fma_f32 v85, v99, v100, v85
	v_fma_f32 v86, v99, v101, v86
	v_fma_f32 v84, v87, v100, v84
	v_fma_f32 v84, v112, v80, v84
	v_fma_f32 v80, v92, v80, v85
	v_mul_f32 v85, v122, v109
	v_mul_f32 v92, v123, v110
	v_fma_f32 v85, v87, v101, v85
	v_fma_f32 v92, v99, v102, v92
	v_fma_f32 v85, v96, v81, v85
	v_fma_f32 v81, v93, v81, v86
	v_mul_f32 v86, v122, v110
	v_fma_f32 v86, v87, v102, v86
	v_mul_f32 v93, v85, v89
	v_mul_f32 v89, v81, v89
	v_fma_f32 v86, v97, v82, v86
	v_fma_f32 v82, v94, v82, v92
	v_mul_f32 v92, v122, v111
	v_fma_f32 v87, v87, v103, v92
	v_mul_f32 v92, v123, v111
	v_fma_f32 v92, v99, v103, v92
	v_fma_f32 v87, v98, v83, v87
	v_fma_f32 v83, v95, v83, v92
	v_mul_f32 v92, v84, v88
	v_mul_f32 v88, v80, v88
	v_fma_f32 v92, v86, v90, v92
	v_fma_f32 v88, v82, v90, v88
	v_fma_f32 v90, v87, v91, v93
	v_fma_f32 v89, v83, v91, v89
	v_add_f32_e32 v90, v92, v90
	v_add_f32_e32 v91, v88, v89
	v_mov_b32_e32 v89, 0
	v_add_f32_dpp v88, v90, v90 row_ror:8 row_mask:0xf bank_mask:0xf bound_ctrl:1
	v_add_f32_dpp v90, v91, v91 row_ror:8 row_mask:0xf bank_mask:0xf bound_ctrl:1
	v_mov_b32_e32 v91, 0
	v_add_f32_dpp v88, v88, v88 row_ror:4 row_mask:0xf bank_mask:0xf bound_ctrl:1
	v_add_f32_dpp v90, v90, v90 row_ror:4 row_mask:0xf bank_mask:0xf bound_ctrl:1
	s_nop 0
	v_add_f32_dpp v88, v88, v88 row_ror:2 row_mask:0xf bank_mask:0xf bound_ctrl:1
	v_add_f32_dpp v90, v90, v90 row_ror:2 row_mask:0xf bank_mask:0xf bound_ctrl:1
	s_nop 0
	v_mov_b32_dpp v89, v88 row_ror:1 row_mask:0xf bank_mask:0xf
	v_mov_b32_dpp v91, v90 row_ror:1 row_mask:0xf bank_mask:0xf
	s_and_saveexec_b64 s[8:9], s[40:41]
	s_cbranch_execz .LBB0_332
	v_add_f32_e32 v90, v90, v91
	v_add_f32_e32 v88, v88, v89
	ds_write2_b32 v153, v88, v90 offset0:224 offset1:240
	s_branch .LBB0_332

.LBB0_1156:
	s_or_b64 exec, exec, s[8:9]
	s_waitcnt lgkmcnt(0)
	s_barrier
	v_add_u32_e64 v196, s83, 0
	ds_read_b128 v[72:75], v194
	ds_read_b128 v[80:83], v194 offset:256
	ds_read_b128 v[112:115], v194 offset:8192
	ds_read_b128 v[132:135], v194 offset:8448
	ds_read2_b64 v[92:95], v196 offset0:32 offset1:40
	v_add_u32_e32 v198, 0x4000, v190
	ds_read2_b32 v[64:65], v198 offset1:16
	ds_read_b128 v[206:209], v194 offset:512
	ds_read_b128 v[210:213], v194 offset:768
	ds_read_b128 v[154:157], v194 offset:8704
	ds_read_b128 v[200:203], v194 offset:8960
	ds_read_b128 v[96:99], v194 offset:1024
	ds_read_b128 v[84:87], v194 offset:1280
	ds_read_b128 v[128:131], v194 offset:9216
	ds_read_b128 v[120:123], v194 offset:9472
	ds_read_b128 v[76:79], v194 offset:1536
	ds_read_b128 v[68:71], v194 offset:1792
	ds_read_b128 v[124:127], v194 offset:9728
	ds_read_b128 v[116:119], v194 offset:9984
	s_waitcnt lgkmcnt(12)
	v_mul_f32_e32 v64, v94, v64
	v_mul_f32 v66, v112, v64
	v_mul_f32 v67, v113, v64
	v_mul_f32 v94, v114, v64
	v_mul_f32 v112, v115, v64
	v_mul_f32 v113, v132, v64
	v_mul_f32 v114, v133, v64
	v_mul_f32 v115, v134, v64
	v_mul_f32 v132, v135, v64
	s_waitcnt lgkmcnt(9)
	v_mul_f32 v133, v154, v64
	v_mul_f32 v134, v155, v64
	v_mul_f32 v135, v156, v64
	v_mul_f32 v154, v157, v64
	s_waitcnt lgkmcnt(8)
	v_mul_f32 v214, v200, v64
	v_mul_f32 v215, v201, v64
	v_mul_f32 v216, v202, v64
	v_mul_f32 v64, v203, v64
	v_fma_f32 v205, v92, v88, v66
	v_fma_f32 v204, v92, v89, v67
	v_fma_f32 v203, v92, v90, v94
	v_fma_f32 v202, v92, v100, v112
	v_fma_f32 v155, v92, v91, v113
	v_fma_f32 v157, v92, v101, v114
	v_fma_f32 v199, v92, v102, v115
	v_fma_f32 v201, v92, v104, v132
	v_fma_f32 v200, v92, v103, v133
	v_fma_f32 v197, v92, v105, v134
	v_fma_f32 v156, v92, v106, v135
	v_fma_f32 v154, v92, v109, v154
	v_fma_f32 v135, v92, v107, v214
	v_fma_f32 v134, v92, v110, v215
	v_fma_f32 v94, v92, v108, v216
	v_fma_f32 v92, v92, v111, v64
	v_fma_f32 v64, v72, v205, v140
	v_fma_f32 v66, v73, v204, v140
	v_fma_f32 v67, v74, v203, v140
	v_fma_f32 v72, v75, v202, v140
	v_fma_f32 v64, v80, v155, v64
	v_fma_f32 v66, v81, v157, v66
	v_fma_f32 v67, v82, v199, v67
	v_fma_f32 v72, v83, v201, v72
	v_fma_f32 v64, v206, v200, v64
	v_fma_f32 v66, v207, v197, v66
	v_fma_f32 v67, v208, v156, v67
	v_fma_f32 v72, v209, v154, v72
	v_fma_f32 v64, v210, v135, v64
	v_fma_f32 v66, v211, v134, v66
	v_fma_f32 v67, v212, v94, v67
	v_fma_f32 v72, v213, v92, v72
	v_add_f32_e32 v64, v64, v66
	v_add_f32_e32 v66, v67, v72
	v_add_f32_e32 v64, v64, v66
	s_nop 1
	v_add_f32_dpp v64, v64, v64 row_ror:8 row_mask:0xf bank_mask:0xf bound_ctrl:1
	s_nop 1
	v_add_f32_dpp v64, v64, v64 row_ror:4 row_mask:0xf bank_mask:0xf bound_ctrl:1
	s_nop 1
	v_add_f32_dpp v64, v64, v64 row_ror:2 row_mask:0xf bank_mask:0xf bound_ctrl:1
	s_nop 1
	v_add_f32_dpp v64, v64, v64 row_ror:1 row_mask:0xf bank_mask:0xf bound_ctrl:1
	ds_write_b32 v190, v64 offset:34048
	v_mul_f32_e32 v206, v95, v65
	ds_read_b128 v[88:91], v194 offset:2048
	ds_read_b128 v[80:83], v194 offset:2304
	ds_read_b128 v[112:115], v194 offset:10240
	ds_read_b128 v[104:107], v194 offset:10496
	ds_read_b128 v[72:75], v194 offset:2560
	ds_read_b128 v[64:67], v194 offset:2816
	ds_read_b128 v[108:111], v194 offset:10752
	ds_read_b128 v[100:103], v194 offset:11008
	ds_read2_b32 v[132:133], v196 offset0:66 offset1:82
	ds_read_b32 v95, v190 offset:16512
	s_waitcnt lgkmcnt(14)
	v_mul_f32 v128, v128, v206
	v_mul_f32 v129, v129, v206
	v_mul_f32 v130, v130, v206
	v_mul_f32 v131, v131, v206
	v_mul_f32 v120, v120, v206
	v_mul_f32 v121, v121, v206
	v_mul_f32 v122, v122, v206
	v_mul_f32 v123, v123, v206
	s_waitcnt lgkmcnt(11)
	v_mul_f32 v124, v124, v206
	v_mul_f32 v125, v125, v206
	v_mul_f32 v126, v126, v206
	v_mul_f32 v127, v127, v206
	s_waitcnt lgkmcnt(10)
	v_mul_f32 v116, v116, v206
	v_mul_f32 v117, v117, v206
	v_mul_f32 v118, v118, v206
	v_mul_f32 v119, v119, v206
	v_fma_f32 v128, v93, v205, v128
	v_fma_f32 v129, v93, v204, v129
	v_fma_f32 v130, v93, v203, v130
	v_fma_f32 v131, v93, v202, v131
	v_fma_f32 v155, v93, v155, v120
	v_fma_f32 v157, v93, v157, v121
	v_fma_f32 v199, v93, v199, v122
	v_fma_f32 v201, v93, v201, v123
	v_fma_f32 v200, v93, v200, v124
	v_fma_f32 v197, v93, v197, v125
	v_fma_f32 v156, v93, v156, v126
	v_fma_f32 v154, v93, v154, v127
	v_fma_f32 v202, v93, v135, v116
	v_fma_f32 v203, v93, v134, v117
	v_fma_f32 v204, v93, v94, v118
	v_fma_f32 v205, v93, v92, v119
	v_fma_f32 v92, v96, v128, v140
	v_fma_f32 v93, v97, v129, v140
	v_fma_f32 v94, v98, v130, v140
	v_fma_f32 v96, v99, v131, v140
	v_fma_f32 v84, v84, v155, v92
	v_fma_f32 v85, v85, v157, v93
	v_fma_f32 v86, v86, v199, v94
	v_fma_f32 v87, v87, v201, v96
	v_fma_f32 v76, v76, v200, v84
	v_fma_f32 v77, v77, v197, v85
	v_fma_f32 v78, v78, v156, v86
	v_fma_f32 v79, v79, v154, v87
	v_fma_f32 v68, v68, v202, v76
	v_fma_f32 v69, v69, v203, v77
	v_fma_f32 v70, v70, v204, v78
	v_fma_f32 v71, v71, v205, v79
	v_add_f32_e32 v68, v68, v69
	v_add_f32_e32 v69, v70, v71
	v_add_f32_e32 v68, v68, v69
	s_nop 1
	v_add_f32_dpp v68, v68, v68 row_ror:8 row_mask:0xf bank_mask:0xf bound_ctrl:1
	s_nop 1
	v_add_f32_dpp v68, v68, v68 row_ror:4 row_mask:0xf bank_mask:0xf bound_ctrl:1
	s_nop 1
	v_add_f32_dpp v68, v68, v68 row_ror:2 row_mask:0xf bank_mask:0xf bound_ctrl:1
	s_nop 1
	v_add_f32_dpp v68, v68, v68 row_ror:1 row_mask:0xf bank_mask:0xf bound_ctrl:1
	ds_write_b32 v190, v68 offset:34112
	s_waitcnt lgkmcnt(0)
	v_mul_f32_e32 v206, v133, v95
	ds_read_b128 v[92:95], v194 offset:3072
	ds_read_b128 v[84:87], v194 offset:3328
	ds_read_b128 v[124:127], v194 offset:11264
	ds_read_b128 v[116:119], v194 offset:11520
	ds_read_b128 v[76:79], v194 offset:3584
	ds_read_b128 v[68:71], v194 offset:3840
	ds_read_b128 v[120:123], v194 offset:11776
	ds_read_b128 v[96:99], v194 offset:12032
	ds_read2_b32 v[134:135], v196 offset0:67 offset1:83
	ds_read_b32 v133, v190 offset:16576
	v_mul_f32 v112, v112, v206
	v_mul_f32 v113, v113, v206
	v_mul_f32 v114, v114, v206
	v_mul_f32 v115, v115, v206
	v_mul_f32 v104, v104, v206
	v_mul_f32 v105, v105, v206
	v_mul_f32 v108, v108, v206
	v_mul_f32 v109, v109, v206
	v_mul_f32 v100, v100, v206
	v_mul_f32 v101, v101, v206
	v_fma_f32 v112, v132, v128, v112
	v_fma_f32 v113, v132, v129, v113
	v_fma_f32 v155, v132, v155, v104
	v_fma_f32 v157, v132, v157, v105
	v_fma_f32 v200, v132, v200, v108
	v_fma_f32 v197, v132, v197, v109
	v_fma_f32 v202, v132, v202, v100
	v_fma_f32 v203, v132, v203, v101
	v_fma_f32 v88, v88, v112, v140
	v_fma_f32 v89, v89, v113, v140
	v_mul_f32 v106, v106, v206
	v_mul_f32 v107, v107, v206
	v_mul_f32 v110, v110, v206
	v_mul_f32 v111, v111, v206
	v_fma_f32 v80, v80, v155, v88
	v_fma_f32 v81, v81, v157, v89
	v_mul_f32 v102, v102, v206
	v_mul_f32 v103, v103, v206
	v_fma_f32 v114, v132, v130, v114
	v_fma_f32 v115, v132, v131, v115
	v_fma_f32 v72, v72, v200, v80
	v_fma_f32 v73, v73, v197, v81
	v_fma_f32 v199, v132, v199, v106
	v_fma_f32 v201, v132, v201, v107
	v_fma_f32 v156, v132, v156, v110
	v_fma_f32 v154, v132, v154, v111
	v_fma_f32 v64, v64, v202, v72
	v_fma_f32 v65, v65, v203, v73
	v_fma_f32 v204, v132, v204, v102
	v_fma_f32 v205, v132, v205, v103
	v_fma_f32 v90, v90, v114, v140
	v_fma_f32 v91, v91, v115, v140
	v_add_f32_e32 v64, v64, v65
	v_fma_f32 v82, v82, v199, v90
	v_fma_f32 v83, v83, v201, v91
	v_fma_f32 v74, v74, v156, v82
	v_fma_f32 v75, v75, v154, v83
	v_fma_f32 v66, v66, v204, v74
	v_fma_f32 v67, v67, v205, v75
	v_add_f32_e32 v65, v66, v67
	v_add_f32_e32 v64, v64, v65
	s_nop 1
	v_add_f32_dpp v64, v64, v64 row_ror:8 row_mask:0xf bank_mask:0xf bound_ctrl:1
	s_nop 1
	v_add_f32_dpp v64, v64, v64 row_ror:4 row_mask:0xf bank_mask:0xf bound_ctrl:1
	s_nop 1
	v_add_f32_dpp v64, v64, v64 row_ror:2 row_mask:0xf bank_mask:0xf bound_ctrl:1
	s_nop 1
	v_add_f32_dpp v64, v64, v64 row_ror:1 row_mask:0xf bank_mask:0xf bound_ctrl:1
	ds_write_b32 v190, v64 offset:34176
	s_waitcnt lgkmcnt(0)
	v_mul_f32_e32 v206, v135, v133
	ds_read_b128 v[88:91], v194 offset:4096
	ds_read_b128 v[80:83], v194 offset:4352
	ds_read_b128 v[128:131], v194 offset:12288
	ds_read_b128 v[104:107], v194 offset:12544
	ds_read_b128 v[72:75], v194 offset:4608
	ds_read_b128 v[64:67], v194 offset:4864
	ds_read_b128 v[108:111], v194 offset:12800
	ds_read_b128 v[100:103], v194 offset:13056
	ds_read2_b32 v[132:133], v196 offset0:68 offset1:84
	ds_read_b32 v135, v190 offset:16640
	v_mul_f32 v124, v124, v206
	v_mul_f32 v125, v125, v206
	v_mul_f32 v126, v126, v206
	v_mul_f32 v127, v127, v206
	v_mul_f32 v116, v116, v206
	v_mul_f32 v117, v117, v206
	v_mul_f32 v120, v120, v206
	v_mul_f32 v121, v121, v206
	v_mul_f32 v96, v96, v206
	v_mul_f32 v97, v97, v206
	v_fma_f32 v124, v134, v112, v124
	v_fma_f32 v125, v134, v113, v125
	v_fma_f32 v155, v134, v155, v116
	v_fma_f32 v157, v134, v157, v117
	v_fma_f32 v200, v134, v200, v120
	v_fma_f32 v197, v134, v197, v121
	v_fma_f32 v202, v134, v202, v96
	v_fma_f32 v203, v134, v203, v97
	v_fma_f32 v92, v92, v124, v140
	v_fma_f32 v93, v93, v125, v140
	v_mul_f32 v118, v118, v206
	v_mul_f32 v119, v119, v206
	v_mul_f32 v122, v122, v206
	v_mul_f32 v123, v123, v206
	v_fma_f32 v84, v84, v155, v92
	v_fma_f32 v85, v85, v157, v93
	v_mul_f32 v98, v98, v206
	v_mul_f32 v99, v99, v206
	v_fma_f32 v126, v134, v114, v126
	v_fma_f32 v127, v134, v115, v127
	v_fma_f32 v76, v76, v200, v84
	v_fma_f32 v77, v77, v197, v85
	v_fma_f32 v199, v134, v199, v118
	v_fma_f32 v201, v134, v201, v119
	v_fma_f32 v156, v134, v156, v122
	v_fma_f32 v154, v134, v154, v123
	v_fma_f32 v68, v68, v202, v76
	v_fma_f32 v69, v69, v203, v77
	v_fma_f32 v204, v134, v204, v98
	v_fma_f32 v205, v134, v205, v99
	v_fma_f32 v94, v94, v126, v140
	v_fma_f32 v95, v95, v127, v140
	v_add_f32_e32 v68, v68, v69
	v_fma_f32 v86, v86, v199, v94
	v_fma_f32 v87, v87, v201, v95
	v_fma_f32 v78, v78, v156, v86
	v_fma_f32 v79, v79, v154, v87
	v_fma_f32 v70, v70, v204, v78
	v_fma_f32 v71, v71, v205, v79
	v_add_f32_e32 v69, v70, v71
	v_add_f32_e32 v68, v68, v69
	s_nop 1
	v_add_f32_dpp v68, v68, v68 row_ror:8 row_mask:0xf bank_mask:0xf bound_ctrl:1
	s_nop 1
	v_add_f32_dpp v68, v68, v68 row_ror:4 row_mask:0xf bank_mask:0xf bound_ctrl:1
	s_nop 1
	v_add_f32_dpp v68, v68, v68 row_ror:2 row_mask:0xf bank_mask:0xf bound_ctrl:1
	s_nop 1
	v_add_f32_dpp v68, v68, v68 row_ror:1 row_mask:0xf bank_mask:0xf bound_ctrl:1
	ds_write_b32 v190, v68 offset:34240
	s_waitcnt lgkmcnt(0)
	v_mul_f32_e32 v133, v133, v135
	ds_read_b128 v[92:95], v194 offset:5120
	ds_read_b128 v[84:87], v194 offset:5376
	ds_read_b128 v[120:123], v194 offset:13312
	ds_read_b128 v[112:115], v194 offset:13568
	ds_read_b128 v[76:79], v194 offset:5632
	ds_read_b128 v[68:71], v194 offset:5888
	ds_read_b128 v[116:119], v194 offset:13824
	ds_read_b128 v[96:99], v194 offset:14080
	ds_read2_b32 v[134:135], v196 offset0:69 offset1:85
	ds_read_b32 v207, v190 offset:16704
	v_mul_f32 v128, v128, v133
	v_mul_f32 v129, v129, v133
	v_mul_f32 v206, v130, v133
	v_mul_f32 v208, v131, v133
	v_mul_f32 v104, v104, v133
	v_mul_f32 v105, v105, v133
	v_mul_f32 v108, v108, v133
	v_mul_f32 v109, v109, v133
	v_mul_f32 v100, v100, v133
	v_mul_f32 v101, v101, v133
	v_fma_f32 v130, v132, v124, v128
	v_fma_f32 v131, v132, v125, v129
	v_fma_f32 v155, v132, v155, v104
	v_fma_f32 v157, v132, v157, v105
	v_fma_f32 v200, v132, v200, v108
	v_fma_f32 v197, v132, v197, v109
	v_fma_f32 v202, v132, v202, v100
	v_fma_f32 v203, v132, v203, v101
	v_fma_f32 v88, v88, v130, v140
	v_fma_f32 v89, v89, v131, v140
	v_mul_f32 v106, v106, v133
	v_mul_f32 v107, v107, v133
	v_mul_f32 v110, v110, v133
	v_mul_f32 v111, v111, v133
	v_fma_f32 v80, v80, v155, v88
	v_fma_f32 v81, v81, v157, v89
	v_mul_f32 v102, v102, v133
	v_mul_f32 v103, v103, v133
	v_fma_f32 v133, v132, v126, v206
	v_fma_f32 v206, v132, v127, v208
	v_fma_f32 v72, v72, v200, v80
	v_fma_f32 v73, v73, v197, v81
	v_fma_f32 v199, v132, v199, v106
	v_fma_f32 v201, v132, v201, v107
	v_fma_f32 v156, v132, v156, v110
	v_fma_f32 v154, v132, v154, v111
	v_fma_f32 v64, v64, v202, v72
	v_fma_f32 v65, v65, v203, v73
	v_fma_f32 v204, v132, v204, v102
	v_fma_f32 v132, v132, v205, v103
	v_fma_f32 v90, v90, v133, v140
	v_fma_f32 v91, v91, v206, v140
	v_add_f32_e32 v64, v64, v65
	v_fma_f32 v82, v82, v199, v90
	v_fma_f32 v83, v83, v201, v91
	v_fma_f32 v74, v74, v156, v82
	v_fma_f32 v75, v75, v154, v83
	v_fma_f32 v66, v66, v204, v74
	v_fma_f32 v67, v67, v132, v75
	v_add_f32_e32 v65, v66, v67
	v_add_f32_e32 v64, v64, v65
	s_nop 1
	v_add_f32_dpp v64, v64, v64 row_ror:8 row_mask:0xf bank_mask:0xf bound_ctrl:1
	s_nop 1
	v_add_f32_dpp v64, v64, v64 row_ror:4 row_mask:0xf bank_mask:0xf bound_ctrl:1
	s_nop 1
	v_add_f32_dpp v64, v64, v64 row_ror:2 row_mask:0xf bank_mask:0xf bound_ctrl:1
	s_nop 1
	v_add_f32_dpp v64, v64, v64 row_ror:1 row_mask:0xf bank_mask:0xf bound_ctrl:1
	ds_write_b32 v190, v64 offset:34304
	s_waitcnt lgkmcnt(0)
	v_mul_f32_e32 v135, v135, v207
	ds_read_b128 v[88:91], v194 offset:6144
	ds_read_b128 v[80:83], v194 offset:6400
	ds_read_b128 v[124:127], v194 offset:14336
	ds_read_b128 v[104:107], v194 offset:14592
	ds_read_b128 v[72:75], v194 offset:6656
	ds_read_b128 v[64:67], v194 offset:6912
	ds_read_b128 v[108:111], v194 offset:14848
	ds_read_b128 v[100:103], v194 offset:15104
	ds_read2_b32 v[128:129], v196 offset0:70 offset1:86
	ds_read_b32 v207, v190 offset:16768
	v_mul_f32 v120, v120, v135
	v_mul_f32 v121, v121, v135
	v_mul_f32 v122, v122, v135
	v_mul_f32 v123, v123, v135
	v_mul_f32 v112, v112, v135
	v_mul_f32 v113, v113, v135
	v_mul_f32 v114, v114, v135
	v_mul_f32 v115, v115, v135
	v_mul_f32 v116, v116, v135
	v_mul_f32 v117, v117, v135
	v_mul_f32 v118, v118, v135
	v_mul_f32 v119, v119, v135
	v_mul_f32 v96, v96, v135
	v_mul_f32 v97, v97, v135
	v_mul_f32 v98, v98, v135
	v_mul_f32 v99, v99, v135
	v_fma_f32 v135, v134, v130, v120
	v_fma_f32 v205, v134, v131, v121
	v_fma_f32 v155, v134, v155, v112
	v_fma_f32 v157, v134, v157, v113
	v_fma_f32 v200, v134, v200, v116
	v_fma_f32 v197, v134, v197, v117
	v_fma_f32 v202, v134, v202, v96
	v_fma_f32 v203, v134, v203, v97
	v_fma_f32 v92, v92, v135, v140
	v_fma_f32 v93, v93, v205, v140
	v_fma_f32 v133, v134, v133, v122
	v_fma_f32 v206, v134, v206, v123
	v_fma_f32 v199, v134, v199, v114
	v_fma_f32 v201, v134, v201, v115
	v_fma_f32 v84, v84, v155, v92
	v_fma_f32 v85, v85, v157, v93
	v_fma_f32 v156, v134, v156, v118
	v_fma_f32 v154, v134, v154, v119
	v_fma_f32 v204, v134, v204, v98
	v_fma_f32 v132, v134, v132, v99
	v_fma_f32 v76, v76, v200, v84
	v_fma_f32 v77, v77, v197, v85
	v_fma_f32 v94, v94, v133, v140
	v_fma_f32 v95, v95, v206, v140
	v_fma_f32 v68, v68, v202, v76
	v_fma_f32 v69, v69, v203, v77
	v_fma_f32 v86, v86, v199, v94
	v_fma_f32 v87, v87, v201, v95
	v_fma_f32 v78, v78, v156, v86
	v_fma_f32 v79, v79, v154, v87
	v_add_f32_e32 v68, v68, v69
	v_fma_f32 v70, v70, v204, v78
	v_fma_f32 v71, v71, v132, v79
	v_add_f32_e32 v69, v70, v71
	v_add_f32_e32 v68, v68, v69
	s_nop 1
	v_add_f32_dpp v68, v68, v68 row_ror:8 row_mask:0xf bank_mask:0xf bound_ctrl:1
	s_nop 1
	v_add_f32_dpp v68, v68, v68 row_ror:4 row_mask:0xf bank_mask:0xf bound_ctrl:1
	s_nop 1
	v_add_f32_dpp v68, v68, v68 row_ror:2 row_mask:0xf bank_mask:0xf bound_ctrl:1
	s_nop 1
	v_add_f32_dpp v68, v68, v68 row_ror:1 row_mask:0xf bank_mask:0xf bound_ctrl:1
	ds_write_b32 v190, v68 offset:34368
	s_waitcnt lgkmcnt(0)
	v_mul_f32_e32 v134, v129, v207
	ds_read_b128 v[92:95], v194 offset:7168
	ds_read_b128 v[84:87], v194 offset:7424
	ds_read_b128 v[120:123], v194 offset:15360
	ds_read_b128 v[112:115], v194 offset:15616
	ds_read_b128 v[76:79], v194 offset:7680
	ds_read_b128 v[68:71], v194 offset:7936
	ds_read_b128 v[116:119], v194 offset:15872
	ds_read_b128 v[96:99], v194 offset:16128
	ds_read2_b32 v[130:131], v196 offset0:71 offset1:87
	ds_read_b32 v129, v190 offset:16832
	v_mul_f32 v126, v126, v134
	v_mul_f32 v127, v127, v134
	v_mul_f32 v104, v104, v134
	v_mul_f32 v105, v105, v134
	v_mul_f32 v124, v124, v134
	v_mul_f32 v125, v125, v134
	v_mul_f32 v106, v106, v134
	v_mul_f32 v107, v107, v134
	v_mul_f32 v108, v108, v134
	v_mul_f32 v109, v109, v134
	v_mul_f32 v110, v110, v134
	v_mul_f32 v111, v111, v134
	v_mul_f32 v207, v100, v134
	v_mul_f32 v208, v101, v134
	v_mul_f32 v209, v102, v134
	v_mul_f32 v210, v103, v134
	v_fma_f32 v100, v128, v135, v124
	v_fma_f32 v101, v128, v205, v125
	v_fma_f32 v102, v128, v133, v126
	v_fma_f32 v103, v128, v206, v127
	v_fma_f32 v104, v128, v155, v104
	v_fma_f32 v105, v128, v157, v105
	v_fma_f32 v126, v128, v200, v108
	v_fma_f32 v127, v128, v197, v109
	v_fma_f32 v134, v128, v154, v111
	v_fma_f32 v135, v128, v202, v207
	v_fma_f32 v154, v128, v203, v208
	v_fma_f32 v88, v88, v100, v140
	v_fma_f32 v89, v89, v101, v140
	v_fma_f32 v124, v128, v199, v106
	v_fma_f32 v125, v128, v201, v107
	v_fma_f32 v133, v128, v156, v110
	v_fma_f32 v155, v128, v204, v209
	v_fma_f32 v80, v80, v104, v88
	v_fma_f32 v81, v81, v105, v89
	v_fma_f32 v128, v128, v132, v210
	v_fma_f32 v90, v90, v102, v140
	v_fma_f32 v91, v91, v103, v140
	v_fma_f32 v72, v72, v126, v80
	v_fma_f32 v73, v73, v127, v81
	v_fma_f32 v64, v64, v135, v72
	v_fma_f32 v65, v65, v154, v73
	v_fma_f32 v82, v82, v124, v90
	v_fma_f32 v83, v83, v125, v91
	v_fma_f32 v74, v74, v133, v82
	v_fma_f32 v75, v75, v134, v83
	v_add_f32_e32 v64, v64, v65
	v_fma_f32 v66, v66, v155, v74
	v_fma_f32 v67, v67, v128, v75
	v_add_f32_e32 v65, v66, v67
	v_add_f32_e32 v64, v64, v65
	s_nop 1
	v_add_f32_dpp v64, v64, v64 row_ror:8 row_mask:0xf bank_mask:0xf bound_ctrl:1
	s_nop 1
	v_add_f32_dpp v64, v64, v64 row_ror:4 row_mask:0xf bank_mask:0xf bound_ctrl:1
	s_nop 1
	v_add_f32_dpp v64, v64, v64 row_ror:2 row_mask:0xf bank_mask:0xf bound_ctrl:1
	s_nop 1
	v_add_f32_dpp v64, v64, v64 row_ror:1 row_mask:0xf bank_mask:0xf bound_ctrl:1
	ds_write_b32 v190, v64 offset:34432
	s_waitcnt lgkmcnt(0)
	v_mul_f32_e32 v64, v131, v129
	v_mul_f32 v65, v120, v64
	v_mul_f32 v66, v121, v64
	v_mul_f32 v67, v122, v64
	v_mul_f32 v72, v123, v64
	v_mul_f32 v73, v112, v64
	v_mul_f32 v74, v113, v64
	v_mul_f32 v75, v114, v64
	v_mul_f32 v80, v115, v64
	v_mul_f32 v81, v116, v64
	v_mul_f32 v82, v117, v64
	v_mul_f32 v83, v118, v64
	v_mul_f32 v88, v119, v64
	v_mul_f32 v89, v96, v64
	v_mul_f32 v90, v97, v64
	v_mul_f32 v112, v98, v64
	v_mul_f32 v64, v99, v64
	v_fma_f32 v111, v130, v100, v65
	v_fma_f32 v110, v130, v101, v66
	v_fma_f32 v96, v130, v134, v88
	v_fma_f32 v109, v130, v102, v67
	v_fma_f32 v108, v130, v103, v72
	v_fma_f32 v88, v130, v128, v64
	v_fma_f32 v64, v92, v111, v140
	v_fma_f32 v65, v93, v110, v140
	v_fma_f32 v107, v130, v104, v73
	v_fma_f32 v106, v130, v105, v74
	v_fma_f32 v66, v94, v109, v140
	v_fma_f32 v67, v95, v108, v140
	v_fma_f32 v105, v130, v124, v75
	v_fma_f32 v104, v130, v125, v80
	v_fma_f32 v64, v84, v107, v64
	v_fma_f32 v65, v85, v106, v65
	v_fma_f32 v99, v130, v126, v81
	v_fma_f32 v98, v130, v127, v82
	v_fma_f32 v66, v86, v105, v66
	v_fma_f32 v67, v87, v104, v67
	v_fma_f32 v97, v130, v133, v83
	v_fma_f32 v91, v130, v135, v89
	v_fma_f32 v64, v76, v99, v64
	v_fma_f32 v65, v77, v98, v65
	v_fma_f32 v90, v130, v154, v90
	v_fma_f32 v67, v79, v96, v67
	v_fma_f32 v66, v78, v97, v66
	v_fma_f32 v89, v130, v155, v112
	v_fma_f32 v64, v68, v91, v64
	v_fma_f32 v65, v69, v90, v65
	v_fma_f32 v67, v71, v88, v67
	v_fma_f32 v66, v70, v89, v66
	v_add_f32_e32 v64, v64, v65
	v_add_f32_e32 v65, v66, v67
	v_add_f32_e32 v64, v64, v65
	s_nop 1
	v_add_f32_dpp v64, v64, v64 row_ror:8 row_mask:0xf bank_mask:0xf bound_ctrl:1
	s_nop 1
	v_add_f32_dpp v64, v64, v64 row_ror:4 row_mask:0xf bank_mask:0xf bound_ctrl:1
	s_nop 1
	v_add_f32_dpp v64, v64, v64 row_ror:2 row_mask:0xf bank_mask:0xf bound_ctrl:1
	s_nop 1
	v_add_f32_dpp v64, v64, v64 row_ror:1 row_mask:0xf bank_mask:0xf bound_ctrl:1
	ds_write_b32 v190, v64 offset:34496
	s_waitcnt vmcnt(11)
	ds_write_b128 v188, v[16:19] offset:17024
	s_waitcnt vmcnt(9)
	ds_write_b128 v191, v[24:27] offset:17024
	ds_write_b128 v188, v[20:23] offset:25216
	s_waitcnt vmcnt(8)
	ds_write_b128 v191, v[28:31] offset:25216
	s_and_saveexec_b64 s[8:9], s[40:41]
	ds_write_b32 v145, v183 offset:33408
	s_or_b64 exec, exec, s[8:9]
	s_and_saveexec_b64 s[8:9], s[42:43]
	s_cbranch_execz .LBB0_1176
	v_add_f32_e32 v64, v178, v185
	v_mul_f32_e64 v65, |v64|, s62
	v_exp_f32_e32 v65, v65
	v_min_f32_e32 v64, 0, v64
	v_add_f32_e32 v65, 1.0, v65
	v_cmp_gt_f32_e32 vcc, s5, v65
	s_nop 1
	v_cndmask_b32_e64 v66, 0, 32, vcc
	v_ldexp_f32 v65, v65, v66
	v_log_f32_e32 v65, v65
	v_cndmask_b32_e32 v67, 0, v171, vcc
	v_add_f32_e32 v66, v147, v184
	v_mul_f32_e32 v68, 0x3f317217, v65
	v_fma_f32 v68, v65, s76, -v68
	v_fmac_f32_e32 v68, 0x3377d1cf, v65
	v_fmac_f32_e32 v68, 0x3f317217, v65
	v_cmp_lt_f32_e64 vcc, |v65|, s77
	s_nop 1
	v_cndmask_b32_e32 v65, v65, v68, vcc
	v_sub_f32_e32 v65, v65, v67
	v_sub_f32_e32 v64, v64, v65
	v_add_u32_e32 v65, 0x8400, v145
	ds_write2_b32 v65, v66, v64 offset0:32 offset1:48

.LBB0_1189:
	s_or_b64 exec, exec, s[8:9]
	s_waitcnt lgkmcnt(0)
	s_barrier
	ds_read_b128 v[92:95], v194 offset:17024
	ds_read_b128 v[112:115], v194 offset:17280
	ds_read_b128 v[124:127], v194 offset:25216
	ds_read_b128 v[132:135], v194 offset:25472
	ds_read2_b64 v[80:83], v196 offset0:32 offset1:40
	v_add_u32_e32 v197, 0x8000, v190
	ds_read2_b32 v[76:77], v197 offset0:160 offset1:176
	ds_read_b128 v[208:211], v194 offset:17536
	ds_read_b128 v[212:215], v194 offset:17792
	ds_read_b128 v[154:157], v194 offset:25728
	ds_read_b128 v[200:203], v194 offset:25984
	ds_read_b128 v[84:87], v194 offset:18048
	ds_read_b128 v[72:75], v194 offset:18304
	ds_read_b128 v[128:131], v194 offset:26240
	ds_read_b128 v[116:119], v194 offset:26496
	ds_read_b128 v[68:71], v194 offset:18560
	ds_read_b128 v[64:67], v194 offset:18816
	ds_read_b128 v[120:123], v194 offset:26752
	ds_read_b128 v[100:103], v194 offset:27008
	s_waitcnt lgkmcnt(12)
	v_mul_f32_e32 v76, v82, v76
	v_mul_f32 v78, v124, v76
	v_mul_f32 v79, v125, v76
	v_mul_f32 v124, v126, v76
	v_mul_f32 v125, v127, v76
	v_mul_f32 v126, v132, v76
	v_mul_f32 v127, v133, v76
	v_mul_f32 v199, v134, v76
	v_mul_f32 v204, v135, v76
	s_waitcnt lgkmcnt(9)
	v_mul_f32 v154, v154, v76
	v_mul_f32 v155, v155, v76
	v_mul_f32 v205, v156, v76
	v_mul_f32 v206, v157, v76
	s_waitcnt lgkmcnt(8)
	v_mul_f32 v207, v200, v76
	v_mul_f32 v216, v201, v76
	v_mul_f32 v217, v202, v76
	v_mul_f32 v76, v203, v76
	v_fma_f32 v82, v80, v111, v78
	v_fma_f32 v132, v80, v110, v79
	v_fma_f32 v133, v80, v109, v124
	v_fma_f32 v134, v80, v108, v125
	v_fma_f32 v135, v80, v107, v126
	v_fma_f32 v156, v80, v106, v127
	v_fma_f32 v157, v80, v105, v199
	v_fma_f32 v199, v80, v104, v204
	v_fma_f32 v200, v80, v99, v154
	v_fma_f32 v201, v80, v98, v155
	v_fma_f32 v202, v80, v97, v205
	v_fma_f32 v203, v80, v96, v206
	v_fma_f32 v204, v80, v91, v207
	v_fma_f32 v205, v80, v90, v216
	v_fma_f32 v206, v80, v89, v217
	v_fma_f32 v80, v80, v88, v76
	v_fma_f32 v76, v92, v82, v140
	v_fma_f32 v78, v93, v132, v140
	v_fma_f32 v79, v94, v133, v140
	v_fma_f32 v88, v95, v134, v140
	v_fma_f32 v76, v112, v135, v76
	v_fma_f32 v78, v113, v156, v78
	v_fma_f32 v79, v114, v157, v79
	v_fma_f32 v88, v115, v199, v88
	v_fma_f32 v76, v208, v200, v76
	v_fma_f32 v78, v209, v201, v78
	v_fma_f32 v79, v210, v202, v79
	v_fma_f32 v88, v211, v203, v88
	v_fma_f32 v76, v212, v204, v76
	v_fma_f32 v78, v213, v205, v78
	v_fma_f32 v79, v214, v206, v79
	v_fma_f32 v88, v215, v80, v88
	v_add_f32_e32 v76, v76, v78
	v_add_f32_e32 v78, v79, v88
	v_add_f32_e32 v76, v76, v78
	s_nop 1
	v_add_f32_dpp v76, v76, v76 row_ror:8 row_mask:0xf bank_mask:0xf bound_ctrl:1
	s_nop 1
	v_add_f32_dpp v76, v76, v76 row_ror:4 row_mask:0xf bank_mask:0xf bound_ctrl:1
	s_nop 1
	v_add_f32_dpp v76, v76, v76 row_ror:2 row_mask:0xf bank_mask:0xf bound_ctrl:1
	s_nop 1
	v_add_f32_dpp v76, v76, v76 row_ror:1 row_mask:0xf bank_mask:0xf bound_ctrl:1
	ds_write_b32 v190, v76 offset:34560
	v_mul_f32_e32 v207, v83, v77
	ds_read_b128 v[96:99], v194 offset:19072
	ds_read_b128 v[92:95], v194 offset:19328
	ds_read_b128 v[124:127], v194 offset:27264
	ds_read_b128 v[108:111], v194 offset:27520
	ds_read_b128 v[88:91], v194 offset:19584
	ds_read_b128 v[76:79], v194 offset:19840
	ds_read_b128 v[112:115], v194 offset:27776
	ds_read_b128 v[104:107], v194 offset:28032
	ds_read2_b32 v[154:155], v196 offset0:66 offset1:82
	ds_read_b32 v83, v190 offset:33536
	s_waitcnt lgkmcnt(14)
	v_mul_f32 v128, v128, v207
	v_mul_f32 v129, v129, v207
	v_mul_f32 v130, v130, v207
	v_mul_f32 v131, v131, v207
	v_mul_f32 v116, v116, v207
	v_mul_f32 v117, v117, v207
	v_mul_f32 v118, v118, v207
	v_mul_f32 v119, v119, v207
	s_waitcnt lgkmcnt(11)
	v_mul_f32 v120, v120, v207
	v_mul_f32 v121, v121, v207
	v_mul_f32 v122, v122, v207
	v_mul_f32 v123, v123, v207
	s_waitcnt lgkmcnt(10)
	v_mul_f32 v100, v100, v207
	v_mul_f32 v101, v101, v207
	v_mul_f32 v102, v102, v207
	v_mul_f32 v103, v103, v207
	v_fma_f32 v207, v81, v82, v128
	v_fma_f32 v208, v81, v132, v129
	v_fma_f32 v209, v81, v133, v130
	v_fma_f32 v210, v81, v134, v131
	v_fma_f32 v211, v81, v135, v116
	v_fma_f32 v212, v81, v156, v117
	v_fma_f32 v213, v81, v157, v118
	v_fma_f32 v199, v81, v199, v119
	v_fma_f32 v200, v81, v200, v120
	v_fma_f32 v201, v81, v201, v121
	v_fma_f32 v202, v81, v202, v122
	v_fma_f32 v203, v81, v203, v123
	v_fma_f32 v204, v81, v204, v100
	v_fma_f32 v205, v81, v205, v101
	v_fma_f32 v206, v81, v206, v102
	v_fma_f32 v214, v81, v80, v103
	v_fma_f32 v80, v84, v207, v140
	v_fma_f32 v81, v85, v208, v140
	v_fma_f32 v82, v86, v209, v140
	v_fma_f32 v84, v87, v210, v140
	v_fma_f32 v72, v72, v211, v80
	v_fma_f32 v73, v73, v212, v81
	v_fma_f32 v74, v74, v213, v82
	v_fma_f32 v75, v75, v199, v84
	v_fma_f32 v68, v68, v200, v72
	v_fma_f32 v69, v69, v201, v73
	v_fma_f32 v70, v70, v202, v74
	v_fma_f32 v71, v71, v203, v75
	v_fma_f32 v64, v64, v204, v68
	v_fma_f32 v65, v65, v205, v69
	v_fma_f32 v66, v66, v206, v70
	v_fma_f32 v67, v67, v214, v71
	v_add_f32_e32 v64, v64, v65
	v_add_f32_e32 v65, v66, v67
	v_add_f32_e32 v64, v64, v65
	s_nop 1
	v_add_f32_dpp v64, v64, v64 row_ror:8 row_mask:0xf bank_mask:0xf bound_ctrl:1
	s_nop 1
	v_add_f32_dpp v64, v64, v64 row_ror:4 row_mask:0xf bank_mask:0xf bound_ctrl:1
	s_nop 1
	v_add_f32_dpp v64, v64, v64 row_ror:2 row_mask:0xf bank_mask:0xf bound_ctrl:1
	s_nop 1
	v_add_f32_dpp v64, v64, v64 row_ror:1 row_mask:0xf bank_mask:0xf bound_ctrl:1
	ds_write_b32 v190, v64 offset:34624
	s_waitcnt lgkmcnt(0)
	v_mul_f32_e32 v69, v155, v83
	ds_read_b128 v[100:103], v194 offset:20096
	ds_read_b128 v[80:83], v194 offset:20352
	ds_read_b128 v[132:135], v194 offset:28288
	ds_read_b128 v[120:123], v194 offset:28544
	ds_read_b128 v[72:75], v194 offset:20608
	ds_read_b128 v[64:67], v194 offset:20864
	ds_read_b128 v[128:131], v194 offset:28800
	ds_read_b128 v[116:119], v194 offset:29056
	ds_read2_b32 v[156:157], v196 offset0:67 offset1:83
	ds_read_b32 v68, v190 offset:33600
	v_mul_f32 v70, v124, v69
	v_mul_f32 v71, v125, v69
	v_mul_f32 v84, v126, v69
	v_mul_f32 v85, v127, v69
	v_mul_f32 v86, v108, v69
	v_mul_f32 v87, v109, v69
	v_mul_f32 v108, v110, v69
	v_mul_f32 v109, v111, v69
	v_mul_f32 v110, v112, v69
	v_mul_f32 v111, v113, v69
	v_mul_f32 v124, v114, v69
	v_mul_f32 v125, v115, v69
	v_mul_f32 v104, v104, v69
	v_mul_f32 v105, v105, v69
	v_mul_f32 v106, v106, v69
	v_mul_f32 v69, v107, v69
	v_fma_f32 v112, v154, v207, v70
	v_fma_f32 v113, v154, v208, v71
	v_fma_f32 v115, v154, v210, v85
	v_fma_f32 v114, v154, v209, v84
	v_fma_f32 v207, v154, v211, v86
	v_fma_f32 v210, v154, v214, v69
	v_fma_f32 v69, v96, v112, v140
	v_fma_f32 v70, v97, v113, v140
	v_fma_f32 v208, v154, v212, v87
	v_fma_f32 v71, v98, v114, v140
	v_fma_f32 v209, v154, v213, v108
	v_fma_f32 v200, v154, v200, v110
	v_fma_f32 v69, v92, v207, v69
	v_fma_f32 v201, v154, v201, v111
	v_fma_f32 v70, v93, v208, v70
	v_fma_f32 v84, v99, v115, v140
	v_fma_f32 v71, v94, v209, v71
	v_fma_f32 v199, v154, v199, v109
	v_fma_f32 v69, v88, v200, v69
	v_fma_f32 v202, v154, v202, v124
	v_fma_f32 v70, v89, v201, v70
	v_fma_f32 v204, v154, v204, v104
	v_fma_f32 v205, v154, v205, v105
	v_fma_f32 v84, v95, v199, v84
	v_fma_f32 v203, v154, v203, v125
	v_fma_f32 v71, v90, v202, v71
	v_fma_f32 v206, v154, v206, v106
	v_fma_f32 v69, v76, v204, v69
	v_fma_f32 v70, v77, v205, v70
	v_fma_f32 v84, v91, v203, v84
	v_fma_f32 v71, v78, v206, v71
	v_fma_f32 v76, v79, v210, v84
	v_add_f32_e32 v69, v69, v70
	v_add_f32_e32 v70, v71, v76
	v_add_f32_e32 v69, v69, v70
	s_nop 1
	v_add_f32_dpp v69, v69, v69 row_ror:8 row_mask:0xf bank_mask:0xf bound_ctrl:1
	s_nop 1
	v_add_f32_dpp v69, v69, v69 row_ror:4 row_mask:0xf bank_mask:0xf bound_ctrl:1
	s_nop 1
	v_add_f32_dpp v69, v69, v69 row_ror:2 row_mask:0xf bank_mask:0xf bound_ctrl:1
	s_nop 1
	v_add_f32_dpp v69, v69, v69 row_ror:1 row_mask:0xf bank_mask:0xf bound_ctrl:1
	ds_write_b32 v190, v69 offset:34688
	s_waitcnt lgkmcnt(0)
	v_mul_f32_e32 v93, v157, v68
	ds_read_b128 v[88:91], v194 offset:21120
	ds_read_b128 v[84:87], v194 offset:21376
	ds_read_b128 v[124:127], v194 offset:29312
	ds_read_b128 v[104:107], v194 offset:29568
	ds_read_b128 v[76:79], v194 offset:21632
	ds_read_b128 v[68:71], v194 offset:21888
	ds_read_b128 v[108:111], v194 offset:29824
	ds_read_b128 v[96:99], v194 offset:30080
	ds_read2_b32 v[154:155], v196 offset0:68 offset1:84
	ds_read_b32 v92, v190 offset:33664
	v_mul_f32 v94, v132, v93
	v_mul_f32 v95, v133, v93
	v_mul_f32 v132, v134, v93
	v_mul_f32 v133, v135, v93
	v_mul_f32 v120, v120, v93
	v_mul_f32 v121, v121, v93
	v_mul_f32 v122, v122, v93
	v_mul_f32 v123, v123, v93
	v_mul_f32 v128, v128, v93
	v_mul_f32 v129, v129, v93
	v_mul_f32 v211, v130, v93
	v_mul_f32 v212, v131, v93
	v_mul_f32 v116, v116, v93
	v_mul_f32 v117, v117, v93
	v_mul_f32 v118, v118, v93
	v_mul_f32 v93, v119, v93
	v_fma_f32 v130, v156, v112, v94
	v_fma_f32 v131, v156, v113, v95
	v_fma_f32 v132, v156, v114, v132
	v_fma_f32 v133, v156, v115, v133
	v_fma_f32 v134, v156, v207, v120
	v_fma_f32 v135, v156, v208, v121
	v_fma_f32 v157, v156, v209, v122
	v_fma_f32 v199, v156, v199, v123
	v_fma_f32 v200, v156, v200, v128
	v_fma_f32 v201, v156, v201, v129
	v_fma_f32 v202, v156, v202, v211
	v_fma_f32 v203, v156, v203, v212
	v_fma_f32 v204, v156, v204, v116
	v_fma_f32 v205, v156, v205, v117
	v_fma_f32 v206, v156, v206, v118
	v_fma_f32 v156, v156, v210, v93
	v_fma_f32 v93, v100, v130, v140
	v_fma_f32 v94, v101, v131, v140
	v_fma_f32 v95, v102, v132, v140
	v_fma_f32 v100, v103, v133, v140
	v_fma_f32 v80, v80, v134, v93
	v_fma_f32 v81, v81, v135, v94
	v_fma_f32 v82, v82, v157, v95
	v_fma_f32 v83, v83, v199, v100
	v_fma_f32 v72, v72, v200, v80
	v_fma_f32 v73, v73, v201, v81
	v_fma_f32 v74, v74, v202, v82
	v_fma_f32 v75, v75, v203, v83
	v_fma_f32 v64, v64, v204, v72
	v_fma_f32 v65, v65, v205, v73
	v_fma_f32 v66, v66, v206, v74
	v_fma_f32 v67, v67, v156, v75
	v_add_f32_e32 v64, v64, v65
	v_add_f32_e32 v65, v66, v67
	v_add_f32_e32 v64, v64, v65
	s_nop 1
	v_add_f32_dpp v64, v64, v64 row_ror:8 row_mask:0xf bank_mask:0xf bound_ctrl:1
	s_nop 1
	v_add_f32_dpp v64, v64, v64 row_ror:4 row_mask:0xf bank_mask:0xf bound_ctrl:1
	s_nop 1
	v_add_f32_dpp v64, v64, v64 row_ror:2 row_mask:0xf bank_mask:0xf bound_ctrl:1
	s_nop 1
	v_add_f32_dpp v64, v64, v64 row_ror:1 row_mask:0xf bank_mask:0xf bound_ctrl:1
	ds_write_b32 v190, v64 offset:34752
	s_waitcnt lgkmcnt(0)
	v_mul_f32_e32 v155, v155, v92
	ds_read_b128 v[92:95], v194 offset:22144
	ds_read_b128 v[80:83], v194 offset:22400
	ds_read_b128 v[120:123], v194 offset:30336
	ds_read_b128 v[112:115], v194 offset:30592
	ds_read_b128 v[72:75], v194 offset:22656
	ds_read_b128 v[64:67], v194 offset:22912
	ds_read_b128 v[116:119], v194 offset:30848
	ds_read_b128 v[100:103], v194 offset:31104
	ds_read2_b32 v[128:129], v196 offset0:69 offset1:85
	ds_read_b32 v208, v190 offset:33728
	v_mul_f32 v124, v124, v155
	v_mul_f32 v125, v125, v155
	v_mul_f32 v126, v126, v155
	v_mul_f32 v127, v127, v155
	v_mul_f32 v104, v104, v155
	v_mul_f32 v105, v105, v155
	v_mul_f32 v106, v106, v155
	v_mul_f32 v107, v107, v155
	v_mul_f32 v108, v108, v155
	v_mul_f32 v109, v109, v155
	v_mul_f32 v110, v110, v155
	v_mul_f32 v111, v111, v155
	v_mul_f32 v96, v96, v155
	v_mul_f32 v97, v97, v155
	v_mul_f32 v98, v98, v155
	v_mul_f32 v99, v99, v155
	v_fma_f32 v155, v154, v130, v124
	v_fma_f32 v207, v154, v131, v125
	v_fma_f32 v134, v154, v134, v104
	v_fma_f32 v135, v154, v135, v105
	v_fma_f32 v200, v154, v200, v108
	v_fma_f32 v201, v154, v201, v109
	v_fma_f32 v204, v154, v204, v96
	v_fma_f32 v205, v154, v205, v97
	v_fma_f32 v88, v88, v155, v140
	v_fma_f32 v89, v89, v207, v140
	v_fma_f32 v132, v154, v132, v126
	v_fma_f32 v133, v154, v133, v127
	v_fma_f32 v157, v154, v157, v106
	v_fma_f32 v199, v154, v199, v107
	v_fma_f32 v84, v84, v134, v88
	v_fma_f32 v85, v85, v135, v89
	v_fma_f32 v202, v154, v202, v110
	v_fma_f32 v203, v154, v203, v111
	v_fma_f32 v206, v154, v206, v98
	v_fma_f32 v154, v154, v156, v99
	v_fma_f32 v76, v76, v200, v84
	v_fma_f32 v77, v77, v201, v85
	v_fma_f32 v90, v90, v132, v140
	v_fma_f32 v91, v91, v133, v140
	v_fma_f32 v68, v68, v204, v76
	v_fma_f32 v69, v69, v205, v77
	v_fma_f32 v86, v86, v157, v90
	v_fma_f32 v87, v87, v199, v91
	v_fma_f32 v78, v78, v202, v86
	v_fma_f32 v79, v79, v203, v87
	v_add_f32_e32 v68, v68, v69
	v_fma_f32 v70, v70, v206, v78
	v_fma_f32 v71, v71, v154, v79
	v_add_f32_e32 v69, v70, v71
	v_add_f32_e32 v68, v68, v69
	s_nop 1
	v_add_f32_dpp v68, v68, v68 row_ror:8 row_mask:0xf bank_mask:0xf bound_ctrl:1
	s_nop 1
	v_add_f32_dpp v68, v68, v68 row_ror:4 row_mask:0xf bank_mask:0xf bound_ctrl:1
	s_nop 1
	v_add_f32_dpp v68, v68, v68 row_ror:2 row_mask:0xf bank_mask:0xf bound_ctrl:1
	s_nop 1
	v_add_f32_dpp v68, v68, v68 row_ror:1 row_mask:0xf bank_mask:0xf bound_ctrl:1
	ds_write_b32 v190, v68 offset:34816
	s_waitcnt lgkmcnt(0)
	v_mul_f32_e32 v156, v129, v208
	ds_read_b128 v[88:91], v194 offset:23168
	ds_read_b128 v[84:87], v194 offset:23424
	ds_read_b128 v[124:127], v194 offset:31360
	ds_read_b128 v[104:107], v194 offset:31616
	ds_read_b128 v[76:79], v194 offset:23680
	ds_read_b128 v[68:71], v194 offset:23936
	ds_read_b128 v[108:111], v194 offset:31872
	ds_read_b128 v[96:99], v194 offset:32128
	ds_read2_b32 v[130:131], v196 offset0:70 offset1:86
	ds_read_b32 v129, v190 offset:33792
	v_mul_f32 v120, v120, v156
	v_mul_f32 v121, v121, v156
	v_mul_f32 v122, v122, v156
	v_mul_f32 v123, v123, v156
	v_mul_f32 v112, v112, v156
	v_mul_f32 v113, v113, v156
	v_mul_f32 v114, v114, v156
	v_mul_f32 v115, v115, v156
	v_mul_f32 v116, v116, v156
	v_mul_f32 v117, v117, v156
	v_mul_f32 v118, v118, v156
	v_mul_f32 v119, v119, v156
	v_mul_f32 v100, v100, v156
	v_mul_f32 v101, v101, v156
	v_mul_f32 v102, v102, v156
	v_mul_f32 v103, v103, v156
	v_fma_f32 v155, v128, v155, v120
	v_fma_f32 v156, v128, v207, v121
	v_fma_f32 v134, v128, v134, v112
	v_fma_f32 v135, v128, v135, v113
	v_fma_f32 v200, v128, v200, v116
	v_fma_f32 v201, v128, v201, v117
	v_fma_f32 v204, v128, v204, v100
	v_fma_f32 v205, v128, v205, v101
	v_fma_f32 v92, v92, v155, v140
	v_fma_f32 v93, v93, v156, v140
	v_fma_f32 v132, v128, v132, v122
	v_fma_f32 v133, v128, v133, v123
	v_fma_f32 v157, v128, v157, v114
	v_fma_f32 v199, v128, v199, v115
	v_fma_f32 v80, v80, v134, v92
	v_fma_f32 v81, v81, v135, v93
	v_fma_f32 v202, v128, v202, v118
	v_fma_f32 v203, v128, v203, v119
	v_fma_f32 v206, v128, v206, v102
	v_fma_f32 v154, v128, v154, v103
	v_fma_f32 v72, v72, v200, v80
	v_fma_f32 v73, v73, v201, v81
	v_fma_f32 v94, v94, v132, v140
	v_fma_f32 v95, v95, v133, v140
	v_fma_f32 v64, v64, v204, v72
	v_fma_f32 v65, v65, v205, v73
	v_fma_f32 v82, v82, v157, v94
	v_fma_f32 v83, v83, v199, v95
	v_fma_f32 v74, v74, v202, v82
	v_fma_f32 v75, v75, v203, v83
	v_add_f32_e32 v64, v64, v65
	v_fma_f32 v66, v66, v206, v74
	v_fma_f32 v67, v67, v154, v75
	v_add_f32_e32 v65, v66, v67
	v_add_f32_e32 v64, v64, v65
	s_nop 1
	v_add_f32_dpp v64, v64, v64 row_ror:8 row_mask:0xf bank_mask:0xf bound_ctrl:1
	s_nop 1
	v_add_f32_dpp v64, v64, v64 row_ror:4 row_mask:0xf bank_mask:0xf bound_ctrl:1
	s_nop 1
	v_add_f32_dpp v64, v64, v64 row_ror:2 row_mask:0xf bank_mask:0xf bound_ctrl:1
	s_nop 1
	v_add_f32_dpp v64, v64, v64 row_ror:1 row_mask:0xf bank_mask:0xf bound_ctrl:1
	ds_write_b32 v190, v64 offset:34880
	s_waitcnt lgkmcnt(0)
	v_mul_f32_e32 v207, v131, v129
	ds_read_b128 v[92:95], v194 offset:24192
	ds_read_b128 v[80:83], v194 offset:24448
	ds_read_b128 v[120:123], v194 offset:32384
	ds_read_b128 v[112:115], v194 offset:32640
	ds_read_b128 v[72:75], v194 offset:24704
	ds_read_b128 v[64:67], v194 offset:24960
	ds_read_b128 v[116:119], v194 offset:32896
	ds_read_b128 v[100:103], v194 offset:33152
	ds_read2_b32 v[128:129], v196 offset0:71 offset1:87
	ds_read_b32 v131, v190 offset:33856
	v_mul_f32 v125, v125, v207
	v_mul_f32 v126, v126, v207
	v_mul_f32 v104, v104, v207
	v_mul_f32 v124, v124, v207
	v_mul_f32 v127, v127, v207
	v_mul_f32 v105, v105, v207
	v_mul_f32 v106, v106, v207
	v_mul_f32 v107, v107, v207
	v_mul_f32 v108, v108, v207
	v_mul_f32 v109, v109, v207
	v_mul_f32 v208, v110, v207
	v_mul_f32 v209, v111, v207
	v_mul_f32 v210, v96, v207
	v_mul_f32 v211, v97, v207
	v_mul_f32 v212, v98, v207
	v_mul_f32 v207, v99, v207
	v_fma_f32 v96, v130, v155, v124
	v_fma_f32 v97, v130, v156, v125
	v_fma_f32 v98, v130, v132, v126
	v_fma_f32 v99, v130, v133, v127
	v_fma_f32 v104, v130, v134, v104
	v_fma_f32 v110, v130, v135, v105
	v_fma_f32 v125, v130, v200, v108
	v_fma_f32 v126, v130, v201, v109
	v_fma_f32 v133, v130, v204, v210
	v_fma_f32 v134, v130, v205, v211
	v_fma_f32 v88, v88, v96, v140
	v_fma_f32 v89, v89, v97, v140
	v_fma_f32 v111, v130, v157, v106
	v_fma_f32 v124, v130, v199, v107
	v_fma_f32 v127, v130, v202, v208
	v_fma_f32 v132, v130, v203, v209
	v_fma_f32 v84, v84, v104, v88
	v_fma_f32 v85, v85, v110, v89
	v_fma_f32 v135, v130, v206, v212
	v_fma_f32 v130, v130, v154, v207
	v_fma_f32 v90, v90, v98, v140
	v_fma_f32 v91, v91, v99, v140
	v_fma_f32 v76, v76, v125, v84
	v_fma_f32 v77, v77, v126, v85
	v_fma_f32 v68, v68, v133, v76
	v_fma_f32 v69, v69, v134, v77
	v_fma_f32 v86, v86, v111, v90
	v_fma_f32 v87, v87, v124, v91
	v_fma_f32 v78, v78, v127, v86
	v_fma_f32 v79, v79, v132, v87
	v_add_f32_e32 v68, v68, v69
	v_fma_f32 v70, v70, v135, v78
	v_fma_f32 v71, v71, v130, v79
	v_add_f32_e32 v69, v70, v71
	v_add_f32_e32 v68, v68, v69
	s_nop 1
	v_add_f32_dpp v68, v68, v68 row_ror:8 row_mask:0xf bank_mask:0xf bound_ctrl:1
	s_nop 1
	v_add_f32_dpp v68, v68, v68 row_ror:4 row_mask:0xf bank_mask:0xf bound_ctrl:1
	s_nop 1
	v_add_f32_dpp v68, v68, v68 row_ror:2 row_mask:0xf bank_mask:0xf bound_ctrl:1
	s_nop 1
	v_add_f32_dpp v68, v68, v68 row_ror:1 row_mask:0xf bank_mask:0xf bound_ctrl:1
	ds_write_b32 v190, v68 offset:34944
	s_waitcnt lgkmcnt(0)
	v_mul_f32_e32 v68, v129, v131
	v_mul_f32 v69, v120, v68
	v_mul_f32 v70, v121, v68
	v_mul_f32 v71, v122, v68
	v_mul_f32 v76, v123, v68
	v_mul_f32 v77, v112, v68
	v_mul_f32 v78, v113, v68
	v_mul_f32 v79, v114, v68
	v_mul_f32 v84, v115, v68
	v_mul_f32 v85, v116, v68
	v_mul_f32 v86, v117, v68
	v_mul_f32 v87, v118, v68
	v_mul_f32 v88, v119, v68
	v_mul_f32 v89, v100, v68
	v_mul_f32 v100, v101, v68
	v_mul_f32 v101, v102, v68
	v_mul_f32 v68, v103, v68
	v_fma_f32 v109, v128, v96, v69
	v_fma_f32 v108, v128, v97, v70
	v_fma_f32 v105, v128, v104, v77
	v_fma_f32 v104, v128, v110, v78
	v_fma_f32 v107, v128, v98, v71
	v_fma_f32 v78, v128, v130, v68
	v_fma_f32 v68, v92, v109, v140
	v_fma_f32 v69, v93, v108, v140
	v_fma_f32 v106, v128, v99, v76
	v_fma_f32 v99, v128, v111, v79
	v_fma_f32 v70, v94, v107, v140
	v_fma_f32 v98, v128, v124, v84
	v_fma_f32 v68, v80, v105, v68
	v_fma_f32 v69, v81, v104, v69
	v_fma_f32 v71, v95, v106, v140
	v_fma_f32 v97, v128, v125, v85
	v_fma_f32 v96, v128, v126, v86
	v_fma_f32 v90, v128, v132, v88
	v_fma_f32 v89, v128, v133, v89
	v_fma_f32 v88, v128, v134, v100
	v_fma_f32 v70, v82, v99, v70
	v_fma_f32 v71, v83, v98, v71
	v_fma_f32 v68, v72, v97, v68
	v_fma_f32 v69, v73, v96, v69
	v_fma_f32 v91, v128, v127, v87
	v_fma_f32 v79, v128, v135, v101
	v_fma_f32 v71, v75, v90, v71
	v_fma_f32 v64, v64, v89, v68
	v_fma_f32 v65, v65, v88, v69
	v_fma_f32 v70, v74, v91, v70
	v_fma_f32 v66, v66, v79, v70
	v_fma_f32 v67, v67, v78, v71
	v_add_f32_e32 v64, v64, v65
	v_add_f32_e32 v65, v66, v67
	v_add_f32_e32 v64, v64, v65
	s_nop 1
	v_add_f32_dpp v64, v64, v64 row_ror:8 row_mask:0xf bank_mask:0xf bound_ctrl:1
	s_nop 1
	v_add_f32_dpp v64, v64, v64 row_ror:4 row_mask:0xf bank_mask:0xf bound_ctrl:1
	s_nop 1
	v_add_f32_dpp v64, v64, v64 row_ror:2 row_mask:0xf bank_mask:0xf bound_ctrl:1
	s_nop 1
	v_add_f32_dpp v64, v64, v64 row_ror:1 row_mask:0xf bank_mask:0xf bound_ctrl:1
	ds_write_b32 v190, v64 offset:35008
	s_waitcnt vmcnt(7)
	ds_write_b128 v188, v[32:35]
	s_waitcnt vmcnt(5)
	ds_write_b128 v191, v[40:43]
	ds_write_b128 v188, v[36:39] offset:8192
	s_waitcnt vmcnt(4)
	ds_write_b128 v191, v[44:47] offset:8192
	s_and_saveexec_b64 s[8:9], s[40:41]
	ds_write_b32 v145, v186 offset:16384
	s_or_b64 exec, exec, s[8:9]
	s_and_saveexec_b64 s[8:9], s[42:43]
	s_cbranch_execz .LBB0_1209
	v_add_f32_e32 v64, v178, v189
	v_mul_f32_e64 v65, |v64|, s62
	v_exp_f32_e32 v65, v65
	v_min_f32_e32 v64, 0, v64
	v_add_f32_e32 v65, 1.0, v65
	v_cmp_gt_f32_e32 vcc, s5, v65
	s_nop 1
	v_cndmask_b32_e64 v66, 0, 32, vcc
	v_ldexp_f32 v65, v65, v66
	v_log_f32_e32 v65, v65
	v_cndmask_b32_e32 v67, 0, v171, vcc
	v_add_f32_e32 v66, v147, v187
	v_mul_f32_e32 v68, 0x3f317217, v65
	v_fma_f32 v68, v65, s76, -v68
	v_fmac_f32_e32 v68, 0x3377d1cf, v65
	v_fmac_f32_e32 v68, 0x3f317217, v65
	v_cmp_lt_f32_e64 vcc, |v65|, s77
	s_nop 1
	v_cndmask_b32_e32 v65, v65, v68, vcc
	v_sub_f32_e32 v65, v65, v67
	v_sub_f32_e32 v64, v64, v65
	v_add_u32_e32 v65, 0x4000, v145
	ds_write2_b32 v65, v66, v64 offset0:128 offset1:144

.LBB0_1222:
	s_or_b64 exec, exec, s[8:9]
	s_waitcnt lgkmcnt(0)
	s_barrier
	ds_read_b128 v[92:95], v194
	ds_read_b128 v[110:113], v194 offset:256
	ds_read_b128 v[124:127], v194 offset:8192
	ds_read_b128 v[132:135], v194 offset:8448
	ds_read2_b64 v[80:83], v196 offset0:32 offset1:40
	ds_read2_b32 v[76:77], v198 offset1:16
	ds_read_b128 v[206:209], v194 offset:512
	ds_read_b128 v[210:213], v194 offset:768
	ds_read_b128 v[154:157], v194 offset:8704
	ds_read_b128 v[198:201], v194 offset:8960
	s_waitcnt lgkmcnt(4)
	v_mul_f32_e32 v76, v82, v76
	v_mul_f32 v82, v124, v76
	v_mul_f32 v114, v125, v76
	v_mul_f32 v115, v126, v76
	v_mul_f32 v124, v127, v76
	v_mul_f32 v125, v132, v76
	v_mul_f32 v126, v133, v76
	v_mul_f32 v127, v134, v76
	v_mul_f32 v202, v135, v76
	s_waitcnt lgkmcnt(1)
	v_mul_f32 v154, v154, v76
	v_mul_f32 v155, v155, v76
	v_mul_f32 v203, v156, v76
	v_mul_f32 v204, v157, v76
	s_waitcnt lgkmcnt(0)
	v_mul_f32 v205, v198, v76
	v_mul_f32 v214, v199, v76
	v_mul_f32 v215, v200, v76
	v_mul_f32 v76, v201, v76
	ds_read_b128 v[84:87], v194 offset:1024
	ds_read_b128 v[72:75], v194 offset:1280
	ds_read_b128 v[128:131], v194 offset:9216
	ds_read_b128 v[116:119], v194 offset:9472
	ds_read_b128 v[68:71], v194 offset:1536
	ds_read_b128 v[64:67], v194 offset:1792
	ds_read_b128 v[120:123], v194 offset:9728
	ds_read_b128 v[100:103], v194 offset:9984
	v_fma_f32 v82, v80, v109, v82
	v_fma_f32 v132, v80, v108, v114
	v_fma_f32 v133, v80, v107, v115
	v_fma_f32 v134, v80, v106, v124
	v_fma_f32 v135, v80, v105, v125
	v_fma_f32 v156, v80, v104, v126
	v_fma_f32 v157, v80, v99, v127
	v_fma_f32 v198, v80, v98, v202
	v_fma_f32 v199, v80, v97, v154
	v_fma_f32 v200, v80, v96, v155
	v_fma_f32 v201, v80, v91, v203
	v_fma_f32 v202, v80, v90, v204
	v_fma_f32 v203, v80, v89, v205
	v_fma_f32 v204, v80, v88, v214
	v_fma_f32 v205, v80, v79, v215
	v_fma_f32 v80, v80, v78, v76
	v_fma_f32 v76, v92, v82, v140
	v_fma_f32 v78, v93, v132, v140
	v_fma_f32 v79, v94, v133, v140
	v_fma_f32 v88, v95, v134, v140
	v_fma_f32 v76, v110, v135, v76
	v_fma_f32 v78, v111, v156, v78
	v_fma_f32 v79, v112, v157, v79
	v_fma_f32 v88, v113, v198, v88
	v_fma_f32 v76, v206, v199, v76
	v_fma_f32 v78, v207, v200, v78
	v_fma_f32 v79, v208, v201, v79
	v_fma_f32 v88, v209, v202, v88
	v_fma_f32 v76, v210, v203, v76
	v_fma_f32 v78, v211, v204, v78
	v_fma_f32 v79, v212, v205, v79
	v_fma_f32 v88, v213, v80, v88
	v_add_f32_e32 v76, v76, v78
	v_add_f32_e32 v78, v79, v88
	v_add_f32_e32 v76, v76, v78
	s_nop 1
	v_add_f32_dpp v76, v76, v76 row_ror:8 row_mask:0xf bank_mask:0xf bound_ctrl:1
	s_nop 1
	v_add_f32_dpp v76, v76, v76 row_ror:4 row_mask:0xf bank_mask:0xf bound_ctrl:1
	s_nop 1
	v_add_f32_dpp v76, v76, v76 row_ror:2 row_mask:0xf bank_mask:0xf bound_ctrl:1
	s_nop 1
	v_add_f32_dpp v76, v76, v76 row_ror:1 row_mask:0xf bank_mask:0xf bound_ctrl:1
	ds_write_b32 v190, v76 offset:34048
	v_mul_f32_e32 v206, v83, v77
	ds_read_b128 v[96:99], v194 offset:2048
	ds_read_b128 v[92:95], v194 offset:2304
	ds_read_b128 v[124:127], v194 offset:10240
	ds_read_b128 v[108:111], v194 offset:10496
	ds_read_b128 v[88:91], v194 offset:2560
	ds_read_b128 v[76:79], v194 offset:2816
	ds_read_b128 v[112:115], v194 offset:10752
	ds_read_b128 v[104:107], v194 offset:11008
	ds_read2_b32 v[154:155], v196 offset0:66 offset1:82
	ds_read_b32 v83, v190 offset:16512
	s_waitcnt lgkmcnt(14)
	v_mul_f32 v128, v128, v206
	v_mul_f32 v129, v129, v206
	v_mul_f32 v130, v130, v206
	v_mul_f32 v131, v131, v206
	v_mul_f32 v116, v116, v206
	v_mul_f32 v117, v117, v206
	v_mul_f32 v118, v118, v206
	v_mul_f32 v119, v119, v206
	s_waitcnt lgkmcnt(11)
	v_mul_f32 v120, v120, v206
	v_mul_f32 v121, v121, v206
	v_mul_f32 v122, v122, v206
	v_mul_f32 v123, v123, v206
	s_waitcnt lgkmcnt(10)
	v_mul_f32 v100, v100, v206
	v_mul_f32 v101, v101, v206
	v_mul_f32 v102, v102, v206
	v_mul_f32 v103, v103, v206
	v_fma_f32 v206, v81, v82, v128
	v_fma_f32 v207, v81, v132, v129
	v_fma_f32 v208, v81, v133, v130
	v_fma_f32 v209, v81, v134, v131
	v_fma_f32 v210, v81, v135, v116
	v_fma_f32 v211, v81, v156, v117
	v_fma_f32 v212, v81, v157, v118
	v_fma_f32 v198, v81, v198, v119
	v_fma_f32 v199, v81, v199, v120
	v_fma_f32 v200, v81, v200, v121
	v_fma_f32 v201, v81, v201, v122
	v_fma_f32 v202, v81, v202, v123
	v_fma_f32 v203, v81, v203, v100
	v_fma_f32 v204, v81, v204, v101
	v_fma_f32 v205, v81, v205, v102
	v_fma_f32 v213, v81, v80, v103
	v_fma_f32 v80, v84, v206, v140
	v_fma_f32 v81, v85, v207, v140
	v_fma_f32 v82, v86, v208, v140
	v_fma_f32 v84, v87, v209, v140
	v_fma_f32 v72, v72, v210, v80
	v_fma_f32 v73, v73, v211, v81
	v_fma_f32 v74, v74, v212, v82
	v_fma_f32 v75, v75, v198, v84
	v_fma_f32 v68, v68, v199, v72
	v_fma_f32 v69, v69, v200, v73
	v_fma_f32 v70, v70, v201, v74
	v_fma_f32 v71, v71, v202, v75
	v_fma_f32 v64, v64, v203, v68
	v_fma_f32 v65, v65, v204, v69
	v_fma_f32 v66, v66, v205, v70
	v_fma_f32 v67, v67, v213, v71
	v_add_f32_e32 v64, v64, v65
	v_add_f32_e32 v65, v66, v67
	v_add_f32_e32 v64, v64, v65
	s_nop 1
	v_add_f32_dpp v64, v64, v64 row_ror:8 row_mask:0xf bank_mask:0xf bound_ctrl:1
	s_nop 1
	v_add_f32_dpp v64, v64, v64 row_ror:4 row_mask:0xf bank_mask:0xf bound_ctrl:1
	s_nop 1
	v_add_f32_dpp v64, v64, v64 row_ror:2 row_mask:0xf bank_mask:0xf bound_ctrl:1
	s_nop 1
	v_add_f32_dpp v64, v64, v64 row_ror:1 row_mask:0xf bank_mask:0xf bound_ctrl:1
	ds_write_b32 v190, v64 offset:34112
	s_waitcnt lgkmcnt(0)
	v_mul_f32_e32 v69, v155, v83
	ds_read_b128 v[100:103], v194 offset:3072
	ds_read_b128 v[80:83], v194 offset:3328
	ds_read_b128 v[132:135], v194 offset:11264
	ds_read_b128 v[120:123], v194 offset:11520
	ds_read_b128 v[72:75], v194 offset:3584
	ds_read_b128 v[64:67], v194 offset:3840
	ds_read_b128 v[128:131], v194 offset:11776
	ds_read_b128 v[116:119], v194 offset:12032
	ds_read2_b32 v[156:157], v196 offset0:67 offset1:83
	ds_read_b32 v68, v190 offset:16576
	v_mul_f32 v70, v124, v69
	v_mul_f32 v71, v125, v69
	v_mul_f32 v84, v126, v69
	v_mul_f32 v85, v127, v69
	v_mul_f32 v86, v108, v69
	v_mul_f32 v87, v109, v69
	v_mul_f32 v108, v110, v69
	v_mul_f32 v109, v111, v69
	v_mul_f32 v110, v112, v69
	v_mul_f32 v111, v113, v69
	v_mul_f32 v124, v114, v69
	v_mul_f32 v125, v115, v69
	v_mul_f32 v104, v104, v69
	v_mul_f32 v105, v105, v69
	v_mul_f32 v106, v106, v69
	v_mul_f32 v69, v107, v69
	v_fma_f32 v112, v154, v206, v70
	v_fma_f32 v113, v154, v207, v71
	v_fma_f32 v115, v154, v209, v85
	v_fma_f32 v114, v154, v208, v84
	v_fma_f32 v206, v154, v210, v86
	v_fma_f32 v209, v154, v213, v69
	v_fma_f32 v69, v96, v112, v140
	v_fma_f32 v70, v97, v113, v140
	v_fma_f32 v207, v154, v211, v87
	v_fma_f32 v71, v98, v114, v140
	v_fma_f32 v208, v154, v212, v108
	v_fma_f32 v199, v154, v199, v110
	v_fma_f32 v69, v92, v206, v69
	v_fma_f32 v200, v154, v200, v111
	v_fma_f32 v70, v93, v207, v70
	v_fma_f32 v84, v99, v115, v140
	v_fma_f32 v71, v94, v208, v71
	v_fma_f32 v198, v154, v198, v109
	v_fma_f32 v69, v88, v199, v69
	v_fma_f32 v201, v154, v201, v124
	v_fma_f32 v70, v89, v200, v70
	v_fma_f32 v203, v154, v203, v104
	v_fma_f32 v204, v154, v204, v105
	v_fma_f32 v84, v95, v198, v84
	v_fma_f32 v202, v154, v202, v125
	v_fma_f32 v71, v90, v201, v71
	v_fma_f32 v205, v154, v205, v106
	v_fma_f32 v69, v76, v203, v69
	v_fma_f32 v70, v77, v204, v70
	v_fma_f32 v84, v91, v202, v84
	v_fma_f32 v71, v78, v205, v71
	v_fma_f32 v76, v79, v209, v84
	v_add_f32_e32 v69, v69, v70
	v_add_f32_e32 v70, v71, v76
	v_add_f32_e32 v69, v69, v70
	s_nop 1
	v_add_f32_dpp v69, v69, v69 row_ror:8 row_mask:0xf bank_mask:0xf bound_ctrl:1
	s_nop 1
	v_add_f32_dpp v69, v69, v69 row_ror:4 row_mask:0xf bank_mask:0xf bound_ctrl:1
	s_nop 1
	v_add_f32_dpp v69, v69, v69 row_ror:2 row_mask:0xf bank_mask:0xf bound_ctrl:1
	s_nop 1
	v_add_f32_dpp v69, v69, v69 row_ror:1 row_mask:0xf bank_mask:0xf bound_ctrl:1
	ds_write_b32 v190, v69 offset:34176
	s_waitcnt lgkmcnt(0)
	v_mul_f32_e32 v93, v157, v68
	ds_read_b128 v[88:91], v194 offset:4096
	ds_read_b128 v[84:87], v194 offset:4352
	ds_read_b128 v[124:127], v194 offset:12288
	ds_read_b128 v[104:107], v194 offset:12544
	ds_read_b128 v[76:79], v194 offset:4608
	ds_read_b128 v[68:71], v194 offset:4864
	ds_read_b128 v[108:111], v194 offset:12800
	ds_read_b128 v[96:99], v194 offset:13056
	ds_read2_b32 v[154:155], v196 offset0:68 offset1:84
	ds_read_b32 v92, v190 offset:16640
	v_mul_f32 v94, v132, v93
	v_mul_f32 v95, v133, v93
	v_mul_f32 v132, v134, v93
	v_mul_f32 v133, v135, v93
	v_mul_f32 v120, v120, v93
	v_mul_f32 v121, v121, v93
	v_mul_f32 v122, v122, v93
	v_mul_f32 v123, v123, v93
	v_mul_f32 v128, v128, v93
	v_mul_f32 v129, v129, v93
	v_mul_f32 v210, v130, v93
	v_mul_f32 v211, v131, v93
	v_mul_f32 v116, v116, v93
	v_mul_f32 v117, v117, v93
	v_mul_f32 v118, v118, v93
	v_mul_f32 v93, v119, v93
	v_fma_f32 v130, v156, v112, v94
	v_fma_f32 v131, v156, v113, v95
	v_fma_f32 v132, v156, v114, v132
	v_fma_f32 v133, v156, v115, v133
	v_fma_f32 v134, v156, v206, v120
	v_fma_f32 v135, v156, v207, v121
	v_fma_f32 v157, v156, v208, v122
	v_fma_f32 v198, v156, v198, v123
	v_fma_f32 v199, v156, v199, v128
	v_fma_f32 v200, v156, v200, v129
	v_fma_f32 v201, v156, v201, v210
	v_fma_f32 v202, v156, v202, v211
	v_fma_f32 v203, v156, v203, v116
	v_fma_f32 v204, v156, v204, v117
	v_fma_f32 v205, v156, v205, v118
	v_fma_f32 v156, v156, v209, v93
	v_fma_f32 v93, v100, v130, v140
	v_fma_f32 v94, v101, v131, v140
	v_fma_f32 v95, v102, v132, v140
	v_fma_f32 v100, v103, v133, v140
	v_fma_f32 v80, v80, v134, v93
	v_fma_f32 v81, v81, v135, v94
	v_fma_f32 v82, v82, v157, v95
	v_fma_f32 v83, v83, v198, v100
	v_fma_f32 v72, v72, v199, v80
	v_fma_f32 v73, v73, v200, v81
	v_fma_f32 v74, v74, v201, v82
	v_fma_f32 v75, v75, v202, v83
	v_fma_f32 v64, v64, v203, v72
	v_fma_f32 v65, v65, v204, v73
	v_fma_f32 v66, v66, v205, v74
	v_fma_f32 v67, v67, v156, v75
	v_add_f32_e32 v64, v64, v65
	v_add_f32_e32 v65, v66, v67
	v_add_f32_e32 v64, v64, v65
	s_nop 1
	v_add_f32_dpp v64, v64, v64 row_ror:8 row_mask:0xf bank_mask:0xf bound_ctrl:1
	s_nop 1
	v_add_f32_dpp v64, v64, v64 row_ror:4 row_mask:0xf bank_mask:0xf bound_ctrl:1
	s_nop 1
	v_add_f32_dpp v64, v64, v64 row_ror:2 row_mask:0xf bank_mask:0xf bound_ctrl:1
	s_nop 1
	v_add_f32_dpp v64, v64, v64 row_ror:1 row_mask:0xf bank_mask:0xf bound_ctrl:1
	ds_write_b32 v190, v64 offset:34240
	s_waitcnt lgkmcnt(0)
	v_mul_f32_e32 v155, v155, v92
	ds_read_b128 v[92:95], v194 offset:5120
	ds_read_b128 v[80:83], v194 offset:5376
	ds_read_b128 v[120:123], v194 offset:13312
	ds_read_b128 v[112:115], v194 offset:13568
	ds_read_b128 v[72:75], v194 offset:5632
	ds_read_b128 v[64:67], v194 offset:5888
	ds_read_b128 v[116:119], v194 offset:13824
	ds_read_b128 v[100:103], v194 offset:14080
	ds_read2_b32 v[128:129], v196 offset0:69 offset1:85
	ds_read_b32 v207, v190 offset:16704
	v_mul_f32 v124, v124, v155
	v_mul_f32 v125, v125, v155
	v_mul_f32 v126, v126, v155
	v_mul_f32 v127, v127, v155
	v_mul_f32 v104, v104, v155
	v_mul_f32 v105, v105, v155
	v_mul_f32 v106, v106, v155
	v_mul_f32 v107, v107, v155
	v_mul_f32 v108, v108, v155
	v_mul_f32 v109, v109, v155
	v_mul_f32 v110, v110, v155
	v_mul_f32 v111, v111, v155
	v_mul_f32 v96, v96, v155
	v_mul_f32 v97, v97, v155
	v_mul_f32 v98, v98, v155
	v_mul_f32 v99, v99, v155
	v_fma_f32 v155, v154, v130, v124
	v_fma_f32 v206, v154, v131, v125
	v_fma_f32 v134, v154, v134, v104
	v_fma_f32 v135, v154, v135, v105
	v_fma_f32 v199, v154, v199, v108
	v_fma_f32 v200, v154, v200, v109
	v_fma_f32 v203, v154, v203, v96
	v_fma_f32 v204, v154, v204, v97
	v_fma_f32 v88, v88, v155, v140
	v_fma_f32 v89, v89, v206, v140
	v_fma_f32 v132, v154, v132, v126
	v_fma_f32 v133, v154, v133, v127
	v_fma_f32 v157, v154, v157, v106
	v_fma_f32 v198, v154, v198, v107
	v_fma_f32 v84, v84, v134, v88
	v_fma_f32 v85, v85, v135, v89
	v_fma_f32 v201, v154, v201, v110
	v_fma_f32 v202, v154, v202, v111
	v_fma_f32 v205, v154, v205, v98
	v_fma_f32 v154, v154, v156, v99
	v_fma_f32 v76, v76, v199, v84
	v_fma_f32 v77, v77, v200, v85
	v_fma_f32 v90, v90, v132, v140
	v_fma_f32 v91, v91, v133, v140
	v_fma_f32 v68, v68, v203, v76
	v_fma_f32 v69, v69, v204, v77
	v_fma_f32 v86, v86, v157, v90
	v_fma_f32 v87, v87, v198, v91
	v_fma_f32 v78, v78, v201, v86
	v_fma_f32 v79, v79, v202, v87
	v_add_f32_e32 v68, v68, v69
	v_fma_f32 v70, v70, v205, v78
	v_fma_f32 v71, v71, v154, v79
	v_add_f32_e32 v69, v70, v71
	v_add_f32_e32 v68, v68, v69
	s_nop 1
	v_add_f32_dpp v68, v68, v68 row_ror:8 row_mask:0xf bank_mask:0xf bound_ctrl:1
	s_nop 1
	v_add_f32_dpp v68, v68, v68 row_ror:4 row_mask:0xf bank_mask:0xf bound_ctrl:1
	s_nop 1
	v_add_f32_dpp v68, v68, v68 row_ror:2 row_mask:0xf bank_mask:0xf bound_ctrl:1
	s_nop 1
	v_add_f32_dpp v68, v68, v68 row_ror:1 row_mask:0xf bank_mask:0xf bound_ctrl:1
	ds_write_b32 v190, v68 offset:34304
	s_waitcnt lgkmcnt(0)
	v_mul_f32_e32 v156, v129, v207
	ds_read_b128 v[88:91], v194 offset:6144
	ds_read_b128 v[84:87], v194 offset:6400
	ds_read_b128 v[124:127], v194 offset:14336
	ds_read_b128 v[104:107], v194 offset:14592
	ds_read_b128 v[76:79], v194 offset:6656
	ds_read_b128 v[68:71], v194 offset:6912
	ds_read_b128 v[108:111], v194 offset:14848
	ds_read_b128 v[96:99], v194 offset:15104
	ds_read2_b32 v[130:131], v196 offset0:70 offset1:86
	ds_read_b32 v129, v190 offset:16768
	v_mul_f32 v120, v120, v156
	v_mul_f32 v121, v121, v156
	v_mul_f32 v122, v122, v156
	v_mul_f32 v123, v123, v156
	v_mul_f32 v112, v112, v156
	v_mul_f32 v113, v113, v156
	v_mul_f32 v114, v114, v156
	v_mul_f32 v115, v115, v156
	v_mul_f32 v116, v116, v156
	v_mul_f32 v117, v117, v156
	v_mul_f32 v118, v118, v156
	v_mul_f32 v119, v119, v156
	v_mul_f32 v100, v100, v156
	v_mul_f32 v101, v101, v156
	v_mul_f32 v102, v102, v156
	v_mul_f32 v103, v103, v156
	v_fma_f32 v155, v128, v155, v120
	v_fma_f32 v156, v128, v206, v121
	v_fma_f32 v134, v128, v134, v112
	v_fma_f32 v135, v128, v135, v113
	v_fma_f32 v199, v128, v199, v116
	v_fma_f32 v200, v128, v200, v117
	v_fma_f32 v203, v128, v203, v100
	v_fma_f32 v204, v128, v204, v101
	v_fma_f32 v92, v92, v155, v140
	v_fma_f32 v93, v93, v156, v140
	v_fma_f32 v132, v128, v132, v122
	v_fma_f32 v133, v128, v133, v123
	v_fma_f32 v157, v128, v157, v114
	v_fma_f32 v198, v128, v198, v115
	v_fma_f32 v80, v80, v134, v92
	v_fma_f32 v81, v81, v135, v93
	v_fma_f32 v201, v128, v201, v118
	v_fma_f32 v202, v128, v202, v119
	v_fma_f32 v205, v128, v205, v102
	v_fma_f32 v154, v128, v154, v103
	v_fma_f32 v72, v72, v199, v80
	v_fma_f32 v73, v73, v200, v81
	v_fma_f32 v94, v94, v132, v140
	v_fma_f32 v95, v95, v133, v140
	v_fma_f32 v64, v64, v203, v72
	v_fma_f32 v65, v65, v204, v73
	v_fma_f32 v82, v82, v157, v94
	v_fma_f32 v83, v83, v198, v95
	v_fma_f32 v74, v74, v201, v82
	v_fma_f32 v75, v75, v202, v83
	v_add_f32_e32 v64, v64, v65
	v_fma_f32 v66, v66, v205, v74
	v_fma_f32 v67, v67, v154, v75
	v_add_f32_e32 v65, v66, v67
	v_add_f32_e32 v64, v64, v65
	s_nop 1
	v_add_f32_dpp v64, v64, v64 row_ror:8 row_mask:0xf bank_mask:0xf bound_ctrl:1
	s_nop 1
	v_add_f32_dpp v64, v64, v64 row_ror:4 row_mask:0xf bank_mask:0xf bound_ctrl:1
	s_nop 1
	v_add_f32_dpp v64, v64, v64 row_ror:2 row_mask:0xf bank_mask:0xf bound_ctrl:1
	s_nop 1
	v_add_f32_dpp v64, v64, v64 row_ror:1 row_mask:0xf bank_mask:0xf bound_ctrl:1
	ds_write_b32 v190, v64 offset:34368
	s_waitcnt lgkmcnt(0)
	v_mul_f32_e32 v206, v131, v129
	ds_read_b128 v[92:95], v194 offset:7168
	ds_read_b128 v[80:83], v194 offset:7424
	ds_read_b128 v[120:123], v194 offset:15360
	ds_read_b128 v[112:115], v194 offset:15616
	ds_read_b128 v[72:75], v194 offset:7680
	ds_read_b128 v[64:67], v194 offset:7936
	ds_read_b128 v[116:119], v194 offset:15872
	ds_read_b128 v[100:103], v194 offset:16128
	ds_read2_b32 v[128:129], v196 offset0:71 offset1:87
	ds_read_b32 v131, v190 offset:16832
	v_mul_f32 v125, v125, v206
	v_mul_f32 v126, v126, v206
	v_mul_f32 v104, v104, v206
	v_mul_f32 v124, v124, v206
	v_mul_f32 v127, v127, v206
	v_mul_f32 v105, v105, v206
	v_mul_f32 v106, v106, v206
	v_mul_f32 v107, v107, v206
	v_mul_f32 v108, v108, v206
	v_mul_f32 v109, v109, v206
	v_mul_f32 v207, v110, v206
	v_mul_f32 v208, v111, v206
	v_mul_f32 v209, v96, v206
	v_mul_f32 v210, v97, v206
	v_mul_f32 v211, v98, v206
	v_mul_f32 v206, v99, v206
	v_fma_f32 v96, v130, v155, v124
	v_fma_f32 v97, v130, v156, v125
	v_fma_f32 v98, v130, v132, v126
	v_fma_f32 v99, v130, v133, v127
	v_fma_f32 v104, v130, v134, v104
	v_fma_f32 v110, v130, v135, v105
	v_fma_f32 v125, v130, v199, v108
	v_fma_f32 v126, v130, v200, v109
	v_fma_f32 v133, v130, v203, v209
	v_fma_f32 v134, v130, v204, v210
	v_fma_f32 v88, v88, v96, v140
	v_fma_f32 v89, v89, v97, v140
	v_fma_f32 v111, v130, v157, v106
	v_fma_f32 v124, v130, v198, v107
	v_fma_f32 v127, v130, v201, v207
	v_fma_f32 v132, v130, v202, v208
	v_fma_f32 v84, v84, v104, v88
	v_fma_f32 v85, v85, v110, v89
	v_fma_f32 v135, v130, v205, v211
	v_fma_f32 v130, v130, v154, v206
	v_fma_f32 v90, v90, v98, v140
	v_fma_f32 v91, v91, v99, v140
	v_fma_f32 v76, v76, v125, v84
	v_fma_f32 v77, v77, v126, v85
	v_fma_f32 v68, v68, v133, v76
	v_fma_f32 v69, v69, v134, v77
	v_fma_f32 v86, v86, v111, v90
	v_fma_f32 v87, v87, v124, v91
	v_fma_f32 v78, v78, v127, v86
	v_fma_f32 v79, v79, v132, v87
	v_add_f32_e32 v68, v68, v69
	v_fma_f32 v70, v70, v135, v78
	v_fma_f32 v71, v71, v130, v79
	v_add_f32_e32 v69, v70, v71
	v_add_f32_e32 v68, v68, v69
	s_nop 1
	v_add_f32_dpp v68, v68, v68 row_ror:8 row_mask:0xf bank_mask:0xf bound_ctrl:1
	s_nop 1
	v_add_f32_dpp v68, v68, v68 row_ror:4 row_mask:0xf bank_mask:0xf bound_ctrl:1
	s_nop 1
	v_add_f32_dpp v68, v68, v68 row_ror:2 row_mask:0xf bank_mask:0xf bound_ctrl:1
	s_nop 1
	v_add_f32_dpp v68, v68, v68 row_ror:1 row_mask:0xf bank_mask:0xf bound_ctrl:1
	ds_write_b32 v190, v68 offset:34432
	s_waitcnt lgkmcnt(0)
	v_mul_f32_e32 v68, v129, v131
	v_mul_f32 v69, v120, v68
	v_mul_f32 v70, v121, v68
	v_mul_f32 v71, v122, v68
	v_mul_f32 v76, v123, v68
	v_mul_f32 v77, v112, v68
	v_mul_f32 v78, v113, v68
	v_mul_f32 v79, v114, v68
	v_mul_f32 v84, v115, v68
	v_mul_f32 v85, v116, v68
	v_mul_f32 v86, v117, v68
	v_mul_f32 v87, v118, v68
	v_mul_f32 v88, v119, v68
	v_mul_f32 v89, v100, v68
	v_mul_f32 v100, v101, v68
	v_mul_f32 v101, v102, v68
	v_mul_f32 v68, v103, v68
	v_fma_f32 v109, v128, v96, v69
	v_fma_f32 v108, v128, v97, v70
	v_fma_f32 v105, v128, v104, v77
	v_fma_f32 v104, v128, v110, v78
	v_fma_f32 v107, v128, v98, v71
	v_fma_f32 v78, v128, v130, v68
	v_fma_f32 v68, v92, v109, v140
	v_fma_f32 v69, v93, v108, v140
	v_fma_f32 v106, v128, v99, v76
	v_fma_f32 v99, v128, v111, v79
	v_fma_f32 v70, v94, v107, v140
	v_fma_f32 v98, v128, v124, v84
	v_fma_f32 v68, v80, v105, v68
	v_fma_f32 v69, v81, v104, v69
	v_fma_f32 v71, v95, v106, v140
	v_fma_f32 v97, v128, v125, v85
	v_fma_f32 v96, v128, v126, v86
	v_fma_f32 v90, v128, v132, v88
	v_fma_f32 v89, v128, v133, v89
	v_fma_f32 v88, v128, v134, v100
	v_fma_f32 v70, v82, v99, v70
	v_fma_f32 v71, v83, v98, v71
	v_fma_f32 v68, v72, v97, v68
	v_fma_f32 v69, v73, v96, v69
	v_fma_f32 v91, v128, v127, v87
	v_fma_f32 v79, v128, v135, v101
	v_fma_f32 v71, v75, v90, v71
	v_fma_f32 v64, v64, v89, v68
	v_fma_f32 v65, v65, v88, v69
	v_fma_f32 v70, v74, v91, v70
	v_fma_f32 v66, v66, v79, v70
	v_fma_f32 v67, v67, v78, v71
	v_add_f32_e32 v64, v64, v65
	v_add_f32_e32 v65, v66, v67
	v_add_f32_e32 v64, v64, v65
	s_nop 1
	v_add_f32_dpp v64, v64, v64 row_ror:8 row_mask:0xf bank_mask:0xf bound_ctrl:1
	s_nop 1
	v_add_f32_dpp v64, v64, v64 row_ror:4 row_mask:0xf bank_mask:0xf bound_ctrl:1
	s_nop 1
	v_add_f32_dpp v64, v64, v64 row_ror:2 row_mask:0xf bank_mask:0xf bound_ctrl:1
	s_nop 1
	v_add_f32_dpp v64, v64, v64 row_ror:1 row_mask:0xf bank_mask:0xf bound_ctrl:1
	ds_write_b32 v190, v64 offset:34496
	s_waitcnt vmcnt(3)
	ds_write_b128 v188, v[48:51] offset:17024
	s_waitcnt vmcnt(1)
	ds_write_b128 v191, v[56:59] offset:17024
	ds_write_b128 v188, v[52:55] offset:25216
	s_waitcnt vmcnt(0)
	ds_write_b128 v191, v[60:63] offset:25216
	s_and_saveexec_b64 s[8:9], s[40:41]
	ds_write_b32 v145, v192 offset:33408
	s_or_b64 exec, exec, s[8:9]
	s_and_saveexec_b64 s[8:9], s[42:43]
	s_cbranch_execz .LBB0_1242
	v_add_f32_e32 v64, v178, v195
	v_mul_f32_e64 v65, |v64|, s62
	v_exp_f32_e32 v65, v65
	v_min_f32_e32 v64, 0, v64
	v_add_f32_e32 v65, 1.0, v65
	v_cmp_gt_f32_e32 vcc, s5, v65
	s_nop 1
	v_cndmask_b32_e64 v66, 0, 32, vcc
	v_ldexp_f32 v65, v65, v66
	v_log_f32_e32 v65, v65
	v_cndmask_b32_e32 v67, 0, v171, vcc
	v_add_f32_e32 v66, v147, v193
	v_mul_f32_e32 v68, 0x3f317217, v65
	v_fma_f32 v68, v65, s76, -v68
	v_fmac_f32_e32 v68, 0x3377d1cf, v65
	v_fmac_f32_e32 v68, 0x3f317217, v65
	v_cmp_lt_f32_e64 vcc, |v65|, s77
	s_nop 1
	v_cndmask_b32_e32 v65, v65, v68, vcc
	v_sub_f32_e32 v65, v65, v67
	v_sub_f32_e32 v64, v64, v65
	v_add_u32_e32 v65, 0x8400, v145
	ds_write2_b32 v65, v66, v64 offset0:32 offset1:48

.LBB0_1255:
	s_or_b64 exec, exec, s[8:9]
	s_waitcnt lgkmcnt(0)
	s_barrier
	ds_read_b128 v[92:95], v194 offset:17024
	ds_read_b128 v[110:113], v194 offset:17280
	ds_read_b128 v[124:127], v194 offset:25216
	ds_read_b128 v[132:135], v194 offset:25472
	ds_read2_b64 v[80:83], v196 offset0:32 offset1:40
	ds_read2_b32 v[76:77], v197 offset0:160 offset1:176
	ds_read_b128 v[206:209], v194 offset:17536
	ds_read_b128 v[210:213], v194 offset:17792
	ds_read_b128 v[154:157], v194 offset:25728
	ds_read_b128 v[198:201], v194 offset:25984
	s_waitcnt lgkmcnt(4)
	v_mul_f32_e32 v76, v82, v76
	v_mul_f32 v82, v124, v76
	v_mul_f32 v114, v125, v76
	v_mul_f32 v115, v126, v76
	v_mul_f32 v124, v127, v76
	v_mul_f32 v125, v132, v76
	v_mul_f32 v126, v133, v76
	v_mul_f32 v127, v134, v76
	v_mul_f32 v197, v135, v76
	s_waitcnt lgkmcnt(1)
	v_mul_f32 v154, v154, v76
	v_mul_f32 v155, v155, v76
	v_mul_f32 v202, v156, v76
	v_mul_f32 v203, v157, v76
	s_waitcnt lgkmcnt(0)
	v_mul_f32 v204, v198, v76
	v_mul_f32 v205, v199, v76
	v_mul_f32 v214, v200, v76
	v_mul_f32 v76, v201, v76
	ds_read_b128 v[84:87], v194 offset:18048
	ds_read_b128 v[72:75], v194 offset:18304
	ds_read_b128 v[128:131], v194 offset:26240
	ds_read_b128 v[116:119], v194 offset:26496
	ds_read_b128 v[68:71], v194 offset:18560
	ds_read_b128 v[64:67], v194 offset:18816
	ds_read_b128 v[120:123], v194 offset:26752
	ds_read_b128 v[100:103], v194 offset:27008
	v_fma_f32 v82, v80, v109, v82
	v_fma_f32 v132, v80, v108, v114
	v_fma_f32 v133, v80, v107, v115
	v_fma_f32 v134, v80, v106, v124
	v_fma_f32 v135, v80, v105, v125
	v_fma_f32 v156, v80, v104, v126
	v_fma_f32 v157, v80, v99, v127
	v_fma_f32 v197, v80, v98, v197
	v_fma_f32 v198, v80, v97, v154
	v_fma_f32 v199, v80, v96, v155
	v_fma_f32 v200, v80, v91, v202
	v_fma_f32 v201, v80, v90, v203
	v_fma_f32 v202, v80, v89, v204
	v_fma_f32 v203, v80, v88, v205
	v_fma_f32 v204, v80, v79, v214
	v_fma_f32 v80, v80, v78, v76
	v_fma_f32 v76, v92, v82, v140
	v_fma_f32 v78, v93, v132, v140
	v_fma_f32 v79, v94, v133, v140
	v_fma_f32 v88, v95, v134, v140
	v_fma_f32 v76, v110, v135, v76
	v_fma_f32 v78, v111, v156, v78
	v_fma_f32 v79, v112, v157, v79
	v_fma_f32 v88, v113, v197, v88
	v_fma_f32 v76, v206, v198, v76
	v_fma_f32 v78, v207, v199, v78
	v_fma_f32 v79, v208, v200, v79
	v_fma_f32 v88, v209, v201, v88
	v_fma_f32 v76, v210, v202, v76
	v_fma_f32 v78, v211, v203, v78
	v_fma_f32 v79, v212, v204, v79
	v_fma_f32 v88, v213, v80, v88
	v_add_f32_e32 v76, v76, v78
	v_add_f32_e32 v78, v79, v88
	v_add_f32_e32 v76, v76, v78
	s_nop 1
	v_add_f32_dpp v76, v76, v76 row_ror:8 row_mask:0xf bank_mask:0xf bound_ctrl:1
	s_nop 1
	v_add_f32_dpp v76, v76, v76 row_ror:4 row_mask:0xf bank_mask:0xf bound_ctrl:1
	s_nop 1
	v_add_f32_dpp v76, v76, v76 row_ror:2 row_mask:0xf bank_mask:0xf bound_ctrl:1
	s_nop 1
	v_add_f32_dpp v76, v76, v76 row_ror:1 row_mask:0xf bank_mask:0xf bound_ctrl:1
	ds_write_b32 v190, v76 offset:34560
	v_mul_f32_e32 v205, v83, v77
	ds_read_b128 v[96:99], v194 offset:19072
	ds_read_b128 v[92:95], v194 offset:19328
	ds_read_b128 v[124:127], v194 offset:27264
	ds_read_b128 v[108:111], v194 offset:27520
	ds_read_b128 v[88:91], v194 offset:19584
	ds_read_b128 v[76:79], v194 offset:19840
	ds_read_b128 v[112:115], v194 offset:27776
	ds_read_b128 v[104:107], v194 offset:28032
	ds_read2_b32 v[154:155], v196 offset0:66 offset1:82
	ds_read_b32 v83, v190 offset:33536
	s_waitcnt lgkmcnt(14)
	v_mul_f32 v128, v128, v205
	v_mul_f32 v129, v129, v205
	v_mul_f32 v130, v130, v205
	v_mul_f32 v131, v131, v205
	v_mul_f32 v116, v116, v205
	v_mul_f32 v117, v117, v205
	v_mul_f32 v118, v118, v205
	v_mul_f32 v119, v119, v205
	s_waitcnt lgkmcnt(11)
	v_mul_f32 v120, v120, v205
	v_mul_f32 v121, v121, v205
	v_mul_f32 v122, v122, v205
	v_mul_f32 v123, v123, v205
	s_waitcnt lgkmcnt(10)
	v_mul_f32 v100, v100, v205
	v_mul_f32 v101, v101, v205
	v_mul_f32 v102, v102, v205
	v_mul_f32 v103, v103, v205
	v_fma_f32 v205, v81, v82, v128
	v_fma_f32 v206, v81, v132, v129
	v_fma_f32 v207, v81, v133, v130
	v_fma_f32 v208, v81, v134, v131
	v_fma_f32 v209, v81, v135, v116
	v_fma_f32 v210, v81, v156, v117
	v_fma_f32 v211, v81, v157, v118
	v_fma_f32 v197, v81, v197, v119
	v_fma_f32 v198, v81, v198, v120
	v_fma_f32 v199, v81, v199, v121
	v_fma_f32 v200, v81, v200, v122
	v_fma_f32 v201, v81, v201, v123
	v_fma_f32 v202, v81, v202, v100
	v_fma_f32 v203, v81, v203, v101
	v_fma_f32 v204, v81, v204, v102
	v_fma_f32 v212, v81, v80, v103
	v_fma_f32 v80, v84, v205, v140
	v_fma_f32 v81, v85, v206, v140
	v_fma_f32 v82, v86, v207, v140
	v_fma_f32 v84, v87, v208, v140
	v_fma_f32 v72, v72, v209, v80
	v_fma_f32 v73, v73, v210, v81
	v_fma_f32 v74, v74, v211, v82
	v_fma_f32 v75, v75, v197, v84
	v_fma_f32 v68, v68, v198, v72
	v_fma_f32 v69, v69, v199, v73
	v_fma_f32 v70, v70, v200, v74
	v_fma_f32 v71, v71, v201, v75
	v_fma_f32 v64, v64, v202, v68
	v_fma_f32 v65, v65, v203, v69
	v_fma_f32 v66, v66, v204, v70
	v_fma_f32 v67, v67, v212, v71
	v_add_f32_e32 v64, v64, v65
	v_add_f32_e32 v65, v66, v67
	v_add_f32_e32 v64, v64, v65
	s_nop 1
	v_add_f32_dpp v64, v64, v64 row_ror:8 row_mask:0xf bank_mask:0xf bound_ctrl:1
	s_nop 1
	v_add_f32_dpp v64, v64, v64 row_ror:4 row_mask:0xf bank_mask:0xf bound_ctrl:1
	s_nop 1
	v_add_f32_dpp v64, v64, v64 row_ror:2 row_mask:0xf bank_mask:0xf bound_ctrl:1
	s_nop 1
	v_add_f32_dpp v64, v64, v64 row_ror:1 row_mask:0xf bank_mask:0xf bound_ctrl:1
	ds_write_b32 v190, v64 offset:34624
	s_waitcnt lgkmcnt(0)
	v_mul_f32_e32 v69, v155, v83
	ds_read_b128 v[100:103], v194 offset:20096
	ds_read_b128 v[80:83], v194 offset:20352
	ds_read_b128 v[132:135], v194 offset:28288
	ds_read_b128 v[120:123], v194 offset:28544
	ds_read_b128 v[72:75], v194 offset:20608
	ds_read_b128 v[64:67], v194 offset:20864
	ds_read_b128 v[128:131], v194 offset:28800
	ds_read_b128 v[116:119], v194 offset:29056
	ds_read2_b32 v[156:157], v196 offset0:67 offset1:83
	ds_read_b32 v68, v190 offset:33600
	v_mul_f32 v70, v124, v69
	v_mul_f32 v71, v125, v69
	v_mul_f32 v84, v126, v69
	v_mul_f32 v85, v127, v69
	v_mul_f32 v86, v108, v69
	v_mul_f32 v87, v109, v69
	v_mul_f32 v108, v110, v69
	v_mul_f32 v109, v111, v69
	v_mul_f32 v110, v112, v69
	v_mul_f32 v111, v113, v69
	v_mul_f32 v124, v114, v69
	v_mul_f32 v125, v115, v69
	v_mul_f32 v104, v104, v69
	v_mul_f32 v105, v105, v69
	v_mul_f32 v106, v106, v69
	v_mul_f32 v69, v107, v69
	v_fma_f32 v112, v154, v205, v70
	v_fma_f32 v113, v154, v206, v71
	v_fma_f32 v115, v154, v208, v85
	v_fma_f32 v114, v154, v207, v84
	v_fma_f32 v205, v154, v209, v86
	v_fma_f32 v208, v154, v212, v69
	v_fma_f32 v69, v96, v112, v140
	v_fma_f32 v70, v97, v113, v140
	v_fma_f32 v206, v154, v210, v87
	v_fma_f32 v71, v98, v114, v140
	v_fma_f32 v207, v154, v211, v108
	v_fma_f32 v198, v154, v198, v110
	v_fma_f32 v69, v92, v205, v69
	v_fma_f32 v199, v154, v199, v111
	v_fma_f32 v70, v93, v206, v70
	v_fma_f32 v84, v99, v115, v140
	v_fma_f32 v71, v94, v207, v71
	v_fma_f32 v197, v154, v197, v109
	v_fma_f32 v69, v88, v198, v69
	v_fma_f32 v200, v154, v200, v124
	v_fma_f32 v70, v89, v199, v70
	v_fma_f32 v202, v154, v202, v104
	v_fma_f32 v203, v154, v203, v105
	v_fma_f32 v84, v95, v197, v84
	v_fma_f32 v201, v154, v201, v125
	v_fma_f32 v71, v90, v200, v71
	v_fma_f32 v204, v154, v204, v106
	v_fma_f32 v69, v76, v202, v69
	v_fma_f32 v70, v77, v203, v70
	v_fma_f32 v84, v91, v201, v84
	v_fma_f32 v71, v78, v204, v71
	v_fma_f32 v76, v79, v208, v84
	v_add_f32_e32 v69, v69, v70
	v_add_f32_e32 v70, v71, v76
	v_add_f32_e32 v69, v69, v70
	s_nop 1
	v_add_f32_dpp v69, v69, v69 row_ror:8 row_mask:0xf bank_mask:0xf bound_ctrl:1
	s_nop 1
	v_add_f32_dpp v69, v69, v69 row_ror:4 row_mask:0xf bank_mask:0xf bound_ctrl:1
	s_nop 1
	v_add_f32_dpp v69, v69, v69 row_ror:2 row_mask:0xf bank_mask:0xf bound_ctrl:1
	s_nop 1
	v_add_f32_dpp v69, v69, v69 row_ror:1 row_mask:0xf bank_mask:0xf bound_ctrl:1
	ds_write_b32 v190, v69 offset:34688
	s_waitcnt lgkmcnt(0)
	v_mul_f32_e32 v93, v157, v68
	ds_read_b128 v[88:91], v194 offset:21120
	ds_read_b128 v[84:87], v194 offset:21376
	ds_read_b128 v[124:127], v194 offset:29312
	ds_read_b128 v[104:107], v194 offset:29568
	ds_read_b128 v[76:79], v194 offset:21632
	ds_read_b128 v[68:71], v194 offset:21888
	ds_read_b128 v[108:111], v194 offset:29824
	ds_read_b128 v[96:99], v194 offset:30080
	ds_read2_b32 v[154:155], v196 offset0:68 offset1:84
	ds_read_b32 v92, v190 offset:33664
	v_mul_f32 v94, v132, v93
	v_mul_f32 v95, v133, v93
	v_mul_f32 v132, v134, v93
	v_mul_f32 v133, v135, v93
	v_mul_f32 v120, v120, v93
	v_mul_f32 v121, v121, v93
	v_mul_f32 v122, v122, v93
	v_mul_f32 v123, v123, v93
	v_mul_f32 v128, v128, v93
	v_mul_f32 v129, v129, v93
	v_mul_f32 v209, v130, v93
	v_mul_f32 v210, v131, v93
	v_mul_f32 v116, v116, v93
	v_mul_f32 v117, v117, v93
	v_mul_f32 v118, v118, v93
	v_mul_f32 v93, v119, v93
	v_fma_f32 v130, v156, v112, v94
	v_fma_f32 v131, v156, v113, v95
	v_fma_f32 v132, v156, v114, v132
	v_fma_f32 v133, v156, v115, v133
	v_fma_f32 v134, v156, v205, v120
	v_fma_f32 v135, v156, v206, v121
	v_fma_f32 v157, v156, v207, v122
	v_fma_f32 v197, v156, v197, v123
	v_fma_f32 v198, v156, v198, v128
	v_fma_f32 v199, v156, v199, v129
	v_fma_f32 v200, v156, v200, v209
	v_fma_f32 v201, v156, v201, v210
	v_fma_f32 v202, v156, v202, v116
	v_fma_f32 v203, v156, v203, v117
	v_fma_f32 v204, v156, v204, v118
	v_fma_f32 v156, v156, v208, v93
	v_fma_f32 v93, v100, v130, v140
	v_fma_f32 v94, v101, v131, v140
	v_fma_f32 v95, v102, v132, v140
	v_fma_f32 v100, v103, v133, v140
	v_fma_f32 v80, v80, v134, v93
	v_fma_f32 v81, v81, v135, v94
	v_fma_f32 v82, v82, v157, v95
	v_fma_f32 v83, v83, v197, v100
	v_fma_f32 v72, v72, v198, v80
	v_fma_f32 v73, v73, v199, v81
	v_fma_f32 v74, v74, v200, v82
	v_fma_f32 v75, v75, v201, v83
	v_fma_f32 v64, v64, v202, v72
	v_fma_f32 v65, v65, v203, v73
	v_fma_f32 v66, v66, v204, v74
	v_fma_f32 v67, v67, v156, v75
	v_add_f32_e32 v64, v64, v65
	v_add_f32_e32 v65, v66, v67
	v_add_f32_e32 v64, v64, v65
	s_nop 1
	v_add_f32_dpp v64, v64, v64 row_ror:8 row_mask:0xf bank_mask:0xf bound_ctrl:1
	s_nop 1
	v_add_f32_dpp v64, v64, v64 row_ror:4 row_mask:0xf bank_mask:0xf bound_ctrl:1
	s_nop 1
	v_add_f32_dpp v64, v64, v64 row_ror:2 row_mask:0xf bank_mask:0xf bound_ctrl:1
	s_nop 1
	v_add_f32_dpp v64, v64, v64 row_ror:1 row_mask:0xf bank_mask:0xf bound_ctrl:1
	ds_write_b32 v190, v64 offset:34752
	s_waitcnt lgkmcnt(0)
	v_mul_f32_e32 v155, v155, v92
	ds_read_b128 v[92:95], v194 offset:22144
	ds_read_b128 v[80:83], v194 offset:22400
	ds_read_b128 v[120:123], v194 offset:30336
	ds_read_b128 v[112:115], v194 offset:30592
	ds_read_b128 v[72:75], v194 offset:22656
	ds_read_b128 v[64:67], v194 offset:22912
	ds_read_b128 v[116:119], v194 offset:30848
	ds_read_b128 v[100:103], v194 offset:31104
	ds_read2_b32 v[128:129], v196 offset0:69 offset1:85
	ds_read_b32 v206, v190 offset:33728
	v_mul_f32 v124, v124, v155
	v_mul_f32 v125, v125, v155
	v_mul_f32 v126, v126, v155
	v_mul_f32 v127, v127, v155
	v_mul_f32 v104, v104, v155
	v_mul_f32 v105, v105, v155
	v_mul_f32 v106, v106, v155
	v_mul_f32 v107, v107, v155
	v_mul_f32 v108, v108, v155
	v_mul_f32 v109, v109, v155
	v_mul_f32 v110, v110, v155
	v_mul_f32 v111, v111, v155
	v_mul_f32 v96, v96, v155
	v_mul_f32 v97, v97, v155
	v_mul_f32 v98, v98, v155
	v_mul_f32 v99, v99, v155
	v_fma_f32 v155, v154, v130, v124
	v_fma_f32 v205, v154, v131, v125
	v_fma_f32 v134, v154, v134, v104
	v_fma_f32 v135, v154, v135, v105
	v_fma_f32 v198, v154, v198, v108
	v_fma_f32 v199, v154, v199, v109
	v_fma_f32 v202, v154, v202, v96
	v_fma_f32 v203, v154, v203, v97
	v_fma_f32 v88, v88, v155, v140
	v_fma_f32 v89, v89, v205, v140
	v_fma_f32 v132, v154, v132, v126
	v_fma_f32 v133, v154, v133, v127
	v_fma_f32 v157, v154, v157, v106
	v_fma_f32 v197, v154, v197, v107
	v_fma_f32 v84, v84, v134, v88
	v_fma_f32 v85, v85, v135, v89
	v_fma_f32 v200, v154, v200, v110
	v_fma_f32 v201, v154, v201, v111
	v_fma_f32 v204, v154, v204, v98
	v_fma_f32 v154, v154, v156, v99
	v_fma_f32 v76, v76, v198, v84
	v_fma_f32 v77, v77, v199, v85
	v_fma_f32 v90, v90, v132, v140
	v_fma_f32 v91, v91, v133, v140
	v_fma_f32 v68, v68, v202, v76
	v_fma_f32 v69, v69, v203, v77
	v_fma_f32 v86, v86, v157, v90
	v_fma_f32 v87, v87, v197, v91
	v_fma_f32 v78, v78, v200, v86
	v_fma_f32 v79, v79, v201, v87
	v_add_f32_e32 v68, v68, v69
	v_fma_f32 v70, v70, v204, v78
	v_fma_f32 v71, v71, v154, v79
	v_add_f32_e32 v69, v70, v71
	v_add_f32_e32 v68, v68, v69
	s_nop 1
	v_add_f32_dpp v68, v68, v68 row_ror:8 row_mask:0xf bank_mask:0xf bound_ctrl:1
	s_nop 1
	v_add_f32_dpp v68, v68, v68 row_ror:4 row_mask:0xf bank_mask:0xf bound_ctrl:1
	s_nop 1
	v_add_f32_dpp v68, v68, v68 row_ror:2 row_mask:0xf bank_mask:0xf bound_ctrl:1
	s_nop 1
	v_add_f32_dpp v68, v68, v68 row_ror:1 row_mask:0xf bank_mask:0xf bound_ctrl:1
	ds_write_b32 v190, v68 offset:34816
	s_waitcnt lgkmcnt(0)
	v_mul_f32_e32 v156, v129, v206
	ds_read_b128 v[88:91], v194 offset:23168
	ds_read_b128 v[84:87], v194 offset:23424
	ds_read_b128 v[124:127], v194 offset:31360
	ds_read_b128 v[104:107], v194 offset:31616
	ds_read_b128 v[76:79], v194 offset:23680
	ds_read_b128 v[68:71], v194 offset:23936
	ds_read_b128 v[108:111], v194 offset:31872
	ds_read_b128 v[96:99], v194 offset:32128
	ds_read2_b32 v[130:131], v196 offset0:70 offset1:86
	ds_read_b32 v129, v190 offset:33792
	v_mul_f32 v120, v120, v156
	v_mul_f32 v121, v121, v156
	v_mul_f32 v122, v122, v156
	v_mul_f32 v123, v123, v156
	v_mul_f32 v112, v112, v156
	v_mul_f32 v113, v113, v156
	v_mul_f32 v114, v114, v156
	v_mul_f32 v115, v115, v156
	v_mul_f32 v116, v116, v156
	v_mul_f32 v117, v117, v156
	v_mul_f32 v118, v118, v156
	v_mul_f32 v119, v119, v156
	v_mul_f32 v100, v100, v156
	v_mul_f32 v101, v101, v156
	v_mul_f32 v102, v102, v156
	v_mul_f32 v103, v103, v156
	v_fma_f32 v155, v128, v155, v120
	v_fma_f32 v156, v128, v205, v121
	v_fma_f32 v134, v128, v134, v112
	v_fma_f32 v135, v128, v135, v113
	v_fma_f32 v198, v128, v198, v116
	v_fma_f32 v199, v128, v199, v117
	v_fma_f32 v202, v128, v202, v100
	v_fma_f32 v203, v128, v203, v101
	v_fma_f32 v92, v92, v155, v140
	v_fma_f32 v93, v93, v156, v140
	v_fma_f32 v132, v128, v132, v122
	v_fma_f32 v133, v128, v133, v123
	v_fma_f32 v157, v128, v157, v114
	v_fma_f32 v197, v128, v197, v115
	v_fma_f32 v80, v80, v134, v92
	v_fma_f32 v81, v81, v135, v93
	v_fma_f32 v200, v128, v200, v118
	v_fma_f32 v201, v128, v201, v119
	v_fma_f32 v204, v128, v204, v102
	v_fma_f32 v154, v128, v154, v103
	v_fma_f32 v72, v72, v198, v80
	v_fma_f32 v73, v73, v199, v81
	v_fma_f32 v94, v94, v132, v140
	v_fma_f32 v95, v95, v133, v140
	v_fma_f32 v64, v64, v202, v72
	v_fma_f32 v65, v65, v203, v73
	v_fma_f32 v82, v82, v157, v94
	v_fma_f32 v83, v83, v197, v95
	v_fma_f32 v74, v74, v200, v82
	v_fma_f32 v75, v75, v201, v83
	v_add_f32_e32 v64, v64, v65
	v_fma_f32 v66, v66, v204, v74
	v_fma_f32 v67, v67, v154, v75
	v_add_f32_e32 v65, v66, v67
	v_add_f32_e32 v64, v64, v65
	s_nop 1
	v_add_f32_dpp v64, v64, v64 row_ror:8 row_mask:0xf bank_mask:0xf bound_ctrl:1
	s_nop 1
	v_add_f32_dpp v64, v64, v64 row_ror:4 row_mask:0xf bank_mask:0xf bound_ctrl:1
	s_nop 1
	v_add_f32_dpp v64, v64, v64 row_ror:2 row_mask:0xf bank_mask:0xf bound_ctrl:1
	s_nop 1
	v_add_f32_dpp v64, v64, v64 row_ror:1 row_mask:0xf bank_mask:0xf bound_ctrl:1
	ds_write_b32 v190, v64 offset:34880
	s_waitcnt lgkmcnt(0)
	v_mul_f32_e32 v205, v131, v129
	ds_read_b128 v[92:95], v194 offset:24192
	ds_read_b128 v[80:83], v194 offset:24448
	ds_read_b128 v[120:123], v194 offset:32384
	ds_read_b128 v[112:115], v194 offset:32640
	ds_read_b128 v[72:75], v194 offset:24704
	ds_read_b128 v[64:67], v194 offset:24960
	ds_read_b128 v[116:119], v194 offset:32896
	ds_read_b128 v[100:103], v194 offset:33152
	ds_read2_b32 v[128:129], v196 offset0:71 offset1:87
	ds_read_b32 v131, v190 offset:33856
	v_mul_f32 v124, v124, v205
	v_mul_f32 v125, v125, v205
	v_mul_f32 v104, v104, v205
	v_mul_f32 v105, v105, v205
	v_mul_f32 v108, v108, v205
	v_mul_f32 v109, v109, v205
	v_mul_f32 v126, v126, v205
	v_mul_f32 v127, v127, v205
	v_mul_f32 v106, v106, v205
	v_mul_f32 v107, v107, v205
	v_mul_f32 v110, v110, v205
	v_mul_f32 v111, v111, v205
	v_mul_f32 v196, v96, v205
	v_mul_f32 v206, v97, v205
	v_fma_f32 v96, v130, v155, v124
	v_fma_f32 v97, v130, v156, v125
	v_fma_f32 v104, v130, v134, v104
	v_fma_f32 v105, v130, v135, v105
	v_fma_f32 v108, v130, v198, v108
	v_fma_f32 v109, v130, v199, v109
	v_fma_f32 v124, v130, v202, v196
	v_fma_f32 v125, v130, v203, v206
	v_fma_f32 v88, v88, v96, v140
	v_fma_f32 v89, v89, v97, v140
	v_mul_f32 v207, v98, v205
	v_mul_f32 v205, v99, v205
	v_fma_f32 v98, v130, v132, v126
	v_fma_f32 v99, v130, v133, v127
	v_fma_f32 v84, v84, v104, v88
	v_fma_f32 v85, v85, v105, v89
	v_fma_f32 v106, v130, v157, v106
	v_fma_f32 v107, v130, v197, v107
	v_fma_f32 v110, v130, v200, v110
	v_fma_f32 v111, v130, v201, v111
	v_fma_f32 v76, v76, v108, v84
	v_fma_f32 v77, v77, v109, v85
	v_fma_f32 v126, v130, v204, v207
	v_fma_f32 v127, v130, v154, v205
	v_fma_f32 v90, v90, v98, v140
	v_fma_f32 v91, v91, v99, v140
	v_fma_f32 v68, v68, v124, v76
	v_fma_f32 v69, v69, v125, v77
	v_fma_f32 v86, v86, v106, v90
	v_fma_f32 v87, v87, v107, v91
	v_add_f32_e32 v68, v68, v69
	v_fma_f32 v78, v78, v110, v86
	v_fma_f32 v79, v79, v111, v87
	v_fma_f32 v70, v70, v126, v78
	v_fma_f32 v71, v71, v127, v79
	v_add_f32_e32 v69, v70, v71
	v_add_f32_e32 v68, v68, v69
	s_nop 1
	v_add_f32_dpp v68, v68, v68 row_ror:8 row_mask:0xf bank_mask:0xf bound_ctrl:1
	s_nop 1
	v_add_f32_dpp v68, v68, v68 row_ror:4 row_mask:0xf bank_mask:0xf bound_ctrl:1
	s_nop 1
	v_add_f32_dpp v68, v68, v68 row_ror:2 row_mask:0xf bank_mask:0xf bound_ctrl:1
	s_nop 1
	v_add_f32_dpp v68, v68, v68 row_ror:1 row_mask:0xf bank_mask:0xf bound_ctrl:1
	ds_write_b32 v190, v68 offset:34944
	s_waitcnt lgkmcnt(0)
	v_mul_f32_e32 v68, v129, v131
	v_mul_f32 v69, v120, v68
	v_mul_f32 v70, v121, v68
	v_mul_f32 v71, v122, v68
	v_mul_f32 v76, v123, v68
	v_mul_f32 v77, v112, v68
	v_mul_f32 v78, v113, v68
	v_mul_f32 v79, v114, v68
	v_mul_f32 v84, v115, v68
	v_mul_f32 v85, v116, v68
	v_mul_f32 v86, v117, v68
	v_mul_f32 v87, v118, v68
	v_mul_f32 v112, v119, v68
	v_mul_f32 v113, v100, v68
	v_mul_f32 v114, v101, v68
	v_mul_f32 v115, v102, v68
	v_mul_f32 v68, v103, v68
	v_fma_f32 v88, v128, v96, v69
	v_fma_f32 v89, v128, v97, v70
	v_fma_f32 v101, v128, v105, v78
	v_fma_f32 v105, v128, v109, v86
	v_fma_f32 v109, v128, v111, v112
	v_fma_f32 v111, v128, v127, v68
	v_fma_f32 v68, v92, v88, v140
	v_fma_f32 v69, v93, v89, v140
	v_fma_f32 v90, v128, v98, v71
	v_fma_f32 v100, v128, v99, v76
	v_fma_f32 v91, v128, v104, v77
	v_fma_f32 v102, v128, v106, v79
	v_fma_f32 v104, v128, v107, v84
	v_fma_f32 v69, v81, v101, v69
	v_fma_f32 v70, v94, v90, v140
	v_fma_f32 v71, v95, v100, v140
	v_fma_f32 v68, v80, v91, v68
	v_fma_f32 v103, v128, v108, v85
	v_fma_f32 v106, v128, v110, v87
	v_fma_f32 v107, v128, v124, v113
	v_fma_f32 v110, v128, v125, v114
	v_fma_f32 v70, v82, v102, v70
	v_fma_f32 v71, v83, v104, v71
	v_fma_f32 v68, v72, v103, v68
	v_fma_f32 v69, v73, v105, v69
	v_fma_f32 v108, v128, v126, v115
	v_fma_f32 v70, v74, v106, v70
	v_fma_f32 v71, v75, v109, v71
	v_fma_f32 v64, v64, v107, v68
	v_fma_f32 v65, v65, v110, v69
	v_fma_f32 v66, v66, v108, v70
	v_fma_f32 v67, v67, v111, v71
	v_add_f32_e32 v64, v64, v65
	v_add_f32_e32 v65, v66, v67
	v_add_f32_e32 v64, v64, v65
	v_mov_b32_e32 v65, 0
	s_nop 0
	v_add_f32_dpp v64, v64, v64 row_ror:8 row_mask:0xf bank_mask:0xf bound_ctrl:1
	s_nop 1
	v_add_f32_dpp v64, v64, v64 row_ror:4 row_mask:0xf bank_mask:0xf bound_ctrl:1
	s_nop 1
	v_add_f32_dpp v64, v64, v64 row_ror:2 row_mask:0xf bank_mask:0xf bound_ctrl:1
	s_nop 1
	v_mov_b32_dpp v65, v64 row_ror:1 row_mask:0xf bank_mask:0xf
	s_and_saveexec_b64 s[8:9], s[44:45]
	s_cbranch_execz .LBB0_1138
	v_add_f32_e32 v64, v64, v65
	ds_write_b32 v190, v64 offset:35008
	s_branch .LBB0_1138

.LBB0_1289:
	ds_read_b128 v[64:67], v145
	ds_read_b128 v[72:75], v145 offset:256
	ds_read_b128 v[178:181], v145 offset:8192
	ds_read_b128 v[182:185], v145 offset:8448
	v_add_u32_e32 v152, 0x4000, v103
	ds_read2_b32 v[96:97], v152 offset1:16
	ds_read_b128 v[76:79], v145 offset:512
	ds_read_b128 v[68:71], v145 offset:768
	ds_read_b128 v[92:95], v145 offset:8704
	ds_read_b128 v[84:87], v145 offset:8960
	ds_read2_b32 v[98:99], v152 offset0:32 offset1:48
	s_waitcnt lgkmcnt(5)
	v_sub_f32 v115, v118, v96
	v_sub_f32 v118, v119, v96
	v_sub_f32 v119, v120, v97
	v_sub_f32 v120, v121, v97
	v_sub_f32 v80, v80, v96
	v_sub_f32 v81, v81, v96
	v_sub_f32 v82, v82, v96
	v_sub_f32 v117, v146, v97
	v_sub_f32 v88, v88, v96
	v_sub_f32 v121, v147, v97
	v_sub_f32 v83, v83, v97
	v_fma_f32 v157, v178, v115, v96
	v_fma_f32 v154, v179, v118, v96
	v_fma_f32 v156, v178, v117, v97
	v_fma_f32 v155, v179, v119, v97
	v_fma_f32 v151, v180, v88, v96
	v_fma_f32 v153, v180, v120, v97
	v_fma_f32 v120, v183, v80, v96
	v_fma_f32 v118, v184, v81, v96
	v_fma_f32 v115, v185, v82, v96
	v_fma_f32 v80, v64, v157, v140
	v_fma_f32 v64, v64, v156, v140
	v_fma_f32 v81, v65, v154, v140
	v_fma_f32 v65, v65, v155, v140
	v_fma_f32 v82, v66, v151, v140
	v_fma_f32 v66, v66, v153, v140
	v_sub_f32 v89, v89, v96
	v_sub_f32 v91, v91, v97
	v_sub_f32 v90, v90, v96
	v_sub_f32 v146, v148, v97
	v_sub_f32 v186, v149, v97
	v_fma_f32 v148, v182, v121, v97
	v_fma_f32 v149, v181, v89, v96
	v_fma_f32 v150, v181, v91, v97
	v_fma_f32 v147, v182, v90, v96
	v_fma_f32 v121, v183, v146, v97
	v_fma_f32 v119, v184, v186, v97
	v_fma_f32 v117, v185, v83, v97
	v_fma_f32 v83, v67, v149, v140
	v_fma_f32 v67, v67, v150, v140
	v_fma_f32 v80, v72, v147, v80
	v_fma_f32 v72, v72, v148, v64
	v_fma_f32 v64, v73, v120, v81
	v_fma_f32 v73, v73, v121, v65
	v_fma_f32 v65, v74, v118, v82
	v_fma_f32 v66, v74, v119, v66
	v_fma_f32 v74, v75, v115, v83
	v_fma_f32 v67, v75, v117, v67
	v_add_f32_e32 v64, v80, v64
	v_add_f32_e32 v65, v65, v74
	v_add_f32_e32 v72, v72, v73
	v_add_f32_e32 v66, v66, v67
	v_add_f32_e32 v64, v64, v65
	v_add_f32_e32 v66, v72, v66
	s_nop 0
	v_add_f32_dpp v64, v64, v64 row_ror:8 row_mask:0xf bank_mask:0xf bound_ctrl:1
	v_add_f32_dpp v66, v66, v66 row_ror:8 row_mask:0xf bank_mask:0xf bound_ctrl:1
	s_nop 0
	v_add_f32_dpp v64, v64, v64 row_ror:4 row_mask:0xf bank_mask:0xf bound_ctrl:1
	v_add_f32_dpp v66, v66, v66 row_ror:4 row_mask:0xf bank_mask:0xf bound_ctrl:1
	v_add_u32_e32 v146, 0x9000, v103
	v_add_f32_dpp v64, v64, v64 row_ror:2 row_mask:0xf bank_mask:0xf bound_ctrl:1
	v_add_f32_dpp v66, v66, v66 row_ror:2 row_mask:0xf bank_mask:0xf bound_ctrl:1
	s_nop 0
	v_add_f32_dpp v64, v64, v64 row_ror:1 row_mask:0xf bank_mask:0xf bound_ctrl:1
	v_add_f32_dpp v66, v66, v66 row_ror:1 row_mask:0xf bank_mask:0xf bound_ctrl:1
	ds_write2_b32 v146, v64, v66 offset1:16
	s_waitcnt lgkmcnt(0)
	v_sub_f32 v157, v157, v98
	v_sub_f32 v156, v156, v99
	v_sub_f32 v154, v154, v98
	v_sub_f32 v155, v155, v99
	v_sub_f32 v147, v147, v98
	v_sub_f32 v148, v148, v99
	v_sub_f32 v120, v120, v98
	v_sub_f32 v121, v121, v99
	v_sub_f32 v151, v151, v98
	v_sub_f32 v153, v153, v99
	v_sub_f32 v118, v118, v98
	v_sub_f32 v119, v119, v99
	v_fma_f32 v157, v92, v157, v98
	v_fma_f32 v156, v92, v156, v99
	v_fma_f32 v154, v93, v154, v98
	v_fma_f32 v155, v93, v155, v99
	v_fma_f32 v147, v84, v147, v98
	v_fma_f32 v148, v84, v148, v99
	v_fma_f32 v120, v85, v120, v98
	v_fma_f32 v121, v85, v121, v99
	v_fma_f32 v84, v76, v157, v140
	v_fma_f32 v76, v76, v156, v140
	v_fma_f32 v85, v77, v154, v140
	v_fma_f32 v77, v77, v155, v140
	ds_read_b128 v[72:75], v145 offset:1024
	ds_read_b128 v[64:67], v145 offset:1280
	ds_read_b128 v[88:91], v145 offset:9216
	ds_read_b128 v[80:83], v145 offset:9472
	ds_read2_b32 v[96:97], v152 offset0:64 offset1:80
	v_sub_f32 v149, v149, v98
	v_sub_f32 v150, v150, v99
	v_sub_f32 v115, v115, v98
	v_sub_f32 v117, v117, v99
	v_fma_f32 v151, v94, v151, v98
	v_fma_f32 v153, v94, v153, v99
	v_fma_f32 v118, v86, v118, v98
	v_fma_f32 v119, v86, v119, v99
	v_fma_f32 v84, v68, v147, v84
	v_fma_f32 v76, v68, v148, v76
	v_fma_f32 v86, v78, v151, v140
	v_fma_f32 v78, v78, v153, v140
	v_fma_f32 v68, v69, v120, v85
	v_fma_f32 v77, v69, v121, v77
	v_fma_f32 v149, v95, v149, v98
	v_fma_f32 v150, v95, v150, v99
	v_fma_f32 v69, v70, v118, v86
	v_fma_f32 v70, v70, v119, v78
	v_fma_f32 v115, v87, v115, v98
	v_fma_f32 v117, v87, v117, v99
	v_fma_f32 v87, v79, v149, v140
	v_fma_f32 v79, v79, v150, v140
	v_add_f32_e32 v68, v84, v68
	v_fma_f32 v78, v71, v115, v87
	v_fma_f32 v71, v71, v117, v79
	v_add_f32_e32 v76, v76, v77
	v_add_f32_e32 v69, v69, v78
	v_add_f32_e32 v70, v70, v71
	v_add_f32_e32 v68, v68, v69
	v_add_f32_e32 v70, v76, v70
	s_nop 0
	v_add_f32_dpp v68, v68, v68 row_ror:8 row_mask:0xf bank_mask:0xf bound_ctrl:1
	v_add_f32_dpp v70, v70, v70 row_ror:8 row_mask:0xf bank_mask:0xf bound_ctrl:1
	s_nop 0
	v_add_f32_dpp v68, v68, v68 row_ror:4 row_mask:0xf bank_mask:0xf bound_ctrl:1
	v_add_f32_dpp v70, v70, v70 row_ror:4 row_mask:0xf bank_mask:0xf bound_ctrl:1
	s_nop 0
	v_add_f32_dpp v68, v68, v68 row_ror:2 row_mask:0xf bank_mask:0xf bound_ctrl:1
	v_add_f32_dpp v70, v70, v70 row_ror:2 row_mask:0xf bank_mask:0xf bound_ctrl:1
	s_nop 0
	v_add_f32_dpp v68, v68, v68 row_ror:1 row_mask:0xf bank_mask:0xf bound_ctrl:1
	v_add_f32_dpp v70, v70, v70 row_ror:1 row_mask:0xf bank_mask:0xf bound_ctrl:1
	ds_write2_b32 v146, v68, v70 offset0:32 offset1:48
	s_waitcnt lgkmcnt(0)
	v_sub_f32 v157, v157, v96
	v_sub_f32 v156, v156, v97
	v_sub_f32 v154, v154, v96
	v_sub_f32 v155, v155, v97
	v_sub_f32 v147, v147, v96
	v_sub_f32 v148, v148, v97
	v_sub_f32 v120, v120, v96
	v_sub_f32 v121, v121, v97
	v_sub_f32 v151, v151, v96
	v_sub_f32 v153, v153, v97
	v_sub_f32 v118, v118, v96
	v_sub_f32 v119, v119, v97
	v_fma_f32 v157, v88, v157, v96
	v_fma_f32 v156, v88, v156, v97
	v_fma_f32 v154, v89, v154, v96
	v_fma_f32 v155, v89, v155, v97
	v_fma_f32 v147, v80, v147, v96
	v_fma_f32 v148, v80, v148, v97
	v_fma_f32 v120, v81, v120, v96
	v_fma_f32 v121, v81, v121, v97
	v_fma_f32 v80, v72, v157, v140
	v_fma_f32 v72, v72, v156, v140
	v_fma_f32 v81, v73, v154, v140
	v_fma_f32 v73, v73, v155, v140
	ds_read_b128 v[76:79], v145 offset:1536
	ds_read_b128 v[68:71], v145 offset:1792
	ds_read_b128 v[92:95], v145 offset:9728
	ds_read_b128 v[84:87], v145 offset:9984
	ds_read2_b32 v[98:99], v152 offset0:96 offset1:112
	v_sub_f32 v149, v149, v96
	v_sub_f32 v150, v150, v97
	v_sub_f32 v115, v115, v96
	v_sub_f32 v117, v117, v97
	v_fma_f32 v151, v90, v151, v96
	v_fma_f32 v153, v90, v153, v97
	v_fma_f32 v118, v82, v118, v96
	v_fma_f32 v119, v82, v119, v97
	v_fma_f32 v80, v64, v147, v80
	v_fma_f32 v72, v64, v148, v72
	v_fma_f32 v82, v74, v151, v140
	v_fma_f32 v74, v74, v153, v140
	v_fma_f32 v64, v65, v120, v81
	v_fma_f32 v73, v65, v121, v73
	v_fma_f32 v149, v91, v149, v96
	v_fma_f32 v150, v91, v150, v97
	v_fma_f32 v65, v66, v118, v82
	v_fma_f32 v66, v66, v119, v74
	v_fma_f32 v115, v83, v115, v96
	v_fma_f32 v117, v83, v117, v97
	v_fma_f32 v83, v75, v149, v140
	v_fma_f32 v75, v75, v150, v140
	v_add_f32_e32 v64, v80, v64
	v_fma_f32 v74, v67, v115, v83
	v_fma_f32 v67, v67, v117, v75
	v_add_f32_e32 v72, v72, v73
	v_add_f32_e32 v65, v65, v74
	v_add_f32_e32 v66, v66, v67
	v_add_f32_e32 v64, v64, v65
	v_add_f32_e32 v66, v72, v66
	s_nop 0
	v_add_f32_dpp v64, v64, v64 row_ror:8 row_mask:0xf bank_mask:0xf bound_ctrl:1
	v_add_f32_dpp v66, v66, v66 row_ror:8 row_mask:0xf bank_mask:0xf bound_ctrl:1
	s_nop 0
	v_add_f32_dpp v64, v64, v64 row_ror:4 row_mask:0xf bank_mask:0xf bound_ctrl:1
	v_add_f32_dpp v66, v66, v66 row_ror:4 row_mask:0xf bank_mask:0xf bound_ctrl:1
	s_nop 0
	v_add_f32_dpp v64, v64, v64 row_ror:2 row_mask:0xf bank_mask:0xf bound_ctrl:1
	v_add_f32_dpp v66, v66, v66 row_ror:2 row_mask:0xf bank_mask:0xf bound_ctrl:1
	s_nop 0
	v_add_f32_dpp v64, v64, v64 row_ror:1 row_mask:0xf bank_mask:0xf bound_ctrl:1
	v_add_f32_dpp v66, v66, v66 row_ror:1 row_mask:0xf bank_mask:0xf bound_ctrl:1
	ds_write2_b32 v146, v64, v66 offset0:64 offset1:80
	s_waitcnt lgkmcnt(0)
	v_sub_f32 v157, v157, v98
	v_sub_f32 v156, v156, v99
	v_sub_f32 v154, v154, v98
	v_sub_f32 v155, v155, v99
	v_sub_f32 v147, v147, v98
	v_sub_f32 v148, v148, v99
	v_sub_f32 v120, v120, v98
	v_sub_f32 v121, v121, v99
	v_sub_f32 v151, v151, v98
	v_sub_f32 v153, v153, v99
	v_fma_f32 v157, v92, v157, v98
	v_fma_f32 v156, v92, v156, v99
	v_fma_f32 v154, v93, v154, v98
	v_fma_f32 v155, v93, v155, v99
	v_fma_f32 v147, v84, v147, v98
	v_fma_f32 v148, v84, v148, v99
	v_fma_f32 v120, v85, v120, v98
	v_fma_f32 v121, v85, v121, v99
	v_fma_f32 v84, v76, v157, v140
	v_fma_f32 v76, v76, v156, v140
	v_fma_f32 v85, v77, v154, v140
	v_fma_f32 v77, v77, v155, v140
	ds_read_b128 v[72:75], v145 offset:2048
	ds_read_b128 v[64:67], v145 offset:2304
	ds_read_b128 v[88:91], v145 offset:10240
	ds_read_b128 v[80:83], v145 offset:10496
	ds_read2_b32 v[96:97], v152 offset0:128 offset1:144
	v_sub_f32 v149, v149, v98
	v_sub_f32 v150, v150, v99
	v_sub_f32 v118, v118, v98
	v_sub_f32 v119, v119, v99
	v_sub_f32 v178, v115, v98
	v_sub_f32 v179, v117, v99
	v_fma_f32 v151, v94, v151, v98
	v_fma_f32 v153, v94, v153, v99
	v_fma_f32 v115, v86, v118, v98
	v_fma_f32 v117, v86, v119, v99
	v_fma_f32 v84, v68, v147, v84
	v_fma_f32 v76, v68, v148, v76
	v_fma_f32 v86, v78, v151, v140
	v_fma_f32 v78, v78, v153, v140
	v_fma_f32 v68, v69, v120, v85
	v_fma_f32 v77, v69, v121, v77
	v_fma_f32 v149, v95, v149, v98
	v_fma_f32 v150, v95, v150, v99
	v_fma_f32 v69, v70, v115, v86
	v_fma_f32 v70, v70, v117, v78
	v_fma_f32 v98, v87, v178, v98
	v_fma_f32 v99, v87, v179, v99
	v_fma_f32 v87, v79, v149, v140
	v_fma_f32 v79, v79, v150, v140
	v_add_f32_e32 v68, v84, v68
	v_fma_f32 v78, v71, v98, v87
	v_fma_f32 v71, v71, v99, v79
	v_add_f32_e32 v76, v76, v77
	v_add_f32_e32 v69, v69, v78
	v_add_f32_e32 v70, v70, v71
	v_add_f32_e32 v68, v68, v69
	v_add_f32_e32 v70, v76, v70
	s_nop 0
	v_add_f32_dpp v68, v68, v68 row_ror:8 row_mask:0xf bank_mask:0xf bound_ctrl:1
	v_add_f32_dpp v70, v70, v70 row_ror:8 row_mask:0xf bank_mask:0xf bound_ctrl:1
	s_nop 0
	v_add_f32_dpp v68, v68, v68 row_ror:4 row_mask:0xf bank_mask:0xf bound_ctrl:1
	v_add_f32_dpp v70, v70, v70 row_ror:4 row_mask:0xf bank_mask:0xf bound_ctrl:1
	s_nop 0
	v_add_f32_dpp v68, v68, v68 row_ror:2 row_mask:0xf bank_mask:0xf bound_ctrl:1
	v_add_f32_dpp v70, v70, v70 row_ror:2 row_mask:0xf bank_mask:0xf bound_ctrl:1
	s_nop 0
	v_add_f32_dpp v68, v68, v68 row_ror:1 row_mask:0xf bank_mask:0xf bound_ctrl:1
	v_add_f32_dpp v70, v70, v70 row_ror:1 row_mask:0xf bank_mask:0xf bound_ctrl:1
	ds_write2_b32 v146, v68, v70 offset0:96 offset1:112
	s_waitcnt lgkmcnt(0)
	v_sub_f32 v157, v157, v96
	v_sub_f32 v156, v156, v97
	v_sub_f32 v154, v154, v96
	v_sub_f32 v155, v155, v97
	v_sub_f32 v151, v151, v96
	v_sub_f32 v153, v153, v97
	v_sub_f32 v149, v149, v96
	v_sub_f32 v150, v150, v97
	v_sub_f32 v147, v147, v96
	v_sub_f32 v148, v148, v97
	v_sub_f32 v120, v120, v96
	v_sub_f32 v121, v121, v97
	v_fma_f32 v181, v88, v157, v96
	v_fma_f32 v180, v88, v156, v97
	v_fma_f32 v178, v89, v154, v96
	v_fma_f32 v179, v89, v155, v97
	v_fma_f32 v156, v90, v151, v96
	v_fma_f32 v157, v90, v153, v97
	v_fma_f32 v154, v91, v149, v96
	v_fma_f32 v155, v91, v150, v97
	v_fma_f32 v151, v80, v147, v96
	v_fma_f32 v153, v80, v148, v97
	v_fma_f32 v149, v81, v120, v96
	v_fma_f32 v150, v81, v121, v97
	v_fma_f32 v80, v72, v181, v140
	v_fma_f32 v72, v72, v180, v140
	v_fma_f32 v81, v73, v178, v140
	v_fma_f32 v73, v73, v179, v140
	ds_read_b128 v[76:79], v145 offset:2560
	ds_read_b128 v[68:71], v145 offset:2816
	ds_read_b128 v[92:95], v145 offset:10752
	ds_read_b128 v[84:87], v145 offset:11008
	ds_read2_b32 v[118:119], v152 offset0:160 offset1:176
	v_sub_f32 v115, v115, v96
	v_sub_f32 v117, v117, v97
	v_fma_f32 v80, v64, v151, v80
	v_fma_f32 v72, v64, v153, v72
	v_fma_f32 v64, v65, v149, v81
	v_fma_f32 v73, v65, v150, v73
	v_fma_f32 v147, v82, v115, v96
	v_fma_f32 v148, v82, v117, v97
	v_fma_f32 v82, v74, v156, v140
	v_fma_f32 v74, v74, v157, v140
	v_sub_f32 v98, v98, v96
	v_sub_f32 v99, v99, v97
	v_add_f32_e32 v64, v80, v64
	v_fma_f32 v65, v66, v147, v82
	v_fma_f32 v66, v66, v148, v74
	v_fma_f32 v115, v83, v98, v96
	v_fma_f32 v117, v83, v99, v97
	v_fma_f32 v83, v75, v154, v140
	v_fma_f32 v75, v75, v155, v140
	v_add_f32_e32 v72, v72, v73
	v_fma_f32 v74, v67, v115, v83
	v_fma_f32 v67, v67, v117, v75
	v_add_f32_e32 v65, v65, v74
	v_add_f32_e32 v66, v66, v67
	v_add_f32_e32 v64, v64, v65
	v_add_f32_e32 v66, v72, v66
	s_nop 0
	v_add_f32_dpp v64, v64, v64 row_ror:8 row_mask:0xf bank_mask:0xf bound_ctrl:1
	v_add_f32_dpp v66, v66, v66 row_ror:8 row_mask:0xf bank_mask:0xf bound_ctrl:1
	s_nop 0
	v_add_f32_dpp v64, v64, v64 row_ror:4 row_mask:0xf bank_mask:0xf bound_ctrl:1
	v_add_f32_dpp v66, v66, v66 row_ror:4 row_mask:0xf bank_mask:0xf bound_ctrl:1
	s_nop 0
	v_add_f32_dpp v64, v64, v64 row_ror:2 row_mask:0xf bank_mask:0xf bound_ctrl:1
	v_add_f32_dpp v66, v66, v66 row_ror:2 row_mask:0xf bank_mask:0xf bound_ctrl:1
	s_nop 0
	v_add_f32_dpp v64, v64, v64 row_ror:1 row_mask:0xf bank_mask:0xf bound_ctrl:1
	v_add_f32_dpp v66, v66, v66 row_ror:1 row_mask:0xf bank_mask:0xf bound_ctrl:1
	ds_write2_b32 v146, v64, v66 offset0:128 offset1:144
	s_waitcnt lgkmcnt(0)
	v_sub_f32 v64, v181, v118
	v_sub_f32 v65, v180, v119
	v_sub_f32 v66, v178, v118
	v_sub_f32 v67, v179, v119
	v_sub_f32 v156, v156, v118
	v_sub_f32 v151, v151, v118
	v_sub_f32 v153, v153, v119
	v_sub_f32 v149, v149, v118
	v_sub_f32 v150, v150, v119
	v_sub_f32 v147, v147, v118
	v_fma_f32 v181, v92, v64, v118
	v_fma_f32 v180, v92, v65, v119
	v_fma_f32 v178, v93, v66, v118
	v_fma_f32 v179, v93, v67, v119
	ds_read_b128 v[80:83], v145 offset:3072
	ds_read_b128 v[72:75], v145 offset:3328
	ds_read_b128 v[96:99], v145 offset:11264
	ds_read_b128 v[88:91], v145 offset:11520
	ds_read2_b32 v[120:121], v152 offset0:192 offset1:208
	v_fma_f32 v64, v76, v181, v140
	v_fma_f32 v65, v76, v180, v140
	v_fma_f32 v66, v77, v178, v140
	v_fma_f32 v67, v77, v179, v140
	v_sub_f32 v157, v157, v119
	v_sub_f32 v154, v154, v118
	v_sub_f32 v155, v155, v119
	v_sub_f32 v148, v148, v119
	v_sub_f32 v115, v115, v118
	v_sub_f32 v117, v117, v119
	v_fma_f32 v156, v94, v156, v118
	v_fma_f32 v151, v84, v151, v118
	v_fma_f32 v153, v84, v153, v119
	v_fma_f32 v149, v85, v149, v118
	v_fma_f32 v150, v85, v150, v119
	v_fma_f32 v147, v86, v147, v118
	v_fma_f32 v76, v78, v156, v140
	v_fma_f32 v64, v68, v151, v64
	v_fma_f32 v68, v68, v153, v65
	v_fma_f32 v65, v69, v149, v66
	v_fma_f32 v66, v69, v150, v67
	v_fma_f32 v157, v94, v157, v119
	v_fma_f32 v67, v70, v147, v76
	v_fma_f32 v154, v95, v154, v118
	v_fma_f32 v155, v95, v155, v119
	v_fma_f32 v148, v86, v148, v119
	v_fma_f32 v115, v87, v115, v118
	v_fma_f32 v117, v87, v117, v119
	v_fma_f32 v77, v78, v157, v140
	v_fma_f32 v78, v79, v154, v140
	v_fma_f32 v79, v79, v155, v140
	v_add_f32_e32 v64, v64, v65
	v_fma_f32 v69, v70, v148, v77
	v_fma_f32 v70, v71, v115, v78
	v_fma_f32 v71, v71, v117, v79
	v_add_f32_e32 v66, v68, v66
	v_add_f32_e32 v65, v67, v70
	v_add_f32_e32 v67, v69, v71
	v_add_f32_e32 v64, v64, v65
	v_add_f32_e32 v66, v66, v67
	s_nop 0
	v_add_f32_dpp v64, v64, v64 row_ror:8 row_mask:0xf bank_mask:0xf bound_ctrl:1
	v_add_f32_dpp v66, v66, v66 row_ror:8 row_mask:0xf bank_mask:0xf bound_ctrl:1
	s_nop 0
	v_add_f32_dpp v64, v64, v64 row_ror:4 row_mask:0xf bank_mask:0xf bound_ctrl:1
	v_add_f32_dpp v66, v66, v66 row_ror:4 row_mask:0xf bank_mask:0xf bound_ctrl:1
	s_nop 0
	v_add_f32_dpp v64, v64, v64 row_ror:2 row_mask:0xf bank_mask:0xf bound_ctrl:1
	v_add_f32_dpp v66, v66, v66 row_ror:2 row_mask:0xf bank_mask:0xf bound_ctrl:1
	s_nop 0
	v_add_f32_dpp v64, v64, v64 row_ror:1 row_mask:0xf bank_mask:0xf bound_ctrl:1
	v_add_f32_dpp v66, v66, v66 row_ror:1 row_mask:0xf bank_mask:0xf bound_ctrl:1
	ds_write2_b32 v146, v64, v66 offset0:160 offset1:176
	s_waitcnt lgkmcnt(0)
	v_sub_f32 v68, v181, v120
	v_sub_f32 v69, v180, v121
	v_sub_f32 v70, v178, v120
	v_sub_f32 v71, v179, v121
	v_sub_f32 v181, v157, v121
	v_sub_f32 v151, v151, v120
	v_sub_f32 v149, v149, v120
	v_fma_f32 v180, v96, v68, v120
	v_fma_f32 v179, v96, v69, v121
	v_fma_f32 v157, v97, v70, v120
	v_fma_f32 v178, v97, v71, v121
	ds_read_b128 v[76:79], v145 offset:3584
	ds_read_b128 v[64:67], v145 offset:3840
	ds_read_b128 v[92:95], v145 offset:11776
	ds_read_b128 v[84:87], v145 offset:12032
	ds_read2_b32 v[118:119], v152 offset0:224 offset1:240
	v_fma_f32 v68, v80, v180, v140
	v_fma_f32 v69, v80, v179, v140
	v_fma_f32 v70, v81, v157, v140
	v_fma_f32 v71, v81, v178, v140
	v_sub_f32 v156, v156, v120
	v_sub_f32 v154, v154, v120
	v_sub_f32 v182, v155, v121
	v_sub_f32 v183, v153, v121
	v_sub_f32 v184, v150, v121
	v_sub_f32 v185, v147, v120
	v_sub_f32 v186, v115, v120
	v_fma_f32 v155, v98, v156, v120
	v_fma_f32 v150, v88, v151, v120
	v_fma_f32 v151, v88, v183, v121
	v_fma_f32 v147, v89, v149, v120
	v_fma_f32 v149, v89, v184, v121
	v_fma_f32 v115, v90, v185, v120
	v_fma_f32 v80, v82, v155, v140
	v_fma_f32 v68, v72, v150, v68
	v_fma_f32 v72, v72, v151, v69
	v_fma_f32 v69, v73, v147, v70
	v_fma_f32 v70, v73, v149, v71
	v_sub_f32 v148, v148, v121
	v_fma_f32 v71, v74, v115, v80
	v_sub_f32 v187, v117, v121
	v_fma_f32 v156, v98, v181, v121
	v_fma_f32 v153, v99, v154, v120
	v_fma_f32 v154, v99, v182, v121
	v_fma_f32 v117, v90, v148, v121
	v_fma_f32 v96, v91, v186, v120
	v_fma_f32 v97, v91, v187, v121
	v_fma_f32 v81, v82, v156, v140
	v_fma_f32 v82, v83, v153, v140
	v_fma_f32 v83, v83, v154, v140
	v_add_f32_e32 v68, v68, v69
	v_fma_f32 v73, v74, v117, v81
	v_fma_f32 v74, v75, v96, v82
	v_fma_f32 v75, v75, v97, v83
	v_add_f32_e32 v70, v72, v70
	v_add_f32_e32 v69, v71, v74
	v_add_f32_e32 v71, v73, v75
	v_add_f32_e32 v68, v68, v69
	v_add_f32_e32 v70, v70, v71
	s_nop 0
	v_add_f32_dpp v68, v68, v68 row_ror:8 row_mask:0xf bank_mask:0xf bound_ctrl:1
	v_add_f32_dpp v70, v70, v70 row_ror:8 row_mask:0xf bank_mask:0xf bound_ctrl:1
	s_nop 0
	v_add_f32_dpp v68, v68, v68 row_ror:4 row_mask:0xf bank_mask:0xf bound_ctrl:1
	v_add_f32_dpp v70, v70, v70 row_ror:4 row_mask:0xf bank_mask:0xf bound_ctrl:1
	s_nop 0
	v_add_f32_dpp v68, v68, v68 row_ror:2 row_mask:0xf bank_mask:0xf bound_ctrl:1
	v_add_f32_dpp v70, v70, v70 row_ror:2 row_mask:0xf bank_mask:0xf bound_ctrl:1
	s_nop 0
	v_add_f32_dpp v68, v68, v68 row_ror:1 row_mask:0xf bank_mask:0xf bound_ctrl:1
	v_add_f32_dpp v70, v70, v70 row_ror:1 row_mask:0xf bank_mask:0xf bound_ctrl:1
	ds_write2_b32 v146, v68, v70 offset0:192 offset1:208
	s_waitcnt lgkmcnt(0)
	v_sub_f32 v157, v157, v118
	v_sub_f32 v178, v178, v119
	v_sub_f32 v150, v150, v118
	v_sub_f32 v151, v151, v119
	v_sub_f32 v147, v147, v118
	v_sub_f32 v149, v149, v119
	v_sub_f32 v120, v180, v118
	v_sub_f32 v121, v179, v119
	v_sub_f32 v155, v155, v118
	v_sub_f32 v156, v156, v119
	v_fma_f32 v157, v93, v157, v118
	v_fma_f32 v178, v93, v178, v119
	v_fma_f32 v180, v92, v120, v118
	v_fma_f32 v179, v92, v121, v119
	v_fma_f32 v150, v84, v150, v118
	v_fma_f32 v151, v84, v151, v119
	v_fma_f32 v147, v85, v147, v118
	v_fma_f32 v149, v85, v149, v119
	v_fma_f32 v84, v76, v180, v140
	v_fma_f32 v76, v76, v179, v140
	v_fma_f32 v85, v77, v157, v140
	v_fma_f32 v77, v77, v178, v140
	v_sub_f32 v153, v153, v118
	v_sub_f32 v154, v154, v119
	v_sub_f32 v115, v115, v118
	v_sub_f32 v117, v117, v119
	v_fma_f32 v155, v94, v155, v118
	v_fma_f32 v156, v94, v156, v119
	v_fma_f32 v84, v64, v150, v84
	v_fma_f32 v76, v64, v151, v76
	v_fma_f32 v120, v86, v115, v118
	v_fma_f32 v121, v86, v117, v119
	v_fma_f32 v86, v78, v155, v140
	v_fma_f32 v78, v78, v156, v140
	v_fma_f32 v64, v65, v147, v85
	v_fma_f32 v77, v65, v149, v77
	ds_read_b128 v[72:75], v145 offset:4096
	ds_read_b128 v[68:71], v145 offset:4352
	ds_read_b128 v[88:91], v145 offset:12288
	ds_read_b128 v[80:83], v145 offset:12544
	v_fma_f32 v65, v66, v120, v86
	v_fma_f32 v66, v66, v121, v78
	v_sub_f32 v96, v96, v118
	v_sub_f32 v97, v97, v119
	v_fma_f32 v153, v95, v153, v118
	v_fma_f32 v154, v95, v154, v119
	v_add_f32_e32 v64, v84, v64
	v_fma_f32 v115, v87, v96, v118
	v_fma_f32 v117, v87, v97, v119
	v_fma_f32 v87, v79, v153, v140
	v_fma_f32 v79, v79, v154, v140
	v_add_f32_e32 v76, v76, v77
	v_fma_f32 v78, v67, v115, v87
	v_fma_f32 v67, v67, v117, v79
	v_add_u32_e32 v148, 0x4400, v103
	v_add_f32_e32 v65, v65, v78
	v_add_f32_e32 v66, v66, v67
	v_add_f32_e32 v64, v64, v65
	v_add_f32_e32 v66, v76, v66
	ds_read2_b32 v[98:99], v148 offset1:16
	v_add_f32_dpp v64, v64, v64 row_ror:8 row_mask:0xf bank_mask:0xf bound_ctrl:1
	v_add_f32_dpp v66, v66, v66 row_ror:8 row_mask:0xf bank_mask:0xf bound_ctrl:1
	s_nop 0
	v_add_f32_dpp v64, v64, v64 row_ror:4 row_mask:0xf bank_mask:0xf bound_ctrl:1
	v_add_f32_dpp v66, v66, v66 row_ror:4 row_mask:0xf bank_mask:0xf bound_ctrl:1
	s_nop 0
	v_add_f32_dpp v64, v64, v64 row_ror:2 row_mask:0xf bank_mask:0xf bound_ctrl:1
	v_add_f32_dpp v66, v66, v66 row_ror:2 row_mask:0xf bank_mask:0xf bound_ctrl:1
	s_nop 0
	v_add_f32_dpp v64, v64, v64 row_ror:1 row_mask:0xf bank_mask:0xf bound_ctrl:1
	v_add_f32_dpp v66, v66, v66 row_ror:1 row_mask:0xf bank_mask:0xf bound_ctrl:1
	ds_write2_b32 v146, v64, v66 offset0:224 offset1:240
	s_waitcnt lgkmcnt(0)
	v_sub_f32 v157, v157, v98
	v_sub_f32 v150, v150, v98
	v_sub_f32 v118, v180, v98
	v_sub_f32 v119, v179, v99
	v_sub_f32 v180, v178, v99
	v_sub_f32 v155, v155, v98
	v_sub_f32 v181, v156, v99
	v_sub_f32 v183, v151, v99
	v_sub_f32 v147, v147, v98
	v_sub_f32 v184, v149, v99
	v_sub_f32 v185, v120, v98
	v_sub_f32 v186, v121, v99
	v_fma_f32 v179, v88, v118, v98
	v_fma_f32 v178, v88, v119, v99
	v_fma_f32 v156, v89, v157, v98
	v_fma_f32 v157, v89, v180, v99
	v_fma_f32 v149, v80, v150, v98
	v_fma_f32 v150, v80, v183, v99
	v_fma_f32 v120, v81, v147, v98
	v_fma_f32 v121, v81, v184, v99
	v_fma_f32 v80, v72, v179, v140
	v_fma_f32 v72, v72, v178, v140
	v_fma_f32 v81, v73, v156, v140
	v_fma_f32 v73, v73, v157, v140
	ds_read_b128 v[76:79], v145 offset:4608
	ds_read_b128 v[64:67], v145 offset:4864
	ds_read_b128 v[92:95], v145 offset:12800
	ds_read_b128 v[84:87], v145 offset:13056
	ds_read2_b32 v[96:97], v148 offset0:32 offset1:48
	v_sub_f32 v153, v153, v98
	v_sub_f32 v182, v154, v99
	v_sub_f32 v115, v115, v98
	v_sub_f32 v117, v117, v99
	v_fma_f32 v154, v90, v155, v98
	v_fma_f32 v155, v90, v181, v99
	v_fma_f32 v118, v82, v185, v98
	v_fma_f32 v119, v82, v186, v99
	v_fma_f32 v80, v68, v149, v80
	v_fma_f32 v72, v68, v150, v72
	v_fma_f32 v82, v74, v154, v140
	v_fma_f32 v74, v74, v155, v140
	v_fma_f32 v68, v69, v120, v81
	v_fma_f32 v73, v69, v121, v73
	v_fma_f32 v151, v91, v153, v98
	v_fma_f32 v153, v91, v182, v99
	v_fma_f32 v69, v70, v118, v82
	v_fma_f32 v70, v70, v119, v74
	v_fma_f32 v115, v83, v115, v98
	v_fma_f32 v117, v83, v117, v99
	v_fma_f32 v83, v75, v151, v140
	v_fma_f32 v75, v75, v153, v140
	v_add_f32_e32 v68, v80, v68
	v_fma_f32 v74, v71, v115, v83
	v_fma_f32 v71, v71, v117, v75
	v_add_f32_e32 v72, v72, v73
	v_add_f32_e32 v69, v69, v74
	v_add_f32_e32 v70, v70, v71
	v_add_f32_e32 v68, v68, v69
	v_add_f32_e32 v70, v72, v70
	s_nop 0
	v_add_f32_dpp v68, v68, v68 row_ror:8 row_mask:0xf bank_mask:0xf bound_ctrl:1
	v_add_f32_dpp v70, v70, v70 row_ror:8 row_mask:0xf bank_mask:0xf bound_ctrl:1
	s_nop 0
	v_add_f32_dpp v68, v68, v68 row_ror:4 row_mask:0xf bank_mask:0xf bound_ctrl:1
	v_add_f32_dpp v70, v70, v70 row_ror:4 row_mask:0xf bank_mask:0xf bound_ctrl:1
	v_add_u32_e32 v147, 0x9400, v103
	v_add_f32_dpp v68, v68, v68 row_ror:2 row_mask:0xf bank_mask:0xf bound_ctrl:1
	v_add_f32_dpp v70, v70, v70 row_ror:2 row_mask:0xf bank_mask:0xf bound_ctrl:1
	s_nop 0
	v_add_f32_dpp v68, v68, v68 row_ror:1 row_mask:0xf bank_mask:0xf bound_ctrl:1
	v_add_f32_dpp v70, v70, v70 row_ror:1 row_mask:0xf bank_mask:0xf bound_ctrl:1
	ds_write2_b32 v147, v68, v70 offset1:16
	s_waitcnt lgkmcnt(0)
	v_sub_f32 v179, v179, v96
	v_sub_f32 v178, v178, v97
	v_sub_f32 v156, v156, v96
	v_sub_f32 v157, v157, v97
	v_sub_f32 v149, v149, v96
	v_sub_f32 v150, v150, v97
	v_sub_f32 v120, v120, v96
	v_sub_f32 v121, v121, v97
	v_sub_f32 v154, v154, v96
	v_sub_f32 v155, v155, v97
	v_sub_f32 v118, v118, v96
	v_sub_f32 v119, v119, v97
	v_fma_f32 v179, v92, v179, v96
	v_fma_f32 v178, v92, v178, v97
	v_fma_f32 v156, v93, v156, v96
	v_fma_f32 v157, v93, v157, v97
	v_fma_f32 v149, v84, v149, v96
	v_fma_f32 v150, v84, v150, v97
	v_fma_f32 v120, v85, v120, v96
	v_fma_f32 v121, v85, v121, v97
	v_fma_f32 v84, v76, v179, v140
	v_fma_f32 v76, v76, v178, v140
	v_fma_f32 v85, v77, v156, v140
	v_fma_f32 v77, v77, v157, v140
	ds_read_b128 v[72:75], v145 offset:5120
	ds_read_b128 v[68:71], v145 offset:5376
	ds_read_b128 v[88:91], v145 offset:13312
	ds_read_b128 v[80:83], v145 offset:13568
	ds_read2_b32 v[98:99], v148 offset0:64 offset1:80
	v_sub_f32 v151, v151, v96
	v_sub_f32 v153, v153, v97
	v_sub_f32 v115, v115, v96
	v_sub_f32 v117, v117, v97
	v_fma_f32 v154, v94, v154, v96
	v_fma_f32 v155, v94, v155, v97
	v_fma_f32 v118, v86, v118, v96
	v_fma_f32 v119, v86, v119, v97
	v_fma_f32 v84, v64, v149, v84
	v_fma_f32 v76, v64, v150, v76
	v_fma_f32 v86, v78, v154, v140
	v_fma_f32 v78, v78, v155, v140
	v_fma_f32 v64, v65, v120, v85
	v_fma_f32 v77, v65, v121, v77
	v_fma_f32 v151, v95, v151, v96
	v_fma_f32 v153, v95, v153, v97
	v_fma_f32 v65, v66, v118, v86
	v_fma_f32 v66, v66, v119, v78
	v_fma_f32 v115, v87, v115, v96
	v_fma_f32 v117, v87, v117, v97
	v_fma_f32 v87, v79, v151, v140
	v_fma_f32 v79, v79, v153, v140
	v_add_f32_e32 v64, v84, v64
	v_fma_f32 v78, v67, v115, v87
	v_fma_f32 v67, v67, v117, v79
	v_add_f32_e32 v76, v76, v77
	v_add_f32_e32 v65, v65, v78
	v_add_f32_e32 v66, v66, v67
	v_add_f32_e32 v64, v64, v65
	v_add_f32_e32 v66, v76, v66
	s_nop 0
	v_add_f32_dpp v64, v64, v64 row_ror:8 row_mask:0xf bank_mask:0xf bound_ctrl:1
	v_add_f32_dpp v66, v66, v66 row_ror:8 row_mask:0xf bank_mask:0xf bound_ctrl:1
	s_nop 0
	v_add_f32_dpp v64, v64, v64 row_ror:4 row_mask:0xf bank_mask:0xf bound_ctrl:1
	v_add_f32_dpp v66, v66, v66 row_ror:4 row_mask:0xf bank_mask:0xf bound_ctrl:1
	s_nop 0
	v_add_f32_dpp v64, v64, v64 row_ror:2 row_mask:0xf bank_mask:0xf bound_ctrl:1
	v_add_f32_dpp v66, v66, v66 row_ror:2 row_mask:0xf bank_mask:0xf bound_ctrl:1
	s_nop 0
	v_add_f32_dpp v64, v64, v64 row_ror:1 row_mask:0xf bank_mask:0xf bound_ctrl:1
	v_add_f32_dpp v66, v66, v66 row_ror:1 row_mask:0xf bank_mask:0xf bound_ctrl:1
	ds_write2_b32 v147, v64, v66 offset0:32 offset1:48
	s_waitcnt lgkmcnt(0)
	v_sub_f32 v179, v179, v98
	v_sub_f32 v178, v178, v99
	v_sub_f32 v156, v156, v98
	v_sub_f32 v157, v157, v99
	v_sub_f32 v149, v149, v98
	v_sub_f32 v150, v150, v99
	v_sub_f32 v120, v120, v98
	v_sub_f32 v121, v121, v99
	v_sub_f32 v154, v154, v98
	v_sub_f32 v155, v155, v99
	v_sub_f32 v118, v118, v98
	v_sub_f32 v119, v119, v99
	v_fma_f32 v179, v88, v179, v98
	v_fma_f32 v178, v88, v178, v99
	v_fma_f32 v156, v89, v156, v98
	v_fma_f32 v157, v89, v157, v99
	v_fma_f32 v149, v80, v149, v98
	v_fma_f32 v150, v80, v150, v99
	v_fma_f32 v120, v81, v120, v98
	v_fma_f32 v121, v81, v121, v99
	v_fma_f32 v80, v72, v179, v140
	v_fma_f32 v72, v72, v178, v140
	v_fma_f32 v81, v73, v156, v140
	v_fma_f32 v73, v73, v157, v140
	ds_read_b128 v[76:79], v145 offset:5632
	ds_read_b128 v[64:67], v145 offset:5888
	ds_read_b128 v[92:95], v145 offset:13824
	ds_read_b128 v[84:87], v145 offset:14080
	ds_read2_b32 v[96:97], v148 offset0:96 offset1:112
	v_sub_f32 v151, v151, v98
	v_sub_f32 v153, v153, v99
	v_sub_f32 v115, v115, v98
	v_sub_f32 v117, v117, v99
	v_fma_f32 v154, v90, v154, v98
	v_fma_f32 v155, v90, v155, v99
	v_fma_f32 v118, v82, v118, v98
	v_fma_f32 v119, v82, v119, v99
	v_fma_f32 v80, v68, v149, v80
	v_fma_f32 v72, v68, v150, v72
	v_fma_f32 v82, v74, v154, v140
	v_fma_f32 v74, v74, v155, v140
	v_fma_f32 v68, v69, v120, v81
	v_fma_f32 v73, v69, v121, v73
	v_fma_f32 v151, v91, v151, v98
	v_fma_f32 v153, v91, v153, v99
	v_fma_f32 v69, v70, v118, v82
	v_fma_f32 v70, v70, v119, v74
	v_fma_f32 v115, v83, v115, v98
	v_fma_f32 v117, v83, v117, v99
	v_fma_f32 v83, v75, v151, v140
	v_fma_f32 v75, v75, v153, v140
	v_add_f32_e32 v68, v80, v68
	v_fma_f32 v74, v71, v115, v83
	v_fma_f32 v71, v71, v117, v75
	v_add_f32_e32 v72, v72, v73
	v_add_f32_e32 v69, v69, v74
	v_add_f32_e32 v70, v70, v71
	v_add_f32_e32 v68, v68, v69
	v_add_f32_e32 v70, v72, v70
	s_nop 0
	v_add_f32_dpp v68, v68, v68 row_ror:8 row_mask:0xf bank_mask:0xf bound_ctrl:1
	v_add_f32_dpp v70, v70, v70 row_ror:8 row_mask:0xf bank_mask:0xf bound_ctrl:1
	s_nop 0
	v_add_f32_dpp v68, v68, v68 row_ror:4 row_mask:0xf bank_mask:0xf bound_ctrl:1
	v_add_f32_dpp v70, v70, v70 row_ror:4 row_mask:0xf bank_mask:0xf bound_ctrl:1
	s_nop 0
	v_add_f32_dpp v68, v68, v68 row_ror:2 row_mask:0xf bank_mask:0xf bound_ctrl:1
	v_add_f32_dpp v70, v70, v70 row_ror:2 row_mask:0xf bank_mask:0xf bound_ctrl:1
	s_nop 0
	v_add_f32_dpp v68, v68, v68 row_ror:1 row_mask:0xf bank_mask:0xf bound_ctrl:1
	v_add_f32_dpp v70, v70, v70 row_ror:1 row_mask:0xf bank_mask:0xf bound_ctrl:1
	ds_write2_b32 v147, v68, v70 offset0:64 offset1:80
	s_waitcnt lgkmcnt(0)
	v_sub_f32 v179, v179, v96
	v_sub_f32 v178, v178, v97
	v_sub_f32 v156, v156, v96
	v_sub_f32 v157, v157, v97
	v_sub_f32 v149, v149, v96
	v_sub_f32 v150, v150, v97
	v_sub_f32 v120, v120, v96
	v_sub_f32 v121, v121, v97
	v_sub_f32 v154, v154, v96
	v_sub_f32 v155, v155, v97
	v_sub_f32 v118, v118, v96
	v_sub_f32 v119, v119, v97
	v_fma_f32 v179, v92, v179, v96
	v_fma_f32 v178, v92, v178, v97
	v_fma_f32 v156, v93, v156, v96
	v_fma_f32 v157, v93, v157, v97
	v_fma_f32 v149, v84, v149, v96
	v_fma_f32 v150, v84, v150, v97
	v_fma_f32 v120, v85, v120, v96
	v_fma_f32 v121, v85, v121, v97
	v_fma_f32 v84, v76, v179, v140
	v_fma_f32 v76, v76, v178, v140
	v_fma_f32 v85, v77, v156, v140
	v_fma_f32 v77, v77, v157, v140
	ds_read_b128 v[72:75], v145 offset:6144
	ds_read_b128 v[68:71], v145 offset:6400
	ds_read_b128 v[88:91], v145 offset:14336
	ds_read_b128 v[80:83], v145 offset:14592
	ds_read2_b32 v[98:99], v148 offset0:128 offset1:144
	v_sub_f32 v151, v151, v96
	v_sub_f32 v153, v153, v97
	v_sub_f32 v115, v115, v96
	v_sub_f32 v117, v117, v97
	v_fma_f32 v154, v94, v154, v96
	v_fma_f32 v155, v94, v155, v97
	v_fma_f32 v118, v86, v118, v96
	v_fma_f32 v119, v86, v119, v97
	v_fma_f32 v84, v64, v149, v84
	v_fma_f32 v76, v64, v150, v76
	v_fma_f32 v86, v78, v154, v140
	v_fma_f32 v78, v78, v155, v140
	v_fma_f32 v64, v65, v120, v85
	v_fma_f32 v77, v65, v121, v77
	v_fma_f32 v151, v95, v151, v96
	v_fma_f32 v153, v95, v153, v97
	v_fma_f32 v65, v66, v118, v86
	v_fma_f32 v66, v66, v119, v78
	v_fma_f32 v115, v87, v115, v96
	v_fma_f32 v117, v87, v117, v97
	v_fma_f32 v87, v79, v151, v140
	v_fma_f32 v79, v79, v153, v140
	v_add_f32_e32 v64, v84, v64
	v_fma_f32 v78, v67, v115, v87
	v_fma_f32 v67, v67, v117, v79
	v_add_f32_e32 v76, v76, v77
	v_add_f32_e32 v65, v65, v78
	v_add_f32_e32 v66, v66, v67
	v_add_f32_e32 v64, v64, v65
	v_add_f32_e32 v66, v76, v66
	s_nop 0
	v_add_f32_dpp v64, v64, v64 row_ror:8 row_mask:0xf bank_mask:0xf bound_ctrl:1
	v_add_f32_dpp v66, v66, v66 row_ror:8 row_mask:0xf bank_mask:0xf bound_ctrl:1
	s_nop 0
	v_add_f32_dpp v64, v64, v64 row_ror:4 row_mask:0xf bank_mask:0xf bound_ctrl:1
	v_add_f32_dpp v66, v66, v66 row_ror:4 row_mask:0xf bank_mask:0xf bound_ctrl:1
	s_nop 0
	v_add_f32_dpp v64, v64, v64 row_ror:2 row_mask:0xf bank_mask:0xf bound_ctrl:1
	v_add_f32_dpp v66, v66, v66 row_ror:2 row_mask:0xf bank_mask:0xf bound_ctrl:1
	s_nop 0
	v_add_f32_dpp v64, v64, v64 row_ror:1 row_mask:0xf bank_mask:0xf bound_ctrl:1
	v_add_f32_dpp v66, v66, v66 row_ror:1 row_mask:0xf bank_mask:0xf bound_ctrl:1
	ds_write2_b32 v147, v64, v66 offset0:96 offset1:112
	s_waitcnt lgkmcnt(0)
	v_sub_f32 v179, v179, v98
	v_sub_f32 v178, v178, v99
	v_sub_f32 v156, v156, v98
	v_sub_f32 v157, v157, v99
	v_sub_f32 v149, v149, v98
	v_sub_f32 v150, v150, v99
	v_sub_f32 v120, v120, v98
	v_sub_f32 v121, v121, v99
	v_sub_f32 v154, v154, v98
	v_sub_f32 v155, v155, v99
	v_sub_f32 v118, v118, v98
	v_sub_f32 v119, v119, v99
	v_fma_f32 v179, v88, v179, v98
	v_fma_f32 v178, v88, v178, v99
	v_fma_f32 v156, v89, v156, v98
	v_fma_f32 v157, v89, v157, v99
	v_fma_f32 v149, v80, v149, v98
	v_fma_f32 v150, v80, v150, v99
	v_fma_f32 v120, v81, v120, v98
	v_fma_f32 v121, v81, v121, v99
	v_fma_f32 v80, v72, v179, v140
	v_fma_f32 v72, v72, v178, v140
	v_fma_f32 v81, v73, v156, v140
	v_fma_f32 v73, v73, v157, v140
	ds_read_b128 v[76:79], v145 offset:6656
	ds_read_b128 v[64:67], v145 offset:6912
	ds_read_b128 v[92:95], v145 offset:14848
	ds_read_b128 v[84:87], v145 offset:15104
	ds_read2_b32 v[96:97], v148 offset0:160 offset1:176
	v_sub_f32 v151, v151, v98
	v_sub_f32 v153, v153, v99
	v_sub_f32 v115, v115, v98
	v_sub_f32 v117, v117, v99
	v_fma_f32 v154, v90, v154, v98
	v_fma_f32 v155, v90, v155, v99
	v_fma_f32 v118, v82, v118, v98
	v_fma_f32 v119, v82, v119, v99
	v_fma_f32 v80, v68, v149, v80
	v_fma_f32 v72, v68, v150, v72
	v_fma_f32 v82, v74, v154, v140
	v_fma_f32 v74, v74, v155, v140
	v_fma_f32 v68, v69, v120, v81
	v_fma_f32 v73, v69, v121, v73
	v_fma_f32 v151, v91, v151, v98
	v_fma_f32 v153, v91, v153, v99
	v_fma_f32 v69, v70, v118, v82
	v_fma_f32 v70, v70, v119, v74
	v_fma_f32 v115, v83, v115, v98
	v_fma_f32 v117, v83, v117, v99
	v_fma_f32 v83, v75, v151, v140
	v_fma_f32 v75, v75, v153, v140
	v_add_f32_e32 v68, v80, v68
	v_fma_f32 v74, v71, v115, v83
	v_fma_f32 v71, v71, v117, v75
	v_add_f32_e32 v72, v72, v73
	v_add_f32_e32 v69, v69, v74
	v_add_f32_e32 v70, v70, v71
	v_add_f32_e32 v68, v68, v69
	v_add_f32_e32 v70, v72, v70
	s_nop 0
	v_add_f32_dpp v68, v68, v68 row_ror:8 row_mask:0xf bank_mask:0xf bound_ctrl:1
	v_add_f32_dpp v70, v70, v70 row_ror:8 row_mask:0xf bank_mask:0xf bound_ctrl:1
	s_nop 0
	v_add_f32_dpp v68, v68, v68 row_ror:4 row_mask:0xf bank_mask:0xf bound_ctrl:1
	v_add_f32_dpp v70, v70, v70 row_ror:4 row_mask:0xf bank_mask:0xf bound_ctrl:1
	s_nop 0
	v_add_f32_dpp v68, v68, v68 row_ror:2 row_mask:0xf bank_mask:0xf bound_ctrl:1
	v_add_f32_dpp v70, v70, v70 row_ror:2 row_mask:0xf bank_mask:0xf bound_ctrl:1
	s_nop 0
	v_add_f32_dpp v68, v68, v68 row_ror:1 row_mask:0xf bank_mask:0xf bound_ctrl:1
	v_add_f32_dpp v70, v70, v70 row_ror:1 row_mask:0xf bank_mask:0xf bound_ctrl:1
	ds_write2_b32 v147, v68, v70 offset0:128 offset1:144
	s_waitcnt lgkmcnt(0)
	v_sub_f32 v179, v179, v96
	v_sub_f32 v178, v178, v97
	v_sub_f32 v156, v156, v96
	v_sub_f32 v157, v157, v97
	v_sub_f32 v149, v149, v96
	v_sub_f32 v150, v150, v97
	v_sub_f32 v120, v120, v96
	v_sub_f32 v121, v121, v97
	v_sub_f32 v154, v154, v96
	v_sub_f32 v155, v155, v97
	v_sub_f32 v118, v118, v96
	v_sub_f32 v119, v119, v97
	v_fma_f32 v179, v92, v179, v96
	v_fma_f32 v178, v92, v178, v97
	v_fma_f32 v156, v93, v156, v96
	v_fma_f32 v157, v93, v157, v97
	v_fma_f32 v149, v84, v149, v96
	v_fma_f32 v150, v84, v150, v97
	v_fma_f32 v120, v85, v120, v96
	v_fma_f32 v121, v85, v121, v97
	v_fma_f32 v84, v76, v179, v140
	v_fma_f32 v76, v76, v178, v140
	v_fma_f32 v85, v77, v156, v140
	v_fma_f32 v77, v77, v157, v140
	ds_read_b128 v[72:75], v145 offset:7168
	ds_read_b128 v[68:71], v145 offset:7424
	ds_read_b128 v[88:91], v145 offset:15360
	ds_read_b128 v[80:83], v145 offset:15616
	ds_read2_b32 v[98:99], v148 offset0:192 offset1:208
	v_sub_f32 v151, v151, v96
	v_sub_f32 v153, v153, v97
	v_sub_f32 v115, v115, v96
	v_sub_f32 v117, v117, v97
	v_fma_f32 v154, v94, v154, v96
	v_fma_f32 v155, v94, v155, v97
	v_fma_f32 v118, v86, v118, v96
	v_fma_f32 v119, v86, v119, v97
	v_fma_f32 v84, v64, v149, v84
	v_fma_f32 v76, v64, v150, v76
	v_fma_f32 v86, v78, v154, v140
	v_fma_f32 v78, v78, v155, v140
	v_fma_f32 v64, v65, v120, v85
	v_fma_f32 v77, v65, v121, v77
	v_fma_f32 v151, v95, v151, v96
	v_fma_f32 v153, v95, v153, v97
	v_fma_f32 v65, v66, v118, v86
	v_fma_f32 v66, v66, v119, v78
	v_fma_f32 v115, v87, v115, v96
	v_fma_f32 v117, v87, v117, v97
	v_fma_f32 v87, v79, v151, v140
	v_fma_f32 v79, v79, v153, v140
	v_add_f32_e32 v64, v84, v64
	v_fma_f32 v78, v67, v115, v87
	v_fma_f32 v67, v67, v117, v79
	v_add_f32_e32 v76, v76, v77
	v_add_f32_e32 v65, v65, v78
	v_add_f32_e32 v66, v66, v67
	v_add_f32_e32 v64, v64, v65
	v_add_f32_e32 v66, v76, v66
	s_nop 0
	v_add_f32_dpp v64, v64, v64 row_ror:8 row_mask:0xf bank_mask:0xf bound_ctrl:1
	v_add_f32_dpp v66, v66, v66 row_ror:8 row_mask:0xf bank_mask:0xf bound_ctrl:1
	s_nop 0
	v_add_f32_dpp v64, v64, v64 row_ror:4 row_mask:0xf bank_mask:0xf bound_ctrl:1
	v_add_f32_dpp v66, v66, v66 row_ror:4 row_mask:0xf bank_mask:0xf bound_ctrl:1
	s_nop 0
	v_add_f32_dpp v64, v64, v64 row_ror:2 row_mask:0xf bank_mask:0xf bound_ctrl:1
	v_add_f32_dpp v66, v66, v66 row_ror:2 row_mask:0xf bank_mask:0xf bound_ctrl:1
	s_nop 0
	v_add_f32_dpp v64, v64, v64 row_ror:1 row_mask:0xf bank_mask:0xf bound_ctrl:1
	v_add_f32_dpp v66, v66, v66 row_ror:1 row_mask:0xf bank_mask:0xf bound_ctrl:1
	ds_write2_b32 v147, v64, v66 offset0:160 offset1:176
	s_waitcnt lgkmcnt(0)
	v_sub_f32 v179, v179, v98
	v_sub_f32 v178, v178, v99
	v_sub_f32 v156, v156, v98
	v_sub_f32 v157, v157, v99
	v_sub_f32 v154, v154, v98
	v_sub_f32 v155, v155, v99
	v_sub_f32 v180, v151, v98
	v_sub_f32 v153, v153, v99
	v_sub_f32 v181, v149, v98
	v_sub_f32 v182, v150, v99
	v_sub_f32 v183, v120, v98
	v_sub_f32 v184, v121, v99
	v_sub_f32 v185, v118, v98
	v_sub_f32 v186, v119, v99
	v_sub_f32 v187, v115, v98
	v_sub_f32 v188, v117, v99
	v_fma_f32 v151, v88, v179, v98
	v_fma_f32 v150, v88, v178, v99
	v_fma_f32 v121, v89, v156, v98
	v_fma_f32 v149, v89, v157, v99
	v_fma_f32 v119, v90, v154, v98
	v_fma_f32 v120, v90, v155, v99
	v_fma_f32 v117, v91, v180, v98
	v_fma_f32 v118, v91, v153, v99
	v_fma_f32 v91, v80, v181, v98
	v_fma_f32 v115, v80, v182, v99
	v_fma_f32 v89, v81, v183, v98
	v_fma_f32 v90, v81, v184, v99
	v_fma_f32 v88, v82, v185, v98
	v_fma_f32 v80, v83, v187, v98
	v_fma_f32 v81, v83, v188, v99
	v_fma_f32 v83, v72, v151, v140
	v_fma_f32 v72, v72, v150, v140
	v_fma_f32 v98, v73, v121, v140
	v_fma_f32 v73, v73, v149, v140
	ds_read_b128 v[76:79], v145 offset:7680
	ds_read_b128 v[64:67], v145 offset:7936
	ds_read_b128 v[92:95], v145 offset:15872
	ds_read_b128 v[84:87], v145 offset:16128
	ds_read2_b32 v[96:97], v148 offset0:224 offset1:240
	v_fma_f32 v82, v82, v186, v99
	v_fma_f32 v99, v74, v119, v140
	v_fma_f32 v74, v74, v120, v140
	v_fma_f32 v83, v68, v91, v83
	v_fma_f32 v72, v68, v115, v72
	v_fma_f32 v68, v69, v89, v98
	v_fma_f32 v73, v69, v90, v73
	v_fma_f32 v69, v70, v88, v99
	v_fma_f32 v70, v70, v82, v74
	v_fma_f32 v153, v75, v117, v140
	v_fma_f32 v75, v75, v118, v140
	v_add_f32_e32 v68, v83, v68
	v_fma_f32 v74, v71, v80, v153
	v_fma_f32 v71, v71, v81, v75
	v_add_f32_e32 v72, v72, v73
	v_add_f32_e32 v69, v69, v74
	v_add_f32_e32 v70, v70, v71
	v_add_f32_e32 v68, v68, v69
	v_add_f32_e32 v70, v72, v70
	s_nop 0
	v_add_f32_dpp v68, v68, v68 row_ror:8 row_mask:0xf bank_mask:0xf bound_ctrl:1
	v_add_f32_dpp v70, v70, v70 row_ror:8 row_mask:0xf bank_mask:0xf bound_ctrl:1
	s_nop 0
	v_add_f32_dpp v68, v68, v68 row_ror:4 row_mask:0xf bank_mask:0xf bound_ctrl:1
	v_add_f32_dpp v70, v70, v70 row_ror:4 row_mask:0xf bank_mask:0xf bound_ctrl:1
	s_nop 0
	v_add_f32_dpp v68, v68, v68 row_ror:2 row_mask:0xf bank_mask:0xf bound_ctrl:1
	v_add_f32_dpp v70, v70, v70 row_ror:2 row_mask:0xf bank_mask:0xf bound_ctrl:1
	s_nop 0
	v_add_f32_dpp v68, v68, v68 row_ror:1 row_mask:0xf bank_mask:0xf bound_ctrl:1
	v_add_f32_dpp v70, v70, v70 row_ror:1 row_mask:0xf bank_mask:0xf bound_ctrl:1
	ds_write2_b32 v147, v68, v70 offset0:192 offset1:208
	s_waitcnt lgkmcnt(0)
	v_sub_f32 v72, v119, v96
	v_sub_f32 v73, v120, v97
	v_sub_f32 v74, v117, v96
	v_sub_f32 v68, v151, v96
	v_sub_f32 v69, v150, v97
	v_sub_f32 v70, v121, v96
	v_sub_f32 v71, v149, v97
	v_sub_f32 v75, v118, v97
	v_fma_f32 v120, v94, v72, v96
	v_fma_f32 v154, v92, v68, v96
	v_fma_f32 v151, v92, v69, v97
	v_fma_f32 v149, v93, v70, v96
	v_fma_f32 v121, v94, v73, v97
	v_fma_f32 v94, v95, v74, v96
	v_sub_f32 v83, v91, v96
	v_fma_f32 v72, v76, v154, v140
	v_fma_f32 v73, v76, v151, v140
	v_fma_f32 v74, v77, v149, v140
	v_sub_f32 v91, v115, v97
	v_sub_f32 v89, v89, v96
	v_sub_f32 v90, v90, v97
	v_sub_f32 v88, v88, v96
	v_sub_f32 v82, v82, v97
	v_fma_f32 v150, v93, v71, v97
	v_fma_f32 v95, v95, v75, v97
	v_fma_f32 v92, v84, v83, v96
	v_fma_f32 v93, v84, v91, v97
	v_fma_f32 v84, v85, v89, v96
	v_fma_f32 v85, v85, v90, v97
	v_fma_f32 v70, v86, v88, v96
	v_fma_f32 v71, v86, v82, v97
	v_fma_f32 v75, v77, v150, v140
	v_fma_f32 v76, v78, v120, v140
	v_fma_f32 v77, v78, v121, v140
	v_fma_f32 v72, v64, v92, v72
	v_fma_f32 v73, v64, v93, v73
	v_fma_f32 v64, v65, v84, v74
	v_fma_f32 v74, v65, v85, v75
	v_fma_f32 v65, v66, v70, v76
	v_fma_f32 v66, v66, v71, v77
	v_sub_f32 v80, v80, v96
	v_sub_f32 v81, v81, v97
	v_fma_f32 v78, v79, v94, v140
	v_fma_f32 v79, v79, v95, v140
	v_add_f32_e32 v64, v72, v64
	v_fma_f32 v68, v87, v80, v96
	v_fma_f32 v69, v87, v81, v97
	v_add_f32_e32 v72, v73, v74
	v_fma_f32 v75, v67, v68, v78
	v_fma_f32 v67, v67, v69, v79
	v_add_f32_e32 v65, v65, v75
	v_add_f32_e32 v66, v66, v67
	v_add_f32_e32 v64, v64, v65
	v_add_f32_e32 v66, v72, v66
	s_nop 0
	v_add_f32_dpp v64, v64, v64 row_ror:8 row_mask:0xf bank_mask:0xf bound_ctrl:1
	v_add_f32_dpp v66, v66, v66 row_ror:8 row_mask:0xf bank_mask:0xf bound_ctrl:1
	s_nop 0
	v_add_f32_dpp v64, v64, v64 row_ror:4 row_mask:0xf bank_mask:0xf bound_ctrl:1
	v_add_f32_dpp v66, v66, v66 row_ror:4 row_mask:0xf bank_mask:0xf bound_ctrl:1
	s_nop 0
	v_add_f32_dpp v64, v64, v64 row_ror:2 row_mask:0xf bank_mask:0xf bound_ctrl:1
	v_add_f32_dpp v66, v66, v66 row_ror:2 row_mask:0xf bank_mask:0xf bound_ctrl:1
	s_nop 0
	v_add_f32_dpp v64, v64, v64 row_ror:1 row_mask:0xf bank_mask:0xf bound_ctrl:1
	v_add_f32_dpp v66, v66, v66 row_ror:1 row_mask:0xf bank_mask:0xf bound_ctrl:1
	ds_write2_b32 v147, v64, v66 offset0:224 offset1:240
	s_waitcnt vmcnt(9)
	v_mul_f32_e32 v64, 0xbfb8aa3b, v16
	v_mul_f32_e32 v65, 0xbfb8aa3b, v17
	v_exp_f32_e32 v64, v64
	v_exp_f32_e32 v65, v65
	v_mul_f32_e32 v66, 0xbfb8aa3b, v18
	v_mul_f32_e32 v67, 0xbfb8aa3b, v19
	v_exp_f32_e32 v66, v66
	v_pk_add_f32 v[64:65], v[64:65], 1.0 op_sel_hi:[1,0]
	v_exp_f32_e32 v67, v67
	v_div_scale_f32 v76, s[8:9], v65, v65, v17
	v_rcp_f32_e32 v77, v76
	v_pk_add_f32 v[66:67], v[66:67], 1.0 op_sel_hi:[1,0]
	s_waitcnt vmcnt(8)
	v_mul_f32_e32 v72, 0xbfb8aa3b, v20
	v_mul_f32_e32 v73, 0xbfb8aa3b, v21
	v_fma_f32 v78, -v76, v77, 1.0
	v_fmac_f32_e32 v77, v78, v77
	v_div_scale_f32 v78, vcc, v17, v65, v17
	v_mul_f32_e32 v79, v78, v77
	v_fma_f32 v80, -v76, v79, v78
	v_fmac_f32_e32 v79, v80, v77
	v_fma_f32 v76, -v76, v79, v78
	v_div_fmas_f32 v76, v76, v77, v79
	v_div_fixup_f32 v65, v76, v65, v17
	v_div_scale_f32 v76, s[8:9], v64, v64, v16
	v_rcp_f32_e32 v77, v76
	v_exp_f32_e32 v72, v72
	v_exp_f32_e32 v73, v73
	v_mul_f32_e32 v74, 0xbfb8aa3b, v22
	v_fma_f32 v78, -v76, v77, 1.0
	v_fmac_f32_e32 v77, v78, v77
	v_div_scale_f32 v78, vcc, v16, v64, v16
	v_mul_f32_e32 v79, v78, v77
	v_fma_f32 v80, -v76, v79, v78
	v_fmac_f32_e32 v79, v80, v77
	v_fma_f32 v76, -v76, v79, v78
	v_div_fmas_f32 v76, v76, v77, v79
	v_div_fixup_f32 v64, v76, v64, v16
	v_div_scale_f32 v76, s[8:9], v67, v67, v19
	v_rcp_f32_e32 v77, v76
	v_pk_mul_f32 v[64:65], v[64:65], s[18:19] op_sel_hi:[1,0]
	v_mul_f32_e32 v75, 0xbfb8aa3b, v23
	v_exp_f32_e32 v74, v74
	v_fma_f32 v78, -v76, v77, 1.0
	v_fmac_f32_e32 v77, v78, v77
	v_div_scale_f32 v78, vcc, v19, v67, v19
	v_mul_f32_e32 v79, v78, v77
	v_fma_f32 v80, -v76, v79, v78
	v_fmac_f32_e32 v79, v80, v77
	v_fma_f32 v76, -v76, v79, v78
	v_div_fmas_f32 v76, v76, v77, v79
	v_div_fixup_f32 v67, v76, v67, v19
	v_div_scale_f32 v76, s[8:9], v66, v66, v18
	v_rcp_f32_e32 v77, v76
	v_exp_f32_e32 v75, v75
	s_cmpk_lt_u32 s48, 0x7b
	v_fma_f32 v78, -v76, v77, 1.0
	v_fmac_f32_e32 v77, v78, v77
	v_div_scale_f32 v78, vcc, v18, v66, v18
	v_mul_f32_e32 v79, v78, v77
	v_fma_f32 v80, -v76, v79, v78
	v_fmac_f32_e32 v79, v80, v77
	v_fma_f32 v76, -v76, v79, v78
	v_div_fmas_f32 v76, v76, v77, v79
	v_div_fixup_f32 v66, v76, v66, v18
	v_pk_mul_f32 v[66:67], v[66:67], s[18:19] op_sel_hi:[1,0]
	ds_write_b128 v141, v[64:67] offset:18432
	v_pk_add_f32 v[64:65], v[72:73], 1.0 op_sel_hi:[1,0]
	v_div_scale_f32 v66, s[8:9], v65, v65, 1.0
	v_rcp_f32_e32 v67, v66
	s_nop 0
	v_fma_f32 v72, -v66, v67, 1.0
	v_fmac_f32_e32 v67, v72, v67
	v_div_scale_f32 v72, vcc, 1.0, v65, 1.0
	v_mul_f32_e32 v73, v72, v67
	v_fma_f32 v76, -v66, v73, v72
	v_fmac_f32_e32 v73, v76, v67
	v_fma_f32 v66, -v66, v73, v72
	v_div_fmas_f32 v66, v66, v67, v73
	v_div_fixup_f32 v65, v66, v65, 1.0
	v_div_scale_f32 v66, s[8:9], v64, v64, 1.0
	v_rcp_f32_e32 v67, v66
	s_nop 0
	v_fma_f32 v72, -v66, v67, 1.0
	v_fmac_f32_e32 v67, v72, v67
	v_div_scale_f32 v72, vcc, 1.0, v64, 1.0
	v_mul_f32_e32 v73, v72, v67
	v_fma_f32 v76, -v66, v73, v72
	v_fmac_f32_e32 v73, v76, v67
	v_fma_f32 v66, -v66, v73, v72
	v_div_fmas_f32 v66, v66, v67, v73
	v_div_fixup_f32 v64, v66, v64, 1.0
	v_pk_add_f32 v[66:67], v[74:75], 1.0 op_sel_hi:[1,0]
	v_pk_fma_f32 v[64:65], v[110:111], v[64:65], v[104:105]
	v_div_scale_f32 v72, s[8:9], v67, v67, 1.0
	v_rcp_f32_e32 v73, v72
	s_nop 0
	v_fma_f32 v74, -v72, v73, 1.0
	v_fmac_f32_e32 v73, v74, v73
	v_div_scale_f32 v74, vcc, 1.0, v67, 1.0
	v_mul_f32_e32 v75, v74, v73
	v_fma_f32 v76, -v72, v75, v74
	v_fmac_f32_e32 v75, v76, v73
	v_fma_f32 v72, -v72, v75, v74
	v_div_fmas_f32 v72, v72, v73, v75
	v_div_fixup_f32 v67, v72, v67, 1.0
	v_div_scale_f32 v72, s[8:9], v66, v66, 1.0
	v_rcp_f32_e32 v73, v72
	s_nop 0
	v_fma_f32 v74, -v72, v73, 1.0
	v_fmac_f32_e32 v73, v74, v73
	v_div_scale_f32 v74, vcc, 1.0, v66, 1.0
	v_mul_f32_e32 v75, v74, v73
	v_fma_f32 v76, -v72, v75, v74
	v_fmac_f32_e32 v75, v76, v73
	v_fma_f32 v72, -v72, v75, v74
	v_div_fmas_f32 v72, v72, v73, v75
	v_div_fixup_f32 v66, v72, v66, 1.0
	v_pk_fma_f32 v[66:67], v[112:113], v[66:67], v[106:107]
	ds_write_b128 v141, v[64:67] offset:26624
	ds_write_b32 v134, v129 offset:34816
	v_mul_f32_e32 v64, 0xbfb8aa3b, v24
	v_mul_f32_e32 v65, 0xbfb8aa3b, v25
	v_exp_f32_e32 v64, v64
	v_exp_f32_e32 v65, v65
	v_mul_f32_e32 v66, 0xbfb8aa3b, v26
	v_mul_f32_e32 v67, 0xbfb8aa3b, v27
	v_exp_f32_e32 v66, v66
	v_pk_add_f32 v[64:65], v[64:65], 1.0 op_sel_hi:[1,0]
	v_exp_f32_e32 v67, v67
	v_div_scale_f32 v76, s[8:9], v65, v65, v25
	v_rcp_f32_e32 v77, v76
	v_pk_add_f32 v[66:67], v[66:67], 1.0 op_sel_hi:[1,0]
	v_mul_f32_e32 v72, 0xbfb8aa3b, v36
	v_mul_f32_e32 v73, 0xbfb8aa3b, v37
	v_fma_f32 v78, -v76, v77, 1.0
	v_fmac_f32_e32 v77, v78, v77
	v_div_scale_f32 v78, vcc, v25, v65, v25
	v_mul_f32_e32 v79, v78, v77
	v_fma_f32 v80, -v76, v79, v78
	v_fmac_f32_e32 v79, v80, v77
	v_fma_f32 v76, -v76, v79, v78
	v_div_fmas_f32 v76, v76, v77, v79
	v_div_fixup_f32 v65, v76, v65, v25
	v_div_scale_f32 v76, s[8:9], v64, v64, v24
	v_rcp_f32_e32 v77, v76
	v_exp_f32_e32 v72, v72
	v_exp_f32_e32 v73, v73
	v_mul_f32_e32 v74, 0xbfb8aa3b, v38
	v_fma_f32 v78, -v76, v77, 1.0
	v_fmac_f32_e32 v77, v78, v77
	v_div_scale_f32 v78, vcc, v24, v64, v24
	v_mul_f32_e32 v79, v78, v77
	v_fma_f32 v80, -v76, v79, v78
	v_fmac_f32_e32 v79, v80, v77
	v_fma_f32 v76, -v76, v79, v78
	v_div_fmas_f32 v76, v76, v77, v79
	v_div_fixup_f32 v64, v76, v64, v24
	v_div_scale_f32 v76, s[8:9], v67, v67, v27
	v_rcp_f32_e32 v77, v76
	v_pk_mul_f32 v[64:65], v[64:65], s[18:19] op_sel_hi:[1,0]
	v_mul_f32_e32 v75, 0xbfb8aa3b, v39
	v_exp_f32_e32 v74, v74
	v_fma_f32 v78, -v76, v77, 1.0
	v_fmac_f32_e32 v77, v78, v77
	v_div_scale_f32 v78, vcc, v27, v67, v27
	v_mul_f32_e32 v79, v78, v77
	v_fma_f32 v80, -v76, v79, v78
	v_fmac_f32_e32 v79, v80, v77
	v_fma_f32 v76, -v76, v79, v78
	v_div_fmas_f32 v76, v76, v77, v79
	v_div_fixup_f32 v67, v76, v67, v27
	v_div_scale_f32 v76, s[8:9], v66, v66, v26
	v_rcp_f32_e32 v77, v76
	v_exp_f32_e32 v75, v75
	v_fma_f32 v78, -v76, v77, 1.0
	v_fmac_f32_e32 v77, v78, v77
	v_div_scale_f32 v78, vcc, v26, v66, v26
	v_mul_f32_e32 v79, v78, v77
	v_fma_f32 v80, -v76, v79, v78
	v_fmac_f32_e32 v79, v80, v77
	v_fma_f32 v76, -v76, v79, v78
	v_div_fmas_f32 v76, v76, v77, v79
	v_div_fixup_f32 v66, v76, v66, v26
	v_pk_mul_f32 v[66:67], v[66:67], s[18:19] op_sel_hi:[1,0]
	ds_write_b128 v144, v[64:67] offset:18432
	v_pk_add_f32 v[64:65], v[72:73], 1.0 op_sel_hi:[1,0]
	v_div_scale_f32 v66, s[8:9], v65, v65, 1.0
	v_rcp_f32_e32 v67, v66
	s_nop 0
	v_fma_f32 v72, -v66, v67, 1.0
	v_fmac_f32_e32 v67, v72, v67
	v_div_scale_f32 v72, vcc, 1.0, v65, 1.0
	v_mul_f32_e32 v73, v72, v67
	v_fma_f32 v76, -v66, v73, v72
	v_fmac_f32_e32 v73, v76, v67
	v_fma_f32 v66, -v66, v73, v72
	v_div_fmas_f32 v66, v66, v67, v73
	v_div_fixup_f32 v65, v66, v65, 1.0
	v_div_scale_f32 v66, s[8:9], v64, v64, 1.0
	v_rcp_f32_e32 v67, v66
	s_nop 0
	v_fma_f32 v72, -v66, v67, 1.0
	v_fmac_f32_e32 v67, v72, v67
	v_div_scale_f32 v72, vcc, 1.0, v64, 1.0
	v_mul_f32_e32 v73, v72, v67
	v_fma_f32 v76, -v66, v73, v72
	v_fmac_f32_e32 v73, v76, v67
	v_fma_f32 v66, -v66, v73, v72
	v_div_fmas_f32 v66, v66, v67, v73
	v_div_fixup_f32 v64, v66, v64, 1.0
	v_pk_add_f32 v[66:67], v[74:75], 1.0 op_sel_hi:[1,0]
	v_pk_fma_f32 v[64:65], v[110:111], v[64:65], v[104:105]
	v_div_scale_f32 v72, s[8:9], v67, v67, 1.0
	v_rcp_f32_e32 v73, v72
	s_nop 0
	v_fma_f32 v74, -v72, v73, 1.0
	v_fmac_f32_e32 v73, v74, v73
	v_div_scale_f32 v74, vcc, 1.0, v67, 1.0
	v_mul_f32_e32 v75, v74, v73
	v_fma_f32 v76, -v72, v75, v74
	v_fmac_f32_e32 v75, v76, v73
	v_fma_f32 v72, -v72, v75, v74
	v_div_fmas_f32 v72, v72, v73, v75
	v_div_fixup_f32 v67, v72, v67, 1.0
	v_div_scale_f32 v72, s[8:9], v66, v66, 1.0
	v_rcp_f32_e32 v73, v72
	s_mov_b64 s[8:9], -1
	v_fma_f32 v74, -v72, v73, 1.0
	v_fmac_f32_e32 v73, v74, v73
	v_div_scale_f32 v74, vcc, 1.0, v66, 1.0
	v_mul_f32_e32 v75, v74, v73
	v_fma_f32 v76, -v72, v75, v74
	v_fmac_f32_e32 v75, v76, v73
	v_fma_f32 v72, -v72, v75, v74
	v_div_fmas_f32 v72, v72, v73, v75
	v_div_fixup_f32 v66, v72, v66, 1.0
	v_pk_fma_f32 v[66:67], v[112:113], v[66:67], v[106:107]
	ds_write_b128 v144, v[64:67] offset:26624
	ds_write_b32 v134, v130 offset:35840
	s_waitcnt lgkmcnt(0)
	s_barrier
	v_add_u32_e32 v64, s47, v124
	v_add_u32_e32 v65, s47, v126
	s_cbranch_scc1 .LBB0_1323
	v_add_u32_e32 v98, s47, v124
	v_add_u32_e32 v96, s47, v126
	s_mov_b64 s[8:9], 0

.LBB0_1325:
	ds_read2st64_b32 v[64:65], v134 offset0:144 offset1:148
	v_ashrrev_i32_e32 v99, 31, v98
	v_lshlrev_b64 v[66:67], 12, v[98:99]
	v_ashrrev_i32_e32 v97, 31, v96
	v_lshl_add_u64 v[66:67], v[108:109], 0, v[66:67]
	s_waitcnt lgkmcnt(0)
	global_store_dword v[66:67], v64, off
	v_lshlrev_b64 v[66:67], 12, v[96:97]
	v_lshl_add_u64 v[66:67], v[108:109], 0, v[66:67]
	global_store_dword v[66:67], v65, off
	ds_read_b128 v[76:79], v145 offset:18432
	ds_read_b128 v[184:187], v145 offset:18688
	ds_read_b128 v[188:191], v145 offset:26624
	ds_read_b128 v[192:195], v145 offset:26880
	v_add_u32_e32 v153, 0x8800, v103
	ds_read2_b32 v[86:87], v153 offset1:16
	ds_read_b128 v[72:75], v145 offset:18944
	ds_read_b128 v[64:67], v145 offset:19200
	ds_read_b128 v[88:91], v145 offset:27136
	ds_read_b128 v[80:83], v145 offset:27392
	ds_read2_b32 v[118:119], v153 offset0:32 offset1:48
	s_waitcnt lgkmcnt(5)
	v_sub_f32 v97, v154, v86
	v_sub_f32 v99, v151, v87
	v_sub_f32 v115, v149, v86
	v_sub_f32 v117, v150, v87
	v_sub_f32 v70, v70, v86
	v_sub_f32 v71, v71, v87
	v_sub_f32 v68, v68, v86
	v_sub_f32 v69, v69, v87
	v_sub_f32 v84, v84, v86
	v_fma_f32 v183, v188, v97, v86
	v_fma_f32 v182, v188, v99, v87
	v_fma_f32 v180, v189, v115, v86
	v_fma_f32 v181, v189, v117, v87
	v_fma_f32 v115, v194, v70, v86
	v_fma_f32 v117, v194, v71, v87
	v_fma_f32 v97, v195, v68, v86
	v_fma_f32 v99, v195, v69, v87
	v_fma_f32 v68, v76, v183, v140
	v_fma_f32 v69, v76, v182, v140
	v_fma_f32 v70, v77, v180, v140
	v_fma_f32 v71, v77, v181, v140
	v_sub_f32 v120, v120, v86
	v_sub_f32 v121, v121, v87
	v_sub_f32 v94, v94, v86
	v_sub_f32 v92, v92, v86
	v_sub_f32 v93, v93, v87
	v_sub_f32 v85, v85, v87
	v_fma_f32 v178, v190, v120, v86
	v_fma_f32 v179, v190, v121, v87
	v_fma_f32 v156, v191, v94, v86
	v_fma_f32 v154, v192, v92, v86
	v_fma_f32 v155, v192, v93, v87
	v_fma_f32 v150, v193, v84, v86
	v_fma_f32 v151, v193, v85, v87
	v_fma_f32 v76, v78, v178, v140
	v_fma_f32 v77, v78, v179, v140
	v_fma_f32 v78, v79, v156, v140
	v_fma_f32 v68, v184, v154, v68
	v_fma_f32 v84, v184, v155, v69
	v_fma_f32 v69, v185, v150, v70
	v_fma_f32 v70, v185, v151, v71
	v_fma_f32 v71, v186, v115, v76
	v_sub_f32 v95, v95, v87
	v_fma_f32 v76, v186, v117, v77
	v_fma_f32 v77, v187, v97, v78
	v_add_f32_e32 v68, v68, v69
	v_fma_f32 v157, v191, v95, v87
	v_add_f32_e32 v69, v71, v77
	v_fma_f32 v79, v79, v157, v140
	v_add_f32_e32 v70, v84, v70
	v_fma_f32 v78, v187, v99, v79
	v_add_f32_e32 v68, v68, v69
	v_add_f32_e32 v71, v76, v78
	v_add_f32_e32 v70, v70, v71
	v_add_f32_dpp v68, v68, v68 row_ror:8 row_mask:0xf bank_mask:0xf bound_ctrl:1
	s_nop 0
	v_add_f32_dpp v70, v70, v70 row_ror:8 row_mask:0xf bank_mask:0xf bound_ctrl:1
	v_add_f32_dpp v68, v68, v68 row_ror:4 row_mask:0xf bank_mask:0xf bound_ctrl:1
	s_nop 0
	v_add_f32_dpp v70, v70, v70 row_ror:4 row_mask:0xf bank_mask:0xf bound_ctrl:1
	v_add_u32_e32 v149, 0x9800, v103
	v_add_f32_dpp v68, v68, v68 row_ror:2 row_mask:0xf bank_mask:0xf bound_ctrl:1
	v_add_f32_dpp v70, v70, v70 row_ror:2 row_mask:0xf bank_mask:0xf bound_ctrl:1
	s_nop 0
	v_add_f32_dpp v68, v68, v68 row_ror:1 row_mask:0xf bank_mask:0xf bound_ctrl:1
	v_add_f32_dpp v70, v70, v70 row_ror:1 row_mask:0xf bank_mask:0xf bound_ctrl:1
	ds_write2_b32 v149, v68, v70 offset1:16
	s_waitcnt lgkmcnt(0)
	v_sub_f32 v183, v183, v118
	v_sub_f32 v182, v182, v119
	v_sub_f32 v180, v180, v118
	v_sub_f32 v181, v181, v119
	v_sub_f32 v154, v154, v118
	v_sub_f32 v155, v155, v119
	v_sub_f32 v150, v150, v118
	v_sub_f32 v151, v151, v119
	v_sub_f32 v178, v178, v118
	v_sub_f32 v179, v179, v119
	v_sub_f32 v115, v115, v118
	v_sub_f32 v117, v117, v119
	v_fma_f32 v183, v88, v183, v118
	v_fma_f32 v182, v88, v182, v119
	v_fma_f32 v180, v89, v180, v118
	v_fma_f32 v181, v89, v181, v119
	v_fma_f32 v154, v80, v154, v118
	v_fma_f32 v155, v80, v155, v119
	v_fma_f32 v150, v81, v150, v118
	v_fma_f32 v151, v81, v151, v119
	v_fma_f32 v80, v72, v183, v140
	v_fma_f32 v72, v72, v182, v140
	v_fma_f32 v81, v73, v180, v140
	v_fma_f32 v73, v73, v181, v140
	ds_read_b128 v[76:79], v145 offset:19456
	ds_read_b128 v[68:71], v145 offset:19712
	ds_read_b128 v[92:95], v145 offset:27648
	ds_read_b128 v[84:87], v145 offset:27904
	ds_read2_b32 v[120:121], v153 offset0:64 offset1:80
	v_sub_f32 v156, v156, v118
	v_sub_f32 v157, v157, v119
	v_sub_f32 v97, v97, v118
	v_sub_f32 v99, v99, v119
	v_fma_f32 v178, v90, v178, v118
	v_fma_f32 v179, v90, v179, v119
	v_fma_f32 v115, v82, v115, v118
	v_fma_f32 v117, v82, v117, v119
	v_fma_f32 v80, v64, v154, v80
	v_fma_f32 v72, v64, v155, v72
	v_fma_f32 v82, v74, v178, v140
	v_fma_f32 v74, v74, v179, v140
	v_fma_f32 v64, v65, v150, v81
	v_fma_f32 v73, v65, v151, v73
	v_fma_f32 v156, v91, v156, v118
	v_fma_f32 v157, v91, v157, v119
	v_fma_f32 v65, v66, v115, v82
	v_fma_f32 v66, v66, v117, v74
	v_fma_f32 v97, v83, v97, v118
	v_fma_f32 v99, v83, v99, v119
	v_fma_f32 v83, v75, v156, v140
	v_fma_f32 v75, v75, v157, v140
	v_add_f32_e32 v64, v80, v64
	v_fma_f32 v74, v67, v97, v83
	v_fma_f32 v67, v67, v99, v75
	v_add_f32_e32 v72, v72, v73
	v_add_f32_e32 v65, v65, v74
	v_add_f32_e32 v66, v66, v67
	v_add_f32_e32 v64, v64, v65
	v_add_f32_e32 v66, v72, v66
	s_nop 0
	v_add_f32_dpp v64, v64, v64 row_ror:8 row_mask:0xf bank_mask:0xf bound_ctrl:1
	v_add_f32_dpp v66, v66, v66 row_ror:8 row_mask:0xf bank_mask:0xf bound_ctrl:1
	s_nop 0
	v_add_f32_dpp v64, v64, v64 row_ror:4 row_mask:0xf bank_mask:0xf bound_ctrl:1
	v_add_f32_dpp v66, v66, v66 row_ror:4 row_mask:0xf bank_mask:0xf bound_ctrl:1
	s_nop 0
	v_add_f32_dpp v64, v64, v64 row_ror:2 row_mask:0xf bank_mask:0xf bound_ctrl:1
	v_add_f32_dpp v66, v66, v66 row_ror:2 row_mask:0xf bank_mask:0xf bound_ctrl:1
	s_nop 0
	v_add_f32_dpp v64, v64, v64 row_ror:1 row_mask:0xf bank_mask:0xf bound_ctrl:1
	v_add_f32_dpp v66, v66, v66 row_ror:1 row_mask:0xf bank_mask:0xf bound_ctrl:1
	ds_write2_b32 v149, v64, v66 offset0:32 offset1:48
	s_waitcnt lgkmcnt(0)
	v_sub_f32 v183, v183, v120
	v_sub_f32 v182, v182, v121
	v_sub_f32 v180, v180, v120
	v_sub_f32 v181, v181, v121
	v_sub_f32 v154, v154, v120
	v_sub_f32 v155, v155, v121
	v_sub_f32 v150, v150, v120
	v_sub_f32 v151, v151, v121
	v_sub_f32 v178, v178, v120
	v_sub_f32 v179, v179, v121
	v_sub_f32 v115, v115, v120
	v_sub_f32 v117, v117, v121
	v_fma_f32 v183, v92, v183, v120
	v_fma_f32 v182, v92, v182, v121
	v_fma_f32 v180, v93, v180, v120
	v_fma_f32 v181, v93, v181, v121
	v_fma_f32 v154, v84, v154, v120
	v_fma_f32 v155, v84, v155, v121
	v_fma_f32 v150, v85, v150, v120
	v_fma_f32 v151, v85, v151, v121
	v_fma_f32 v84, v76, v183, v140
	v_fma_f32 v76, v76, v182, v140
	v_fma_f32 v85, v77, v180, v140
	v_fma_f32 v77, v77, v181, v140
	ds_read_b128 v[72:75], v145 offset:19968
	ds_read_b128 v[64:67], v145 offset:20224
	ds_read_b128 v[88:91], v145 offset:28160
	ds_read_b128 v[80:83], v145 offset:28416
	ds_read2_b32 v[118:119], v153 offset0:96 offset1:112
	v_sub_f32 v156, v156, v120
	v_sub_f32 v157, v157, v121
	v_sub_f32 v97, v97, v120
	v_sub_f32 v99, v99, v121
	v_fma_f32 v178, v94, v178, v120
	v_fma_f32 v179, v94, v179, v121
	v_fma_f32 v115, v86, v115, v120
	v_fma_f32 v117, v86, v117, v121
	v_fma_f32 v84, v68, v154, v84
	v_fma_f32 v76, v68, v155, v76
	v_fma_f32 v86, v78, v178, v140
	v_fma_f32 v78, v78, v179, v140
	v_fma_f32 v68, v69, v150, v85
	v_fma_f32 v77, v69, v151, v77
	v_fma_f32 v156, v95, v156, v120
	v_fma_f32 v157, v95, v157, v121
	v_fma_f32 v69, v70, v115, v86
	v_fma_f32 v70, v70, v117, v78
	v_fma_f32 v97, v87, v97, v120
	v_fma_f32 v99, v87, v99, v121
	v_fma_f32 v87, v79, v156, v140
	v_fma_f32 v79, v79, v157, v140
	v_add_f32_e32 v68, v84, v68
	v_fma_f32 v78, v71, v97, v87
	v_fma_f32 v71, v71, v99, v79
	v_add_f32_e32 v76, v76, v77
	v_add_f32_e32 v69, v69, v78
	v_add_f32_e32 v70, v70, v71
	v_add_f32_e32 v68, v68, v69
	v_add_f32_e32 v70, v76, v70
	s_nop 0
	v_add_f32_dpp v68, v68, v68 row_ror:8 row_mask:0xf bank_mask:0xf bound_ctrl:1
	v_add_f32_dpp v70, v70, v70 row_ror:8 row_mask:0xf bank_mask:0xf bound_ctrl:1
	s_nop 0
	v_add_f32_dpp v68, v68, v68 row_ror:4 row_mask:0xf bank_mask:0xf bound_ctrl:1
	v_add_f32_dpp v70, v70, v70 row_ror:4 row_mask:0xf bank_mask:0xf bound_ctrl:1
	s_nop 0
	v_add_f32_dpp v68, v68, v68 row_ror:2 row_mask:0xf bank_mask:0xf bound_ctrl:1
	v_add_f32_dpp v70, v70, v70 row_ror:2 row_mask:0xf bank_mask:0xf bound_ctrl:1
	s_nop 0
	v_add_f32_dpp v68, v68, v68 row_ror:1 row_mask:0xf bank_mask:0xf bound_ctrl:1
	v_add_f32_dpp v70, v70, v70 row_ror:1 row_mask:0xf bank_mask:0xf bound_ctrl:1
	ds_write2_b32 v149, v68, v70 offset0:64 offset1:80
	s_waitcnt lgkmcnt(0)
	v_sub_f32 v183, v183, v118
	v_sub_f32 v182, v182, v119
	v_sub_f32 v180, v180, v118
	v_sub_f32 v181, v181, v119
	v_sub_f32 v154, v154, v118
	v_sub_f32 v155, v155, v119
	v_sub_f32 v150, v150, v118
	v_sub_f32 v151, v151, v119
	v_sub_f32 v178, v178, v118
	v_sub_f32 v179, v179, v119
	v_sub_f32 v115, v115, v118
	v_sub_f32 v117, v117, v119
	v_fma_f32 v183, v88, v183, v118
	v_fma_f32 v182, v88, v182, v119
	v_fma_f32 v180, v89, v180, v118
	v_fma_f32 v181, v89, v181, v119
	v_fma_f32 v154, v80, v154, v118
	v_fma_f32 v155, v80, v155, v119
	v_fma_f32 v150, v81, v150, v118
	v_fma_f32 v151, v81, v151, v119
	v_fma_f32 v80, v72, v183, v140
	v_fma_f32 v72, v72, v182, v140
	v_fma_f32 v81, v73, v180, v140
	v_fma_f32 v73, v73, v181, v140
	ds_read_b128 v[76:79], v145 offset:20480
	ds_read_b128 v[68:71], v145 offset:20736
	ds_read_b128 v[92:95], v145 offset:28672
	ds_read_b128 v[84:87], v145 offset:28928
	ds_read2_b32 v[120:121], v153 offset0:128 offset1:144
	v_sub_f32 v156, v156, v118
	v_sub_f32 v157, v157, v119
	v_sub_f32 v97, v97, v118
	v_sub_f32 v99, v99, v119
	v_fma_f32 v178, v90, v178, v118
	v_fma_f32 v179, v90, v179, v119
	v_fma_f32 v115, v82, v115, v118
	v_fma_f32 v117, v82, v117, v119
	v_fma_f32 v80, v64, v154, v80
	v_fma_f32 v72, v64, v155, v72
	v_fma_f32 v82, v74, v178, v140
	v_fma_f32 v74, v74, v179, v140
	v_fma_f32 v64, v65, v150, v81
	v_fma_f32 v73, v65, v151, v73
	v_fma_f32 v156, v91, v156, v118
	v_fma_f32 v157, v91, v157, v119
	v_fma_f32 v65, v66, v115, v82
	v_fma_f32 v66, v66, v117, v74
	v_fma_f32 v97, v83, v97, v118
	v_fma_f32 v99, v83, v99, v119
	v_fma_f32 v83, v75, v156, v140
	v_fma_f32 v75, v75, v157, v140
	v_add_f32_e32 v64, v80, v64
	v_fma_f32 v74, v67, v97, v83
	v_fma_f32 v67, v67, v99, v75
	v_add_f32_e32 v72, v72, v73
	v_add_f32_e32 v65, v65, v74
	v_add_f32_e32 v66, v66, v67
	v_add_f32_e32 v64, v64, v65
	v_add_f32_e32 v66, v72, v66
	s_nop 0
	v_add_f32_dpp v64, v64, v64 row_ror:8 row_mask:0xf bank_mask:0xf bound_ctrl:1
	v_add_f32_dpp v66, v66, v66 row_ror:8 row_mask:0xf bank_mask:0xf bound_ctrl:1
	s_nop 0
	v_add_f32_dpp v64, v64, v64 row_ror:4 row_mask:0xf bank_mask:0xf bound_ctrl:1
	v_add_f32_dpp v66, v66, v66 row_ror:4 row_mask:0xf bank_mask:0xf bound_ctrl:1
	s_nop 0
	v_add_f32_dpp v64, v64, v64 row_ror:2 row_mask:0xf bank_mask:0xf bound_ctrl:1
	v_add_f32_dpp v66, v66, v66 row_ror:2 row_mask:0xf bank_mask:0xf bound_ctrl:1
	s_nop 0
	v_add_f32_dpp v64, v64, v64 row_ror:1 row_mask:0xf bank_mask:0xf bound_ctrl:1
	v_add_f32_dpp v66, v66, v66 row_ror:1 row_mask:0xf bank_mask:0xf bound_ctrl:1
	ds_write2_b32 v149, v64, v66 offset0:96 offset1:112
	s_waitcnt lgkmcnt(0)
	v_sub_f32 v183, v183, v120
	v_sub_f32 v182, v182, v121
	v_sub_f32 v180, v180, v120
	v_sub_f32 v181, v181, v121
	v_sub_f32 v154, v154, v120
	v_sub_f32 v155, v155, v121
	v_sub_f32 v150, v150, v120
	v_sub_f32 v151, v151, v121
	v_sub_f32 v178, v178, v120
	v_sub_f32 v179, v179, v121
	v_sub_f32 v115, v115, v120
	v_sub_f32 v117, v117, v121
	v_fma_f32 v183, v92, v183, v120
	v_fma_f32 v182, v92, v182, v121
	v_fma_f32 v180, v93, v180, v120
	v_fma_f32 v181, v93, v181, v121
	v_fma_f32 v154, v84, v154, v120
	v_fma_f32 v155, v84, v155, v121
	v_fma_f32 v150, v85, v150, v120
	v_fma_f32 v151, v85, v151, v121
	v_fma_f32 v84, v76, v183, v140
	v_fma_f32 v76, v76, v182, v140
	v_fma_f32 v85, v77, v180, v140
	v_fma_f32 v77, v77, v181, v140
	ds_read_b128 v[72:75], v145 offset:20992
	ds_read_b128 v[64:67], v145 offset:21248
	ds_read_b128 v[88:91], v145 offset:29184
	ds_read_b128 v[80:83], v145 offset:29440
	ds_read2_b32 v[118:119], v153 offset0:160 offset1:176
	v_sub_f32 v156, v156, v120
	v_sub_f32 v157, v157, v121
	v_sub_f32 v97, v97, v120
	v_sub_f32 v99, v99, v121
	v_fma_f32 v178, v94, v178, v120
	v_fma_f32 v179, v94, v179, v121
	v_fma_f32 v115, v86, v115, v120
	v_fma_f32 v117, v86, v117, v121
	v_fma_f32 v84, v68, v154, v84
	v_fma_f32 v76, v68, v155, v76
	v_fma_f32 v86, v78, v178, v140
	v_fma_f32 v78, v78, v179, v140
	v_fma_f32 v68, v69, v150, v85
	v_fma_f32 v77, v69, v151, v77
	v_fma_f32 v156, v95, v156, v120
	v_fma_f32 v157, v95, v157, v121
	v_fma_f32 v69, v70, v115, v86
	v_fma_f32 v70, v70, v117, v78
	v_fma_f32 v97, v87, v97, v120
	v_fma_f32 v99, v87, v99, v121
	v_fma_f32 v87, v79, v156, v140
	v_fma_f32 v79, v79, v157, v140
	v_add_f32_e32 v68, v84, v68
	v_fma_f32 v78, v71, v97, v87
	v_fma_f32 v71, v71, v99, v79
	v_add_f32_e32 v76, v76, v77
	v_add_f32_e32 v69, v69, v78
	v_add_f32_e32 v70, v70, v71
	v_add_f32_e32 v68, v68, v69
	v_add_f32_e32 v70, v76, v70
	s_nop 0
	v_add_f32_dpp v68, v68, v68 row_ror:8 row_mask:0xf bank_mask:0xf bound_ctrl:1
	v_add_f32_dpp v70, v70, v70 row_ror:8 row_mask:0xf bank_mask:0xf bound_ctrl:1
	s_nop 0
	v_add_f32_dpp v68, v68, v68 row_ror:4 row_mask:0xf bank_mask:0xf bound_ctrl:1
	v_add_f32_dpp v70, v70, v70 row_ror:4 row_mask:0xf bank_mask:0xf bound_ctrl:1
	s_nop 0
	v_add_f32_dpp v68, v68, v68 row_ror:2 row_mask:0xf bank_mask:0xf bound_ctrl:1
	v_add_f32_dpp v70, v70, v70 row_ror:2 row_mask:0xf bank_mask:0xf bound_ctrl:1
	s_nop 0
	v_add_f32_dpp v68, v68, v68 row_ror:1 row_mask:0xf bank_mask:0xf bound_ctrl:1
	v_add_f32_dpp v70, v70, v70 row_ror:1 row_mask:0xf bank_mask:0xf bound_ctrl:1
	ds_write2_b32 v149, v68, v70 offset0:128 offset1:144
	s_waitcnt lgkmcnt(0)
	v_sub_f32 v183, v183, v118
	v_sub_f32 v182, v182, v119
	v_sub_f32 v180, v180, v118
	v_sub_f32 v181, v181, v119
	v_sub_f32 v154, v154, v118
	v_sub_f32 v155, v155, v119
	v_sub_f32 v150, v150, v118
	v_sub_f32 v151, v151, v119
	v_sub_f32 v178, v178, v118
	v_sub_f32 v179, v179, v119
	v_sub_f32 v115, v115, v118
	v_sub_f32 v117, v117, v119
	v_fma_f32 v183, v88, v183, v118
	v_fma_f32 v182, v88, v182, v119
	v_fma_f32 v180, v89, v180, v118
	v_fma_f32 v181, v89, v181, v119
	v_fma_f32 v154, v80, v154, v118
	v_fma_f32 v155, v80, v155, v119
	v_fma_f32 v150, v81, v150, v118
	v_fma_f32 v151, v81, v151, v119
	v_fma_f32 v80, v72, v183, v140
	v_fma_f32 v72, v72, v182, v140
	v_fma_f32 v81, v73, v180, v140
	v_fma_f32 v73, v73, v181, v140
	ds_read_b128 v[76:79], v145 offset:21504
	ds_read_b128 v[68:71], v145 offset:21760
	ds_read_b128 v[92:95], v145 offset:29696
	ds_read_b128 v[84:87], v145 offset:29952
	ds_read2_b32 v[120:121], v153 offset0:192 offset1:208
	v_sub_f32 v156, v156, v118
	v_sub_f32 v157, v157, v119
	v_sub_f32 v97, v97, v118
	v_sub_f32 v99, v99, v119
	v_fma_f32 v178, v90, v178, v118
	v_fma_f32 v179, v90, v179, v119
	v_fma_f32 v115, v82, v115, v118
	v_fma_f32 v117, v82, v117, v119
	v_fma_f32 v80, v64, v154, v80
	v_fma_f32 v72, v64, v155, v72
	v_fma_f32 v82, v74, v178, v140
	v_fma_f32 v74, v74, v179, v140
	v_fma_f32 v64, v65, v150, v81
	v_fma_f32 v73, v65, v151, v73
	v_fma_f32 v156, v91, v156, v118
	v_fma_f32 v157, v91, v157, v119
	v_fma_f32 v65, v66, v115, v82
	v_fma_f32 v66, v66, v117, v74
	v_fma_f32 v97, v83, v97, v118
	v_fma_f32 v99, v83, v99, v119
	v_fma_f32 v83, v75, v156, v140
	v_fma_f32 v75, v75, v157, v140
	v_add_f32_e32 v64, v80, v64
	v_fma_f32 v74, v67, v97, v83
	v_fma_f32 v67, v67, v99, v75
	v_add_f32_e32 v72, v72, v73
	v_add_f32_e32 v65, v65, v74
	v_add_f32_e32 v66, v66, v67
	v_add_f32_e32 v64, v64, v65
	v_add_f32_e32 v66, v72, v66
	s_nop 0
	v_add_f32_dpp v64, v64, v64 row_ror:8 row_mask:0xf bank_mask:0xf bound_ctrl:1
	v_add_f32_dpp v66, v66, v66 row_ror:8 row_mask:0xf bank_mask:0xf bound_ctrl:1
	s_nop 0
	v_add_f32_dpp v64, v64, v64 row_ror:4 row_mask:0xf bank_mask:0xf bound_ctrl:1
	v_add_f32_dpp v66, v66, v66 row_ror:4 row_mask:0xf bank_mask:0xf bound_ctrl:1
	s_nop 0
	v_add_f32_dpp v64, v64, v64 row_ror:2 row_mask:0xf bank_mask:0xf bound_ctrl:1
	v_add_f32_dpp v66, v66, v66 row_ror:2 row_mask:0xf bank_mask:0xf bound_ctrl:1
	s_nop 0
	v_add_f32_dpp v64, v64, v64 row_ror:1 row_mask:0xf bank_mask:0xf bound_ctrl:1
	v_add_f32_dpp v66, v66, v66 row_ror:1 row_mask:0xf bank_mask:0xf bound_ctrl:1
	ds_write2_b32 v149, v64, v66 offset0:160 offset1:176
	s_waitcnt lgkmcnt(0)
	v_sub_f32 v183, v183, v120
	v_sub_f32 v182, v182, v121
	v_sub_f32 v156, v156, v120
	v_sub_f32 v154, v154, v120
	v_sub_f32 v150, v150, v120
	v_sub_f32 v180, v180, v120
	v_sub_f32 v185, v181, v121
	v_sub_f32 v187, v157, v121
	v_sub_f32 v188, v155, v121
	v_sub_f32 v151, v151, v121
	v_sub_f32 v115, v115, v120
	v_sub_f32 v117, v117, v121
	v_fma_f32 v184, v92, v183, v120
	v_fma_f32 v183, v92, v182, v121
	v_fma_f32 v181, v93, v180, v120
	v_fma_f32 v182, v93, v185, v121
	v_fma_f32 v157, v95, v156, v120
	v_fma_f32 v155, v84, v154, v120
	v_fma_f32 v156, v84, v188, v121
	v_fma_f32 v150, v85, v150, v120
	v_fma_f32 v154, v85, v151, v121
	v_fma_f32 v84, v76, v184, v140
	v_fma_f32 v76, v76, v183, v140
	v_fma_f32 v85, v77, v181, v140
	v_fma_f32 v77, v77, v182, v140
	ds_read_b128 v[72:75], v145 offset:22016
	ds_read_b128 v[64:67], v145 offset:22272
	ds_read_b128 v[88:91], v145 offset:30208
	ds_read_b128 v[80:83], v145 offset:30464
	ds_read2_b32 v[118:119], v153 offset0:224 offset1:240
	v_sub_f32 v178, v178, v120
	v_sub_f32 v186, v179, v121
	v_sub_f32 v97, v97, v120
	v_sub_f32 v99, v99, v121
	v_fma_f32 v115, v86, v115, v120
	v_fma_f32 v117, v86, v117, v121
	v_fma_f32 v179, v94, v178, v120
	v_fma_f32 v180, v94, v186, v121
	v_fma_f32 v84, v68, v155, v84
	v_fma_f32 v76, v68, v156, v76
	v_fma_f32 v68, v69, v150, v85
	v_fma_f32 v77, v69, v154, v77
	v_fma_f32 v86, v78, v179, v140
	v_fma_f32 v78, v78, v180, v140
	v_fma_f32 v178, v95, v187, v121
	v_fma_f32 v97, v87, v97, v120
	v_fma_f32 v99, v87, v99, v121
	v_fma_f32 v87, v79, v157, v140
	v_fma_f32 v69, v70, v115, v86
	v_fma_f32 v70, v70, v117, v78
	v_fma_f32 v79, v79, v178, v140
	v_add_f32_e32 v68, v84, v68
	v_fma_f32 v78, v71, v97, v87
	v_fma_f32 v71, v71, v99, v79
	v_add_f32_e32 v76, v76, v77
	v_add_f32_e32 v69, v69, v78
	v_add_f32_e32 v70, v70, v71
	v_add_f32_e32 v68, v68, v69
	v_add_f32_e32 v70, v76, v70
	s_nop 0
	v_add_f32_dpp v68, v68, v68 row_ror:8 row_mask:0xf bank_mask:0xf bound_ctrl:1
	v_add_f32_dpp v70, v70, v70 row_ror:8 row_mask:0xf bank_mask:0xf bound_ctrl:1
	s_nop 0
	v_add_f32_dpp v68, v68, v68 row_ror:4 row_mask:0xf bank_mask:0xf bound_ctrl:1
	v_add_f32_dpp v70, v70, v70 row_ror:4 row_mask:0xf bank_mask:0xf bound_ctrl:1
	s_nop 0
	v_add_f32_dpp v68, v68, v68 row_ror:2 row_mask:0xf bank_mask:0xf bound_ctrl:1
	v_add_f32_dpp v70, v70, v70 row_ror:2 row_mask:0xf bank_mask:0xf bound_ctrl:1
	s_nop 0
	v_add_f32_dpp v68, v68, v68 row_ror:1 row_mask:0xf bank_mask:0xf bound_ctrl:1
	v_add_f32_dpp v70, v70, v70 row_ror:1 row_mask:0xf bank_mask:0xf bound_ctrl:1
	ds_write2_b32 v149, v68, v70 offset0:192 offset1:208
	s_waitcnt lgkmcnt(0)
	v_sub_f32 v184, v184, v118
	v_sub_f32 v183, v183, v119
	v_sub_f32 v181, v181, v118
	v_sub_f32 v182, v182, v119
	v_sub_f32 v155, v155, v118
	v_sub_f32 v156, v156, v119
	v_sub_f32 v150, v150, v118
	v_sub_f32 v154, v154, v119
	v_sub_f32 v179, v179, v118
	v_sub_f32 v180, v180, v119
	v_sub_f32 v115, v115, v118
	v_sub_f32 v117, v117, v119
	v_fma_f32 v184, v88, v184, v118
	v_fma_f32 v183, v88, v183, v119
	v_fma_f32 v181, v89, v181, v118
	v_fma_f32 v182, v89, v182, v119
	v_fma_f32 v155, v80, v155, v118
	v_fma_f32 v156, v80, v156, v119
	v_fma_f32 v150, v81, v150, v118
	v_fma_f32 v154, v81, v154, v119
	v_fma_f32 v80, v72, v184, v140
	v_fma_f32 v72, v72, v183, v140
	v_fma_f32 v81, v73, v181, v140
	v_fma_f32 v73, v73, v182, v140
	v_sub_f32 v157, v157, v118
	v_sub_f32 v178, v178, v119
	v_sub_f32 v97, v97, v118
	v_sub_f32 v99, v99, v119
	v_fma_f32 v179, v90, v179, v118
	v_fma_f32 v180, v90, v180, v119
	v_fma_f32 v115, v82, v115, v118
	v_fma_f32 v117, v82, v117, v119
	v_fma_f32 v80, v64, v155, v80
	v_fma_f32 v72, v64, v156, v72
	v_fma_f32 v82, v74, v179, v140
	v_fma_f32 v74, v74, v180, v140
	v_fma_f32 v64, v65, v150, v81
	v_fma_f32 v73, v65, v154, v73
	ds_read_b128 v[76:79], v145 offset:22528
	ds_read_b128 v[68:71], v145 offset:22784
	ds_read_b128 v[92:95], v145 offset:30720
	ds_read_b128 v[84:87], v145 offset:30976
	v_fma_f32 v65, v66, v115, v82
	v_fma_f32 v66, v66, v117, v74
	v_fma_f32 v157, v91, v157, v118
	v_fma_f32 v178, v91, v178, v119
	v_fma_f32 v97, v83, v97, v118
	v_fma_f32 v99, v83, v99, v119
	v_add_f32_e32 v64, v80, v64
	v_fma_f32 v83, v75, v157, v140
	v_fma_f32 v75, v75, v178, v140
	v_add_f32_e32 v72, v72, v73
	v_fma_f32 v74, v67, v97, v83
	v_fma_f32 v67, v67, v99, v75
	v_add_u32_e32 v151, 0x8c00, v103
	v_add_f32_e32 v65, v65, v74
	v_add_f32_e32 v66, v66, v67
	v_add_f32_e32 v64, v64, v65
	v_add_f32_e32 v66, v72, v66
	ds_read2_b32 v[120:121], v151 offset1:16
	v_add_f32_dpp v64, v64, v64 row_ror:8 row_mask:0xf bank_mask:0xf bound_ctrl:1
	v_add_f32_dpp v66, v66, v66 row_ror:8 row_mask:0xf bank_mask:0xf bound_ctrl:1
	s_nop 0
	v_add_f32_dpp v64, v64, v64 row_ror:4 row_mask:0xf bank_mask:0xf bound_ctrl:1
	v_add_f32_dpp v66, v66, v66 row_ror:4 row_mask:0xf bank_mask:0xf bound_ctrl:1
	s_nop 0
	v_add_f32_dpp v64, v64, v64 row_ror:2 row_mask:0xf bank_mask:0xf bound_ctrl:1
	v_add_f32_dpp v66, v66, v66 row_ror:2 row_mask:0xf bank_mask:0xf bound_ctrl:1
	s_nop 0
	v_add_f32_dpp v64, v64, v64 row_ror:1 row_mask:0xf bank_mask:0xf bound_ctrl:1
	v_add_f32_dpp v66, v66, v66 row_ror:1 row_mask:0xf bank_mask:0xf bound_ctrl:1
	ds_write2_b32 v149, v64, v66 offset0:224 offset1:240
	s_waitcnt lgkmcnt(0)
	v_sub_f32 v184, v184, v120
	v_sub_f32 v183, v183, v121
	v_sub_f32 v157, v157, v120
	v_sub_f32 v155, v155, v120
	v_sub_f32 v181, v181, v120
	v_sub_f32 v186, v182, v121
	v_sub_f32 v188, v178, v121
	v_sub_f32 v189, v156, v121
	v_sub_f32 v150, v150, v120
	v_sub_f32 v190, v154, v121
	v_sub_f32 v115, v115, v120
	v_sub_f32 v117, v117, v121
	v_fma_f32 v185, v92, v184, v120
	v_fma_f32 v184, v92, v183, v121
	v_fma_f32 v182, v93, v181, v120
	v_fma_f32 v183, v93, v186, v121
	v_fma_f32 v178, v95, v157, v120
	v_fma_f32 v156, v84, v155, v120
	v_fma_f32 v157, v84, v189, v121
	v_fma_f32 v154, v85, v150, v120
	v_fma_f32 v155, v85, v190, v121
	v_fma_f32 v84, v76, v185, v140
	v_fma_f32 v76, v76, v184, v140
	v_fma_f32 v85, v77, v182, v140
	v_fma_f32 v77, v77, v183, v140
	ds_read_b128 v[72:75], v145 offset:23040
	ds_read_b128 v[64:67], v145 offset:23296
	ds_read_b128 v[88:91], v145 offset:31232
	ds_read_b128 v[80:83], v145 offset:31488
	ds_read2_b32 v[118:119], v151 offset0:32 offset1:48
	v_sub_f32 v179, v179, v120
	v_sub_f32 v187, v180, v121
	v_sub_f32 v97, v97, v120
	v_sub_f32 v99, v99, v121
	v_fma_f32 v115, v86, v115, v120
	v_fma_f32 v117, v86, v117, v121
	v_fma_f32 v180, v94, v179, v120
	v_fma_f32 v181, v94, v187, v121
	v_fma_f32 v84, v68, v156, v84
	v_fma_f32 v76, v68, v157, v76
	v_fma_f32 v68, v69, v154, v85
	v_fma_f32 v77, v69, v155, v77
	v_fma_f32 v86, v78, v180, v140
	v_fma_f32 v78, v78, v181, v140
	v_fma_f32 v179, v95, v188, v121
	v_fma_f32 v97, v87, v97, v120
	v_fma_f32 v99, v87, v99, v121
	v_fma_f32 v87, v79, v178, v140
	v_fma_f32 v69, v70, v115, v86
	v_fma_f32 v70, v70, v117, v78
	v_fma_f32 v79, v79, v179, v140
	v_add_f32_e32 v68, v84, v68
	v_fma_f32 v78, v71, v97, v87
	v_fma_f32 v71, v71, v99, v79
	v_add_f32_e32 v76, v76, v77
	v_add_f32_e32 v69, v69, v78
	v_add_f32_e32 v70, v70, v71
	v_add_f32_e32 v68, v68, v69
	v_add_f32_e32 v70, v76, v70
	s_nop 0
	v_add_f32_dpp v68, v68, v68 row_ror:8 row_mask:0xf bank_mask:0xf bound_ctrl:1
	v_add_f32_dpp v70, v70, v70 row_ror:8 row_mask:0xf bank_mask:0xf bound_ctrl:1
	s_nop 0
	v_add_f32_dpp v68, v68, v68 row_ror:4 row_mask:0xf bank_mask:0xf bound_ctrl:1
	v_add_f32_dpp v70, v70, v70 row_ror:4 row_mask:0xf bank_mask:0xf bound_ctrl:1
	v_add_u32_e32 v150, 0x9c00, v103
	v_add_f32_dpp v68, v68, v68 row_ror:2 row_mask:0xf bank_mask:0xf bound_ctrl:1
	v_add_f32_dpp v70, v70, v70 row_ror:2 row_mask:0xf bank_mask:0xf bound_ctrl:1
	s_nop 0
	v_add_f32_dpp v68, v68, v68 row_ror:1 row_mask:0xf bank_mask:0xf bound_ctrl:1
	v_add_f32_dpp v70, v70, v70 row_ror:1 row_mask:0xf bank_mask:0xf bound_ctrl:1
	ds_write2_b32 v150, v68, v70 offset1:16
	s_waitcnt lgkmcnt(0)
	v_sub_f32 v185, v185, v118
	v_sub_f32 v184, v184, v119
	v_sub_f32 v182, v182, v118
	v_sub_f32 v183, v183, v119
	v_sub_f32 v156, v156, v118
	v_sub_f32 v157, v157, v119
	v_sub_f32 v154, v154, v118
	v_sub_f32 v155, v155, v119
	v_sub_f32 v180, v180, v118
	v_sub_f32 v181, v181, v119
	v_sub_f32 v115, v115, v118
	v_sub_f32 v117, v117, v119
	v_fma_f32 v185, v88, v185, v118
	v_fma_f32 v184, v88, v184, v119
	v_fma_f32 v182, v89, v182, v118
	v_fma_f32 v183, v89, v183, v119
	v_fma_f32 v156, v80, v156, v118
	v_fma_f32 v157, v80, v157, v119
	v_fma_f32 v154, v81, v154, v118
	v_fma_f32 v155, v81, v155, v119
	v_fma_f32 v80, v72, v185, v140
	v_fma_f32 v72, v72, v184, v140
	v_fma_f32 v81, v73, v182, v140
	v_fma_f32 v73, v73, v183, v140
	ds_read_b128 v[76:79], v145 offset:23552
	ds_read_b128 v[68:71], v145 offset:23808
	ds_read_b128 v[92:95], v145 offset:31744
	ds_read_b128 v[84:87], v145 offset:32000
	ds_read2_b32 v[120:121], v151 offset0:64 offset1:80
	v_sub_f32 v178, v178, v118
	v_sub_f32 v179, v179, v119
	v_sub_f32 v97, v97, v118
	v_sub_f32 v99, v99, v119
	v_fma_f32 v180, v90, v180, v118
	v_fma_f32 v181, v90, v181, v119
	v_fma_f32 v115, v82, v115, v118
	v_fma_f32 v117, v82, v117, v119
	v_fma_f32 v80, v64, v156, v80
	v_fma_f32 v72, v64, v157, v72
	v_fma_f32 v82, v74, v180, v140
	v_fma_f32 v74, v74, v181, v140
	v_fma_f32 v64, v65, v154, v81
	v_fma_f32 v73, v65, v155, v73
	v_fma_f32 v178, v91, v178, v118
	v_fma_f32 v179, v91, v179, v119
	v_fma_f32 v65, v66, v115, v82
	v_fma_f32 v66, v66, v117, v74
	v_fma_f32 v97, v83, v97, v118
	v_fma_f32 v99, v83, v99, v119
	v_fma_f32 v83, v75, v178, v140
	v_fma_f32 v75, v75, v179, v140
	v_add_f32_e32 v64, v80, v64
	v_fma_f32 v74, v67, v97, v83
	v_fma_f32 v67, v67, v99, v75
	v_add_f32_e32 v72, v72, v73
	v_add_f32_e32 v65, v65, v74
	v_add_f32_e32 v66, v66, v67
	v_add_f32_e32 v64, v64, v65
	v_add_f32_e32 v66, v72, v66
	s_nop 0
	v_add_f32_dpp v64, v64, v64 row_ror:8 row_mask:0xf bank_mask:0xf bound_ctrl:1
	v_add_f32_dpp v66, v66, v66 row_ror:8 row_mask:0xf bank_mask:0xf bound_ctrl:1
	s_nop 0
	v_add_f32_dpp v64, v64, v64 row_ror:4 row_mask:0xf bank_mask:0xf bound_ctrl:1
	v_add_f32_dpp v66, v66, v66 row_ror:4 row_mask:0xf bank_mask:0xf bound_ctrl:1
	s_nop 0
	v_add_f32_dpp v64, v64, v64 row_ror:2 row_mask:0xf bank_mask:0xf bound_ctrl:1
	v_add_f32_dpp v66, v66, v66 row_ror:2 row_mask:0xf bank_mask:0xf bound_ctrl:1
	s_nop 0
	v_add_f32_dpp v64, v64, v64 row_ror:1 row_mask:0xf bank_mask:0xf bound_ctrl:1
	v_add_f32_dpp v66, v66, v66 row_ror:1 row_mask:0xf bank_mask:0xf bound_ctrl:1
	ds_write2_b32 v150, v64, v66 offset0:32 offset1:48
	s_waitcnt lgkmcnt(0)
	v_sub_f32 v185, v185, v120
	v_sub_f32 v184, v184, v121
	v_sub_f32 v182, v182, v120
	v_sub_f32 v183, v183, v121
	v_sub_f32 v156, v156, v120
	v_sub_f32 v157, v157, v121
	v_sub_f32 v154, v154, v120
	v_sub_f32 v155, v155, v121
	v_sub_f32 v180, v180, v120
	v_sub_f32 v181, v181, v121
	v_sub_f32 v115, v115, v120
	v_sub_f32 v117, v117, v121
	v_fma_f32 v185, v92, v185, v120
	v_fma_f32 v184, v92, v184, v121
	v_fma_f32 v182, v93, v182, v120
	v_fma_f32 v183, v93, v183, v121
	v_fma_f32 v156, v84, v156, v120
	v_fma_f32 v157, v84, v157, v121
	v_fma_f32 v154, v85, v154, v120
	v_fma_f32 v155, v85, v155, v121
	v_fma_f32 v84, v76, v185, v140
	v_fma_f32 v76, v76, v184, v140
	v_fma_f32 v85, v77, v182, v140
	v_fma_f32 v77, v77, v183, v140
	ds_read_b128 v[72:75], v145 offset:24064
	ds_read_b128 v[64:67], v145 offset:24320
	ds_read_b128 v[88:91], v145 offset:32256
	ds_read_b128 v[80:83], v145 offset:32512
	ds_read2_b32 v[118:119], v151 offset0:96 offset1:112
	v_sub_f32 v178, v178, v120
	v_sub_f32 v179, v179, v121
	v_sub_f32 v97, v97, v120
	v_sub_f32 v99, v99, v121
	v_fma_f32 v180, v94, v180, v120
	v_fma_f32 v181, v94, v181, v121
	v_fma_f32 v115, v86, v115, v120
	v_fma_f32 v117, v86, v117, v121
	v_fma_f32 v84, v68, v156, v84
	v_fma_f32 v76, v68, v157, v76
	v_fma_f32 v86, v78, v180, v140
	v_fma_f32 v78, v78, v181, v140
	v_fma_f32 v68, v69, v154, v85
	v_fma_f32 v77, v69, v155, v77
	v_fma_f32 v178, v95, v178, v120
	v_fma_f32 v179, v95, v179, v121
	v_fma_f32 v69, v70, v115, v86
	v_fma_f32 v70, v70, v117, v78
	v_fma_f32 v97, v87, v97, v120
	v_fma_f32 v99, v87, v99, v121
	v_fma_f32 v87, v79, v178, v140
	v_fma_f32 v79, v79, v179, v140
	v_add_f32_e32 v68, v84, v68
	v_fma_f32 v78, v71, v97, v87
	v_fma_f32 v71, v71, v99, v79
	v_add_f32_e32 v76, v76, v77
	v_add_f32_e32 v69, v69, v78
	v_add_f32_e32 v70, v70, v71
	v_add_f32_e32 v68, v68, v69
	v_add_f32_e32 v70, v76, v70
	s_nop 0
	v_add_f32_dpp v68, v68, v68 row_ror:8 row_mask:0xf bank_mask:0xf bound_ctrl:1
	v_add_f32_dpp v70, v70, v70 row_ror:8 row_mask:0xf bank_mask:0xf bound_ctrl:1
	s_nop 0
	v_add_f32_dpp v68, v68, v68 row_ror:4 row_mask:0xf bank_mask:0xf bound_ctrl:1
	v_add_f32_dpp v70, v70, v70 row_ror:4 row_mask:0xf bank_mask:0xf bound_ctrl:1
	s_nop 0
	v_add_f32_dpp v68, v68, v68 row_ror:2 row_mask:0xf bank_mask:0xf bound_ctrl:1
	v_add_f32_dpp v70, v70, v70 row_ror:2 row_mask:0xf bank_mask:0xf bound_ctrl:1
	s_nop 0
	v_add_f32_dpp v68, v68, v68 row_ror:1 row_mask:0xf bank_mask:0xf bound_ctrl:1
	v_add_f32_dpp v70, v70, v70 row_ror:1 row_mask:0xf bank_mask:0xf bound_ctrl:1
	ds_write2_b32 v150, v68, v70 offset0:64 offset1:80
	s_waitcnt lgkmcnt(0)
	v_sub_f32 v185, v185, v118
	v_sub_f32 v184, v184, v119
	v_sub_f32 v182, v182, v118
	v_sub_f32 v183, v183, v119
	v_sub_f32 v156, v156, v118
	v_sub_f32 v157, v157, v119
	v_sub_f32 v154, v154, v118
	v_sub_f32 v155, v155, v119
	v_sub_f32 v180, v180, v118
	v_sub_f32 v181, v181, v119
	v_sub_f32 v115, v115, v118
	v_sub_f32 v117, v117, v119
	v_fma_f32 v185, v88, v185, v118
	v_fma_f32 v184, v88, v184, v119
	v_fma_f32 v182, v89, v182, v118
	v_fma_f32 v183, v89, v183, v119
	v_fma_f32 v156, v80, v156, v118
	v_fma_f32 v157, v80, v157, v119
	v_fma_f32 v154, v81, v154, v118
	v_fma_f32 v155, v81, v155, v119
	v_fma_f32 v80, v72, v185, v140
	v_fma_f32 v72, v72, v184, v140
	v_fma_f32 v81, v73, v182, v140
	v_fma_f32 v73, v73, v183, v140
	ds_read_b128 v[76:79], v145 offset:24576
	ds_read_b128 v[68:71], v145 offset:24832
	ds_read_b128 v[92:95], v145 offset:32768
	ds_read_b128 v[84:87], v145 offset:33024
	ds_read2_b32 v[120:121], v151 offset0:128 offset1:144
	v_sub_f32 v178, v178, v118
	v_sub_f32 v179, v179, v119
	v_sub_f32 v97, v97, v118
	v_sub_f32 v99, v99, v119
	v_fma_f32 v180, v90, v180, v118
	v_fma_f32 v181, v90, v181, v119
	v_fma_f32 v115, v82, v115, v118
	v_fma_f32 v117, v82, v117, v119
	v_fma_f32 v80, v64, v156, v80
	v_fma_f32 v72, v64, v157, v72
	v_fma_f32 v82, v74, v180, v140
	v_fma_f32 v74, v74, v181, v140
	v_fma_f32 v64, v65, v154, v81
	v_fma_f32 v73, v65, v155, v73
	v_fma_f32 v178, v91, v178, v118
	v_fma_f32 v179, v91, v179, v119
	v_fma_f32 v65, v66, v115, v82
	v_fma_f32 v66, v66, v117, v74
	v_fma_f32 v97, v83, v97, v118
	v_fma_f32 v99, v83, v99, v119
	v_fma_f32 v83, v75, v178, v140
	v_fma_f32 v75, v75, v179, v140
	v_add_f32_e32 v64, v80, v64
	v_fma_f32 v74, v67, v97, v83
	v_fma_f32 v67, v67, v99, v75
	v_add_f32_e32 v72, v72, v73
	v_add_f32_e32 v65, v65, v74
	v_add_f32_e32 v66, v66, v67
	v_add_f32_e32 v64, v64, v65
	v_add_f32_e32 v66, v72, v66
	s_nop 0
	v_add_f32_dpp v64, v64, v64 row_ror:8 row_mask:0xf bank_mask:0xf bound_ctrl:1
	v_add_f32_dpp v66, v66, v66 row_ror:8 row_mask:0xf bank_mask:0xf bound_ctrl:1
	s_nop 0
	v_add_f32_dpp v64, v64, v64 row_ror:4 row_mask:0xf bank_mask:0xf bound_ctrl:1
	v_add_f32_dpp v66, v66, v66 row_ror:4 row_mask:0xf bank_mask:0xf bound_ctrl:1
	s_nop 0
	v_add_f32_dpp v64, v64, v64 row_ror:2 row_mask:0xf bank_mask:0xf bound_ctrl:1
	v_add_f32_dpp v66, v66, v66 row_ror:2 row_mask:0xf bank_mask:0xf bound_ctrl:1
	s_nop 0
	v_add_f32_dpp v64, v64, v64 row_ror:1 row_mask:0xf bank_mask:0xf bound_ctrl:1
	v_add_f32_dpp v66, v66, v66 row_ror:1 row_mask:0xf bank_mask:0xf bound_ctrl:1
	ds_write2_b32 v150, v64, v66 offset0:96 offset1:112
	s_waitcnt lgkmcnt(0)
	v_sub_f32 v185, v185, v120
	v_sub_f32 v184, v184, v121
	v_sub_f32 v182, v182, v120
	v_sub_f32 v183, v183, v121
	v_sub_f32 v156, v156, v120
	v_sub_f32 v157, v157, v121
	v_sub_f32 v154, v154, v120
	v_sub_f32 v155, v155, v121
	v_sub_f32 v180, v180, v120
	v_sub_f32 v181, v181, v121
	v_sub_f32 v115, v115, v120
	v_sub_f32 v117, v117, v121
	v_fma_f32 v185, v92, v185, v120
	v_fma_f32 v184, v92, v184, v121
	v_fma_f32 v182, v93, v182, v120
	v_fma_f32 v183, v93, v183, v121
	v_fma_f32 v156, v84, v156, v120
	v_fma_f32 v157, v84, v157, v121
	v_fma_f32 v154, v85, v154, v120
	v_fma_f32 v155, v85, v155, v121
	v_fma_f32 v84, v76, v185, v140
	v_fma_f32 v76, v76, v184, v140
	v_fma_f32 v85, v77, v182, v140
	v_fma_f32 v77, v77, v183, v140
	ds_read_b128 v[72:75], v145 offset:25088
	ds_read_b128 v[64:67], v145 offset:25344
	ds_read_b128 v[88:91], v145 offset:33280
	ds_read_b128 v[80:83], v145 offset:33536
	ds_read2_b32 v[118:119], v151 offset0:160 offset1:176
	v_sub_f32 v178, v178, v120
	v_sub_f32 v179, v179, v121
	v_sub_f32 v97, v97, v120
	v_sub_f32 v99, v99, v121
	v_fma_f32 v180, v94, v180, v120
	v_fma_f32 v181, v94, v181, v121
	v_fma_f32 v115, v86, v115, v120
	v_fma_f32 v117, v86, v117, v121
	v_fma_f32 v84, v68, v156, v84
	v_fma_f32 v76, v68, v157, v76
	v_fma_f32 v86, v78, v180, v140
	v_fma_f32 v78, v78, v181, v140
	v_fma_f32 v68, v69, v154, v85
	v_fma_f32 v77, v69, v155, v77
	v_fma_f32 v178, v95, v178, v120
	v_fma_f32 v179, v95, v179, v121
	v_fma_f32 v69, v70, v115, v86
	v_fma_f32 v70, v70, v117, v78
	v_fma_f32 v97, v87, v97, v120
	v_fma_f32 v99, v87, v99, v121
	v_fma_f32 v87, v79, v178, v140
	v_fma_f32 v79, v79, v179, v140
	v_add_f32_e32 v68, v84, v68
	v_fma_f32 v78, v71, v97, v87
	v_fma_f32 v71, v71, v99, v79
	v_add_f32_e32 v76, v76, v77
	v_add_f32_e32 v69, v69, v78
	v_add_f32_e32 v70, v70, v71
	v_add_f32_e32 v68, v68, v69
	v_add_f32_e32 v70, v76, v70
	s_nop 0
	v_add_f32_dpp v68, v68, v68 row_ror:8 row_mask:0xf bank_mask:0xf bound_ctrl:1
	v_add_f32_dpp v70, v70, v70 row_ror:8 row_mask:0xf bank_mask:0xf bound_ctrl:1
	s_nop 0
	v_add_f32_dpp v68, v68, v68 row_ror:4 row_mask:0xf bank_mask:0xf bound_ctrl:1
	v_add_f32_dpp v70, v70, v70 row_ror:4 row_mask:0xf bank_mask:0xf bound_ctrl:1
	s_nop 0
	v_add_f32_dpp v68, v68, v68 row_ror:2 row_mask:0xf bank_mask:0xf bound_ctrl:1
	v_add_f32_dpp v70, v70, v70 row_ror:2 row_mask:0xf bank_mask:0xf bound_ctrl:1
	s_nop 0
	v_add_f32_dpp v68, v68, v68 row_ror:1 row_mask:0xf bank_mask:0xf bound_ctrl:1
	v_add_f32_dpp v70, v70, v70 row_ror:1 row_mask:0xf bank_mask:0xf bound_ctrl:1
	ds_write2_b32 v150, v68, v70 offset0:128 offset1:144
	s_waitcnt lgkmcnt(0)
	v_sub_f32 v185, v185, v118
	v_sub_f32 v184, v184, v119
	v_sub_f32 v182, v182, v118
	v_sub_f32 v183, v183, v119
	v_sub_f32 v156, v156, v118
	v_sub_f32 v157, v157, v119
	v_sub_f32 v154, v154, v118
	v_sub_f32 v155, v155, v119
	v_sub_f32 v180, v180, v118
	v_sub_f32 v181, v181, v119
	v_sub_f32 v115, v115, v118
	v_sub_f32 v117, v117, v119
	v_fma_f32 v185, v88, v185, v118
	v_fma_f32 v184, v88, v184, v119
	v_fma_f32 v182, v89, v182, v118
	v_fma_f32 v183, v89, v183, v119
	v_fma_f32 v156, v80, v156, v118
	v_fma_f32 v157, v80, v157, v119
	v_fma_f32 v154, v81, v154, v118
	v_fma_f32 v155, v81, v155, v119
	v_fma_f32 v80, v72, v185, v140
	v_fma_f32 v72, v72, v184, v140
	v_fma_f32 v81, v73, v182, v140
	v_fma_f32 v73, v73, v183, v140
	ds_read_b128 v[76:79], v145 offset:25600
	ds_read_b128 v[68:71], v145 offset:25856
	ds_read_b128 v[92:95], v145 offset:33792
	ds_read_b128 v[84:87], v145 offset:34048
	ds_read2_b32 v[120:121], v151 offset0:192 offset1:208
	v_sub_f32 v178, v178, v118
	v_sub_f32 v179, v179, v119
	v_sub_f32 v97, v97, v118
	v_sub_f32 v99, v99, v119
	v_fma_f32 v180, v90, v180, v118
	v_fma_f32 v181, v90, v181, v119
	v_fma_f32 v115, v82, v115, v118
	v_fma_f32 v117, v82, v117, v119
	v_fma_f32 v80, v64, v156, v80
	v_fma_f32 v72, v64, v157, v72
	v_fma_f32 v82, v74, v180, v140
	v_fma_f32 v74, v74, v181, v140
	v_fma_f32 v64, v65, v154, v81
	v_fma_f32 v73, v65, v155, v73
	v_fma_f32 v178, v91, v178, v118
	v_fma_f32 v179, v91, v179, v119
	v_fma_f32 v65, v66, v115, v82
	v_fma_f32 v66, v66, v117, v74
	v_fma_f32 v97, v83, v97, v118
	v_fma_f32 v99, v83, v99, v119
	v_fma_f32 v83, v75, v178, v140
	v_fma_f32 v75, v75, v179, v140
	v_add_f32_e32 v64, v80, v64
	v_fma_f32 v74, v67, v97, v83
	v_fma_f32 v67, v67, v99, v75
	v_add_f32_e32 v72, v72, v73
	v_add_f32_e32 v65, v65, v74
	v_add_f32_e32 v66, v66, v67
	v_add_f32_e32 v64, v64, v65
	v_add_f32_e32 v66, v72, v66
	s_nop 0
	v_add_f32_dpp v64, v64, v64 row_ror:8 row_mask:0xf bank_mask:0xf bound_ctrl:1
	v_add_f32_dpp v66, v66, v66 row_ror:8 row_mask:0xf bank_mask:0xf bound_ctrl:1
	s_nop 0
	v_add_f32_dpp v64, v64, v64 row_ror:4 row_mask:0xf bank_mask:0xf bound_ctrl:1
	v_add_f32_dpp v66, v66, v66 row_ror:4 row_mask:0xf bank_mask:0xf bound_ctrl:1
	s_nop 0
	v_add_f32_dpp v64, v64, v64 row_ror:2 row_mask:0xf bank_mask:0xf bound_ctrl:1
	v_add_f32_dpp v66, v66, v66 row_ror:2 row_mask:0xf bank_mask:0xf bound_ctrl:1
	s_nop 0
	v_add_f32_dpp v64, v64, v64 row_ror:1 row_mask:0xf bank_mask:0xf bound_ctrl:1
	v_add_f32_dpp v66, v66, v66 row_ror:1 row_mask:0xf bank_mask:0xf bound_ctrl:1
	ds_write2_b32 v150, v64, v66 offset0:160 offset1:176
	s_waitcnt lgkmcnt(0)
	v_sub_f32 v185, v185, v120
	v_sub_f32 v184, v184, v121
	v_sub_f32 v182, v182, v120
	v_sub_f32 v183, v183, v121
	v_sub_f32 v180, v180, v120
	v_sub_f32 v181, v181, v121
	v_sub_f32 v186, v178, v120
	v_sub_f32 v179, v179, v121
	v_sub_f32 v187, v156, v120
	v_sub_f32 v188, v157, v121
	v_sub_f32 v189, v154, v120
	v_sub_f32 v190, v155, v121
	v_sub_f32 v191, v115, v120
	v_sub_f32 v192, v117, v121
	v_sub_f32 v193, v97, v120
	v_sub_f32 v194, v99, v121
	v_fma_f32 v178, v92, v185, v120
	v_fma_f32 v157, v92, v184, v121
	v_fma_f32 v155, v93, v182, v120
	v_fma_f32 v156, v93, v183, v121
	v_fma_f32 v117, v94, v180, v120
	v_fma_f32 v154, v94, v181, v121
	v_fma_f32 v99, v95, v186, v120
	v_fma_f32 v115, v95, v179, v121
	v_fma_f32 v95, v84, v187, v120
	v_fma_f32 v97, v84, v188, v121
	v_fma_f32 v93, v85, v189, v120
	v_fma_f32 v94, v85, v190, v121
	v_fma_f32 v92, v86, v191, v120
	v_fma_f32 v84, v87, v193, v120
	v_fma_f32 v85, v87, v194, v121
	v_fma_f32 v87, v76, v178, v140
	v_fma_f32 v76, v76, v157, v140
	v_fma_f32 v120, v77, v155, v140
	v_fma_f32 v77, v77, v156, v140
	ds_read_b128 v[72:75], v145 offset:26112
	ds_read_b128 v[64:67], v145 offset:26368
	ds_read_b128 v[88:91], v145 offset:34304
	ds_read_b128 v[80:83], v145 offset:34560
	ds_read2_b32 v[118:119], v151 offset0:224 offset1:240
	v_fma_f32 v86, v86, v192, v121
	v_fma_f32 v121, v78, v117, v140
	v_fma_f32 v78, v78, v154, v140
	v_fma_f32 v87, v68, v95, v87
	v_fma_f32 v76, v68, v97, v76
	v_fma_f32 v68, v69, v93, v120
	v_fma_f32 v77, v69, v94, v77
	v_fma_f32 v69, v70, v92, v121
	v_fma_f32 v70, v70, v86, v78
	v_fma_f32 v179, v79, v99, v140
	v_fma_f32 v79, v79, v115, v140
	v_add_f32_e32 v68, v87, v68
	v_fma_f32 v78, v71, v84, v179
	v_fma_f32 v71, v71, v85, v79
	v_add_f32_e32 v76, v76, v77
	v_add_f32_e32 v69, v69, v78
	v_add_f32_e32 v70, v70, v71
	v_add_f32_e32 v68, v68, v69
	v_add_f32_e32 v70, v76, v70
	s_nop 0
	v_add_f32_dpp v68, v68, v68 row_ror:8 row_mask:0xf bank_mask:0xf bound_ctrl:1
	v_add_f32_dpp v70, v70, v70 row_ror:8 row_mask:0xf bank_mask:0xf bound_ctrl:1
	s_nop 0
	v_add_f32_dpp v68, v68, v68 row_ror:4 row_mask:0xf bank_mask:0xf bound_ctrl:1
	v_add_f32_dpp v70, v70, v70 row_ror:4 row_mask:0xf bank_mask:0xf bound_ctrl:1
	s_nop 0
	v_add_f32_dpp v68, v68, v68 row_ror:2 row_mask:0xf bank_mask:0xf bound_ctrl:1
	v_add_f32_dpp v70, v70, v70 row_ror:2 row_mask:0xf bank_mask:0xf bound_ctrl:1
	s_nop 0
	v_add_f32_dpp v68, v68, v68 row_ror:1 row_mask:0xf bank_mask:0xf bound_ctrl:1
	v_add_f32_dpp v70, v70, v70 row_ror:1 row_mask:0xf bank_mask:0xf bound_ctrl:1
	ds_write2_b32 v150, v68, v70 offset0:192 offset1:208
	s_waitcnt lgkmcnt(0)
	v_sub_f32 v76, v117, v118
	v_sub_f32 v77, v154, v119
	v_sub_f32 v78, v99, v118
	v_sub_f32 v79, v115, v119
	v_sub_f32 v68, v178, v118
	v_sub_f32 v69, v157, v119
	v_sub_f32 v70, v155, v118
	v_sub_f32 v71, v156, v119
	v_sub_f32 v99, v95, v118
	v_sub_f32 v97, v97, v119
	v_sub_f32 v115, v93, v118
	v_sub_f32 v117, v94, v119
	v_sub_f32 v120, v92, v118
	v_sub_f32 v121, v86, v119
	v_sub_f32 v154, v84, v118
	v_sub_f32 v155, v85, v119
	v_fma_f32 v95, v88, v68, v118
	v_fma_f32 v94, v88, v69, v119
	v_fma_f32 v92, v89, v70, v118
	v_fma_f32 v93, v89, v71, v119
	v_fma_f32 v86, v90, v76, v118
	v_fma_f32 v87, v90, v77, v119
	v_fma_f32 v84, v91, v78, v118
	v_fma_f32 v85, v91, v79, v119
	v_fma_f32 v78, v80, v99, v118
	v_fma_f32 v79, v80, v97, v119
	v_fma_f32 v76, v81, v115, v118
	v_fma_f32 v77, v81, v117, v119
	v_fma_f32 v80, v72, v95, v140
	v_fma_f32 v72, v72, v94, v140
	v_fma_f32 v81, v73, v92, v140
	v_fma_f32 v73, v73, v93, v140
	v_fma_f32 v70, v82, v120, v118
	v_fma_f32 v71, v82, v121, v119
	v_fma_f32 v82, v74, v86, v140
	v_fma_f32 v74, v74, v87, v140
	v_fma_f32 v80, v64, v78, v80
	v_fma_f32 v72, v64, v79, v72
	v_fma_f32 v64, v65, v76, v81
	v_fma_f32 v73, v65, v77, v73
	v_fma_f32 v65, v66, v70, v82
	v_fma_f32 v66, v66, v71, v74
	v_fma_f32 v68, v83, v154, v118
	v_fma_f32 v69, v83, v155, v119
	v_fma_f32 v83, v75, v84, v140
	v_fma_f32 v75, v75, v85, v140
	v_add_f32_e32 v64, v80, v64
	v_fma_f32 v74, v67, v68, v83
	v_fma_f32 v67, v67, v69, v75
	v_add_f32_e32 v72, v72, v73
	v_add_f32_e32 v65, v65, v74
	v_add_f32_e32 v66, v66, v67
	v_add_f32_e32 v64, v64, v65
	v_add_f32_e32 v66, v72, v66
	s_nop 0
	v_add_f32_dpp v64, v64, v64 row_ror:8 row_mask:0xf bank_mask:0xf bound_ctrl:1
	v_add_f32_dpp v66, v66, v66 row_ror:8 row_mask:0xf bank_mask:0xf bound_ctrl:1
	s_nop 0
	v_add_f32_dpp v64, v64, v64 row_ror:4 row_mask:0xf bank_mask:0xf bound_ctrl:1
	v_add_f32_dpp v66, v66, v66 row_ror:4 row_mask:0xf bank_mask:0xf bound_ctrl:1
	s_nop 0
	v_add_f32_dpp v64, v64, v64 row_ror:2 row_mask:0xf bank_mask:0xf bound_ctrl:1
	v_add_f32_dpp v66, v66, v66 row_ror:2 row_mask:0xf bank_mask:0xf bound_ctrl:1
	s_nop 0
	v_add_f32_dpp v64, v64, v64 row_ror:1 row_mask:0xf bank_mask:0xf bound_ctrl:1
	v_add_f32_dpp v66, v66, v66 row_ror:1 row_mask:0xf bank_mask:0xf bound_ctrl:1
	ds_write2_b32 v150, v64, v66 offset0:224 offset1:240
	s_waitcnt vmcnt(9)
	v_mul_f32_e32 v64, 0xbfb8aa3b, v28
	v_mul_f32_e32 v65, 0xbfb8aa3b, v29
	v_exp_f32_e32 v64, v64
	v_exp_f32_e32 v65, v65
	v_mul_f32_e32 v66, 0xbfb8aa3b, v30
	v_mul_f32_e32 v67, 0xbfb8aa3b, v31
	v_exp_f32_e32 v66, v66
	v_pk_add_f32 v[64:65], v[64:65], 1.0 op_sel_hi:[1,0]
	v_exp_f32_e32 v67, v67
	v_div_scale_f32 v80, s[8:9], v65, v65, v29
	v_rcp_f32_e32 v81, v80
	v_pk_add_f32 v[66:67], v[66:67], 1.0 op_sel_hi:[1,0]
	s_waitcnt vmcnt(8)
	v_mul_f32_e32 v72, 0xbfb8aa3b, v32
	v_mul_f32_e32 v73, 0xbfb8aa3b, v33
	v_fma_f32 v82, -v80, v81, 1.0
	v_fmac_f32_e32 v81, v82, v81
	v_div_scale_f32 v82, vcc, v29, v65, v29
	v_mul_f32_e32 v83, v82, v81
	v_fma_f32 v88, -v80, v83, v82
	v_fmac_f32_e32 v83, v88, v81
	v_fma_f32 v80, -v80, v83, v82
	v_div_fmas_f32 v80, v80, v81, v83
	v_div_fixup_f32 v65, v80, v65, v29
	v_div_scale_f32 v80, s[8:9], v64, v64, v28
	v_rcp_f32_e32 v81, v80
	v_exp_f32_e32 v72, v72
	v_exp_f32_e32 v73, v73
	v_mul_f32_e32 v74, 0xbfb8aa3b, v34
	v_fma_f32 v82, -v80, v81, 1.0
	v_fmac_f32_e32 v81, v82, v81
	v_div_scale_f32 v82, vcc, v28, v64, v28
	v_mul_f32_e32 v83, v82, v81
	v_fma_f32 v88, -v80, v83, v82
	v_fmac_f32_e32 v83, v88, v81
	v_fma_f32 v80, -v80, v83, v82
	v_div_fmas_f32 v80, v80, v81, v83
	v_div_fixup_f32 v64, v80, v64, v28
	v_div_scale_f32 v80, s[8:9], v67, v67, v31
	v_rcp_f32_e32 v81, v80
	v_pk_mul_f32 v[64:65], v[64:65], s[18:19] op_sel_hi:[1,0]
	v_mul_f32_e32 v75, 0xbfb8aa3b, v35
	v_exp_f32_e32 v74, v74
	v_fma_f32 v82, -v80, v81, 1.0
	v_fmac_f32_e32 v81, v82, v81
	v_div_scale_f32 v82, vcc, v31, v67, v31
	v_mul_f32_e32 v83, v82, v81
	v_fma_f32 v88, -v80, v83, v82
	v_fmac_f32_e32 v83, v88, v81
	v_fma_f32 v80, -v80, v83, v82
	v_div_fmas_f32 v80, v80, v81, v83
	v_div_fixup_f32 v67, v80, v67, v31
	v_div_scale_f32 v80, s[8:9], v66, v66, v30
	v_rcp_f32_e32 v81, v80
	v_exp_f32_e32 v75, v75
	s_cmpk_gt_u32 s48, 0x79
	v_fma_f32 v82, -v80, v81, 1.0
	v_fmac_f32_e32 v81, v82, v81
	v_div_scale_f32 v82, vcc, v30, v66, v30
	v_mul_f32_e32 v83, v82, v81
	v_fma_f32 v88, -v80, v83, v82
	v_fmac_f32_e32 v83, v88, v81
	v_fma_f32 v80, -v80, v83, v82
	v_div_fmas_f32 v80, v80, v81, v83
	v_div_fixup_f32 v66, v80, v66, v30
	v_pk_mul_f32 v[66:67], v[66:67], s[18:19] op_sel_hi:[1,0]
	ds_write_b128 v141, v[64:67]
	v_pk_add_f32 v[64:65], v[72:73], 1.0 op_sel_hi:[1,0]
	v_div_scale_f32 v66, s[8:9], v65, v65, 1.0
	v_rcp_f32_e32 v67, v66
	s_nop 0
	v_fma_f32 v72, -v66, v67, 1.0
	v_fmac_f32_e32 v67, v72, v67
	v_div_scale_f32 v72, vcc, 1.0, v65, 1.0
	v_mul_f32_e32 v73, v72, v67
	v_fma_f32 v80, -v66, v73, v72
	v_fmac_f32_e32 v73, v80, v67
	v_fma_f32 v66, -v66, v73, v72
	v_div_fmas_f32 v66, v66, v67, v73
	v_div_fixup_f32 v65, v66, v65, 1.0
	v_div_scale_f32 v66, s[8:9], v64, v64, 1.0
	v_rcp_f32_e32 v67, v66
	s_nop 0
	v_fma_f32 v72, -v66, v67, 1.0
	v_fmac_f32_e32 v67, v72, v67
	v_div_scale_f32 v72, vcc, 1.0, v64, 1.0
	v_mul_f32_e32 v73, v72, v67
	v_fma_f32 v80, -v66, v73, v72
	v_fmac_f32_e32 v73, v80, v67
	v_fma_f32 v66, -v66, v73, v72
	v_div_fmas_f32 v66, v66, v67, v73
	v_div_fixup_f32 v64, v66, v64, 1.0
	v_pk_add_f32 v[66:67], v[74:75], 1.0 op_sel_hi:[1,0]
	v_pk_fma_f32 v[64:65], v[110:111], v[64:65], v[104:105]
	v_div_scale_f32 v72, s[8:9], v67, v67, 1.0
	v_rcp_f32_e32 v73, v72
	s_nop 0
	v_fma_f32 v74, -v72, v73, 1.0
	v_fmac_f32_e32 v73, v74, v73
	v_div_scale_f32 v74, vcc, 1.0, v67, 1.0
	v_mul_f32_e32 v75, v74, v73
	v_fma_f32 v80, -v72, v75, v74
	v_fmac_f32_e32 v75, v80, v73
	v_fma_f32 v72, -v72, v75, v74
	v_div_fmas_f32 v72, v72, v73, v75
	v_div_fixup_f32 v67, v72, v67, 1.0
	v_div_scale_f32 v72, s[8:9], v66, v66, 1.0
	v_rcp_f32_e32 v73, v72
	s_nop 0
	v_fma_f32 v74, -v72, v73, 1.0
	v_fmac_f32_e32 v73, v74, v73
	v_div_scale_f32 v74, vcc, 1.0, v66, 1.0
	v_mul_f32_e32 v75, v74, v73
	v_fma_f32 v80, -v72, v75, v74
	v_fmac_f32_e32 v75, v80, v73
	v_fma_f32 v72, -v72, v75, v74
	v_div_fmas_f32 v72, v72, v73, v75
	v_div_fixup_f32 v66, v72, v66, 1.0
	v_pk_fma_f32 v[66:67], v[112:113], v[66:67], v[106:107]
	ds_write_b128 v141, v[64:67] offset:8192
	ds_write_b32 v134, v131 offset:16384
	v_mul_f32_e32 v64, 0xbfb8aa3b, v40
	v_mul_f32_e32 v65, 0xbfb8aa3b, v41
	v_exp_f32_e32 v64, v64
	v_exp_f32_e32 v65, v65
	v_mul_f32_e32 v66, 0xbfb8aa3b, v42
	v_mul_f32_e32 v67, 0xbfb8aa3b, v43
	v_exp_f32_e32 v66, v66
	v_pk_add_f32 v[64:65], v[64:65], 1.0 op_sel_hi:[1,0]
	v_exp_f32_e32 v67, v67
	v_div_scale_f32 v80, s[8:9], v65, v65, v41
	v_rcp_f32_e32 v81, v80
	v_pk_add_f32 v[66:67], v[66:67], 1.0 op_sel_hi:[1,0]
	s_waitcnt vmcnt(7)
	v_mul_f32_e32 v72, 0xbfb8aa3b, v52
	v_mul_f32_e32 v73, 0xbfb8aa3b, v53
	v_fma_f32 v82, -v80, v81, 1.0
	v_fmac_f32_e32 v81, v82, v81
	v_div_scale_f32 v82, vcc, v41, v65, v41
	v_mul_f32_e32 v83, v82, v81
	v_fma_f32 v88, -v80, v83, v82
	v_fmac_f32_e32 v83, v88, v81
	v_fma_f32 v80, -v80, v83, v82
	v_div_fmas_f32 v80, v80, v81, v83
	v_div_fixup_f32 v65, v80, v65, v41
	v_div_scale_f32 v80, s[8:9], v64, v64, v40
	v_rcp_f32_e32 v81, v80
	v_exp_f32_e32 v72, v72
	v_exp_f32_e32 v73, v73
	v_mul_f32_e32 v74, 0xbfb8aa3b, v54
	v_fma_f32 v82, -v80, v81, 1.0
	v_fmac_f32_e32 v81, v82, v81
	v_div_scale_f32 v82, vcc, v40, v64, v40
	v_mul_f32_e32 v83, v82, v81
	v_fma_f32 v88, -v80, v83, v82
	v_fmac_f32_e32 v83, v88, v81
	v_fma_f32 v80, -v80, v83, v82
	v_div_fmas_f32 v80, v80, v81, v83
	v_div_fixup_f32 v64, v80, v64, v40
	v_div_scale_f32 v80, s[8:9], v67, v67, v43
	v_rcp_f32_e32 v81, v80
	v_pk_mul_f32 v[64:65], v[64:65], s[18:19] op_sel_hi:[1,0]
	v_mul_f32_e32 v75, 0xbfb8aa3b, v55
	v_exp_f32_e32 v74, v74
	v_fma_f32 v82, -v80, v81, 1.0
	v_fmac_f32_e32 v81, v82, v81
	v_div_scale_f32 v82, vcc, v43, v67, v43
	v_mul_f32_e32 v83, v82, v81
	v_fma_f32 v88, -v80, v83, v82
	v_fmac_f32_e32 v83, v88, v81
	v_fma_f32 v80, -v80, v83, v82
	v_div_fmas_f32 v80, v80, v81, v83
	v_div_fixup_f32 v67, v80, v67, v43
	v_div_scale_f32 v80, s[8:9], v66, v66, v42
	v_rcp_f32_e32 v81, v80
	v_exp_f32_e32 v75, v75
	v_fma_f32 v82, -v80, v81, 1.0
	v_fmac_f32_e32 v81, v82, v81
	v_div_scale_f32 v82, vcc, v42, v66, v42
	v_mul_f32_e32 v83, v82, v81
	v_fma_f32 v88, -v80, v83, v82
	v_fmac_f32_e32 v83, v88, v81
	v_fma_f32 v80, -v80, v83, v82
	v_div_fmas_f32 v80, v80, v81, v83
	v_div_fixup_f32 v66, v80, v66, v42
	v_pk_mul_f32 v[66:67], v[66:67], s[18:19] op_sel_hi:[1,0]
	ds_write_b128 v144, v[64:67]
	v_pk_add_f32 v[64:65], v[72:73], 1.0 op_sel_hi:[1,0]
	v_div_scale_f32 v66, s[8:9], v65, v65, 1.0
	v_rcp_f32_e32 v67, v66
	s_nop 0
	v_fma_f32 v72, -v66, v67, 1.0
	v_fmac_f32_e32 v67, v72, v67
	v_div_scale_f32 v72, vcc, 1.0, v65, 1.0
	v_mul_f32_e32 v73, v72, v67
	v_fma_f32 v80, -v66, v73, v72
	v_fmac_f32_e32 v73, v80, v67
	v_fma_f32 v66, -v66, v73, v72
	v_div_fmas_f32 v66, v66, v67, v73
	v_div_fixup_f32 v65, v66, v65, 1.0
	v_div_scale_f32 v66, s[8:9], v64, v64, 1.0
	v_rcp_f32_e32 v67, v66
	s_nop 0
	v_fma_f32 v72, -v66, v67, 1.0
	v_fmac_f32_e32 v67, v72, v67
	v_div_scale_f32 v72, vcc, 1.0, v64, 1.0
	v_mul_f32_e32 v73, v72, v67
	v_fma_f32 v80, -v66, v73, v72
	v_fmac_f32_e32 v73, v80, v67
	v_fma_f32 v66, -v66, v73, v72
	v_div_fmas_f32 v66, v66, v67, v73
	v_div_fixup_f32 v64, v66, v64, 1.0
	v_pk_add_f32 v[66:67], v[74:75], 1.0 op_sel_hi:[1,0]
	v_pk_fma_f32 v[64:65], v[110:111], v[64:65], v[104:105]
	v_div_scale_f32 v72, s[8:9], v67, v67, 1.0
	v_rcp_f32_e32 v73, v72
	s_nop 0
	v_fma_f32 v74, -v72, v73, 1.0
	v_fmac_f32_e32 v73, v74, v73
	v_div_scale_f32 v74, vcc, 1.0, v67, 1.0
	v_mul_f32_e32 v75, v74, v73
	v_fma_f32 v80, -v72, v75, v74
	v_fmac_f32_e32 v75, v80, v73
	v_fma_f32 v72, -v72, v75, v74
	v_div_fmas_f32 v72, v72, v73, v75
	v_div_fixup_f32 v67, v72, v67, 1.0
	v_div_scale_f32 v72, s[8:9], v66, v66, 1.0
	v_rcp_f32_e32 v73, v72
	s_nop 0
	v_fma_f32 v74, -v72, v73, 1.0
	v_fmac_f32_e32 v73, v74, v73
	v_div_scale_f32 v74, vcc, 1.0, v66, 1.0
	v_mul_f32_e32 v75, v74, v73
	v_fma_f32 v80, -v72, v75, v74
	v_fmac_f32_e32 v75, v80, v73
	v_fma_f32 v72, -v72, v75, v74
	v_div_fmas_f32 v72, v72, v73, v75
	v_div_fixup_f32 v66, v72, v66, 1.0
	v_pk_fma_f32 v[66:67], v[112:113], v[66:67], v[106:107]
	ds_write_b128 v144, v[64:67] offset:8192
	s_waitcnt vmcnt(6)
	ds_write_b32 v134, v132 offset:17408
	s_waitcnt lgkmcnt(0)
	s_barrier
	s_cbranch_scc1 .LBB0_1359
	v_add_u32_e32 v28, 0x60, v98
	v_mov_b64_e32 v[40:41], s[30:31]
	v_mad_i64_i32 v[28:29], s[8:9], v28, s25, v[40:41]
	s_lshl_b32 s94, s46, 2
	v_lshl_add_u64 v[42:43], v[28:29], 0, s[94:95]
	v_mov_b32_e32 v117, v140
	v_lshl_add_u64 v[28:29], v[42:43], 0, v[116:117]
	v_add_co_u32_e32 v30, vcc, 0x4000, v28
	s_lshl_b32 s8, s42, 2
	s_nop 0
	v_addc_co_u32_e32 v31, vcc, 0, v29, vcc
	s_mov_b32 s9, s95
	v_add_co_u32_e32 v32, vcc, 0x5000, v28
	v_lshl_add_u64 v[42:43], v[42:43], 0, s[8:9]
	v_mov_b32_e32 v115, v140
	v_add_u32_e32 v52, 0x60, v96
	v_addc_co_u32_e32 v33, vcc, 0, v29, vcc
	v_lshl_add_u64 v[42:43], v[42:43], 0, v[114:115]
	v_mad_i64_i32 v[40:41], s[22:23], v52, s25, v[40:41]
	v_add_co_u32_e32 v42, vcc, s81, v42
	v_lshl_add_u64 v[52:53], v[40:41], 0, s[94:95]
	s_nop 0
	v_addc_co_u32_e32 v43, vcc, 0, v43, vcc
	v_lshl_add_u64 v[54:55], v[52:53], 0, v[116:117]
	v_add_co_u32_e32 v40, vcc, s80, v54
	v_lshl_add_u64 v[52:53], v[52:53], 0, s[8:9]
	s_nop 0
	v_addc_co_u32_e32 v41, vcc, 0, v55, vcc
	v_add_co_u32_e32 v54, vcc, 0x5000, v54
	v_lshl_add_u64 v[52:53], v[52:53], 0, v[114:115]
	s_nop 0
	v_addc_co_u32_e32 v55, vcc, 0, v55, vcc
	v_add_co_u32_e32 v64, vcc, 0x6000, v52
	global_load_dwordx4 v[28:31], v[30:31], off offset:32
	s_nop 0
	global_load_dwordx4 v[32:35], v[32:33], off offset:32
	s_nop 0
	global_load_dword v131, v[42:43], off offset:32
	s_nop 0
	global_load_dwordx4 v[40:43], v[40:41], off offset:32
	v_addc_co_u32_e32 v65, vcc, 0, v53, vcc
	global_load_dwordx4 v[52:55], v[54:55], off offset:32
	s_nop 0
	global_load_dword v132, v[64:65], off offset:32
.LBB0_1359:
	ds_read2st64_b32 v[64:65], v134 offset0:152 offset1:156
	v_add_u32_e32 v66, 16, v98
	v_ashrrev_i32_e32 v67, 31, v66
	v_lshlrev_b64 v[66:67], 12, v[66:67]
	v_lshl_add_u64 v[66:67], v[108:109], 0, v[66:67]
	s_waitcnt lgkmcnt(0)
	global_store_dword v[66:67], v64, off
	v_add_u32_e32 v66, 16, v96
	v_ashrrev_i32_e32 v67, 31, v66
	v_lshlrev_b64 v[66:67], 12, v[66:67]
	v_lshl_add_u64 v[66:67], v[108:109], 0, v[66:67]
	global_store_dword v[66:67], v65, off
	ds_read_b128 v[186:189], v145
	ds_read_b128 v[190:193], v145 offset:256
	ds_read_b128 v[154:157], v145 offset:8192
	ds_read_b128 v[194:197], v145 offset:8448
	ds_read2_b32 v[120:121], v152 offset1:16
	ds_read_b128 v[72:75], v145 offset:512
	ds_read_b128 v[64:67], v145 offset:768
	ds_read_b128 v[88:91], v145 offset:8704
	ds_read_b128 v[80:83], v145 offset:8960
	ds_read2_b32 v[118:119], v152 offset0:32 offset1:48
	s_waitcnt lgkmcnt(5)
	v_sub_f32 v70, v70, v120
	v_sub_f32 v71, v71, v121
	v_sub_f32 v68, v68, v120
	v_sub_f32 v69, v69, v121
	v_sub_f32 v95, v95, v120
	v_sub_f32 v94, v94, v121
	v_sub_f32 v92, v92, v120
	v_sub_f32 v93, v93, v121
	v_sub_f32 v84, v84, v120
	v_sub_f32 v78, v78, v120
	v_sub_f32 v76, v76, v120
	v_sub_f32 v77, v77, v121
	v_fma_f32 v185, v154, v95, v120
	v_fma_f32 v184, v154, v94, v121
	v_fma_f32 v182, v155, v92, v120
	v_fma_f32 v183, v155, v93, v121
	v_fma_f32 v115, v196, v70, v120
	v_fma_f32 v117, v196, v71, v121
	v_fma_f32 v97, v197, v68, v120
	v_fma_f32 v99, v197, v69, v121
	v_fma_f32 v68, v186, v185, v140
	v_fma_f32 v69, v186, v184, v140
	v_fma_f32 v70, v187, v182, v140
	v_fma_f32 v71, v187, v183, v140
	v_sub_f32 v86, v86, v120
	v_sub_f32 v87, v87, v121
	v_sub_f32 v85, v85, v121
	v_sub_f32 v79, v79, v121
	v_fma_f32 v178, v157, v84, v120
	v_fma_f32 v154, v195, v76, v120
	v_fma_f32 v180, v156, v86, v120
	v_fma_f32 v181, v156, v87, v121
	v_fma_f32 v179, v157, v85, v121
	v_fma_f32 v156, v194, v78, v120
	v_fma_f32 v157, v194, v79, v121
	v_fma_f32 v155, v195, v77, v121
	v_fma_f32 v76, v188, v180, v140
	v_fma_f32 v77, v188, v181, v140
	v_fma_f32 v78, v189, v178, v140
	v_fma_f32 v68, v190, v156, v68
	v_fma_f32 v84, v190, v157, v69
	v_fma_f32 v69, v191, v154, v70
	v_fma_f32 v70, v191, v155, v71
	v_fma_f32 v71, v192, v115, v76
	v_fma_f32 v79, v189, v179, v140
	v_fma_f32 v76, v192, v117, v77
	v_fma_f32 v77, v193, v97, v78
	v_add_f32_e32 v68, v68, v69
	v_fma_f32 v78, v193, v99, v79
	v_add_f32_e32 v69, v71, v77
	v_add_f32_e32 v70, v84, v70
	v_add_f32_e32 v71, v76, v78
	v_add_f32_e32 v68, v68, v69
	v_add_f32_e32 v70, v70, v71
	s_nop 0
	v_add_f32_dpp v68, v68, v68 row_ror:8 row_mask:0xf bank_mask:0xf bound_ctrl:1
	v_add_f32_dpp v70, v70, v70 row_ror:8 row_mask:0xf bank_mask:0xf bound_ctrl:1
	s_nop 0
	v_add_f32_dpp v68, v68, v68 row_ror:4 row_mask:0xf bank_mask:0xf bound_ctrl:1
	v_add_f32_dpp v70, v70, v70 row_ror:4 row_mask:0xf bank_mask:0xf bound_ctrl:1
	s_nop 0
	v_add_f32_dpp v68, v68, v68 row_ror:2 row_mask:0xf bank_mask:0xf bound_ctrl:1
	v_add_f32_dpp v70, v70, v70 row_ror:2 row_mask:0xf bank_mask:0xf bound_ctrl:1
	s_nop 0
	v_add_f32_dpp v68, v68, v68 row_ror:1 row_mask:0xf bank_mask:0xf bound_ctrl:1
	v_add_f32_dpp v70, v70, v70 row_ror:1 row_mask:0xf bank_mask:0xf bound_ctrl:1
	ds_write2_b32 v146, v68, v70 offset1:16
	s_waitcnt lgkmcnt(0)
	v_sub_f32 v185, v185, v118
	v_sub_f32 v184, v184, v119
	v_sub_f32 v182, v182, v118
	v_sub_f32 v183, v183, v119
	v_sub_f32 v156, v156, v118
	v_sub_f32 v157, v157, v119
	v_sub_f32 v154, v154, v118
	v_sub_f32 v155, v155, v119
	v_sub_f32 v180, v180, v118
	v_sub_f32 v181, v181, v119
	v_sub_f32 v115, v115, v118
	v_sub_f32 v117, v117, v119
	v_fma_f32 v185, v88, v185, v118
	v_fma_f32 v184, v88, v184, v119
	v_fma_f32 v182, v89, v182, v118
	v_fma_f32 v183, v89, v183, v119
	v_fma_f32 v156, v80, v156, v118
	v_fma_f32 v157, v80, v157, v119
	v_fma_f32 v154, v81, v154, v118
	v_fma_f32 v155, v81, v155, v119
	v_fma_f32 v80, v72, v185, v140
	v_fma_f32 v72, v72, v184, v140
	v_fma_f32 v81, v73, v182, v140
	v_fma_f32 v73, v73, v183, v140
	ds_read_b128 v[76:79], v145 offset:1024
	ds_read_b128 v[68:71], v145 offset:1280
	ds_read_b128 v[92:95], v145 offset:9216
	ds_read_b128 v[84:87], v145 offset:9472
	ds_read2_b32 v[120:121], v152 offset0:64 offset1:80
	v_sub_f32 v178, v178, v118
	v_sub_f32 v179, v179, v119
	v_sub_f32 v97, v97, v118
	v_sub_f32 v99, v99, v119
	v_fma_f32 v180, v90, v180, v118
	v_fma_f32 v181, v90, v181, v119
	v_fma_f32 v115, v82, v115, v118
	v_fma_f32 v117, v82, v117, v119
	v_fma_f32 v80, v64, v156, v80
	v_fma_f32 v72, v64, v157, v72
	v_fma_f32 v82, v74, v180, v140
	v_fma_f32 v74, v74, v181, v140
	v_fma_f32 v64, v65, v154, v81
	v_fma_f32 v73, v65, v155, v73
	v_fma_f32 v178, v91, v178, v118
	v_fma_f32 v179, v91, v179, v119
	v_fma_f32 v65, v66, v115, v82
	v_fma_f32 v66, v66, v117, v74
	v_fma_f32 v97, v83, v97, v118
	v_fma_f32 v99, v83, v99, v119
	v_fma_f32 v83, v75, v178, v140
	v_fma_f32 v75, v75, v179, v140
	v_add_f32_e32 v64, v80, v64
	v_fma_f32 v74, v67, v97, v83
	v_fma_f32 v67, v67, v99, v75
	v_add_f32_e32 v72, v72, v73
	v_add_f32_e32 v65, v65, v74
	v_add_f32_e32 v66, v66, v67
	v_add_f32_e32 v64, v64, v65
	v_add_f32_e32 v66, v72, v66
	s_nop 0
	v_add_f32_dpp v64, v64, v64 row_ror:8 row_mask:0xf bank_mask:0xf bound_ctrl:1
	v_add_f32_dpp v66, v66, v66 row_ror:8 row_mask:0xf bank_mask:0xf bound_ctrl:1
	s_nop 0
	v_add_f32_dpp v64, v64, v64 row_ror:4 row_mask:0xf bank_mask:0xf bound_ctrl:1
	v_add_f32_dpp v66, v66, v66 row_ror:4 row_mask:0xf bank_mask:0xf bound_ctrl:1
	s_nop 0
	v_add_f32_dpp v64, v64, v64 row_ror:2 row_mask:0xf bank_mask:0xf bound_ctrl:1
	v_add_f32_dpp v66, v66, v66 row_ror:2 row_mask:0xf bank_mask:0xf bound_ctrl:1
	s_nop 0
	v_add_f32_dpp v64, v64, v64 row_ror:1 row_mask:0xf bank_mask:0xf bound_ctrl:1
	v_add_f32_dpp v66, v66, v66 row_ror:1 row_mask:0xf bank_mask:0xf bound_ctrl:1
	ds_write2_b32 v146, v64, v66 offset0:32 offset1:48
	s_waitcnt lgkmcnt(0)
	v_sub_f32 v185, v185, v120
	v_sub_f32 v184, v184, v121
	v_sub_f32 v182, v182, v120
	v_sub_f32 v183, v183, v121
	v_sub_f32 v156, v156, v120
	v_sub_f32 v157, v157, v121
	v_sub_f32 v154, v154, v120
	v_sub_f32 v155, v155, v121
	v_sub_f32 v180, v180, v120
	v_sub_f32 v181, v181, v121
	v_sub_f32 v115, v115, v120
	v_sub_f32 v117, v117, v121
	v_fma_f32 v185, v92, v185, v120
	v_fma_f32 v184, v92, v184, v121
	v_fma_f32 v182, v93, v182, v120
	v_fma_f32 v183, v93, v183, v121
	v_fma_f32 v156, v84, v156, v120
	v_fma_f32 v157, v84, v157, v121
	v_fma_f32 v154, v85, v154, v120
	v_fma_f32 v155, v85, v155, v121
	v_fma_f32 v84, v76, v185, v140
	v_fma_f32 v76, v76, v184, v140
	v_fma_f32 v85, v77, v182, v140
	v_fma_f32 v77, v77, v183, v140
	ds_read_b128 v[72:75], v145 offset:1536
	ds_read_b128 v[64:67], v145 offset:1792
	ds_read_b128 v[88:91], v145 offset:9728
	ds_read_b128 v[80:83], v145 offset:9984
	ds_read2_b32 v[118:119], v152 offset0:96 offset1:112
	v_sub_f32 v178, v178, v120
	v_sub_f32 v179, v179, v121
	v_sub_f32 v97, v97, v120
	v_sub_f32 v99, v99, v121
	v_fma_f32 v180, v94, v180, v120
	v_fma_f32 v181, v94, v181, v121
	v_fma_f32 v115, v86, v115, v120
	v_fma_f32 v117, v86, v117, v121
	v_fma_f32 v84, v68, v156, v84
	v_fma_f32 v76, v68, v157, v76
	v_fma_f32 v86, v78, v180, v140
	v_fma_f32 v78, v78, v181, v140
	v_fma_f32 v68, v69, v154, v85
	v_fma_f32 v77, v69, v155, v77
	v_fma_f32 v178, v95, v178, v120
	v_fma_f32 v179, v95, v179, v121
	v_fma_f32 v69, v70, v115, v86
	v_fma_f32 v70, v70, v117, v78
	v_fma_f32 v97, v87, v97, v120
	v_fma_f32 v99, v87, v99, v121
	v_fma_f32 v87, v79, v178, v140
	v_fma_f32 v79, v79, v179, v140
	v_add_f32_e32 v68, v84, v68
	v_fma_f32 v78, v71, v97, v87
	v_fma_f32 v71, v71, v99, v79
	v_add_f32_e32 v76, v76, v77
	v_add_f32_e32 v69, v69, v78
	v_add_f32_e32 v70, v70, v71
	v_add_f32_e32 v68, v68, v69
	v_add_f32_e32 v70, v76, v70
	s_nop 0
	v_add_f32_dpp v68, v68, v68 row_ror:8 row_mask:0xf bank_mask:0xf bound_ctrl:1
	v_add_f32_dpp v70, v70, v70 row_ror:8 row_mask:0xf bank_mask:0xf bound_ctrl:1
	s_nop 0
	v_add_f32_dpp v68, v68, v68 row_ror:4 row_mask:0xf bank_mask:0xf bound_ctrl:1
	v_add_f32_dpp v70, v70, v70 row_ror:4 row_mask:0xf bank_mask:0xf bound_ctrl:1
	s_nop 0
	v_add_f32_dpp v68, v68, v68 row_ror:2 row_mask:0xf bank_mask:0xf bound_ctrl:1
	v_add_f32_dpp v70, v70, v70 row_ror:2 row_mask:0xf bank_mask:0xf bound_ctrl:1
	s_nop 0
	v_add_f32_dpp v68, v68, v68 row_ror:1 row_mask:0xf bank_mask:0xf bound_ctrl:1
	v_add_f32_dpp v70, v70, v70 row_ror:1 row_mask:0xf bank_mask:0xf bound_ctrl:1
	ds_write2_b32 v146, v68, v70 offset0:64 offset1:80
	s_waitcnt lgkmcnt(0)
	v_sub_f32 v185, v185, v118
	v_sub_f32 v184, v184, v119
	v_sub_f32 v182, v182, v118
	v_sub_f32 v183, v183, v119
	v_sub_f32 v156, v156, v118
	v_sub_f32 v157, v157, v119
	v_sub_f32 v154, v154, v118
	v_sub_f32 v155, v155, v119
	v_sub_f32 v180, v180, v118
	v_sub_f32 v181, v181, v119
	v_sub_f32 v115, v115, v118
	v_sub_f32 v117, v117, v119
	v_fma_f32 v185, v88, v185, v118
	v_fma_f32 v184, v88, v184, v119
	v_fma_f32 v182, v89, v182, v118
	v_fma_f32 v183, v89, v183, v119
	v_fma_f32 v156, v80, v156, v118
	v_fma_f32 v157, v80, v157, v119
	v_fma_f32 v154, v81, v154, v118
	v_fma_f32 v155, v81, v155, v119
	v_fma_f32 v80, v72, v185, v140
	v_fma_f32 v72, v72, v184, v140
	v_fma_f32 v81, v73, v182, v140
	v_fma_f32 v73, v73, v183, v140
	ds_read_b128 v[76:79], v145 offset:2048
	ds_read_b128 v[68:71], v145 offset:2304
	ds_read_b128 v[92:95], v145 offset:10240
	ds_read_b128 v[84:87], v145 offset:10496
	ds_read2_b32 v[120:121], v152 offset0:128 offset1:144
	v_sub_f32 v178, v178, v118
	v_sub_f32 v179, v179, v119
	v_sub_f32 v97, v97, v118
	v_sub_f32 v99, v99, v119
	v_fma_f32 v180, v90, v180, v118
	v_fma_f32 v181, v90, v181, v119
	v_fma_f32 v115, v82, v115, v118
	v_fma_f32 v117, v82, v117, v119
	v_fma_f32 v80, v64, v156, v80
	v_fma_f32 v72, v64, v157, v72
	v_fma_f32 v82, v74, v180, v140
	v_fma_f32 v74, v74, v181, v140
	v_fma_f32 v64, v65, v154, v81
	v_fma_f32 v73, v65, v155, v73
	v_fma_f32 v178, v91, v178, v118
	v_fma_f32 v179, v91, v179, v119
	v_fma_f32 v65, v66, v115, v82
	v_fma_f32 v66, v66, v117, v74
	v_fma_f32 v97, v83, v97, v118
	v_fma_f32 v99, v83, v99, v119
	v_fma_f32 v83, v75, v178, v140
	v_fma_f32 v75, v75, v179, v140
	v_add_f32_e32 v64, v80, v64
	v_fma_f32 v74, v67, v97, v83
	v_fma_f32 v67, v67, v99, v75
	v_add_f32_e32 v72, v72, v73
	v_add_f32_e32 v65, v65, v74
	v_add_f32_e32 v66, v66, v67
	v_add_f32_e32 v64, v64, v65
	v_add_f32_e32 v66, v72, v66
	s_nop 0
	v_add_f32_dpp v64, v64, v64 row_ror:8 row_mask:0xf bank_mask:0xf bound_ctrl:1
	v_add_f32_dpp v66, v66, v66 row_ror:8 row_mask:0xf bank_mask:0xf bound_ctrl:1
	s_nop 0
	v_add_f32_dpp v64, v64, v64 row_ror:4 row_mask:0xf bank_mask:0xf bound_ctrl:1
	v_add_f32_dpp v66, v66, v66 row_ror:4 row_mask:0xf bank_mask:0xf bound_ctrl:1
	s_nop 0
	v_add_f32_dpp v64, v64, v64 row_ror:2 row_mask:0xf bank_mask:0xf bound_ctrl:1
	v_add_f32_dpp v66, v66, v66 row_ror:2 row_mask:0xf bank_mask:0xf bound_ctrl:1
	s_nop 0
	v_add_f32_dpp v64, v64, v64 row_ror:1 row_mask:0xf bank_mask:0xf bound_ctrl:1
	v_add_f32_dpp v66, v66, v66 row_ror:1 row_mask:0xf bank_mask:0xf bound_ctrl:1
	ds_write2_b32 v146, v64, v66 offset0:96 offset1:112
	s_waitcnt lgkmcnt(0)
	v_sub_f32 v185, v185, v120
	v_sub_f32 v184, v184, v121
	v_sub_f32 v182, v182, v120
	v_sub_f32 v183, v183, v121
	v_sub_f32 v156, v156, v120
	v_sub_f32 v157, v157, v121
	v_sub_f32 v154, v154, v120
	v_sub_f32 v155, v155, v121
	v_sub_f32 v180, v180, v120
	v_sub_f32 v181, v181, v121
	v_sub_f32 v115, v115, v120
	v_sub_f32 v117, v117, v121
	v_fma_f32 v185, v92, v185, v120
	v_fma_f32 v184, v92, v184, v121
	v_fma_f32 v182, v93, v182, v120
	v_fma_f32 v183, v93, v183, v121
	v_fma_f32 v156, v84, v156, v120
	v_fma_f32 v157, v84, v157, v121
	v_fma_f32 v154, v85, v154, v120
	v_fma_f32 v155, v85, v155, v121
	v_fma_f32 v84, v76, v185, v140
	v_fma_f32 v76, v76, v184, v140
	v_fma_f32 v85, v77, v182, v140
	v_fma_f32 v77, v77, v183, v140
	ds_read_b128 v[72:75], v145 offset:2560
	ds_read_b128 v[64:67], v145 offset:2816
	ds_read_b128 v[88:91], v145 offset:10752
	ds_read_b128 v[80:83], v145 offset:11008
	ds_read2_b32 v[118:119], v152 offset0:160 offset1:176
	v_sub_f32 v178, v178, v120
	v_sub_f32 v179, v179, v121
	v_sub_f32 v97, v97, v120
	v_sub_f32 v99, v99, v121
	v_fma_f32 v180, v94, v180, v120
	v_fma_f32 v181, v94, v181, v121
	v_fma_f32 v115, v86, v115, v120
	v_fma_f32 v117, v86, v117, v121
	v_fma_f32 v84, v68, v156, v84
	v_fma_f32 v76, v68, v157, v76
	v_fma_f32 v86, v78, v180, v140
	v_fma_f32 v78, v78, v181, v140
	v_fma_f32 v68, v69, v154, v85
	v_fma_f32 v77, v69, v155, v77
	v_fma_f32 v178, v95, v178, v120
	v_fma_f32 v179, v95, v179, v121
	v_fma_f32 v69, v70, v115, v86
	v_fma_f32 v70, v70, v117, v78
	v_fma_f32 v97, v87, v97, v120
	v_fma_f32 v99, v87, v99, v121
	v_fma_f32 v87, v79, v178, v140
	v_fma_f32 v79, v79, v179, v140
	v_add_f32_e32 v68, v84, v68
	v_fma_f32 v78, v71, v97, v87
	v_fma_f32 v71, v71, v99, v79
	v_add_f32_e32 v76, v76, v77
	v_add_f32_e32 v69, v69, v78
	v_add_f32_e32 v70, v70, v71
	v_add_f32_e32 v68, v68, v69
	v_add_f32_e32 v70, v76, v70
	s_nop 0
	v_add_f32_dpp v68, v68, v68 row_ror:8 row_mask:0xf bank_mask:0xf bound_ctrl:1
	v_add_f32_dpp v70, v70, v70 row_ror:8 row_mask:0xf bank_mask:0xf bound_ctrl:1
	s_nop 0
	v_add_f32_dpp v68, v68, v68 row_ror:4 row_mask:0xf bank_mask:0xf bound_ctrl:1
	v_add_f32_dpp v70, v70, v70 row_ror:4 row_mask:0xf bank_mask:0xf bound_ctrl:1
	s_nop 0
	v_add_f32_dpp v68, v68, v68 row_ror:2 row_mask:0xf bank_mask:0xf bound_ctrl:1
	v_add_f32_dpp v70, v70, v70 row_ror:2 row_mask:0xf bank_mask:0xf bound_ctrl:1
	s_nop 0
	v_add_f32_dpp v68, v68, v68 row_ror:1 row_mask:0xf bank_mask:0xf bound_ctrl:1
	v_add_f32_dpp v70, v70, v70 row_ror:1 row_mask:0xf bank_mask:0xf bound_ctrl:1
	ds_write2_b32 v146, v68, v70 offset0:128 offset1:144
	s_waitcnt lgkmcnt(0)
	v_sub_f32 v185, v185, v118
	v_sub_f32 v184, v184, v119
	v_sub_f32 v182, v182, v118
	v_sub_f32 v183, v183, v119
	v_sub_f32 v156, v156, v118
	v_sub_f32 v157, v157, v119
	v_sub_f32 v154, v154, v118
	v_sub_f32 v155, v155, v119
	v_sub_f32 v180, v180, v118
	v_sub_f32 v181, v181, v119
	v_sub_f32 v115, v115, v118
	v_sub_f32 v117, v117, v119
	v_fma_f32 v185, v88, v185, v118
	v_fma_f32 v184, v88, v184, v119
	v_fma_f32 v182, v89, v182, v118
	v_fma_f32 v183, v89, v183, v119
	v_fma_f32 v156, v80, v156, v118
	v_fma_f32 v157, v80, v157, v119
	v_fma_f32 v154, v81, v154, v118
	v_fma_f32 v155, v81, v155, v119
	v_fma_f32 v80, v72, v185, v140
	v_fma_f32 v72, v72, v184, v140
	v_fma_f32 v81, v73, v182, v140
	v_fma_f32 v73, v73, v183, v140
	ds_read_b128 v[76:79], v145 offset:3072
	ds_read_b128 v[68:71], v145 offset:3328
	ds_read_b128 v[92:95], v145 offset:11264
	ds_read_b128 v[84:87], v145 offset:11520
	ds_read2_b32 v[120:121], v152 offset0:192 offset1:208
	v_sub_f32 v178, v178, v118
	v_sub_f32 v179, v179, v119
	v_sub_f32 v97, v97, v118
	v_sub_f32 v99, v99, v119
	v_fma_f32 v180, v90, v180, v118
	v_fma_f32 v181, v90, v181, v119
	v_fma_f32 v115, v82, v115, v118
	v_fma_f32 v117, v82, v117, v119
	v_fma_f32 v80, v64, v156, v80
	v_fma_f32 v72, v64, v157, v72
	v_fma_f32 v82, v74, v180, v140
	v_fma_f32 v74, v74, v181, v140
	v_fma_f32 v64, v65, v154, v81
	v_fma_f32 v73, v65, v155, v73
	v_fma_f32 v178, v91, v178, v118
	v_fma_f32 v179, v91, v179, v119
	v_fma_f32 v65, v66, v115, v82
	v_fma_f32 v66, v66, v117, v74
	v_fma_f32 v97, v83, v97, v118
	v_fma_f32 v99, v83, v99, v119
	v_fma_f32 v83, v75, v178, v140
	v_fma_f32 v75, v75, v179, v140
	v_add_f32_e32 v64, v80, v64
	v_fma_f32 v74, v67, v97, v83
	v_fma_f32 v67, v67, v99, v75
	v_add_f32_e32 v72, v72, v73
	v_add_f32_e32 v65, v65, v74
	v_add_f32_e32 v66, v66, v67
	v_add_f32_e32 v64, v64, v65
	v_add_f32_e32 v66, v72, v66
	s_nop 0
	v_add_f32_dpp v64, v64, v64 row_ror:8 row_mask:0xf bank_mask:0xf bound_ctrl:1
	v_add_f32_dpp v66, v66, v66 row_ror:8 row_mask:0xf bank_mask:0xf bound_ctrl:1
	s_nop 0
	v_add_f32_dpp v64, v64, v64 row_ror:4 row_mask:0xf bank_mask:0xf bound_ctrl:1
	v_add_f32_dpp v66, v66, v66 row_ror:4 row_mask:0xf bank_mask:0xf bound_ctrl:1
	s_nop 0
	v_add_f32_dpp v64, v64, v64 row_ror:2 row_mask:0xf bank_mask:0xf bound_ctrl:1
	v_add_f32_dpp v66, v66, v66 row_ror:2 row_mask:0xf bank_mask:0xf bound_ctrl:1
	s_nop 0
	v_add_f32_dpp v64, v64, v64 row_ror:1 row_mask:0xf bank_mask:0xf bound_ctrl:1
	v_add_f32_dpp v66, v66, v66 row_ror:1 row_mask:0xf bank_mask:0xf bound_ctrl:1
	ds_write2_b32 v146, v64, v66 offset0:160 offset1:176
	ds_read_b128 v[72:75], v145 offset:3584
	ds_read_b128 v[64:67], v145 offset:3840
	ds_read_b128 v[88:91], v145 offset:11776
	ds_read_b128 v[80:83], v145 offset:12032
	ds_read2_b32 v[118:119], v152 offset0:224 offset1:240
	s_waitcnt lgkmcnt(5)
	v_sub_f32 v152, v185, v120
	v_sub_f32 v182, v182, v120
	v_sub_f32 v156, v156, v120
	v_sub_f32 v154, v154, v120
	v_sub_f32 v185, v184, v121
	v_sub_f32 v186, v183, v121
	v_sub_f32 v180, v180, v120
	v_sub_f32 v187, v181, v121
	v_sub_f32 v189, v157, v121
	v_sub_f32 v190, v155, v121
	v_sub_f32 v115, v115, v120
	v_sub_f32 v117, v117, v121
	v_fma_f32 v184, v92, v152, v120
	v_fma_f32 v183, v92, v185, v121
	v_fma_f32 v181, v93, v182, v120
	v_fma_f32 v182, v93, v186, v121
	v_fma_f32 v155, v84, v156, v120
	v_fma_f32 v156, v84, v189, v121
	v_fma_f32 v152, v85, v154, v120
	v_fma_f32 v154, v85, v190, v121
	v_fma_f32 v84, v76, v184, v140
	v_fma_f32 v76, v76, v183, v140
	v_fma_f32 v85, v77, v181, v140
	v_fma_f32 v77, v77, v182, v140
	v_sub_f32 v178, v178, v120
	v_sub_f32 v188, v179, v121
	v_sub_f32 v97, v97, v120
	v_sub_f32 v99, v99, v121
	v_fma_f32 v179, v94, v180, v120
	v_fma_f32 v180, v94, v187, v121
	v_fma_f32 v115, v86, v115, v120
	v_fma_f32 v117, v86, v117, v121
	v_fma_f32 v84, v68, v155, v84
	v_fma_f32 v76, v68, v156, v76
	v_fma_f32 v86, v78, v179, v140
	v_fma_f32 v78, v78, v180, v140
	v_fma_f32 v68, v69, v152, v85
	v_fma_f32 v77, v69, v154, v77
	v_fma_f32 v157, v95, v178, v120
	v_fma_f32 v178, v95, v188, v121
	v_fma_f32 v69, v70, v115, v86
	v_fma_f32 v70, v70, v117, v78
	v_fma_f32 v97, v87, v97, v120
	v_fma_f32 v99, v87, v99, v121
	v_fma_f32 v87, v79, v157, v140
	v_fma_f32 v79, v79, v178, v140
	v_add_f32_e32 v68, v84, v68
	v_fma_f32 v78, v71, v97, v87
	v_fma_f32 v71, v71, v99, v79
	v_add_f32_e32 v76, v76, v77
	v_add_f32_e32 v69, v69, v78
	v_add_f32_e32 v70, v70, v71
	v_add_f32_e32 v68, v68, v69
	v_add_f32_e32 v70, v76, v70
	s_nop 0
	v_add_f32_dpp v68, v68, v68 row_ror:8 row_mask:0xf bank_mask:0xf bound_ctrl:1
	v_add_f32_dpp v70, v70, v70 row_ror:8 row_mask:0xf bank_mask:0xf bound_ctrl:1
	s_nop 0
	v_add_f32_dpp v68, v68, v68 row_ror:4 row_mask:0xf bank_mask:0xf bound_ctrl:1
	v_add_f32_dpp v70, v70, v70 row_ror:4 row_mask:0xf bank_mask:0xf bound_ctrl:1
	s_nop 0
	v_add_f32_dpp v68, v68, v68 row_ror:2 row_mask:0xf bank_mask:0xf bound_ctrl:1
	v_add_f32_dpp v70, v70, v70 row_ror:2 row_mask:0xf bank_mask:0xf bound_ctrl:1
	s_nop 0
	v_add_f32_dpp v68, v68, v68 row_ror:1 row_mask:0xf bank_mask:0xf bound_ctrl:1
	v_add_f32_dpp v70, v70, v70 row_ror:1 row_mask:0xf bank_mask:0xf bound_ctrl:1
	ds_write2_b32 v146, v68, v70 offset0:192 offset1:208
	s_waitcnt lgkmcnt(0)
	v_sub_f32 v184, v184, v118
	v_sub_f32 v183, v183, v119
	v_sub_f32 v181, v181, v118
	v_sub_f32 v182, v182, v119
	v_sub_f32 v155, v155, v118
	v_sub_f32 v156, v156, v119
	v_sub_f32 v152, v152, v118
	v_sub_f32 v154, v154, v119
	v_sub_f32 v179, v179, v118
	v_sub_f32 v180, v180, v119
	v_sub_f32 v115, v115, v118
	v_sub_f32 v117, v117, v119
	v_fma_f32 v184, v88, v184, v118
	v_fma_f32 v183, v88, v183, v119
	v_fma_f32 v181, v89, v181, v118
	v_fma_f32 v182, v89, v182, v119
	v_fma_f32 v155, v80, v155, v118
	v_fma_f32 v156, v80, v156, v119
	v_fma_f32 v152, v81, v152, v118
	v_fma_f32 v154, v81, v154, v119
	v_fma_f32 v80, v72, v184, v140
	v_fma_f32 v72, v72, v183, v140
	v_fma_f32 v81, v73, v181, v140
	v_fma_f32 v73, v73, v182, v140
	ds_read_b128 v[76:79], v145 offset:4096
	ds_read_b128 v[68:71], v145 offset:4352
	ds_read_b128 v[92:95], v145 offset:12288
	ds_read_b128 v[84:87], v145 offset:12544
	ds_read2_b32 v[120:121], v148 offset1:16
	v_sub_f32 v157, v157, v118
	v_sub_f32 v178, v178, v119
	v_sub_f32 v97, v97, v118
	v_sub_f32 v99, v99, v119
	v_fma_f32 v179, v90, v179, v118
	v_fma_f32 v180, v90, v180, v119
	v_fma_f32 v115, v82, v115, v118
	v_fma_f32 v117, v82, v117, v119
	v_fma_f32 v80, v64, v155, v80
	v_fma_f32 v72, v64, v156, v72
	v_fma_f32 v82, v74, v179, v140
	v_fma_f32 v74, v74, v180, v140
	v_fma_f32 v64, v65, v152, v81
	v_fma_f32 v73, v65, v154, v73
	v_fma_f32 v157, v91, v157, v118
	v_fma_f32 v178, v91, v178, v119
	v_fma_f32 v65, v66, v115, v82
	v_fma_f32 v66, v66, v117, v74
	v_fma_f32 v97, v83, v97, v118
	v_fma_f32 v99, v83, v99, v119
	v_fma_f32 v83, v75, v157, v140
	v_fma_f32 v75, v75, v178, v140
	v_add_f32_e32 v64, v80, v64
	v_fma_f32 v74, v67, v97, v83
	v_fma_f32 v67, v67, v99, v75
	v_add_f32_e32 v72, v72, v73
	v_add_f32_e32 v65, v65, v74
	v_add_f32_e32 v66, v66, v67
	v_add_f32_e32 v64, v64, v65
	v_add_f32_e32 v66, v72, v66
	s_nop 0
	v_add_f32_dpp v64, v64, v64 row_ror:8 row_mask:0xf bank_mask:0xf bound_ctrl:1
	v_add_f32_dpp v66, v66, v66 row_ror:8 row_mask:0xf bank_mask:0xf bound_ctrl:1
	s_nop 0
	v_add_f32_dpp v64, v64, v64 row_ror:4 row_mask:0xf bank_mask:0xf bound_ctrl:1
	v_add_f32_dpp v66, v66, v66 row_ror:4 row_mask:0xf bank_mask:0xf bound_ctrl:1
	s_nop 0
	v_add_f32_dpp v64, v64, v64 row_ror:2 row_mask:0xf bank_mask:0xf bound_ctrl:1
	v_add_f32_dpp v66, v66, v66 row_ror:2 row_mask:0xf bank_mask:0xf bound_ctrl:1
	s_nop 0
	v_add_f32_dpp v64, v64, v64 row_ror:1 row_mask:0xf bank_mask:0xf bound_ctrl:1
	v_add_f32_dpp v66, v66, v66 row_ror:1 row_mask:0xf bank_mask:0xf bound_ctrl:1
	ds_write2_b32 v146, v64, v66 offset0:224 offset1:240
	s_waitcnt lgkmcnt(0)
	v_sub_f32 v146, v184, v120
	v_sub_f32 v181, v181, v120
	v_sub_f32 v155, v155, v120
	v_sub_f32 v152, v152, v120
	v_sub_f32 v184, v183, v121
	v_sub_f32 v185, v182, v121
	v_sub_f32 v179, v179, v120
	v_sub_f32 v186, v180, v121
	v_sub_f32 v188, v156, v121
	v_sub_f32 v189, v154, v121
	v_sub_f32 v115, v115, v120
	v_sub_f32 v117, v117, v121
	v_fma_f32 v183, v92, v146, v120
	v_fma_f32 v182, v92, v184, v121
	v_fma_f32 v180, v93, v181, v120
	v_fma_f32 v181, v93, v185, v121
	v_fma_f32 v154, v84, v155, v120
	v_fma_f32 v155, v84, v188, v121
	v_fma_f32 v146, v85, v152, v120
	v_fma_f32 v152, v85, v189, v121
	v_fma_f32 v84, v76, v183, v140
	v_fma_f32 v76, v76, v182, v140
	v_fma_f32 v85, v77, v180, v140
	v_fma_f32 v77, v77, v181, v140
	ds_read_b128 v[72:75], v145 offset:4608
	ds_read_b128 v[64:67], v145 offset:4864
	ds_read_b128 v[88:91], v145 offset:12800
	ds_read_b128 v[80:83], v145 offset:13056
	ds_read2_b32 v[118:119], v148 offset0:32 offset1:48
	v_sub_f32 v157, v157, v120
	v_sub_f32 v187, v178, v121
	v_sub_f32 v97, v97, v120
	v_sub_f32 v99, v99, v121
	v_fma_f32 v178, v94, v179, v120
	v_fma_f32 v179, v94, v186, v121
	v_fma_f32 v115, v86, v115, v120
	v_fma_f32 v117, v86, v117, v121
	v_fma_f32 v84, v68, v154, v84
	v_fma_f32 v76, v68, v155, v76
	v_fma_f32 v86, v78, v178, v140
	v_fma_f32 v78, v78, v179, v140
	v_fma_f32 v68, v69, v146, v85
	v_fma_f32 v77, v69, v152, v77
	v_fma_f32 v156, v95, v157, v120
	v_fma_f32 v157, v95, v187, v121
	v_fma_f32 v69, v70, v115, v86
	v_fma_f32 v70, v70, v117, v78
	v_fma_f32 v97, v87, v97, v120
	v_fma_f32 v99, v87, v99, v121
	v_fma_f32 v87, v79, v156, v140
	v_fma_f32 v79, v79, v157, v140
	v_add_f32_e32 v68, v84, v68
	v_fma_f32 v78, v71, v97, v87
	v_fma_f32 v71, v71, v99, v79
	v_add_f32_e32 v76, v76, v77
	v_add_f32_e32 v69, v69, v78
	v_add_f32_e32 v70, v70, v71
	v_add_f32_e32 v68, v68, v69
	v_add_f32_e32 v70, v76, v70
	s_nop 0
	v_add_f32_dpp v68, v68, v68 row_ror:8 row_mask:0xf bank_mask:0xf bound_ctrl:1
	v_add_f32_dpp v70, v70, v70 row_ror:8 row_mask:0xf bank_mask:0xf bound_ctrl:1
	s_nop 0
	v_add_f32_dpp v68, v68, v68 row_ror:4 row_mask:0xf bank_mask:0xf bound_ctrl:1
	v_add_f32_dpp v70, v70, v70 row_ror:4 row_mask:0xf bank_mask:0xf bound_ctrl:1
	s_nop 0
	v_add_f32_dpp v68, v68, v68 row_ror:2 row_mask:0xf bank_mask:0xf bound_ctrl:1
	v_add_f32_dpp v70, v70, v70 row_ror:2 row_mask:0xf bank_mask:0xf bound_ctrl:1
	s_nop 0
	v_add_f32_dpp v68, v68, v68 row_ror:1 row_mask:0xf bank_mask:0xf bound_ctrl:1
	v_add_f32_dpp v70, v70, v70 row_ror:1 row_mask:0xf bank_mask:0xf bound_ctrl:1
	ds_write2_b32 v147, v68, v70 offset1:16
	s_waitcnt lgkmcnt(0)
	v_sub_f32 v183, v183, v118
	v_sub_f32 v182, v182, v119
	v_sub_f32 v180, v180, v118
	v_sub_f32 v181, v181, v119
	v_sub_f32 v154, v154, v118
	v_sub_f32 v155, v155, v119
	v_sub_f32 v146, v146, v118
	v_sub_f32 v152, v152, v119
	v_sub_f32 v178, v178, v118
	v_sub_f32 v179, v179, v119
	v_sub_f32 v115, v115, v118
	v_sub_f32 v117, v117, v119
	v_fma_f32 v183, v88, v183, v118
	v_fma_f32 v182, v88, v182, v119
	v_fma_f32 v180, v89, v180, v118
	v_fma_f32 v181, v89, v181, v119
	v_fma_f32 v154, v80, v154, v118
	v_fma_f32 v155, v80, v155, v119
	v_fma_f32 v146, v81, v146, v118
	v_fma_f32 v152, v81, v152, v119
	v_fma_f32 v80, v72, v183, v140
	v_fma_f32 v72, v72, v182, v140
	v_fma_f32 v81, v73, v180, v140
	v_fma_f32 v73, v73, v181, v140
	ds_read_b128 v[76:79], v145 offset:5120
	ds_read_b128 v[68:71], v145 offset:5376
	ds_read_b128 v[92:95], v145 offset:13312
	ds_read_b128 v[84:87], v145 offset:13568
	ds_read2_b32 v[120:121], v148 offset0:64 offset1:80
	v_sub_f32 v156, v156, v118
	v_sub_f32 v157, v157, v119
	v_sub_f32 v97, v97, v118
	v_sub_f32 v99, v99, v119
	v_fma_f32 v178, v90, v178, v118
	v_fma_f32 v179, v90, v179, v119
	v_fma_f32 v115, v82, v115, v118
	v_fma_f32 v117, v82, v117, v119
	v_fma_f32 v80, v64, v154, v80
	v_fma_f32 v72, v64, v155, v72
	v_fma_f32 v82, v74, v178, v140
	v_fma_f32 v74, v74, v179, v140
	v_fma_f32 v64, v65, v146, v81
	v_fma_f32 v73, v65, v152, v73
	v_fma_f32 v156, v91, v156, v118
	v_fma_f32 v157, v91, v157, v119
	v_fma_f32 v65, v66, v115, v82
	v_fma_f32 v66, v66, v117, v74
	v_fma_f32 v97, v83, v97, v118
	v_fma_f32 v99, v83, v99, v119
	v_fma_f32 v83, v75, v156, v140
	v_fma_f32 v75, v75, v157, v140
	v_add_f32_e32 v64, v80, v64
	v_fma_f32 v74, v67, v97, v83
	v_fma_f32 v67, v67, v99, v75
	v_add_f32_e32 v72, v72, v73
	v_add_f32_e32 v65, v65, v74
	v_add_f32_e32 v66, v66, v67
	v_add_f32_e32 v64, v64, v65
	v_add_f32_e32 v66, v72, v66
	s_nop 0
	v_add_f32_dpp v64, v64, v64 row_ror:8 row_mask:0xf bank_mask:0xf bound_ctrl:1
	v_add_f32_dpp v66, v66, v66 row_ror:8 row_mask:0xf bank_mask:0xf bound_ctrl:1
	s_nop 0
	v_add_f32_dpp v64, v64, v64 row_ror:4 row_mask:0xf bank_mask:0xf bound_ctrl:1
	v_add_f32_dpp v66, v66, v66 row_ror:4 row_mask:0xf bank_mask:0xf bound_ctrl:1
	s_nop 0
	v_add_f32_dpp v64, v64, v64 row_ror:2 row_mask:0xf bank_mask:0xf bound_ctrl:1
	v_add_f32_dpp v66, v66, v66 row_ror:2 row_mask:0xf bank_mask:0xf bound_ctrl:1
	s_nop 0
	v_add_f32_dpp v64, v64, v64 row_ror:1 row_mask:0xf bank_mask:0xf bound_ctrl:1
	v_add_f32_dpp v66, v66, v66 row_ror:1 row_mask:0xf bank_mask:0xf bound_ctrl:1
	ds_write2_b32 v147, v64, v66 offset0:32 offset1:48
	s_waitcnt lgkmcnt(0)
	v_sub_f32 v183, v183, v120
	v_sub_f32 v182, v182, v121
	v_sub_f32 v180, v180, v120
	v_sub_f32 v181, v181, v121
	v_sub_f32 v154, v154, v120
	v_sub_f32 v155, v155, v121
	v_sub_f32 v146, v146, v120
	v_sub_f32 v152, v152, v121
	v_sub_f32 v178, v178, v120
	v_sub_f32 v179, v179, v121
	v_sub_f32 v115, v115, v120
	v_sub_f32 v117, v117, v121
	v_fma_f32 v183, v92, v183, v120
	v_fma_f32 v182, v92, v182, v121
	v_fma_f32 v180, v93, v180, v120
	v_fma_f32 v181, v93, v181, v121
	v_fma_f32 v154, v84, v154, v120
	v_fma_f32 v155, v84, v155, v121
	v_fma_f32 v146, v85, v146, v120
	v_fma_f32 v152, v85, v152, v121
	v_fma_f32 v84, v76, v183, v140
	v_fma_f32 v76, v76, v182, v140
	v_fma_f32 v85, v77, v180, v140
	v_fma_f32 v77, v77, v181, v140
	ds_read_b128 v[72:75], v145 offset:5632
	ds_read_b128 v[64:67], v145 offset:5888
	ds_read_b128 v[88:91], v145 offset:13824
	ds_read_b128 v[80:83], v145 offset:14080
	ds_read2_b32 v[118:119], v148 offset0:96 offset1:112
	v_sub_f32 v156, v156, v120
	v_sub_f32 v157, v157, v121
	v_sub_f32 v97, v97, v120
	v_sub_f32 v99, v99, v121
	v_fma_f32 v178, v94, v178, v120
	v_fma_f32 v179, v94, v179, v121
	v_fma_f32 v115, v86, v115, v120
	v_fma_f32 v117, v86, v117, v121
	v_fma_f32 v84, v68, v154, v84
	v_fma_f32 v76, v68, v155, v76
	v_fma_f32 v86, v78, v178, v140
	v_fma_f32 v78, v78, v179, v140
	v_fma_f32 v68, v69, v146, v85
	v_fma_f32 v77, v69, v152, v77
	v_fma_f32 v156, v95, v156, v120
	v_fma_f32 v157, v95, v157, v121
	v_fma_f32 v69, v70, v115, v86
	v_fma_f32 v70, v70, v117, v78
	v_fma_f32 v97, v87, v97, v120
	v_fma_f32 v99, v87, v99, v121
	v_fma_f32 v87, v79, v156, v140
	v_fma_f32 v79, v79, v157, v140
	v_add_f32_e32 v68, v84, v68
	v_fma_f32 v78, v71, v97, v87
	v_fma_f32 v71, v71, v99, v79
	v_add_f32_e32 v76, v76, v77
	v_add_f32_e32 v69, v69, v78
	v_add_f32_e32 v70, v70, v71
	v_add_f32_e32 v68, v68, v69
	v_add_f32_e32 v70, v76, v70
	s_nop 0
	v_add_f32_dpp v68, v68, v68 row_ror:8 row_mask:0xf bank_mask:0xf bound_ctrl:1
	v_add_f32_dpp v70, v70, v70 row_ror:8 row_mask:0xf bank_mask:0xf bound_ctrl:1
	s_nop 0
	v_add_f32_dpp v68, v68, v68 row_ror:4 row_mask:0xf bank_mask:0xf bound_ctrl:1
	v_add_f32_dpp v70, v70, v70 row_ror:4 row_mask:0xf bank_mask:0xf bound_ctrl:1
	s_nop 0
	v_add_f32_dpp v68, v68, v68 row_ror:2 row_mask:0xf bank_mask:0xf bound_ctrl:1
	v_add_f32_dpp v70, v70, v70 row_ror:2 row_mask:0xf bank_mask:0xf bound_ctrl:1
	s_nop 0
	v_add_f32_dpp v68, v68, v68 row_ror:1 row_mask:0xf bank_mask:0xf bound_ctrl:1
	v_add_f32_dpp v70, v70, v70 row_ror:1 row_mask:0xf bank_mask:0xf bound_ctrl:1
	ds_write2_b32 v147, v68, v70 offset0:64 offset1:80
	s_waitcnt lgkmcnt(0)
	v_sub_f32 v183, v183, v118
	v_sub_f32 v182, v182, v119
	v_sub_f32 v180, v180, v118
	v_sub_f32 v181, v181, v119
	v_sub_f32 v154, v154, v118
	v_sub_f32 v155, v155, v119
	v_sub_f32 v146, v146, v118
	v_sub_f32 v152, v152, v119
	v_sub_f32 v178, v178, v118
	v_sub_f32 v179, v179, v119
	v_sub_f32 v115, v115, v118
	v_sub_f32 v117, v117, v119
	v_fma_f32 v183, v88, v183, v118
	v_fma_f32 v182, v88, v182, v119
	v_fma_f32 v180, v89, v180, v118
	v_fma_f32 v181, v89, v181, v119
	v_fma_f32 v154, v80, v154, v118
	v_fma_f32 v155, v80, v155, v119
	v_fma_f32 v146, v81, v146, v118
	v_fma_f32 v152, v81, v152, v119
	v_fma_f32 v80, v72, v183, v140
	v_fma_f32 v72, v72, v182, v140
	v_fma_f32 v81, v73, v180, v140
	v_fma_f32 v73, v73, v181, v140
	ds_read_b128 v[76:79], v145 offset:6144
	ds_read_b128 v[68:71], v145 offset:6400
	ds_read_b128 v[92:95], v145 offset:14336
	ds_read_b128 v[84:87], v145 offset:14592
	ds_read2_b32 v[120:121], v148 offset0:128 offset1:144
	v_sub_f32 v156, v156, v118
	v_sub_f32 v157, v157, v119
	v_sub_f32 v97, v97, v118
	v_sub_f32 v99, v99, v119
	v_fma_f32 v178, v90, v178, v118
	v_fma_f32 v179, v90, v179, v119
	v_fma_f32 v115, v82, v115, v118
	v_fma_f32 v117, v82, v117, v119
	v_fma_f32 v80, v64, v154, v80
	v_fma_f32 v72, v64, v155, v72
	v_fma_f32 v82, v74, v178, v140
	v_fma_f32 v74, v74, v179, v140
	v_fma_f32 v64, v65, v146, v81
	v_fma_f32 v73, v65, v152, v73
	v_fma_f32 v156, v91, v156, v118
	v_fma_f32 v157, v91, v157, v119
	v_fma_f32 v65, v66, v115, v82
	v_fma_f32 v66, v66, v117, v74
	v_fma_f32 v97, v83, v97, v118
	v_fma_f32 v99, v83, v99, v119
	v_fma_f32 v83, v75, v156, v140
	v_fma_f32 v75, v75, v157, v140
	v_add_f32_e32 v64, v80, v64
	v_fma_f32 v74, v67, v97, v83
	v_fma_f32 v67, v67, v99, v75
	v_add_f32_e32 v72, v72, v73
	v_add_f32_e32 v65, v65, v74
	v_add_f32_e32 v66, v66, v67
	v_add_f32_e32 v64, v64, v65
	v_add_f32_e32 v66, v72, v66
	s_nop 0
	v_add_f32_dpp v64, v64, v64 row_ror:8 row_mask:0xf bank_mask:0xf bound_ctrl:1
	v_add_f32_dpp v66, v66, v66 row_ror:8 row_mask:0xf bank_mask:0xf bound_ctrl:1
	s_nop 0
	v_add_f32_dpp v64, v64, v64 row_ror:4 row_mask:0xf bank_mask:0xf bound_ctrl:1
	v_add_f32_dpp v66, v66, v66 row_ror:4 row_mask:0xf bank_mask:0xf bound_ctrl:1
	s_nop 0
	v_add_f32_dpp v64, v64, v64 row_ror:2 row_mask:0xf bank_mask:0xf bound_ctrl:1
	v_add_f32_dpp v66, v66, v66 row_ror:2 row_mask:0xf bank_mask:0xf bound_ctrl:1
	s_nop 0
	v_add_f32_dpp v64, v64, v64 row_ror:1 row_mask:0xf bank_mask:0xf bound_ctrl:1
	v_add_f32_dpp v66, v66, v66 row_ror:1 row_mask:0xf bank_mask:0xf bound_ctrl:1
	ds_write2_b32 v147, v64, v66 offset0:96 offset1:112
	s_waitcnt lgkmcnt(0)
	v_sub_f32 v183, v183, v120
	v_sub_f32 v182, v182, v121
	v_sub_f32 v180, v180, v120
	v_sub_f32 v181, v181, v121
	v_sub_f32 v154, v154, v120
	v_sub_f32 v155, v155, v121
	v_sub_f32 v146, v146, v120
	v_sub_f32 v152, v152, v121
	v_sub_f32 v178, v178, v120
	v_sub_f32 v179, v179, v121
	v_sub_f32 v115, v115, v120
	v_sub_f32 v117, v117, v121
	v_fma_f32 v183, v92, v183, v120
	v_fma_f32 v182, v92, v182, v121
	v_fma_f32 v180, v93, v180, v120
	v_fma_f32 v181, v93, v181, v121
	v_fma_f32 v154, v84, v154, v120
	v_fma_f32 v155, v84, v155, v121
	v_fma_f32 v146, v85, v146, v120
	v_fma_f32 v152, v85, v152, v121
	v_fma_f32 v84, v76, v183, v140
	v_fma_f32 v76, v76, v182, v140
	v_fma_f32 v85, v77, v180, v140
	v_fma_f32 v77, v77, v181, v140
	ds_read_b128 v[72:75], v145 offset:6656
	ds_read_b128 v[64:67], v145 offset:6912
	ds_read_b128 v[88:91], v145 offset:14848
	ds_read_b128 v[80:83], v145 offset:15104
	ds_read2_b32 v[118:119], v148 offset0:160 offset1:176
	v_sub_f32 v156, v156, v120
	v_sub_f32 v157, v157, v121
	v_sub_f32 v97, v97, v120
	v_sub_f32 v99, v99, v121
	v_fma_f32 v178, v94, v178, v120
	v_fma_f32 v179, v94, v179, v121
	v_fma_f32 v115, v86, v115, v120
	v_fma_f32 v117, v86, v117, v121
	v_fma_f32 v84, v68, v154, v84
	v_fma_f32 v76, v68, v155, v76
	v_fma_f32 v86, v78, v178, v140
	v_fma_f32 v78, v78, v179, v140
	v_fma_f32 v68, v69, v146, v85
	v_fma_f32 v77, v69, v152, v77
	v_fma_f32 v156, v95, v156, v120
	v_fma_f32 v157, v95, v157, v121
	v_fma_f32 v69, v70, v115, v86
	v_fma_f32 v70, v70, v117, v78
	v_fma_f32 v97, v87, v97, v120
	v_fma_f32 v99, v87, v99, v121
	v_fma_f32 v87, v79, v156, v140
	v_fma_f32 v79, v79, v157, v140
	v_add_f32_e32 v68, v84, v68
	v_fma_f32 v78, v71, v97, v87
	v_fma_f32 v71, v71, v99, v79
	v_add_f32_e32 v76, v76, v77
	v_add_f32_e32 v69, v69, v78
	v_add_f32_e32 v70, v70, v71
	v_add_f32_e32 v68, v68, v69
	v_add_f32_e32 v70, v76, v70
	s_nop 0
	v_add_f32_dpp v68, v68, v68 row_ror:8 row_mask:0xf bank_mask:0xf bound_ctrl:1
	v_add_f32_dpp v70, v70, v70 row_ror:8 row_mask:0xf bank_mask:0xf bound_ctrl:1
	s_nop 0
	v_add_f32_dpp v68, v68, v68 row_ror:4 row_mask:0xf bank_mask:0xf bound_ctrl:1
	v_add_f32_dpp v70, v70, v70 row_ror:4 row_mask:0xf bank_mask:0xf bound_ctrl:1
	s_nop 0
	v_add_f32_dpp v68, v68, v68 row_ror:2 row_mask:0xf bank_mask:0xf bound_ctrl:1
	v_add_f32_dpp v70, v70, v70 row_ror:2 row_mask:0xf bank_mask:0xf bound_ctrl:1
	s_nop 0
	v_add_f32_dpp v68, v68, v68 row_ror:1 row_mask:0xf bank_mask:0xf bound_ctrl:1
	v_add_f32_dpp v70, v70, v70 row_ror:1 row_mask:0xf bank_mask:0xf bound_ctrl:1
	ds_write2_b32 v147, v68, v70 offset0:128 offset1:144
	s_waitcnt lgkmcnt(0)
	v_sub_f32 v183, v183, v118
	v_sub_f32 v182, v182, v119
	v_sub_f32 v180, v180, v118
	v_sub_f32 v181, v181, v119
	v_sub_f32 v154, v154, v118
	v_sub_f32 v155, v155, v119
	v_sub_f32 v146, v146, v118
	v_sub_f32 v152, v152, v119
	v_sub_f32 v178, v178, v118
	v_sub_f32 v179, v179, v119
	v_sub_f32 v115, v115, v118
	v_sub_f32 v117, v117, v119
	v_fma_f32 v183, v88, v183, v118
	v_fma_f32 v182, v88, v182, v119
	v_fma_f32 v180, v89, v180, v118
	v_fma_f32 v181, v89, v181, v119
	v_fma_f32 v154, v80, v154, v118
	v_fma_f32 v155, v80, v155, v119
	v_fma_f32 v146, v81, v146, v118
	v_fma_f32 v152, v81, v152, v119
	v_fma_f32 v80, v72, v183, v140
	v_fma_f32 v72, v72, v182, v140
	v_fma_f32 v81, v73, v180, v140
	v_fma_f32 v73, v73, v181, v140
	ds_read_b128 v[76:79], v145 offset:7168
	ds_read_b128 v[68:71], v145 offset:7424
	ds_read_b128 v[92:95], v145 offset:15360
	ds_read_b128 v[84:87], v145 offset:15616
	ds_read2_b32 v[120:121], v148 offset0:192 offset1:208
	v_sub_f32 v156, v156, v118
	v_sub_f32 v157, v157, v119
	v_sub_f32 v97, v97, v118
	v_sub_f32 v99, v99, v119
	v_fma_f32 v178, v90, v178, v118
	v_fma_f32 v179, v90, v179, v119
	v_fma_f32 v115, v82, v115, v118
	v_fma_f32 v117, v82, v117, v119
	v_fma_f32 v80, v64, v154, v80
	v_fma_f32 v72, v64, v155, v72
	v_fma_f32 v82, v74, v178, v140
	v_fma_f32 v74, v74, v179, v140
	v_fma_f32 v64, v65, v146, v81
	v_fma_f32 v73, v65, v152, v73
	v_fma_f32 v156, v91, v156, v118
	v_fma_f32 v157, v91, v157, v119
	v_fma_f32 v65, v66, v115, v82
	v_fma_f32 v66, v66, v117, v74
	v_fma_f32 v97, v83, v97, v118
	v_fma_f32 v99, v83, v99, v119
	v_fma_f32 v83, v75, v156, v140
	v_fma_f32 v75, v75, v157, v140
	v_add_f32_e32 v64, v80, v64
	v_fma_f32 v74, v67, v97, v83
	v_fma_f32 v67, v67, v99, v75
	v_add_f32_e32 v72, v72, v73
	v_add_f32_e32 v65, v65, v74
	v_add_f32_e32 v66, v66, v67
	v_add_f32_e32 v64, v64, v65
	v_add_f32_e32 v66, v72, v66
	s_nop 0
	v_add_f32_dpp v64, v64, v64 row_ror:8 row_mask:0xf bank_mask:0xf bound_ctrl:1
	v_add_f32_dpp v66, v66, v66 row_ror:8 row_mask:0xf bank_mask:0xf bound_ctrl:1
	s_nop 0
	v_add_f32_dpp v64, v64, v64 row_ror:4 row_mask:0xf bank_mask:0xf bound_ctrl:1
	v_add_f32_dpp v66, v66, v66 row_ror:4 row_mask:0xf bank_mask:0xf bound_ctrl:1
	s_nop 0
	v_add_f32_dpp v64, v64, v64 row_ror:2 row_mask:0xf bank_mask:0xf bound_ctrl:1
	v_add_f32_dpp v66, v66, v66 row_ror:2 row_mask:0xf bank_mask:0xf bound_ctrl:1
	s_nop 0
	v_add_f32_dpp v64, v64, v64 row_ror:1 row_mask:0xf bank_mask:0xf bound_ctrl:1
	v_add_f32_dpp v66, v66, v66 row_ror:1 row_mask:0xf bank_mask:0xf bound_ctrl:1
	ds_write2_b32 v147, v64, v66 offset0:160 offset1:176
	ds_read_b128 v[72:75], v145 offset:7680
	ds_read_b128 v[64:67], v145 offset:7936
	ds_read_b128 v[88:91], v145 offset:15872
	ds_read_b128 v[80:83], v145 offset:16128
	ds_read2_b32 v[118:119], v148 offset0:224 offset1:240
	s_waitcnt lgkmcnt(5)
	v_sub_f32 v148, v183, v120
	v_sub_f32 v182, v182, v121
	v_sub_f32 v180, v180, v120
	v_sub_f32 v181, v181, v121
	v_sub_f32 v178, v178, v120
	v_sub_f32 v179, v179, v121
	v_sub_f32 v156, v156, v120
	v_sub_f32 v157, v157, v121
	v_sub_f32 v183, v154, v120
	v_sub_f32 v184, v155, v121
	v_sub_f32 v185, v146, v120
	v_sub_f32 v186, v152, v121
	v_sub_f32 v187, v115, v120
	v_sub_f32 v188, v117, v121
	v_sub_f32 v189, v97, v120
	v_sub_f32 v190, v99, v121
	v_fma_f32 v155, v92, v148, v120
	v_fma_f32 v154, v92, v182, v121
	v_fma_f32 v148, v93, v180, v120
	v_fma_f32 v152, v93, v181, v121
	v_fma_f32 v117, v94, v178, v120
	v_fma_f32 v146, v94, v179, v121
	v_fma_f32 v99, v95, v156, v120
	v_fma_f32 v115, v95, v157, v121
	v_fma_f32 v95, v84, v183, v120
	v_fma_f32 v97, v84, v184, v121
	v_fma_f32 v93, v85, v185, v120
	v_fma_f32 v94, v85, v186, v121
	v_fma_f32 v92, v86, v187, v120
	v_fma_f32 v84, v87, v189, v120
	v_fma_f32 v85, v87, v190, v121
	v_fma_f32 v87, v76, v155, v140
	v_fma_f32 v76, v76, v154, v140
	v_fma_f32 v120, v77, v148, v140
	v_fma_f32 v77, v77, v152, v140
	v_fma_f32 v86, v86, v188, v121
	v_fma_f32 v121, v78, v117, v140
	v_fma_f32 v78, v78, v146, v140
	v_fma_f32 v87, v68, v95, v87
	v_fma_f32 v76, v68, v97, v76
	v_fma_f32 v68, v69, v93, v120
	v_fma_f32 v77, v69, v94, v77
	v_fma_f32 v69, v70, v92, v121
	v_fma_f32 v70, v70, v86, v78
	v_fma_f32 v156, v79, v99, v140
	v_fma_f32 v79, v79, v115, v140
	v_add_f32_e32 v68, v87, v68
	v_fma_f32 v78, v71, v84, v156
	v_fma_f32 v71, v71, v85, v79
	v_add_f32_e32 v76, v76, v77
	v_add_f32_e32 v69, v69, v78
	v_add_f32_e32 v70, v70, v71
	v_add_f32_e32 v68, v68, v69
	v_add_f32_e32 v70, v76, v70
	s_nop 0
	v_add_f32_dpp v68, v68, v68 row_ror:8 row_mask:0xf bank_mask:0xf bound_ctrl:1
	v_add_f32_dpp v70, v70, v70 row_ror:8 row_mask:0xf bank_mask:0xf bound_ctrl:1
	s_nop 0
	v_add_f32_dpp v68, v68, v68 row_ror:4 row_mask:0xf bank_mask:0xf bound_ctrl:1
	v_add_f32_dpp v70, v70, v70 row_ror:4 row_mask:0xf bank_mask:0xf bound_ctrl:1
	s_nop 0
	v_add_f32_dpp v68, v68, v68 row_ror:2 row_mask:0xf bank_mask:0xf bound_ctrl:1
	v_add_f32_dpp v70, v70, v70 row_ror:2 row_mask:0xf bank_mask:0xf bound_ctrl:1
	s_nop 0
	v_add_f32_dpp v68, v68, v68 row_ror:1 row_mask:0xf bank_mask:0xf bound_ctrl:1
	v_add_f32_dpp v70, v70, v70 row_ror:1 row_mask:0xf bank_mask:0xf bound_ctrl:1
	ds_write2_b32 v147, v68, v70 offset0:192 offset1:208
	s_waitcnt lgkmcnt(0)
	v_sub_f32 v76, v117, v118
	v_sub_f32 v77, v146, v119
	v_sub_f32 v78, v99, v118
	v_sub_f32 v79, v115, v119
	v_sub_f32 v68, v155, v118
	v_sub_f32 v69, v154, v119
	v_sub_f32 v70, v148, v118
	v_sub_f32 v71, v152, v119
	v_sub_f32 v99, v95, v118
	v_sub_f32 v97, v97, v119
	v_sub_f32 v115, v93, v118
	v_sub_f32 v117, v94, v119
	v_sub_f32 v120, v92, v118
	v_sub_f32 v121, v86, v119
	v_sub_f32 v146, v84, v118
	v_sub_f32 v148, v85, v119
	v_fma_f32 v95, v88, v68, v118
	v_fma_f32 v94, v88, v69, v119
	v_fma_f32 v92, v89, v70, v118
	v_fma_f32 v93, v89, v71, v119
	v_fma_f32 v86, v90, v76, v118
	v_fma_f32 v87, v90, v77, v119
	v_fma_f32 v84, v91, v78, v118
	v_fma_f32 v85, v91, v79, v119
	v_fma_f32 v78, v80, v99, v118
	v_fma_f32 v79, v80, v97, v119
	v_fma_f32 v76, v81, v115, v118
	v_fma_f32 v77, v81, v117, v119
	v_fma_f32 v80, v72, v95, v140
	v_fma_f32 v72, v72, v94, v140
	v_fma_f32 v81, v73, v92, v140
	v_fma_f32 v73, v73, v93, v140
	v_fma_f32 v70, v82, v120, v118
	v_fma_f32 v71, v82, v121, v119
	v_fma_f32 v82, v74, v86, v140
	v_fma_f32 v74, v74, v87, v140
	v_fma_f32 v80, v64, v78, v80
	v_fma_f32 v72, v64, v79, v72
	v_fma_f32 v64, v65, v76, v81
	v_fma_f32 v73, v65, v77, v73
	v_fma_f32 v65, v66, v70, v82
	v_fma_f32 v66, v66, v71, v74
	v_fma_f32 v68, v83, v146, v118
	v_fma_f32 v69, v83, v148, v119
	v_fma_f32 v83, v75, v84, v140
	v_fma_f32 v75, v75, v85, v140
	v_add_f32_e32 v64, v80, v64
	v_fma_f32 v74, v67, v68, v83
	v_fma_f32 v67, v67, v69, v75
	v_add_f32_e32 v72, v72, v73
	v_add_f32_e32 v65, v65, v74
	v_add_f32_e32 v66, v66, v67
	v_add_f32_e32 v64, v64, v65
	v_add_f32_e32 v66, v72, v66
	s_nop 0
	v_add_f32_dpp v64, v64, v64 row_ror:8 row_mask:0xf bank_mask:0xf bound_ctrl:1
	v_add_f32_dpp v66, v66, v66 row_ror:8 row_mask:0xf bank_mask:0xf bound_ctrl:1
	s_nop 0
	v_add_f32_dpp v64, v64, v64 row_ror:4 row_mask:0xf bank_mask:0xf bound_ctrl:1
	v_add_f32_dpp v66, v66, v66 row_ror:4 row_mask:0xf bank_mask:0xf bound_ctrl:1
	s_nop 0
	v_add_f32_dpp v64, v64, v64 row_ror:2 row_mask:0xf bank_mask:0xf bound_ctrl:1
	v_add_f32_dpp v66, v66, v66 row_ror:2 row_mask:0xf bank_mask:0xf bound_ctrl:1
	s_nop 0
	v_add_f32_dpp v64, v64, v64 row_ror:1 row_mask:0xf bank_mask:0xf bound_ctrl:1
	v_add_f32_dpp v66, v66, v66 row_ror:1 row_mask:0xf bank_mask:0xf bound_ctrl:1
	ds_write2_b32 v147, v64, v66 offset0:224 offset1:240
	s_waitcnt vmcnt(5)
	v_mul_f32_e32 v64, 0xbfb8aa3b, v44
	v_mul_f32_e32 v65, 0xbfb8aa3b, v45
	v_exp_f32_e32 v64, v64
	v_exp_f32_e32 v65, v65
	v_mul_f32_e32 v66, 0xbfb8aa3b, v46
	v_mul_f32_e32 v67, 0xbfb8aa3b, v47
	v_exp_f32_e32 v66, v66
	v_pk_add_f32 v[64:65], v[64:65], 1.0 op_sel_hi:[1,0]
	v_exp_f32_e32 v67, v67
	v_div_scale_f32 v80, s[8:9], v65, v65, v45
	v_rcp_f32_e32 v81, v80
	v_pk_add_f32 v[66:67], v[66:67], 1.0 op_sel_hi:[1,0]
	v_mul_f32_e32 v72, 0xbfb8aa3b, v48
	v_mul_f32_e32 v73, 0xbfb8aa3b, v49
	v_fma_f32 v82, -v80, v81, 1.0
	v_fmac_f32_e32 v81, v82, v81
	v_div_scale_f32 v82, vcc, v45, v65, v45
	v_mul_f32_e32 v83, v82, v81
	v_fma_f32 v88, -v80, v83, v82
	v_fmac_f32_e32 v83, v88, v81
	v_fma_f32 v80, -v80, v83, v82
	v_div_fmas_f32 v80, v80, v81, v83
	v_div_fixup_f32 v65, v80, v65, v45
	v_div_scale_f32 v80, s[8:9], v64, v64, v44
	v_rcp_f32_e32 v81, v80
	v_exp_f32_e32 v72, v72
	v_exp_f32_e32 v73, v73
	v_mul_f32_e32 v74, 0xbfb8aa3b, v50
	v_fma_f32 v82, -v80, v81, 1.0
	v_fmac_f32_e32 v81, v82, v81
	v_div_scale_f32 v82, vcc, v44, v64, v44
	v_mul_f32_e32 v83, v82, v81
	v_fma_f32 v88, -v80, v83, v82
	v_fmac_f32_e32 v83, v88, v81
	v_fma_f32 v80, -v80, v83, v82
	v_div_fmas_f32 v80, v80, v81, v83
	v_div_fixup_f32 v64, v80, v64, v44
	v_div_scale_f32 v80, s[8:9], v67, v67, v47
	v_rcp_f32_e32 v81, v80
	v_pk_mul_f32 v[64:65], v[64:65], s[18:19] op_sel_hi:[1,0]
	v_mul_f32_e32 v75, 0xbfb8aa3b, v51
	v_exp_f32_e32 v74, v74
	v_fma_f32 v82, -v80, v81, 1.0
	v_fmac_f32_e32 v81, v82, v81
	v_div_scale_f32 v82, vcc, v47, v67, v47
	v_mul_f32_e32 v83, v82, v81
	v_fma_f32 v88, -v80, v83, v82
	v_fmac_f32_e32 v83, v88, v81
	v_fma_f32 v80, -v80, v83, v82
	v_div_fmas_f32 v80, v80, v81, v83
	v_div_fixup_f32 v67, v80, v67, v47
	v_div_scale_f32 v80, s[8:9], v66, v66, v46
	v_rcp_f32_e32 v81, v80
	v_exp_f32_e32 v75, v75
	s_cmpk_gt_u32 s48, 0x78
	v_fma_f32 v82, -v80, v81, 1.0
	v_fmac_f32_e32 v81, v82, v81
	v_div_scale_f32 v82, vcc, v46, v66, v46
	v_mul_f32_e32 v83, v82, v81
	v_fma_f32 v88, -v80, v83, v82
	v_fmac_f32_e32 v83, v88, v81
	v_fma_f32 v80, -v80, v83, v82
	v_div_fmas_f32 v80, v80, v81, v83
	v_div_fixup_f32 v66, v80, v66, v46
	v_pk_mul_f32 v[66:67], v[66:67], s[18:19] op_sel_hi:[1,0]
	ds_write_b128 v141, v[64:67] offset:18432
	v_pk_add_f32 v[64:65], v[72:73], 1.0 op_sel_hi:[1,0]
	v_div_scale_f32 v66, s[8:9], v65, v65, 1.0
	v_rcp_f32_e32 v67, v66
	s_nop 0
	v_fma_f32 v72, -v66, v67, 1.0
	v_fmac_f32_e32 v67, v72, v67
	v_div_scale_f32 v72, vcc, 1.0, v65, 1.0
	v_mul_f32_e32 v73, v72, v67
	v_fma_f32 v80, -v66, v73, v72
	v_fmac_f32_e32 v73, v80, v67
	v_fma_f32 v66, -v66, v73, v72
	v_div_fmas_f32 v66, v66, v67, v73
	v_div_fixup_f32 v65, v66, v65, 1.0
	v_div_scale_f32 v66, s[8:9], v64, v64, 1.0
	v_rcp_f32_e32 v67, v66
	s_nop 0
	v_fma_f32 v72, -v66, v67, 1.0
	v_fmac_f32_e32 v67, v72, v67
	v_div_scale_f32 v72, vcc, 1.0, v64, 1.0
	v_mul_f32_e32 v73, v72, v67
	v_fma_f32 v80, -v66, v73, v72
	v_fmac_f32_e32 v73, v80, v67
	v_fma_f32 v66, -v66, v73, v72
	v_div_fmas_f32 v66, v66, v67, v73
	v_div_fixup_f32 v64, v66, v64, 1.0
	v_pk_add_f32 v[66:67], v[74:75], 1.0 op_sel_hi:[1,0]
	v_pk_fma_f32 v[64:65], v[110:111], v[64:65], v[104:105]
	v_div_scale_f32 v72, s[8:9], v67, v67, 1.0
	v_rcp_f32_e32 v73, v72
	s_nop 0
	v_fma_f32 v74, -v72, v73, 1.0
	v_fmac_f32_e32 v73, v74, v73
	v_div_scale_f32 v74, vcc, 1.0, v67, 1.0
	v_mul_f32_e32 v75, v74, v73
	v_fma_f32 v80, -v72, v75, v74
	v_fmac_f32_e32 v75, v80, v73
	v_fma_f32 v72, -v72, v75, v74
	v_div_fmas_f32 v72, v72, v73, v75
	v_div_fixup_f32 v67, v72, v67, 1.0
	v_div_scale_f32 v72, s[8:9], v66, v66, 1.0
	v_rcp_f32_e32 v73, v72
	s_nop 0
	v_fma_f32 v74, -v72, v73, 1.0
	v_fmac_f32_e32 v73, v74, v73
	v_div_scale_f32 v74, vcc, 1.0, v66, 1.0
	v_mul_f32_e32 v75, v74, v73
	v_fma_f32 v80, -v72, v75, v74
	v_fmac_f32_e32 v75, v80, v73
	v_fma_f32 v72, -v72, v75, v74
	v_div_fmas_f32 v72, v72, v73, v75
	v_div_fixup_f32 v66, v72, v66, 1.0
	v_pk_fma_f32 v[66:67], v[112:113], v[66:67], v[106:107]
	ds_write_b128 v141, v[64:67] offset:26624
	ds_write_b32 v134, v133 offset:34816
	v_mul_f32_e32 v64, 0xbfb8aa3b, v56
	v_mul_f32_e32 v65, 0xbfb8aa3b, v57
	v_exp_f32_e32 v64, v64
	v_exp_f32_e32 v65, v65
	v_mul_f32_e32 v66, 0xbfb8aa3b, v58
	v_mul_f32_e32 v67, 0xbfb8aa3b, v59
	v_exp_f32_e32 v66, v66
	v_pk_add_f32 v[64:65], v[64:65], 1.0 op_sel_hi:[1,0]
	v_exp_f32_e32 v67, v67
	v_div_scale_f32 v80, s[8:9], v65, v65, v57
	v_rcp_f32_e32 v81, v80
	v_pk_add_f32 v[66:67], v[66:67], 1.0 op_sel_hi:[1,0]
	s_waitcnt vmcnt(4)
	v_mul_f32_e32 v72, 0xbfb8aa3b, v60
	v_mul_f32_e32 v73, 0xbfb8aa3b, v61
	v_fma_f32 v82, -v80, v81, 1.0
	v_fmac_f32_e32 v81, v82, v81
	v_div_scale_f32 v82, vcc, v57, v65, v57
	v_mul_f32_e32 v83, v82, v81
	v_fma_f32 v88, -v80, v83, v82
	v_fmac_f32_e32 v83, v88, v81
	v_fma_f32 v80, -v80, v83, v82
	v_div_fmas_f32 v80, v80, v81, v83
	v_div_fixup_f32 v65, v80, v65, v57
	v_div_scale_f32 v80, s[8:9], v64, v64, v56
	v_rcp_f32_e32 v81, v80
	v_exp_f32_e32 v72, v72
	v_exp_f32_e32 v73, v73
	v_mul_f32_e32 v74, 0xbfb8aa3b, v62
	v_fma_f32 v82, -v80, v81, 1.0
	v_fmac_f32_e32 v81, v82, v81
	v_div_scale_f32 v82, vcc, v56, v64, v56
	v_mul_f32_e32 v83, v82, v81
	v_fma_f32 v88, -v80, v83, v82
	v_fmac_f32_e32 v83, v88, v81
	v_fma_f32 v80, -v80, v83, v82
	v_div_fmas_f32 v80, v80, v81, v83
	v_div_fixup_f32 v64, v80, v64, v56
	v_div_scale_f32 v80, s[8:9], v67, v67, v59
	v_rcp_f32_e32 v81, v80
	v_pk_mul_f32 v[64:65], v[64:65], s[18:19] op_sel_hi:[1,0]
	v_mul_f32_e32 v75, 0xbfb8aa3b, v63
	v_exp_f32_e32 v74, v74
	v_fma_f32 v82, -v80, v81, 1.0
	v_fmac_f32_e32 v81, v82, v81
	v_div_scale_f32 v82, vcc, v59, v67, v59
	v_mul_f32_e32 v83, v82, v81
	v_fma_f32 v88, -v80, v83, v82
	v_fmac_f32_e32 v83, v88, v81
	v_fma_f32 v80, -v80, v83, v82
	v_div_fmas_f32 v80, v80, v81, v83
	v_div_fixup_f32 v67, v80, v67, v59
	v_div_scale_f32 v80, s[8:9], v66, v66, v58
	v_rcp_f32_e32 v81, v80
	v_exp_f32_e32 v75, v75
	v_fma_f32 v82, -v80, v81, 1.0
	v_fmac_f32_e32 v81, v82, v81
	v_div_scale_f32 v82, vcc, v58, v66, v58
	v_mul_f32_e32 v83, v82, v81
	v_fma_f32 v88, -v80, v83, v82
	v_fmac_f32_e32 v83, v88, v81
	v_fma_f32 v80, -v80, v83, v82
	v_div_fmas_f32 v80, v80, v81, v83
	v_div_fixup_f32 v66, v80, v66, v58
	v_pk_mul_f32 v[66:67], v[66:67], s[18:19] op_sel_hi:[1,0]
	ds_write_b128 v144, v[64:67] offset:18432
	v_pk_add_f32 v[64:65], v[72:73], 1.0 op_sel_hi:[1,0]
	v_div_scale_f32 v66, s[8:9], v65, v65, 1.0
	v_rcp_f32_e32 v67, v66
	s_nop 0
	v_fma_f32 v72, -v66, v67, 1.0
	v_fmac_f32_e32 v67, v72, v67
	v_div_scale_f32 v72, vcc, 1.0, v65, 1.0
	v_mul_f32_e32 v73, v72, v67
	v_fma_f32 v80, -v66, v73, v72
	v_fmac_f32_e32 v73, v80, v67
	v_fma_f32 v66, -v66, v73, v72
	v_div_fmas_f32 v66, v66, v67, v73
	v_div_fixup_f32 v65, v66, v65, 1.0
	v_div_scale_f32 v66, s[8:9], v64, v64, 1.0
	v_rcp_f32_e32 v67, v66
	s_nop 0
	v_fma_f32 v72, -v66, v67, 1.0
	v_fmac_f32_e32 v67, v72, v67
	v_div_scale_f32 v72, vcc, 1.0, v64, 1.0
	v_mul_f32_e32 v73, v72, v67
	v_fma_f32 v80, -v66, v73, v72
	v_fmac_f32_e32 v73, v80, v67
	v_fma_f32 v66, -v66, v73, v72
	v_div_fmas_f32 v66, v66, v67, v73
	v_div_fixup_f32 v64, v66, v64, 1.0
	v_pk_add_f32 v[66:67], v[74:75], 1.0 op_sel_hi:[1,0]
	v_pk_fma_f32 v[64:65], v[110:111], v[64:65], v[104:105]
	v_div_scale_f32 v72, s[8:9], v67, v67, 1.0
	v_rcp_f32_e32 v73, v72
	s_nop 0
	v_fma_f32 v74, -v72, v73, 1.0
	v_fmac_f32_e32 v73, v74, v73
	v_div_scale_f32 v74, vcc, 1.0, v67, 1.0
	v_mul_f32_e32 v75, v74, v73
	v_fma_f32 v80, -v72, v75, v74
	v_fmac_f32_e32 v75, v80, v73
	v_fma_f32 v72, -v72, v75, v74
	v_div_fmas_f32 v72, v72, v73, v75
	v_div_fixup_f32 v67, v72, v67, 1.0
	v_div_scale_f32 v72, s[8:9], v66, v66, 1.0
	v_rcp_f32_e32 v73, v72
	s_nop 0
	v_fma_f32 v74, -v72, v73, 1.0
	v_fmac_f32_e32 v73, v74, v73
	v_div_scale_f32 v74, vcc, 1.0, v66, 1.0
	v_mul_f32_e32 v75, v74, v73
	v_fma_f32 v80, -v72, v75, v74
	v_fmac_f32_e32 v75, v80, v73
	v_fma_f32 v72, -v72, v75, v74
	v_div_fmas_f32 v72, v72, v73, v75
	v_div_fixup_f32 v66, v72, v66, 1.0
	v_pk_fma_f32 v[66:67], v[112:113], v[66:67], v[106:107]
	ds_write_b128 v144, v[64:67] offset:26624
	ds_write_b32 v134, v135 offset:35840
	s_waitcnt lgkmcnt(0)
	s_barrier
	s_cbranch_scc1 .LBB0_1393
	v_add_u32_e32 v44, 0x70, v98
	v_mov_b64_e32 v[56:57], s[30:31]
	v_mad_i64_i32 v[44:45], s[8:9], v44, s25, v[56:57]
	s_lshl_b32 s94, s46, 2
	v_lshl_add_u64 v[58:59], v[44:45], 0, s[94:95]
	v_mov_b32_e32 v117, v140
	v_lshl_add_u64 v[44:45], v[58:59], 0, v[116:117]
	v_add_co_u32_e32 v46, vcc, 0x4000, v44
	s_lshl_b32 s8, s42, 2
	s_nop 0
	v_addc_co_u32_e32 v47, vcc, 0, v45, vcc
	s_mov_b32 s9, s95
	v_add_co_u32_e32 v48, vcc, 0x5000, v44
	v_lshl_add_u64 v[58:59], v[58:59], 0, s[8:9]
	v_mov_b32_e32 v115, v140
	v_add_u32_e32 v60, 0x70, v96
	v_addc_co_u32_e32 v49, vcc, 0, v45, vcc
	v_lshl_add_u64 v[58:59], v[58:59], 0, v[114:115]
	v_mad_i64_i32 v[56:57], s[22:23], v60, s25, v[56:57]
	v_add_co_u32_e32 v58, vcc, s81, v58
	v_lshl_add_u64 v[60:61], v[56:57], 0, s[94:95]
	s_nop 0
	v_addc_co_u32_e32 v59, vcc, 0, v59, vcc
	v_lshl_add_u64 v[62:63], v[60:61], 0, v[116:117]
	v_add_co_u32_e32 v56, vcc, s80, v62
	v_lshl_add_u64 v[60:61], v[60:61], 0, s[8:9]
	s_nop 0
	v_addc_co_u32_e32 v57, vcc, 0, v63, vcc
	v_add_co_u32_e32 v62, vcc, 0x5000, v62
	v_lshl_add_u64 v[60:61], v[60:61], 0, v[114:115]
	s_nop 0
	v_addc_co_u32_e32 v63, vcc, 0, v63, vcc
	v_add_co_u32_e32 v64, vcc, 0x6000, v60
	global_load_dwordx4 v[44:47], v[46:47], off offset:32
	s_nop 0
	global_load_dwordx4 v[48:51], v[48:49], off offset:32
	s_nop 0
	global_load_dword v133, v[58:59], off offset:32
	s_nop 0
	global_load_dwordx4 v[56:59], v[56:57], off offset:32
	v_addc_co_u32_e32 v65, vcc, 0, v61, vcc
	global_load_dwordx4 v[60:63], v[62:63], off offset:32
	s_nop 0
	global_load_dword v135, v[64:65], off offset:32
.LBB0_1393:
	ds_read2st64_b32 v[64:65], v134 offset0:144 offset1:148
	v_add_u32_e32 v66, 32, v98
	v_ashrrev_i32_e32 v67, 31, v66
	v_lshlrev_b64 v[66:67], 12, v[66:67]
	v_lshl_add_u64 v[66:67], v[108:109], 0, v[66:67]
	s_waitcnt lgkmcnt(0)
	global_store_dword v[66:67], v64, off
	v_add_u32_e32 v66, 32, v96
	v_ashrrev_i32_e32 v67, 31, v66
	v_lshlrev_b64 v[66:67], 12, v[66:67]
	v_lshl_add_u64 v[66:67], v[108:109], 0, v[66:67]
	global_store_dword v[66:67], v65, off
	ds_read_b128 v[178:181], v145 offset:18432
	ds_read_b128 v[182:185], v145 offset:18688
	ds_read_b128 v[114:117], v145 offset:26624
	ds_read_b128 v[186:189], v145 offset:26880
	ds_read2_b32 v[98:99], v153 offset1:16
	ds_read_b128 v[72:75], v145 offset:18944
	ds_read_b128 v[64:67], v145 offset:19200
	ds_read_b128 v[88:91], v145 offset:27136
	ds_read_b128 v[80:83], v145 offset:27392
	ds_read2_b32 v[96:97], v153 offset0:32 offset1:48
	s_waitcnt lgkmcnt(5)
	v_sub_f32 v70, v70, v98
	v_sub_f32 v71, v71, v99
	v_sub_f32 v68, v68, v98
	v_sub_f32 v69, v69, v99
	v_sub_f32 v95, v95, v98
	v_sub_f32 v94, v94, v99
	v_sub_f32 v92, v92, v98
	v_sub_f32 v93, v93, v99
	v_sub_f32 v86, v86, v98
	v_sub_f32 v87, v87, v99
	v_sub_f32 v84, v84, v98
	v_sub_f32 v85, v85, v99
	v_sub_f32 v78, v78, v98
	v_sub_f32 v76, v76, v98
	v_sub_f32 v77, v77, v99
	v_fma_f32 v157, v114, v95, v98
	v_fma_f32 v156, v114, v94, v99
	v_fma_f32 v154, v115, v92, v98
	v_fma_f32 v155, v115, v93, v99
	v_fma_f32 v148, v116, v86, v98
	v_fma_f32 v152, v116, v87, v99
	v_fma_f32 v146, v117, v84, v98
	v_fma_f32 v147, v117, v85, v99
	v_fma_f32 v116, v188, v70, v98
	v_fma_f32 v117, v188, v71, v99
	v_fma_f32 v114, v189, v68, v98
	v_fma_f32 v115, v189, v69, v99
	v_fma_f32 v68, v178, v157, v140
	v_fma_f32 v69, v178, v156, v140
	v_fma_f32 v70, v179, v154, v140
	v_fma_f32 v71, v179, v155, v140
	v_sub_f32 v79, v79, v99
	v_fma_f32 v120, v186, v78, v98
	v_fma_f32 v118, v187, v76, v98
	v_fma_f32 v119, v187, v77, v99
	v_fma_f32 v76, v180, v148, v140
	v_fma_f32 v77, v180, v152, v140
	v_fma_f32 v121, v186, v79, v99
	v_fma_f32 v78, v181, v146, v140
	v_fma_f32 v68, v182, v120, v68
	v_fma_f32 v79, v181, v147, v140
	v_fma_f32 v84, v182, v121, v69
	v_fma_f32 v69, v183, v118, v70
	v_fma_f32 v70, v183, v119, v71
	v_fma_f32 v71, v184, v116, v76
	v_fma_f32 v76, v184, v117, v77
	v_fma_f32 v77, v185, v114, v78
	v_fma_f32 v78, v185, v115, v79
	v_add_f32_e32 v68, v68, v69
	v_add_f32_e32 v69, v71, v77
	v_add_f32_e32 v70, v84, v70
	v_add_f32_e32 v71, v76, v78
	v_add_f32_e32 v68, v68, v69
	v_add_f32_e32 v70, v70, v71
	s_nop 0
	v_add_f32_dpp v68, v68, v68 row_ror:8 row_mask:0xf bank_mask:0xf bound_ctrl:1
	v_add_f32_dpp v70, v70, v70 row_ror:8 row_mask:0xf bank_mask:0xf bound_ctrl:1
	s_nop 0
	v_add_f32_dpp v68, v68, v68 row_ror:4 row_mask:0xf bank_mask:0xf bound_ctrl:1
	v_add_f32_dpp v70, v70, v70 row_ror:4 row_mask:0xf bank_mask:0xf bound_ctrl:1
	s_nop 0
	v_add_f32_dpp v68, v68, v68 row_ror:2 row_mask:0xf bank_mask:0xf bound_ctrl:1
	v_add_f32_dpp v70, v70, v70 row_ror:2 row_mask:0xf bank_mask:0xf bound_ctrl:1
	s_nop 0
	v_add_f32_dpp v68, v68, v68 row_ror:1 row_mask:0xf bank_mask:0xf bound_ctrl:1
	v_add_f32_dpp v70, v70, v70 row_ror:1 row_mask:0xf bank_mask:0xf bound_ctrl:1
	ds_write2_b32 v149, v68, v70 offset1:16
	s_waitcnt lgkmcnt(0)
	v_sub_f32 v157, v157, v96
	v_sub_f32 v156, v156, v97
	v_sub_f32 v154, v154, v96
	v_sub_f32 v155, v155, v97
	v_sub_f32 v120, v120, v96
	v_sub_f32 v121, v121, v97
	v_sub_f32 v118, v118, v96
	v_sub_f32 v119, v119, v97
	v_sub_f32 v148, v148, v96
	v_sub_f32 v152, v152, v97
	v_sub_f32 v116, v116, v96
	v_sub_f32 v117, v117, v97
	v_fma_f32 v157, v88, v157, v96
	v_fma_f32 v156, v88, v156, v97
	v_fma_f32 v154, v89, v154, v96
	v_fma_f32 v155, v89, v155, v97
	v_fma_f32 v120, v80, v120, v96
	v_fma_f32 v121, v80, v121, v97
	v_fma_f32 v118, v81, v118, v96
	v_fma_f32 v119, v81, v119, v97
	v_fma_f32 v80, v72, v157, v140
	v_fma_f32 v72, v72, v156, v140
	v_fma_f32 v81, v73, v154, v140
	v_fma_f32 v73, v73, v155, v140
	ds_read_b128 v[76:79], v145 offset:19456
	ds_read_b128 v[68:71], v145 offset:19712
	ds_read_b128 v[92:95], v145 offset:27648
	ds_read_b128 v[84:87], v145 offset:27904
	ds_read2_b32 v[98:99], v153 offset0:64 offset1:80
	v_sub_f32 v146, v146, v96
	v_sub_f32 v147, v147, v97
	v_sub_f32 v114, v114, v96
	v_sub_f32 v115, v115, v97
	v_fma_f32 v148, v90, v148, v96
	v_fma_f32 v152, v90, v152, v97
	v_fma_f32 v116, v82, v116, v96
	v_fma_f32 v117, v82, v117, v97
	v_fma_f32 v80, v64, v120, v80
	v_fma_f32 v72, v64, v121, v72
	v_fma_f32 v82, v74, v148, v140
	v_fma_f32 v74, v74, v152, v140
	v_fma_f32 v64, v65, v118, v81
	v_fma_f32 v73, v65, v119, v73
	v_fma_f32 v146, v91, v146, v96
	v_fma_f32 v147, v91, v147, v97
	v_fma_f32 v65, v66, v116, v82
	v_fma_f32 v66, v66, v117, v74
	v_fma_f32 v114, v83, v114, v96
	v_fma_f32 v115, v83, v115, v97
	v_fma_f32 v83, v75, v146, v140
	v_fma_f32 v75, v75, v147, v140
	v_add_f32_e32 v64, v80, v64
	v_fma_f32 v74, v67, v114, v83
	v_fma_f32 v67, v67, v115, v75
	v_add_f32_e32 v72, v72, v73
	v_add_f32_e32 v65, v65, v74
	v_add_f32_e32 v66, v66, v67
	v_add_f32_e32 v64, v64, v65
	v_add_f32_e32 v66, v72, v66
	s_nop 0
	v_add_f32_dpp v64, v64, v64 row_ror:8 row_mask:0xf bank_mask:0xf bound_ctrl:1
	v_add_f32_dpp v66, v66, v66 row_ror:8 row_mask:0xf bank_mask:0xf bound_ctrl:1
	s_nop 0
	v_add_f32_dpp v64, v64, v64 row_ror:4 row_mask:0xf bank_mask:0xf bound_ctrl:1
	v_add_f32_dpp v66, v66, v66 row_ror:4 row_mask:0xf bank_mask:0xf bound_ctrl:1
	s_nop 0
	v_add_f32_dpp v64, v64, v64 row_ror:2 row_mask:0xf bank_mask:0xf bound_ctrl:1
	v_add_f32_dpp v66, v66, v66 row_ror:2 row_mask:0xf bank_mask:0xf bound_ctrl:1
	s_nop 0
	v_add_f32_dpp v64, v64, v64 row_ror:1 row_mask:0xf bank_mask:0xf bound_ctrl:1
	v_add_f32_dpp v66, v66, v66 row_ror:1 row_mask:0xf bank_mask:0xf bound_ctrl:1
	ds_write2_b32 v149, v64, v66 offset0:32 offset1:48
	s_waitcnt lgkmcnt(0)
	v_sub_f32 v157, v157, v98
	v_sub_f32 v156, v156, v99
	v_sub_f32 v154, v154, v98
	v_sub_f32 v155, v155, v99
	v_sub_f32 v120, v120, v98
	v_sub_f32 v121, v121, v99
	v_sub_f32 v118, v118, v98
	v_sub_f32 v119, v119, v99
	v_sub_f32 v148, v148, v98
	v_sub_f32 v152, v152, v99
	v_sub_f32 v116, v116, v98
	v_sub_f32 v117, v117, v99
	v_fma_f32 v157, v92, v157, v98
	v_fma_f32 v156, v92, v156, v99
	v_fma_f32 v154, v93, v154, v98
	v_fma_f32 v155, v93, v155, v99
	v_fma_f32 v120, v84, v120, v98
	v_fma_f32 v121, v84, v121, v99
	v_fma_f32 v118, v85, v118, v98
	v_fma_f32 v119, v85, v119, v99
	v_fma_f32 v84, v76, v157, v140
	v_fma_f32 v76, v76, v156, v140
	v_fma_f32 v85, v77, v154, v140
	v_fma_f32 v77, v77, v155, v140
	ds_read_b128 v[72:75], v145 offset:19968
	ds_read_b128 v[64:67], v145 offset:20224
	ds_read_b128 v[88:91], v145 offset:28160
	ds_read_b128 v[80:83], v145 offset:28416
	ds_read2_b32 v[96:97], v153 offset0:96 offset1:112
	v_sub_f32 v146, v146, v98
	v_sub_f32 v147, v147, v99
	v_sub_f32 v114, v114, v98
	v_sub_f32 v115, v115, v99
	v_fma_f32 v148, v94, v148, v98
	v_fma_f32 v152, v94, v152, v99
	v_fma_f32 v116, v86, v116, v98
	v_fma_f32 v117, v86, v117, v99
	v_fma_f32 v84, v68, v120, v84
	v_fma_f32 v76, v68, v121, v76
	v_fma_f32 v86, v78, v148, v140
	v_fma_f32 v78, v78, v152, v140
	v_fma_f32 v68, v69, v118, v85
	v_fma_f32 v77, v69, v119, v77
	v_fma_f32 v146, v95, v146, v98
	v_fma_f32 v147, v95, v147, v99
	v_fma_f32 v69, v70, v116, v86
	v_fma_f32 v70, v70, v117, v78
	v_fma_f32 v114, v87, v114, v98
	v_fma_f32 v115, v87, v115, v99
	v_fma_f32 v87, v79, v146, v140
	v_fma_f32 v79, v79, v147, v140
	v_add_f32_e32 v68, v84, v68
	v_fma_f32 v78, v71, v114, v87
	v_fma_f32 v71, v71, v115, v79
	v_add_f32_e32 v76, v76, v77
	v_add_f32_e32 v69, v69, v78
	v_add_f32_e32 v70, v70, v71
	v_add_f32_e32 v68, v68, v69
	v_add_f32_e32 v70, v76, v70
	s_nop 0
	v_add_f32_dpp v68, v68, v68 row_ror:8 row_mask:0xf bank_mask:0xf bound_ctrl:1
	v_add_f32_dpp v70, v70, v70 row_ror:8 row_mask:0xf bank_mask:0xf bound_ctrl:1
	s_nop 0
	v_add_f32_dpp v68, v68, v68 row_ror:4 row_mask:0xf bank_mask:0xf bound_ctrl:1
	v_add_f32_dpp v70, v70, v70 row_ror:4 row_mask:0xf bank_mask:0xf bound_ctrl:1
	s_nop 0
	v_add_f32_dpp v68, v68, v68 row_ror:2 row_mask:0xf bank_mask:0xf bound_ctrl:1
	v_add_f32_dpp v70, v70, v70 row_ror:2 row_mask:0xf bank_mask:0xf bound_ctrl:1
	s_nop 0
	v_add_f32_dpp v68, v68, v68 row_ror:1 row_mask:0xf bank_mask:0xf bound_ctrl:1
	v_add_f32_dpp v70, v70, v70 row_ror:1 row_mask:0xf bank_mask:0xf bound_ctrl:1
	ds_write2_b32 v149, v68, v70 offset0:64 offset1:80
	s_waitcnt lgkmcnt(0)
	v_sub_f32 v157, v157, v96
	v_sub_f32 v156, v156, v97
	v_sub_f32 v154, v154, v96
	v_sub_f32 v155, v155, v97
	v_sub_f32 v120, v120, v96
	v_sub_f32 v121, v121, v97
	v_sub_f32 v118, v118, v96
	v_sub_f32 v119, v119, v97
	v_sub_f32 v148, v148, v96
	v_sub_f32 v152, v152, v97
	v_sub_f32 v116, v116, v96
	v_sub_f32 v117, v117, v97
	v_fma_f32 v157, v88, v157, v96
	v_fma_f32 v156, v88, v156, v97
	v_fma_f32 v154, v89, v154, v96
	v_fma_f32 v155, v89, v155, v97
	v_fma_f32 v120, v80, v120, v96
	v_fma_f32 v121, v80, v121, v97
	v_fma_f32 v118, v81, v118, v96
	v_fma_f32 v119, v81, v119, v97
	v_fma_f32 v80, v72, v157, v140
	v_fma_f32 v72, v72, v156, v140
	v_fma_f32 v81, v73, v154, v140
	v_fma_f32 v73, v73, v155, v140
	ds_read_b128 v[76:79], v145 offset:20480
	ds_read_b128 v[68:71], v145 offset:20736
	ds_read_b128 v[92:95], v145 offset:28672
	ds_read_b128 v[84:87], v145 offset:28928
	ds_read2_b32 v[98:99], v153 offset0:128 offset1:144
	v_sub_f32 v146, v146, v96
	v_sub_f32 v147, v147, v97
	v_sub_f32 v114, v114, v96
	v_sub_f32 v115, v115, v97
	v_fma_f32 v148, v90, v148, v96
	v_fma_f32 v152, v90, v152, v97
	v_fma_f32 v116, v82, v116, v96
	v_fma_f32 v117, v82, v117, v97
	v_fma_f32 v80, v64, v120, v80
	v_fma_f32 v72, v64, v121, v72
	v_fma_f32 v82, v74, v148, v140
	v_fma_f32 v74, v74, v152, v140
	v_fma_f32 v64, v65, v118, v81
	v_fma_f32 v73, v65, v119, v73
	v_fma_f32 v146, v91, v146, v96
	v_fma_f32 v147, v91, v147, v97
	v_fma_f32 v65, v66, v116, v82
	v_fma_f32 v66, v66, v117, v74
	v_fma_f32 v114, v83, v114, v96
	v_fma_f32 v115, v83, v115, v97
	v_fma_f32 v83, v75, v146, v140
	v_fma_f32 v75, v75, v147, v140
	v_add_f32_e32 v64, v80, v64
	v_fma_f32 v74, v67, v114, v83
	v_fma_f32 v67, v67, v115, v75
	v_add_f32_e32 v72, v72, v73
	v_add_f32_e32 v65, v65, v74
	v_add_f32_e32 v66, v66, v67
	v_add_f32_e32 v64, v64, v65
	v_add_f32_e32 v66, v72, v66
	s_nop 0
	v_add_f32_dpp v64, v64, v64 row_ror:8 row_mask:0xf bank_mask:0xf bound_ctrl:1
	v_add_f32_dpp v66, v66, v66 row_ror:8 row_mask:0xf bank_mask:0xf bound_ctrl:1
	s_nop 0
	v_add_f32_dpp v64, v64, v64 row_ror:4 row_mask:0xf bank_mask:0xf bound_ctrl:1
	v_add_f32_dpp v66, v66, v66 row_ror:4 row_mask:0xf bank_mask:0xf bound_ctrl:1
	s_nop 0
	v_add_f32_dpp v64, v64, v64 row_ror:2 row_mask:0xf bank_mask:0xf bound_ctrl:1
	v_add_f32_dpp v66, v66, v66 row_ror:2 row_mask:0xf bank_mask:0xf bound_ctrl:1
	s_nop 0
	v_add_f32_dpp v64, v64, v64 row_ror:1 row_mask:0xf bank_mask:0xf bound_ctrl:1
	v_add_f32_dpp v66, v66, v66 row_ror:1 row_mask:0xf bank_mask:0xf bound_ctrl:1
	ds_write2_b32 v149, v64, v66 offset0:96 offset1:112
	s_waitcnt lgkmcnt(0)
	v_sub_f32 v157, v157, v98
	v_sub_f32 v156, v156, v99
	v_sub_f32 v154, v154, v98
	v_sub_f32 v155, v155, v99
	v_sub_f32 v120, v120, v98
	v_sub_f32 v121, v121, v99
	v_sub_f32 v118, v118, v98
	v_sub_f32 v119, v119, v99
	v_sub_f32 v148, v148, v98
	v_sub_f32 v152, v152, v99
	v_sub_f32 v116, v116, v98
	v_sub_f32 v117, v117, v99
	v_fma_f32 v157, v92, v157, v98
	v_fma_f32 v156, v92, v156, v99
	v_fma_f32 v154, v93, v154, v98
	v_fma_f32 v155, v93, v155, v99
	v_fma_f32 v120, v84, v120, v98
	v_fma_f32 v121, v84, v121, v99
	v_fma_f32 v118, v85, v118, v98
	v_fma_f32 v119, v85, v119, v99
	v_fma_f32 v84, v76, v157, v140
	v_fma_f32 v76, v76, v156, v140
	v_fma_f32 v85, v77, v154, v140
	v_fma_f32 v77, v77, v155, v140
	ds_read_b128 v[72:75], v145 offset:20992
	ds_read_b128 v[64:67], v145 offset:21248
	ds_read_b128 v[88:91], v145 offset:29184
	ds_read_b128 v[80:83], v145 offset:29440
	ds_read2_b32 v[96:97], v153 offset0:160 offset1:176
	v_sub_f32 v146, v146, v98
	v_sub_f32 v147, v147, v99
	v_sub_f32 v114, v114, v98
	v_sub_f32 v115, v115, v99
	v_fma_f32 v148, v94, v148, v98
	v_fma_f32 v152, v94, v152, v99
	v_fma_f32 v116, v86, v116, v98
	v_fma_f32 v117, v86, v117, v99
	v_fma_f32 v84, v68, v120, v84
	v_fma_f32 v76, v68, v121, v76
	v_fma_f32 v86, v78, v148, v140
	v_fma_f32 v78, v78, v152, v140
	v_fma_f32 v68, v69, v118, v85
	v_fma_f32 v77, v69, v119, v77
	v_fma_f32 v146, v95, v146, v98
	v_fma_f32 v147, v95, v147, v99
	v_fma_f32 v69, v70, v116, v86
	v_fma_f32 v70, v70, v117, v78
	v_fma_f32 v114, v87, v114, v98
	v_fma_f32 v115, v87, v115, v99
	v_fma_f32 v87, v79, v146, v140
	v_fma_f32 v79, v79, v147, v140
	v_add_f32_e32 v68, v84, v68
	v_fma_f32 v78, v71, v114, v87
	v_fma_f32 v71, v71, v115, v79
	v_add_f32_e32 v76, v76, v77
	v_add_f32_e32 v69, v69, v78
	v_add_f32_e32 v70, v70, v71
	v_add_f32_e32 v68, v68, v69
	v_add_f32_e32 v70, v76, v70
	s_nop 0
	v_add_f32_dpp v68, v68, v68 row_ror:8 row_mask:0xf bank_mask:0xf bound_ctrl:1
	v_add_f32_dpp v70, v70, v70 row_ror:8 row_mask:0xf bank_mask:0xf bound_ctrl:1
	s_nop 0
	v_add_f32_dpp v68, v68, v68 row_ror:4 row_mask:0xf bank_mask:0xf bound_ctrl:1
	v_add_f32_dpp v70, v70, v70 row_ror:4 row_mask:0xf bank_mask:0xf bound_ctrl:1
	s_nop 0
	v_add_f32_dpp v68, v68, v68 row_ror:2 row_mask:0xf bank_mask:0xf bound_ctrl:1
	v_add_f32_dpp v70, v70, v70 row_ror:2 row_mask:0xf bank_mask:0xf bound_ctrl:1
	s_nop 0
	v_add_f32_dpp v68, v68, v68 row_ror:1 row_mask:0xf bank_mask:0xf bound_ctrl:1
	v_add_f32_dpp v70, v70, v70 row_ror:1 row_mask:0xf bank_mask:0xf bound_ctrl:1
	ds_write2_b32 v149, v68, v70 offset0:128 offset1:144
	s_waitcnt lgkmcnt(0)
	v_sub_f32 v157, v157, v96
	v_sub_f32 v156, v156, v97
	v_sub_f32 v154, v154, v96
	v_sub_f32 v155, v155, v97
	v_sub_f32 v120, v120, v96
	v_sub_f32 v121, v121, v97
	v_sub_f32 v118, v118, v96
	v_sub_f32 v119, v119, v97
	v_sub_f32 v148, v148, v96
	v_sub_f32 v152, v152, v97
	v_sub_f32 v116, v116, v96
	v_sub_f32 v117, v117, v97
	v_fma_f32 v157, v88, v157, v96
	v_fma_f32 v156, v88, v156, v97
	v_fma_f32 v154, v89, v154, v96
	v_fma_f32 v155, v89, v155, v97
	v_fma_f32 v120, v80, v120, v96
	v_fma_f32 v121, v80, v121, v97
	v_fma_f32 v118, v81, v118, v96
	v_fma_f32 v119, v81, v119, v97
	v_fma_f32 v80, v72, v157, v140
	v_fma_f32 v72, v72, v156, v140
	v_fma_f32 v81, v73, v154, v140
	v_fma_f32 v73, v73, v155, v140
	ds_read_b128 v[76:79], v145 offset:21504
	ds_read_b128 v[68:71], v145 offset:21760
	ds_read_b128 v[92:95], v145 offset:29696
	ds_read_b128 v[84:87], v145 offset:29952
	ds_read2_b32 v[98:99], v153 offset0:192 offset1:208
	v_sub_f32 v146, v146, v96
	v_sub_f32 v147, v147, v97
	v_sub_f32 v114, v114, v96
	v_sub_f32 v115, v115, v97
	v_fma_f32 v148, v90, v148, v96
	v_fma_f32 v152, v90, v152, v97
	v_fma_f32 v116, v82, v116, v96
	v_fma_f32 v117, v82, v117, v97
	v_fma_f32 v80, v64, v120, v80
	v_fma_f32 v72, v64, v121, v72
	v_fma_f32 v82, v74, v148, v140
	v_fma_f32 v74, v74, v152, v140
	v_fma_f32 v64, v65, v118, v81
	v_fma_f32 v73, v65, v119, v73
	v_fma_f32 v146, v91, v146, v96
	v_fma_f32 v147, v91, v147, v97
	v_fma_f32 v65, v66, v116, v82
	v_fma_f32 v66, v66, v117, v74
	v_fma_f32 v114, v83, v114, v96
	v_fma_f32 v115, v83, v115, v97
	v_fma_f32 v83, v75, v146, v140
	v_fma_f32 v75, v75, v147, v140
	v_add_f32_e32 v64, v80, v64
	v_fma_f32 v74, v67, v114, v83
	v_fma_f32 v67, v67, v115, v75
	v_add_f32_e32 v72, v72, v73
	v_add_f32_e32 v65, v65, v74
	v_add_f32_e32 v66, v66, v67
	v_add_f32_e32 v64, v64, v65
	v_add_f32_e32 v66, v72, v66
	s_nop 0
	v_add_f32_dpp v64, v64, v64 row_ror:8 row_mask:0xf bank_mask:0xf bound_ctrl:1
	v_add_f32_dpp v66, v66, v66 row_ror:8 row_mask:0xf bank_mask:0xf bound_ctrl:1
	s_nop 0
	v_add_f32_dpp v64, v64, v64 row_ror:4 row_mask:0xf bank_mask:0xf bound_ctrl:1
	v_add_f32_dpp v66, v66, v66 row_ror:4 row_mask:0xf bank_mask:0xf bound_ctrl:1
	s_nop 0
	v_add_f32_dpp v64, v64, v64 row_ror:2 row_mask:0xf bank_mask:0xf bound_ctrl:1
	v_add_f32_dpp v66, v66, v66 row_ror:2 row_mask:0xf bank_mask:0xf bound_ctrl:1
	s_nop 0
	v_add_f32_dpp v64, v64, v64 row_ror:1 row_mask:0xf bank_mask:0xf bound_ctrl:1
	v_add_f32_dpp v66, v66, v66 row_ror:1 row_mask:0xf bank_mask:0xf bound_ctrl:1
	ds_write2_b32 v149, v64, v66 offset0:160 offset1:176
	ds_read_b128 v[72:75], v145 offset:22016
	ds_read_b128 v[64:67], v145 offset:22272
	ds_read_b128 v[88:91], v145 offset:30208
	ds_read_b128 v[80:83], v145 offset:30464
	ds_read2_b32 v[96:97], v153 offset0:224 offset1:240
	s_waitcnt lgkmcnt(5)
	v_sub_f32 v153, v157, v98
	v_sub_f32 v154, v154, v98
	v_sub_f32 v120, v120, v98
	v_sub_f32 v121, v121, v99
	v_sub_f32 v118, v118, v98
	v_sub_f32 v119, v119, v99
	v_sub_f32 v157, v156, v99
	v_sub_f32 v178, v155, v99
	v_sub_f32 v148, v148, v98
	v_sub_f32 v152, v152, v99
	v_sub_f32 v116, v116, v98
	v_sub_f32 v117, v117, v99
	v_fma_f32 v156, v92, v153, v98
	v_fma_f32 v155, v92, v157, v99
	v_fma_f32 v153, v93, v154, v98
	v_fma_f32 v154, v93, v178, v99
	v_fma_f32 v120, v84, v120, v98
	v_fma_f32 v121, v84, v121, v99
	v_fma_f32 v118, v85, v118, v98
	v_fma_f32 v119, v85, v119, v99
	v_fma_f32 v84, v76, v156, v140
	v_fma_f32 v76, v76, v155, v140
	v_fma_f32 v85, v77, v153, v140
	v_fma_f32 v77, v77, v154, v140
	v_sub_f32 v146, v146, v98
	v_sub_f32 v147, v147, v99
	v_sub_f32 v114, v114, v98
	v_sub_f32 v115, v115, v99
	v_fma_f32 v148, v94, v148, v98
	v_fma_f32 v152, v94, v152, v99
	v_fma_f32 v116, v86, v116, v98
	v_fma_f32 v117, v86, v117, v99
	v_fma_f32 v84, v68, v120, v84
	v_fma_f32 v76, v68, v121, v76
	v_fma_f32 v86, v78, v148, v140
	v_fma_f32 v78, v78, v152, v140
	v_fma_f32 v68, v69, v118, v85
	v_fma_f32 v77, v69, v119, v77
	v_fma_f32 v146, v95, v146, v98
	v_fma_f32 v147, v95, v147, v99
	v_fma_f32 v69, v70, v116, v86
	v_fma_f32 v70, v70, v117, v78
	v_fma_f32 v114, v87, v114, v98
	v_fma_f32 v115, v87, v115, v99
	v_fma_f32 v87, v79, v146, v140
	v_fma_f32 v79, v79, v147, v140
	v_add_f32_e32 v68, v84, v68
	v_fma_f32 v78, v71, v114, v87
	v_fma_f32 v71, v71, v115, v79
	v_add_f32_e32 v76, v76, v77
	v_add_f32_e32 v69, v69, v78
	v_add_f32_e32 v70, v70, v71
	v_add_f32_e32 v68, v68, v69
	v_add_f32_e32 v70, v76, v70
	s_nop 0
	v_add_f32_dpp v68, v68, v68 row_ror:8 row_mask:0xf bank_mask:0xf bound_ctrl:1
	v_add_f32_dpp v70, v70, v70 row_ror:8 row_mask:0xf bank_mask:0xf bound_ctrl:1
	s_nop 0
	v_add_f32_dpp v68, v68, v68 row_ror:4 row_mask:0xf bank_mask:0xf bound_ctrl:1
	v_add_f32_dpp v70, v70, v70 row_ror:4 row_mask:0xf bank_mask:0xf bound_ctrl:1
	s_nop 0
	v_add_f32_dpp v68, v68, v68 row_ror:2 row_mask:0xf bank_mask:0xf bound_ctrl:1
	v_add_f32_dpp v70, v70, v70 row_ror:2 row_mask:0xf bank_mask:0xf bound_ctrl:1
	s_nop 0
	v_add_f32_dpp v68, v68, v68 row_ror:1 row_mask:0xf bank_mask:0xf bound_ctrl:1
	v_add_f32_dpp v70, v70, v70 row_ror:1 row_mask:0xf bank_mask:0xf bound_ctrl:1
	ds_write2_b32 v149, v68, v70 offset0:192 offset1:208
	s_waitcnt lgkmcnt(0)
	v_sub_f32 v156, v156, v96
	v_sub_f32 v155, v155, v97
	v_sub_f32 v153, v153, v96
	v_sub_f32 v154, v154, v97
	v_sub_f32 v120, v120, v96
	v_sub_f32 v121, v121, v97
	v_sub_f32 v118, v118, v96
	v_sub_f32 v119, v119, v97
	v_sub_f32 v148, v148, v96
	v_sub_f32 v152, v152, v97
	v_sub_f32 v116, v116, v96
	v_sub_f32 v117, v117, v97
	v_fma_f32 v156, v88, v156, v96
	v_fma_f32 v155, v88, v155, v97
	v_fma_f32 v153, v89, v153, v96
	v_fma_f32 v154, v89, v154, v97
	v_fma_f32 v120, v80, v120, v96
	v_fma_f32 v121, v80, v121, v97
	v_fma_f32 v118, v81, v118, v96
	v_fma_f32 v119, v81, v119, v97
	v_fma_f32 v80, v72, v156, v140
	v_fma_f32 v72, v72, v155, v140
	v_fma_f32 v81, v73, v153, v140
	v_fma_f32 v73, v73, v154, v140
	ds_read_b128 v[76:79], v145 offset:22528
	ds_read_b128 v[68:71], v145 offset:22784
	ds_read_b128 v[92:95], v145 offset:30720
	ds_read_b128 v[84:87], v145 offset:30976
	ds_read2_b32 v[98:99], v151 offset1:16
	v_sub_f32 v146, v146, v96
	v_sub_f32 v147, v147, v97
	v_sub_f32 v114, v114, v96
	v_sub_f32 v115, v115, v97
	v_fma_f32 v148, v90, v148, v96
	v_fma_f32 v152, v90, v152, v97
	v_fma_f32 v116, v82, v116, v96
	v_fma_f32 v117, v82, v117, v97
	v_fma_f32 v80, v64, v120, v80
	v_fma_f32 v72, v64, v121, v72
	v_fma_f32 v82, v74, v148, v140
	v_fma_f32 v74, v74, v152, v140
	v_fma_f32 v64, v65, v118, v81
	v_fma_f32 v73, v65, v119, v73
	v_fma_f32 v146, v91, v146, v96
	v_fma_f32 v147, v91, v147, v97
	v_fma_f32 v65, v66, v116, v82
	v_fma_f32 v66, v66, v117, v74
	v_fma_f32 v114, v83, v114, v96
	v_fma_f32 v115, v83, v115, v97
	v_fma_f32 v83, v75, v146, v140
	v_fma_f32 v75, v75, v147, v140
	v_add_f32_e32 v64, v80, v64
	v_fma_f32 v74, v67, v114, v83
	v_fma_f32 v67, v67, v115, v75
	v_add_f32_e32 v72, v72, v73
	v_add_f32_e32 v65, v65, v74
	v_add_f32_e32 v66, v66, v67
	v_add_f32_e32 v64, v64, v65
	v_add_f32_e32 v66, v72, v66
	s_nop 0
	v_add_f32_dpp v64, v64, v64 row_ror:8 row_mask:0xf bank_mask:0xf bound_ctrl:1
	v_add_f32_dpp v66, v66, v66 row_ror:8 row_mask:0xf bank_mask:0xf bound_ctrl:1
	s_nop 0
	v_add_f32_dpp v64, v64, v64 row_ror:4 row_mask:0xf bank_mask:0xf bound_ctrl:1
	v_add_f32_dpp v66, v66, v66 row_ror:4 row_mask:0xf bank_mask:0xf bound_ctrl:1
	s_nop 0
	v_add_f32_dpp v64, v64, v64 row_ror:2 row_mask:0xf bank_mask:0xf bound_ctrl:1
	v_add_f32_dpp v66, v66, v66 row_ror:2 row_mask:0xf bank_mask:0xf bound_ctrl:1
	s_nop 0
	v_add_f32_dpp v64, v64, v64 row_ror:1 row_mask:0xf bank_mask:0xf bound_ctrl:1
	v_add_f32_dpp v66, v66, v66 row_ror:1 row_mask:0xf bank_mask:0xf bound_ctrl:1
	ds_write2_b32 v149, v64, v66 offset0:224 offset1:240
	s_waitcnt lgkmcnt(0)
	v_sub_f32 v153, v153, v98
	v_sub_f32 v120, v120, v98
	v_sub_f32 v121, v121, v99
	v_sub_f32 v118, v118, v98
	v_sub_f32 v119, v119, v99
	v_sub_f32 v149, v156, v98
	v_sub_f32 v156, v155, v99
	v_sub_f32 v157, v154, v99
	v_sub_f32 v148, v148, v98
	v_sub_f32 v178, v152, v99
	v_sub_f32 v116, v116, v98
	v_sub_f32 v117, v117, v99
	v_fma_f32 v155, v92, v149, v98
	v_fma_f32 v154, v92, v156, v99
	v_fma_f32 v152, v93, v153, v98
	v_fma_f32 v153, v93, v157, v99
	v_fma_f32 v120, v84, v120, v98
	v_fma_f32 v121, v84, v121, v99
	v_fma_f32 v118, v85, v118, v98
	v_fma_f32 v119, v85, v119, v99
	v_fma_f32 v84, v76, v155, v140
	v_fma_f32 v76, v76, v154, v140
	v_fma_f32 v85, v77, v152, v140
	v_fma_f32 v77, v77, v153, v140
	ds_read_b128 v[72:75], v145 offset:23040
	ds_read_b128 v[64:67], v145 offset:23296
	ds_read_b128 v[88:91], v145 offset:31232
	ds_read_b128 v[80:83], v145 offset:31488
	ds_read2_b32 v[96:97], v151 offset0:32 offset1:48
	v_sub_f32 v146, v146, v98
	v_sub_f32 v147, v147, v99
	v_sub_f32 v114, v114, v98
	v_sub_f32 v115, v115, v99
	v_fma_f32 v148, v94, v148, v98
	v_fma_f32 v149, v94, v178, v99
	v_fma_f32 v116, v86, v116, v98
	v_fma_f32 v117, v86, v117, v99
	v_fma_f32 v84, v68, v120, v84
	v_fma_f32 v76, v68, v121, v76
	v_fma_f32 v86, v78, v148, v140
	v_fma_f32 v78, v78, v149, v140
	v_fma_f32 v68, v69, v118, v85
	v_fma_f32 v77, v69, v119, v77
	v_fma_f32 v146, v95, v146, v98
	v_fma_f32 v147, v95, v147, v99
	v_fma_f32 v69, v70, v116, v86
	v_fma_f32 v70, v70, v117, v78
	v_fma_f32 v114, v87, v114, v98
	v_fma_f32 v115, v87, v115, v99
	v_fma_f32 v87, v79, v146, v140
	v_fma_f32 v79, v79, v147, v140
	v_add_f32_e32 v68, v84, v68
	v_fma_f32 v78, v71, v114, v87
	v_fma_f32 v71, v71, v115, v79
	v_add_f32_e32 v76, v76, v77
	v_add_f32_e32 v69, v69, v78
	v_add_f32_e32 v70, v70, v71
	v_add_f32_e32 v68, v68, v69
	v_add_f32_e32 v70, v76, v70
	s_nop 0
	v_add_f32_dpp v68, v68, v68 row_ror:8 row_mask:0xf bank_mask:0xf bound_ctrl:1
	v_add_f32_dpp v70, v70, v70 row_ror:8 row_mask:0xf bank_mask:0xf bound_ctrl:1
	s_nop 0
	v_add_f32_dpp v68, v68, v68 row_ror:4 row_mask:0xf bank_mask:0xf bound_ctrl:1
	v_add_f32_dpp v70, v70, v70 row_ror:4 row_mask:0xf bank_mask:0xf bound_ctrl:1
	s_nop 0
	v_add_f32_dpp v68, v68, v68 row_ror:2 row_mask:0xf bank_mask:0xf bound_ctrl:1
	v_add_f32_dpp v70, v70, v70 row_ror:2 row_mask:0xf bank_mask:0xf bound_ctrl:1
	s_nop 0
	v_add_f32_dpp v68, v68, v68 row_ror:1 row_mask:0xf bank_mask:0xf bound_ctrl:1
	v_add_f32_dpp v70, v70, v70 row_ror:1 row_mask:0xf bank_mask:0xf bound_ctrl:1
	ds_write2_b32 v150, v68, v70 offset1:16
	s_waitcnt lgkmcnt(0)
	v_sub_f32 v155, v155, v96
	v_sub_f32 v154, v154, v97
	v_sub_f32 v152, v152, v96
	v_sub_f32 v153, v153, v97
	v_sub_f32 v120, v120, v96
	v_sub_f32 v121, v121, v97
	v_sub_f32 v118, v118, v96
	v_sub_f32 v119, v119, v97
	v_sub_f32 v148, v148, v96
	v_sub_f32 v149, v149, v97
	v_sub_f32 v116, v116, v96
	v_sub_f32 v117, v117, v97
	v_fma_f32 v155, v88, v155, v96
	v_fma_f32 v154, v88, v154, v97
	v_fma_f32 v152, v89, v152, v96
	v_fma_f32 v153, v89, v153, v97
	v_fma_f32 v120, v80, v120, v96
	v_fma_f32 v121, v80, v121, v97
	v_fma_f32 v118, v81, v118, v96
	v_fma_f32 v119, v81, v119, v97
	v_fma_f32 v80, v72, v155, v140
	v_fma_f32 v72, v72, v154, v140
	v_fma_f32 v81, v73, v152, v140
	v_fma_f32 v73, v73, v153, v140
	ds_read_b128 v[76:79], v145 offset:23552
	ds_read_b128 v[68:71], v145 offset:23808
	ds_read_b128 v[92:95], v145 offset:31744
	ds_read_b128 v[84:87], v145 offset:32000
	ds_read2_b32 v[98:99], v151 offset0:64 offset1:80
	v_sub_f32 v146, v146, v96
	v_sub_f32 v147, v147, v97
	v_sub_f32 v114, v114, v96
	v_sub_f32 v115, v115, v97
	v_fma_f32 v148, v90, v148, v96
	v_fma_f32 v149, v90, v149, v97
	v_fma_f32 v116, v82, v116, v96
	v_fma_f32 v117, v82, v117, v97
	v_fma_f32 v80, v64, v120, v80
	v_fma_f32 v72, v64, v121, v72
	v_fma_f32 v82, v74, v148, v140
	v_fma_f32 v74, v74, v149, v140
	v_fma_f32 v64, v65, v118, v81
	v_fma_f32 v73, v65, v119, v73
	v_fma_f32 v146, v91, v146, v96
	v_fma_f32 v147, v91, v147, v97
	v_fma_f32 v65, v66, v116, v82
	v_fma_f32 v66, v66, v117, v74
	v_fma_f32 v114, v83, v114, v96
	v_fma_f32 v115, v83, v115, v97
	v_fma_f32 v83, v75, v146, v140
	v_fma_f32 v75, v75, v147, v140
	v_add_f32_e32 v64, v80, v64
	v_fma_f32 v74, v67, v114, v83
	v_fma_f32 v67, v67, v115, v75
	v_add_f32_e32 v72, v72, v73
	v_add_f32_e32 v65, v65, v74
	v_add_f32_e32 v66, v66, v67
	v_add_f32_e32 v64, v64, v65
	v_add_f32_e32 v66, v72, v66
	s_nop 0
	v_add_f32_dpp v64, v64, v64 row_ror:8 row_mask:0xf bank_mask:0xf bound_ctrl:1
	v_add_f32_dpp v66, v66, v66 row_ror:8 row_mask:0xf bank_mask:0xf bound_ctrl:1
	s_nop 0
	v_add_f32_dpp v64, v64, v64 row_ror:4 row_mask:0xf bank_mask:0xf bound_ctrl:1
	v_add_f32_dpp v66, v66, v66 row_ror:4 row_mask:0xf bank_mask:0xf bound_ctrl:1
	s_nop 0
	v_add_f32_dpp v64, v64, v64 row_ror:2 row_mask:0xf bank_mask:0xf bound_ctrl:1
	v_add_f32_dpp v66, v66, v66 row_ror:2 row_mask:0xf bank_mask:0xf bound_ctrl:1
	s_nop 0
	v_add_f32_dpp v64, v64, v64 row_ror:1 row_mask:0xf bank_mask:0xf bound_ctrl:1
	v_add_f32_dpp v66, v66, v66 row_ror:1 row_mask:0xf bank_mask:0xf bound_ctrl:1
	ds_write2_b32 v150, v64, v66 offset0:32 offset1:48
	s_waitcnt lgkmcnt(0)
	v_sub_f32 v155, v155, v98
	v_sub_f32 v154, v154, v99
	v_sub_f32 v152, v152, v98
	v_sub_f32 v153, v153, v99
	v_sub_f32 v120, v120, v98
	v_sub_f32 v121, v121, v99
	v_sub_f32 v118, v118, v98
	v_sub_f32 v119, v119, v99
	v_sub_f32 v148, v148, v98
	v_sub_f32 v149, v149, v99
	v_sub_f32 v116, v116, v98
	v_sub_f32 v117, v117, v99
	v_fma_f32 v155, v92, v155, v98
	v_fma_f32 v154, v92, v154, v99
	v_fma_f32 v152, v93, v152, v98
	v_fma_f32 v153, v93, v153, v99
	v_fma_f32 v120, v84, v120, v98
	v_fma_f32 v121, v84, v121, v99
	v_fma_f32 v118, v85, v118, v98
	v_fma_f32 v119, v85, v119, v99
	v_fma_f32 v84, v76, v155, v140
	v_fma_f32 v76, v76, v154, v140
	v_fma_f32 v85, v77, v152, v140
	v_fma_f32 v77, v77, v153, v140
	ds_read_b128 v[72:75], v145 offset:24064
	ds_read_b128 v[64:67], v145 offset:24320
	ds_read_b128 v[88:91], v145 offset:32256
	ds_read_b128 v[80:83], v145 offset:32512
	ds_read2_b32 v[96:97], v151 offset0:96 offset1:112
	v_sub_f32 v146, v146, v98
	v_sub_f32 v147, v147, v99
	v_sub_f32 v114, v114, v98
	v_sub_f32 v115, v115, v99
	v_fma_f32 v148, v94, v148, v98
	v_fma_f32 v149, v94, v149, v99
	v_fma_f32 v116, v86, v116, v98
	v_fma_f32 v117, v86, v117, v99
	v_fma_f32 v84, v68, v120, v84
	v_fma_f32 v76, v68, v121, v76
	v_fma_f32 v86, v78, v148, v140
	v_fma_f32 v78, v78, v149, v140
	v_fma_f32 v68, v69, v118, v85
	v_fma_f32 v77, v69, v119, v77
	v_fma_f32 v146, v95, v146, v98
	v_fma_f32 v147, v95, v147, v99
	v_fma_f32 v69, v70, v116, v86
	v_fma_f32 v70, v70, v117, v78
	v_fma_f32 v114, v87, v114, v98
	v_fma_f32 v115, v87, v115, v99
	v_fma_f32 v87, v79, v146, v140
	v_fma_f32 v79, v79, v147, v140
	v_add_f32_e32 v68, v84, v68
	v_fma_f32 v78, v71, v114, v87
	v_fma_f32 v71, v71, v115, v79
	v_add_f32_e32 v76, v76, v77
	v_add_f32_e32 v69, v69, v78
	v_add_f32_e32 v70, v70, v71
	v_add_f32_e32 v68, v68, v69
	v_add_f32_e32 v70, v76, v70
	s_nop 0
	v_add_f32_dpp v68, v68, v68 row_ror:8 row_mask:0xf bank_mask:0xf bound_ctrl:1
	v_add_f32_dpp v70, v70, v70 row_ror:8 row_mask:0xf bank_mask:0xf bound_ctrl:1
	s_nop 0
	v_add_f32_dpp v68, v68, v68 row_ror:4 row_mask:0xf bank_mask:0xf bound_ctrl:1
	v_add_f32_dpp v70, v70, v70 row_ror:4 row_mask:0xf bank_mask:0xf bound_ctrl:1
	s_nop 0
	v_add_f32_dpp v68, v68, v68 row_ror:2 row_mask:0xf bank_mask:0xf bound_ctrl:1
	v_add_f32_dpp v70, v70, v70 row_ror:2 row_mask:0xf bank_mask:0xf bound_ctrl:1
	s_nop 0
	v_add_f32_dpp v68, v68, v68 row_ror:1 row_mask:0xf bank_mask:0xf bound_ctrl:1
	v_add_f32_dpp v70, v70, v70 row_ror:1 row_mask:0xf bank_mask:0xf bound_ctrl:1
	ds_write2_b32 v150, v68, v70 offset0:64 offset1:80
	s_waitcnt lgkmcnt(0)
	v_sub_f32 v155, v155, v96
	v_sub_f32 v154, v154, v97
	v_sub_f32 v152, v152, v96
	v_sub_f32 v153, v153, v97
	v_sub_f32 v120, v120, v96
	v_sub_f32 v121, v121, v97
	v_sub_f32 v118, v118, v96
	v_sub_f32 v119, v119, v97
	v_sub_f32 v148, v148, v96
	v_sub_f32 v149, v149, v97
	v_sub_f32 v116, v116, v96
	v_sub_f32 v117, v117, v97
	v_fma_f32 v155, v88, v155, v96
	v_fma_f32 v154, v88, v154, v97
	v_fma_f32 v152, v89, v152, v96
	v_fma_f32 v153, v89, v153, v97
	v_fma_f32 v120, v80, v120, v96
	v_fma_f32 v121, v80, v121, v97
	v_fma_f32 v118, v81, v118, v96
	v_fma_f32 v119, v81, v119, v97
	v_fma_f32 v80, v72, v155, v140
	v_fma_f32 v72, v72, v154, v140
	v_fma_f32 v81, v73, v152, v140
	v_fma_f32 v73, v73, v153, v140
	ds_read_b128 v[76:79], v145 offset:24576
	ds_read_b128 v[68:71], v145 offset:24832
	ds_read_b128 v[92:95], v145 offset:32768
	ds_read_b128 v[84:87], v145 offset:33024
	ds_read2_b32 v[98:99], v151 offset0:128 offset1:144
	v_sub_f32 v146, v146, v96
	v_sub_f32 v147, v147, v97
	v_sub_f32 v114, v114, v96
	v_sub_f32 v115, v115, v97
	v_fma_f32 v148, v90, v148, v96
	v_fma_f32 v149, v90, v149, v97
	v_fma_f32 v116, v82, v116, v96
	v_fma_f32 v117, v82, v117, v97
	v_fma_f32 v80, v64, v120, v80
	v_fma_f32 v72, v64, v121, v72
	v_fma_f32 v82, v74, v148, v140
	v_fma_f32 v74, v74, v149, v140
	v_fma_f32 v64, v65, v118, v81
	v_fma_f32 v73, v65, v119, v73
	v_fma_f32 v146, v91, v146, v96
	v_fma_f32 v147, v91, v147, v97
	v_fma_f32 v65, v66, v116, v82
	v_fma_f32 v66, v66, v117, v74
	v_fma_f32 v114, v83, v114, v96
	v_fma_f32 v115, v83, v115, v97
	v_fma_f32 v83, v75, v146, v140
	v_fma_f32 v75, v75, v147, v140
	v_add_f32_e32 v64, v80, v64
	v_fma_f32 v74, v67, v114, v83
	v_fma_f32 v67, v67, v115, v75
	v_add_f32_e32 v72, v72, v73
	v_add_f32_e32 v65, v65, v74
	v_add_f32_e32 v66, v66, v67
	v_add_f32_e32 v64, v64, v65
	v_add_f32_e32 v66, v72, v66
	s_nop 0
	v_add_f32_dpp v64, v64, v64 row_ror:8 row_mask:0xf bank_mask:0xf bound_ctrl:1
	v_add_f32_dpp v66, v66, v66 row_ror:8 row_mask:0xf bank_mask:0xf bound_ctrl:1
	s_nop 0
	v_add_f32_dpp v64, v64, v64 row_ror:4 row_mask:0xf bank_mask:0xf bound_ctrl:1
	v_add_f32_dpp v66, v66, v66 row_ror:4 row_mask:0xf bank_mask:0xf bound_ctrl:1
	s_nop 0
	v_add_f32_dpp v64, v64, v64 row_ror:2 row_mask:0xf bank_mask:0xf bound_ctrl:1
	v_add_f32_dpp v66, v66, v66 row_ror:2 row_mask:0xf bank_mask:0xf bound_ctrl:1
	s_nop 0
	v_add_f32_dpp v64, v64, v64 row_ror:1 row_mask:0xf bank_mask:0xf bound_ctrl:1
	v_add_f32_dpp v66, v66, v66 row_ror:1 row_mask:0xf bank_mask:0xf bound_ctrl:1
	ds_write2_b32 v150, v64, v66 offset0:96 offset1:112
	s_waitcnt lgkmcnt(0)
	v_sub_f32 v155, v155, v98
	v_sub_f32 v154, v154, v99
	v_sub_f32 v152, v152, v98
	v_sub_f32 v153, v153, v99
	v_sub_f32 v120, v120, v98
	v_sub_f32 v121, v121, v99
	v_sub_f32 v118, v118, v98
	v_sub_f32 v119, v119, v99
	v_sub_f32 v148, v148, v98
	v_sub_f32 v149, v149, v99
	v_sub_f32 v116, v116, v98
	v_sub_f32 v117, v117, v99
	v_fma_f32 v155, v92, v155, v98
	v_fma_f32 v154, v92, v154, v99
	v_fma_f32 v152, v93, v152, v98
	v_fma_f32 v153, v93, v153, v99
	v_fma_f32 v120, v84, v120, v98
	v_fma_f32 v121, v84, v121, v99
	v_fma_f32 v118, v85, v118, v98
	v_fma_f32 v119, v85, v119, v99
	v_fma_f32 v84, v76, v155, v140
	v_fma_f32 v76, v76, v154, v140
	v_fma_f32 v85, v77, v152, v140
	v_fma_f32 v77, v77, v153, v140
	ds_read_b128 v[72:75], v145 offset:25088
	ds_read_b128 v[64:67], v145 offset:25344
	ds_read_b128 v[88:91], v145 offset:33280
	ds_read_b128 v[80:83], v145 offset:33536
	ds_read2_b32 v[96:97], v151 offset0:160 offset1:176
	v_sub_f32 v146, v146, v98
	v_sub_f32 v147, v147, v99
	v_sub_f32 v114, v114, v98
	v_sub_f32 v115, v115, v99
	v_fma_f32 v148, v94, v148, v98
	v_fma_f32 v149, v94, v149, v99
	v_fma_f32 v116, v86, v116, v98
	v_fma_f32 v117, v86, v117, v99
	v_fma_f32 v84, v68, v120, v84
	v_fma_f32 v76, v68, v121, v76
	v_fma_f32 v86, v78, v148, v140
	v_fma_f32 v78, v78, v149, v140
	v_fma_f32 v68, v69, v118, v85
	v_fma_f32 v77, v69, v119, v77
	v_fma_f32 v146, v95, v146, v98
	v_fma_f32 v147, v95, v147, v99
	v_fma_f32 v69, v70, v116, v86
	v_fma_f32 v70, v70, v117, v78
	v_fma_f32 v114, v87, v114, v98
	v_fma_f32 v115, v87, v115, v99
	v_fma_f32 v87, v79, v146, v140
	v_fma_f32 v79, v79, v147, v140
	v_add_f32_e32 v68, v84, v68
	v_fma_f32 v78, v71, v114, v87
	v_fma_f32 v71, v71, v115, v79
	v_add_f32_e32 v76, v76, v77
	v_add_f32_e32 v69, v69, v78
	v_add_f32_e32 v70, v70, v71
	v_add_f32_e32 v68, v68, v69
	v_add_f32_e32 v70, v76, v70
	s_nop 0
	v_add_f32_dpp v68, v68, v68 row_ror:8 row_mask:0xf bank_mask:0xf bound_ctrl:1
	v_add_f32_dpp v70, v70, v70 row_ror:8 row_mask:0xf bank_mask:0xf bound_ctrl:1
	s_nop 0
	v_add_f32_dpp v68, v68, v68 row_ror:4 row_mask:0xf bank_mask:0xf bound_ctrl:1
	v_add_f32_dpp v70, v70, v70 row_ror:4 row_mask:0xf bank_mask:0xf bound_ctrl:1
	s_nop 0
	v_add_f32_dpp v68, v68, v68 row_ror:2 row_mask:0xf bank_mask:0xf bound_ctrl:1
	v_add_f32_dpp v70, v70, v70 row_ror:2 row_mask:0xf bank_mask:0xf bound_ctrl:1
	s_nop 0
	v_add_f32_dpp v68, v68, v68 row_ror:1 row_mask:0xf bank_mask:0xf bound_ctrl:1
	v_add_f32_dpp v70, v70, v70 row_ror:1 row_mask:0xf bank_mask:0xf bound_ctrl:1
	ds_write2_b32 v150, v68, v70 offset0:128 offset1:144
	s_waitcnt lgkmcnt(0)
	v_sub_f32 v155, v155, v96
	v_sub_f32 v154, v154, v97
	v_sub_f32 v152, v152, v96
	v_sub_f32 v153, v153, v97
	v_sub_f32 v120, v120, v96
	v_sub_f32 v121, v121, v97
	v_sub_f32 v118, v118, v96
	v_sub_f32 v119, v119, v97
	v_sub_f32 v148, v148, v96
	v_sub_f32 v149, v149, v97
	v_sub_f32 v116, v116, v96
	v_sub_f32 v117, v117, v97
	v_fma_f32 v155, v88, v155, v96
	v_fma_f32 v154, v88, v154, v97
	v_fma_f32 v152, v89, v152, v96
	v_fma_f32 v153, v89, v153, v97
	v_fma_f32 v120, v80, v120, v96
	v_fma_f32 v121, v80, v121, v97
	v_fma_f32 v118, v81, v118, v96
	v_fma_f32 v119, v81, v119, v97
	v_fma_f32 v80, v72, v155, v140
	v_fma_f32 v72, v72, v154, v140
	v_fma_f32 v81, v73, v152, v140
	v_fma_f32 v73, v73, v153, v140
	ds_read_b128 v[76:79], v145 offset:25600
	ds_read_b128 v[68:71], v145 offset:25856
	ds_read_b128 v[92:95], v145 offset:33792
	ds_read_b128 v[84:87], v145 offset:34048
	ds_read2_b32 v[98:99], v151 offset0:192 offset1:208
	v_sub_f32 v146, v146, v96
	v_sub_f32 v147, v147, v97
	v_sub_f32 v114, v114, v96
	v_sub_f32 v115, v115, v97
	v_fma_f32 v148, v90, v148, v96
	v_fma_f32 v149, v90, v149, v97
	v_fma_f32 v116, v82, v116, v96
	v_fma_f32 v117, v82, v117, v97
	v_fma_f32 v80, v64, v120, v80
	v_fma_f32 v72, v64, v121, v72
	v_fma_f32 v82, v74, v148, v140
	v_fma_f32 v74, v74, v149, v140
	v_fma_f32 v64, v65, v118, v81
	v_fma_f32 v73, v65, v119, v73
	v_fma_f32 v146, v91, v146, v96
	v_fma_f32 v147, v91, v147, v97
	v_fma_f32 v65, v66, v116, v82
	v_fma_f32 v66, v66, v117, v74
	v_fma_f32 v114, v83, v114, v96
	v_fma_f32 v115, v83, v115, v97
	v_fma_f32 v83, v75, v146, v140
	v_fma_f32 v75, v75, v147, v140
	v_add_f32_e32 v64, v80, v64
	v_fma_f32 v74, v67, v114, v83
	v_fma_f32 v67, v67, v115, v75
	v_add_f32_e32 v72, v72, v73
	v_add_f32_e32 v65, v65, v74
	v_add_f32_e32 v66, v66, v67
	v_add_f32_e32 v64, v64, v65
	v_add_f32_e32 v66, v72, v66
	s_nop 0
	v_add_f32_dpp v64, v64, v64 row_ror:8 row_mask:0xf bank_mask:0xf bound_ctrl:1
	v_add_f32_dpp v66, v66, v66 row_ror:8 row_mask:0xf bank_mask:0xf bound_ctrl:1
	s_nop 0
	v_add_f32_dpp v64, v64, v64 row_ror:4 row_mask:0xf bank_mask:0xf bound_ctrl:1
	v_add_f32_dpp v66, v66, v66 row_ror:4 row_mask:0xf bank_mask:0xf bound_ctrl:1
	s_nop 0
	v_add_f32_dpp v64, v64, v64 row_ror:2 row_mask:0xf bank_mask:0xf bound_ctrl:1
	v_add_f32_dpp v66, v66, v66 row_ror:2 row_mask:0xf bank_mask:0xf bound_ctrl:1
	s_nop 0
	v_add_f32_dpp v64, v64, v64 row_ror:1 row_mask:0xf bank_mask:0xf bound_ctrl:1
	v_add_f32_dpp v66, v66, v66 row_ror:1 row_mask:0xf bank_mask:0xf bound_ctrl:1
	ds_write2_b32 v150, v64, v66 offset0:160 offset1:176
	ds_read_b128 v[72:75], v145 offset:26112
	ds_read_b128 v[64:67], v145 offset:26368
	ds_read_b128 v[88:91], v145 offset:34304
	ds_read_b128 v[80:83], v145 offset:34560
	ds_read2_b32 v[96:97], v151 offset0:224 offset1:240
	s_waitcnt lgkmcnt(5)
	v_sub_f32 v151, v155, v98
	v_sub_f32 v154, v154, v99
	v_sub_f32 v152, v152, v98
	v_sub_f32 v153, v153, v99
	v_sub_f32 v148, v148, v98
	v_sub_f32 v149, v149, v99
	v_sub_f32 v155, v146, v98
	v_sub_f32 v147, v147, v99
	v_sub_f32 v156, v120, v98
	v_sub_f32 v157, v121, v99
	v_sub_f32 v178, v118, v98
	v_sub_f32 v179, v119, v99
	v_sub_f32 v180, v116, v98
	v_sub_f32 v181, v117, v99
	v_sub_f32 v182, v114, v98
	v_sub_f32 v183, v115, v99
	v_fma_f32 v146, v92, v151, v98
	v_fma_f32 v121, v92, v154, v99
	v_fma_f32 v119, v93, v152, v98
	v_fma_f32 v120, v93, v153, v99
	v_fma_f32 v117, v94, v148, v98
	v_fma_f32 v118, v94, v149, v99
	v_fma_f32 v115, v95, v155, v98
	v_fma_f32 v116, v95, v147, v99
	v_fma_f32 v95, v84, v156, v98
	v_fma_f32 v114, v84, v157, v99
	v_fma_f32 v93, v85, v178, v98
	v_fma_f32 v94, v85, v179, v99
	v_fma_f32 v92, v86, v180, v98
	v_fma_f32 v84, v87, v182, v98
	v_fma_f32 v85, v87, v183, v99
	v_fma_f32 v87, v76, v146, v140
	v_fma_f32 v76, v76, v121, v140
	v_fma_f32 v98, v77, v119, v140
	v_fma_f32 v77, v77, v120, v140
	v_fma_f32 v86, v86, v181, v99
	v_fma_f32 v99, v78, v117, v140
	v_fma_f32 v78, v78, v118, v140
	v_fma_f32 v87, v68, v95, v87
	v_fma_f32 v76, v68, v114, v76
	v_fma_f32 v68, v69, v93, v98
	v_fma_f32 v77, v69, v94, v77
	v_fma_f32 v69, v70, v92, v99
	v_fma_f32 v70, v70, v86, v78
	v_fma_f32 v147, v79, v115, v140
	v_fma_f32 v79, v79, v116, v140
	v_add_f32_e32 v68, v87, v68
	v_fma_f32 v78, v71, v84, v147
	v_fma_f32 v71, v71, v85, v79
	v_add_f32_e32 v76, v76, v77
	v_add_f32_e32 v69, v69, v78
	v_add_f32_e32 v70, v70, v71
	v_add_f32_e32 v68, v68, v69
	v_add_f32_e32 v70, v76, v70
	s_nop 0
	v_add_f32_dpp v68, v68, v68 row_ror:8 row_mask:0xf bank_mask:0xf bound_ctrl:1
	v_add_f32_dpp v70, v70, v70 row_ror:8 row_mask:0xf bank_mask:0xf bound_ctrl:1
	s_nop 0
	v_add_f32_dpp v68, v68, v68 row_ror:4 row_mask:0xf bank_mask:0xf bound_ctrl:1
	v_add_f32_dpp v70, v70, v70 row_ror:4 row_mask:0xf bank_mask:0xf bound_ctrl:1
	s_nop 0
	v_add_f32_dpp v68, v68, v68 row_ror:2 row_mask:0xf bank_mask:0xf bound_ctrl:1
	v_add_f32_dpp v70, v70, v70 row_ror:2 row_mask:0xf bank_mask:0xf bound_ctrl:1
	s_nop 0
	v_add_f32_dpp v68, v68, v68 row_ror:1 row_mask:0xf bank_mask:0xf bound_ctrl:1
	v_add_f32_dpp v70, v70, v70 row_ror:1 row_mask:0xf bank_mask:0xf bound_ctrl:1
	ds_write2_b32 v150, v68, v70 offset0:192 offset1:208
	s_waitcnt lgkmcnt(0)
	v_sub_f32 v68, v146, v96
	v_sub_f32 v69, v121, v97
	v_sub_f32 v70, v119, v96
	v_sub_f32 v71, v120, v97
	v_sub_f32 v77, v118, v97
	v_sub_f32 v76, v117, v96
	v_fma_f32 v118, v88, v68, v96
	v_fma_f32 v146, v88, v69, v97
	v_fma_f32 v119, v89, v70, v96
	v_sub_f32 v87, v95, v96
	v_sub_f32 v95, v114, v97
	v_sub_f32 v93, v93, v96
	v_fma_f32 v68, v72, v118, v140
	v_fma_f32 v69, v72, v146, v140
	v_fma_f32 v70, v73, v119, v140
	v_sub_f32 v94, v94, v97
	v_sub_f32 v92, v92, v96
	v_sub_f32 v86, v86, v97
	v_fma_f32 v120, v89, v71, v97
	v_fma_f32 v88, v90, v76, v96
	v_fma_f32 v121, v90, v77, v97
	v_fma_f32 v90, v80, v87, v96
	v_fma_f32 v147, v80, v95, v97
	v_fma_f32 v80, v81, v93, v96
	v_fma_f32 v148, v81, v94, v97
	v_fma_f32 v81, v82, v92, v96
	v_fma_f32 v149, v82, v86, v97
	v_fma_f32 v71, v73, v120, v140
	v_fma_f32 v72, v74, v88, v140
	v_fma_f32 v73, v74, v121, v140
	v_fma_f32 v68, v64, v90, v68
	v_fma_f32 v69, v64, v147, v69
	v_fma_f32 v64, v65, v80, v70
	v_fma_f32 v70, v65, v148, v71
	v_fma_f32 v65, v66, v81, v72
	v_fma_f32 v66, v66, v149, v73
	v_sub_f32 v78, v115, v96
	v_sub_f32 v79, v116, v97
	v_sub_f32 v84, v84, v96
	v_sub_f32 v85, v85, v97
	v_add_f32_e32 v64, v68, v64
	v_fma_f32 v89, v91, v78, v96
	v_fma_f32 v91, v91, v79, v97
	v_fma_f32 v82, v83, v84, v96
	v_fma_f32 v83, v83, v85, v97
	v_add_f32_e32 v68, v69, v70
	v_fma_f32 v74, v75, v89, v140
	v_fma_f32 v75, v75, v91, v140
	v_fma_f32 v71, v67, v82, v74
	v_fma_f32 v67, v67, v83, v75
	v_add_f32_e32 v65, v65, v71
	v_add_f32_e32 v66, v66, v67
	v_add_f32_e32 v64, v64, v65
	v_add_f32_e32 v66, v68, v66
	v_mov_b32_e32 v65, 0
	v_add_f32_dpp v64, v64, v64 row_ror:8 row_mask:0xf bank_mask:0xf bound_ctrl:1
	v_add_f32_dpp v66, v66, v66 row_ror:8 row_mask:0xf bank_mask:0xf bound_ctrl:1
	v_mov_b32_e32 v67, 0
	v_add_f32_dpp v64, v64, v64 row_ror:4 row_mask:0xf bank_mask:0xf bound_ctrl:1
	v_add_f32_dpp v66, v66, v66 row_ror:4 row_mask:0xf bank_mask:0xf bound_ctrl:1
	s_nop 0
	v_add_f32_dpp v64, v64, v64 row_ror:2 row_mask:0xf bank_mask:0xf bound_ctrl:1
	v_add_f32_dpp v66, v66, v66 row_ror:2 row_mask:0xf bank_mask:0xf bound_ctrl:1
	s_nop 0
	v_mov_b32_dpp v65, v64 row_ror:1 row_mask:0xf bank_mask:0xf
	v_mov_b32_dpp v67, v66 row_ror:1 row_mask:0xf bank_mask:0xf
	s_and_saveexec_b64 s[8:9], s[38:39]
	s_cbranch_execz .LBB0_1284
	v_add_f32_e32 v66, v66, v67
	v_add_f32_e32 v64, v64, v65
	ds_write2_b32 v150, v64, v66 offset0:224 offset1:240
	s_branch .LBB0_1284

.LBB0_1454:
	s_or_b64 exec, exec, s[8:9]
	s_waitcnt lgkmcnt(0)
	s_barrier
	v_add_u32_e64 v190, s83, 0
	ds_read_b128 v[104:107], v188
	ds_read_b128 v[108:111], v188 offset:256
	ds_read_b128 v[112:115], v188 offset:8192
	ds_read_b128 v[116:119], v188 offset:8448
	ds_read2_b64 v[96:99], v190 offset0:32 offset1:40
	v_add_u32_e32 v192, 0x4000, v189
	ds_read2_b32 v[92:93], v192 offset1:16
	ds_read_b128 v[202:205], v188 offset:512
	ds_read_b128 v[206:209], v188 offset:768
	ds_read_b128 v[152:155], v188 offset:8704
	ds_read_b128 v[194:197], v188 offset:8960
	ds_read_b128 v[100:103], v188 offset:1024
	ds_read_b128 v[88:91], v188 offset:1280
	ds_read_b128 v[132:135], v188 offset:9216
	ds_read_b128 v[124:127], v188 offset:9472
	ds_read_b128 v[84:87], v188 offset:1536
	ds_read_b128 v[80:83], v188 offset:1792
	ds_read_b128 v[128:131], v188 offset:9728
	ds_read_b128 v[120:123], v188 offset:9984
	s_waitcnt lgkmcnt(12)
	v_mul_f32_e32 v92, v98, v92
	v_mul_f32 v94, v112, v92
	v_mul_f32 v95, v113, v92
	v_mul_f32 v98, v114, v92
	v_mul_f32 v112, v115, v92
	v_mul_f32 v113, v116, v92
	v_mul_f32 v114, v117, v92
	v_fma_f32 v200, v96, v64, v94
	v_fma_f32 v199, v96, v65, v95
	v_mul_f32 v115, v118, v92
	v_mul_f32 v116, v119, v92
	s_waitcnt lgkmcnt(9)
	v_mul_f32 v117, v152, v92
	v_mul_f32 v118, v153, v92
	v_fma_f32 v64, v104, v200, v140
	v_fma_f32 v65, v105, v199, v140
	v_mul_f32 v119, v154, v92
	v_mul_f32 v152, v155, v92
	s_waitcnt lgkmcnt(8)
	v_mul_f32 v153, v194, v92
	v_mul_f32 v201, v195, v92
	v_mul_f32 v210, v196, v92
	v_mul_f32 v92, v197, v92
	v_fma_f32 v198, v96, v66, v98
	v_fma_f32 v197, v96, v67, v112
	v_fma_f32 v191, v96, v76, v113
	v_fma_f32 v193, v96, v77, v114
	v_fma_f32 v194, v96, v78, v115
	v_fma_f32 v196, v96, v79, v116
	v_fma_f32 v66, v106, v198, v140
	v_fma_f32 v67, v107, v197, v140
	v_fma_f32 v64, v108, v191, v64
	v_fma_f32 v65, v109, v193, v65
	v_fma_f32 v195, v96, v72, v117
	v_fma_f32 v155, v96, v73, v118
	v_fma_f32 v66, v110, v194, v66
	v_fma_f32 v67, v111, v196, v67
	v_fma_f32 v154, v96, v74, v119
	v_fma_f32 v98, v96, v75, v152
	v_fma_f32 v64, v202, v195, v64
	v_fma_f32 v65, v203, v155, v65
	v_fma_f32 v79, v96, v68, v153
	v_fma_f32 v78, v96, v69, v201
	v_fma_f32 v66, v204, v154, v66
	v_fma_f32 v67, v205, v98, v67
	v_fma_f32 v77, v96, v70, v210
	v_fma_f32 v76, v96, v71, v92
	v_fma_f32 v64, v206, v79, v64
	v_fma_f32 v65, v207, v78, v65
	v_fma_f32 v66, v208, v77, v66
	v_fma_f32 v67, v209, v76, v67
	v_add_f32_e32 v64, v64, v65
	v_add_f32_e32 v65, v66, v67
	v_add_f32_e32 v64, v64, v65
	s_nop 1
	v_add_f32_dpp v64, v64, v64 row_ror:8 row_mask:0xf bank_mask:0xf bound_ctrl:1
	s_nop 1
	v_add_f32_dpp v64, v64, v64 row_ror:4 row_mask:0xf bank_mask:0xf bound_ctrl:1
	s_nop 1
	v_add_f32_dpp v64, v64, v64 row_ror:2 row_mask:0xf bank_mask:0xf bound_ctrl:1
	s_nop 1
	v_add_f32_dpp v64, v64, v64 row_ror:1 row_mask:0xf bank_mask:0xf bound_ctrl:1
	ds_write_b32 v189, v64 offset:34048
	v_mul_f32_e32 v99, v99, v93
	ds_read_b128 v[92:95], v188 offset:2048
	ds_read_b128 v[72:75], v188 offset:2304
	ds_read_b128 v[116:119], v188 offset:10240
	ds_read_b128 v[108:111], v188 offset:10496
	ds_read_b128 v[68:71], v188 offset:2560
	ds_read_b128 v[64:67], v188 offset:2816
	ds_read_b128 v[112:115], v188 offset:10752
	ds_read_b128 v[104:107], v188 offset:11008
	ds_read2_b32 v[152:153], v190 offset0:66 offset1:82
	ds_read_b32 v96, v189 offset:16512
	s_waitcnt lgkmcnt(14)
	v_mul_f32 v132, v132, v99
	v_mul_f32 v133, v133, v99
	v_mul_f32 v134, v134, v99
	v_mul_f32 v135, v135, v99
	v_mul_f32 v124, v124, v99
	v_mul_f32 v125, v125, v99
	v_mul_f32 v126, v126, v99
	v_mul_f32 v127, v127, v99
	s_waitcnt lgkmcnt(11)
	v_mul_f32 v128, v128, v99
	v_mul_f32 v129, v129, v99
	v_mul_f32 v130, v130, v99
	v_mul_f32 v131, v131, v99
	s_waitcnt lgkmcnt(10)
	v_mul_f32 v120, v120, v99
	v_mul_f32 v121, v121, v99
	v_mul_f32 v122, v122, v99
	v_mul_f32 v99, v123, v99
	v_fma_f32 v132, v97, v200, v132
	v_fma_f32 v133, v97, v199, v133
	v_fma_f32 v134, v97, v198, v134
	v_fma_f32 v135, v97, v197, v135
	v_fma_f32 v202, v97, v77, v122
	v_fma_f32 v203, v97, v76, v99
	v_fma_f32 v76, v100, v132, v140
	v_fma_f32 v77, v101, v133, v140
	v_fma_f32 v191, v97, v191, v124
	v_fma_f32 v193, v97, v193, v125
	v_fma_f32 v200, v97, v79, v120
	v_fma_f32 v201, v97, v78, v121
	v_fma_f32 v78, v102, v134, v140
	v_fma_f32 v79, v103, v135, v140
	v_fma_f32 v76, v88, v191, v76
	v_fma_f32 v77, v89, v193, v77
	v_fma_f32 v194, v97, v194, v126
	v_fma_f32 v196, v97, v196, v127
	v_fma_f32 v195, v97, v195, v128
	v_fma_f32 v197, v97, v155, v129
	v_fma_f32 v198, v97, v154, v130
	v_fma_f32 v199, v97, v98, v131
	v_fma_f32 v78, v90, v194, v78
	v_fma_f32 v79, v91, v196, v79
	v_fma_f32 v76, v84, v195, v76
	v_fma_f32 v77, v85, v197, v77
	v_fma_f32 v78, v86, v198, v78
	v_fma_f32 v79, v87, v199, v79
	v_fma_f32 v76, v80, v200, v76
	v_fma_f32 v77, v81, v201, v77
	v_fma_f32 v78, v82, v202, v78
	v_fma_f32 v79, v83, v203, v79
	v_add_f32_e32 v76, v76, v77
	v_add_f32_e32 v77, v78, v79
	v_add_f32_e32 v76, v76, v77
	s_nop 1
	v_add_f32_dpp v76, v76, v76 row_ror:8 row_mask:0xf bank_mask:0xf bound_ctrl:1
	s_nop 1
	v_add_f32_dpp v76, v76, v76 row_ror:4 row_mask:0xf bank_mask:0xf bound_ctrl:1
	s_nop 1
	v_add_f32_dpp v76, v76, v76 row_ror:2 row_mask:0xf bank_mask:0xf bound_ctrl:1
	s_nop 1
	v_add_f32_dpp v76, v76, v76 row_ror:1 row_mask:0xf bank_mask:0xf bound_ctrl:1
	ds_write_b32 v189, v76 offset:34112
	s_waitcnt lgkmcnt(0)
	v_mul_f32_e32 v89, v153, v96
	ds_read_b128 v[96:99], v188 offset:3072
	ds_read_b128 v[84:87], v188 offset:3328
	ds_read_b128 v[128:131], v188 offset:11264
	ds_read_b128 v[120:123], v188 offset:11520
	ds_read_b128 v[80:83], v188 offset:3584
	ds_read_b128 v[76:79], v188 offset:3840
	ds_read_b128 v[124:127], v188 offset:11776
	ds_read_b128 v[100:103], v188 offset:12032
	ds_read2_b32 v[154:155], v190 offset0:67 offset1:83
	ds_read_b32 v88, v189 offset:16576
	v_mul_f32 v90, v116, v89
	v_mul_f32 v91, v117, v89
	v_mul_f32 v118, v118, v89
	v_mul_f32 v119, v119, v89
	v_mul_f32 v108, v108, v89
	v_mul_f32 v109, v109, v89
	v_mul_f32 v110, v110, v89
	v_mul_f32 v111, v111, v89
	v_mul_f32 v112, v112, v89
	v_mul_f32 v113, v113, v89
	v_mul_f32 v114, v114, v89
	v_mul_f32 v115, v115, v89
	v_mul_f32 v104, v104, v89
	v_mul_f32 v105, v105, v89
	v_mul_f32 v106, v106, v89
	v_mul_f32 v89, v107, v89
	v_fma_f32 v116, v152, v132, v90
	v_fma_f32 v117, v152, v133, v91
	v_fma_f32 v191, v152, v191, v108
	v_fma_f32 v193, v152, v193, v109
	v_fma_f32 v195, v152, v195, v112
	v_fma_f32 v197, v152, v197, v113
	v_fma_f32 v200, v152, v200, v104
	v_fma_f32 v201, v152, v201, v105
	v_fma_f32 v203, v152, v203, v89
	v_fma_f32 v89, v92, v116, v140
	v_fma_f32 v90, v93, v117, v140
	v_fma_f32 v118, v152, v134, v118
	v_fma_f32 v119, v152, v135, v119
	v_fma_f32 v194, v152, v194, v110
	v_fma_f32 v196, v152, v196, v111
	v_fma_f32 v72, v72, v191, v89
	v_fma_f32 v73, v73, v193, v90
	v_fma_f32 v198, v152, v198, v114
	v_fma_f32 v199, v152, v199, v115
	v_fma_f32 v202, v152, v202, v106
	v_fma_f32 v91, v94, v118, v140
	v_fma_f32 v68, v68, v195, v72
	v_fma_f32 v69, v69, v197, v73
	v_fma_f32 v92, v95, v119, v140
	v_fma_f32 v64, v64, v200, v68
	v_fma_f32 v65, v65, v201, v69
	v_fma_f32 v74, v74, v194, v91
	v_fma_f32 v75, v75, v196, v92
	v_fma_f32 v70, v70, v198, v74
	v_fma_f32 v71, v71, v199, v75
	v_add_f32_e32 v64, v64, v65
	v_fma_f32 v66, v66, v202, v70
	v_fma_f32 v67, v67, v203, v71
	v_add_f32_e32 v65, v66, v67
	v_add_f32_e32 v64, v64, v65
	s_nop 1
	v_add_f32_dpp v64, v64, v64 row_ror:8 row_mask:0xf bank_mask:0xf bound_ctrl:1
	s_nop 1
	v_add_f32_dpp v64, v64, v64 row_ror:4 row_mask:0xf bank_mask:0xf bound_ctrl:1
	s_nop 1
	v_add_f32_dpp v64, v64, v64 row_ror:2 row_mask:0xf bank_mask:0xf bound_ctrl:1
	s_nop 1
	v_add_f32_dpp v64, v64, v64 row_ror:1 row_mask:0xf bank_mask:0xf bound_ctrl:1
	ds_write_b32 v189, v64 offset:34176
	s_waitcnt lgkmcnt(0)
	v_mul_f32_e32 v69, v155, v88
	ds_read_b128 v[92:95], v188 offset:4096
	ds_read_b128 v[88:91], v188 offset:4352
	ds_read_b128 v[132:135], v188 offset:12288
	ds_read_b128 v[108:111], v188 offset:12544
	ds_read_b128 v[72:75], v188 offset:4608
	ds_read_b128 v[64:67], v188 offset:4864
	ds_read_b128 v[112:115], v188 offset:12800
	ds_read_b128 v[104:107], v188 offset:13056
	ds_read2_b32 v[152:153], v190 offset0:68 offset1:84
	ds_read_b32 v68, v189 offset:16640
	v_mul_f32 v70, v128, v69
	v_mul_f32 v71, v129, v69
	v_mul_f32 v130, v130, v69
	v_mul_f32 v131, v131, v69
	v_mul_f32 v120, v120, v69
	v_mul_f32 v121, v121, v69
	v_mul_f32 v122, v122, v69
	v_mul_f32 v123, v123, v69
	v_mul_f32 v124, v124, v69
	v_mul_f32 v125, v125, v69
	v_mul_f32 v126, v126, v69
	v_mul_f32 v127, v127, v69
	v_mul_f32 v100, v100, v69
	v_mul_f32 v101, v101, v69
	v_mul_f32 v102, v102, v69
	v_mul_f32 v69, v103, v69
	v_fma_f32 v128, v154, v116, v70
	v_fma_f32 v129, v154, v117, v71
	v_fma_f32 v130, v154, v118, v130
	v_fma_f32 v191, v154, v191, v120
	v_fma_f32 v193, v154, v193, v121
	v_fma_f32 v203, v154, v203, v69
	v_fma_f32 v69, v96, v128, v140
	v_fma_f32 v70, v97, v129, v140
	v_fma_f32 v71, v98, v130, v140
	v_fma_f32 v194, v154, v194, v122
	v_fma_f32 v195, v154, v195, v124
	v_fma_f32 v197, v154, v197, v125
	v_fma_f32 v69, v84, v191, v69
	v_fma_f32 v70, v85, v193, v70
	v_fma_f32 v198, v154, v198, v126
	v_fma_f32 v71, v86, v194, v71
	v_fma_f32 v200, v154, v200, v100
	v_fma_f32 v201, v154, v201, v101
	v_fma_f32 v69, v80, v195, v69
	v_fma_f32 v70, v81, v197, v70
	v_fma_f32 v131, v154, v119, v131
	v_fma_f32 v71, v82, v198, v71
	v_fma_f32 v196, v154, v196, v123
	v_fma_f32 v199, v154, v199, v127
	v_fma_f32 v69, v76, v200, v69
	v_fma_f32 v70, v77, v201, v70
	v_fma_f32 v202, v154, v202, v102
	v_fma_f32 v96, v99, v131, v140
	v_fma_f32 v84, v87, v196, v96
	v_fma_f32 v71, v78, v202, v71
	v_add_f32_e32 v69, v69, v70
	v_fma_f32 v80, v83, v199, v84
	v_fma_f32 v76, v79, v203, v80
	v_add_f32_e32 v70, v71, v76
	v_add_f32_e32 v69, v69, v70
	s_nop 1
	v_add_f32_dpp v69, v69, v69 row_ror:8 row_mask:0xf bank_mask:0xf bound_ctrl:1
	s_nop 1
	v_add_f32_dpp v69, v69, v69 row_ror:4 row_mask:0xf bank_mask:0xf bound_ctrl:1
	s_nop 1
	v_add_f32_dpp v69, v69, v69 row_ror:2 row_mask:0xf bank_mask:0xf bound_ctrl:1
	s_nop 1
	v_add_f32_dpp v69, v69, v69 row_ror:1 row_mask:0xf bank_mask:0xf bound_ctrl:1
	ds_write_b32 v189, v69 offset:34240
	s_waitcnt lgkmcnt(0)
	v_mul_f32_e32 v85, v153, v68
	ds_read_b128 v[96:99], v188 offset:5120
	ds_read_b128 v[80:83], v188 offset:5376
	ds_read_b128 v[124:127], v188 offset:13312
	ds_read_b128 v[116:119], v188 offset:13568
	ds_read_b128 v[76:79], v188 offset:5632
	ds_read_b128 v[68:71], v188 offset:5888
	ds_read_b128 v[120:123], v188 offset:13824
	ds_read_b128 v[100:103], v188 offset:14080
	ds_read2_b32 v[154:155], v190 offset0:69 offset1:85
	ds_read_b32 v84, v189 offset:16704
	v_mul_f32 v86, v132, v85
	v_mul_f32 v87, v133, v85
	v_mul_f32 v132, v134, v85
	v_mul_f32 v133, v135, v85
	v_mul_f32 v108, v108, v85
	v_mul_f32 v109, v109, v85
	v_mul_f32 v110, v110, v85
	v_mul_f32 v111, v111, v85
	v_mul_f32 v112, v112, v85
	v_mul_f32 v113, v113, v85
	v_mul_f32 v114, v114, v85
	v_mul_f32 v115, v115, v85
	v_mul_f32 v104, v104, v85
	v_mul_f32 v105, v105, v85
	v_mul_f32 v106, v106, v85
	v_mul_f32 v85, v107, v85
	v_fma_f32 v134, v152, v128, v86
	v_fma_f32 v135, v152, v129, v87
	v_fma_f32 v153, v152, v130, v132
	v_fma_f32 v204, v152, v131, v133
	v_fma_f32 v191, v152, v191, v108
	v_fma_f32 v193, v152, v193, v109
	v_fma_f32 v194, v152, v194, v110
	v_fma_f32 v196, v152, v196, v111
	v_fma_f32 v195, v152, v195, v112
	v_fma_f32 v197, v152, v197, v113
	v_fma_f32 v198, v152, v198, v114
	v_fma_f32 v199, v152, v199, v115
	v_fma_f32 v200, v152, v200, v104
	v_fma_f32 v201, v152, v201, v105
	v_fma_f32 v202, v152, v202, v106
	v_fma_f32 v152, v152, v203, v85
	v_fma_f32 v85, v92, v134, v140
	v_fma_f32 v86, v93, v135, v140
	v_fma_f32 v87, v94, v153, v140
	v_fma_f32 v92, v95, v204, v140
	v_fma_f32 v85, v88, v191, v85
	v_fma_f32 v86, v89, v193, v86
	v_fma_f32 v87, v90, v194, v87
	v_fma_f32 v88, v91, v196, v92
	v_fma_f32 v72, v72, v195, v85
	v_fma_f32 v73, v73, v197, v86
	v_fma_f32 v74, v74, v198, v87
	v_fma_f32 v75, v75, v199, v88
	v_fma_f32 v64, v64, v200, v72
	v_fma_f32 v65, v65, v201, v73
	v_fma_f32 v66, v66, v202, v74
	v_fma_f32 v67, v67, v152, v75
	v_add_f32_e32 v64, v64, v65
	v_add_f32_e32 v65, v66, v67
	v_add_f32_e32 v64, v64, v65
	s_nop 1
	v_add_f32_dpp v64, v64, v64 row_ror:8 row_mask:0xf bank_mask:0xf bound_ctrl:1
	s_nop 1
	v_add_f32_dpp v64, v64, v64 row_ror:4 row_mask:0xf bank_mask:0xf bound_ctrl:1
	s_nop 1
	v_add_f32_dpp v64, v64, v64 row_ror:2 row_mask:0xf bank_mask:0xf bound_ctrl:1
	s_nop 1
	v_add_f32_dpp v64, v64, v64 row_ror:1 row_mask:0xf bank_mask:0xf bound_ctrl:1
	ds_write_b32 v189, v64 offset:34304
	s_waitcnt lgkmcnt(0)
	v_mul_f32_e32 v93, v155, v84
	ds_read_b128 v[88:91], v188 offset:6144
	ds_read_b128 v[84:87], v188 offset:6400
	ds_read_b128 v[128:131], v188 offset:14336
	ds_read_b128 v[108:111], v188 offset:14592
	ds_read_b128 v[72:75], v188 offset:6656
	ds_read_b128 v[64:67], v188 offset:6912
	ds_read_b128 v[112:115], v188 offset:14848
	ds_read_b128 v[104:107], v188 offset:15104
	ds_read2_b32 v[132:133], v190 offset0:70 offset1:86
	ds_read_b32 v92, v189 offset:16768
	v_mul_f32 v94, v124, v93
	v_mul_f32 v95, v125, v93
	v_mul_f32 v124, v126, v93
	v_mul_f32 v125, v127, v93
	v_mul_f32 v116, v116, v93
	v_mul_f32 v117, v117, v93
	v_mul_f32 v118, v118, v93
	v_mul_f32 v119, v119, v93
	v_mul_f32 v120, v120, v93
	v_mul_f32 v121, v121, v93
	v_mul_f32 v122, v122, v93
	v_mul_f32 v123, v123, v93
	v_mul_f32 v100, v100, v93
	v_mul_f32 v101, v101, v93
	v_mul_f32 v102, v102, v93
	v_mul_f32 v93, v103, v93
	v_fma_f32 v126, v154, v134, v94
	v_fma_f32 v127, v154, v135, v95
	v_fma_f32 v134, v154, v153, v124
	v_fma_f32 v153, v154, v191, v116
	v_fma_f32 v155, v154, v193, v117
	v_fma_f32 v191, v154, v194, v118
	v_fma_f32 v193, v154, v196, v119
	v_fma_f32 v194, v154, v195, v120
	v_fma_f32 v195, v154, v197, v121
	v_fma_f32 v196, v154, v198, v122
	v_fma_f32 v197, v154, v199, v123
	v_fma_f32 v198, v154, v200, v100
	v_fma_f32 v199, v154, v201, v101
	v_fma_f32 v152, v154, v152, v93
	v_fma_f32 v93, v96, v126, v140
	v_fma_f32 v94, v97, v127, v140
	v_fma_f32 v135, v154, v204, v125
	v_fma_f32 v200, v154, v202, v102
	v_fma_f32 v95, v98, v134, v140
	v_fma_f32 v80, v80, v153, v93
	v_fma_f32 v81, v81, v155, v94
	v_fma_f32 v96, v99, v135, v140
	v_fma_f32 v76, v76, v194, v80
	v_fma_f32 v77, v77, v195, v81
	v_fma_f32 v82, v82, v191, v95
	v_fma_f32 v83, v83, v193, v96
	v_fma_f32 v68, v68, v198, v76
	v_fma_f32 v69, v69, v199, v77
	v_fma_f32 v78, v78, v196, v82
	v_fma_f32 v79, v79, v197, v83
	v_fma_f32 v70, v70, v200, v78
	v_fma_f32 v71, v71, v152, v79
	v_add_f32_e32 v68, v68, v69
	v_add_f32_e32 v69, v70, v71
	v_add_f32_e32 v68, v68, v69
	s_nop 1
	v_add_f32_dpp v68, v68, v68 row_ror:8 row_mask:0xf bank_mask:0xf bound_ctrl:1
	s_nop 1
	v_add_f32_dpp v68, v68, v68 row_ror:4 row_mask:0xf bank_mask:0xf bound_ctrl:1
	s_nop 1
	v_add_f32_dpp v68, v68, v68 row_ror:2 row_mask:0xf bank_mask:0xf bound_ctrl:1
	s_nop 1
	v_add_f32_dpp v68, v68, v68 row_ror:1 row_mask:0xf bank_mask:0xf bound_ctrl:1
	ds_write_b32 v189, v68 offset:34368
	s_waitcnt lgkmcnt(0)
	v_mul_f32_e32 v154, v133, v92
	ds_read_b128 v[92:95], v188 offset:7168
	ds_read_b128 v[80:83], v188 offset:7424
	ds_read_b128 v[120:123], v188 offset:15360
	ds_read_b128 v[100:103], v188 offset:15616
	ds_read_b128 v[76:79], v188 offset:7680
	ds_read_b128 v[68:71], v188 offset:7936
	ds_read_b128 v[116:119], v188 offset:15872
	ds_read_b128 v[96:99], v188 offset:16128
	ds_read2_b32 v[124:125], v190 offset0:71 offset1:87
	ds_read_b32 v133, v189 offset:16832
	v_mul_f32 v130, v130, v154
	v_mul_f32 v131, v131, v154
	v_mul_f32 v128, v128, v154
	v_mul_f32 v129, v129, v154
	v_mul_f32 v108, v108, v154
	v_mul_f32 v109, v109, v154
	v_mul_f32 v110, v110, v154
	v_mul_f32 v111, v111, v154
	v_mul_f32 v201, v112, v154
	v_mul_f32 v202, v113, v154
	v_mul_f32 v203, v114, v154
	v_mul_f32 v204, v115, v154
	v_mul_f32 v205, v104, v154
	v_mul_f32 v206, v105, v154
	v_mul_f32 v207, v106, v154
	v_mul_f32 v154, v107, v154
	v_fma_f32 v104, v132, v126, v128
	v_fma_f32 v105, v132, v127, v129
	v_fma_f32 v106, v132, v134, v130
	v_fma_f32 v107, v132, v135, v131
	v_fma_f32 v112, v132, v153, v108
	v_fma_f32 v113, v132, v155, v109
	v_fma_f32 v126, v132, v194, v201
	v_fma_f32 v127, v132, v195, v202
	v_fma_f32 v130, v132, v198, v205
	v_fma_f32 v131, v132, v199, v206
	v_fma_f32 v88, v88, v104, v140
	v_fma_f32 v89, v89, v105, v140
	v_fma_f32 v114, v132, v191, v110
	v_fma_f32 v115, v132, v193, v111
	v_fma_f32 v128, v132, v196, v203
	v_fma_f32 v129, v132, v197, v204
	v_fma_f32 v84, v84, v112, v88
	v_fma_f32 v85, v85, v113, v89
	v_fma_f32 v134, v132, v200, v207
	v_fma_f32 v132, v132, v152, v154
	v_fma_f32 v90, v90, v106, v140
	v_fma_f32 v91, v91, v107, v140
	v_fma_f32 v72, v72, v126, v84
	v_fma_f32 v73, v73, v127, v85
	v_fma_f32 v64, v64, v130, v72
	v_fma_f32 v65, v65, v131, v73
	v_fma_f32 v86, v86, v114, v90
	v_fma_f32 v87, v87, v115, v91
	v_fma_f32 v74, v74, v128, v86
	v_fma_f32 v75, v75, v129, v87
	v_add_f32_e32 v64, v64, v65
	v_fma_f32 v66, v66, v134, v74
	v_fma_f32 v67, v67, v132, v75
	v_add_f32_e32 v65, v66, v67
	v_add_f32_e32 v64, v64, v65
	s_nop 1
	v_add_f32_dpp v64, v64, v64 row_ror:8 row_mask:0xf bank_mask:0xf bound_ctrl:1
	s_nop 1
	v_add_f32_dpp v64, v64, v64 row_ror:4 row_mask:0xf bank_mask:0xf bound_ctrl:1
	s_nop 1
	v_add_f32_dpp v64, v64, v64 row_ror:2 row_mask:0xf bank_mask:0xf bound_ctrl:1
	s_nop 1
	v_add_f32_dpp v64, v64, v64 row_ror:1 row_mask:0xf bank_mask:0xf bound_ctrl:1
	ds_write_b32 v189, v64 offset:34432
	s_waitcnt lgkmcnt(0)
	v_mul_f32_e32 v64, v125, v133
	v_mul_f32 v65, v120, v64
	v_mul_f32 v66, v121, v64
	v_mul_f32 v67, v122, v64
	v_mul_f32 v72, v123, v64
	v_mul_f32 v73, v100, v64
	v_mul_f32 v74, v101, v64
	v_mul_f32 v75, v102, v64
	v_mul_f32 v84, v103, v64
	v_mul_f32 v85, v116, v64
	v_mul_f32 v86, v117, v64
	v_mul_f32 v87, v118, v64
	v_mul_f32 v88, v119, v64
	v_mul_f32 v89, v96, v64
	v_mul_f32 v90, v97, v64
	v_mul_f32 v100, v98, v64
	v_mul_f32 v64, v99, v64
	v_fma_f32 v111, v124, v104, v65
	v_fma_f32 v110, v124, v105, v66
	v_fma_f32 v96, v124, v129, v88
	v_fma_f32 v109, v124, v106, v67
	v_fma_f32 v108, v124, v107, v72
	v_fma_f32 v88, v124, v132, v64
	v_fma_f32 v64, v92, v111, v140
	v_fma_f32 v65, v93, v110, v140
	v_fma_f32 v107, v124, v112, v73
	v_fma_f32 v106, v124, v113, v74
	v_fma_f32 v66, v94, v109, v140
	v_fma_f32 v67, v95, v108, v140
	v_fma_f32 v105, v124, v114, v75
	v_fma_f32 v104, v124, v115, v84
	v_fma_f32 v64, v80, v107, v64
	v_fma_f32 v65, v81, v106, v65
	v_fma_f32 v99, v124, v126, v85
	v_fma_f32 v98, v124, v127, v86
	v_fma_f32 v66, v82, v105, v66
	v_fma_f32 v67, v83, v104, v67
	v_fma_f32 v97, v124, v128, v87
	v_fma_f32 v91, v124, v130, v89
	v_fma_f32 v64, v76, v99, v64
	v_fma_f32 v65, v77, v98, v65
	v_fma_f32 v90, v124, v131, v90
	v_fma_f32 v67, v79, v96, v67
	v_fma_f32 v66, v78, v97, v66
	v_fma_f32 v89, v124, v134, v100
	v_fma_f32 v64, v68, v91, v64
	v_fma_f32 v65, v69, v90, v65
	v_fma_f32 v67, v71, v88, v67
	v_fma_f32 v66, v70, v89, v66
	v_add_f32_e32 v64, v64, v65
	v_add_f32_e32 v65, v66, v67
	v_add_f32_e32 v64, v64, v65
	s_nop 1
	v_add_f32_dpp v64, v64, v64 row_ror:8 row_mask:0xf bank_mask:0xf bound_ctrl:1
	s_nop 1
	v_add_f32_dpp v64, v64, v64 row_ror:4 row_mask:0xf bank_mask:0xf bound_ctrl:1
	s_nop 1
	v_add_f32_dpp v64, v64, v64 row_ror:2 row_mask:0xf bank_mask:0xf bound_ctrl:1
	s_nop 1
	v_add_f32_dpp v64, v64, v64 row_ror:1 row_mask:0xf bank_mask:0xf bound_ctrl:1
	ds_write_b32 v189, v64 offset:34496
	s_waitcnt vmcnt(11)
	ds_write_b128 v185, v[16:19] offset:17024
	s_waitcnt vmcnt(9)
	ds_write_b128 v186, v[24:27] offset:17024
	ds_write_b128 v185, v[20:23] offset:25216
	s_waitcnt vmcnt(8)
	ds_write_b128 v186, v[28:31] offset:25216
	s_and_saveexec_b64 s[8:9], s[42:43]
	ds_write_b32 v144, v184 offset:33408
	s_or_b64 exec, exec, s[8:9]
	s_and_saveexec_b64 s[8:9], s[40:41]
	s_cbranch_execz .LBB0_1474
	v_add_f32_e32 v64, v156, v157
	v_mul_f32_e64 v65, |v64|, s62
	v_exp_f32_e32 v65, v65
	v_min_f32_e32 v64, 0, v64
	v_add_f32_e32 v65, 1.0, v65
	v_cmp_gt_f32_e32 vcc, s5, v65
	s_nop 1
	v_cndmask_b32_e64 v66, 0, 32, vcc
	v_ldexp_f32 v65, v65, v66
	v_log_f32_e32 v65, v65
	v_cndmask_b32_e32 v67, 0, v171, vcc
	v_add_f32_e32 v66, v145, v179
	v_mul_f32_e32 v68, 0x3f317217, v65
	v_fma_f32 v68, v65, s76, -v68
	v_fmac_f32_e32 v68, 0x3377d1cf, v65
	v_fmac_f32_e32 v68, 0x3f317217, v65
	v_cmp_lt_f32_e64 vcc, |v65|, s77
	s_nop 1
	v_cndmask_b32_e32 v65, v65, v68, vcc
	v_sub_f32_e32 v65, v65, v67
	v_sub_f32_e32 v64, v64, v65
	v_add_u32_e32 v65, 0x8400, v144
	ds_write2_b32 v65, v66, v64 offset0:32 offset1:48

.LBB0_1485:
	s_or_b64 exec, exec, s[8:9]
	s_waitcnt lgkmcnt(0)
	s_barrier
	ds_read_b128 v[92:95], v188 offset:17024
	ds_read_b128 v[112:115], v188 offset:17280
	ds_read_b128 v[124:127], v188 offset:25216
	ds_read_b128 v[132:135], v188 offset:25472
	ds_read2_b64 v[80:83], v190 offset0:32 offset1:40
	v_add_u32_e32 v191, 0x8000, v189
	ds_read2_b32 v[76:77], v191 offset0:160 offset1:176
	ds_read_b128 v[202:205], v188 offset:17536
	ds_read_b128 v[206:209], v188 offset:17792
	ds_read_b128 v[152:155], v188 offset:25728
	ds_read_b128 v[194:197], v188 offset:25984
	ds_read_b128 v[84:87], v188 offset:18048
	ds_read_b128 v[72:75], v188 offset:18304
	ds_read_b128 v[128:131], v188 offset:26240
	ds_read_b128 v[116:119], v188 offset:26496
	ds_read_b128 v[68:71], v188 offset:18560
	ds_read_b128 v[64:67], v188 offset:18816
	ds_read_b128 v[120:123], v188 offset:26752
	ds_read_b128 v[100:103], v188 offset:27008
	s_waitcnt lgkmcnt(12)
	v_mul_f32_e32 v76, v82, v76
	v_mul_f32 v78, v124, v76
	v_mul_f32 v79, v125, v76
	v_mul_f32 v124, v126, v76
	v_mul_f32 v125, v127, v76
	v_mul_f32 v126, v132, v76
	v_mul_f32 v127, v133, v76
	v_mul_f32 v193, v134, v76
	v_mul_f32 v198, v135, v76
	s_waitcnt lgkmcnt(9)
	v_mul_f32 v152, v152, v76
	v_mul_f32 v153, v153, v76
	v_mul_f32 v199, v154, v76
	v_mul_f32 v200, v155, v76
	s_waitcnt lgkmcnt(8)
	v_mul_f32 v201, v194, v76
	v_mul_f32 v210, v195, v76
	v_mul_f32 v211, v196, v76
	v_mul_f32 v76, v197, v76
	v_fma_f32 v82, v80, v111, v78
	v_fma_f32 v132, v80, v110, v79
	v_fma_f32 v133, v80, v109, v124
	v_fma_f32 v134, v80, v108, v125
	v_fma_f32 v135, v80, v107, v126
	v_fma_f32 v154, v80, v106, v127
	v_fma_f32 v155, v80, v105, v193
	v_fma_f32 v193, v80, v104, v198
	v_fma_f32 v194, v80, v99, v152
	v_fma_f32 v195, v80, v98, v153
	v_fma_f32 v196, v80, v97, v199
	v_fma_f32 v197, v80, v96, v200
	v_fma_f32 v198, v80, v91, v201
	v_fma_f32 v199, v80, v90, v210
	v_fma_f32 v200, v80, v89, v211
	v_fma_f32 v80, v80, v88, v76
	v_fma_f32 v76, v92, v82, v140
	v_fma_f32 v78, v93, v132, v140
	v_fma_f32 v79, v94, v133, v140
	v_fma_f32 v88, v95, v134, v140
	v_fma_f32 v76, v112, v135, v76
	v_fma_f32 v78, v113, v154, v78
	v_fma_f32 v79, v114, v155, v79
	v_fma_f32 v88, v115, v193, v88
	v_fma_f32 v76, v202, v194, v76
	v_fma_f32 v78, v203, v195, v78
	v_fma_f32 v79, v204, v196, v79
	v_fma_f32 v88, v205, v197, v88
	v_fma_f32 v76, v206, v198, v76
	v_fma_f32 v78, v207, v199, v78
	v_fma_f32 v79, v208, v200, v79
	v_fma_f32 v88, v209, v80, v88
	v_add_f32_e32 v76, v76, v78
	v_add_f32_e32 v78, v79, v88
	v_add_f32_e32 v76, v76, v78
	s_nop 1
	v_add_f32_dpp v76, v76, v76 row_ror:8 row_mask:0xf bank_mask:0xf bound_ctrl:1
	s_nop 1
	v_add_f32_dpp v76, v76, v76 row_ror:4 row_mask:0xf bank_mask:0xf bound_ctrl:1
	s_nop 1
	v_add_f32_dpp v76, v76, v76 row_ror:2 row_mask:0xf bank_mask:0xf bound_ctrl:1
	s_nop 1
	v_add_f32_dpp v76, v76, v76 row_ror:1 row_mask:0xf bank_mask:0xf bound_ctrl:1
	ds_write_b32 v189, v76 offset:34560
	v_mul_f32_e32 v201, v83, v77
	ds_read_b128 v[96:99], v188 offset:19072
	ds_read_b128 v[92:95], v188 offset:19328
	ds_read_b128 v[124:127], v188 offset:27264
	ds_read_b128 v[108:111], v188 offset:27520
	ds_read_b128 v[88:91], v188 offset:19584
	ds_read_b128 v[76:79], v188 offset:19840
	ds_read_b128 v[112:115], v188 offset:27776
	ds_read_b128 v[104:107], v188 offset:28032
	ds_read2_b32 v[152:153], v190 offset0:66 offset1:82
	ds_read_b32 v83, v189 offset:33536
	s_waitcnt lgkmcnt(14)
	v_mul_f32 v128, v128, v201
	v_mul_f32 v129, v129, v201
	v_mul_f32 v130, v130, v201
	v_mul_f32 v131, v131, v201
	v_mul_f32 v116, v116, v201
	v_mul_f32 v117, v117, v201
	v_mul_f32 v118, v118, v201
	v_mul_f32 v119, v119, v201
	s_waitcnt lgkmcnt(11)
	v_mul_f32 v120, v120, v201
	v_mul_f32 v121, v121, v201
	v_mul_f32 v122, v122, v201
	v_mul_f32 v123, v123, v201
	s_waitcnt lgkmcnt(10)
	v_mul_f32 v100, v100, v201
	v_mul_f32 v101, v101, v201
	v_mul_f32 v102, v102, v201
	v_mul_f32 v103, v103, v201
	v_fma_f32 v201, v81, v82, v128
	v_fma_f32 v202, v81, v132, v129
	v_fma_f32 v203, v81, v133, v130
	v_fma_f32 v204, v81, v134, v131
	v_fma_f32 v205, v81, v135, v116
	v_fma_f32 v206, v81, v154, v117
	v_fma_f32 v207, v81, v155, v118
	v_fma_f32 v193, v81, v193, v119
	v_fma_f32 v194, v81, v194, v120
	v_fma_f32 v195, v81, v195, v121
	v_fma_f32 v196, v81, v196, v122
	v_fma_f32 v197, v81, v197, v123
	v_fma_f32 v198, v81, v198, v100
	v_fma_f32 v199, v81, v199, v101
	v_fma_f32 v200, v81, v200, v102
	v_fma_f32 v208, v81, v80, v103
	v_fma_f32 v80, v84, v201, v140
	v_fma_f32 v81, v85, v202, v140
	v_fma_f32 v82, v86, v203, v140
	v_fma_f32 v84, v87, v204, v140
	v_fma_f32 v72, v72, v205, v80
	v_fma_f32 v73, v73, v206, v81
	v_fma_f32 v74, v74, v207, v82
	v_fma_f32 v75, v75, v193, v84
	v_fma_f32 v68, v68, v194, v72
	v_fma_f32 v69, v69, v195, v73
	v_fma_f32 v70, v70, v196, v74
	v_fma_f32 v71, v71, v197, v75
	v_fma_f32 v64, v64, v198, v68
	v_fma_f32 v65, v65, v199, v69
	v_fma_f32 v66, v66, v200, v70
	v_fma_f32 v67, v67, v208, v71
	v_add_f32_e32 v64, v64, v65
	v_add_f32_e32 v65, v66, v67
	v_add_f32_e32 v64, v64, v65
	s_nop 1
	v_add_f32_dpp v64, v64, v64 row_ror:8 row_mask:0xf bank_mask:0xf bound_ctrl:1
	s_nop 1
	v_add_f32_dpp v64, v64, v64 row_ror:4 row_mask:0xf bank_mask:0xf bound_ctrl:1
	s_nop 1
	v_add_f32_dpp v64, v64, v64 row_ror:2 row_mask:0xf bank_mask:0xf bound_ctrl:1
	s_nop 1
	v_add_f32_dpp v64, v64, v64 row_ror:1 row_mask:0xf bank_mask:0xf bound_ctrl:1
	ds_write_b32 v189, v64 offset:34624
	s_waitcnt lgkmcnt(0)
	v_mul_f32_e32 v69, v153, v83
	ds_read_b128 v[100:103], v188 offset:20096
	ds_read_b128 v[80:83], v188 offset:20352
	ds_read_b128 v[132:135], v188 offset:28288
	ds_read_b128 v[120:123], v188 offset:28544
	ds_read_b128 v[72:75], v188 offset:20608
	ds_read_b128 v[64:67], v188 offset:20864
	ds_read_b128 v[128:131], v188 offset:28800
	ds_read_b128 v[116:119], v188 offset:29056
	ds_read2_b32 v[154:155], v190 offset0:67 offset1:83
	ds_read_b32 v68, v189 offset:33600
	v_mul_f32 v70, v124, v69
	v_mul_f32 v71, v125, v69
	v_mul_f32 v84, v126, v69
	v_mul_f32 v85, v127, v69
	v_mul_f32 v86, v108, v69
	v_mul_f32 v87, v109, v69
	v_mul_f32 v108, v110, v69
	v_mul_f32 v109, v111, v69
	v_mul_f32 v110, v112, v69
	v_mul_f32 v111, v113, v69
	v_mul_f32 v124, v114, v69
	v_mul_f32 v125, v115, v69
	v_mul_f32 v104, v104, v69
	v_mul_f32 v105, v105, v69
	v_mul_f32 v106, v106, v69
	v_mul_f32 v69, v107, v69
	v_fma_f32 v112, v152, v201, v70
	v_fma_f32 v113, v152, v202, v71
	v_fma_f32 v115, v152, v204, v85
	v_fma_f32 v114, v152, v203, v84
	v_fma_f32 v201, v152, v205, v86
	v_fma_f32 v204, v152, v208, v69
	v_fma_f32 v69, v96, v112, v140
	v_fma_f32 v70, v97, v113, v140
	v_fma_f32 v202, v152, v206, v87
	v_fma_f32 v71, v98, v114, v140
	v_fma_f32 v203, v152, v207, v108
	v_fma_f32 v194, v152, v194, v110
	v_fma_f32 v69, v92, v201, v69
	v_fma_f32 v195, v152, v195, v111
	v_fma_f32 v70, v93, v202, v70
	v_fma_f32 v84, v99, v115, v140
	v_fma_f32 v71, v94, v203, v71
	v_fma_f32 v193, v152, v193, v109
	v_fma_f32 v69, v88, v194, v69
	v_fma_f32 v196, v152, v196, v124
	v_fma_f32 v70, v89, v195, v70
	v_fma_f32 v198, v152, v198, v104
	v_fma_f32 v199, v152, v199, v105
	v_fma_f32 v84, v95, v193, v84
	v_fma_f32 v197, v152, v197, v125
	v_fma_f32 v71, v90, v196, v71
	v_fma_f32 v200, v152, v200, v106
	v_fma_f32 v69, v76, v198, v69
	v_fma_f32 v70, v77, v199, v70
	v_fma_f32 v84, v91, v197, v84
	v_fma_f32 v71, v78, v200, v71
	v_fma_f32 v76, v79, v204, v84
	v_add_f32_e32 v69, v69, v70
	v_add_f32_e32 v70, v71, v76
	v_add_f32_e32 v69, v69, v70
	s_nop 1
	v_add_f32_dpp v69, v69, v69 row_ror:8 row_mask:0xf bank_mask:0xf bound_ctrl:1
	s_nop 1
	v_add_f32_dpp v69, v69, v69 row_ror:4 row_mask:0xf bank_mask:0xf bound_ctrl:1
	s_nop 1
	v_add_f32_dpp v69, v69, v69 row_ror:2 row_mask:0xf bank_mask:0xf bound_ctrl:1
	s_nop 1
	v_add_f32_dpp v69, v69, v69 row_ror:1 row_mask:0xf bank_mask:0xf bound_ctrl:1
	ds_write_b32 v189, v69 offset:34688
	s_waitcnt lgkmcnt(0)
	v_mul_f32_e32 v93, v155, v68
	ds_read_b128 v[88:91], v188 offset:21120
	ds_read_b128 v[84:87], v188 offset:21376
	ds_read_b128 v[124:127], v188 offset:29312
	ds_read_b128 v[104:107], v188 offset:29568
	ds_read_b128 v[76:79], v188 offset:21632
	ds_read_b128 v[68:71], v188 offset:21888
	ds_read_b128 v[108:111], v188 offset:29824
	ds_read_b128 v[96:99], v188 offset:30080
	ds_read2_b32 v[152:153], v190 offset0:68 offset1:84
	ds_read_b32 v92, v189 offset:33664
	v_mul_f32 v94, v132, v93
	v_mul_f32 v95, v133, v93
	v_mul_f32 v132, v134, v93
	v_mul_f32 v133, v135, v93
	v_mul_f32 v120, v120, v93
	v_mul_f32 v121, v121, v93
	v_mul_f32 v122, v122, v93
	v_mul_f32 v123, v123, v93
	v_mul_f32 v128, v128, v93
	v_mul_f32 v129, v129, v93
	v_mul_f32 v205, v130, v93
	v_mul_f32 v206, v131, v93
	v_mul_f32 v116, v116, v93
	v_mul_f32 v117, v117, v93
	v_mul_f32 v118, v118, v93
	v_mul_f32 v93, v119, v93
	v_fma_f32 v130, v154, v112, v94
	v_fma_f32 v131, v154, v113, v95
	v_fma_f32 v132, v154, v114, v132
	v_fma_f32 v133, v154, v115, v133
	v_fma_f32 v134, v154, v201, v120
	v_fma_f32 v135, v154, v202, v121
	v_fma_f32 v155, v154, v203, v122
	v_fma_f32 v193, v154, v193, v123
	v_fma_f32 v194, v154, v194, v128
	v_fma_f32 v195, v154, v195, v129
	v_fma_f32 v196, v154, v196, v205
	v_fma_f32 v197, v154, v197, v206
	v_fma_f32 v198, v154, v198, v116
	v_fma_f32 v199, v154, v199, v117
	v_fma_f32 v200, v154, v200, v118
	v_fma_f32 v154, v154, v204, v93
	v_fma_f32 v93, v100, v130, v140
	v_fma_f32 v94, v101, v131, v140
	v_fma_f32 v95, v102, v132, v140
	v_fma_f32 v100, v103, v133, v140
	v_fma_f32 v80, v80, v134, v93
	v_fma_f32 v81, v81, v135, v94
	v_fma_f32 v82, v82, v155, v95
	v_fma_f32 v83, v83, v193, v100
	v_fma_f32 v72, v72, v194, v80
	v_fma_f32 v73, v73, v195, v81
	v_fma_f32 v74, v74, v196, v82
	v_fma_f32 v75, v75, v197, v83
	v_fma_f32 v64, v64, v198, v72
	v_fma_f32 v65, v65, v199, v73
	v_fma_f32 v66, v66, v200, v74
	v_fma_f32 v67, v67, v154, v75
	v_add_f32_e32 v64, v64, v65
	v_add_f32_e32 v65, v66, v67
	v_add_f32_e32 v64, v64, v65
	s_nop 1
	v_add_f32_dpp v64, v64, v64 row_ror:8 row_mask:0xf bank_mask:0xf bound_ctrl:1
	s_nop 1
	v_add_f32_dpp v64, v64, v64 row_ror:4 row_mask:0xf bank_mask:0xf bound_ctrl:1
	s_nop 1
	v_add_f32_dpp v64, v64, v64 row_ror:2 row_mask:0xf bank_mask:0xf bound_ctrl:1
	s_nop 1
	v_add_f32_dpp v64, v64, v64 row_ror:1 row_mask:0xf bank_mask:0xf bound_ctrl:1
	ds_write_b32 v189, v64 offset:34752
	s_waitcnt lgkmcnt(0)
	v_mul_f32_e32 v153, v153, v92
	ds_read_b128 v[92:95], v188 offset:22144
	ds_read_b128 v[80:83], v188 offset:22400
	ds_read_b128 v[120:123], v188 offset:30336
	ds_read_b128 v[112:115], v188 offset:30592
	ds_read_b128 v[72:75], v188 offset:22656
	ds_read_b128 v[64:67], v188 offset:22912
	ds_read_b128 v[116:119], v188 offset:30848
	ds_read_b128 v[100:103], v188 offset:31104
	ds_read2_b32 v[128:129], v190 offset0:69 offset1:85
	ds_read_b32 v202, v189 offset:33728
	v_mul_f32 v124, v124, v153
	v_mul_f32 v125, v125, v153
	v_mul_f32 v126, v126, v153
	v_mul_f32 v127, v127, v153
	v_mul_f32 v104, v104, v153
	v_mul_f32 v105, v105, v153
	v_mul_f32 v106, v106, v153
	v_mul_f32 v107, v107, v153
	v_mul_f32 v108, v108, v153
	v_mul_f32 v109, v109, v153
	v_mul_f32 v110, v110, v153
	v_mul_f32 v111, v111, v153
	v_mul_f32 v96, v96, v153
	v_mul_f32 v97, v97, v153
	v_mul_f32 v98, v98, v153
	v_mul_f32 v99, v99, v153
	v_fma_f32 v153, v152, v130, v124
	v_fma_f32 v201, v152, v131, v125
	v_fma_f32 v134, v152, v134, v104
	v_fma_f32 v135, v152, v135, v105
	v_fma_f32 v194, v152, v194, v108
	v_fma_f32 v195, v152, v195, v109
	v_fma_f32 v198, v152, v198, v96
	v_fma_f32 v199, v152, v199, v97
	v_fma_f32 v88, v88, v153, v140
	v_fma_f32 v89, v89, v201, v140
	v_fma_f32 v132, v152, v132, v126
	v_fma_f32 v133, v152, v133, v127
	v_fma_f32 v155, v152, v155, v106
	v_fma_f32 v193, v152, v193, v107
	v_fma_f32 v84, v84, v134, v88
	v_fma_f32 v85, v85, v135, v89
	v_fma_f32 v196, v152, v196, v110
	v_fma_f32 v197, v152, v197, v111
	v_fma_f32 v200, v152, v200, v98
	v_fma_f32 v152, v152, v154, v99
	v_fma_f32 v76, v76, v194, v84
	v_fma_f32 v77, v77, v195, v85
	v_fma_f32 v90, v90, v132, v140
	v_fma_f32 v91, v91, v133, v140
	v_fma_f32 v68, v68, v198, v76
	v_fma_f32 v69, v69, v199, v77
	v_fma_f32 v86, v86, v155, v90
	v_fma_f32 v87, v87, v193, v91
	v_fma_f32 v78, v78, v196, v86
	v_fma_f32 v79, v79, v197, v87
	v_add_f32_e32 v68, v68, v69
	v_fma_f32 v70, v70, v200, v78
	v_fma_f32 v71, v71, v152, v79
	v_add_f32_e32 v69, v70, v71
	v_add_f32_e32 v68, v68, v69
	s_nop 1
	v_add_f32_dpp v68, v68, v68 row_ror:8 row_mask:0xf bank_mask:0xf bound_ctrl:1
	s_nop 1
	v_add_f32_dpp v68, v68, v68 row_ror:4 row_mask:0xf bank_mask:0xf bound_ctrl:1
	s_nop 1
	v_add_f32_dpp v68, v68, v68 row_ror:2 row_mask:0xf bank_mask:0xf bound_ctrl:1
	s_nop 1
	v_add_f32_dpp v68, v68, v68 row_ror:1 row_mask:0xf bank_mask:0xf bound_ctrl:1
	ds_write_b32 v189, v68 offset:34816
	s_waitcnt lgkmcnt(0)
	v_mul_f32_e32 v154, v129, v202
	ds_read_b128 v[88:91], v188 offset:23168
	ds_read_b128 v[84:87], v188 offset:23424
	ds_read_b128 v[124:127], v188 offset:31360
	ds_read_b128 v[104:107], v188 offset:31616
	ds_read_b128 v[76:79], v188 offset:23680
	ds_read_b128 v[68:71], v188 offset:23936
	ds_read_b128 v[108:111], v188 offset:31872
	ds_read_b128 v[96:99], v188 offset:32128
	ds_read2_b32 v[130:131], v190 offset0:70 offset1:86
	ds_read_b32 v129, v189 offset:33792
	v_mul_f32 v120, v120, v154
	v_mul_f32 v121, v121, v154
	v_mul_f32 v122, v122, v154
	v_mul_f32 v123, v123, v154
	v_mul_f32 v112, v112, v154
	v_mul_f32 v113, v113, v154
	v_mul_f32 v114, v114, v154
	v_mul_f32 v115, v115, v154
	v_mul_f32 v116, v116, v154
	v_mul_f32 v117, v117, v154
	v_mul_f32 v118, v118, v154
	v_mul_f32 v119, v119, v154
	v_mul_f32 v100, v100, v154
	v_mul_f32 v101, v101, v154
	v_mul_f32 v102, v102, v154
	v_mul_f32 v103, v103, v154
	v_fma_f32 v153, v128, v153, v120
	v_fma_f32 v154, v128, v201, v121
	v_fma_f32 v134, v128, v134, v112
	v_fma_f32 v135, v128, v135, v113
	v_fma_f32 v194, v128, v194, v116
	v_fma_f32 v195, v128, v195, v117
	v_fma_f32 v198, v128, v198, v100
	v_fma_f32 v199, v128, v199, v101
	v_fma_f32 v92, v92, v153, v140
	v_fma_f32 v93, v93, v154, v140
	v_fma_f32 v132, v128, v132, v122
	v_fma_f32 v133, v128, v133, v123
	v_fma_f32 v155, v128, v155, v114
	v_fma_f32 v193, v128, v193, v115
	v_fma_f32 v80, v80, v134, v92
	v_fma_f32 v81, v81, v135, v93
	v_fma_f32 v196, v128, v196, v118
	v_fma_f32 v197, v128, v197, v119
	v_fma_f32 v200, v128, v200, v102
	v_fma_f32 v152, v128, v152, v103
	v_fma_f32 v72, v72, v194, v80
	v_fma_f32 v73, v73, v195, v81
	v_fma_f32 v94, v94, v132, v140
	v_fma_f32 v95, v95, v133, v140
	v_fma_f32 v64, v64, v198, v72
	v_fma_f32 v65, v65, v199, v73
	v_fma_f32 v82, v82, v155, v94
	v_fma_f32 v83, v83, v193, v95
	v_fma_f32 v74, v74, v196, v82
	v_fma_f32 v75, v75, v197, v83
	v_add_f32_e32 v64, v64, v65
	v_fma_f32 v66, v66, v200, v74
	v_fma_f32 v67, v67, v152, v75
	v_add_f32_e32 v65, v66, v67
	v_add_f32_e32 v64, v64, v65
	s_nop 1
	v_add_f32_dpp v64, v64, v64 row_ror:8 row_mask:0xf bank_mask:0xf bound_ctrl:1
	s_nop 1
	v_add_f32_dpp v64, v64, v64 row_ror:4 row_mask:0xf bank_mask:0xf bound_ctrl:1
	s_nop 1
	v_add_f32_dpp v64, v64, v64 row_ror:2 row_mask:0xf bank_mask:0xf bound_ctrl:1
	s_nop 1
	v_add_f32_dpp v64, v64, v64 row_ror:1 row_mask:0xf bank_mask:0xf bound_ctrl:1
	ds_write_b32 v189, v64 offset:34880
	s_waitcnt lgkmcnt(0)
	v_mul_f32_e32 v201, v131, v129
	ds_read_b128 v[92:95], v188 offset:24192
	ds_read_b128 v[80:83], v188 offset:24448
	ds_read_b128 v[120:123], v188 offset:32384
	ds_read_b128 v[112:115], v188 offset:32640
	ds_read_b128 v[72:75], v188 offset:24704
	ds_read_b128 v[64:67], v188 offset:24960
	ds_read_b128 v[116:119], v188 offset:32896
	ds_read_b128 v[100:103], v188 offset:33152
	ds_read2_b32 v[128:129], v190 offset0:71 offset1:87
	ds_read_b32 v131, v189 offset:33856
	v_mul_f32 v125, v125, v201
	v_mul_f32 v126, v126, v201
	v_mul_f32 v104, v104, v201
	v_mul_f32 v124, v124, v201
	v_mul_f32 v127, v127, v201
	v_mul_f32 v105, v105, v201
	v_mul_f32 v106, v106, v201
	v_mul_f32 v107, v107, v201
	v_mul_f32 v108, v108, v201
	v_mul_f32 v109, v109, v201
	v_mul_f32 v202, v110, v201
	v_mul_f32 v203, v111, v201
	v_mul_f32 v204, v96, v201
	v_mul_f32 v205, v97, v201
	v_mul_f32 v206, v98, v201
	v_mul_f32 v201, v99, v201
	v_fma_f32 v96, v130, v153, v124
	v_fma_f32 v97, v130, v154, v125
	v_fma_f32 v98, v130, v132, v126
	v_fma_f32 v99, v130, v133, v127
	v_fma_f32 v104, v130, v134, v104
	v_fma_f32 v110, v130, v135, v105
	v_fma_f32 v125, v130, v194, v108
	v_fma_f32 v126, v130, v195, v109
	v_fma_f32 v133, v130, v198, v204
	v_fma_f32 v134, v130, v199, v205
	v_fma_f32 v88, v88, v96, v140
	v_fma_f32 v89, v89, v97, v140
	v_fma_f32 v111, v130, v155, v106
	v_fma_f32 v124, v130, v193, v107
	v_fma_f32 v127, v130, v196, v202
	v_fma_f32 v132, v130, v197, v203
	v_fma_f32 v84, v84, v104, v88
	v_fma_f32 v85, v85, v110, v89
	v_fma_f32 v135, v130, v200, v206
	v_fma_f32 v130, v130, v152, v201
	v_fma_f32 v90, v90, v98, v140
	v_fma_f32 v91, v91, v99, v140
	v_fma_f32 v76, v76, v125, v84
	v_fma_f32 v77, v77, v126, v85
	v_fma_f32 v68, v68, v133, v76
	v_fma_f32 v69, v69, v134, v77
	v_fma_f32 v86, v86, v111, v90
	v_fma_f32 v87, v87, v124, v91
	v_fma_f32 v78, v78, v127, v86
	v_fma_f32 v79, v79, v132, v87
	v_add_f32_e32 v68, v68, v69
	v_fma_f32 v70, v70, v135, v78
	v_fma_f32 v71, v71, v130, v79
	v_add_f32_e32 v69, v70, v71
	v_add_f32_e32 v68, v68, v69
	s_nop 1
	v_add_f32_dpp v68, v68, v68 row_ror:8 row_mask:0xf bank_mask:0xf bound_ctrl:1
	s_nop 1
	v_add_f32_dpp v68, v68, v68 row_ror:4 row_mask:0xf bank_mask:0xf bound_ctrl:1
	s_nop 1
	v_add_f32_dpp v68, v68, v68 row_ror:2 row_mask:0xf bank_mask:0xf bound_ctrl:1
	s_nop 1
	v_add_f32_dpp v68, v68, v68 row_ror:1 row_mask:0xf bank_mask:0xf bound_ctrl:1
	ds_write_b32 v189, v68 offset:34944
	s_waitcnt lgkmcnt(0)
	v_mul_f32_e32 v68, v129, v131
	v_mul_f32 v69, v120, v68
	v_mul_f32 v70, v121, v68
	v_mul_f32 v71, v122, v68
	v_mul_f32 v76, v123, v68
	v_mul_f32 v77, v112, v68
	v_mul_f32 v78, v113, v68
	v_mul_f32 v79, v114, v68
	v_mul_f32 v84, v115, v68
	v_mul_f32 v85, v116, v68
	v_mul_f32 v86, v117, v68
	v_mul_f32 v87, v118, v68
	v_mul_f32 v88, v119, v68
	v_mul_f32 v89, v100, v68
	v_mul_f32 v100, v101, v68
	v_mul_f32 v101, v102, v68
	v_mul_f32 v68, v103, v68
	v_fma_f32 v109, v128, v96, v69
	v_fma_f32 v108, v128, v97, v70
	v_fma_f32 v105, v128, v104, v77
	v_fma_f32 v104, v128, v110, v78
	v_fma_f32 v107, v128, v98, v71
	v_fma_f32 v78, v128, v130, v68
	v_fma_f32 v68, v92, v109, v140
	v_fma_f32 v69, v93, v108, v140
	v_fma_f32 v106, v128, v99, v76
	v_fma_f32 v99, v128, v111, v79
	v_fma_f32 v70, v94, v107, v140
	v_fma_f32 v98, v128, v124, v84
	v_fma_f32 v68, v80, v105, v68
	v_fma_f32 v69, v81, v104, v69
	v_fma_f32 v71, v95, v106, v140
	v_fma_f32 v97, v128, v125, v85
	v_fma_f32 v96, v128, v126, v86
	v_fma_f32 v90, v128, v132, v88
	v_fma_f32 v89, v128, v133, v89
	v_fma_f32 v88, v128, v134, v100
	v_fma_f32 v70, v82, v99, v70
	v_fma_f32 v71, v83, v98, v71
	v_fma_f32 v68, v72, v97, v68
	v_fma_f32 v69, v73, v96, v69
	v_fma_f32 v91, v128, v127, v87
	v_fma_f32 v79, v128, v135, v101
	v_fma_f32 v71, v75, v90, v71
	v_fma_f32 v64, v64, v89, v68
	v_fma_f32 v65, v65, v88, v69
	v_fma_f32 v70, v74, v91, v70
	v_fma_f32 v66, v66, v79, v70
	v_fma_f32 v67, v67, v78, v71
	v_add_f32_e32 v64, v64, v65
	v_add_f32_e32 v65, v66, v67
	v_add_f32_e32 v64, v64, v65
	s_nop 1
	v_add_f32_dpp v64, v64, v64 row_ror:8 row_mask:0xf bank_mask:0xf bound_ctrl:1
	s_nop 1
	v_add_f32_dpp v64, v64, v64 row_ror:4 row_mask:0xf bank_mask:0xf bound_ctrl:1
	s_nop 1
	v_add_f32_dpp v64, v64, v64 row_ror:2 row_mask:0xf bank_mask:0xf bound_ctrl:1
	s_nop 1
	v_add_f32_dpp v64, v64, v64 row_ror:1 row_mask:0xf bank_mask:0xf bound_ctrl:1
	ds_write_b32 v189, v64 offset:35008
	s_waitcnt vmcnt(7)
	ds_write_b128 v185, v[32:35]
	s_waitcnt vmcnt(5)
	ds_write_b128 v186, v[40:43]
	ds_write_b128 v185, v[36:39] offset:8192
	s_waitcnt vmcnt(4)
	ds_write_b128 v186, v[44:47] offset:8192
	s_and_saveexec_b64 s[8:9], s[42:43]
	ds_write_b32 v144, v184 offset:16384
	s_or_b64 exec, exec, s[8:9]
	s_and_saveexec_b64 s[8:9], s[40:41]
	s_cbranch_execz .LBB0_1505
	v_add_f32_e32 v64, v156, v182
	v_mul_f32_e64 v65, |v64|, s62
	v_exp_f32_e32 v65, v65
	v_min_f32_e32 v64, 0, v64
	v_add_f32_e32 v65, 1.0, v65
	v_cmp_gt_f32_e32 vcc, s5, v65
	s_nop 1
	v_cndmask_b32_e64 v66, 0, 32, vcc
	v_ldexp_f32 v65, v65, v66
	v_log_f32_e32 v65, v65
	v_cndmask_b32_e32 v67, 0, v171, vcc
	v_add_f32_e32 v66, v145, v180
	v_mul_f32_e32 v68, 0x3f317217, v65
	v_fma_f32 v68, v65, s76, -v68
	v_fmac_f32_e32 v68, 0x3377d1cf, v65
	v_fmac_f32_e32 v68, 0x3f317217, v65
	v_cmp_lt_f32_e64 vcc, |v65|, s77
	s_nop 1
	v_cndmask_b32_e32 v65, v65, v68, vcc
	v_sub_f32_e32 v65, v65, v67
	v_sub_f32_e32 v64, v64, v65
	v_add_u32_e32 v65, 0x4000, v144
	ds_write2_b32 v65, v66, v64 offset0:128 offset1:144

.LBB0_1516:
	s_or_b64 exec, exec, s[8:9]
	s_waitcnt lgkmcnt(0)
	s_barrier
	ds_read_b128 v[92:95], v188
	ds_read_b128 v[110:113], v188 offset:256
	ds_read_b128 v[124:127], v188 offset:8192
	ds_read_b128 v[132:135], v188 offset:8448
	ds_read2_b64 v[80:83], v190 offset0:32 offset1:40
	ds_read2_b32 v[76:77], v192 offset1:16
	ds_read_b128 v[200:203], v188 offset:512
	ds_read_b128 v[204:207], v188 offset:768
	ds_read_b128 v[152:155], v188 offset:8704
	ds_read_b128 v[192:195], v188 offset:8960
	s_waitcnt lgkmcnt(4)
	v_mul_f32_e32 v76, v82, v76
	v_mul_f32 v82, v124, v76
	v_mul_f32 v114, v125, v76
	v_mul_f32 v115, v126, v76
	v_mul_f32 v124, v127, v76
	v_mul_f32 v125, v132, v76
	v_mul_f32 v126, v133, v76
	v_mul_f32 v127, v134, v76
	v_mul_f32 v196, v135, v76
	s_waitcnt lgkmcnt(1)
	v_mul_f32 v152, v152, v76
	v_mul_f32 v153, v153, v76
	v_mul_f32 v197, v154, v76
	v_mul_f32 v198, v155, v76
	s_waitcnt lgkmcnt(0)
	v_mul_f32 v199, v192, v76
	v_mul_f32 v208, v193, v76
	v_mul_f32 v209, v194, v76
	v_mul_f32 v76, v195, v76
	ds_read_b128 v[84:87], v188 offset:1024
	ds_read_b128 v[72:75], v188 offset:1280
	ds_read_b128 v[128:131], v188 offset:9216
	ds_read_b128 v[116:119], v188 offset:9472
	ds_read_b128 v[68:71], v188 offset:1536
	ds_read_b128 v[64:67], v188 offset:1792
	ds_read_b128 v[120:123], v188 offset:9728
	ds_read_b128 v[100:103], v188 offset:9984
	v_fma_f32 v82, v80, v109, v82
	v_fma_f32 v132, v80, v108, v114
	v_fma_f32 v133, v80, v107, v115
	v_fma_f32 v134, v80, v106, v124
	v_fma_f32 v135, v80, v105, v125
	v_fma_f32 v154, v80, v104, v126
	v_fma_f32 v155, v80, v99, v127
	v_fma_f32 v192, v80, v98, v196
	v_fma_f32 v193, v80, v97, v152
	v_fma_f32 v194, v80, v96, v153
	v_fma_f32 v195, v80, v91, v197
	v_fma_f32 v196, v80, v90, v198
	v_fma_f32 v197, v80, v89, v199
	v_fma_f32 v198, v80, v88, v208
	v_fma_f32 v199, v80, v79, v209
	v_fma_f32 v80, v80, v78, v76
	v_fma_f32 v76, v92, v82, v140
	v_fma_f32 v78, v93, v132, v140
	v_fma_f32 v79, v94, v133, v140
	v_fma_f32 v88, v95, v134, v140
	v_fma_f32 v76, v110, v135, v76
	v_fma_f32 v78, v111, v154, v78
	v_fma_f32 v79, v112, v155, v79
	v_fma_f32 v88, v113, v192, v88
	v_fma_f32 v76, v200, v193, v76
	v_fma_f32 v78, v201, v194, v78
	v_fma_f32 v79, v202, v195, v79
	v_fma_f32 v88, v203, v196, v88
	v_fma_f32 v76, v204, v197, v76
	v_fma_f32 v78, v205, v198, v78
	v_fma_f32 v79, v206, v199, v79
	v_fma_f32 v88, v207, v80, v88
	v_add_f32_e32 v76, v76, v78
	v_add_f32_e32 v78, v79, v88
	v_add_f32_e32 v76, v76, v78
	s_nop 1
	v_add_f32_dpp v76, v76, v76 row_ror:8 row_mask:0xf bank_mask:0xf bound_ctrl:1
	s_nop 1
	v_add_f32_dpp v76, v76, v76 row_ror:4 row_mask:0xf bank_mask:0xf bound_ctrl:1
	s_nop 1
	v_add_f32_dpp v76, v76, v76 row_ror:2 row_mask:0xf bank_mask:0xf bound_ctrl:1
	s_nop 1
	v_add_f32_dpp v76, v76, v76 row_ror:1 row_mask:0xf bank_mask:0xf bound_ctrl:1
	ds_write_b32 v189, v76 offset:34048
	v_mul_f32_e32 v200, v83, v77
	ds_read_b128 v[96:99], v188 offset:2048
	ds_read_b128 v[92:95], v188 offset:2304
	ds_read_b128 v[124:127], v188 offset:10240
	ds_read_b128 v[108:111], v188 offset:10496
	ds_read_b128 v[88:91], v188 offset:2560
	ds_read_b128 v[76:79], v188 offset:2816
	ds_read_b128 v[112:115], v188 offset:10752
	ds_read_b128 v[104:107], v188 offset:11008
	ds_read2_b32 v[152:153], v190 offset0:66 offset1:82
	ds_read_b32 v83, v189 offset:16512
	s_waitcnt lgkmcnt(14)
	v_mul_f32 v128, v128, v200
	v_mul_f32 v129, v129, v200
	v_mul_f32 v130, v130, v200
	v_mul_f32 v131, v131, v200
	v_mul_f32 v116, v116, v200
	v_mul_f32 v117, v117, v200
	v_mul_f32 v118, v118, v200
	v_mul_f32 v119, v119, v200
	s_waitcnt lgkmcnt(11)
	v_mul_f32 v120, v120, v200
	v_mul_f32 v121, v121, v200
	v_mul_f32 v122, v122, v200
	v_mul_f32 v123, v123, v200
	s_waitcnt lgkmcnt(10)
	v_mul_f32 v100, v100, v200
	v_mul_f32 v101, v101, v200
	v_mul_f32 v102, v102, v200
	v_mul_f32 v103, v103, v200
	v_fma_f32 v200, v81, v82, v128
	v_fma_f32 v201, v81, v132, v129
	v_fma_f32 v202, v81, v133, v130
	v_fma_f32 v203, v81, v134, v131
	v_fma_f32 v204, v81, v135, v116
	v_fma_f32 v205, v81, v154, v117
	v_fma_f32 v206, v81, v155, v118
	v_fma_f32 v192, v81, v192, v119
	v_fma_f32 v193, v81, v193, v120
	v_fma_f32 v194, v81, v194, v121
	v_fma_f32 v195, v81, v195, v122
	v_fma_f32 v196, v81, v196, v123
	v_fma_f32 v197, v81, v197, v100
	v_fma_f32 v198, v81, v198, v101
	v_fma_f32 v199, v81, v199, v102
	v_fma_f32 v207, v81, v80, v103
	v_fma_f32 v80, v84, v200, v140
	v_fma_f32 v81, v85, v201, v140
	v_fma_f32 v82, v86, v202, v140
	v_fma_f32 v84, v87, v203, v140
	v_fma_f32 v72, v72, v204, v80
	v_fma_f32 v73, v73, v205, v81
	v_fma_f32 v74, v74, v206, v82
	v_fma_f32 v75, v75, v192, v84
	v_fma_f32 v68, v68, v193, v72
	v_fma_f32 v69, v69, v194, v73
	v_fma_f32 v70, v70, v195, v74
	v_fma_f32 v71, v71, v196, v75
	v_fma_f32 v64, v64, v197, v68
	v_fma_f32 v65, v65, v198, v69
	v_fma_f32 v66, v66, v199, v70
	v_fma_f32 v67, v67, v207, v71
	v_add_f32_e32 v64, v64, v65
	v_add_f32_e32 v65, v66, v67
	v_add_f32_e32 v64, v64, v65
	s_nop 1
	v_add_f32_dpp v64, v64, v64 row_ror:8 row_mask:0xf bank_mask:0xf bound_ctrl:1
	s_nop 1
	v_add_f32_dpp v64, v64, v64 row_ror:4 row_mask:0xf bank_mask:0xf bound_ctrl:1
	s_nop 1
	v_add_f32_dpp v64, v64, v64 row_ror:2 row_mask:0xf bank_mask:0xf bound_ctrl:1
	s_nop 1
	v_add_f32_dpp v64, v64, v64 row_ror:1 row_mask:0xf bank_mask:0xf bound_ctrl:1
	ds_write_b32 v189, v64 offset:34112
	s_waitcnt lgkmcnt(0)
	v_mul_f32_e32 v69, v153, v83
	ds_read_b128 v[100:103], v188 offset:3072
	ds_read_b128 v[80:83], v188 offset:3328
	ds_read_b128 v[132:135], v188 offset:11264
	ds_read_b128 v[120:123], v188 offset:11520
	ds_read_b128 v[72:75], v188 offset:3584
	ds_read_b128 v[64:67], v188 offset:3840
	ds_read_b128 v[128:131], v188 offset:11776
	ds_read_b128 v[116:119], v188 offset:12032
	ds_read2_b32 v[154:155], v190 offset0:67 offset1:83
	ds_read_b32 v68, v189 offset:16576
	v_mul_f32 v70, v124, v69
	v_mul_f32 v71, v125, v69
	v_mul_f32 v84, v126, v69
	v_mul_f32 v85, v127, v69
	v_mul_f32 v86, v108, v69
	v_mul_f32 v87, v109, v69
	v_mul_f32 v108, v110, v69
	v_mul_f32 v109, v111, v69
	v_mul_f32 v110, v112, v69
	v_mul_f32 v111, v113, v69
	v_mul_f32 v124, v114, v69
	v_mul_f32 v125, v115, v69
	v_mul_f32 v104, v104, v69
	v_mul_f32 v105, v105, v69
	v_mul_f32 v106, v106, v69
	v_mul_f32 v69, v107, v69
	v_fma_f32 v112, v152, v200, v70
	v_fma_f32 v113, v152, v201, v71
	v_fma_f32 v115, v152, v203, v85
	v_fma_f32 v114, v152, v202, v84
	v_fma_f32 v200, v152, v204, v86
	v_fma_f32 v203, v152, v207, v69
	v_fma_f32 v69, v96, v112, v140
	v_fma_f32 v70, v97, v113, v140
	v_fma_f32 v201, v152, v205, v87
	v_fma_f32 v71, v98, v114, v140
	v_fma_f32 v202, v152, v206, v108
	v_fma_f32 v193, v152, v193, v110
	v_fma_f32 v69, v92, v200, v69
	v_fma_f32 v194, v152, v194, v111
	v_fma_f32 v70, v93, v201, v70
	v_fma_f32 v84, v99, v115, v140
	v_fma_f32 v71, v94, v202, v71
	v_fma_f32 v192, v152, v192, v109
	v_fma_f32 v69, v88, v193, v69
	v_fma_f32 v195, v152, v195, v124
	v_fma_f32 v70, v89, v194, v70
	v_fma_f32 v197, v152, v197, v104
	v_fma_f32 v198, v152, v198, v105
	v_fma_f32 v84, v95, v192, v84
	v_fma_f32 v196, v152, v196, v125
	v_fma_f32 v71, v90, v195, v71
	v_fma_f32 v199, v152, v199, v106
	v_fma_f32 v69, v76, v197, v69
	v_fma_f32 v70, v77, v198, v70
	v_fma_f32 v84, v91, v196, v84
	v_fma_f32 v71, v78, v199, v71
	v_fma_f32 v76, v79, v203, v84
	v_add_f32_e32 v69, v69, v70
	v_add_f32_e32 v70, v71, v76
	v_add_f32_e32 v69, v69, v70
	s_nop 1
	v_add_f32_dpp v69, v69, v69 row_ror:8 row_mask:0xf bank_mask:0xf bound_ctrl:1
	s_nop 1
	v_add_f32_dpp v69, v69, v69 row_ror:4 row_mask:0xf bank_mask:0xf bound_ctrl:1
	s_nop 1
	v_add_f32_dpp v69, v69, v69 row_ror:2 row_mask:0xf bank_mask:0xf bound_ctrl:1
	s_nop 1
	v_add_f32_dpp v69, v69, v69 row_ror:1 row_mask:0xf bank_mask:0xf bound_ctrl:1
	ds_write_b32 v189, v69 offset:34176
	s_waitcnt lgkmcnt(0)
	v_mul_f32_e32 v93, v155, v68
	ds_read_b128 v[88:91], v188 offset:4096
	ds_read_b128 v[84:87], v188 offset:4352
	ds_read_b128 v[124:127], v188 offset:12288
	ds_read_b128 v[104:107], v188 offset:12544
	ds_read_b128 v[76:79], v188 offset:4608
	ds_read_b128 v[68:71], v188 offset:4864
	ds_read_b128 v[108:111], v188 offset:12800
	ds_read_b128 v[96:99], v188 offset:13056
	ds_read2_b32 v[152:153], v190 offset0:68 offset1:84
	ds_read_b32 v92, v189 offset:16640
	v_mul_f32 v94, v132, v93
	v_mul_f32 v95, v133, v93
	v_mul_f32 v132, v134, v93
	v_mul_f32 v133, v135, v93
	v_mul_f32 v120, v120, v93
	v_mul_f32 v121, v121, v93
	v_mul_f32 v122, v122, v93
	v_mul_f32 v123, v123, v93
	v_mul_f32 v128, v128, v93
	v_mul_f32 v129, v129, v93
	v_mul_f32 v204, v130, v93
	v_mul_f32 v205, v131, v93
	v_mul_f32 v116, v116, v93
	v_mul_f32 v117, v117, v93
	v_mul_f32 v118, v118, v93
	v_mul_f32 v93, v119, v93
	v_fma_f32 v130, v154, v112, v94
	v_fma_f32 v131, v154, v113, v95
	v_fma_f32 v132, v154, v114, v132
	v_fma_f32 v133, v154, v115, v133
	v_fma_f32 v134, v154, v200, v120
	v_fma_f32 v135, v154, v201, v121
	v_fma_f32 v155, v154, v202, v122
	v_fma_f32 v192, v154, v192, v123
	v_fma_f32 v193, v154, v193, v128
	v_fma_f32 v194, v154, v194, v129
	v_fma_f32 v195, v154, v195, v204
	v_fma_f32 v196, v154, v196, v205
	v_fma_f32 v197, v154, v197, v116
	v_fma_f32 v198, v154, v198, v117
	v_fma_f32 v199, v154, v199, v118
	v_fma_f32 v154, v154, v203, v93
	v_fma_f32 v93, v100, v130, v140
	v_fma_f32 v94, v101, v131, v140
	v_fma_f32 v95, v102, v132, v140
	v_fma_f32 v100, v103, v133, v140
	v_fma_f32 v80, v80, v134, v93
	v_fma_f32 v81, v81, v135, v94
	v_fma_f32 v82, v82, v155, v95
	v_fma_f32 v83, v83, v192, v100
	v_fma_f32 v72, v72, v193, v80
	v_fma_f32 v73, v73, v194, v81
	v_fma_f32 v74, v74, v195, v82
	v_fma_f32 v75, v75, v196, v83
	v_fma_f32 v64, v64, v197, v72
	v_fma_f32 v65, v65, v198, v73
	v_fma_f32 v66, v66, v199, v74
	v_fma_f32 v67, v67, v154, v75
	v_add_f32_e32 v64, v64, v65
	v_add_f32_e32 v65, v66, v67
	v_add_f32_e32 v64, v64, v65
	s_nop 1
	v_add_f32_dpp v64, v64, v64 row_ror:8 row_mask:0xf bank_mask:0xf bound_ctrl:1
	s_nop 1
	v_add_f32_dpp v64, v64, v64 row_ror:4 row_mask:0xf bank_mask:0xf bound_ctrl:1
	s_nop 1
	v_add_f32_dpp v64, v64, v64 row_ror:2 row_mask:0xf bank_mask:0xf bound_ctrl:1
	s_nop 1
	v_add_f32_dpp v64, v64, v64 row_ror:1 row_mask:0xf bank_mask:0xf bound_ctrl:1
	ds_write_b32 v189, v64 offset:34240
	s_waitcnt lgkmcnt(0)
	v_mul_f32_e32 v153, v153, v92
	ds_read_b128 v[92:95], v188 offset:5120
	ds_read_b128 v[80:83], v188 offset:5376
	ds_read_b128 v[120:123], v188 offset:13312
	ds_read_b128 v[112:115], v188 offset:13568
	ds_read_b128 v[72:75], v188 offset:5632
	ds_read_b128 v[64:67], v188 offset:5888
	ds_read_b128 v[116:119], v188 offset:13824
	ds_read_b128 v[100:103], v188 offset:14080
	ds_read2_b32 v[128:129], v190 offset0:69 offset1:85
	ds_read_b32 v201, v189 offset:16704
	v_mul_f32 v124, v124, v153
	v_mul_f32 v125, v125, v153
	v_mul_f32 v126, v126, v153
	v_mul_f32 v127, v127, v153
	v_mul_f32 v104, v104, v153
	v_mul_f32 v105, v105, v153
	v_mul_f32 v106, v106, v153
	v_mul_f32 v107, v107, v153
	v_mul_f32 v108, v108, v153
	v_mul_f32 v109, v109, v153
	v_mul_f32 v110, v110, v153
	v_mul_f32 v111, v111, v153
	v_mul_f32 v96, v96, v153
	v_mul_f32 v97, v97, v153
	v_mul_f32 v98, v98, v153
	v_mul_f32 v99, v99, v153
	v_fma_f32 v153, v152, v130, v124
	v_fma_f32 v200, v152, v131, v125
	v_fma_f32 v134, v152, v134, v104
	v_fma_f32 v135, v152, v135, v105
	v_fma_f32 v193, v152, v193, v108
	v_fma_f32 v194, v152, v194, v109
	v_fma_f32 v197, v152, v197, v96
	v_fma_f32 v198, v152, v198, v97
	v_fma_f32 v88, v88, v153, v140
	v_fma_f32 v89, v89, v200, v140
	v_fma_f32 v132, v152, v132, v126
	v_fma_f32 v133, v152, v133, v127
	v_fma_f32 v155, v152, v155, v106
	v_fma_f32 v192, v152, v192, v107
	v_fma_f32 v84, v84, v134, v88
	v_fma_f32 v85, v85, v135, v89
	v_fma_f32 v195, v152, v195, v110
	v_fma_f32 v196, v152, v196, v111
	v_fma_f32 v199, v152, v199, v98
	v_fma_f32 v152, v152, v154, v99
	v_fma_f32 v76, v76, v193, v84
	v_fma_f32 v77, v77, v194, v85
	v_fma_f32 v90, v90, v132, v140
	v_fma_f32 v91, v91, v133, v140
	v_fma_f32 v68, v68, v197, v76
	v_fma_f32 v69, v69, v198, v77
	v_fma_f32 v86, v86, v155, v90
	v_fma_f32 v87, v87, v192, v91
	v_fma_f32 v78, v78, v195, v86
	v_fma_f32 v79, v79, v196, v87
	v_add_f32_e32 v68, v68, v69
	v_fma_f32 v70, v70, v199, v78
	v_fma_f32 v71, v71, v152, v79
	v_add_f32_e32 v69, v70, v71
	v_add_f32_e32 v68, v68, v69
	s_nop 1
	v_add_f32_dpp v68, v68, v68 row_ror:8 row_mask:0xf bank_mask:0xf bound_ctrl:1
	s_nop 1
	v_add_f32_dpp v68, v68, v68 row_ror:4 row_mask:0xf bank_mask:0xf bound_ctrl:1
	s_nop 1
	v_add_f32_dpp v68, v68, v68 row_ror:2 row_mask:0xf bank_mask:0xf bound_ctrl:1
	s_nop 1
	v_add_f32_dpp v68, v68, v68 row_ror:1 row_mask:0xf bank_mask:0xf bound_ctrl:1
	ds_write_b32 v189, v68 offset:34304
	s_waitcnt lgkmcnt(0)
	v_mul_f32_e32 v154, v129, v201
	ds_read_b128 v[88:91], v188 offset:6144
	ds_read_b128 v[84:87], v188 offset:6400
	ds_read_b128 v[124:127], v188 offset:14336
	ds_read_b128 v[104:107], v188 offset:14592
	ds_read_b128 v[76:79], v188 offset:6656
	ds_read_b128 v[68:71], v188 offset:6912
	ds_read_b128 v[108:111], v188 offset:14848
	ds_read_b128 v[96:99], v188 offset:15104
	ds_read2_b32 v[130:131], v190 offset0:70 offset1:86
	ds_read_b32 v129, v189 offset:16768
	v_mul_f32 v120, v120, v154
	v_mul_f32 v121, v121, v154
	v_mul_f32 v122, v122, v154
	v_mul_f32 v123, v123, v154
	v_mul_f32 v112, v112, v154
	v_mul_f32 v113, v113, v154
	v_mul_f32 v114, v114, v154
	v_mul_f32 v115, v115, v154
	v_mul_f32 v116, v116, v154
	v_mul_f32 v117, v117, v154
	v_mul_f32 v118, v118, v154
	v_mul_f32 v119, v119, v154
	v_mul_f32 v100, v100, v154
	v_mul_f32 v101, v101, v154
	v_mul_f32 v102, v102, v154
	v_mul_f32 v103, v103, v154
	v_fma_f32 v153, v128, v153, v120
	v_fma_f32 v154, v128, v200, v121
	v_fma_f32 v134, v128, v134, v112
	v_fma_f32 v135, v128, v135, v113
	v_fma_f32 v193, v128, v193, v116
	v_fma_f32 v194, v128, v194, v117
	v_fma_f32 v197, v128, v197, v100
	v_fma_f32 v198, v128, v198, v101
	v_fma_f32 v92, v92, v153, v140
	v_fma_f32 v93, v93, v154, v140
	v_fma_f32 v132, v128, v132, v122
	v_fma_f32 v133, v128, v133, v123
	v_fma_f32 v155, v128, v155, v114
	v_fma_f32 v192, v128, v192, v115
	v_fma_f32 v80, v80, v134, v92
	v_fma_f32 v81, v81, v135, v93
	v_fma_f32 v195, v128, v195, v118
	v_fma_f32 v196, v128, v196, v119
	v_fma_f32 v199, v128, v199, v102
	v_fma_f32 v152, v128, v152, v103
	v_fma_f32 v72, v72, v193, v80
	v_fma_f32 v73, v73, v194, v81
	v_fma_f32 v94, v94, v132, v140
	v_fma_f32 v95, v95, v133, v140
	v_fma_f32 v64, v64, v197, v72
	v_fma_f32 v65, v65, v198, v73
	v_fma_f32 v82, v82, v155, v94
	v_fma_f32 v83, v83, v192, v95
	v_fma_f32 v74, v74, v195, v82
	v_fma_f32 v75, v75, v196, v83
	v_add_f32_e32 v64, v64, v65
	v_fma_f32 v66, v66, v199, v74
	v_fma_f32 v67, v67, v152, v75
	v_add_f32_e32 v65, v66, v67
	v_add_f32_e32 v64, v64, v65
	s_nop 1
	v_add_f32_dpp v64, v64, v64 row_ror:8 row_mask:0xf bank_mask:0xf bound_ctrl:1
	s_nop 1
	v_add_f32_dpp v64, v64, v64 row_ror:4 row_mask:0xf bank_mask:0xf bound_ctrl:1
	s_nop 1
	v_add_f32_dpp v64, v64, v64 row_ror:2 row_mask:0xf bank_mask:0xf bound_ctrl:1
	s_nop 1
	v_add_f32_dpp v64, v64, v64 row_ror:1 row_mask:0xf bank_mask:0xf bound_ctrl:1
	ds_write_b32 v189, v64 offset:34368
	s_waitcnt lgkmcnt(0)
	v_mul_f32_e32 v200, v131, v129
	ds_read_b128 v[92:95], v188 offset:7168
	ds_read_b128 v[80:83], v188 offset:7424
	ds_read_b128 v[120:123], v188 offset:15360
	ds_read_b128 v[112:115], v188 offset:15616
	ds_read_b128 v[72:75], v188 offset:7680
	ds_read_b128 v[64:67], v188 offset:7936
	ds_read_b128 v[116:119], v188 offset:15872
	ds_read_b128 v[100:103], v188 offset:16128
	ds_read2_b32 v[128:129], v190 offset0:71 offset1:87
	ds_read_b32 v131, v189 offset:16832
	v_mul_f32 v125, v125, v200
	v_mul_f32 v126, v126, v200
	v_mul_f32 v104, v104, v200
	v_mul_f32 v124, v124, v200
	v_mul_f32 v127, v127, v200
	v_mul_f32 v105, v105, v200
	v_mul_f32 v106, v106, v200
	v_mul_f32 v107, v107, v200
	v_mul_f32 v108, v108, v200
	v_mul_f32 v109, v109, v200
	v_mul_f32 v201, v110, v200
	v_mul_f32 v202, v111, v200
	v_mul_f32 v203, v96, v200
	v_mul_f32 v204, v97, v200
	v_mul_f32 v205, v98, v200
	v_mul_f32 v200, v99, v200
	v_fma_f32 v96, v130, v153, v124
	v_fma_f32 v97, v130, v154, v125
	v_fma_f32 v98, v130, v132, v126
	v_fma_f32 v99, v130, v133, v127
	v_fma_f32 v104, v130, v134, v104
	v_fma_f32 v110, v130, v135, v105
	v_fma_f32 v125, v130, v193, v108
	v_fma_f32 v126, v130, v194, v109
	v_fma_f32 v133, v130, v197, v203
	v_fma_f32 v134, v130, v198, v204
	v_fma_f32 v88, v88, v96, v140
	v_fma_f32 v89, v89, v97, v140
	v_fma_f32 v111, v130, v155, v106
	v_fma_f32 v124, v130, v192, v107
	v_fma_f32 v127, v130, v195, v201
	v_fma_f32 v132, v130, v196, v202
	v_fma_f32 v84, v84, v104, v88
	v_fma_f32 v85, v85, v110, v89
	v_fma_f32 v135, v130, v199, v205
	v_fma_f32 v130, v130, v152, v200
	v_fma_f32 v90, v90, v98, v140
	v_fma_f32 v91, v91, v99, v140
	v_fma_f32 v76, v76, v125, v84
	v_fma_f32 v77, v77, v126, v85
	v_fma_f32 v68, v68, v133, v76
	v_fma_f32 v69, v69, v134, v77
	v_fma_f32 v86, v86, v111, v90
	v_fma_f32 v87, v87, v124, v91
	v_fma_f32 v78, v78, v127, v86
	v_fma_f32 v79, v79, v132, v87
	v_add_f32_e32 v68, v68, v69
	v_fma_f32 v70, v70, v135, v78
	v_fma_f32 v71, v71, v130, v79
	v_add_f32_e32 v69, v70, v71
	v_add_f32_e32 v68, v68, v69
	s_nop 1
	v_add_f32_dpp v68, v68, v68 row_ror:8 row_mask:0xf bank_mask:0xf bound_ctrl:1
	s_nop 1
	v_add_f32_dpp v68, v68, v68 row_ror:4 row_mask:0xf bank_mask:0xf bound_ctrl:1
	s_nop 1
	v_add_f32_dpp v68, v68, v68 row_ror:2 row_mask:0xf bank_mask:0xf bound_ctrl:1
	s_nop 1
	v_add_f32_dpp v68, v68, v68 row_ror:1 row_mask:0xf bank_mask:0xf bound_ctrl:1
	ds_write_b32 v189, v68 offset:34432
	s_waitcnt lgkmcnt(0)
	v_mul_f32_e32 v68, v129, v131
	v_mul_f32 v69, v120, v68
	v_mul_f32 v70, v121, v68
	v_mul_f32 v71, v122, v68
	v_mul_f32 v76, v123, v68
	v_mul_f32 v77, v112, v68
	v_mul_f32 v78, v113, v68
	v_mul_f32 v79, v114, v68
	v_mul_f32 v84, v115, v68
	v_mul_f32 v85, v116, v68
	v_mul_f32 v86, v117, v68
	v_mul_f32 v87, v118, v68
	v_mul_f32 v88, v119, v68
	v_mul_f32 v89, v100, v68
	v_mul_f32 v100, v101, v68
	v_mul_f32 v101, v102, v68
	v_mul_f32 v68, v103, v68
	v_fma_f32 v109, v128, v96, v69
	v_fma_f32 v108, v128, v97, v70
	v_fma_f32 v105, v128, v104, v77
	v_fma_f32 v104, v128, v110, v78
	v_fma_f32 v107, v128, v98, v71
	v_fma_f32 v78, v128, v130, v68
	v_fma_f32 v68, v92, v109, v140
	v_fma_f32 v69, v93, v108, v140
	v_fma_f32 v106, v128, v99, v76
	v_fma_f32 v99, v128, v111, v79
	v_fma_f32 v70, v94, v107, v140
	v_fma_f32 v98, v128, v124, v84
	v_fma_f32 v68, v80, v105, v68
	v_fma_f32 v69, v81, v104, v69
	v_fma_f32 v71, v95, v106, v140
	v_fma_f32 v97, v128, v125, v85
	v_fma_f32 v96, v128, v126, v86
	v_fma_f32 v90, v128, v132, v88
	v_fma_f32 v89, v128, v133, v89
	v_fma_f32 v88, v128, v134, v100
	v_fma_f32 v70, v82, v99, v70
	v_fma_f32 v71, v83, v98, v71
	v_fma_f32 v68, v72, v97, v68
	v_fma_f32 v69, v73, v96, v69
	v_fma_f32 v91, v128, v127, v87
	v_fma_f32 v79, v128, v135, v101
	v_fma_f32 v71, v75, v90, v71
	v_fma_f32 v64, v64, v89, v68
	v_fma_f32 v65, v65, v88, v69
	v_fma_f32 v70, v74, v91, v70
	v_fma_f32 v66, v66, v79, v70
	v_fma_f32 v67, v67, v78, v71
	v_add_f32_e32 v64, v64, v65
	v_add_f32_e32 v65, v66, v67
	v_add_f32_e32 v64, v64, v65
	s_nop 1
	v_add_f32_dpp v64, v64, v64 row_ror:8 row_mask:0xf bank_mask:0xf bound_ctrl:1
	s_nop 1
	v_add_f32_dpp v64, v64, v64 row_ror:4 row_mask:0xf bank_mask:0xf bound_ctrl:1
	s_nop 1
	v_add_f32_dpp v64, v64, v64 row_ror:2 row_mask:0xf bank_mask:0xf bound_ctrl:1
	s_nop 1
	v_add_f32_dpp v64, v64, v64 row_ror:1 row_mask:0xf bank_mask:0xf bound_ctrl:1
	ds_write_b32 v189, v64 offset:34496
	s_waitcnt vmcnt(3)
	ds_write_b128 v185, v[48:51] offset:17024
	s_waitcnt vmcnt(1)
	ds_write_b128 v186, v[56:59] offset:17024
	ds_write_b128 v185, v[52:55] offset:25216
	s_waitcnt vmcnt(0)
	ds_write_b128 v186, v[60:63] offset:25216
	s_and_saveexec_b64 s[8:9], s[42:43]
	ds_write_b32 v144, v184 offset:33408
	s_or_b64 exec, exec, s[8:9]
	s_and_saveexec_b64 s[8:9], s[40:41]
	s_cbranch_execz .LBB0_1536
	v_add_f32_e32 v64, v156, v181
	v_mul_f32_e64 v65, |v64|, s62
	v_exp_f32_e32 v65, v65
	v_min_f32_e32 v64, 0, v64
	v_add_f32_e32 v65, 1.0, v65
	v_cmp_gt_f32_e32 vcc, s5, v65
	s_nop 1
	v_cndmask_b32_e64 v66, 0, 32, vcc
	v_ldexp_f32 v65, v65, v66
	v_log_f32_e32 v65, v65
	v_cndmask_b32_e32 v67, 0, v171, vcc
	v_add_f32_e32 v66, v145, v187
	v_mul_f32_e32 v68, 0x3f317217, v65
	v_fma_f32 v68, v65, s76, -v68
	v_fmac_f32_e32 v68, 0x3377d1cf, v65
	v_fmac_f32_e32 v68, 0x3f317217, v65
	v_cmp_lt_f32_e64 vcc, |v65|, s77
	s_nop 1
	v_cndmask_b32_e32 v65, v65, v68, vcc
	v_sub_f32_e32 v65, v65, v67
	v_sub_f32_e32 v64, v64, v65
	v_add_u32_e32 v65, 0x8400, v144
	ds_write2_b32 v65, v66, v64 offset0:32 offset1:48

.LBB0_1547:
	s_or_b64 exec, exec, s[8:9]
	s_waitcnt lgkmcnt(0)
	s_barrier
	ds_read_b128 v[92:95], v188 offset:17024
	ds_read_b128 v[110:113], v188 offset:17280
	ds_read_b128 v[124:127], v188 offset:25216
	ds_read_b128 v[132:135], v188 offset:25472
	ds_read2_b64 v[80:83], v190 offset0:32 offset1:40
	ds_read2_b32 v[76:77], v191 offset0:160 offset1:176
	ds_read_b128 v[200:203], v188 offset:17536
	ds_read_b128 v[204:207], v188 offset:17792
	ds_read_b128 v[152:155], v188 offset:25728
	ds_read_b128 v[192:195], v188 offset:25984
	s_waitcnt lgkmcnt(4)
	v_mul_f32_e32 v76, v82, v76
	v_mul_f32 v82, v124, v76
	v_mul_f32 v114, v125, v76
	v_mul_f32 v115, v126, v76
	v_mul_f32 v124, v127, v76
	v_mul_f32 v125, v132, v76
	v_mul_f32 v126, v133, v76
	v_mul_f32 v127, v134, v76
	v_mul_f32 v191, v135, v76
	s_waitcnt lgkmcnt(1)
	v_mul_f32 v152, v152, v76
	v_mul_f32 v153, v153, v76
	v_mul_f32 v196, v154, v76
	v_mul_f32 v197, v155, v76
	s_waitcnt lgkmcnt(0)
	v_mul_f32 v198, v192, v76
	v_mul_f32 v199, v193, v76
	v_mul_f32 v208, v194, v76
	v_mul_f32 v76, v195, v76
	ds_read_b128 v[84:87], v188 offset:18048
	ds_read_b128 v[72:75], v188 offset:18304
	ds_read_b128 v[128:131], v188 offset:26240
	ds_read_b128 v[116:119], v188 offset:26496
	ds_read_b128 v[68:71], v188 offset:18560
	ds_read_b128 v[64:67], v188 offset:18816
	ds_read_b128 v[120:123], v188 offset:26752
	ds_read_b128 v[100:103], v188 offset:27008
	v_fma_f32 v82, v80, v109, v82
	v_fma_f32 v132, v80, v108, v114
	v_fma_f32 v133, v80, v107, v115
	v_fma_f32 v134, v80, v106, v124
	v_fma_f32 v135, v80, v105, v125
	v_fma_f32 v154, v80, v104, v126
	v_fma_f32 v155, v80, v99, v127
	v_fma_f32 v191, v80, v98, v191
	v_fma_f32 v192, v80, v97, v152
	v_fma_f32 v193, v80, v96, v153
	v_fma_f32 v194, v80, v91, v196
	v_fma_f32 v195, v80, v90, v197
	v_fma_f32 v196, v80, v89, v198
	v_fma_f32 v197, v80, v88, v199
	v_fma_f32 v198, v80, v79, v208
	v_fma_f32 v80, v80, v78, v76
	v_fma_f32 v76, v92, v82, v140
	v_fma_f32 v78, v93, v132, v140
	v_fma_f32 v79, v94, v133, v140
	v_fma_f32 v88, v95, v134, v140
	v_fma_f32 v76, v110, v135, v76
	v_fma_f32 v78, v111, v154, v78
	v_fma_f32 v79, v112, v155, v79
	v_fma_f32 v88, v113, v191, v88
	v_fma_f32 v76, v200, v192, v76
	v_fma_f32 v78, v201, v193, v78
	v_fma_f32 v79, v202, v194, v79
	v_fma_f32 v88, v203, v195, v88
	v_fma_f32 v76, v204, v196, v76
	v_fma_f32 v78, v205, v197, v78
	v_fma_f32 v79, v206, v198, v79
	v_fma_f32 v88, v207, v80, v88
	v_add_f32_e32 v76, v76, v78
	v_add_f32_e32 v78, v79, v88
	v_add_f32_e32 v76, v76, v78
	s_nop 1
	v_add_f32_dpp v76, v76, v76 row_ror:8 row_mask:0xf bank_mask:0xf bound_ctrl:1
	s_nop 1
	v_add_f32_dpp v76, v76, v76 row_ror:4 row_mask:0xf bank_mask:0xf bound_ctrl:1
	s_nop 1
	v_add_f32_dpp v76, v76, v76 row_ror:2 row_mask:0xf bank_mask:0xf bound_ctrl:1
	s_nop 1
	v_add_f32_dpp v76, v76, v76 row_ror:1 row_mask:0xf bank_mask:0xf bound_ctrl:1
	ds_write_b32 v189, v76 offset:34560
	v_mul_f32_e32 v199, v83, v77
	ds_read_b128 v[96:99], v188 offset:19072
	ds_read_b128 v[92:95], v188 offset:19328
	ds_read_b128 v[124:127], v188 offset:27264
	ds_read_b128 v[108:111], v188 offset:27520
	ds_read_b128 v[88:91], v188 offset:19584
	ds_read_b128 v[76:79], v188 offset:19840
	ds_read_b128 v[112:115], v188 offset:27776
	ds_read_b128 v[104:107], v188 offset:28032
	ds_read2_b32 v[152:153], v190 offset0:66 offset1:82
	ds_read_b32 v83, v189 offset:33536
	s_waitcnt lgkmcnt(14)
	v_mul_f32 v128, v128, v199
	v_mul_f32 v129, v129, v199
	v_mul_f32 v130, v130, v199
	v_mul_f32 v131, v131, v199
	v_mul_f32 v116, v116, v199
	v_mul_f32 v117, v117, v199
	v_mul_f32 v118, v118, v199
	v_mul_f32 v119, v119, v199
	s_waitcnt lgkmcnt(11)
	v_mul_f32 v120, v120, v199
	v_mul_f32 v121, v121, v199
	v_mul_f32 v122, v122, v199
	v_mul_f32 v123, v123, v199
	s_waitcnt lgkmcnt(10)
	v_mul_f32 v100, v100, v199
	v_mul_f32 v101, v101, v199
	v_mul_f32 v102, v102, v199
	v_mul_f32 v103, v103, v199
	v_fma_f32 v199, v81, v82, v128
	v_fma_f32 v200, v81, v132, v129
	v_fma_f32 v201, v81, v133, v130
	v_fma_f32 v202, v81, v134, v131
	v_fma_f32 v203, v81, v135, v116
	v_fma_f32 v204, v81, v154, v117
	v_fma_f32 v205, v81, v155, v118
	v_fma_f32 v191, v81, v191, v119
	v_fma_f32 v192, v81, v192, v120
	v_fma_f32 v193, v81, v193, v121
	v_fma_f32 v194, v81, v194, v122
	v_fma_f32 v195, v81, v195, v123
	v_fma_f32 v196, v81, v196, v100
	v_fma_f32 v197, v81, v197, v101
	v_fma_f32 v198, v81, v198, v102
	v_fma_f32 v206, v81, v80, v103
	v_fma_f32 v80, v84, v199, v140
	v_fma_f32 v81, v85, v200, v140
	v_fma_f32 v82, v86, v201, v140
	v_fma_f32 v84, v87, v202, v140
	v_fma_f32 v72, v72, v203, v80
	v_fma_f32 v73, v73, v204, v81
	v_fma_f32 v74, v74, v205, v82
	v_fma_f32 v75, v75, v191, v84
	v_fma_f32 v68, v68, v192, v72
	v_fma_f32 v69, v69, v193, v73
	v_fma_f32 v70, v70, v194, v74
	v_fma_f32 v71, v71, v195, v75
	v_fma_f32 v64, v64, v196, v68
	v_fma_f32 v65, v65, v197, v69
	v_fma_f32 v66, v66, v198, v70
	v_fma_f32 v67, v67, v206, v71
	v_add_f32_e32 v64, v64, v65
	v_add_f32_e32 v65, v66, v67
	v_add_f32_e32 v64, v64, v65
	s_nop 1
	v_add_f32_dpp v64, v64, v64 row_ror:8 row_mask:0xf bank_mask:0xf bound_ctrl:1
	s_nop 1
	v_add_f32_dpp v64, v64, v64 row_ror:4 row_mask:0xf bank_mask:0xf bound_ctrl:1
	s_nop 1
	v_add_f32_dpp v64, v64, v64 row_ror:2 row_mask:0xf bank_mask:0xf bound_ctrl:1
	s_nop 1
	v_add_f32_dpp v64, v64, v64 row_ror:1 row_mask:0xf bank_mask:0xf bound_ctrl:1
	ds_write_b32 v189, v64 offset:34624
	s_waitcnt lgkmcnt(0)
	v_mul_f32_e32 v69, v153, v83
	ds_read_b128 v[100:103], v188 offset:20096
	ds_read_b128 v[80:83], v188 offset:20352
	ds_read_b128 v[132:135], v188 offset:28288
	ds_read_b128 v[120:123], v188 offset:28544
	ds_read_b128 v[72:75], v188 offset:20608
	ds_read_b128 v[64:67], v188 offset:20864
	ds_read_b128 v[128:131], v188 offset:28800
	ds_read_b128 v[116:119], v188 offset:29056
	ds_read2_b32 v[154:155], v190 offset0:67 offset1:83
	ds_read_b32 v68, v189 offset:33600
	v_mul_f32 v70, v124, v69
	v_mul_f32 v71, v125, v69
	v_mul_f32 v84, v126, v69
	v_mul_f32 v85, v127, v69
	v_mul_f32 v86, v108, v69
	v_mul_f32 v87, v109, v69
	v_mul_f32 v108, v110, v69
	v_mul_f32 v109, v111, v69
	v_mul_f32 v110, v112, v69
	v_mul_f32 v111, v113, v69
	v_mul_f32 v124, v114, v69
	v_mul_f32 v125, v115, v69
	v_mul_f32 v104, v104, v69
	v_mul_f32 v105, v105, v69
	v_mul_f32 v106, v106, v69
	v_mul_f32 v69, v107, v69
	v_fma_f32 v112, v152, v199, v70
	v_fma_f32 v113, v152, v200, v71
	v_fma_f32 v115, v152, v202, v85
	v_fma_f32 v114, v152, v201, v84
	v_fma_f32 v199, v152, v203, v86
	v_fma_f32 v202, v152, v206, v69
	v_fma_f32 v69, v96, v112, v140
	v_fma_f32 v70, v97, v113, v140
	v_fma_f32 v200, v152, v204, v87
	v_fma_f32 v71, v98, v114, v140
	v_fma_f32 v201, v152, v205, v108
	v_fma_f32 v192, v152, v192, v110
	v_fma_f32 v69, v92, v199, v69
	v_fma_f32 v193, v152, v193, v111
	v_fma_f32 v70, v93, v200, v70
	v_fma_f32 v84, v99, v115, v140
	v_fma_f32 v71, v94, v201, v71
	v_fma_f32 v191, v152, v191, v109
	v_fma_f32 v69, v88, v192, v69
	v_fma_f32 v194, v152, v194, v124
	v_fma_f32 v70, v89, v193, v70
	v_fma_f32 v196, v152, v196, v104
	v_fma_f32 v197, v152, v197, v105
	v_fma_f32 v84, v95, v191, v84
	v_fma_f32 v195, v152, v195, v125
	v_fma_f32 v71, v90, v194, v71
	v_fma_f32 v198, v152, v198, v106
	v_fma_f32 v69, v76, v196, v69
	v_fma_f32 v70, v77, v197, v70
	v_fma_f32 v84, v91, v195, v84
	v_fma_f32 v71, v78, v198, v71
	v_fma_f32 v76, v79, v202, v84
	v_add_f32_e32 v69, v69, v70
	v_add_f32_e32 v70, v71, v76
	v_add_f32_e32 v69, v69, v70
	s_nop 1
	v_add_f32_dpp v69, v69, v69 row_ror:8 row_mask:0xf bank_mask:0xf bound_ctrl:1
	s_nop 1
	v_add_f32_dpp v69, v69, v69 row_ror:4 row_mask:0xf bank_mask:0xf bound_ctrl:1
	s_nop 1
	v_add_f32_dpp v69, v69, v69 row_ror:2 row_mask:0xf bank_mask:0xf bound_ctrl:1
	s_nop 1
	v_add_f32_dpp v69, v69, v69 row_ror:1 row_mask:0xf bank_mask:0xf bound_ctrl:1
	ds_write_b32 v189, v69 offset:34688
	s_waitcnt lgkmcnt(0)
	v_mul_f32_e32 v93, v155, v68
	ds_read_b128 v[88:91], v188 offset:21120
	ds_read_b128 v[84:87], v188 offset:21376
	ds_read_b128 v[124:127], v188 offset:29312
	ds_read_b128 v[104:107], v188 offset:29568
	ds_read_b128 v[76:79], v188 offset:21632
	ds_read_b128 v[68:71], v188 offset:21888
	ds_read_b128 v[108:111], v188 offset:29824
	ds_read_b128 v[96:99], v188 offset:30080
	ds_read2_b32 v[152:153], v190 offset0:68 offset1:84
	ds_read_b32 v92, v189 offset:33664
	v_mul_f32 v94, v132, v93
	v_mul_f32 v95, v133, v93
	v_mul_f32 v132, v134, v93
	v_mul_f32 v133, v135, v93
	v_mul_f32 v134, v120, v93
	v_mul_f32 v135, v121, v93
	v_mul_f32 v155, v122, v93
	v_mul_f32 v203, v123, v93
	v_mul_f32 v128, v128, v93
	v_mul_f32 v129, v129, v93
	v_mul_f32 v130, v130, v93
	v_mul_f32 v131, v131, v93
	v_mul_f32 v116, v116, v93
	v_mul_f32 v117, v117, v93
	v_mul_f32 v118, v118, v93
	v_mul_f32 v93, v119, v93
	v_fma_f32 v120, v154, v112, v94
	v_fma_f32 v121, v154, v113, v95
	v_fma_f32 v122, v154, v114, v132
	v_fma_f32 v123, v154, v115, v133
	v_fma_f32 v134, v154, v199, v134
	v_fma_f32 v135, v154, v200, v135
	v_fma_f32 v155, v154, v201, v155
	v_fma_f32 v191, v154, v191, v203
	v_fma_f32 v192, v154, v192, v128
	v_fma_f32 v193, v154, v193, v129
	v_fma_f32 v194, v154, v194, v130
	v_fma_f32 v195, v154, v195, v131
	v_fma_f32 v196, v154, v196, v116
	v_fma_f32 v197, v154, v197, v117
	v_fma_f32 v198, v154, v198, v118
	v_fma_f32 v154, v154, v202, v93
	v_fma_f32 v93, v100, v120, v140
	v_fma_f32 v94, v101, v121, v140
	v_fma_f32 v95, v102, v122, v140
	v_fma_f32 v100, v103, v123, v140
	v_fma_f32 v80, v80, v134, v93
	v_fma_f32 v81, v81, v135, v94
	v_fma_f32 v82, v82, v155, v95
	v_fma_f32 v83, v83, v191, v100
	v_fma_f32 v72, v72, v192, v80
	v_fma_f32 v73, v73, v193, v81
	v_fma_f32 v74, v74, v194, v82
	v_fma_f32 v75, v75, v195, v83
	v_fma_f32 v64, v64, v196, v72
	v_fma_f32 v65, v65, v197, v73
	v_fma_f32 v66, v66, v198, v74
	v_fma_f32 v67, v67, v154, v75
	v_add_f32_e32 v64, v64, v65
	v_add_f32_e32 v65, v66, v67
	v_add_f32_e32 v64, v64, v65
	s_nop 1
	v_add_f32_dpp v64, v64, v64 row_ror:8 row_mask:0xf bank_mask:0xf bound_ctrl:1
	s_nop 1
	v_add_f32_dpp v64, v64, v64 row_ror:4 row_mask:0xf bank_mask:0xf bound_ctrl:1
	s_nop 1
	v_add_f32_dpp v64, v64, v64 row_ror:2 row_mask:0xf bank_mask:0xf bound_ctrl:1
	s_nop 1
	v_add_f32_dpp v64, v64, v64 row_ror:1 row_mask:0xf bank_mask:0xf bound_ctrl:1
	ds_write_b32 v189, v64 offset:34752
	s_waitcnt lgkmcnt(0)
	v_mul_f32_e32 v153, v153, v92
	ds_read_b128 v[92:95], v188 offset:22144
	ds_read_b128 v[80:83], v188 offset:22400
	ds_read_b128 v[128:131], v188 offset:30336
	ds_read_b128 v[112:115], v188 offset:30592
	ds_read_b128 v[72:75], v188 offset:22656
	ds_read_b128 v[64:67], v188 offset:22912
	ds_read_b128 v[116:119], v188 offset:30848
	ds_read_b128 v[100:103], v188 offset:31104
	ds_read2_b32 v[132:133], v190 offset0:69 offset1:85
	ds_read_b32 v200, v189 offset:33728
	v_mul_f32 v124, v124, v153
	v_mul_f32 v125, v125, v153
	v_mul_f32 v126, v126, v153
	v_mul_f32 v127, v127, v153
	v_mul_f32 v104, v104, v153
	v_mul_f32 v105, v105, v153
	v_mul_f32 v106, v106, v153
	v_mul_f32 v107, v107, v153
	v_mul_f32 v108, v108, v153
	v_mul_f32 v109, v109, v153
	v_mul_f32 v110, v110, v153
	v_mul_f32 v111, v111, v153
	v_mul_f32 v201, v96, v153
	v_mul_f32 v202, v97, v153
	v_mul_f32 v203, v98, v153
	v_mul_f32 v204, v99, v153
	v_fma_f32 v96, v152, v120, v124
	v_fma_f32 v97, v152, v121, v125
	v_fma_f32 v153, v152, v134, v104
	v_fma_f32 v199, v152, v135, v105
	v_fma_f32 v192, v152, v192, v108
	v_fma_f32 v193, v152, v193, v109
	v_fma_f32 v196, v152, v196, v201
	v_fma_f32 v197, v152, v197, v202
	v_fma_f32 v88, v88, v96, v140
	v_fma_f32 v89, v89, v97, v140
	v_fma_f32 v98, v152, v122, v126
	v_fma_f32 v99, v152, v123, v127
	v_fma_f32 v155, v152, v155, v106
	v_fma_f32 v191, v152, v191, v107
	v_fma_f32 v84, v84, v153, v88
	v_fma_f32 v85, v85, v199, v89
	v_fma_f32 v194, v152, v194, v110
	v_fma_f32 v195, v152, v195, v111
	v_fma_f32 v198, v152, v198, v203
	v_fma_f32 v152, v152, v154, v204
	v_fma_f32 v76, v76, v192, v84
	v_fma_f32 v77, v77, v193, v85
	v_fma_f32 v90, v90, v98, v140
	v_fma_f32 v91, v91, v99, v140
	v_fma_f32 v68, v68, v196, v76
	v_fma_f32 v69, v69, v197, v77
	v_fma_f32 v86, v86, v155, v90
	v_fma_f32 v87, v87, v191, v91
	v_fma_f32 v78, v78, v194, v86
	v_fma_f32 v79, v79, v195, v87
	v_add_f32_e32 v68, v68, v69
	v_fma_f32 v70, v70, v198, v78
	v_fma_f32 v71, v71, v152, v79
	v_add_f32_e32 v69, v70, v71
	v_add_f32_e32 v68, v68, v69
	s_nop 1
	v_add_f32_dpp v68, v68, v68 row_ror:8 row_mask:0xf bank_mask:0xf bound_ctrl:1
	s_nop 1
	v_add_f32_dpp v68, v68, v68 row_ror:4 row_mask:0xf bank_mask:0xf bound_ctrl:1
	s_nop 1
	v_add_f32_dpp v68, v68, v68 row_ror:2 row_mask:0xf bank_mask:0xf bound_ctrl:1
	s_nop 1
	v_add_f32_dpp v68, v68, v68 row_ror:1 row_mask:0xf bank_mask:0xf bound_ctrl:1
	ds_write_b32 v189, v68 offset:34816
	s_waitcnt lgkmcnt(0)
	v_mul_f32_e32 v133, v133, v200
	ds_read_b128 v[88:91], v188 offset:23168
	ds_read_b128 v[84:87], v188 offset:23424
	ds_read_b128 v[124:127], v188 offset:31360
	ds_read_b128 v[108:111], v188 offset:31616
	ds_read_b128 v[76:79], v188 offset:23680
	ds_read_b128 v[68:71], v188 offset:23936
	ds_read_b128 v[120:123], v188 offset:31872
	ds_read_b128 v[104:107], v188 offset:32128
	ds_read2_b32 v[134:135], v190 offset0:70 offset1:86
	ds_read_b32 v200, v189 offset:33792
	v_mul_f32 v128, v128, v133
	v_mul_f32 v129, v129, v133
	v_mul_f32 v154, v130, v133
	v_mul_f32 v201, v131, v133
	v_mul_f32 v112, v112, v133
	v_mul_f32 v113, v113, v133
	v_mul_f32 v116, v116, v133
	v_mul_f32 v117, v117, v133
	v_mul_f32 v100, v100, v133
	v_mul_f32 v101, v101, v133
	v_fma_f32 v130, v132, v96, v128
	v_fma_f32 v131, v132, v97, v129
	v_fma_f32 v153, v132, v153, v112
	v_fma_f32 v199, v132, v199, v113
	v_fma_f32 v192, v132, v192, v116
	v_fma_f32 v193, v132, v193, v117
	v_fma_f32 v196, v132, v196, v100
	v_fma_f32 v197, v132, v197, v101
	v_fma_f32 v92, v92, v130, v140
	v_fma_f32 v93, v93, v131, v140
	v_mul_f32 v114, v114, v133
	v_mul_f32 v115, v115, v133
	v_mul_f32 v118, v118, v133
	v_mul_f32 v119, v119, v133
	v_fma_f32 v80, v80, v153, v92
	v_fma_f32 v81, v81, v199, v93
	v_mul_f32 v102, v102, v133
	v_mul_f32 v103, v103, v133
	v_fma_f32 v133, v132, v98, v154
	v_fma_f32 v154, v132, v99, v201
	v_fma_f32 v72, v72, v192, v80
	v_fma_f32 v73, v73, v193, v81
	v_fma_f32 v155, v132, v155, v114
	v_fma_f32 v191, v132, v191, v115
	v_fma_f32 v194, v132, v194, v118
	v_fma_f32 v195, v132, v195, v119
	v_fma_f32 v64, v64, v196, v72
	v_fma_f32 v65, v65, v197, v73
	v_fma_f32 v198, v132, v198, v102
	v_fma_f32 v132, v132, v152, v103
	v_fma_f32 v94, v94, v133, v140
	v_fma_f32 v95, v95, v154, v140
	v_add_f32_e32 v64, v64, v65
	v_fma_f32 v82, v82, v155, v94
	v_fma_f32 v83, v83, v191, v95
	v_fma_f32 v74, v74, v194, v82
	v_fma_f32 v75, v75, v195, v83
	v_fma_f32 v66, v66, v198, v74
	v_fma_f32 v67, v67, v132, v75
	v_add_f32_e32 v65, v66, v67
	v_add_f32_e32 v64, v64, v65
	s_nop 1
	v_add_f32_dpp v64, v64, v64 row_ror:8 row_mask:0xf bank_mask:0xf bound_ctrl:1
	s_nop 1
	v_add_f32_dpp v64, v64, v64 row_ror:4 row_mask:0xf bank_mask:0xf bound_ctrl:1
	s_nop 1
	v_add_f32_dpp v64, v64, v64 row_ror:2 row_mask:0xf bank_mask:0xf bound_ctrl:1
	s_nop 1
	v_add_f32_dpp v64, v64, v64 row_ror:1 row_mask:0xf bank_mask:0xf bound_ctrl:1
	ds_write_b32 v189, v64 offset:34880
	s_waitcnt lgkmcnt(0)
	v_mul_f32_e32 v152, v135, v200
	ds_read_b128 v[100:103], v188 offset:24192
	ds_read_b128 v[96:99], v188 offset:24448
	ds_read_b128 v[116:119], v188 offset:32384
	ds_read_b128 v[72:75], v188 offset:32640
	ds_read_b128 v[92:95], v188 offset:24704
	ds_read_b128 v[80:83], v188 offset:24960
	ds_read_b128 v[112:115], v188 offset:32896
	ds_read_b128 v[64:67], v188 offset:33152
	ds_read2_b32 v[128:129], v190 offset0:71 offset1:87
	ds_read_b32 v135, v189 offset:33856
	v_mul_f32 v124, v124, v152
	v_mul_f32 v125, v125, v152
	v_mul_f32 v108, v108, v152
	v_mul_f32 v109, v109, v152
	v_mul_f32 v120, v120, v152
	v_mul_f32 v121, v121, v152
	v_mul_f32 v126, v126, v152
	v_mul_f32 v127, v127, v152
	v_mul_f32 v110, v110, v152
	v_mul_f32 v111, v111, v152
	v_mul_f32 v122, v122, v152
	v_mul_f32 v123, v123, v152
	v_mul_f32 v190, v104, v152
	v_mul_f32 v200, v105, v152
	v_fma_f32 v104, v134, v130, v124
	v_fma_f32 v105, v134, v131, v125
	v_fma_f32 v108, v134, v153, v108
	v_fma_f32 v109, v134, v199, v109
	v_fma_f32 v120, v134, v192, v120
	v_fma_f32 v121, v134, v193, v121
	v_fma_f32 v124, v134, v196, v190
	v_fma_f32 v125, v134, v197, v200
	v_fma_f32 v88, v88, v104, v140
	v_fma_f32 v89, v89, v105, v140
	v_mul_f32 v201, v106, v152
	v_mul_f32 v152, v107, v152
	v_fma_f32 v106, v134, v133, v126
	v_fma_f32 v107, v134, v154, v127
	v_fma_f32 v84, v84, v108, v88
	v_fma_f32 v85, v85, v109, v89
	v_fma_f32 v110, v134, v155, v110
	v_fma_f32 v111, v134, v191, v111
	v_fma_f32 v122, v134, v194, v122
	v_fma_f32 v123, v134, v195, v123
	v_fma_f32 v76, v76, v120, v84
	v_fma_f32 v77, v77, v121, v85
	v_fma_f32 v126, v134, v198, v201
	v_fma_f32 v127, v134, v132, v152
	v_fma_f32 v90, v90, v106, v140
	v_fma_f32 v91, v91, v107, v140
	v_fma_f32 v68, v68, v124, v76
	v_fma_f32 v69, v69, v125, v77
	v_fma_f32 v86, v86, v110, v90
	v_fma_f32 v87, v87, v111, v91
	v_add_f32_e32 v68, v68, v69
	v_fma_f32 v78, v78, v122, v86
	v_fma_f32 v79, v79, v123, v87
	v_fma_f32 v70, v70, v126, v78
	v_fma_f32 v71, v71, v127, v79
	v_add_f32_e32 v69, v70, v71
	v_add_f32_e32 v68, v68, v69
	s_nop 1
	v_add_f32_dpp v68, v68, v68 row_ror:8 row_mask:0xf bank_mask:0xf bound_ctrl:1
	s_nop 1
	v_add_f32_dpp v68, v68, v68 row_ror:4 row_mask:0xf bank_mask:0xf bound_ctrl:1
	s_nop 1
	v_add_f32_dpp v68, v68, v68 row_ror:2 row_mask:0xf bank_mask:0xf bound_ctrl:1
	s_nop 1
	v_add_f32_dpp v68, v68, v68 row_ror:1 row_mask:0xf bank_mask:0xf bound_ctrl:1
	ds_write_b32 v189, v68 offset:34944
	s_waitcnt lgkmcnt(0)
	v_mul_f32_e32 v68, v129, v135
	v_mul_f32 v76, v119, v68
	v_mul_f32 v72, v72, v68
	v_mul_f32 v73, v73, v68
	v_mul_f32 v84, v112, v68
	v_mul_f32 v85, v113, v68
	v_mul_f32 v69, v116, v68
	v_mul_f32 v70, v117, v68
	v_mul_f32 v74, v74, v68
	v_mul_f32 v75, v75, v68
	v_mul_f32 v86, v114, v68
	v_mul_f32 v87, v115, v68
	v_mul_f32 v88, v64, v68
	v_mul_f32 v89, v65, v68
	v_mul_f32 v91, v67, v68
	v_fma_f32 v64, v128, v104, v69
	v_fma_f32 v65, v128, v105, v70
	v_fma_f32 v67, v128, v107, v76
	v_fma_f32 v76, v128, v108, v72
	v_fma_f32 v77, v128, v109, v73
	v_fma_f32 v72, v128, v120, v84
	v_fma_f32 v73, v128, v121, v85
	v_fma_f32 v84, v100, v64, v140
	v_fma_f32 v85, v101, v65, v140
	v_mul_f32 v71, v118, v68
	v_mul_f32 v90, v66, v68
	v_fma_f32 v78, v128, v110, v74
	v_fma_f32 v79, v128, v111, v75
	v_fma_f32 v74, v128, v122, v86
	v_fma_f32 v75, v128, v123, v87
	v_fma_f32 v66, v128, v106, v71
	v_fma_f32 v87, v103, v67, v140
	v_fma_f32 v84, v96, v76, v84
	v_fma_f32 v85, v97, v77, v85
	v_fma_f32 v68, v128, v124, v88
	v_fma_f32 v69, v128, v125, v89
	v_fma_f32 v86, v102, v66, v140
	v_fma_f32 v87, v99, v79, v87
	v_fma_f32 v84, v92, v72, v84
	v_fma_f32 v85, v93, v73, v85
	v_fma_f32 v70, v128, v126, v90
	v_fma_f32 v71, v128, v127, v91
	v_fma_f32 v86, v98, v78, v86
	v_fma_f32 v87, v95, v75, v87
	v_fma_f32 v80, v80, v68, v84
	v_fma_f32 v81, v81, v69, v85
	v_fma_f32 v86, v94, v74, v86
	v_fma_f32 v83, v83, v71, v87
	v_add_f32_e32 v80, v80, v81
	v_fma_f32 v82, v82, v70, v86
	v_add_f32_e32 v81, v82, v83
	v_add_f32_e32 v80, v80, v81
	v_mov_b32_e32 v81, 0
	s_nop 0
	v_add_f32_dpp v80, v80, v80 row_ror:8 row_mask:0xf bank_mask:0xf bound_ctrl:1
	s_nop 1
	v_add_f32_dpp v80, v80, v80 row_ror:4 row_mask:0xf bank_mask:0xf bound_ctrl:1
	s_nop 1
	v_add_f32_dpp v80, v80, v80 row_ror:2 row_mask:0xf bank_mask:0xf bound_ctrl:1
	s_nop 1
	v_mov_b32_dpp v81, v80 row_ror:1 row_mask:0xf bank_mask:0xf
	s_and_saveexec_b64 s[8:9], s[44:45]
	s_cbranch_execz .LBB0_1438
	v_add_f32_e32 v80, v80, v81
	ds_write_b32 v189, v80 offset:35008
	s_branch .LBB0_1438

.LBB0_1576:
	s_or_b64 exec, exec, s[8:9]
	s_waitcnt lgkmcnt(0)
	s_barrier
	ds_read_b32 v0, v159
	s_movk_i32 s4, 0x31ff
	s_mov_b64 s[8:9], -1
	s_waitcnt lgkmcnt(0)
	v_cmp_lt_i32_e32 vcc, s4, v0
	v_readfirstlane_b32 s42, v0
	s_cbranch_vccnz .LBB0_1571
	s_cmpk_gt_i32 s42, 0x21ff
	s_cbranch_scc0 .LBB0_1595
	v_mov_b32_e32 v14, v143
	s_add_i32 s4, s42, 0xffffde00
	s_load_dwordx2 s[22:23], s[0:1], 0x40
	s_lshr_b32 s4, s4, 2
	s_bfe_u32 s8, s42, 0x30002
	s_and_b32 s4, s4, 0x3ffffff8
	s_lshl_b32 s9, s42, 5
	s_or_b32 s94, s4, s8
	s_and_b32 s9, s9, 0x60
	s_lshl_b64 s[38:39], s[94:95], 16
	s_waitcnt lgkmcnt(0)
	s_add_u32 s15, s22, s38
	s_addc_u32 s23, s23, s39
	s_lshl_b32 s40, s9, 2
	s_waitcnt vmcnt(0)
	v_lshlrev_b32_e32 v62, 2, v14
	s_add_u32 s22, s15, s40
	v_ashrrev_i32_e32 v0, 3, v14
	v_and_b32_e32 v1, 28, v62
	s_addc_u32 s23, s23, 0
	v_lshlrev_b32_e32 v42, 2, v1
	v_mov_b32_e32 v43, v140
	v_ashrrev_i32_e32 v1, 31, v0
	v_lshl_add_u64 v[2:3], s[22:23], 0, v[42:43]
	v_lshlrev_b64 v[44:45], 9, v[0:1]
	s_mov_b64 s[22:23], 0x4000
	v_lshl_add_u64 v[40:41], v[44:45], 0, s[22:23]
	s_mov_b64 s[22:23], 0x8000
	v_lshl_add_u64 v[38:39], v[44:45], 0, s[22:23]
	s_mov_b64 s[22:23], 0xc000
	v_lshl_add_u64 v[4:5], v[2:3], 0, v[44:45]
	v_lshl_add_u64 v[36:37], v[44:45], 0, s[22:23]
	v_mul_lo_u32 v0, v0, s68
	v_lshl_add_u64 v[6:7], v[2:3], 0, v[40:41]
	v_lshl_add_u64 v[8:9], v[2:3], 0, v[38:39]
	v_lshl_add_u64 v[10:11], v[2:3], 0, v[36:37]
	v_add_u32_e32 v12, v42, v0
	global_load_dwordx4 v[0:3], v[4:5], off
	v_add_u32_e32 v54, 0x5140, v12
	v_add_u32_e32 v58, 0x5148, v12
	v_add_u32_e32 v55, 0x61c0, v12
	v_add_u32_e32 v59, 0x61c8, v12
	v_add_u32_e32 v56, 0x7240, v12
	v_add_u32_e32 v60, 0x7248, v12
	v_add_u32_e32 v57, 0x82c0, v12
	v_add_u32_e32 v61, 0x82c8, v12
	s_lshl_b32 s43, s8, 7
	s_addk_i32 s4, 0x2000
	v_and_b32_e32 v49, 15, v14
	s_movk_i32 s9, 0x210
	s_lshl_b32 s8, s8, 9
	s_mov_b32 s41, s95
	v_mov_b32_e32 v47, v140
	v_lshlrev_b32_e32 v17, 4, v14
	v_cmp_eq_u32_e64 s[38:39], 0, v49
	s_waitcnt vmcnt(0)
	ds_write2_b32 v54, v0, v1 offset1:1
	ds_write2_b32 v58, v2, v3 offset1:1
	global_load_dwordx4 v[0:3], v[6:7], off
	s_waitcnt vmcnt(0)
	ds_write2_b32 v55, v0, v1 offset1:1
	ds_write2_b32 v59, v2, v3 offset1:1
	global_load_dwordx4 v[0:3], v[8:9], off
	s_waitcnt vmcnt(0)
	ds_write2_b32 v56, v0, v1 offset1:1
	ds_write2_b32 v60, v2, v3 offset1:1
	global_load_dwordx4 v[0:3], v[10:11], off
	v_and_b32_e32 v10, 31, v14
	v_lshlrev_b32_e32 v46, 2, v10
	s_waitcnt vmcnt(0)
	ds_write2_b32 v57, v0, v1 offset1:1
	ds_write2_b32 v61, v2, v3 offset1:1
	s_waitcnt lgkmcnt(0)
	s_barrier
	s_load_dwordx2 s[22:23], s[0:1], 0xb0
	v_ashrrev_i32_e32 v0, 4, v14
	v_lshlrev_b32_e32 v43, 2, v0
	v_or_b32_e32 v0, s43, v46
	v_lshlrev_b32_e32 v0, 2, v0
	v_mov_b32_e32 v1, v140
	s_waitcnt lgkmcnt(0)
	v_lshl_add_u64 v[4:5], s[22:23], 0, v[0:1]
	v_add_co_u32_e32 v4, vcc, s86, v4
	global_load_dwordx4 v[0:3], v0, s[22:23]
	s_nop 0
	v_addc_co_u32_e32 v5, vcc, 0, v5, vcc
	global_load_dwordx4 v[6:9], v[4:5], off
	v_mad_u32_u24 v18, v49, s9, v43
	s_mov_b32 s9, s95
	v_add_u32_e32 v64, 0x2000, v43
	s_waitcnt vmcnt(0)
	v_sub_f32_e32 v0, v6, v0
	v_mul_f32_e32 v0, 0x3fb8aa3b, v0
	v_exp_f32_e32 v6, v0
	v_sub_f32_e32 v0, v7, v1
	v_mul_f32_e32 v0, 0x3fb8aa3b, v0
	v_exp_f32_e32 v7, v0
	v_sub_f32_e32 v0, v8, v2
	v_mul_f32_e32 v0, 0x3fb8aa3b, v0
	v_exp_f32_e32 v4, v0
	v_sub_f32_e32 v0, v9, v3
	v_mul_f32_e32 v0, 0x3fb8aa3b, v0
	v_exp_f32_e32 v5, v0
	v_ashrrev_i32_e32 v0, 5, v14
	v_add_u32_e32 v48, s4, v0
	v_mov_b64_e32 v[0:1], s[30:31]
	v_mad_i64_i32 v[0:1], s[22:23], v48, s25, v[0:1]
	v_lshl_add_u64 v[8:9], v[0:1], 0, s[8:9]
	v_lshlrev_b32_e32 v0, 4, v10
	v_mov_b32_e32 v1, v140
	v_lshl_add_u64 v[12:13], v[8:9], 0, v[0:1]
	s_movk_i32 s4, 0x5000
	v_add_co_u32_e32 v0, vcc, s4, v12
	v_lshl_add_u64 v[8:9], v[8:9], 0, s[40:41]
	s_nop 0
	v_addc_co_u32_e32 v1, vcc, 0, v13, vcc
	global_load_dwordx4 v[0:3], v[0:1], off offset:32
	v_lshl_add_u64 v[8:9], v[8:9], 0, v[46:47]
	v_add_co_u32_e32 v8, vcc, s81, v8
	v_lshlrev_b32_e32 v47, 4, v49
	s_nop 0
	v_addc_co_u32_e32 v9, vcc, 0, v9, vcc
	global_load_dword v16, v[8:9], off offset:32
	s_waitcnt vmcnt(1)
	v_mul_f32_e32 v0, 0xbfb8aa3b, v0
	v_exp_f32_e32 v10, v0
	v_mul_f32_e32 v0, 0xbfb8aa3b, v1
	v_exp_f32_e32 v11, v0
	v_mul_f32_e32 v0, 0xbfb8aa3b, v2
	v_exp_f32_e32 v8, v0
	v_mul_f32_e32 v0, 0xbfb8aa3b, v3
	v_exp_f32_e32 v9, v0
	v_add_co_u32_e32 v0, vcc, s80, v12
	s_nop 1
	v_addc_co_u32_e32 v1, vcc, 0, v13, vcc
	global_load_dwordx4 v[0:3], v[0:1], off offset:32
	s_waitcnt vmcnt(0)
	v_mul_f32_e32 v12, 0xbfb8aa3b, v0
	v_mul_f32_e32 v13, 0xbfb8aa3b, v1
	v_exp_f32_e32 v12, v12
	v_exp_f32_e32 v13, v13
	s_nop 0
	v_pk_add_f32 v[12:13], v[12:13], 1.0 op_sel_hi:[1,0]
	v_div_scale_f32 v14, s[8:9], v13, v13, v1
	v_rcp_f32_e32 v15, v14
	s_nop 0
	v_fma_f32 v19, -v14, v15, 1.0
	v_fmac_f32_e32 v15, v19, v15
	v_div_scale_f32 v19, vcc, v1, v13, v1
	v_mul_f32_e32 v20, v19, v15
	v_fma_f32 v21, -v14, v20, v19
	v_fmac_f32_e32 v20, v21, v15
	v_fma_f32 v14, -v14, v20, v19
	v_div_fmas_f32 v14, v14, v15, v20
	v_div_fixup_f32 v1, v14, v13, v1
	v_div_scale_f32 v13, s[8:9], v12, v12, v0
	v_rcp_f32_e32 v14, v13
	s_nop 0
	v_fma_f32 v15, -v13, v14, 1.0
	v_fmac_f32_e32 v14, v15, v14
	v_div_scale_f32 v15, vcc, v0, v12, v0
	v_mul_f32_e32 v19, v15, v14
	v_fma_f32 v20, -v13, v19, v15
	v_fmac_f32_e32 v19, v20, v14
	v_fma_f32 v13, -v13, v19, v15
	v_div_fmas_f32 v13, v13, v14, v19
	v_div_fixup_f32 v0, v13, v12, v0
	v_mul_f32_e32 v12, 0xbfb8aa3b, v2
	v_mul_f32_e32 v13, 0xbfb8aa3b, v3
	v_exp_f32_e32 v12, v12
	v_exp_f32_e32 v13, v13
	v_pk_mul_f32 v[0:1], v[0:1], s[18:19] op_sel_hi:[1,0]
	v_pk_add_f32 v[12:13], v[12:13], 1.0 op_sel_hi:[1,0]
	v_div_scale_f32 v14, s[8:9], v13, v13, v3
	v_rcp_f32_e32 v15, v14
	s_nop 0
	v_fma_f32 v19, -v14, v15, 1.0
	v_fmac_f32_e32 v15, v19, v15
	v_div_scale_f32 v19, vcc, v3, v13, v3
	v_mul_f32_e32 v20, v19, v15
	v_fma_f32 v21, -v14, v20, v19
	v_fmac_f32_e32 v20, v21, v15
	v_fma_f32 v14, -v14, v20, v19
	v_div_fmas_f32 v14, v14, v15, v20
	v_div_fixup_f32 v3, v14, v13, v3
	v_div_scale_f32 v13, s[8:9], v12, v12, v2
	v_rcp_f32_e32 v14, v13
	s_nop 0
	v_fma_f32 v15, -v13, v14, 1.0
	v_fmac_f32_e32 v14, v15, v14
	v_div_scale_f32 v15, vcc, v2, v12, v2
	v_mul_f32_e32 v19, v15, v14
	v_fma_f32 v20, -v13, v19, v15
	v_fmac_f32_e32 v19, v20, v14
	v_fma_f32 v13, -v13, v19, v15
	v_div_fmas_f32 v13, v13, v14, v19
	v_div_fixup_f32 v2, v13, v12, v2
	v_add_u32_e32 v19, 0x5000, v18
	v_pk_mul_f32 v[2:3], v[2:3], s[18:19] op_sel_hi:[1,0]
	ds_read2_b32 v[14:15], v19 offset0:80 offset1:96
	ds_read2_b32 v[12:13], v19 offset0:113 offset1:129
	ds_read2_b32 v[24:25], v19 offset0:146 offset1:162
	ds_read2_b32 v[26:27], v19 offset0:179 offset1:195
	v_add_u32_e32 v19, 0x7000, v18
	v_add_u32_e32 v18, 0x7200, v18
	ds_read2_b32 v[28:29], v19 offset0:144 offset1:160
	ds_read2_b32 v[30:31], v19 offset0:177 offset1:193
	ds_read2_b32 v[32:33], v19 offset0:210 offset1:226
	ds_read2_b32 v[34:35], v18 offset0:115 offset1:131
	ds_write_b128 v17, v[0:3]
	v_pk_add_f32 v[0:1], v[6:7], 1.0 op_sel_hi:[1,0]
	v_div_scale_f32 v2, s[8:9], v1, v1, 1.0
	v_rcp_f32_e32 v3, v2
	s_nop 0
	v_fma_f32 v6, -v2, v3, 1.0
	v_fmac_f32_e32 v3, v6, v3
	v_div_scale_f32 v6, vcc, 1.0, v1, 1.0
	v_mul_f32_e32 v7, v6, v3
	v_fma_f32 v18, -v2, v7, v6
	v_fmac_f32_e32 v7, v18, v3
	v_fma_f32 v2, -v2, v7, v6
	v_div_fmas_f32 v2, v2, v3, v7
	v_div_fixup_f32 v1, v2, v1, 1.0
	v_div_scale_f32 v2, s[8:9], v0, v0, 1.0
	v_rcp_f32_e32 v3, v2
	s_nop 0
	v_fma_f32 v6, -v2, v3, 1.0
	v_fmac_f32_e32 v3, v6, v3
	v_div_scale_f32 v6, vcc, 1.0, v0, 1.0
	v_mul_f32_e32 v7, v6, v3
	v_fma_f32 v18, -v2, v7, v6
	v_fmac_f32_e32 v7, v18, v3
	v_fma_f32 v2, -v2, v7, v6
	v_div_fmas_f32 v2, v2, v3, v7
	v_pk_add_f32 v[6:7], v[10:11], 1.0 op_sel_hi:[1,0]
	v_div_fixup_f32 v0, v2, v0, 1.0
	v_div_scale_f32 v10, s[8:9], v7, v7, 1.0
	v_rcp_f32_e32 v11, v10
	v_pk_add_f32 v[2:3], v[0:1], 1.0 op_sel_hi:[1,0] neg_lo:[1,0] neg_hi:[1,0]
	v_fma_f32 v18, -v10, v11, 1.0
	v_fmac_f32_e32 v11, v18, v11
	v_div_scale_f32 v18, vcc, 1.0, v7, 1.0
	v_mul_f32_e32 v19, v18, v11
	v_fma_f32 v20, -v10, v19, v18
	v_fmac_f32_e32 v19, v20, v11
	v_fma_f32 v10, -v10, v19, v18
	v_div_fmas_f32 v10, v10, v11, v19
	v_div_fixup_f32 v7, v10, v7, 1.0
	v_div_scale_f32 v10, s[8:9], v6, v6, 1.0
	v_rcp_f32_e32 v11, v10
	s_nop 0
	v_fma_f32 v18, -v10, v11, 1.0
	v_fmac_f32_e32 v11, v18, v11
	v_div_scale_f32 v18, vcc, 1.0, v6, 1.0
	v_mul_f32_e32 v19, v18, v11
	v_fma_f32 v20, -v10, v19, v18
	v_fmac_f32_e32 v19, v20, v11
	v_fma_f32 v10, -v10, v19, v18
	v_div_fmas_f32 v10, v10, v11, v19
	v_div_fixup_f32 v6, v10, v6, 1.0
	v_pk_fma_f32 v[0:1], v[2:3], v[6:7], v[0:1]
	v_pk_add_f32 v[2:3], v[4:5], 1.0 op_sel_hi:[1,0]
	v_div_scale_f32 v4, s[8:9], v3, v3, 1.0
	v_rcp_f32_e32 v5, v4
	s_nop 0
	v_fma_f32 v6, -v4, v5, 1.0
	v_fmac_f32_e32 v5, v6, v5
	v_div_scale_f32 v6, vcc, 1.0, v3, 1.0
	v_mul_f32_e32 v7, v6, v5
	v_fma_f32 v10, -v4, v7, v6
	v_fmac_f32_e32 v7, v10, v5
	v_fma_f32 v4, -v4, v7, v6
	v_div_fmas_f32 v4, v4, v5, v7
	v_div_fixup_f32 v3, v4, v3, 1.0
	v_div_scale_f32 v4, s[8:9], v2, v2, 1.0
	v_rcp_f32_e32 v5, v4
	s_nop 0
	v_fma_f32 v6, -v4, v5, 1.0
	v_fmac_f32_e32 v5, v6, v5
	v_div_scale_f32 v6, vcc, 1.0, v2, 1.0
	v_mul_f32_e32 v7, v6, v5
	v_fma_f32 v10, -v4, v7, v6
	v_fmac_f32_e32 v7, v10, v5
	v_fma_f32 v4, -v4, v7, v6
	v_div_fmas_f32 v4, v4, v5, v7
	v_pk_add_f32 v[6:7], v[8:9], 1.0 op_sel_hi:[1,0]
	v_div_fixup_f32 v2, v4, v2, 1.0
	v_div_scale_f32 v8, s[8:9], v7, v7, 1.0
	v_rcp_f32_e32 v9, v8
	v_pk_add_f32 v[4:5], v[2:3], 1.0 op_sel_hi:[1,0] neg_lo:[1,0] neg_hi:[1,0]
	v_fma_f32 v10, -v8, v9, 1.0
	v_fmac_f32_e32 v9, v10, v9
	v_div_scale_f32 v10, vcc, 1.0, v7, 1.0
	v_mul_f32_e32 v11, v10, v9
	v_fma_f32 v18, -v8, v11, v10
	v_fmac_f32_e32 v11, v18, v9
	v_fma_f32 v8, -v8, v11, v10
	v_div_fmas_f32 v8, v8, v9, v11
	v_div_fixup_f32 v7, v8, v7, 1.0
	v_div_scale_f32 v8, s[8:9], v6, v6, 1.0
	v_rcp_f32_e32 v9, v8
	s_nop 0
	v_fma_f32 v10, -v8, v9, 1.0
	v_fmac_f32_e32 v9, v10, v9
	v_div_scale_f32 v10, vcc, 1.0, v6, 1.0
	v_mul_f32_e32 v11, v10, v9
	v_fma_f32 v18, -v8, v11, v10
	v_fmac_f32_e32 v11, v18, v9
	v_fma_f32 v8, -v8, v11, v10
	v_div_fmas_f32 v8, v8, v9, v11
	v_div_fixup_f32 v6, v8, v6, 1.0
	v_pk_fma_f32 v[2:3], v[4:5], v[6:7], v[2:3]
	ds_write_b128 v17, v[0:3] offset:4096
	ds_write_b32 v62, v16 offset:8192
	s_waitcnt lgkmcnt(0)
	s_barrier
	ds_read_b128 v[8:11], v47
	ds_read_b128 v[78:81], v47 offset:256
	ds_read_b128 v[82:85], v47 offset:4096
	ds_read_b128 v[86:89], v47 offset:4352
	ds_read_b128 v[4:7], v47 offset:512
	ds_read_b128 v[0:3], v47 offset:768
	ds_read_b128 v[20:23], v47 offset:4608
	ds_read_b128 v[16:19], v47 offset:4864
	ds_read2_b32 v[50:51], v64 offset0:32 offset1:48
	ds_read2_b32 v[52:53], v64 offset1:16
	s_waitcnt lgkmcnt(0)
	v_sub_f32 v14, v14, v52
	v_sub_f32 v12, v12, v52
	v_sub_f32 v13, v13, v53
	v_sub_f32 v15, v15, v53
	v_sub_f32 v24, v24, v52
	v_sub_f32 v25, v25, v53
	v_fma_f32 v76, v82, v14, v52
	v_fma_f32 v73, v83, v12, v52
	v_fma_f32 v74, v83, v13, v53
	v_fma_f32 v75, v82, v15, v53
	v_fma_f32 v71, v84, v24, v52
	v_fma_f32 v72, v84, v25, v53
	v_fma_f32 v12, v8, v76, v140
	v_fma_f32 v13, v9, v73, v140
	v_fma_f32 v9, v9, v74, v140
	v_fma_f32 v8, v8, v75, v140
	v_fma_f32 v14, v10, v71, v140
	v_fma_f32 v10, v10, v72, v140
	v_sub_f32 v26, v26, v52
	v_sub_f32 v27, v27, v53
	v_sub_f32 v28, v28, v52
	v_sub_f32 v29, v29, v53
	v_sub_f32 v30, v30, v52
	v_sub_f32 v31, v31, v53
	v_sub_f32 v32, v32, v52
	v_sub_f32 v33, v33, v53
	v_sub_f32 v63, v34, v52
	v_sub_f32 v77, v35, v53
	v_fma_f32 v69, v85, v26, v52
	v_fma_f32 v70, v85, v27, v53
	v_fma_f32 v67, v86, v28, v52
	v_fma_f32 v68, v86, v29, v53
	v_fma_f32 v65, v87, v30, v52
	v_fma_f32 v66, v87, v31, v53
	v_fma_f32 v34, v88, v32, v52
	v_fma_f32 v35, v88, v33, v53
	v_fma_f32 v15, v11, v69, v140
	v_fma_f32 v11, v11, v70, v140
	v_fma_f32 v12, v78, v67, v12
	v_fma_f32 v24, v78, v68, v8
	v_fma_f32 v8, v79, v65, v13
	v_fma_f32 v13, v79, v66, v9
	v_fma_f32 v9, v80, v34, v14
	v_fma_f32 v10, v80, v35, v10
	v_fma_f32 v32, v89, v63, v52
	v_fma_f32 v33, v89, v77, v53
	v_add_f32_e32 v8, v12, v8
	v_fma_f32 v14, v81, v32, v15
	v_fma_f32 v11, v81, v33, v11
	v_add_f32_e32 v12, v24, v13
	v_add_f32_e32 v9, v9, v14
	v_add_f32_e32 v10, v10, v11
	v_add_f32_e32 v8, v8, v9
	v_add_f32_e32 v10, v12, v10
	s_nop 0
	v_add_f32_dpp v8, v8, v8 row_ror:8 row_mask:0xf bank_mask:0xf bound_ctrl:1
	v_add_f32_dpp v10, v10, v10 row_ror:8 row_mask:0xf bank_mask:0xf bound_ctrl:1
	s_nop 0
	v_add_f32_dpp v8, v8, v8 row_ror:4 row_mask:0xf bank_mask:0xf bound_ctrl:1
	v_add_f32_dpp v10, v10, v10 row_ror:4 row_mask:0xf bank_mask:0xf bound_ctrl:1
	v_add_u32_e32 v63, 0x4800, v43
	v_add_f32_dpp v8, v8, v8 row_ror:2 row_mask:0xf bank_mask:0xf bound_ctrl:1
	v_add_f32_dpp v10, v10, v10 row_ror:2 row_mask:0xf bank_mask:0xf bound_ctrl:1
	s_nop 0
	v_add_f32_dpp v8, v8, v8 row_ror:1 row_mask:0xf bank_mask:0xf bound_ctrl:1
	v_add_f32_dpp v10, v10, v10 row_ror:1 row_mask:0xf bank_mask:0xf bound_ctrl:1
	ds_write2_b32 v63, v8, v10 offset1:16
	v_sub_f32 v76, v76, v50
	v_sub_f32 v75, v75, v51
	v_sub_f32 v73, v73, v50
	v_sub_f32 v74, v74, v51
	v_sub_f32 v71, v71, v50
	v_sub_f32 v72, v72, v51
	v_sub_f32 v69, v69, v50
	v_sub_f32 v70, v70, v51
	v_sub_f32 v67, v67, v50
	v_sub_f32 v68, v68, v51
	v_sub_f32 v65, v65, v50
	v_sub_f32 v66, v66, v51
	v_fma_f32 v80, v20, v76, v50
	v_fma_f32 v79, v20, v75, v51
	v_fma_f32 v77, v21, v73, v50
	v_fma_f32 v78, v21, v74, v51
	v_fma_f32 v75, v22, v71, v50
	v_fma_f32 v76, v22, v72, v51
	v_fma_f32 v73, v23, v69, v50
	v_fma_f32 v74, v23, v70, v51
	v_fma_f32 v71, v16, v67, v50
	v_fma_f32 v72, v16, v68, v51
	v_fma_f32 v69, v17, v65, v50
	v_fma_f32 v70, v17, v66, v51
	v_fma_f32 v16, v4, v80, v140
	v_fma_f32 v4, v4, v79, v140
	v_fma_f32 v17, v5, v77, v140
	v_fma_f32 v5, v5, v78, v140
	ds_read_b128 v[12:15], v47 offset:1024
	ds_read_b128 v[8:11], v47 offset:1280
	ds_read_b128 v[28:31], v47 offset:5120
	ds_read_b128 v[24:27], v47 offset:5376
	ds_read2_b32 v[52:53], v64 offset0:64 offset1:80
	v_sub_f32 v34, v34, v50
	v_sub_f32 v35, v35, v51
	v_fma_f32 v16, v0, v71, v16
	v_fma_f32 v4, v0, v72, v4
	v_fma_f32 v0, v1, v69, v17
	v_fma_f32 v5, v1, v70, v5
	v_fma_f32 v67, v18, v34, v50
	v_fma_f32 v68, v18, v35, v51
	v_fma_f32 v18, v6, v75, v140
	v_fma_f32 v6, v6, v76, v140
	v_sub_f32 v32, v32, v50
	v_sub_f32 v33, v33, v51
	v_add_f32_e32 v0, v16, v0
	v_fma_f32 v1, v2, v67, v18
	v_fma_f32 v2, v2, v68, v6
	v_fma_f32 v65, v19, v32, v50
	v_fma_f32 v66, v19, v33, v51
	v_fma_f32 v19, v7, v73, v140
	v_fma_f32 v7, v7, v74, v140
	v_add_f32_e32 v4, v4, v5
	v_fma_f32 v6, v3, v65, v19
	v_fma_f32 v3, v3, v66, v7
	v_add_f32_e32 v1, v1, v6
	v_add_f32_e32 v2, v2, v3
	v_add_f32_e32 v0, v0, v1
	v_add_f32_e32 v2, v4, v2
	s_nop 0
	v_add_f32_dpp v0, v0, v0 row_ror:8 row_mask:0xf bank_mask:0xf bound_ctrl:1
	v_add_f32_dpp v2, v2, v2 row_ror:8 row_mask:0xf bank_mask:0xf bound_ctrl:1
	s_nop 0
	v_add_f32_dpp v0, v0, v0 row_ror:4 row_mask:0xf bank_mask:0xf bound_ctrl:1
	v_add_f32_dpp v2, v2, v2 row_ror:4 row_mask:0xf bank_mask:0xf bound_ctrl:1
	s_nop 0
	v_add_f32_dpp v0, v0, v0 row_ror:2 row_mask:0xf bank_mask:0xf bound_ctrl:1
	v_add_f32_dpp v2, v2, v2 row_ror:2 row_mask:0xf bank_mask:0xf bound_ctrl:1
	s_nop 0
	v_add_f32_dpp v0, v0, v0 row_ror:1 row_mask:0xf bank_mask:0xf bound_ctrl:1
	v_add_f32_dpp v2, v2, v2 row_ror:1 row_mask:0xf bank_mask:0xf bound_ctrl:1
	ds_write2_b32 v63, v0, v2 offset0:32 offset1:48
	s_waitcnt lgkmcnt(0)
	v_sub_f32 v4, v80, v52
	v_sub_f32 v5, v79, v53
	v_sub_f32 v6, v77, v52
	v_sub_f32 v7, v78, v53
	v_sub_f32 v75, v75, v52
	v_sub_f32 v71, v71, v52
	v_sub_f32 v72, v72, v53
	v_sub_f32 v69, v69, v52
	v_sub_f32 v70, v70, v53
	v_sub_f32 v67, v67, v52
	v_fma_f32 v80, v28, v4, v52
	v_fma_f32 v79, v28, v5, v53
	v_fma_f32 v77, v29, v6, v52
	v_fma_f32 v78, v29, v7, v53
	ds_read_b128 v[16:19], v47 offset:1536
	ds_read_b128 v[0:3], v47 offset:1792
	ds_read_b128 v[32:35], v47 offset:5632
	ds_read_b128 v[20:23], v47 offset:5888
	ds_read2_b32 v[50:51], v64 offset0:96 offset1:112
	v_fma_f32 v4, v12, v80, v140
	v_fma_f32 v5, v12, v79, v140
	v_fma_f32 v6, v13, v77, v140
	v_fma_f32 v7, v13, v78, v140
	v_sub_f32 v76, v76, v53
	v_sub_f32 v73, v73, v52
	v_sub_f32 v74, v74, v53
	v_sub_f32 v68, v68, v53
	v_sub_f32 v65, v65, v52
	v_sub_f32 v66, v66, v53
	v_fma_f32 v75, v30, v75, v52
	v_fma_f32 v71, v24, v71, v52
	v_fma_f32 v72, v24, v72, v53
	v_fma_f32 v69, v25, v69, v52
	v_fma_f32 v70, v25, v70, v53
	v_fma_f32 v67, v26, v67, v52
	v_fma_f32 v12, v14, v75, v140
	v_fma_f32 v4, v8, v71, v4
	v_fma_f32 v8, v8, v72, v5
	v_fma_f32 v5, v9, v69, v6
	v_fma_f32 v6, v9, v70, v7
	v_fma_f32 v76, v30, v76, v53
	v_fma_f32 v7, v10, v67, v12
	v_fma_f32 v73, v31, v73, v52
	v_fma_f32 v74, v31, v74, v53
	v_fma_f32 v68, v26, v68, v53
	v_fma_f32 v65, v27, v65, v52
	v_fma_f32 v66, v27, v66, v53
	v_fma_f32 v13, v14, v76, v140
	v_fma_f32 v14, v15, v73, v140
	v_fma_f32 v15, v15, v74, v140
	v_add_f32_e32 v4, v4, v5
	v_fma_f32 v9, v10, v68, v13
	v_fma_f32 v10, v11, v65, v14
	v_fma_f32 v11, v11, v66, v15
	v_add_f32_e32 v6, v8, v6
	v_add_f32_e32 v5, v7, v10
	v_add_f32_e32 v7, v9, v11
	v_add_f32_e32 v4, v4, v5
	v_add_f32_e32 v6, v6, v7
	s_nop 0
	v_add_f32_dpp v4, v4, v4 row_ror:8 row_mask:0xf bank_mask:0xf bound_ctrl:1
	v_add_f32_dpp v6, v6, v6 row_ror:8 row_mask:0xf bank_mask:0xf bound_ctrl:1
	s_nop 0
	v_add_f32_dpp v4, v4, v4 row_ror:4 row_mask:0xf bank_mask:0xf bound_ctrl:1
	v_add_f32_dpp v6, v6, v6 row_ror:4 row_mask:0xf bank_mask:0xf bound_ctrl:1
	s_nop 0
	v_add_f32_dpp v4, v4, v4 row_ror:2 row_mask:0xf bank_mask:0xf bound_ctrl:1
	v_add_f32_dpp v6, v6, v6 row_ror:2 row_mask:0xf bank_mask:0xf bound_ctrl:1
	s_nop 0
	v_add_f32_dpp v4, v4, v4 row_ror:1 row_mask:0xf bank_mask:0xf bound_ctrl:1
	v_add_f32_dpp v6, v6, v6 row_ror:1 row_mask:0xf bank_mask:0xf bound_ctrl:1
	ds_write2_b32 v63, v4, v6 offset0:64 offset1:80
	s_waitcnt lgkmcnt(0)
	v_sub_f32 v12, v80, v50
	v_sub_f32 v13, v79, v51
	v_sub_f32 v14, v77, v50
	v_sub_f32 v15, v78, v51
	v_sub_f32 v79, v76, v51
	v_sub_f32 v81, v74, v51
	v_fma_f32 v77, v32, v12, v50
	v_fma_f32 v76, v32, v13, v51
	v_fma_f32 v74, v33, v14, v50
	ds_read_b128 v[8:11], v47 offset:2048
	ds_read_b128 v[4:7], v47 offset:2304
	ds_read_b128 v[28:31], v47 offset:6144
	ds_read_b128 v[24:27], v47 offset:6400
	ds_read2_b32 v[52:53], v64 offset0:128 offset1:144
	v_fma_f32 v12, v16, v77, v140
	v_fma_f32 v13, v16, v76, v140
	v_fma_f32 v14, v17, v74, v140
	v_sub_f32 v78, v75, v50
	v_sub_f32 v80, v73, v50
	v_sub_f32 v82, v71, v50
	v_sub_f32 v83, v72, v51
	v_sub_f32 v84, v69, v50
	v_sub_f32 v85, v70, v51
	v_sub_f32 v86, v67, v50
	v_sub_f32 v87, v68, v51
	v_sub_f32 v88, v65, v50
	v_sub_f32 v89, v66, v51
	v_fma_f32 v75, v33, v15, v51
	v_fma_f32 v72, v34, v78, v50
	v_fma_f32 v73, v34, v79, v51
	v_fma_f32 v68, v20, v82, v50
	v_fma_f32 v69, v20, v83, v51
	v_fma_f32 v66, v21, v84, v50
	v_fma_f32 v67, v21, v85, v51
	v_fma_f32 v65, v22, v86, v50
	v_fma_f32 v22, v22, v87, v51
	v_fma_f32 v15, v17, v75, v140
	v_fma_f32 v16, v18, v72, v140
	v_fma_f32 v17, v18, v73, v140
	v_fma_f32 v12, v0, v68, v12
	v_fma_f32 v13, v0, v69, v13
	v_fma_f32 v0, v1, v66, v14
	v_fma_f32 v14, v1, v67, v15
	v_fma_f32 v1, v2, v65, v16
	v_fma_f32 v2, v2, v22, v17
	v_fma_f32 v70, v35, v80, v50
	v_fma_f32 v71, v35, v81, v51
	v_fma_f32 v20, v23, v88, v50
	v_fma_f32 v21, v23, v89, v51
	v_add_f32_e32 v0, v12, v0
	v_fma_f32 v18, v19, v70, v140
	v_fma_f32 v19, v19, v71, v140
	v_add_f32_e32 v12, v13, v14
	v_fma_f32 v15, v3, v20, v18
	v_fma_f32 v3, v3, v21, v19
	v_add_f32_e32 v1, v1, v15
	v_add_f32_e32 v2, v2, v3
	v_add_f32_e32 v0, v0, v1
	v_add_f32_e32 v2, v12, v2
	s_nop 0
	v_add_f32_dpp v0, v0, v0 row_ror:8 row_mask:0xf bank_mask:0xf bound_ctrl:1
	v_add_f32_dpp v2, v2, v2 row_ror:8 row_mask:0xf bank_mask:0xf bound_ctrl:1
	s_nop 0
	v_add_f32_dpp v0, v0, v0 row_ror:4 row_mask:0xf bank_mask:0xf bound_ctrl:1
	v_add_f32_dpp v2, v2, v2 row_ror:4 row_mask:0xf bank_mask:0xf bound_ctrl:1
	s_nop 0
	v_add_f32_dpp v0, v0, v0 row_ror:2 row_mask:0xf bank_mask:0xf bound_ctrl:1
	v_add_f32_dpp v2, v2, v2 row_ror:2 row_mask:0xf bank_mask:0xf bound_ctrl:1
	s_nop 0
	v_add_f32_dpp v0, v0, v0 row_ror:1 row_mask:0xf bank_mask:0xf bound_ctrl:1
	v_add_f32_dpp v2, v2, v2 row_ror:1 row_mask:0xf bank_mask:0xf bound_ctrl:1
	ds_write2_b32 v63, v0, v2 offset0:96 offset1:112
	s_waitcnt lgkmcnt(0)
	v_sub_f32 v74, v74, v52
	v_sub_f32 v20, v20, v52
	v_sub_f32 v21, v21, v53
	v_sub_f32 v23, v77, v52
	v_sub_f32 v77, v76, v53
	v_sub_f32 v78, v75, v53
	v_sub_f32 v72, v72, v52
	v_sub_f32 v79, v73, v53
	v_sub_f32 v70, v70, v52
	v_sub_f32 v68, v68, v52
	v_sub_f32 v66, v66, v52
	v_sub_f32 v22, v22, v53
	v_fma_f32 v76, v28, v23, v52
	v_fma_f32 v75, v28, v77, v53
	v_fma_f32 v73, v29, v74, v52
	v_fma_f32 v74, v29, v78, v53
	v_fma_f32 v28, v27, v20, v52
	v_fma_f32 v29, v27, v21, v53
	v_fma_f32 v20, v8, v76, v140
	v_fma_f32 v8, v8, v75, v140
	v_fma_f32 v21, v9, v73, v140
	v_fma_f32 v9, v9, v74, v140
	ds_read_b128 v[12:15], v47 offset:2560
	ds_read_b128 v[0:3], v47 offset:2816
	ds_read_b128 v[32:35], v47 offset:6656
	ds_read_b128 v[16:19], v47 offset:6912
	ds_read2_b32 v[50:51], v64 offset0:160 offset1:176
	v_sub_f32 v80, v71, v53
	v_sub_f32 v81, v69, v53
	v_sub_f32 v82, v67, v53
	v_sub_f32 v83, v65, v52
	v_fma_f32 v71, v30, v72, v52
	v_fma_f32 v72, v30, v79, v53
	v_fma_f32 v69, v31, v70, v52
	v_fma_f32 v70, v31, v80, v53
	v_fma_f32 v67, v24, v68, v52
	v_fma_f32 v68, v24, v81, v53
	v_fma_f32 v65, v25, v66, v52
	v_fma_f32 v66, v25, v82, v53
	v_fma_f32 v30, v26, v83, v52
	v_fma_f32 v31, v26, v22, v53
	v_fma_f32 v22, v10, v71, v140
	v_fma_f32 v10, v10, v72, v140
	v_fma_f32 v20, v4, v67, v20
	v_fma_f32 v8, v4, v68, v8
	v_fma_f32 v4, v5, v65, v21
	v_fma_f32 v9, v5, v66, v9
	v_fma_f32 v5, v6, v30, v22
	v_fma_f32 v6, v6, v31, v10
	v_fma_f32 v23, v11, v69, v140
	v_fma_f32 v11, v11, v70, v140
	v_add_f32_e32 v4, v20, v4
	v_fma_f32 v10, v7, v28, v23
	v_fma_f32 v7, v7, v29, v11
	v_add_f32_e32 v8, v8, v9
	v_add_f32_e32 v5, v5, v10
	v_add_f32_e32 v6, v6, v7
	v_add_f32_e32 v4, v4, v5
	v_add_f32_e32 v6, v8, v6
	s_nop 0
	v_add_f32_dpp v4, v4, v4 row_ror:8 row_mask:0xf bank_mask:0xf bound_ctrl:1
	v_add_f32_dpp v6, v6, v6 row_ror:8 row_mask:0xf bank_mask:0xf bound_ctrl:1
	s_nop 0
	v_add_f32_dpp v4, v4, v4 row_ror:4 row_mask:0xf bank_mask:0xf bound_ctrl:1
	v_add_f32_dpp v6, v6, v6 row_ror:4 row_mask:0xf bank_mask:0xf bound_ctrl:1
	s_nop 0
	v_add_f32_dpp v4, v4, v4 row_ror:2 row_mask:0xf bank_mask:0xf bound_ctrl:1
	v_add_f32_dpp v6, v6, v6 row_ror:2 row_mask:0xf bank_mask:0xf bound_ctrl:1
	s_nop 0
	v_add_f32_dpp v4, v4, v4 row_ror:1 row_mask:0xf bank_mask:0xf bound_ctrl:1
	v_add_f32_dpp v6, v6, v6 row_ror:1 row_mask:0xf bank_mask:0xf bound_ctrl:1
	ds_write2_b32 v63, v4, v6 offset0:128 offset1:144
	s_waitcnt lgkmcnt(0)
	v_sub_f32 v76, v76, v50
	v_sub_f32 v75, v75, v51
	v_sub_f32 v73, v73, v50
	v_sub_f32 v74, v74, v51
	v_sub_f32 v71, v71, v50
	v_sub_f32 v72, v72, v51
	v_sub_f32 v69, v69, v50
	v_sub_f32 v70, v70, v51
	v_sub_f32 v67, v67, v50
	v_sub_f32 v68, v68, v51
	v_sub_f32 v65, v65, v50
	v_sub_f32 v66, v66, v51
	v_fma_f32 v78, v32, v76, v50
	v_fma_f32 v77, v32, v75, v51
	v_fma_f32 v75, v33, v73, v50
	v_fma_f32 v76, v33, v74, v51
	v_fma_f32 v73, v34, v71, v50
	v_fma_f32 v74, v34, v72, v51
	v_fma_f32 v71, v35, v69, v50
	v_fma_f32 v72, v35, v70, v51
	v_fma_f32 v69, v16, v67, v50
	v_fma_f32 v70, v16, v68, v51
	v_fma_f32 v67, v17, v65, v50
	v_fma_f32 v68, v17, v66, v51
	v_fma_f32 v16, v12, v78, v140
	v_fma_f32 v12, v12, v77, v140
	v_fma_f32 v17, v13, v75, v140
	v_fma_f32 v13, v13, v76, v140
	ds_read_b128 v[8:11], v47 offset:3072
	ds_read_b128 v[4:7], v47 offset:3328
	ds_read_b128 v[24:27], v47 offset:7168
	ds_read_b128 v[20:23], v47 offset:7424
	ds_read2_b32 v[52:53], v64 offset0:192 offset1:208
	v_sub_f32 v30, v30, v50
	v_sub_f32 v31, v31, v51
	v_fma_f32 v16, v0, v69, v16
	v_fma_f32 v12, v0, v70, v12
	v_fma_f32 v0, v1, v67, v17
	v_fma_f32 v13, v1, v68, v13
	v_fma_f32 v65, v18, v30, v50
	v_fma_f32 v66, v18, v31, v51
	v_fma_f32 v18, v14, v73, v140
	v_fma_f32 v14, v14, v74, v140
	v_sub_f32 v28, v28, v50
	v_sub_f32 v29, v29, v51
	v_add_f32_e32 v0, v16, v0
	v_fma_f32 v1, v2, v65, v18
	v_fma_f32 v2, v2, v66, v14
	v_fma_f32 v34, v19, v28, v50
	v_fma_f32 v35, v19, v29, v51
	v_fma_f32 v19, v15, v71, v140
	v_fma_f32 v15, v15, v72, v140
	v_add_f32_e32 v12, v12, v13
	v_fma_f32 v14, v3, v34, v19
	v_fma_f32 v3, v3, v35, v15
	v_add_f32_e32 v1, v1, v14
	v_add_f32_e32 v2, v2, v3
	v_add_f32_e32 v0, v0, v1
	v_add_f32_e32 v2, v12, v2
	s_nop 0
	v_add_f32_dpp v0, v0, v0 row_ror:8 row_mask:0xf bank_mask:0xf bound_ctrl:1
	v_add_f32_dpp v2, v2, v2 row_ror:8 row_mask:0xf bank_mask:0xf bound_ctrl:1
	s_nop 0
	v_add_f32_dpp v0, v0, v0 row_ror:4 row_mask:0xf bank_mask:0xf bound_ctrl:1
	v_add_f32_dpp v2, v2, v2 row_ror:4 row_mask:0xf bank_mask:0xf bound_ctrl:1
	s_nop 0
	v_add_f32_dpp v0, v0, v0 row_ror:2 row_mask:0xf bank_mask:0xf bound_ctrl:1
	v_add_f32_dpp v2, v2, v2 row_ror:2 row_mask:0xf bank_mask:0xf bound_ctrl:1
	s_nop 0
	v_add_f32_dpp v0, v0, v0 row_ror:1 row_mask:0xf bank_mask:0xf bound_ctrl:1
	v_add_f32_dpp v2, v2, v2 row_ror:1 row_mask:0xf bank_mask:0xf bound_ctrl:1
	ds_write2_b32 v63, v0, v2 offset0:160 offset1:176
	ds_read_b128 v[12:15], v47 offset:3584
	ds_read_b128 v[0:3], v47 offset:3840
	ds_read_b128 v[28:31], v47 offset:7680
	ds_read_b128 v[16:19], v47 offset:7936
	ds_read2_b32 v[32:33], v64 offset0:224 offset1:240
	s_waitcnt lgkmcnt(5)
	v_sub_f32 v47, v78, v52
	v_sub_f32 v50, v77, v53
	v_sub_f32 v51, v75, v52
	v_sub_f32 v75, v76, v53
	v_sub_f32 v73, v73, v52
	v_sub_f32 v74, v74, v53
	v_sub_f32 v71, v71, v52
	v_sub_f32 v72, v72, v53
	v_sub_f32 v69, v69, v52
	v_sub_f32 v70, v70, v53
	v_sub_f32 v76, v67, v52
	v_sub_f32 v68, v68, v53
	v_sub_f32 v77, v65, v52
	v_sub_f32 v78, v66, v53
	v_sub_f32 v79, v34, v52
	v_sub_f32 v80, v35, v53
	v_fma_f32 v67, v24, v47, v52
	v_fma_f32 v66, v24, v50, v53
	v_fma_f32 v64, v25, v51, v52
	v_fma_f32 v65, v25, v75, v53
	v_fma_f32 v50, v26, v73, v52
	v_fma_f32 v51, v26, v74, v53
	v_fma_f32 v35, v27, v71, v52
	v_fma_f32 v47, v27, v72, v53
	v_fma_f32 v27, v20, v69, v52
	v_fma_f32 v34, v20, v70, v53
	v_fma_f32 v25, v21, v76, v52
	v_fma_f32 v26, v21, v68, v53
	v_fma_f32 v24, v22, v77, v52
	v_fma_f32 v20, v23, v79, v52
	v_fma_f32 v21, v23, v80, v53
	v_fma_f32 v23, v8, v67, v140
	v_fma_f32 v8, v8, v66, v140
	v_fma_f32 v52, v9, v64, v140
	v_fma_f32 v9, v9, v65, v140
	v_fma_f32 v22, v22, v78, v53
	v_fma_f32 v53, v10, v50, v140
	v_fma_f32 v10, v10, v51, v140
	v_fma_f32 v23, v4, v27, v23
	v_fma_f32 v8, v4, v34, v8
	v_fma_f32 v4, v5, v25, v52
	v_fma_f32 v9, v5, v26, v9
	v_fma_f32 v5, v6, v24, v53
	v_fma_f32 v6, v6, v22, v10
	v_fma_f32 v68, v11, v35, v140
	v_fma_f32 v11, v11, v47, v140
	v_add_f32_e32 v4, v23, v4
	v_fma_f32 v10, v7, v20, v68
	v_fma_f32 v7, v7, v21, v11
	v_add_f32_e32 v8, v8, v9
	v_add_f32_e32 v5, v5, v10
	v_add_f32_e32 v6, v6, v7
	v_add_f32_e32 v4, v4, v5
	v_add_f32_e32 v6, v8, v6
	s_nop 0
	v_add_f32_dpp v4, v4, v4 row_ror:8 row_mask:0xf bank_mask:0xf bound_ctrl:1
	v_add_f32_dpp v6, v6, v6 row_ror:8 row_mask:0xf bank_mask:0xf bound_ctrl:1
	s_nop 0
	v_add_f32_dpp v4, v4, v4 row_ror:4 row_mask:0xf bank_mask:0xf bound_ctrl:1
	v_add_f32_dpp v6, v6, v6 row_ror:4 row_mask:0xf bank_mask:0xf bound_ctrl:1
	s_nop 0
	v_add_f32_dpp v4, v4, v4 row_ror:2 row_mask:0xf bank_mask:0xf bound_ctrl:1
	v_add_f32_dpp v6, v6, v6 row_ror:2 row_mask:0xf bank_mask:0xf bound_ctrl:1
	s_nop 0
	v_add_f32_dpp v4, v4, v4 row_ror:1 row_mask:0xf bank_mask:0xf bound_ctrl:1
	v_add_f32_dpp v6, v6, v6 row_ror:1 row_mask:0xf bank_mask:0xf bound_ctrl:1
	ds_write2_b32 v63, v4, v6 offset0:192 offset1:208
	s_waitcnt lgkmcnt(0)
	v_sub_f32 v4, v67, v32
	v_sub_f32 v5, v66, v33
	v_sub_f32 v6, v64, v32
	v_sub_f32 v7, v65, v33
	v_sub_f32 v25, v25, v32
	v_sub_f32 v24, v24, v32
	v_sub_f32 v8, v50, v32
	v_sub_f32 v9, v51, v33
	v_sub_f32 v11, v47, v33
	v_sub_f32 v23, v27, v32
	v_sub_f32 v27, v34, v33
	v_sub_f32 v26, v26, v33
	v_sub_f32 v34, v22, v33
	v_sub_f32 v47, v21, v33
	v_fma_f32 v4, v28, v4, v32
	v_fma_f32 v5, v28, v5, v33
	v_fma_f32 v6, v29, v6, v32
	v_fma_f32 v7, v29, v7, v33
	v_fma_f32 v21, v17, v25, v32
	v_fma_f32 v22, v18, v24, v32
	v_fma_f32 v24, v12, v4, v140
	v_fma_f32 v12, v12, v5, v140
	v_fma_f32 v25, v13, v6, v140
	v_fma_f32 v13, v13, v7, v140
	v_sub_f32 v10, v35, v32
	v_sub_f32 v35, v20, v32
	v_fma_f32 v8, v30, v8, v32
	v_fma_f32 v9, v30, v9, v33
	v_fma_f32 v20, v31, v11, v33
	v_fma_f32 v11, v16, v23, v32
	v_fma_f32 v16, v16, v27, v33
	v_fma_f32 v17, v17, v26, v33
	v_fma_f32 v23, v18, v34, v33
	v_fma_f32 v26, v14, v8, v140
	v_fma_f32 v14, v14, v9, v140
	v_fma_f32 v24, v0, v11, v24
	v_fma_f32 v12, v0, v16, v12
	v_fma_f32 v0, v1, v21, v25
	v_fma_f32 v13, v1, v17, v13
	v_fma_f32 v1, v2, v22, v26
	v_fma_f32 v2, v2, v23, v14
	v_fma_f32 v10, v31, v10, v32
	v_fma_f32 v18, v19, v35, v32
	v_fma_f32 v19, v19, v47, v33
	v_add_f32_e32 v0, v24, v0
	v_fma_f32 v27, v15, v10, v140
	v_fma_f32 v15, v15, v20, v140
	v_add_f32_e32 v12, v12, v13
	v_fma_f32 v14, v3, v18, v27
	v_fma_f32 v3, v3, v19, v15
	v_add_f32_e32 v1, v1, v14
	v_add_f32_e32 v2, v2, v3
	v_add_f32_e32 v0, v0, v1
	v_add_f32_e32 v2, v12, v2
	s_nop 0
	v_add_f32_dpp v0, v0, v0 row_ror:8 row_mask:0xf bank_mask:0xf bound_ctrl:1
	v_add_f32_dpp v2, v2, v2 row_ror:8 row_mask:0xf bank_mask:0xf bound_ctrl:1
	s_nop 0
	v_add_f32_dpp v0, v0, v0 row_ror:4 row_mask:0xf bank_mask:0xf bound_ctrl:1
	v_add_f32_dpp v2, v2, v2 row_ror:4 row_mask:0xf bank_mask:0xf bound_ctrl:1
	s_nop 0
	v_add_f32_dpp v0, v0, v0 row_ror:2 row_mask:0xf bank_mask:0xf bound_ctrl:1
	v_add_f32_dpp v2, v2, v2 row_ror:2 row_mask:0xf bank_mask:0xf bound_ctrl:1
	s_nop 0
	v_add_f32_dpp v0, v0, v0 row_ror:1 row_mask:0xf bank_mask:0xf bound_ctrl:1
	v_add_f32_dpp v2, v2, v2 row_ror:1 row_mask:0xf bank_mask:0xf bound_ctrl:1
	ds_write2_b32 v63, v0, v2 offset0:224 offset1:240
	s_waitcnt lgkmcnt(0)
	s_barrier
	s_load_dwordx2 s[22:23], s[0:1], 0x158
	v_mov_b32_e32 v47, v140
	ds_read_b32 v13, v62 offset:18432
	s_lshl_b64 s[8:9], s[94:95], 14
	v_lshl_add_u64 v[0:1], s[28:29], 0, v[46:47]
	s_lshl_b32 s94, s43, 2
	v_mul_u32_u24_e32 v12, 0x210, v49
	v_ashrrev_i32_e32 v49, 31, v48
	v_lshl_add_u64 v[0:1], v[0:1], 0, s[94:95]
	s_mov_b32 s41, s95
	v_lshl_add_u64 v[0:1], v[0:1], 0, s[40:41]
	v_lshlrev_b64 v[2:3], 12, v[48:49]
	s_lshl_b64 s[8:9], s[8:9], 2
	v_lshl_add_u64 v[0:1], v[0:1], 0, v[2:3]
	s_waitcnt lgkmcnt(0)
	s_add_u32 s4, s22, s8
	global_store_dword v[0:1], v13, off
	s_addc_u32 s9, s23, s9
	v_add_u32_e32 v0, v43, v12
	v_add_u32_e32 v1, 0x5000, v0
	s_add_u32 s8, s4, s40
	ds_write2_b32 v1, v4, v5 offset0:80 offset1:96
	ds_write2_b32 v1, v6, v7 offset0:113 offset1:129
	ds_write2_b32 v1, v8, v9 offset0:146 offset1:162
	ds_write2_b32 v1, v10, v20 offset0:179 offset1:195
	v_add_u32_e32 v1, 0x7000, v0
	v_add_u32_e32 v0, 0x7200, v0
	s_addc_u32 s9, s9, 0
	v_mov_b32_e32 v43, v140
	ds_write2_b32 v1, v11, v16 offset0:144 offset1:160
	ds_write2_b32 v1, v21, v17 offset0:177 offset1:193
	ds_write2_b32 v1, v22, v23 offset0:210 offset1:226
	ds_write2_b32 v0, v18, v19 offset0:115 offset1:131
	v_lshl_add_u64 v[0:1], s[8:9], 0, v[42:43]
	s_mov_b64 s[8:9], 0xd3a4840
	s_waitcnt lgkmcnt(0)
	s_barrier
	v_lshl_add_u64 v[4:5], v[0:1], 0, s[8:9]
	ds_read2_b32 v[0:1], v54 offset1:1
	ds_read2_b32 v[2:3], v58 offset1:1
	v_lshl_add_u64 v[6:7], v[4:5], 0, v[44:45]
	s_mov_b64 s[8:9], 0
	s_waitcnt lgkmcnt(0)
	global_store_dwordx4 v[6:7], v[0:3], off
	s_nop 1
	ds_read2_b32 v[0:1], v55 offset1:1
	ds_read2_b32 v[2:3], v59 offset1:1
	v_lshl_add_u64 v[6:7], v[4:5], 0, v[40:41]
	s_waitcnt lgkmcnt(0)
	global_store_dwordx4 v[6:7], v[0:3], off
	s_nop 1
	ds_read2_b32 v[0:1], v56 offset1:1
	ds_read2_b32 v[2:3], v60 offset1:1
	v_lshl_add_u64 v[6:7], v[4:5], 0, v[38:39]
	v_lshl_add_u64 v[4:5], v[4:5], 0, v[36:37]
	s_waitcnt lgkmcnt(0)
	global_store_dwordx4 v[6:7], v[0:3], off
	s_nop 1
	ds_read2_b32 v[0:1], v57 offset1:1
	ds_read2_b32 v[2:3], v61 offset1:1
	s_waitcnt lgkmcnt(0)
	global_store_dwordx4 v[4:5], v[0:3], off
